# GEMM tiles: lagging wave group's re-stagger barrier moved after next-tile scheduling + accumulator zeroing (overlaps the leading group's, off the first MFMA slot)
# speedup vs baseline: 1.0056x; 1.0056x over previous
_Z10fwd_kernel6Params:
	v_writelane_b32 v255, 0, 53
	s_mov_b64 s[78:79], s[0:1]
	s_load_dwordx4 s[88:91], s[0:1], 0x100
	s_nop 0
	s_load_dwordx2 s[0:1], s[0:1], 0x110
	v_and_b32_e32 v204, 0x3ff, v0
	s_mov_b32 s80, s2
	v_cmp_gt_u32_e32 vcc, 2, v204
	s_waitcnt lgkmcnt(0)
	v_writelane_b32 v254, s0, 0
	s_nop 1
	v_writelane_b32 v254, s1, 1
	s_and_saveexec_b64 s[0:1], vcc
	v_lshl_add_u32 v1, v204, 2, 0
	v_add_u32_e32 v1, 0x23fc0, v1
	v_mov_b32_e32 v2, 0
	ds_write_b32 v1, v2
	s_or_b64 exec, exec, s[0:1]
	s_load_dwordx2 s[2:3], s[78:79], 0x110
	s_waitcnt lgkmcnt(0)
	s_barrier
	s_sub_i32 s0, s3, s2
	s_cmp_lt_i32 s0, 2
	s_mov_b32 s0, 0
	v_writelane_b32 v254, s0, 2
	s_cbranch_scc1 .LBB0_7
	s_getreg_b32 s0, hwreg(HW_REG_XCC_ID, 0, 4)
	s_and_b32 s0, s0, 15
	v_writelane_b32 v254, s0, 2
	v_cmp_eq_u32_e32 vcc, 0, v204
	s_and_saveexec_b64 s[0:1], vcc
	s_cbranch_execz .LBB0_6
	s_mov_b64 s[2:3], exec
	v_mbcnt_lo_u32_b32 v1, s2, 0
	v_mbcnt_hi_u32_b32 v1, s3, v1
	v_cmp_eq_u32_e32 vcc, 0, v1
	s_and_b64 s[4:5], exec, vcc
	s_mov_b64 exec, s[4:5]
	s_cbranch_execz .LBB0_6
	v_readlane_b32 s4, v254, 2
	s_lshl_b32 s4, s4, 8
	s_bcnt1_i32_b64 s2, s[2:3]
	v_mov_b32_e32 v1, s4
	v_mov_b32_e32 v2, s2
	global_atomic_add v1, v2, s[90:91] offset:1024

.LBB0_334:
	s_ashr_i32 s21, s20, 31
	s_lshl_b64 s[22:23], s[20:21], 19
	s_add_u32 s22, s34, s22
	s_addc_u32 s23, s35, s23
	s_and_b64 s[24:25], s[2:3], exec
	s_cselect_b32 s5, s23, s27
	s_cselect_b32 s21, s22, s26
	s_ashr_i32 s19, s18, 31
	s_lshl_b64 s[24:25], s[18:19], 19
	s_add_u32 s24, s36, s24
	s_addc_u32 s25, s37, s25
	s_and_b64 s[30:31], s[2:3], exec
	s_cselect_b32 s19, s25, s29
	s_cselect_b32 s53, s24, s28
	s_add_u32 s26, s26, 0x40080
	s_addc_u32 s27, s27, 0
	s_add_u32 s54, s28, 0x100
	v_mov_b32_e32 v0, 0
	s_addc_u32 s55, s29, 0
	s_mov_b32 s56, -2
	v_mov_b32_e32 v1, v0
	v_mov_b32_e32 v2, v0
	v_mov_b32_e32 v3, v0
	v_mov_b32_e32 v4, v0
	v_mov_b32_e32 v5, v0
	v_mov_b32_e32 v6, v0
	v_mov_b32_e32 v7, v0
	v_mov_b32_e32 v16, v0
	v_mov_b32_e32 v17, v0
	v_mov_b32_e32 v18, v0
	v_mov_b32_e32 v19, v0
	v_mov_b32_e32 v20, v0
	v_mov_b32_e32 v21, v0
	v_mov_b32_e32 v22, v0
	v_mov_b32_e32 v23, v0
	v_mov_b32_e32 v32, v0
	v_mov_b32_e32 v33, v0
	v_mov_b32_e32 v34, v0
	v_mov_b32_e32 v35, v0
	v_mov_b32_e32 v36, v0
	v_mov_b32_e32 v37, v0
	v_mov_b32_e32 v38, v0
	v_mov_b32_e32 v39, v0
	v_mov_b32_e32 v48, v0
	v_mov_b32_e32 v49, v0
	v_mov_b32_e32 v50, v0
	v_mov_b32_e32 v51, v0
	v_mov_b32_e32 v52, v0
	v_mov_b32_e32 v53, v0
	v_mov_b32_e32 v54, v0
	v_mov_b32_e32 v55, v0
	v_mov_b32_e32 v8, v0
	v_mov_b32_e32 v9, v0
	v_mov_b32_e32 v10, v0
	v_mov_b32_e32 v11, v0
	v_mov_b32_e32 v12, v0
	v_mov_b32_e32 v13, v0
	v_mov_b32_e32 v14, v0
	v_mov_b32_e32 v15, v0
	v_mov_b32_e32 v24, v0
	v_mov_b32_e32 v25, v0
	v_mov_b32_e32 v26, v0
	v_mov_b32_e32 v27, v0
	v_mov_b32_e32 v28, v0
	v_mov_b32_e32 v29, v0
	v_mov_b32_e32 v30, v0
	v_mov_b32_e32 v31, v0
	v_mov_b32_e32 v40, v0
	v_mov_b32_e32 v41, v0
	v_mov_b32_e32 v42, v0
	v_mov_b32_e32 v43, v0
	v_mov_b32_e32 v44, v0
	v_mov_b32_e32 v45, v0
	v_mov_b32_e32 v46, v0
	v_mov_b32_e32 v47, v0
	v_mov_b32_e32 v56, v0
	v_mov_b32_e32 v57, v0
	v_mov_b32_e32 v58, v0
	v_mov_b32_e32 v59, v0
	v_mov_b32_e32 v60, v0
	v_mov_b32_e32 v61, v0
	v_mov_b32_e32 v62, v0
	v_mov_b32_e32 v63, v0
	v_mov_b32_e32 v64, v0
	v_mov_b32_e32 v65, v0
	v_mov_b32_e32 v66, v0
	v_mov_b32_e32 v67, v0
	v_mov_b32_e32 v68, v0
	v_mov_b32_e32 v69, v0
	v_mov_b32_e32 v70, v0
	v_mov_b32_e32 v71, v0
	v_mov_b32_e32 v80, v0
	v_mov_b32_e32 v81, v0
	v_mov_b32_e32 v82, v0
	v_mov_b32_e32 v83, v0
	v_mov_b32_e32 v84, v0
	v_mov_b32_e32 v85, v0
	v_mov_b32_e32 v86, v0
	v_mov_b32_e32 v87, v0
	v_mov_b32_e32 v96, v0
	v_mov_b32_e32 v97, v0
	v_mov_b32_e32 v98, v0
	v_mov_b32_e32 v99, v0
	v_mov_b32_e32 v100, v0
	v_mov_b32_e32 v101, v0
	v_mov_b32_e32 v102, v0
	v_mov_b32_e32 v103, v0
	v_mov_b32_e32 v112, v0
	v_mov_b32_e32 v113, v0
	v_mov_b32_e32 v114, v0
	v_mov_b32_e32 v115, v0
	v_mov_b32_e32 v116, v0
	v_mov_b32_e32 v117, v0
	v_mov_b32_e32 v118, v0
	v_mov_b32_e32 v119, v0
	v_mov_b32_e32 v72, v0
	v_mov_b32_e32 v73, v0
	v_mov_b32_e32 v74, v0
	v_mov_b32_e32 v75, v0
	v_mov_b32_e32 v76, v0
	v_mov_b32_e32 v77, v0
	v_mov_b32_e32 v78, v0
	v_mov_b32_e32 v79, v0
	v_mov_b32_e32 v88, v0
	v_mov_b32_e32 v89, v0
	v_mov_b32_e32 v90, v0
	v_mov_b32_e32 v91, v0
	v_mov_b32_e32 v92, v0
	v_mov_b32_e32 v93, v0
	v_mov_b32_e32 v94, v0
	v_mov_b32_e32 v95, v0
	v_mov_b32_e32 v104, v0
	v_mov_b32_e32 v105, v0
	v_mov_b32_e32 v106, v0
	v_mov_b32_e32 v107, v0
	v_mov_b32_e32 v108, v0
	v_mov_b32_e32 v109, v0
	v_mov_b32_e32 v110, v0
	v_mov_b32_e32 v111, v0
	v_mov_b32_e32 v120, v0
	v_mov_b32_e32 v121, v0
	v_mov_b32_e32 v122, v0
	v_mov_b32_e32 v123, v0
	v_mov_b32_e32 v124, v0
	v_mov_b32_e32 v125, v0
	v_mov_b32_e32 v126, v0
	v_mov_b32_e32 v127, v0
	v_readlane_b32 s97, v255, 53
	s_nop 3
	s_cmp_eq_u32 s97, 1
	s_cbranch_scc0 .Llsb_skip_1
	v_writelane_b32 v255, 0, 53
	s_barrier
.Llsb_skip_1:
.LBB0_335:
	ds_read_b128 v[128:131], v174
	ds_read_b128 v[132:135], v174 offset:1024
	ds_read_b128 v[158:161], v174 offset:2048
	ds_read_b128 v[178:181], v174 offset:3072
	ds_read_b128 v[182:185], v175
	ds_read_b128 v[186:189], v175 offset:1024
	ds_read_b128 v[190:193], v175 offset:2048
	ds_read_b128 v[194:197], v175 offset:3072
	s_add_u32 s28, s26, 0xfffc0080
	s_addc_u32 s29, s27, -1
	s_cmp_eq_u32 s56, 12
	s_cselect_b32 s31, s5, s29
	s_cselect_b32 s30, s21, s28
	s_cselect_b32 s29, s19, s55
	s_cselect_b32 s28, s53, s54
	v_lshl_add_u64 v[202:203], s[26:27], 0, v[150:151]
	s_add_i32 m0, s7, 0xc000
	ds_read_b128 v[198:201], v176
	ds_read_b128 v[206:209], v176 offset:1024
	ds_read_b128 v[210:213], v176 offset:2048
	ds_read_b128 v[214:217], v176 offset:3072
	ds_read_b128 v[218:221], v176 offset:4096
	ds_read_b128 v[222:225], v176 offset:5120
	ds_read_b128 v[226:229], v176 offset:6144
	ds_read_b128 v[230:233], v176 offset:7168
	global_load_lds_dwordx4 v[202:203], off
	v_lshl_add_u64 v[202:203], s[26:27], 0, v[152:153]
	s_add_i32 m0, s7, 0xe000
	s_nop 0
	global_load_lds_dwordx4 v[202:203], off
	s_waitcnt vmcnt(8)
	s_waitcnt lgkmcnt(0)
	s_barrier
	s_setprio 1
	s_waitcnt lgkmcnt(0)
	v_mfma_f32_16x16x32_bf16 v[124:127], v[128:131], v[198:201], v[124:127]
	v_mfma_f32_16x16x32_bf16 v[120:123], v[158:161], v[198:201], v[120:123]
	v_mfma_f32_16x16x32_bf16 v[108:111], v[128:131], v[210:213], v[108:111]
	v_mfma_f32_16x16x32_bf16 v[104:107], v[158:161], v[210:213], v[104:107]
	v_mfma_f32_16x16x32_bf16 v[92:95], v[128:131], v[218:221], v[92:95]
	v_mfma_f32_16x16x32_bf16 v[88:91], v[158:161], v[218:221], v[88:91]
	v_mfma_f32_16x16x32_bf16 v[76:79], v[128:131], v[226:229], v[76:79]
	v_mfma_f32_16x16x32_bf16 v[72:75], v[158:161], v[226:229], v[72:75]
	v_mfma_f32_16x16x32_bf16 v[124:127], v[132:135], v[206:209], v[124:127]
	v_mfma_f32_16x16x32_bf16 v[120:123], v[178:181], v[206:209], v[120:123]
	v_mfma_f32_16x16x32_bf16 v[108:111], v[132:135], v[214:217], v[108:111]
	v_mfma_f32_16x16x32_bf16 v[104:107], v[178:181], v[214:217], v[104:107]
	v_mfma_f32_16x16x32_bf16 v[92:95], v[132:135], v[222:225], v[92:95]
	v_mfma_f32_16x16x32_bf16 v[88:91], v[178:181], v[222:225], v[88:91]
	v_mfma_f32_16x16x32_bf16 v[76:79], v[132:135], v[230:233], v[76:79]
	v_mfma_f32_16x16x32_bf16 v[72:75], v[178:181], v[230:233], v[72:75]
	s_setprio 0
	s_setprio 1
	v_mfma_f32_16x16x32_bf16 v[116:119], v[182:185], v[198:201], v[116:119]
	v_mfma_f32_16x16x32_bf16 v[112:115], v[190:193], v[198:201], v[112:115]
	v_mfma_f32_16x16x32_bf16 v[100:103], v[182:185], v[210:213], v[100:103]
	v_mfma_f32_16x16x32_bf16 v[96:99], v[190:193], v[210:213], v[96:99]
	v_mfma_f32_16x16x32_bf16 v[84:87], v[182:185], v[218:221], v[84:87]
	v_mfma_f32_16x16x32_bf16 v[80:83], v[190:193], v[218:221], v[80:83]
	v_mfma_f32_16x16x32_bf16 v[68:71], v[182:185], v[226:229], v[68:71]
	v_mfma_f32_16x16x32_bf16 v[64:67], v[190:193], v[226:229], v[64:67]
	v_mfma_f32_16x16x32_bf16 v[116:119], v[186:189], v[206:209], v[116:119]
	v_mfma_f32_16x16x32_bf16 v[112:115], v[194:197], v[206:209], v[112:115]
	v_mfma_f32_16x16x32_bf16 v[100:103], v[186:189], v[214:217], v[100:103]
	v_mfma_f32_16x16x32_bf16 v[96:99], v[194:197], v[214:217], v[96:99]
	v_mfma_f32_16x16x32_bf16 v[84:87], v[186:189], v[222:225], v[84:87]
	v_mfma_f32_16x16x32_bf16 v[80:83], v[194:197], v[222:225], v[80:83]
	v_mfma_f32_16x16x32_bf16 v[68:71], v[186:189], v[230:233], v[68:71]
	v_mfma_f32_16x16x32_bf16 v[64:67], v[194:197], v[230:233], v[64:67]
	s_setprio 0
	s_barrier
	s_add_i32 s57, s47, s38
	v_lshl_add_u64 v[202:203], s[28:29], 0, v[140:141]
	s_mov_b32 m0, s57
	ds_read_b128 v[198:201], v176 offset:16384
	ds_read_b128 v[206:209], v176 offset:17408
	ds_read_b128 v[210:213], v176 offset:18432
	ds_read_b128 v[214:217], v176 offset:19456
	ds_read_b128 v[218:221], v176 offset:20480
	ds_read_b128 v[222:225], v176 offset:21504
	ds_read_b128 v[226:229], v176 offset:22528
	ds_read_b128 v[230:233], v176 offset:23552
	global_load_lds_dwordx4 v[202:203], off
	s_add_i32 m0, s57, 0x2000
	s_add_u32 s58, s28, 0x40000
	v_lshl_add_u64 v[234:235], s[28:29], 0, v[142:143]
	s_addc_u32 s59, s29, 0
	s_add_i32 s57, s48, s38
	global_load_lds_dwordx4 v[234:235], off
	v_lshl_add_u64 v[236:237], s[58:59], 0, v[140:141]
	s_mov_b32 m0, s57
	v_lshl_add_u64 v[238:239], s[30:31], 0, v[138:139]
	global_load_lds_dwordx4 v[236:237], off
	v_lshl_add_u64 v[236:237], s[58:59], 0, v[142:143]
	s_add_i32 m0, s57, 0x2000
	s_nop 0
	global_load_lds_dwordx4 v[236:237], off
	v_lshl_add_u64 v[236:237], s[30:31], 0, v[136:137]
	s_mov_b32 m0, s7
	s_nop 0
	global_load_lds_dwordx4 v[236:237], off
	s_mov_b32 m0, s39
	s_nop 0
	global_load_lds_dwordx4 v[238:239], off
	s_waitcnt vmcnt(8)
	s_waitcnt lgkmcnt(0)
	s_barrier
	s_setprio 1
	s_waitcnt lgkmcnt(0)
	v_mfma_f32_16x16x32_bf16 v[60:63], v[128:131], v[198:201], v[60:63]
	v_mfma_f32_16x16x32_bf16 v[56:59], v[158:161], v[198:201], v[56:59]
	v_mfma_f32_16x16x32_bf16 v[44:47], v[128:131], v[210:213], v[44:47]
	v_mfma_f32_16x16x32_bf16 v[40:43], v[158:161], v[210:213], v[40:43]
	v_mfma_f32_16x16x32_bf16 v[28:31], v[128:131], v[218:221], v[28:31]
	v_mfma_f32_16x16x32_bf16 v[24:27], v[158:161], v[218:221], v[24:27]
	v_mfma_f32_16x16x32_bf16 v[12:15], v[128:131], v[226:229], v[12:15]
	v_mfma_f32_16x16x32_bf16 v[8:11], v[158:161], v[226:229], v[8:11]
	v_mfma_f32_16x16x32_bf16 v[60:63], v[132:135], v[206:209], v[60:63]
	v_mfma_f32_16x16x32_bf16 v[56:59], v[178:181], v[206:209], v[56:59]
	v_mfma_f32_16x16x32_bf16 v[44:47], v[132:135], v[214:217], v[44:47]
	v_mfma_f32_16x16x32_bf16 v[40:43], v[178:181], v[214:217], v[40:43]
	v_mfma_f32_16x16x32_bf16 v[28:31], v[132:135], v[222:225], v[28:31]
	v_mfma_f32_16x16x32_bf16 v[24:27], v[178:181], v[222:225], v[24:27]
	v_mfma_f32_16x16x32_bf16 v[12:15], v[132:135], v[230:233], v[12:15]
	v_mfma_f32_16x16x32_bf16 v[8:11], v[178:181], v[230:233], v[8:11]
	s_setprio 0
	s_setprio 1
	v_mfma_f32_16x16x32_bf16 v[52:55], v[182:185], v[198:201], v[52:55]
	v_mfma_f32_16x16x32_bf16 v[48:51], v[190:193], v[198:201], v[48:51]
	v_mfma_f32_16x16x32_bf16 v[36:39], v[182:185], v[210:213], v[36:39]
	v_mfma_f32_16x16x32_bf16 v[32:35], v[190:193], v[210:213], v[32:35]
	v_mfma_f32_16x16x32_bf16 v[20:23], v[182:185], v[218:221], v[20:23]
	v_mfma_f32_16x16x32_bf16 v[16:19], v[190:193], v[218:221], v[16:19]
	v_mfma_f32_16x16x32_bf16 v[4:7], v[182:185], v[226:229], v[4:7]
	v_mfma_f32_16x16x32_bf16 v[0:3], v[190:193], v[226:229], v[0:3]
	v_mfma_f32_16x16x32_bf16 v[52:55], v[186:189], v[206:209], v[52:55]
	v_mfma_f32_16x16x32_bf16 v[48:51], v[194:197], v[206:209], v[48:51]
	v_mfma_f32_16x16x32_bf16 v[36:39], v[186:189], v[214:217], v[36:39]
	v_mfma_f32_16x16x32_bf16 v[32:35], v[194:197], v[214:217], v[32:35]
	v_mfma_f32_16x16x32_bf16 v[20:23], v[186:189], v[222:225], v[20:23]
	v_mfma_f32_16x16x32_bf16 v[16:19], v[194:197], v[222:225], v[16:19]
	v_mfma_f32_16x16x32_bf16 v[4:7], v[186:189], v[230:233], v[4:7]
	v_mfma_f32_16x16x32_bf16 v[0:3], v[194:197], v[230:233], v[0:3]
	s_setprio 0
	s_barrier
	s_add_i32 s57, 0, 0x18000
	v_add_u32_e32 v144, s57, v170
	s_add_i32 s58, 0, 0x1c000
	ds_read_b128 v[128:131], v144
	ds_read_b128 v[132:135], v144 offset:1024
	ds_read_b128 v[158:161], v144 offset:2048
	ds_read_b128 v[178:181], v144 offset:3072
	v_add_u32_e32 v144, s58, v170
	ds_read_b128 v[182:185], v144
	ds_read_b128 v[186:189], v144 offset:1024
	ds_read_b128 v[190:193], v144 offset:2048
	ds_read_b128 v[194:197], v144 offset:3072
	s_add_u32 s30, s30, 0x40000
	s_addc_u32 s31, s31, 0
	s_mov_b32 m0, s40
	v_lshl_add_u64 v[240:241], s[30:31], 0, v[136:137]
	ds_read_b128 v[198:201], v176 offset:32768
	ds_read_b128 v[206:209], v176 offset:33792
	ds_read_b128 v[210:213], v176 offset:34816
	ds_read_b128 v[214:217], v176 offset:35840
	ds_read_b128 v[218:221], v176 offset:36864
	ds_read_b128 v[222:225], v176 offset:37888
	ds_read_b128 v[226:229], v176 offset:38912
	ds_read_b128 v[230:233], v176 offset:39936
	global_load_lds_dwordx4 v[240:241], off
	v_lshl_add_u64 v[240:241], s[30:31], 0, v[138:139]
	s_mov_b32 m0, s41
	s_nop 0
	global_load_lds_dwordx4 v[240:241], off
	s_waitcnt vmcnt(8)
	s_waitcnt lgkmcnt(0)
	s_barrier
	s_setprio 1
	s_waitcnt lgkmcnt(0)
	v_mfma_f32_16x16x32_bf16 v[124:127], v[128:131], v[198:201], v[124:127]
	v_mfma_f32_16x16x32_bf16 v[120:123], v[158:161], v[198:201], v[120:123]
	v_mfma_f32_16x16x32_bf16 v[108:111], v[128:131], v[210:213], v[108:111]
	v_mfma_f32_16x16x32_bf16 v[104:107], v[158:161], v[210:213], v[104:107]
	v_mfma_f32_16x16x32_bf16 v[92:95], v[128:131], v[218:221], v[92:95]
	v_mfma_f32_16x16x32_bf16 v[88:91], v[158:161], v[218:221], v[88:91]
	v_mfma_f32_16x16x32_bf16 v[76:79], v[128:131], v[226:229], v[76:79]
	v_mfma_f32_16x16x32_bf16 v[72:75], v[158:161], v[226:229], v[72:75]
	v_mfma_f32_16x16x32_bf16 v[124:127], v[132:135], v[206:209], v[124:127]
	v_mfma_f32_16x16x32_bf16 v[120:123], v[178:181], v[206:209], v[120:123]
	v_mfma_f32_16x16x32_bf16 v[108:111], v[132:135], v[214:217], v[108:111]
	v_mfma_f32_16x16x32_bf16 v[104:107], v[178:181], v[214:217], v[104:107]
	v_mfma_f32_16x16x32_bf16 v[92:95], v[132:135], v[222:225], v[92:95]
	v_mfma_f32_16x16x32_bf16 v[88:91], v[178:181], v[222:225], v[88:91]
	v_mfma_f32_16x16x32_bf16 v[76:79], v[132:135], v[230:233], v[76:79]
	v_mfma_f32_16x16x32_bf16 v[72:75], v[178:181], v[230:233], v[72:75]
	s_setprio 0
	s_setprio 1
	v_mfma_f32_16x16x32_bf16 v[116:119], v[182:185], v[198:201], v[116:119]
	v_mfma_f32_16x16x32_bf16 v[112:115], v[190:193], v[198:201], v[112:115]
	v_mfma_f32_16x16x32_bf16 v[100:103], v[182:185], v[210:213], v[100:103]
	v_mfma_f32_16x16x32_bf16 v[96:99], v[190:193], v[210:213], v[96:99]
	v_mfma_f32_16x16x32_bf16 v[84:87], v[182:185], v[218:221], v[84:87]
	v_mfma_f32_16x16x32_bf16 v[80:83], v[190:193], v[218:221], v[80:83]
	v_mfma_f32_16x16x32_bf16 v[68:71], v[182:185], v[226:229], v[68:71]
	v_mfma_f32_16x16x32_bf16 v[64:67], v[190:193], v[226:229], v[64:67]
	v_mfma_f32_16x16x32_bf16 v[116:119], v[186:189], v[206:209], v[116:119]
	v_mfma_f32_16x16x32_bf16 v[112:115], v[194:197], v[206:209], v[112:115]
	v_mfma_f32_16x16x32_bf16 v[100:103], v[186:189], v[214:217], v[100:103]
	v_mfma_f32_16x16x32_bf16 v[96:99], v[194:197], v[214:217], v[96:99]
	v_mfma_f32_16x16x32_bf16 v[84:87], v[186:189], v[222:225], v[84:87]
	v_mfma_f32_16x16x32_bf16 v[80:83], v[194:197], v[222:225], v[80:83]
	v_mfma_f32_16x16x32_bf16 v[68:71], v[186:189], v[230:233], v[68:71]
	v_mfma_f32_16x16x32_bf16 v[64:67], v[194:197], v[230:233], v[64:67]
	s_setprio 0
	s_barrier
	s_add_i32 s30, s57, s38
	v_lshl_add_u64 v[202:203], v[202:203], 0, s[14:15]
	s_mov_b32 m0, s30
	ds_read_b128 v[198:201], v176 offset:49152
	ds_read_b128 v[206:209], v176 offset:50176
	ds_read_b128 v[210:213], v176 offset:51200
	ds_read_b128 v[214:217], v176 offset:52224
	ds_read_b128 v[218:221], v176 offset:53248
	ds_read_b128 v[222:225], v176 offset:54272
	ds_read_b128 v[226:229], v176 offset:55296
	ds_read_b128 v[230:233], v176 offset:56320
	global_load_lds_dwordx4 v[202:203], off
	s_add_i32 m0, s30, 0x2000
	s_add_u32 s28, s28, 0x40080
	v_lshl_add_u64 v[202:203], v[234:235], 0, s[14:15]
	s_addc_u32 s29, s29, 0
	s_add_i32 s30, s58, s38
	global_load_lds_dwordx4 v[202:203], off
	v_lshl_add_u64 v[202:203], s[28:29], 0, v[140:141]
	s_mov_b32 m0, s30
	s_nop 0
	global_load_lds_dwordx4 v[202:203], off
	v_lshl_add_u64 v[202:203], s[28:29], 0, v[142:143]
	s_add_i32 m0, s30, 0x2000
	s_nop 0
	global_load_lds_dwordx4 v[202:203], off
	v_lshl_add_u64 v[202:203], v[236:237], 0, s[14:15]
	s_mov_b32 m0, s43
	s_nop 0
	global_load_lds_dwordx4 v[202:203], off
	v_lshl_add_u64 v[202:203], v[238:239], 0, s[14:15]
	s_mov_b32 m0, s44
	s_nop 0
	global_load_lds_dwordx4 v[202:203], off
	s_waitcnt vmcnt(8)
	s_waitcnt lgkmcnt(0)
	s_barrier
	s_setprio 1
	s_waitcnt lgkmcnt(0)
	v_mfma_f32_16x16x32_bf16 v[60:63], v[128:131], v[198:201], v[60:63]
	v_mfma_f32_16x16x32_bf16 v[56:59], v[158:161], v[198:201], v[56:59]
	v_mfma_f32_16x16x32_bf16 v[44:47], v[128:131], v[210:213], v[44:47]
	v_mfma_f32_16x16x32_bf16 v[40:43], v[158:161], v[210:213], v[40:43]
	v_mfma_f32_16x16x32_bf16 v[28:31], v[128:131], v[218:221], v[28:31]
	v_mfma_f32_16x16x32_bf16 v[24:27], v[158:161], v[218:221], v[24:27]
	v_mfma_f32_16x16x32_bf16 v[12:15], v[128:131], v[226:229], v[12:15]
	v_mfma_f32_16x16x32_bf16 v[8:11], v[158:161], v[226:229], v[8:11]
	v_mfma_f32_16x16x32_bf16 v[60:63], v[132:135], v[206:209], v[60:63]
	v_mfma_f32_16x16x32_bf16 v[56:59], v[178:181], v[206:209], v[56:59]
	v_mfma_f32_16x16x32_bf16 v[44:47], v[132:135], v[214:217], v[44:47]
	v_mfma_f32_16x16x32_bf16 v[40:43], v[178:181], v[214:217], v[40:43]
	v_mfma_f32_16x16x32_bf16 v[28:31], v[132:135], v[222:225], v[28:31]
	v_mfma_f32_16x16x32_bf16 v[24:27], v[178:181], v[222:225], v[24:27]
	v_mfma_f32_16x16x32_bf16 v[12:15], v[132:135], v[230:233], v[12:15]
	v_mfma_f32_16x16x32_bf16 v[8:11], v[178:181], v[230:233], v[8:11]
	s_setprio 0
	s_setprio 1
	v_mfma_f32_16x16x32_bf16 v[52:55], v[182:185], v[198:201], v[52:55]
	v_mfma_f32_16x16x32_bf16 v[48:51], v[190:193], v[198:201], v[48:51]
	v_mfma_f32_16x16x32_bf16 v[36:39], v[182:185], v[210:213], v[36:39]
	v_mfma_f32_16x16x32_bf16 v[32:35], v[190:193], v[210:213], v[32:35]
	v_mfma_f32_16x16x32_bf16 v[20:23], v[182:185], v[218:221], v[20:23]
	v_mfma_f32_16x16x32_bf16 v[16:19], v[190:193], v[218:221], v[16:19]
	v_mfma_f32_16x16x32_bf16 v[4:7], v[182:185], v[226:229], v[4:7]
	v_mfma_f32_16x16x32_bf16 v[0:3], v[190:193], v[226:229], v[0:3]
	v_mfma_f32_16x16x32_bf16 v[52:55], v[186:189], v[206:209], v[52:55]
	v_mfma_f32_16x16x32_bf16 v[48:51], v[194:197], v[206:209], v[48:51]
	v_mfma_f32_16x16x32_bf16 v[36:39], v[186:189], v[214:217], v[36:39]
	v_mfma_f32_16x16x32_bf16 v[32:35], v[194:197], v[214:217], v[32:35]
	v_mfma_f32_16x16x32_bf16 v[20:23], v[186:189], v[222:225], v[20:23]
	v_mfma_f32_16x16x32_bf16 v[16:19], v[194:197], v[222:225], v[16:19]
	v_mfma_f32_16x16x32_bf16 v[4:7], v[186:189], v[230:233], v[4:7]
	v_mfma_f32_16x16x32_bf16 v[0:3], v[194:197], v[230:233], v[0:3]
	s_setprio 0
	s_barrier
	s_add_i32 s56, s56, 2
	s_add_u32 s26, s26, 0x100
	s_addc_u32 s27, s27, 0
	s_add_u32 s54, s54, 0x100
	s_addc_u32 s55, s55, 0
	s_cmp_gt_u32 s56, 13
	s_cbranch_scc0 .LBB0_335
	s_and_b64 vcc, exec, s[16:17]
	s_cbranch_vccz .LBB0_338
	s_barrier

.LBB0_467:
	s_andn2_b64 vcc, exec, s[8:9]
	s_cbranch_vccnz .LBB0_326
	v_writelane_b32 v255, 1, 53
	s_branch .LBB0_326

.LBB0_486:
	s_ashr_i32 s21, s20, 31
	s_lshl_b64 s[22:23], s[20:21], 19
	s_add_u32 s22, s39, s22
	s_addc_u32 s23, s40, s23
	s_and_b64 s[24:25], s[16:17], exec
	s_cselect_b32 s21, s23, s27
	s_cselect_b32 s53, s22, s26
	s_ashr_i32 s19, s18, 31
	s_lshl_b64 s[24:25], s[18:19], 19
	s_add_u32 s24, s36, s24
	s_addc_u32 s25, s37, s25
	s_and_b64 s[30:31], s[16:17], exec
	s_cselect_b32 s19, s25, s29
	s_cselect_b32 s54, s24, s28
	s_add_u32 s26, s26, 0x40080
	s_addc_u32 s27, s27, 0
	s_add_u32 s55, s28, 0x100
	v_mov_b32_e32 v0, 0
	s_addc_u32 s56, s29, 0
	s_mov_b32 s57, -2
	v_mov_b32_e32 v1, v0
	v_mov_b32_e32 v2, v0
	v_mov_b32_e32 v3, v0
	v_mov_b32_e32 v4, v0
	v_mov_b32_e32 v5, v0
	v_mov_b32_e32 v6, v0
	v_mov_b32_e32 v7, v0
	v_mov_b32_e32 v8, v0
	v_mov_b32_e32 v9, v0
	v_mov_b32_e32 v10, v0
	v_mov_b32_e32 v11, v0
	v_mov_b32_e32 v12, v0
	v_mov_b32_e32 v13, v0
	v_mov_b32_e32 v14, v0
	v_mov_b32_e32 v15, v0
	v_mov_b32_e32 v20, v0
	v_mov_b32_e32 v21, v0
	v_mov_b32_e32 v22, v0
	v_mov_b32_e32 v23, v0
	v_mov_b32_e32 v28, v0
	v_mov_b32_e32 v29, v0
	v_mov_b32_e32 v30, v0
	v_mov_b32_e32 v31, v0
	v_mov_b32_e32 v36, v0
	v_mov_b32_e32 v37, v0
	v_mov_b32_e32 v38, v0
	v_mov_b32_e32 v39, v0
	v_mov_b32_e32 v44, v0
	v_mov_b32_e32 v45, v0
	v_mov_b32_e32 v46, v0
	v_mov_b32_e32 v47, v0
	v_mov_b32_e32 v16, v0
	v_mov_b32_e32 v17, v0
	v_mov_b32_e32 v18, v0
	v_mov_b32_e32 v19, v0
	v_mov_b32_e32 v24, v0
	v_mov_b32_e32 v25, v0
	v_mov_b32_e32 v26, v0
	v_mov_b32_e32 v27, v0
	v_mov_b32_e32 v32, v0
	v_mov_b32_e32 v33, v0
	v_mov_b32_e32 v34, v0
	v_mov_b32_e32 v35, v0
	v_mov_b32_e32 v40, v0
	v_mov_b32_e32 v41, v0
	v_mov_b32_e32 v42, v0
	v_mov_b32_e32 v43, v0
	v_mov_b32_e32 v48, v0
	v_mov_b32_e32 v49, v0
	v_mov_b32_e32 v50, v0
	v_mov_b32_e32 v51, v0
	v_mov_b32_e32 v52, v0
	v_mov_b32_e32 v53, v0
	v_mov_b32_e32 v54, v0
	v_mov_b32_e32 v55, v0
	v_mov_b32_e32 v56, v0
	v_mov_b32_e32 v57, v0
	v_mov_b32_e32 v58, v0
	v_mov_b32_e32 v59, v0
	v_mov_b32_e32 v60, v0
	v_mov_b32_e32 v61, v0
	v_mov_b32_e32 v62, v0
	v_mov_b32_e32 v63, v0
	v_mov_b32_e32 v64, v0
	v_mov_b32_e32 v65, v0
	v_mov_b32_e32 v66, v0
	v_mov_b32_e32 v67, v0
	v_mov_b32_e32 v68, v0
	v_mov_b32_e32 v69, v0
	v_mov_b32_e32 v70, v0
	v_mov_b32_e32 v71, v0
	v_mov_b32_e32 v72, v0
	v_mov_b32_e32 v73, v0
	v_mov_b32_e32 v74, v0
	v_mov_b32_e32 v75, v0
	v_mov_b32_e32 v76, v0
	v_mov_b32_e32 v77, v0
	v_mov_b32_e32 v78, v0
	v_mov_b32_e32 v79, v0
	v_mov_b32_e32 v84, v0
	v_mov_b32_e32 v85, v0
	v_mov_b32_e32 v86, v0
	v_mov_b32_e32 v87, v0
	v_mov_b32_e32 v92, v0
	v_mov_b32_e32 v93, v0
	v_mov_b32_e32 v94, v0
	v_mov_b32_e32 v95, v0
	v_mov_b32_e32 v100, v0
	v_mov_b32_e32 v101, v0
	v_mov_b32_e32 v102, v0
	v_mov_b32_e32 v103, v0
	v_mov_b32_e32 v108, v0
	v_mov_b32_e32 v109, v0
	v_mov_b32_e32 v110, v0
	v_mov_b32_e32 v111, v0
	v_mov_b32_e32 v80, v0
	v_mov_b32_e32 v81, v0
	v_mov_b32_e32 v82, v0
	v_mov_b32_e32 v83, v0
	v_mov_b32_e32 v88, v0
	v_mov_b32_e32 v89, v0
	v_mov_b32_e32 v90, v0
	v_mov_b32_e32 v91, v0
	v_mov_b32_e32 v96, v0
	v_mov_b32_e32 v97, v0
	v_mov_b32_e32 v98, v0
	v_mov_b32_e32 v99, v0
	v_mov_b32_e32 v104, v0
	v_mov_b32_e32 v105, v0
	v_mov_b32_e32 v106, v0
	v_mov_b32_e32 v107, v0
	v_mov_b32_e32 v112, v0
	v_mov_b32_e32 v113, v0
	v_mov_b32_e32 v114, v0
	v_mov_b32_e32 v115, v0
	v_mov_b32_e32 v116, v0
	v_mov_b32_e32 v117, v0
	v_mov_b32_e32 v118, v0
	v_mov_b32_e32 v119, v0
	v_mov_b32_e32 v120, v0
	v_mov_b32_e32 v121, v0
	v_mov_b32_e32 v122, v0
	v_mov_b32_e32 v123, v0
	v_mov_b32_e32 v124, v0
	v_mov_b32_e32 v125, v0
	v_mov_b32_e32 v126, v0
	v_mov_b32_e32 v127, v0
	v_readlane_b32 s97, v255, 53
	s_nop 3
	s_cmp_eq_u32 s97, 1
	s_cbranch_scc0 .Llsb_skip_2
	v_writelane_b32 v255, 0, 53
	s_barrier
.Llsb_skip_2:
.LBB0_487:
	ds_read_b128 v[142:145], v135
	ds_read_b128 v[146:149], v135 offset:1024
	ds_read_b128 v[150:153], v135 offset:2048
	ds_read_b128 v[154:157], v135 offset:3072
	ds_read_b128 v[158:161], v140
	ds_read_b128 v[162:165], v140 offset:1024
	ds_read_b128 v[166:169], v140 offset:2048
	ds_read_b128 v[170:173], v140 offset:3072
	s_add_u32 s28, s26, 0xfffc0080
	s_addc_u32 s29, s27, -1
	s_cmp_eq_u32 s57, 12
	s_cselect_b32 s31, s21, s29
	s_cselect_b32 s30, s53, s28
	s_cselect_b32 s29, s19, s56
	s_cselect_b32 s28, s54, s55
	v_lshl_add_u64 v[202:203], s[26:27], 0, v[128:129]
	s_add_i32 m0, s41, 0xc000
	ds_read_b128 v[174:177], v141
	ds_read_b128 v[178:181], v141 offset:1024
	ds_read_b128 v[182:185], v141 offset:2048
	ds_read_b128 v[186:189], v141 offset:3072
	ds_read_b128 v[190:193], v141 offset:4096
	ds_read_b128 v[194:197], v141 offset:5120
	ds_read_b128 v[198:201], v141 offset:6144
	ds_read_b128 v[206:209], v141 offset:7168
	global_load_lds_dwordx4 v[202:203], off
	v_lshl_add_u64 v[202:203], s[26:27], 0, v[130:131]
	s_add_i32 m0, s41, 0xe000
	s_nop 0
	global_load_lds_dwordx4 v[202:203], off
	s_waitcnt vmcnt(8)
	s_waitcnt lgkmcnt(0)
	s_barrier
	s_setprio 1
	s_waitcnt lgkmcnt(0)
	v_mfma_f32_16x16x32_bf16 v[124:127], v[142:145], v[174:177], v[124:127]
	v_mfma_f32_16x16x32_bf16 v[120:123], v[150:153], v[174:177], v[120:123]
	v_mfma_f32_16x16x32_bf16 v[116:119], v[142:145], v[182:185], v[116:119]
	v_mfma_f32_16x16x32_bf16 v[112:115], v[150:153], v[182:185], v[112:115]
	v_mfma_f32_16x16x32_bf16 v[104:107], v[142:145], v[190:193], v[104:107]
	v_mfma_f32_16x16x32_bf16 v[96:99], v[150:153], v[190:193], v[96:99]
	v_mfma_f32_16x16x32_bf16 v[88:91], v[142:145], v[198:201], v[88:91]
	v_mfma_f32_16x16x32_bf16 v[80:83], v[150:153], v[198:201], v[80:83]
	v_mfma_f32_16x16x32_bf16 v[124:127], v[146:149], v[178:181], v[124:127]
	v_mfma_f32_16x16x32_bf16 v[120:123], v[154:157], v[178:181], v[120:123]
	v_mfma_f32_16x16x32_bf16 v[116:119], v[146:149], v[186:189], v[116:119]
	v_mfma_f32_16x16x32_bf16 v[112:115], v[154:157], v[186:189], v[112:115]
	v_mfma_f32_16x16x32_bf16 v[104:107], v[146:149], v[194:197], v[104:107]
	v_mfma_f32_16x16x32_bf16 v[96:99], v[154:157], v[194:197], v[96:99]
	v_mfma_f32_16x16x32_bf16 v[88:91], v[146:149], v[206:209], v[88:91]
	v_mfma_f32_16x16x32_bf16 v[80:83], v[154:157], v[206:209], v[80:83]
	s_setprio 0
	s_setprio 1
	v_mfma_f32_16x16x32_bf16 v[108:111], v[158:161], v[174:177], v[108:111]
	v_mfma_f32_16x16x32_bf16 v[100:103], v[166:169], v[174:177], v[100:103]
	v_mfma_f32_16x16x32_bf16 v[92:95], v[158:161], v[182:185], v[92:95]
	v_mfma_f32_16x16x32_bf16 v[84:87], v[166:169], v[182:185], v[84:87]
	v_mfma_f32_16x16x32_bf16 v[76:79], v[158:161], v[190:193], v[76:79]
	v_mfma_f32_16x16x32_bf16 v[72:75], v[166:169], v[190:193], v[72:75]
	v_mfma_f32_16x16x32_bf16 v[68:71], v[158:161], v[198:201], v[68:71]
	v_mfma_f32_16x16x32_bf16 v[64:67], v[166:169], v[198:201], v[64:67]
	v_mfma_f32_16x16x32_bf16 v[108:111], v[162:165], v[178:181], v[108:111]
	v_mfma_f32_16x16x32_bf16 v[100:103], v[170:173], v[178:181], v[100:103]
	v_mfma_f32_16x16x32_bf16 v[92:95], v[162:165], v[186:189], v[92:95]
	v_mfma_f32_16x16x32_bf16 v[84:87], v[170:173], v[186:189], v[84:87]
	v_mfma_f32_16x16x32_bf16 v[76:79], v[162:165], v[194:197], v[76:79]
	v_mfma_f32_16x16x32_bf16 v[72:75], v[170:173], v[194:197], v[72:75]
	v_mfma_f32_16x16x32_bf16 v[68:71], v[162:165], v[206:209], v[68:71]
	v_mfma_f32_16x16x32_bf16 v[64:67], v[170:173], v[206:209], v[64:67]
	s_setprio 0
	s_barrier
	s_add_i32 s58, s49, s38
	v_lshl_add_u64 v[202:203], s[28:29], 0, v[136:137]
	s_mov_b32 m0, s58
	ds_read_b128 v[174:177], v141 offset:16384
	ds_read_b128 v[178:181], v141 offset:17408
	ds_read_b128 v[182:185], v141 offset:18432
	ds_read_b128 v[186:189], v141 offset:19456
	ds_read_b128 v[190:193], v141 offset:20480
	ds_read_b128 v[194:197], v141 offset:21504
	ds_read_b128 v[198:201], v141 offset:22528
	ds_read_b128 v[206:209], v141 offset:23552
	global_load_lds_dwordx4 v[202:203], off
	s_add_i32 m0, s58, 0x2000
	s_add_u32 s58, s28, 0x40000
	v_lshl_add_u64 v[210:211], s[28:29], 0, v[138:139]
	s_addc_u32 s59, s29, 0
	s_add_i32 s60, s50, s38
	global_load_lds_dwordx4 v[210:211], off
	v_lshl_add_u64 v[212:213], s[58:59], 0, v[136:137]
	s_mov_b32 m0, s60
	v_lshl_add_u64 v[214:215], s[30:31], 0, v[138:139]
	global_load_lds_dwordx4 v[212:213], off
	v_lshl_add_u64 v[212:213], s[58:59], 0, v[138:139]
	s_add_i32 m0, s60, 0x2000
	s_nop 0
	global_load_lds_dwordx4 v[212:213], off
	v_lshl_add_u64 v[212:213], s[30:31], 0, v[136:137]
	s_mov_b32 m0, s41
	s_nop 0
	global_load_lds_dwordx4 v[212:213], off
	s_mov_b32 m0, s42
	s_nop 0
	global_load_lds_dwordx4 v[214:215], off
	s_waitcnt vmcnt(8)
	s_waitcnt lgkmcnt(0)
	s_barrier
	s_setprio 1
	s_waitcnt lgkmcnt(0)
	v_mfma_f32_16x16x32_bf16 v[60:63], v[142:145], v[174:177], v[60:63]
	v_mfma_f32_16x16x32_bf16 v[56:59], v[150:153], v[174:177], v[56:59]
	v_mfma_f32_16x16x32_bf16 v[52:55], v[142:145], v[182:185], v[52:55]
	v_mfma_f32_16x16x32_bf16 v[48:51], v[150:153], v[182:185], v[48:51]
	v_mfma_f32_16x16x32_bf16 v[40:43], v[142:145], v[190:193], v[40:43]
	v_mfma_f32_16x16x32_bf16 v[32:35], v[150:153], v[190:193], v[32:35]
	v_mfma_f32_16x16x32_bf16 v[24:27], v[142:145], v[198:201], v[24:27]
	v_mfma_f32_16x16x32_bf16 v[16:19], v[150:153], v[198:201], v[16:19]
	v_mfma_f32_16x16x32_bf16 v[60:63], v[146:149], v[178:181], v[60:63]
	v_mfma_f32_16x16x32_bf16 v[56:59], v[154:157], v[178:181], v[56:59]
	v_mfma_f32_16x16x32_bf16 v[52:55], v[146:149], v[186:189], v[52:55]
	v_mfma_f32_16x16x32_bf16 v[48:51], v[154:157], v[186:189], v[48:51]
	v_mfma_f32_16x16x32_bf16 v[40:43], v[146:149], v[194:197], v[40:43]
	v_mfma_f32_16x16x32_bf16 v[32:35], v[154:157], v[194:197], v[32:35]
	v_mfma_f32_16x16x32_bf16 v[24:27], v[146:149], v[206:209], v[24:27]
	v_mfma_f32_16x16x32_bf16 v[16:19], v[154:157], v[206:209], v[16:19]
	s_setprio 0
	s_setprio 1
	v_mfma_f32_16x16x32_bf16 v[44:47], v[158:161], v[174:177], v[44:47]
	v_mfma_f32_16x16x32_bf16 v[36:39], v[166:169], v[174:177], v[36:39]
	v_mfma_f32_16x16x32_bf16 v[28:31], v[158:161], v[182:185], v[28:31]
	v_mfma_f32_16x16x32_bf16 v[20:23], v[166:169], v[182:185], v[20:23]
	v_mfma_f32_16x16x32_bf16 v[12:15], v[158:161], v[190:193], v[12:15]
	v_mfma_f32_16x16x32_bf16 v[8:11], v[166:169], v[190:193], v[8:11]
	v_mfma_f32_16x16x32_bf16 v[4:7], v[158:161], v[198:201], v[4:7]
	v_mfma_f32_16x16x32_bf16 v[0:3], v[166:169], v[198:201], v[0:3]
	v_mfma_f32_16x16x32_bf16 v[44:47], v[162:165], v[178:181], v[44:47]
	v_mfma_f32_16x16x32_bf16 v[36:39], v[170:173], v[178:181], v[36:39]
	v_mfma_f32_16x16x32_bf16 v[28:31], v[162:165], v[186:189], v[28:31]
	v_mfma_f32_16x16x32_bf16 v[20:23], v[170:173], v[186:189], v[20:23]
	v_mfma_f32_16x16x32_bf16 v[12:15], v[162:165], v[194:197], v[12:15]
	v_mfma_f32_16x16x32_bf16 v[8:11], v[170:173], v[194:197], v[8:11]
	v_mfma_f32_16x16x32_bf16 v[4:7], v[162:165], v[206:209], v[4:7]
	v_mfma_f32_16x16x32_bf16 v[0:3], v[170:173], v[206:209], v[0:3]
	s_setprio 0
	s_barrier
	s_add_i32 s58, 0, 0x18000
	s_add_i32 s59, 0, 0x1c000
	v_add_u32_e32 v154, s58, v133
	v_add_u32_e32 v170, s59, v133
	ds_read_b128 v[142:145], v154
	ds_read_b128 v[146:149], v154 offset:1024
	ds_read_b128 v[150:153], v154 offset:2048
	ds_read_b128 v[154:157], v154 offset:3072
	ds_read_b128 v[158:161], v170
	ds_read_b128 v[162:165], v170 offset:1024
	ds_read_b128 v[166:169], v170 offset:2048
	ds_read_b128 v[170:173], v170 offset:3072
	s_add_u32 s30, s30, 0x40000
	s_addc_u32 s31, s31, 0
	s_mov_b32 m0, s43
	v_lshl_add_u64 v[216:217], s[30:31], 0, v[136:137]
	ds_read_b128 v[174:177], v141 offset:32768
	ds_read_b128 v[178:181], v141 offset:33792
	ds_read_b128 v[182:185], v141 offset:34816
	ds_read_b128 v[186:189], v141 offset:35840
	ds_read_b128 v[190:193], v141 offset:36864
	ds_read_b128 v[194:197], v141 offset:37888
	ds_read_b128 v[198:201], v141 offset:38912
	ds_read_b128 v[206:209], v141 offset:39936
	global_load_lds_dwordx4 v[216:217], off
	v_lshl_add_u64 v[216:217], s[30:31], 0, v[138:139]
	s_mov_b32 m0, s44
	s_nop 0
	global_load_lds_dwordx4 v[216:217], off
	s_waitcnt vmcnt(8)
	s_waitcnt lgkmcnt(0)
	s_barrier
	s_setprio 1
	s_waitcnt lgkmcnt(0)
	v_mfma_f32_16x16x32_bf16 v[124:127], v[142:145], v[174:177], v[124:127]
	v_mfma_f32_16x16x32_bf16 v[120:123], v[150:153], v[174:177], v[120:123]
	v_mfma_f32_16x16x32_bf16 v[116:119], v[142:145], v[182:185], v[116:119]
	v_mfma_f32_16x16x32_bf16 v[112:115], v[150:153], v[182:185], v[112:115]
	v_mfma_f32_16x16x32_bf16 v[104:107], v[142:145], v[190:193], v[104:107]
	v_mfma_f32_16x16x32_bf16 v[96:99], v[150:153], v[190:193], v[96:99]
	v_mfma_f32_16x16x32_bf16 v[88:91], v[142:145], v[198:201], v[88:91]
	v_mfma_f32_16x16x32_bf16 v[80:83], v[150:153], v[198:201], v[80:83]
	v_mfma_f32_16x16x32_bf16 v[124:127], v[146:149], v[178:181], v[124:127]
	v_mfma_f32_16x16x32_bf16 v[120:123], v[154:157], v[178:181], v[120:123]
	v_mfma_f32_16x16x32_bf16 v[116:119], v[146:149], v[186:189], v[116:119]
	v_mfma_f32_16x16x32_bf16 v[112:115], v[154:157], v[186:189], v[112:115]
	v_mfma_f32_16x16x32_bf16 v[104:107], v[146:149], v[194:197], v[104:107]
	v_mfma_f32_16x16x32_bf16 v[96:99], v[154:157], v[194:197], v[96:99]
	v_mfma_f32_16x16x32_bf16 v[88:91], v[146:149], v[206:209], v[88:91]
	v_mfma_f32_16x16x32_bf16 v[80:83], v[154:157], v[206:209], v[80:83]
	s_setprio 0
	s_setprio 1
	v_mfma_f32_16x16x32_bf16 v[108:111], v[158:161], v[174:177], v[108:111]
	v_mfma_f32_16x16x32_bf16 v[100:103], v[166:169], v[174:177], v[100:103]
	v_mfma_f32_16x16x32_bf16 v[92:95], v[158:161], v[182:185], v[92:95]
	v_mfma_f32_16x16x32_bf16 v[84:87], v[166:169], v[182:185], v[84:87]
	v_mfma_f32_16x16x32_bf16 v[76:79], v[158:161], v[190:193], v[76:79]
	v_mfma_f32_16x16x32_bf16 v[72:75], v[166:169], v[190:193], v[72:75]
	v_mfma_f32_16x16x32_bf16 v[68:71], v[158:161], v[198:201], v[68:71]
	v_mfma_f32_16x16x32_bf16 v[64:67], v[166:169], v[198:201], v[64:67]
	v_mfma_f32_16x16x32_bf16 v[108:111], v[162:165], v[178:181], v[108:111]
	v_mfma_f32_16x16x32_bf16 v[100:103], v[170:173], v[178:181], v[100:103]
	v_mfma_f32_16x16x32_bf16 v[92:95], v[162:165], v[186:189], v[92:95]
	v_mfma_f32_16x16x32_bf16 v[84:87], v[170:173], v[186:189], v[84:87]
	v_mfma_f32_16x16x32_bf16 v[76:79], v[162:165], v[194:197], v[76:79]
	v_mfma_f32_16x16x32_bf16 v[72:75], v[170:173], v[194:197], v[72:75]
	v_mfma_f32_16x16x32_bf16 v[68:71], v[162:165], v[206:209], v[68:71]
	v_mfma_f32_16x16x32_bf16 v[64:67], v[170:173], v[206:209], v[64:67]
	s_setprio 0
	s_barrier
	s_add_i32 s30, s58, s38
	v_lshl_add_u64 v[202:203], v[202:203], 0, s[6:7]
	s_mov_b32 m0, s30
	ds_read_b128 v[174:177], v141 offset:49152
	ds_read_b128 v[178:181], v141 offset:50176
	ds_read_b128 v[182:185], v141 offset:51200
	ds_read_b128 v[186:189], v141 offset:52224
	ds_read_b128 v[190:193], v141 offset:53248
	ds_read_b128 v[194:197], v141 offset:54272
	ds_read_b128 v[198:201], v141 offset:55296
	ds_read_b128 v[206:209], v141 offset:56320
	global_load_lds_dwordx4 v[202:203], off
	s_add_i32 m0, s30, 0x2000
	s_add_u32 s28, s28, 0x40080
	v_lshl_add_u64 v[202:203], v[210:211], 0, s[6:7]
	s_addc_u32 s29, s29, 0
	s_add_i32 s30, s59, s38
	global_load_lds_dwordx4 v[202:203], off
	v_lshl_add_u64 v[202:203], s[28:29], 0, v[136:137]
	s_mov_b32 m0, s30
	s_nop 0
	global_load_lds_dwordx4 v[202:203], off
	v_lshl_add_u64 v[202:203], s[28:29], 0, v[138:139]
	s_add_i32 m0, s30, 0x2000
	s_nop 0
	global_load_lds_dwordx4 v[202:203], off
	v_lshl_add_u64 v[202:203], v[212:213], 0, s[6:7]
	s_mov_b32 m0, s46
	s_nop 0
	global_load_lds_dwordx4 v[202:203], off
	v_lshl_add_u64 v[202:203], v[214:215], 0, s[6:7]
	s_mov_b32 m0, s47
	s_nop 0
	global_load_lds_dwordx4 v[202:203], off
	s_waitcnt vmcnt(8)
	s_waitcnt lgkmcnt(0)
	s_barrier
	s_setprio 1
	s_waitcnt lgkmcnt(0)
	v_mfma_f32_16x16x32_bf16 v[60:63], v[142:145], v[174:177], v[60:63]
	v_mfma_f32_16x16x32_bf16 v[56:59], v[150:153], v[174:177], v[56:59]
	v_mfma_f32_16x16x32_bf16 v[52:55], v[142:145], v[182:185], v[52:55]
	v_mfma_f32_16x16x32_bf16 v[48:51], v[150:153], v[182:185], v[48:51]
	v_mfma_f32_16x16x32_bf16 v[40:43], v[142:145], v[190:193], v[40:43]
	v_mfma_f32_16x16x32_bf16 v[32:35], v[150:153], v[190:193], v[32:35]
	v_mfma_f32_16x16x32_bf16 v[24:27], v[142:145], v[198:201], v[24:27]
	v_mfma_f32_16x16x32_bf16 v[16:19], v[150:153], v[198:201], v[16:19]
	v_mfma_f32_16x16x32_bf16 v[60:63], v[146:149], v[178:181], v[60:63]
	v_mfma_f32_16x16x32_bf16 v[56:59], v[154:157], v[178:181], v[56:59]
	v_mfma_f32_16x16x32_bf16 v[52:55], v[146:149], v[186:189], v[52:55]
	v_mfma_f32_16x16x32_bf16 v[48:51], v[154:157], v[186:189], v[48:51]
	v_mfma_f32_16x16x32_bf16 v[40:43], v[146:149], v[194:197], v[40:43]
	v_mfma_f32_16x16x32_bf16 v[32:35], v[154:157], v[194:197], v[32:35]
	v_mfma_f32_16x16x32_bf16 v[24:27], v[146:149], v[206:209], v[24:27]
	v_mfma_f32_16x16x32_bf16 v[16:19], v[154:157], v[206:209], v[16:19]
	s_setprio 0
	s_setprio 1
	v_mfma_f32_16x16x32_bf16 v[44:47], v[158:161], v[174:177], v[44:47]
	v_mfma_f32_16x16x32_bf16 v[36:39], v[166:169], v[174:177], v[36:39]
	v_mfma_f32_16x16x32_bf16 v[28:31], v[158:161], v[182:185], v[28:31]
	v_mfma_f32_16x16x32_bf16 v[20:23], v[166:169], v[182:185], v[20:23]
	v_mfma_f32_16x16x32_bf16 v[12:15], v[158:161], v[190:193], v[12:15]
	v_mfma_f32_16x16x32_bf16 v[8:11], v[166:169], v[190:193], v[8:11]
	v_mfma_f32_16x16x32_bf16 v[4:7], v[158:161], v[198:201], v[4:7]
	v_mfma_f32_16x16x32_bf16 v[0:3], v[166:169], v[198:201], v[0:3]
	v_mfma_f32_16x16x32_bf16 v[44:47], v[162:165], v[178:181], v[44:47]
	v_mfma_f32_16x16x32_bf16 v[36:39], v[170:173], v[178:181], v[36:39]
	v_mfma_f32_16x16x32_bf16 v[28:31], v[162:165], v[186:189], v[28:31]
	v_mfma_f32_16x16x32_bf16 v[20:23], v[170:173], v[186:189], v[20:23]
	v_mfma_f32_16x16x32_bf16 v[12:15], v[162:165], v[194:197], v[12:15]
	v_mfma_f32_16x16x32_bf16 v[8:11], v[170:173], v[194:197], v[8:11]
	v_mfma_f32_16x16x32_bf16 v[4:7], v[162:165], v[206:209], v[4:7]
	v_mfma_f32_16x16x32_bf16 v[0:3], v[170:173], v[206:209], v[0:3]
	s_setprio 0
	s_barrier
	s_add_i32 s57, s57, 2
	s_add_u32 s26, s26, 0x100
	s_addc_u32 s27, s27, 0
	s_add_u32 s55, s55, 0x100
	s_addc_u32 s56, s56, 0
	s_cmp_gt_u32 s57, 13
	s_cbranch_scc0 .LBB0_487
	s_and_b64 vcc, exec, s[10:11]
	s_cbranch_vccz .LBB0_490
	s_barrier
.LBB0_490:
	v_lshl_add_u32 v142, s8, 8, v132
	v_lshl_or_b32 v144, s9, 8, v134
	v_ashrrev_i32_e32 v143, 31, v142
	v_ashrrev_i32_e32 v145, 31, v144
	v_lshlrev_b64 v[146:147], 12, v[142:143]
	v_lshl_add_u64 v[146:147], s[4:5], 0, v[146:147]
	v_lshlrev_b64 v[144:145], 2, v[144:145]
	v_lshl_add_u64 v[146:147], v[146:147], 0, v[144:145]
	global_store_dwordx4 v[146:147], v[124:127], off
	global_store_dwordx4 v[146:147], v[120:123], off offset:64
	global_store_dwordx4 v[146:147], v[108:111], off offset:512
	global_store_dwordx4 v[146:147], v[100:103], off offset:576
	s_mov_b64 s[8:9], 0x80000
	s_nop 0
	v_or_b32_e32 v100, 16, v142
	v_ashrrev_i32_e32 v101, 31, v100
	v_lshlrev_b64 v[100:101], 12, v[100:101]
	v_lshl_add_u64 v[100:101], s[4:5], 0, v[100:101]
	v_lshl_add_u64 v[100:101], v[100:101], 0, v[144:145]
	global_store_dwordx4 v[100:101], v[116:119], off
	global_store_dwordx4 v[100:101], v[112:115], off offset:64
	global_store_dwordx4 v[100:101], v[92:95], off offset:512
	global_store_dwordx4 v[100:101], v[84:87], off offset:576
	s_nop 1
	v_or_b32_e32 v84, 32, v142
	v_ashrrev_i32_e32 v85, 31, v84
	v_lshlrev_b64 v[84:85], 12, v[84:85]
	v_lshl_add_u64 v[84:85], s[4:5], 0, v[84:85]
	v_lshl_add_u64 v[84:85], v[84:85], 0, v[144:145]
	global_store_dwordx4 v[84:85], v[104:107], off
	global_store_dwordx4 v[84:85], v[96:99], off offset:64
	global_store_dwordx4 v[84:85], v[76:79], off offset:512
	global_store_dwordx4 v[84:85], v[72:75], off offset:576
	s_nop 1
	v_or_b32_e32 v72, 48, v142
	v_ashrrev_i32_e32 v73, 31, v72
	v_lshlrev_b64 v[72:73], 12, v[72:73]
	v_lshl_add_u64 v[72:73], s[4:5], 0, v[72:73]
	v_lshl_add_u64 v[72:73], v[72:73], 0, v[144:145]
	global_store_dwordx4 v[72:73], v[88:91], off
	global_store_dwordx4 v[72:73], v[80:83], off offset:64
	global_store_dwordx4 v[72:73], v[68:71], off offset:512
	global_store_dwordx4 v[72:73], v[64:67], off offset:576
	s_nop 1
	v_lshl_add_u64 v[64:65], v[146:147], 0, s[8:9]
	s_mov_b32 s8, 0x80000
	v_add_co_u32_e32 v66, vcc, s8, v146
	s_mov_b64 s[8:9], 0x90000
	s_nop 0
	v_addc_co_u32_e32 v67, vcc, 0, v147, vcc
	global_store_dwordx4 v[66:67], v[60:63], off
	global_store_dwordx4 v[64:65], v[56:59], off offset:64
	global_store_dwordx4 v[64:65], v[44:47], off offset:512
	global_store_dwordx4 v[64:65], v[36:39], off offset:576
	s_nop 1
	v_add_co_u32_e32 v38, vcc, s51, v146
	v_lshl_add_u64 v[36:37], v[146:147], 0, s[8:9]
	s_nop 0
	v_addc_co_u32_e32 v39, vcc, 0, v147, vcc
	global_store_dwordx4 v[38:39], v[52:55], off
	global_store_dwordx4 v[36:37], v[48:51], off offset:64
	global_store_dwordx4 v[36:37], v[28:31], off offset:512
	global_store_dwordx4 v[36:37], v[20:23], off offset:576
	s_mov_b64 s[8:9], -1
	s_nop 0
	v_add_co_u32_e32 v22, vcc, s52, v146
	v_lshl_add_u64 v[20:21], v[146:147], 0, s[12:13]
	s_nop 0
	v_addc_co_u32_e32 v23, vcc, 0, v147, vcc
	global_store_dwordx4 v[22:23], v[40:43], off
	global_store_dwordx4 v[20:21], v[32:35], off offset:64
	global_store_dwordx4 v[20:21], v[12:15], off offset:512
	global_store_dwordx4 v[20:21], v[8:11], off offset:576
	s_nop 1
	v_add_co_u32_e32 v10, vcc, 0xb0000, v146
	v_lshl_add_u64 v[8:9], v[146:147], 0, s[14:15]
	s_nop 0
	v_addc_co_u32_e32 v11, vcc, 0, v147, vcc
	s_andn2_b64 vcc, exec, s[16:17]
	global_store_dwordx4 v[10:11], v[24:27], off
	global_store_dwordx4 v[8:9], v[16:19], off offset:64
	global_store_dwordx4 v[8:9], v[4:7], off offset:512
	global_store_dwordx4 v[8:9], v[0:3], off offset:576
	s_cbranch_vccnz .LBB0_479
	s_andn2_b64 vcc, exec, s[2:3]
	s_cbranch_vccnz .LBB0_478
	v_writelane_b32 v255, 1, 53
	s_branch .LBB0_478

.LBB0_790:
	s_add_u32 s22, s22, 0x28080
	s_addc_u32 s23, s23, 0
	s_add_u32 s54, s24, 0x100
	v_mov_b32_e32 v0, 0
	s_addc_u32 s55, s25, 0
	s_mov_b32 s56, -2
	v_mov_b32_e32 v1, v0
	v_mov_b32_e32 v2, v0
	v_mov_b32_e32 v3, v0
	v_mov_b32_e32 v4, v0
	v_mov_b32_e32 v5, v0
	v_mov_b32_e32 v6, v0
	v_mov_b32_e32 v7, v0
	v_mov_b32_e32 v16, v0
	v_mov_b32_e32 v17, v0
	v_mov_b32_e32 v18, v0
	v_mov_b32_e32 v19, v0
	v_mov_b32_e32 v20, v0
	v_mov_b32_e32 v21, v0
	v_mov_b32_e32 v22, v0
	v_mov_b32_e32 v23, v0
	v_mov_b32_e32 v32, v0
	v_mov_b32_e32 v33, v0
	v_mov_b32_e32 v34, v0
	v_mov_b32_e32 v35, v0
	v_mov_b32_e32 v36, v0
	v_mov_b32_e32 v37, v0
	v_mov_b32_e32 v38, v0
	v_mov_b32_e32 v39, v0
	v_mov_b32_e32 v56, v0
	v_mov_b32_e32 v57, v0
	v_mov_b32_e32 v58, v0
	v_mov_b32_e32 v59, v0
	v_mov_b32_e32 v60, v0
	v_mov_b32_e32 v61, v0
	v_mov_b32_e32 v62, v0
	v_mov_b32_e32 v63, v0
	v_mov_b32_e32 v8, v0
	v_mov_b32_e32 v9, v0
	v_mov_b32_e32 v10, v0
	v_mov_b32_e32 v11, v0
	v_mov_b32_e32 v12, v0
	v_mov_b32_e32 v13, v0
	v_mov_b32_e32 v14, v0
	v_mov_b32_e32 v15, v0
	v_mov_b32_e32 v24, v0
	v_mov_b32_e32 v25, v0
	v_mov_b32_e32 v26, v0
	v_mov_b32_e32 v27, v0
	v_mov_b32_e32 v28, v0
	v_mov_b32_e32 v29, v0
	v_mov_b32_e32 v30, v0
	v_mov_b32_e32 v31, v0
	v_mov_b32_e32 v40, v0
	v_mov_b32_e32 v41, v0
	v_mov_b32_e32 v42, v0
	v_mov_b32_e32 v43, v0
	v_mov_b32_e32 v48, v0
	v_mov_b32_e32 v49, v0
	v_mov_b32_e32 v50, v0
	v_mov_b32_e32 v51, v0
	v_mov_b32_e32 v64, v0
	v_mov_b32_e32 v65, v0
	v_mov_b32_e32 v66, v0
	v_mov_b32_e32 v67, v0
	v_mov_b32_e32 v68, v0
	v_mov_b32_e32 v69, v0
	v_mov_b32_e32 v70, v0
	v_mov_b32_e32 v71, v0
	v_mov_b32_e32 v72, v0
	v_mov_b32_e32 v73, v0
	v_mov_b32_e32 v74, v0
	v_mov_b32_e32 v75, v0
	v_mov_b32_e32 v76, v0
	v_mov_b32_e32 v77, v0
	v_mov_b32_e32 v78, v0
	v_mov_b32_e32 v79, v0
	v_mov_b32_e32 v88, v0
	v_mov_b32_e32 v89, v0
	v_mov_b32_e32 v90, v0
	v_mov_b32_e32 v91, v0
	v_mov_b32_e32 v92, v0
	v_mov_b32_e32 v93, v0
	v_mov_b32_e32 v94, v0
	v_mov_b32_e32 v95, v0
	v_mov_b32_e32 v104, v0
	v_mov_b32_e32 v105, v0
	v_mov_b32_e32 v106, v0
	v_mov_b32_e32 v107, v0
	v_mov_b32_e32 v108, v0
	v_mov_b32_e32 v109, v0
	v_mov_b32_e32 v110, v0
	v_mov_b32_e32 v111, v0
	v_mov_b32_e32 v128, v0
	v_mov_b32_e32 v129, v0
	v_mov_b32_e32 v130, v0
	v_mov_b32_e32 v131, v0
	v_mov_b32_e32 v132, v0
	v_mov_b32_e32 v133, v0
	v_mov_b32_e32 v134, v0
	v_mov_b32_e32 v135, v0
	v_mov_b32_e32 v80, v0
	v_mov_b32_e32 v81, v0
	v_mov_b32_e32 v82, v0
	v_mov_b32_e32 v83, v0
	v_mov_b32_e32 v84, v0
	v_mov_b32_e32 v85, v0
	v_mov_b32_e32 v86, v0
	v_mov_b32_e32 v87, v0
	v_mov_b32_e32 v96, v0
	v_mov_b32_e32 v97, v0
	v_mov_b32_e32 v98, v0
	v_mov_b32_e32 v99, v0
	v_mov_b32_e32 v100, v0
	v_mov_b32_e32 v101, v0
	v_mov_b32_e32 v102, v0
	v_mov_b32_e32 v103, v0
	v_mov_b32_e32 v116, v0
	v_mov_b32_e32 v117, v0
	v_mov_b32_e32 v118, v0
	v_mov_b32_e32 v119, v0
	v_mov_b32_e32 v120, v0
	v_mov_b32_e32 v121, v0
	v_mov_b32_e32 v122, v0
	v_mov_b32_e32 v123, v0
	v_mov_b32_e32 v140, v0
	v_mov_b32_e32 v141, v0
	v_mov_b32_e32 v142, v0
	v_mov_b32_e32 v143, v0
	v_mov_b32_e32 v144, v0
	v_mov_b32_e32 v145, v0
	v_mov_b32_e32 v146, v0
	v_mov_b32_e32 v147, v0
	v_readlane_b32 s97, v255, 53
	s_nop 3
	s_cmp_eq_u32 s97, 1
	s_cbranch_scc0 .Llsb_skip_3
	v_writelane_b32 v255, 0, 53
	s_barrier
.Llsb_skip_3:
.LBB0_791:
	ds_read_b128 v[44:47], v200
	ds_read_b128 v[52:55], v200 offset:1024
	ds_read_b128 v[112:115], v200 offset:2048
	ds_read_b128 v[124:127], v200 offset:3072
	ds_read_b128 v[136:139], v201
	ds_read_b128 v[148:151], v201 offset:1024
	ds_read_b128 v[152:155], v201 offset:2048
	ds_read_b128 v[156:159], v201 offset:3072
	s_add_u32 s24, s22, 0xfffd8080
	s_addc_u32 s25, s23, -1
	s_cmp_eq_u32 s56, 6
	s_cselect_b32 s27, s19, s25
	s_cselect_b32 s26, s18, s24
	s_cselect_b32 s25, s21, s55
	s_cselect_b32 s24, s20, s54
	s_mov_b32 m0, s39
	v_lshl_add_u64 v[236:237], s[22:23], 0, v[178:179]
	ds_read_b128 v[160:163], v202
	ds_read_b128 v[208:211], v202 offset:1024
	ds_read_b128 v[212:215], v202 offset:2048
	ds_read_b128 v[216:219], v202 offset:3072
	ds_read_b128 v[220:223], v202 offset:4096
	ds_read_b128 v[224:227], v202 offset:5120
	ds_read_b128 v[228:231], v202 offset:6144
	ds_read_b128 v[232:235], v202 offset:7168
	global_load_lds_dwordx4 v[236:237], off
	v_lshl_add_u64 v[236:237], s[22:23], 0, v[180:181]
	s_mov_b32 m0, s40
	s_nop 0
	global_load_lds_dwordx4 v[236:237], off
	s_waitcnt vmcnt(8)
	s_waitcnt lgkmcnt(0)
	s_barrier
	s_setprio 1
	s_waitcnt lgkmcnt(0)
	v_mfma_f32_16x16x32_bf16 v[144:147], v[44:47], v[160:163], v[144:147]
	v_mfma_f32_16x16x32_bf16 v[140:143], v[112:115], v[160:163], v[140:143]
	v_mfma_f32_16x16x32_bf16 v[120:123], v[44:47], v[212:215], v[120:123]
	v_mfma_f32_16x16x32_bf16 v[116:119], v[112:115], v[212:215], v[116:119]
	v_mfma_f32_16x16x32_bf16 v[100:103], v[44:47], v[220:223], v[100:103]
	v_mfma_f32_16x16x32_bf16 v[96:99], v[112:115], v[220:223], v[96:99]
	v_mfma_f32_16x16x32_bf16 v[84:87], v[44:47], v[228:231], v[84:87]
	v_mfma_f32_16x16x32_bf16 v[80:83], v[112:115], v[228:231], v[80:83]
	v_mfma_f32_16x16x32_bf16 v[144:147], v[52:55], v[208:211], v[144:147]
	v_mfma_f32_16x16x32_bf16 v[140:143], v[124:127], v[208:211], v[140:143]
	v_mfma_f32_16x16x32_bf16 v[120:123], v[52:55], v[216:219], v[120:123]
	v_mfma_f32_16x16x32_bf16 v[116:119], v[124:127], v[216:219], v[116:119]
	v_mfma_f32_16x16x32_bf16 v[100:103], v[52:55], v[224:227], v[100:103]
	v_mfma_f32_16x16x32_bf16 v[96:99], v[124:127], v[224:227], v[96:99]
	v_mfma_f32_16x16x32_bf16 v[84:87], v[52:55], v[232:235], v[84:87]
	v_mfma_f32_16x16x32_bf16 v[80:83], v[124:127], v[232:235], v[80:83]
	s_setprio 0
	s_setprio 1
	v_mfma_f32_16x16x32_bf16 v[132:135], v[136:139], v[160:163], v[132:135]
	v_mfma_f32_16x16x32_bf16 v[128:131], v[152:155], v[160:163], v[128:131]
	v_mfma_f32_16x16x32_bf16 v[108:111], v[136:139], v[212:215], v[108:111]
	v_mfma_f32_16x16x32_bf16 v[104:107], v[152:155], v[212:215], v[104:107]
	v_mfma_f32_16x16x32_bf16 v[92:95], v[136:139], v[220:223], v[92:95]
	v_mfma_f32_16x16x32_bf16 v[88:91], v[152:155], v[220:223], v[88:91]
	v_mfma_f32_16x16x32_bf16 v[76:79], v[136:139], v[228:231], v[76:79]
	v_mfma_f32_16x16x32_bf16 v[72:75], v[152:155], v[228:231], v[72:75]
	v_mfma_f32_16x16x32_bf16 v[132:135], v[148:151], v[208:211], v[132:135]
	v_mfma_f32_16x16x32_bf16 v[128:131], v[156:159], v[208:211], v[128:131]
	v_mfma_f32_16x16x32_bf16 v[108:111], v[148:151], v[216:219], v[108:111]
	v_mfma_f32_16x16x32_bf16 v[104:107], v[156:159], v[216:219], v[104:107]
	v_mfma_f32_16x16x32_bf16 v[92:95], v[148:151], v[224:227], v[92:95]
	v_mfma_f32_16x16x32_bf16 v[88:91], v[156:159], v[224:227], v[88:91]
	v_mfma_f32_16x16x32_bf16 v[76:79], v[148:151], v[232:235], v[76:79]
	v_mfma_f32_16x16x32_bf16 v[72:75], v[156:159], v[232:235], v[72:75]
	s_setprio 0
	s_barrier
	s_mov_b32 m0, s41
	v_lshl_add_u64 v[236:237], s[24:25], 0, v[168:169]
	s_add_u32 s58, s24, 0x28000
	ds_read_b128 v[160:163], v202 offset:16384
	ds_read_b128 v[208:211], v202 offset:17408
	ds_read_b128 v[212:215], v202 offset:18432
	ds_read_b128 v[216:219], v202 offset:19456
	ds_read_b128 v[220:223], v202 offset:20480
	ds_read_b128 v[224:227], v202 offset:21504
	ds_read_b128 v[228:231], v202 offset:22528
	ds_read_b128 v[232:235], v202 offset:23552
	global_load_lds_dwordx4 v[236:237], off
	v_lshl_add_u64 v[238:239], s[24:25], 0, v[164:165]
	s_mov_b32 m0, s43
	s_addc_u32 s59, s25, 0
	global_load_lds_dwordx4 v[238:239], off
	v_lshl_add_u64 v[240:241], s[58:59], 0, v[168:169]
	s_mov_b32 m0, s44
	v_lshl_add_u64 v[242:243], s[26:27], 0, v[166:167]
	global_load_lds_dwordx4 v[240:241], off
	v_lshl_add_u64 v[240:241], s[58:59], 0, v[164:165]
	s_mov_b32 m0, s45
	s_nop 0
	global_load_lds_dwordx4 v[240:241], off
	v_lshl_add_u64 v[240:241], s[26:27], 0, v[170:171]
	s_mov_b32 m0, s30
	s_nop 0
	global_load_lds_dwordx4 v[240:241], off
	s_mov_b32 m0, s31
	s_nop 0
	global_load_lds_dwordx4 v[242:243], off
	s_waitcnt vmcnt(8)
	s_waitcnt lgkmcnt(0)
	s_barrier
	s_setprio 1
	s_waitcnt lgkmcnt(0)
	v_mfma_f32_16x16x32_bf16 v[68:71], v[44:47], v[160:163], v[68:71]
	v_mfma_f32_16x16x32_bf16 v[64:67], v[112:115], v[160:163], v[64:67]
	v_mfma_f32_16x16x32_bf16 v[48:51], v[44:47], v[212:215], v[48:51]
	v_mfma_f32_16x16x32_bf16 v[40:43], v[112:115], v[212:215], v[40:43]
	v_mfma_f32_16x16x32_bf16 v[28:31], v[44:47], v[220:223], v[28:31]
	v_mfma_f32_16x16x32_bf16 v[24:27], v[112:115], v[220:223], v[24:27]
	v_mfma_f32_16x16x32_bf16 v[12:15], v[44:47], v[228:231], v[12:15]
	v_mfma_f32_16x16x32_bf16 v[8:11], v[112:115], v[228:231], v[8:11]
	v_mfma_f32_16x16x32_bf16 v[68:71], v[52:55], v[208:211], v[68:71]
	v_mfma_f32_16x16x32_bf16 v[64:67], v[124:127], v[208:211], v[64:67]
	v_mfma_f32_16x16x32_bf16 v[48:51], v[52:55], v[216:219], v[48:51]
	v_mfma_f32_16x16x32_bf16 v[40:43], v[124:127], v[216:219], v[40:43]
	v_mfma_f32_16x16x32_bf16 v[28:31], v[52:55], v[224:227], v[28:31]
	v_mfma_f32_16x16x32_bf16 v[24:27], v[124:127], v[224:227], v[24:27]
	v_mfma_f32_16x16x32_bf16 v[12:15], v[52:55], v[232:235], v[12:15]
	v_mfma_f32_16x16x32_bf16 v[8:11], v[124:127], v[232:235], v[8:11]
	s_setprio 0
	s_setprio 1
	v_mfma_f32_16x16x32_bf16 v[36:39], v[136:139], v[212:215], v[36:39]
	v_mfma_f32_16x16x32_bf16 v[32:35], v[152:155], v[212:215], v[32:35]
	v_mfma_f32_16x16x32_bf16 v[20:23], v[136:139], v[220:223], v[20:23]
	v_mfma_f32_16x16x32_bf16 v[16:19], v[152:155], v[220:223], v[16:19]
	v_mfma_f32_16x16x32_bf16 v[4:7], v[136:139], v[228:231], v[4:7]
	v_mfma_f32_16x16x32_bf16 v[0:3], v[152:155], v[228:231], v[0:3]
	v_mfma_f32_16x16x32_bf16 v[44:47], v[136:139], v[160:163], v[60:63]
	v_mfma_f32_16x16x32_bf16 v[52:55], v[152:155], v[160:163], v[56:59]
	v_mfma_f32_16x16x32_bf16 v[36:39], v[148:151], v[216:219], v[36:39]
	v_mfma_f32_16x16x32_bf16 v[32:35], v[156:159], v[216:219], v[32:35]
	v_mfma_f32_16x16x32_bf16 v[20:23], v[148:151], v[224:227], v[20:23]
	v_mfma_f32_16x16x32_bf16 v[16:19], v[156:159], v[224:227], v[16:19]
	v_mfma_f32_16x16x32_bf16 v[4:7], v[148:151], v[232:235], v[4:7]
	v_mfma_f32_16x16x32_bf16 v[0:3], v[156:159], v[232:235], v[0:3]
	v_mfma_f32_16x16x32_bf16 v[44:47], v[148:151], v[208:211], v[44:47]
	v_mfma_f32_16x16x32_bf16 v[52:55], v[156:159], v[208:211], v[52:55]
	s_setprio 0
	s_barrier
	ds_read_b128 v[56:59], v203
	ds_read_b128 v[60:63], v203 offset:1024
	ds_read_b128 v[112:115], v203 offset:2048
	ds_read_b128 v[124:127], v203 offset:3072
	ds_read_b128 v[136:139], v205
	ds_read_b128 v[148:151], v205 offset:1024
	ds_read_b128 v[152:155], v205 offset:2048
	ds_read_b128 v[156:159], v205 offset:3072
	s_add_u32 s26, s26, 0x28000
	s_addc_u32 s27, s27, 0
	s_mov_b32 m0, s33
	v_lshl_add_u64 v[244:245], s[26:27], 0, v[170:171]
	ds_read_b128 v[160:163], v202 offset:32768
	ds_read_b128 v[208:211], v202 offset:33792
	ds_read_b128 v[212:215], v202 offset:34816
	ds_read_b128 v[216:219], v202 offset:35840
	ds_read_b128 v[220:223], v202 offset:36864
	ds_read_b128 v[224:227], v202 offset:37888
	ds_read_b128 v[228:231], v202 offset:38912
	ds_read_b128 v[232:235], v202 offset:39936
	global_load_lds_dwordx4 v[244:245], off
	v_lshl_add_u64 v[244:245], s[26:27], 0, v[166:167]
	s_mov_b32 m0, s34
	s_nop 0
	global_load_lds_dwordx4 v[244:245], off
	s_waitcnt vmcnt(8)
	s_waitcnt lgkmcnt(0)
	s_barrier
	s_setprio 1
	s_waitcnt lgkmcnt(0)
	v_mfma_f32_16x16x32_bf16 v[144:147], v[56:59], v[160:163], v[144:147]
	v_mfma_f32_16x16x32_bf16 v[140:143], v[112:115], v[160:163], v[140:143]
	v_mfma_f32_16x16x32_bf16 v[120:123], v[56:59], v[212:215], v[120:123]
	v_mfma_f32_16x16x32_bf16 v[116:119], v[112:115], v[212:215], v[116:119]
	v_mfma_f32_16x16x32_bf16 v[100:103], v[56:59], v[220:223], v[100:103]
	v_mfma_f32_16x16x32_bf16 v[96:99], v[112:115], v[220:223], v[96:99]
	v_mfma_f32_16x16x32_bf16 v[84:87], v[56:59], v[228:231], v[84:87]
	v_mfma_f32_16x16x32_bf16 v[80:83], v[112:115], v[228:231], v[80:83]
	v_mfma_f32_16x16x32_bf16 v[144:147], v[60:63], v[208:211], v[144:147]
	v_mfma_f32_16x16x32_bf16 v[140:143], v[124:127], v[208:211], v[140:143]
	v_mfma_f32_16x16x32_bf16 v[120:123], v[60:63], v[216:219], v[120:123]
	v_mfma_f32_16x16x32_bf16 v[116:119], v[124:127], v[216:219], v[116:119]
	v_mfma_f32_16x16x32_bf16 v[100:103], v[60:63], v[224:227], v[100:103]
	v_mfma_f32_16x16x32_bf16 v[96:99], v[124:127], v[224:227], v[96:99]
	v_mfma_f32_16x16x32_bf16 v[84:87], v[60:63], v[232:235], v[84:87]
	v_mfma_f32_16x16x32_bf16 v[80:83], v[124:127], v[232:235], v[80:83]
	s_setprio 0
	s_setprio 1
	v_mfma_f32_16x16x32_bf16 v[132:135], v[136:139], v[160:163], v[132:135]
	v_mfma_f32_16x16x32_bf16 v[128:131], v[152:155], v[160:163], v[128:131]
	v_mfma_f32_16x16x32_bf16 v[108:111], v[136:139], v[212:215], v[108:111]
	v_mfma_f32_16x16x32_bf16 v[104:107], v[152:155], v[212:215], v[104:107]
	v_mfma_f32_16x16x32_bf16 v[92:95], v[136:139], v[220:223], v[92:95]
	v_mfma_f32_16x16x32_bf16 v[88:91], v[152:155], v[220:223], v[88:91]
	v_mfma_f32_16x16x32_bf16 v[76:79], v[136:139], v[228:231], v[76:79]
	v_mfma_f32_16x16x32_bf16 v[72:75], v[152:155], v[228:231], v[72:75]
	v_mfma_f32_16x16x32_bf16 v[132:135], v[148:151], v[208:211], v[132:135]
	v_mfma_f32_16x16x32_bf16 v[128:131], v[156:159], v[208:211], v[128:131]
	v_mfma_f32_16x16x32_bf16 v[108:111], v[148:151], v[216:219], v[108:111]
	v_mfma_f32_16x16x32_bf16 v[104:107], v[156:159], v[216:219], v[104:107]
	v_mfma_f32_16x16x32_bf16 v[92:95], v[148:151], v[224:227], v[92:95]
	v_mfma_f32_16x16x32_bf16 v[88:91], v[156:159], v[224:227], v[88:91]
	v_mfma_f32_16x16x32_bf16 v[76:79], v[148:151], v[232:235], v[76:79]
	v_mfma_f32_16x16x32_bf16 v[72:75], v[156:159], v[232:235], v[72:75]
	s_setprio 0
	s_barrier
	s_mov_b32 m0, s46
	v_lshl_add_u64 v[236:237], v[236:237], 0, s[14:15]
	s_add_u32 s24, s24, 0x28080
	ds_read_b128 v[160:163], v202 offset:49152
	ds_read_b128 v[208:211], v202 offset:50176
	ds_read_b128 v[212:215], v202 offset:51200
	ds_read_b128 v[216:219], v202 offset:52224
	ds_read_b128 v[220:223], v202 offset:53248
	ds_read_b128 v[224:227], v202 offset:54272
	ds_read_b128 v[228:231], v202 offset:55296
	ds_read_b128 v[232:235], v202 offset:56320
	global_load_lds_dwordx4 v[236:237], off
	v_lshl_add_u64 v[236:237], v[238:239], 0, s[14:15]
	s_mov_b32 m0, s47
	s_addc_u32 s25, s25, 0
	global_load_lds_dwordx4 v[236:237], off
	v_lshl_add_u64 v[236:237], s[24:25], 0, v[168:169]
	s_mov_b32 m0, s48
	s_nop 0
	global_load_lds_dwordx4 v[236:237], off
	v_lshl_add_u64 v[236:237], s[24:25], 0, v[164:165]
	s_mov_b32 m0, s49
	s_nop 0
	global_load_lds_dwordx4 v[236:237], off
	v_lshl_add_u64 v[236:237], v[240:241], 0, s[14:15]
	s_mov_b32 m0, s37
	s_nop 0
	global_load_lds_dwordx4 v[236:237], off
	v_lshl_add_u64 v[236:237], v[242:243], 0, s[14:15]
	s_mov_b32 m0, s38
	s_nop 0
	global_load_lds_dwordx4 v[236:237], off
	s_waitcnt vmcnt(8)
	s_waitcnt lgkmcnt(0)
	s_barrier
	s_setprio 1
	s_waitcnt lgkmcnt(0)
	v_mfma_f32_16x16x32_bf16 v[68:71], v[56:59], v[160:163], v[68:71]
	v_mfma_f32_16x16x32_bf16 v[64:67], v[112:115], v[160:163], v[64:67]
	v_mfma_f32_16x16x32_bf16 v[48:51], v[56:59], v[212:215], v[48:51]
	v_mfma_f32_16x16x32_bf16 v[40:43], v[112:115], v[212:215], v[40:43]
	v_mfma_f32_16x16x32_bf16 v[28:31], v[56:59], v[220:223], v[28:31]
	v_mfma_f32_16x16x32_bf16 v[24:27], v[112:115], v[220:223], v[24:27]
	v_mfma_f32_16x16x32_bf16 v[12:15], v[56:59], v[228:231], v[12:15]
	v_mfma_f32_16x16x32_bf16 v[8:11], v[112:115], v[228:231], v[8:11]
	v_mfma_f32_16x16x32_bf16 v[68:71], v[60:63], v[208:211], v[68:71]
	v_mfma_f32_16x16x32_bf16 v[64:67], v[124:127], v[208:211], v[64:67]
	v_mfma_f32_16x16x32_bf16 v[48:51], v[60:63], v[216:219], v[48:51]
	v_mfma_f32_16x16x32_bf16 v[40:43], v[124:127], v[216:219], v[40:43]
	v_mfma_f32_16x16x32_bf16 v[28:31], v[60:63], v[224:227], v[28:31]
	v_mfma_f32_16x16x32_bf16 v[24:27], v[124:127], v[224:227], v[24:27]
	v_mfma_f32_16x16x32_bf16 v[12:15], v[60:63], v[232:235], v[12:15]
	v_mfma_f32_16x16x32_bf16 v[8:11], v[124:127], v[232:235], v[8:11]
	s_setprio 0
	s_setprio 1
	v_mfma_f32_16x16x32_bf16 v[44:47], v[136:139], v[160:163], v[44:47]
	v_mfma_f32_16x16x32_bf16 v[60:63], v[148:151], v[208:211], v[44:47]
	v_mfma_f32_16x16x32_bf16 v[44:47], v[152:155], v[160:163], v[52:55]
	v_mfma_f32_16x16x32_bf16 v[36:39], v[136:139], v[212:215], v[36:39]
	v_mfma_f32_16x16x32_bf16 v[32:35], v[152:155], v[212:215], v[32:35]
	v_mfma_f32_16x16x32_bf16 v[20:23], v[136:139], v[220:223], v[20:23]
	v_mfma_f32_16x16x32_bf16 v[16:19], v[152:155], v[220:223], v[16:19]
	v_mfma_f32_16x16x32_bf16 v[4:7], v[136:139], v[228:231], v[4:7]
	v_mfma_f32_16x16x32_bf16 v[0:3], v[152:155], v[228:231], v[0:3]
	v_mfma_f32_16x16x32_bf16 v[56:59], v[156:159], v[208:211], v[44:47]
	v_mfma_f32_16x16x32_bf16 v[36:39], v[148:151], v[216:219], v[36:39]
	v_mfma_f32_16x16x32_bf16 v[32:35], v[156:159], v[216:219], v[32:35]
	v_mfma_f32_16x16x32_bf16 v[20:23], v[148:151], v[224:227], v[20:23]
	v_mfma_f32_16x16x32_bf16 v[16:19], v[156:159], v[224:227], v[16:19]
	v_mfma_f32_16x16x32_bf16 v[4:7], v[148:151], v[232:235], v[4:7]
	v_mfma_f32_16x16x32_bf16 v[0:3], v[156:159], v[232:235], v[0:3]
	s_setprio 0
	s_barrier
	s_add_i32 s56, s56, 2
	s_add_u32 s22, s22, 0x100
	s_addc_u32 s23, s23, 0
	s_add_u32 s54, s54, 0x100
	s_addc_u32 s55, s55, 0
	s_cmp_gt_u32 s56, 7
	s_cbranch_scc0 .LBB0_791
	s_and_b64 vcc, exec, s[16:17]
	s_cbranch_vccz .LBB0_794
	s_barrier
.LBB0_794:
	s_lshl_b32 s22, s52, 8
	s_add_i32 s26, s22, s36
	s_lshl_b32 s22, s53, 8
	s_and_b32 s27, s22, 0x100
	s_lshl_b32 s22, s52, 3
	v_or_b32_e32 v207, s26, v185
	s_and_b32 s22, s22, -16
	v_bitop3_b32 v114, s27, v206, v199 bitop3:0xc8
	s_ashr_i32 s23, s22, 31
	v_mad_i64_i32 v[112:113], s[24:25], v207, s42, v[176:177]
	v_lshlrev_b32_e32 v172, 1, v114
	v_lshl_add_u64 v[52:53], s[22:23], 2, v[174:175]
	v_lshl_add_u64 v[112:113], v[112:113], 0, v[172:173]
	global_load_dwordx4 v[44:47], v[52:53], off offset:16
	s_nop 0
	global_load_dwordx4 v[52:55], v[52:53], off
	s_nop 0
	global_load_dwordx4 v[210:213], v[112:113], off
	global_load_dwordx4 v[160:163], v[112:113], off offset:256
	v_or_b32_e32 v112, 16, v207
	v_mad_i64_i32 v[112:113], s[24:25], v112, s42, v[176:177]
	v_lshl_add_u64 v[112:113], v[112:113], 0, v[172:173]
	global_load_dwordx4 v[156:159], v[112:113], off
	global_load_dwordx4 v[152:155], v[112:113], off offset:256
	v_or_b32_e32 v112, 32, v207
	v_mad_i64_i32 v[112:113], s[24:25], v112, s42, v[176:177]
	v_lshl_add_u64 v[112:113], v[112:113], 0, v[172:173]
	global_load_dwordx4 v[148:151], v[112:113], off
	global_load_dwordx4 v[136:139], v[112:113], off offset:256
	v_or_b32_e32 v112, 48, v207
	v_mad_i64_i32 v[112:113], s[24:25], v112, s42, v[176:177]
	v_lshl_add_u64 v[112:113], v[112:113], 0, v[172:173]
	global_load_dwordx4 v[124:127], v[112:113], off
	s_nop 0
	global_load_dwordx4 v[112:115], v[112:113], off offset:256
	v_lshlrev_b32_e32 v208, 5, v207
	v_or_b32_e32 v183, s27, v199
	v_and_b32_e32 v208, 0x9e0, v208
	s_waitcnt vmcnt(0)
	v_lshlrev_b32_e32 v214, 16, v210
	v_and_b32_e32 v215, 0xffff0000, v210
	v_pk_fma_f32 v[214:215], v[52:53], v[214:215], v[144:145]
	s_lshl_b32 s24, s26, 5
	v_mul_f32_e32 v144, 0x3d372713, v214
	v_mul_f32_e32 v144, v214, v144
	v_fma_f32 v144, v214, v144, v214
	v_mul_f32_e32 v144, 0x3f4c422a, v144
	v_add_f32_e32 v144, v144, v144
	v_mul_f32_e32 v144, 0x3fb8aa3b, v144
	v_exp_f32_e32 v145, v144
	v_mul_f32_e32 v144, 0x3d372713, v215
	v_mul_f32_e32 v144, v215, v144
	v_fma_f32 v144, v215, v144, v215
	v_mul_f32_e32 v144, 0x3f4c422a, v144
	v_add_f32_e32 v144, v144, v144
	v_mul_f32_e32 v144, 0x3fb8aa3b, v144
	v_exp_f32_e32 v210, v144
	v_add_f32_e32 v145, 1.0, v145
	v_rcp_f32_e32 v216, v145
	v_lshrrev_b32_e32 v144, 4, v183
	v_add_f32_e32 v145, 1.0, v210
	v_lshlrev_b32_e32 v210, 16, v211
	v_and_b32_e32 v211, 0xffff0000, v211
	v_pk_fma_f32 v[146:147], v[54:55], v[210:211], v[146:147]
	v_rcp_f32_e32 v217, v145
	v_mul_f32_e32 v145, 0x3d372713, v146
	v_mul_f32_e32 v145, v146, v145
	v_mul_f32_e32 v183, 0x3d372713, v147
	v_fma_f32 v145, v146, v145, v146
	v_mul_f32_e32 v183, v147, v183
	v_mul_f32_e32 v145, 0x3f4c422a, v145
	v_fma_f32 v183, v147, v183, v147
	v_add_f32_e32 v145, v145, v145
	v_mul_f32_e32 v183, 0x3f4c422a, v183
	v_mul_f32_e32 v145, 0x3fb8aa3b, v145
	v_add_f32_e32 v183, v183, v183
	v_exp_f32_e32 v145, v145
	v_mul_f32_e32 v183, 0x3fb8aa3b, v183
	v_exp_f32_e32 v183, v183
	v_pk_fma_f32 v[210:211], v[216:217], 2.0, 1.0 op_sel_hi:[1,0,0] neg_lo:[1,0,0] neg_hi:[1,0,0]
	v_add_f32_e32 v145, 1.0, v145
	v_rcp_f32_e32 v216, v145
	v_add_f32_e32 v145, 1.0, v183
	v_rcp_f32_e32 v217, v145
	v_pk_mul_f32 v[214:215], v[214:215], 0.5 op_sel_hi:[1,0]
	v_pk_add_f32 v[210:211], v[210:211], 1.0 op_sel_hi:[1,0]
	v_pk_mul_f32 v[146:147], v[146:147], 0.5 op_sel_hi:[1,0]
	v_pk_mul_f32 v[210:211], v[214:215], v[210:211]
	v_pk_fma_f32 v[214:215], v[216:217], 2.0, 1.0 op_sel_hi:[1,0,0] neg_lo:[1,0,0] neg_hi:[1,0,0]
	v_lshlrev_b32_e32 v216, 16, v212
	v_and_b32_e32 v217, 0xffff0000, v212
	v_pk_fma_f32 v[140:141], v[44:45], v[216:217], v[140:141]
	v_pk_add_f32 v[214:215], v[214:215], 1.0 op_sel_hi:[1,0]
	v_mul_f32_e32 v145, 0x3d372713, v140
	v_mul_f32_e32 v145, v140, v145
	v_mul_f32_e32 v183, 0x3d372713, v141
	v_fma_f32 v145, v140, v145, v140
	v_mul_f32_e32 v183, v141, v183
	v_mul_f32_e32 v145, 0x3f4c422a, v145
	v_fma_f32 v183, v141, v183, v141
	v_add_f32_e32 v145, v145, v145
	v_mul_f32_e32 v183, 0x3f4c422a, v183
	v_mul_f32_e32 v145, 0x3fb8aa3b, v145
	v_add_f32_e32 v183, v183, v183
	v_exp_f32_e32 v145, v145
	v_mul_f32_e32 v183, 0x3fb8aa3b, v183
	v_exp_f32_e32 v183, v183
	v_lshlrev_b32_e32 v212, 16, v213
	v_add_f32_e32 v145, 1.0, v145
	v_and_b32_e32 v213, 0xffff0000, v213
	v_pk_mul_f32 v[146:147], v[146:147], v[214:215]
	v_rcp_f32_e32 v214, v145
	v_add_f32_e32 v145, 1.0, v183
	v_pk_fma_f32 v[142:143], v[46:47], v[212:213], v[142:143]
	v_rcp_f32_e32 v215, v145
	v_mul_f32_e32 v145, 0x3d372713, v142
	v_mul_f32_e32 v145, v142, v145
	v_mul_f32_e32 v183, 0x3d372713, v143
	v_fma_f32 v145, v142, v145, v142
	v_mul_f32_e32 v183, v143, v183
	v_mul_f32_e32 v145, 0x3f4c422a, v145
	v_fma_f32 v183, v143, v183, v143
	v_add_f32_e32 v145, v145, v145
	v_mul_f32_e32 v183, 0x3f4c422a, v183
	v_mul_f32_e32 v145, 0x3fb8aa3b, v145
	v_add_f32_e32 v183, v183, v183
	v_exp_f32_e32 v145, v145
	v_mul_f32_e32 v183, 0x3fb8aa3b, v183
	v_exp_f32_e32 v183, v183
	v_pk_fma_f32 v[212:213], v[214:215], 2.0, 1.0 op_sel_hi:[1,0,0] neg_lo:[1,0,0] neg_hi:[1,0,0]
	v_add_f32_e32 v145, 1.0, v145
	v_rcp_f32_e32 v214, v145
	v_add_f32_e32 v145, 1.0, v183
	v_rcp_f32_e32 v215, v145
	s_and_b32 s25, s24, 0x3000
	v_pk_mul_f32 v[140:141], v[140:141], 0.5 op_sel_hi:[1,0]
	v_pk_add_f32 v[212:213], v[212:213], 1.0 op_sel_hi:[1,0]
	v_or_b32_e32 v209, s25, v208
	v_pk_mul_f32 v[212:213], v[140:141], v[212:213]
	v_pk_fma_f32 v[140:141], v[214:215], 2.0, 1.0 op_sel_hi:[1,0,0] neg_lo:[1,0,0] neg_hi:[1,0,0]
	v_pk_mul_f32 v[142:143], v[142:143], 0.5 op_sel_hi:[1,0]
	v_pk_add_f32 v[140:141], v[140:141], 1.0 op_sel_hi:[1,0]
	v_or_b32_e32 v145, v209, v144
	v_pk_mul_f32 v[214:215], v[142:143], v[140:141]
	v_cvt_pk_bf16_f32 v141, v146, v147
	v_lshlrev_b32_e32 v146, 10, v145
	v_mov_b32_e32 v147, v173
	v_lshl_add_u64 v[146:147], s[8:9], 0, v[146:147]
	s_lshl_b64 s[22:23], s[22:23], 1
	v_lshl_add_u64 v[146:147], v[146:147], 0, s[22:23]
	v_mov_b32_e32 v183, v173
	v_cvt_pk_bf16_f32 v140, v210, v211
	v_cvt_pk_bf16_f32 v142, v212, v213
	v_cvt_pk_bf16_f32 v143, v214, v215
	v_lshl_add_u64 v[146:147], v[146:147], 0, v[182:183]
	global_store_dwordx4 v[146:147], v[140:143], off
	v_lshlrev_b32_e32 v146, 16, v161
	v_and_b32_e32 v147, 0xffff0000, v161
	v_lshlrev_b32_e32 v140, 16, v160
	v_and_b32_e32 v141, 0xffff0000, v160
	v_pk_fma_f32 v[140:141], v[52:53], v[140:141], v[132:133]
	v_pk_fma_f32 v[134:135], v[54:55], v[146:147], v[134:135]
	v_mul_f32_e32 v132, 0x3d372713, v140
	v_mul_f32_e32 v132, v140, v132
	v_fma_f32 v132, v140, v132, v140
	v_mul_f32_e32 v132, 0x3f4c422a, v132
	v_add_f32_e32 v132, v132, v132
	v_mul_f32_e32 v132, 0x3fb8aa3b, v132
	v_exp_f32_e32 v133, v132
	v_mul_f32_e32 v132, 0x3d372713, v141
	v_mul_f32_e32 v132, v141, v132
	v_fma_f32 v132, v141, v132, v141
	v_mul_f32_e32 v132, 0x3f4c422a, v132
	v_add_f32_e32 v132, v132, v132
	v_mul_f32_e32 v132, 0x3fb8aa3b, v132
	v_exp_f32_e32 v143, v132
	v_add_f32_e32 v133, 1.0, v133
	v_rcp_f32_e32 v142, v133
	v_mul_f32_e32 v145, 0x3d372713, v135
	v_add_f32_e32 v133, 1.0, v143
	v_rcp_f32_e32 v143, v133
	v_mul_f32_e32 v133, 0x3d372713, v134
	v_mul_f32_e32 v133, v134, v133
	v_fma_f32 v133, v134, v133, v134
	v_mul_f32_e32 v145, v135, v145
	v_mul_f32_e32 v133, 0x3f4c422a, v133
	v_fma_f32 v145, v135, v145, v135
	v_add_f32_e32 v133, v133, v133
	v_mul_f32_e32 v145, 0x3f4c422a, v145
	v_mul_f32_e32 v133, 0x3fb8aa3b, v133
	v_add_f32_e32 v145, v145, v145
	v_exp_f32_e32 v133, v133
	v_mul_f32_e32 v145, 0x3fb8aa3b, v145
	v_exp_f32_e32 v145, v145
	v_pk_fma_f32 v[142:143], v[142:143], 2.0, 1.0 op_sel_hi:[1,0,0] neg_lo:[1,0,0] neg_hi:[1,0,0]
	v_add_f32_e32 v133, 1.0, v133
	v_rcp_f32_e32 v146, v133
	v_add_f32_e32 v133, 1.0, v145
	v_rcp_f32_e32 v147, v133
	v_pk_mul_f32 v[140:141], v[140:141], 0.5 op_sel_hi:[1,0]
	v_pk_add_f32 v[142:143], v[142:143], 1.0 op_sel_hi:[1,0]
	v_pk_mul_f32 v[134:135], v[134:135], 0.5 op_sel_hi:[1,0]
	v_pk_mul_f32 v[140:141], v[140:141], v[142:143]
	v_pk_fma_f32 v[142:143], v[146:147], 2.0, 1.0 op_sel_hi:[1,0,0] neg_lo:[1,0,0] neg_hi:[1,0,0]
	v_lshlrev_b32_e32 v146, 16, v162
	v_and_b32_e32 v147, 0xffff0000, v162
	v_pk_fma_f32 v[128:129], v[44:45], v[146:147], v[128:129]
	v_pk_add_f32 v[142:143], v[142:143], 1.0 op_sel_hi:[1,0]
	v_mul_f32_e32 v133, 0x3d372713, v128
	v_mul_f32_e32 v133, v128, v133
	v_mul_f32_e32 v145, 0x3d372713, v129
	v_fma_f32 v133, v128, v133, v128
	v_mul_f32_e32 v145, v129, v145
	v_mul_f32_e32 v133, 0x3f4c422a, v133
	v_fma_f32 v145, v129, v145, v129
	v_add_f32_e32 v133, v133, v133
	v_mul_f32_e32 v145, 0x3f4c422a, v145
	v_mul_f32_e32 v133, 0x3fb8aa3b, v133
	v_add_f32_e32 v145, v145, v145
	v_exp_f32_e32 v133, v133
	v_mul_f32_e32 v145, 0x3fb8aa3b, v145
	v_exp_f32_e32 v145, v145
	v_lshlrev_b32_e32 v146, 16, v163
	v_add_f32_e32 v133, 1.0, v133
	v_and_b32_e32 v147, 0xffff0000, v163
	v_pk_mul_f32 v[134:135], v[134:135], v[142:143]
	v_rcp_f32_e32 v142, v133
	v_add_f32_e32 v133, 1.0, v145
	v_pk_fma_f32 v[130:131], v[46:47], v[146:147], v[130:131]
	v_rcp_f32_e32 v143, v133
	v_mul_f32_e32 v133, 0x3d372713, v130
	v_mul_f32_e32 v133, v130, v133
	v_mul_f32_e32 v145, 0x3d372713, v131
	v_fma_f32 v133, v130, v133, v130
	v_mul_f32_e32 v145, v131, v145
	v_mul_f32_e32 v133, 0x3f4c422a, v133
	v_fma_f32 v145, v131, v145, v131
	v_add_f32_e32 v133, v133, v133
	v_mul_f32_e32 v145, 0x3f4c422a, v145
	v_mul_f32_e32 v133, 0x3fb8aa3b, v133
	v_add_f32_e32 v145, v145, v145
	v_exp_f32_e32 v133, v133
	v_mul_f32_e32 v145, 0x3fb8aa3b, v145
	v_exp_f32_e32 v145, v145
	v_pk_fma_f32 v[142:143], v[142:143], 2.0, 1.0 op_sel_hi:[1,0,0] neg_lo:[1,0,0] neg_hi:[1,0,0]
	v_add_f32_e32 v133, 1.0, v133
	v_rcp_f32_e32 v146, v133
	v_add_f32_e32 v133, 1.0, v145
	v_rcp_f32_e32 v147, v133
	v_pk_mul_f32 v[128:129], v[128:129], 0.5 op_sel_hi:[1,0]
	v_pk_add_f32 v[142:143], v[142:143], 1.0 op_sel_hi:[1,0]
	v_or_b32_e32 v132, 8, v144
	v_pk_mul_f32 v[142:143], v[128:129], v[142:143]
	v_pk_fma_f32 v[128:129], v[146:147], 2.0, 1.0 op_sel_hi:[1,0,0] neg_lo:[1,0,0] neg_hi:[1,0,0]
	v_pk_mul_f32 v[130:131], v[130:131], 0.5 op_sel_hi:[1,0]
	v_pk_add_f32 v[128:129], v[128:129], 1.0 op_sel_hi:[1,0]
	v_or_b32_e32 v133, v209, v132
	v_pk_mul_f32 v[146:147], v[130:131], v[128:129]
	v_cvt_pk_bf16_f32 v129, v134, v135
	v_lshlrev_b32_e32 v134, 10, v133
	v_mov_b32_e32 v135, v173
	v_lshl_add_u64 v[134:135], s[8:9], 0, v[134:135]
	v_lshl_add_u64 v[134:135], v[134:135], 0, s[22:23]
	v_cvt_pk_bf16_f32 v128, v140, v141
	v_cvt_pk_bf16_f32 v130, v142, v143
	v_cvt_pk_bf16_f32 v131, v146, v147
	v_lshl_add_u64 v[134:135], v[134:135], 0, v[182:183]
	global_store_dwordx4 v[134:135], v[128:131], off
	v_or_b32_e32 v133, 0x200, v209
	s_nop 0
	v_lshlrev_b32_e32 v128, 16, v156
	v_and_b32_e32 v129, 0xffff0000, v156
	v_pk_fma_f32 v[120:121], v[52:53], v[128:129], v[120:121]
	v_lshlrev_b32_e32 v130, 16, v157
	v_mul_f32_e32 v128, 0x3d372713, v120
	v_mul_f32_e32 v129, 0x3d372713, v121
	v_and_b32_e32 v131, 0xffff0000, v157
	v_mul_f32_e32 v128, v120, v128
	v_mul_f32_e32 v129, v121, v129
	v_pk_fma_f32 v[122:123], v[54:55], v[130:131], v[122:123]
	v_fma_f32 v128, v120, v128, v120
	v_fma_f32 v129, v121, v129, v121
	v_mul_f32_e32 v130, 0x3d372713, v122
	v_mul_f32_e32 v131, 0x3d372713, v123
	v_mul_f32_e32 v128, 0x3f4c422a, v128
	v_mul_f32_e32 v129, 0x3f4c422a, v129
	v_mul_f32_e32 v130, v122, v130
	v_mul_f32_e32 v131, v123, v131
	v_add_f32_e32 v128, v128, v128
	v_add_f32_e32 v129, v129, v129
	v_fma_f32 v130, v122, v130, v122
	v_fma_f32 v131, v123, v131, v123
	v_mul_f32_e32 v128, 0x3fb8aa3b, v128
	v_mul_f32_e32 v129, 0x3fb8aa3b, v129
	v_mul_f32_e32 v130, 0x3f4c422a, v130
	v_mul_f32_e32 v131, 0x3f4c422a, v131
	v_exp_f32_e32 v128, v128
	v_exp_f32_e32 v129, v129
	v_add_f32_e32 v130, v130, v130
	v_add_f32_e32 v131, v131, v131
	v_mul_f32_e32 v130, 0x3fb8aa3b, v130
	v_mul_f32_e32 v131, 0x3fb8aa3b, v131
	v_exp_f32_e32 v130, v130
	v_exp_f32_e32 v131, v131
	v_add_f32_e32 v128, 1.0, v128
	v_add_f32_e32 v129, 1.0, v129
	v_rcp_f32_e32 v128, v128
	v_rcp_f32_e32 v129, v129
	v_add_f32_e32 v130, 1.0, v130
	v_add_f32_e32 v131, 1.0, v131
	v_rcp_f32_e32 v130, v130
	v_rcp_f32_e32 v131, v131
	v_pk_fma_f32 v[128:129], v[128:129], 2.0, 1.0 op_sel_hi:[1,0,0] neg_lo:[1,0,0] neg_hi:[1,0,0]
	v_pk_mul_f32 v[120:121], v[120:121], 0.5 op_sel_hi:[1,0]
	v_pk_add_f32 v[128:129], v[128:129], 1.0 op_sel_hi:[1,0]
	v_pk_mul_f32 v[122:123], v[122:123], 0.5 op_sel_hi:[1,0]
	v_pk_mul_f32 v[120:121], v[120:121], v[128:129]
	v_pk_fma_f32 v[128:129], v[130:131], 2.0, 1.0 op_sel_hi:[1,0,0] neg_lo:[1,0,0] neg_hi:[1,0,0]
	v_lshlrev_b32_e32 v130, 16, v158
	v_and_b32_e32 v131, 0xffff0000, v158
	v_pk_fma_f32 v[116:117], v[44:45], v[130:131], v[116:117]
	v_pk_add_f32 v[128:129], v[128:129], 1.0 op_sel_hi:[1,0]
	v_mul_f32_e32 v130, 0x3d372713, v116
	v_mul_f32_e32 v131, 0x3d372713, v117
	v_mul_f32_e32 v130, v116, v130
	v_mul_f32_e32 v131, v117, v131
	v_fma_f32 v130, v116, v130, v116
	v_fma_f32 v131, v117, v131, v117
	v_mul_f32_e32 v130, 0x3f4c422a, v130
	v_mul_f32_e32 v131, 0x3f4c422a, v131
	v_add_f32_e32 v130, v130, v130
	v_add_f32_e32 v131, v131, v131
	v_mul_f32_e32 v130, 0x3fb8aa3b, v130
	v_mul_f32_e32 v131, 0x3fb8aa3b, v131
	v_exp_f32_e32 v130, v130
	v_exp_f32_e32 v131, v131
	v_pk_mul_f32 v[122:123], v[122:123], v[128:129]
	v_pk_mul_f32 v[116:117], v[116:117], 0.5 op_sel_hi:[1,0]
	v_add_f32_e32 v128, 1.0, v130
	v_add_f32_e32 v129, 1.0, v131
	v_lshlrev_b32_e32 v130, 16, v159
	v_and_b32_e32 v131, 0xffff0000, v159
	v_pk_fma_f32 v[118:119], v[46:47], v[130:131], v[118:119]
	v_rcp_f32_e32 v128, v128
	v_mul_f32_e32 v130, 0x3d372713, v118
	v_mul_f32_e32 v131, 0x3d372713, v119
	v_mul_f32_e32 v130, v118, v130
	v_mul_f32_e32 v131, v119, v131
	v_fma_f32 v130, v118, v130, v118
	v_fma_f32 v131, v119, v131, v119
	v_mul_f32_e32 v130, 0x3f4c422a, v130
	v_mul_f32_e32 v131, 0x3f4c422a, v131
	v_add_f32_e32 v130, v130, v130
	v_add_f32_e32 v131, v131, v131
	v_mul_f32_e32 v130, 0x3fb8aa3b, v130
	v_mul_f32_e32 v131, 0x3fb8aa3b, v131
	v_exp_f32_e32 v130, v130
	v_exp_f32_e32 v131, v131
	v_rcp_f32_e32 v129, v129
	v_pk_mul_f32 v[118:119], v[118:119], 0.5 op_sel_hi:[1,0]
	v_add_f32_e32 v130, 1.0, v130
	v_add_f32_e32 v131, 1.0, v131
	v_rcp_f32_e32 v130, v130
	v_rcp_f32_e32 v131, v131
	v_pk_fma_f32 v[128:129], v[128:129], 2.0, 1.0 op_sel_hi:[1,0,0] neg_lo:[1,0,0] neg_hi:[1,0,0]
	s_nop 0
	v_pk_add_f32 v[128:129], v[128:129], 1.0 op_sel_hi:[1,0]
	s_nop 0
	v_pk_mul_f32 v[128:129], v[116:117], v[128:129]
	v_pk_fma_f32 v[116:117], v[130:131], 2.0, 1.0 op_sel_hi:[1,0,0] neg_lo:[1,0,0] neg_hi:[1,0,0]
	s_nop 0
	v_pk_add_f32 v[116:117], v[116:117], 1.0 op_sel_hi:[1,0]
	s_nop 0
	v_pk_mul_f32 v[130:131], v[118:119], v[116:117]
	v_cvt_pk_bf16_f32 v116, v120, v121
	v_or_b32_e32 v120, v133, v144
	v_lshlrev_b32_e32 v120, 10, v120
	v_mov_b32_e32 v121, v173
	v_lshl_add_u64 v[120:121], s[8:9], 0, v[120:121]
	v_cvt_pk_bf16_f32 v117, v122, v123
	v_lshl_add_u64 v[120:121], v[120:121], 0, s[22:23]
	v_lshlrev_b32_e32 v122, 16, v152
	v_and_b32_e32 v123, 0xffff0000, v152
	v_cvt_pk_bf16_f32 v118, v128, v129
	v_cvt_pk_bf16_f32 v119, v130, v131
	v_lshl_add_u64 v[120:121], v[120:121], 0, v[182:183]
	v_pk_fma_f32 v[108:109], v[52:53], v[122:123], v[108:109]
	global_store_dwordx4 v[120:121], v[116:119], off
	v_mul_f32_e32 v122, 0x3d372713, v108
	v_mul_f32_e32 v123, 0x3d372713, v109
	v_lshlrev_b32_e32 v118, 16, v153
	v_and_b32_e32 v119, 0xffff0000, v153
	v_mul_f32_e32 v122, v108, v122
	v_mul_f32_e32 v123, v109, v123
	v_pk_fma_f32 v[110:111], v[54:55], v[118:119], v[110:111]
	v_fma_f32 v122, v108, v122, v108
	v_fma_f32 v123, v109, v123, v109
	v_mul_f32_e32 v118, 0x3d372713, v110
	v_mul_f32_e32 v119, 0x3d372713, v111
	v_mul_f32_e32 v122, 0x3f4c422a, v122
	v_mul_f32_e32 v123, 0x3f4c422a, v123
	v_mul_f32_e32 v118, v110, v118
	v_mul_f32_e32 v119, v111, v119
	v_add_f32_e32 v122, v122, v122
	v_add_f32_e32 v123, v123, v123
	v_fma_f32 v118, v110, v118, v110
	v_fma_f32 v119, v111, v119, v111
	v_mul_f32_e32 v122, 0x3fb8aa3b, v122
	v_mul_f32_e32 v123, 0x3fb8aa3b, v123
	v_mul_f32_e32 v118, 0x3f4c422a, v118
	v_mul_f32_e32 v119, 0x3f4c422a, v119
	v_exp_f32_e32 v122, v122
	v_exp_f32_e32 v123, v123
	v_add_f32_e32 v118, v118, v118
	v_add_f32_e32 v119, v119, v119
	v_mul_f32_e32 v118, 0x3fb8aa3b, v118
	v_mul_f32_e32 v119, 0x3fb8aa3b, v119
	v_exp_f32_e32 v118, v118
	v_exp_f32_e32 v119, v119
	v_add_f32_e32 v116, 1.0, v122
	v_add_f32_e32 v117, 1.0, v123
	v_rcp_f32_e32 v116, v116
	v_rcp_f32_e32 v117, v117
	v_add_f32_e32 v118, 1.0, v118
	v_add_f32_e32 v119, 1.0, v119
	v_rcp_f32_e32 v118, v118
	v_rcp_f32_e32 v119, v119
	v_pk_fma_f32 v[116:117], v[116:117], 2.0, 1.0 op_sel_hi:[1,0,0] neg_lo:[1,0,0] neg_hi:[1,0,0]
	v_pk_mul_f32 v[108:109], v[108:109], 0.5 op_sel_hi:[1,0]
	v_pk_add_f32 v[116:117], v[116:117], 1.0 op_sel_hi:[1,0]
	v_pk_mul_f32 v[110:111], v[110:111], 0.5 op_sel_hi:[1,0]
	v_pk_mul_f32 v[108:109], v[108:109], v[116:117]
	v_pk_fma_f32 v[116:117], v[118:119], 2.0, 1.0 op_sel_hi:[1,0,0] neg_lo:[1,0,0] neg_hi:[1,0,0]
	v_lshlrev_b32_e32 v118, 16, v154
	v_and_b32_e32 v119, 0xffff0000, v154
	v_pk_fma_f32 v[104:105], v[44:45], v[118:119], v[104:105]
	v_pk_add_f32 v[116:117], v[116:117], 1.0 op_sel_hi:[1,0]
	v_mul_f32_e32 v118, 0x3d372713, v104
	v_mul_f32_e32 v119, 0x3d372713, v105
	v_mul_f32_e32 v118, v104, v118
	v_mul_f32_e32 v119, v105, v119
	v_fma_f32 v118, v104, v118, v104
	v_fma_f32 v119, v105, v119, v105
	v_mul_f32_e32 v118, 0x3f4c422a, v118
	v_mul_f32_e32 v119, 0x3f4c422a, v119
	v_add_f32_e32 v118, v118, v118
	v_add_f32_e32 v119, v119, v119
	v_mul_f32_e32 v118, 0x3fb8aa3b, v118
	v_mul_f32_e32 v119, 0x3fb8aa3b, v119
	v_exp_f32_e32 v118, v118
	v_exp_f32_e32 v119, v119
	v_pk_mul_f32 v[110:111], v[110:111], v[116:117]
	v_pk_mul_f32 v[104:105], v[104:105], 0.5 op_sel_hi:[1,0]
	v_add_f32_e32 v116, 1.0, v118
	v_add_f32_e32 v117, 1.0, v119
	v_lshlrev_b32_e32 v118, 16, v155
	v_and_b32_e32 v119, 0xffff0000, v155
	v_pk_fma_f32 v[106:107], v[46:47], v[118:119], v[106:107]
	v_rcp_f32_e32 v116, v116
	v_mul_f32_e32 v118, 0x3d372713, v106
	v_mul_f32_e32 v119, 0x3d372713, v107
	v_mul_f32_e32 v118, v106, v118
	v_mul_f32_e32 v119, v107, v119
	v_fma_f32 v118, v106, v118, v106
	v_fma_f32 v119, v107, v119, v107
	v_mul_f32_e32 v118, 0x3f4c422a, v118
	v_mul_f32_e32 v119, 0x3f4c422a, v119
	v_add_f32_e32 v118, v118, v118
	v_add_f32_e32 v119, v119, v119
	v_mul_f32_e32 v118, 0x3fb8aa3b, v118
	v_mul_f32_e32 v119, 0x3fb8aa3b, v119
	v_exp_f32_e32 v118, v118
	v_exp_f32_e32 v119, v119
	v_rcp_f32_e32 v117, v117
	v_pk_mul_f32 v[106:107], v[106:107], 0.5 op_sel_hi:[1,0]
	v_add_f32_e32 v118, 1.0, v118
	v_add_f32_e32 v119, 1.0, v119
	v_rcp_f32_e32 v118, v118
	v_rcp_f32_e32 v119, v119
	v_pk_fma_f32 v[116:117], v[116:117], 2.0, 1.0 op_sel_hi:[1,0,0] neg_lo:[1,0,0] neg_hi:[1,0,0]
	s_nop 0
	v_pk_add_f32 v[116:117], v[116:117], 1.0 op_sel_hi:[1,0]
	s_nop 0
	v_pk_mul_f32 v[116:117], v[104:105], v[116:117]
	v_pk_fma_f32 v[104:105], v[118:119], 2.0, 1.0 op_sel_hi:[1,0,0] neg_lo:[1,0,0] neg_hi:[1,0,0]
	s_nop 0
	v_pk_add_f32 v[104:105], v[104:105], 1.0 op_sel_hi:[1,0]
	s_nop 0
	v_pk_mul_f32 v[118:119], v[106:107], v[104:105]
	v_cvt_pk_bf16_f32 v104, v108, v109
	v_or_b32_e32 v108, v133, v132
	v_lshlrev_b32_e32 v108, 10, v108
	v_mov_b32_e32 v109, v173
	v_lshl_add_u64 v[108:109], s[8:9], 0, v[108:109]
	v_lshl_add_u64 v[108:109], v[108:109], 0, s[22:23]
	v_cvt_pk_bf16_f32 v105, v110, v111
	v_cvt_pk_bf16_f32 v106, v116, v117
	v_cvt_pk_bf16_f32 v107, v118, v119
	v_lshl_add_u64 v[108:109], v[108:109], 0, v[182:183]
	global_store_dwordx4 v[108:109], v[104:107], off
	v_or_b32_e32 v108, 0x400, v209
	s_nop 0
	v_lshlrev_b32_e32 v104, 16, v148
	v_and_b32_e32 v105, 0xffff0000, v148
	v_pk_fma_f32 v[100:101], v[52:53], v[104:105], v[100:101]
	v_lshlrev_b32_e32 v106, 16, v149
	v_mul_f32_e32 v104, 0x3d372713, v100
	v_mul_f32_e32 v105, 0x3d372713, v101
	v_and_b32_e32 v107, 0xffff0000, v149
	v_mul_f32_e32 v104, v100, v104
	v_mul_f32_e32 v105, v101, v105
	v_pk_fma_f32 v[102:103], v[54:55], v[106:107], v[102:103]
	v_fma_f32 v104, v100, v104, v100
	v_fma_f32 v105, v101, v105, v101
	v_mul_f32_e32 v106, 0x3d372713, v102
	v_mul_f32_e32 v107, 0x3d372713, v103
	v_mul_f32_e32 v104, 0x3f4c422a, v104
	v_mul_f32_e32 v105, 0x3f4c422a, v105
	v_mul_f32_e32 v106, v102, v106
	v_mul_f32_e32 v107, v103, v107
	v_add_f32_e32 v104, v104, v104
	v_add_f32_e32 v105, v105, v105
	v_fma_f32 v106, v102, v106, v102
	v_fma_f32 v107, v103, v107, v103
	v_mul_f32_e32 v104, 0x3fb8aa3b, v104
	v_mul_f32_e32 v105, 0x3fb8aa3b, v105
	v_mul_f32_e32 v106, 0x3f4c422a, v106
	v_mul_f32_e32 v107, 0x3f4c422a, v107
	v_exp_f32_e32 v104, v104
	v_exp_f32_e32 v105, v105
	v_add_f32_e32 v106, v106, v106
	v_add_f32_e32 v107, v107, v107
	v_mul_f32_e32 v106, 0x3fb8aa3b, v106
	v_mul_f32_e32 v107, 0x3fb8aa3b, v107
	v_exp_f32_e32 v106, v106
	v_exp_f32_e32 v107, v107
	v_add_f32_e32 v104, 1.0, v104
	v_add_f32_e32 v105, 1.0, v105
	v_rcp_f32_e32 v104, v104
	v_rcp_f32_e32 v105, v105
	v_add_f32_e32 v106, 1.0, v106
	v_add_f32_e32 v107, 1.0, v107
	v_rcp_f32_e32 v106, v106
	v_rcp_f32_e32 v107, v107
	v_pk_fma_f32 v[104:105], v[104:105], 2.0, 1.0 op_sel_hi:[1,0,0] neg_lo:[1,0,0] neg_hi:[1,0,0]
	v_pk_mul_f32 v[100:101], v[100:101], 0.5 op_sel_hi:[1,0]
	v_pk_add_f32 v[104:105], v[104:105], 1.0 op_sel_hi:[1,0]
	v_pk_mul_f32 v[102:103], v[102:103], 0.5 op_sel_hi:[1,0]
	v_pk_mul_f32 v[100:101], v[100:101], v[104:105]
	v_pk_fma_f32 v[104:105], v[106:107], 2.0, 1.0 op_sel_hi:[1,0,0] neg_lo:[1,0,0] neg_hi:[1,0,0]
	v_lshlrev_b32_e32 v106, 16, v150
	v_and_b32_e32 v107, 0xffff0000, v150
	v_pk_fma_f32 v[96:97], v[44:45], v[106:107], v[96:97]
	v_pk_add_f32 v[104:105], v[104:105], 1.0 op_sel_hi:[1,0]
	v_mul_f32_e32 v106, 0x3d372713, v96
	v_mul_f32_e32 v107, 0x3d372713, v97
	v_mul_f32_e32 v106, v96, v106
	v_mul_f32_e32 v107, v97, v107
	v_fma_f32 v106, v96, v106, v96
	v_fma_f32 v107, v97, v107, v97
	v_mul_f32_e32 v106, 0x3f4c422a, v106
	v_mul_f32_e32 v107, 0x3f4c422a, v107
	v_add_f32_e32 v106, v106, v106
	v_add_f32_e32 v107, v107, v107
	v_mul_f32_e32 v106, 0x3fb8aa3b, v106
	v_mul_f32_e32 v107, 0x3fb8aa3b, v107
	v_exp_f32_e32 v106, v106
	v_exp_f32_e32 v107, v107
	v_pk_mul_f32 v[102:103], v[102:103], v[104:105]
	v_pk_mul_f32 v[96:97], v[96:97], 0.5 op_sel_hi:[1,0]
	v_add_f32_e32 v104, 1.0, v106
	v_add_f32_e32 v105, 1.0, v107
	v_lshlrev_b32_e32 v106, 16, v151
	v_and_b32_e32 v107, 0xffff0000, v151
	v_pk_fma_f32 v[98:99], v[46:47], v[106:107], v[98:99]
	v_rcp_f32_e32 v104, v104
	v_mul_f32_e32 v106, 0x3d372713, v98
	v_mul_f32_e32 v107, 0x3d372713, v99
	v_mul_f32_e32 v106, v98, v106
	v_mul_f32_e32 v107, v99, v107
	v_fma_f32 v106, v98, v106, v98
	v_fma_f32 v107, v99, v107, v99
	v_mul_f32_e32 v106, 0x3f4c422a, v106
	v_mul_f32_e32 v107, 0x3f4c422a, v107
	v_add_f32_e32 v106, v106, v106
	v_add_f32_e32 v107, v107, v107
	v_mul_f32_e32 v106, 0x3fb8aa3b, v106
	v_mul_f32_e32 v107, 0x3fb8aa3b, v107
	v_exp_f32_e32 v106, v106
	v_exp_f32_e32 v107, v107
	v_rcp_f32_e32 v105, v105
	v_pk_mul_f32 v[98:99], v[98:99], 0.5 op_sel_hi:[1,0]
	v_add_f32_e32 v106, 1.0, v106
	v_add_f32_e32 v107, 1.0, v107
	v_rcp_f32_e32 v106, v106
	v_rcp_f32_e32 v107, v107
	v_pk_fma_f32 v[104:105], v[104:105], 2.0, 1.0 op_sel_hi:[1,0,0] neg_lo:[1,0,0] neg_hi:[1,0,0]
	s_nop 0
	v_pk_add_f32 v[104:105], v[104:105], 1.0 op_sel_hi:[1,0]
	s_nop 0
	v_pk_mul_f32 v[104:105], v[96:97], v[104:105]
	v_pk_fma_f32 v[96:97], v[106:107], 2.0, 1.0 op_sel_hi:[1,0,0] neg_lo:[1,0,0] neg_hi:[1,0,0]
	s_nop 0
	v_pk_add_f32 v[96:97], v[96:97], 1.0 op_sel_hi:[1,0]
	s_nop 0
	v_pk_mul_f32 v[106:107], v[98:99], v[96:97]
	v_cvt_pk_bf16_f32 v96, v100, v101
	v_or_b32_e32 v100, v108, v144
	v_lshlrev_b32_e32 v100, 10, v100
	v_mov_b32_e32 v101, v173
	v_lshl_add_u64 v[100:101], s[8:9], 0, v[100:101]
	v_cvt_pk_bf16_f32 v97, v102, v103
	v_lshl_add_u64 v[100:101], v[100:101], 0, s[22:23]
	v_lshlrev_b32_e32 v102, 16, v136
	v_and_b32_e32 v103, 0xffff0000, v136
	v_cvt_pk_bf16_f32 v98, v104, v105
	v_cvt_pk_bf16_f32 v99, v106, v107
	v_lshl_add_u64 v[100:101], v[100:101], 0, v[182:183]
	v_pk_fma_f32 v[92:93], v[52:53], v[102:103], v[92:93]
	global_store_dwordx4 v[100:101], v[96:99], off
	v_mul_f32_e32 v102, 0x3d372713, v92
	v_mul_f32_e32 v103, 0x3d372713, v93
	v_lshlrev_b32_e32 v98, 16, v137
	v_and_b32_e32 v99, 0xffff0000, v137
	v_mul_f32_e32 v102, v92, v102
	v_mul_f32_e32 v103, v93, v103
	v_pk_fma_f32 v[94:95], v[54:55], v[98:99], v[94:95]
	v_fma_f32 v102, v92, v102, v92
	v_fma_f32 v103, v93, v103, v93
	v_mul_f32_e32 v98, 0x3d372713, v94
	v_mul_f32_e32 v99, 0x3d372713, v95
	v_mul_f32_e32 v102, 0x3f4c422a, v102
	v_mul_f32_e32 v103, 0x3f4c422a, v103
	v_mul_f32_e32 v98, v94, v98
	v_mul_f32_e32 v99, v95, v99
	v_add_f32_e32 v102, v102, v102
	v_add_f32_e32 v103, v103, v103
	v_fma_f32 v98, v94, v98, v94
	v_fma_f32 v99, v95, v99, v95
	v_mul_f32_e32 v102, 0x3fb8aa3b, v102
	v_mul_f32_e32 v103, 0x3fb8aa3b, v103
	v_mul_f32_e32 v98, 0x3f4c422a, v98
	v_mul_f32_e32 v99, 0x3f4c422a, v99
	v_exp_f32_e32 v102, v102
	v_exp_f32_e32 v103, v103
	v_add_f32_e32 v98, v98, v98
	v_add_f32_e32 v99, v99, v99
	v_mul_f32_e32 v98, 0x3fb8aa3b, v98
	v_mul_f32_e32 v99, 0x3fb8aa3b, v99
	v_exp_f32_e32 v98, v98
	v_exp_f32_e32 v99, v99
	v_add_f32_e32 v96, 1.0, v102
	v_add_f32_e32 v97, 1.0, v103
	v_rcp_f32_e32 v96, v96
	v_rcp_f32_e32 v97, v97
	v_add_f32_e32 v98, 1.0, v98
	v_add_f32_e32 v99, 1.0, v99
	v_rcp_f32_e32 v98, v98
	v_rcp_f32_e32 v99, v99
	v_pk_fma_f32 v[96:97], v[96:97], 2.0, 1.0 op_sel_hi:[1,0,0] neg_lo:[1,0,0] neg_hi:[1,0,0]
	v_pk_mul_f32 v[92:93], v[92:93], 0.5 op_sel_hi:[1,0]
	v_pk_add_f32 v[96:97], v[96:97], 1.0 op_sel_hi:[1,0]
	v_pk_mul_f32 v[94:95], v[94:95], 0.5 op_sel_hi:[1,0]
	v_pk_mul_f32 v[92:93], v[92:93], v[96:97]
	v_pk_fma_f32 v[96:97], v[98:99], 2.0, 1.0 op_sel_hi:[1,0,0] neg_lo:[1,0,0] neg_hi:[1,0,0]
	v_lshlrev_b32_e32 v98, 16, v138
	v_and_b32_e32 v99, 0xffff0000, v138
	v_pk_fma_f32 v[88:89], v[44:45], v[98:99], v[88:89]
	v_pk_add_f32 v[96:97], v[96:97], 1.0 op_sel_hi:[1,0]
	v_mul_f32_e32 v98, 0x3d372713, v88
	v_mul_f32_e32 v99, 0x3d372713, v89
	v_mul_f32_e32 v98, v88, v98
	v_mul_f32_e32 v99, v89, v99
	v_fma_f32 v98, v88, v98, v88
	v_fma_f32 v99, v89, v99, v89
	v_mul_f32_e32 v98, 0x3f4c422a, v98
	v_mul_f32_e32 v99, 0x3f4c422a, v99
	v_add_f32_e32 v98, v98, v98
	v_add_f32_e32 v99, v99, v99
	v_mul_f32_e32 v98, 0x3fb8aa3b, v98
	v_mul_f32_e32 v99, 0x3fb8aa3b, v99
	v_exp_f32_e32 v98, v98
	v_exp_f32_e32 v99, v99
	v_pk_mul_f32 v[94:95], v[94:95], v[96:97]
	v_pk_mul_f32 v[88:89], v[88:89], 0.5 op_sel_hi:[1,0]
	v_add_f32_e32 v96, 1.0, v98
	v_add_f32_e32 v97, 1.0, v99
	v_lshlrev_b32_e32 v98, 16, v139
	v_and_b32_e32 v99, 0xffff0000, v139
	v_pk_fma_f32 v[90:91], v[46:47], v[98:99], v[90:91]
	v_rcp_f32_e32 v96, v96
	v_mul_f32_e32 v98, 0x3d372713, v90
	v_mul_f32_e32 v99, 0x3d372713, v91
	v_mul_f32_e32 v98, v90, v98
	v_mul_f32_e32 v99, v91, v99
	v_fma_f32 v98, v90, v98, v90
	v_fma_f32 v99, v91, v99, v91
	v_mul_f32_e32 v98, 0x3f4c422a, v98
	v_mul_f32_e32 v99, 0x3f4c422a, v99
	v_add_f32_e32 v98, v98, v98
	v_add_f32_e32 v99, v99, v99
	v_mul_f32_e32 v98, 0x3fb8aa3b, v98
	v_mul_f32_e32 v99, 0x3fb8aa3b, v99
	v_exp_f32_e32 v98, v98
	v_exp_f32_e32 v99, v99
	v_rcp_f32_e32 v97, v97
	v_pk_mul_f32 v[90:91], v[90:91], 0.5 op_sel_hi:[1,0]
	v_add_f32_e32 v98, 1.0, v98
	v_add_f32_e32 v99, 1.0, v99
	v_rcp_f32_e32 v98, v98
	v_rcp_f32_e32 v99, v99
	v_pk_fma_f32 v[96:97], v[96:97], 2.0, 1.0 op_sel_hi:[1,0,0] neg_lo:[1,0,0] neg_hi:[1,0,0]
	s_nop 0
	v_pk_add_f32 v[96:97], v[96:97], 1.0 op_sel_hi:[1,0]
	s_nop 0
	v_pk_mul_f32 v[96:97], v[88:89], v[96:97]
	v_pk_fma_f32 v[88:89], v[98:99], 2.0, 1.0 op_sel_hi:[1,0,0] neg_lo:[1,0,0] neg_hi:[1,0,0]
	s_nop 0
	v_pk_add_f32 v[88:89], v[88:89], 1.0 op_sel_hi:[1,0]
	s_nop 0
	v_pk_mul_f32 v[98:99], v[90:91], v[88:89]
	v_cvt_pk_bf16_f32 v88, v92, v93
	v_or_b32_e32 v92, v108, v132
	v_lshlrev_b32_e32 v92, 10, v92
	v_mov_b32_e32 v93, v173
	v_lshl_add_u64 v[92:93], s[8:9], 0, v[92:93]
	v_lshl_add_u64 v[92:93], v[92:93], 0, s[22:23]
	v_cvt_pk_bf16_f32 v89, v94, v95
	v_cvt_pk_bf16_f32 v90, v96, v97
	v_cvt_pk_bf16_f32 v91, v98, v99
	v_lshl_add_u64 v[92:93], v[92:93], 0, v[182:183]
	global_store_dwordx4 v[92:93], v[88:91], off
	v_or_b32_e32 v92, 0x600, v209
	s_nop 0
	v_lshlrev_b32_e32 v88, 16, v124
	v_and_b32_e32 v89, 0xffff0000, v124
	v_pk_fma_f32 v[84:85], v[52:53], v[88:89], v[84:85]
	v_lshlrev_b32_e32 v90, 16, v125
	v_mul_f32_e32 v88, 0x3d372713, v84
	v_mul_f32_e32 v89, 0x3d372713, v85
	v_and_b32_e32 v91, 0xffff0000, v125
	v_mul_f32_e32 v88, v84, v88
	v_mul_f32_e32 v89, v85, v89
	v_pk_fma_f32 v[86:87], v[54:55], v[90:91], v[86:87]
	v_fma_f32 v88, v84, v88, v84
	v_fma_f32 v89, v85, v89, v85
	v_mul_f32_e32 v90, 0x3d372713, v86
	v_mul_f32_e32 v91, 0x3d372713, v87
	v_mul_f32_e32 v88, 0x3f4c422a, v88
	v_mul_f32_e32 v89, 0x3f4c422a, v89
	v_mul_f32_e32 v90, v86, v90
	v_mul_f32_e32 v91, v87, v91
	v_add_f32_e32 v88, v88, v88
	v_add_f32_e32 v89, v89, v89
	v_fma_f32 v90, v86, v90, v86
	v_fma_f32 v91, v87, v91, v87
	v_mul_f32_e32 v88, 0x3fb8aa3b, v88
	v_mul_f32_e32 v89, 0x3fb8aa3b, v89
	v_mul_f32_e32 v90, 0x3f4c422a, v90
	v_mul_f32_e32 v91, 0x3f4c422a, v91
	v_exp_f32_e32 v88, v88
	v_exp_f32_e32 v89, v89
	v_add_f32_e32 v90, v90, v90
	v_add_f32_e32 v91, v91, v91
	v_mul_f32_e32 v90, 0x3fb8aa3b, v90
	v_mul_f32_e32 v91, 0x3fb8aa3b, v91
	v_exp_f32_e32 v90, v90
	v_exp_f32_e32 v91, v91
	v_add_f32_e32 v88, 1.0, v88
	v_add_f32_e32 v89, 1.0, v89
	v_rcp_f32_e32 v88, v88
	v_rcp_f32_e32 v89, v89
	v_add_f32_e32 v90, 1.0, v90
	v_add_f32_e32 v91, 1.0, v91
	v_rcp_f32_e32 v90, v90
	v_rcp_f32_e32 v91, v91
	v_pk_fma_f32 v[88:89], v[88:89], 2.0, 1.0 op_sel_hi:[1,0,0] neg_lo:[1,0,0] neg_hi:[1,0,0]
	v_pk_mul_f32 v[84:85], v[84:85], 0.5 op_sel_hi:[1,0]
	v_pk_add_f32 v[88:89], v[88:89], 1.0 op_sel_hi:[1,0]
	v_pk_mul_f32 v[86:87], v[86:87], 0.5 op_sel_hi:[1,0]
	v_pk_mul_f32 v[84:85], v[84:85], v[88:89]
	v_pk_fma_f32 v[88:89], v[90:91], 2.0, 1.0 op_sel_hi:[1,0,0] neg_lo:[1,0,0] neg_hi:[1,0,0]
	v_lshlrev_b32_e32 v90, 16, v126
	v_and_b32_e32 v91, 0xffff0000, v126
	v_pk_fma_f32 v[80:81], v[44:45], v[90:91], v[80:81]
	v_pk_add_f32 v[88:89], v[88:89], 1.0 op_sel_hi:[1,0]
	v_mul_f32_e32 v90, 0x3d372713, v80
	v_mul_f32_e32 v91, 0x3d372713, v81
	v_mul_f32_e32 v90, v80, v90
	v_mul_f32_e32 v91, v81, v91
	v_fma_f32 v90, v80, v90, v80
	v_fma_f32 v91, v81, v91, v81
	v_mul_f32_e32 v90, 0x3f4c422a, v90
	v_mul_f32_e32 v91, 0x3f4c422a, v91
	v_add_f32_e32 v90, v90, v90
	v_add_f32_e32 v91, v91, v91
	v_mul_f32_e32 v90, 0x3fb8aa3b, v90
	v_mul_f32_e32 v91, 0x3fb8aa3b, v91
	v_exp_f32_e32 v90, v90
	v_exp_f32_e32 v91, v91
	v_pk_mul_f32 v[86:87], v[86:87], v[88:89]
	v_pk_mul_f32 v[80:81], v[80:81], 0.5 op_sel_hi:[1,0]
	v_add_f32_e32 v88, 1.0, v90
	v_add_f32_e32 v89, 1.0, v91
	v_lshlrev_b32_e32 v90, 16, v127
	v_and_b32_e32 v91, 0xffff0000, v127
	v_pk_fma_f32 v[82:83], v[46:47], v[90:91], v[82:83]
	v_rcp_f32_e32 v88, v88
	v_mul_f32_e32 v90, 0x3d372713, v82
	v_mul_f32_e32 v91, 0x3d372713, v83
	v_mul_f32_e32 v90, v82, v90
	v_mul_f32_e32 v91, v83, v91
	v_fma_f32 v90, v82, v90, v82
	v_fma_f32 v91, v83, v91, v83
	v_mul_f32_e32 v90, 0x3f4c422a, v90
	v_mul_f32_e32 v91, 0x3f4c422a, v91
	v_add_f32_e32 v90, v90, v90
	v_add_f32_e32 v91, v91, v91
	v_mul_f32_e32 v90, 0x3fb8aa3b, v90
	v_mul_f32_e32 v91, 0x3fb8aa3b, v91
	v_exp_f32_e32 v90, v90
	v_exp_f32_e32 v91, v91
	v_rcp_f32_e32 v89, v89
	v_pk_mul_f32 v[82:83], v[82:83], 0.5 op_sel_hi:[1,0]
	v_add_f32_e32 v90, 1.0, v90
	v_add_f32_e32 v91, 1.0, v91
	v_rcp_f32_e32 v90, v90
	v_rcp_f32_e32 v91, v91
	v_pk_fma_f32 v[88:89], v[88:89], 2.0, 1.0 op_sel_hi:[1,0,0] neg_lo:[1,0,0] neg_hi:[1,0,0]
	s_nop 0
	v_pk_add_f32 v[88:89], v[88:89], 1.0 op_sel_hi:[1,0]
	s_nop 0
	v_pk_mul_f32 v[88:89], v[80:81], v[88:89]
	v_pk_fma_f32 v[80:81], v[90:91], 2.0, 1.0 op_sel_hi:[1,0,0] neg_lo:[1,0,0] neg_hi:[1,0,0]
	s_nop 0
	v_pk_add_f32 v[80:81], v[80:81], 1.0 op_sel_hi:[1,0]
	s_nop 0
	v_pk_mul_f32 v[90:91], v[82:83], v[80:81]
	v_cvt_pk_bf16_f32 v80, v84, v85
	v_or_b32_e32 v84, v92, v144
	v_lshlrev_b32_e32 v84, 10, v84
	v_mov_b32_e32 v85, v173
	v_lshl_add_u64 v[84:85], s[8:9], 0, v[84:85]
	v_cvt_pk_bf16_f32 v81, v86, v87
	v_lshl_add_u64 v[84:85], v[84:85], 0, s[22:23]
	v_lshlrev_b32_e32 v86, 16, v112
	v_and_b32_e32 v87, 0xffff0000, v112
	v_cvt_pk_bf16_f32 v82, v88, v89
	v_cvt_pk_bf16_f32 v83, v90, v91
	v_lshl_add_u64 v[84:85], v[84:85], 0, v[182:183]
	v_pk_fma_f32 v[76:77], v[52:53], v[86:87], v[76:77]
	global_store_dwordx4 v[84:85], v[80:83], off
	v_mul_f32_e32 v86, 0x3d372713, v76
	v_mul_f32_e32 v87, 0x3d372713, v77
	v_lshlrev_b32_e32 v82, 16, v113
	v_and_b32_e32 v83, 0xffff0000, v113
	v_mul_f32_e32 v86, v76, v86
	v_mul_f32_e32 v87, v77, v87
	v_pk_fma_f32 v[78:79], v[54:55], v[82:83], v[78:79]
	v_fma_f32 v86, v76, v86, v76
	v_fma_f32 v87, v77, v87, v77
	v_mul_f32_e32 v82, 0x3d372713, v78
	v_mul_f32_e32 v83, 0x3d372713, v79
	v_mul_f32_e32 v86, 0x3f4c422a, v86
	v_mul_f32_e32 v87, 0x3f4c422a, v87
	v_mul_f32_e32 v82, v78, v82
	v_mul_f32_e32 v83, v79, v83
	v_add_f32_e32 v86, v86, v86
	v_add_f32_e32 v87, v87, v87
	v_fma_f32 v82, v78, v82, v78
	v_fma_f32 v83, v79, v83, v79
	v_mul_f32_e32 v86, 0x3fb8aa3b, v86
	v_mul_f32_e32 v87, 0x3fb8aa3b, v87
	v_mul_f32_e32 v82, 0x3f4c422a, v82
	v_mul_f32_e32 v83, 0x3f4c422a, v83
	v_exp_f32_e32 v86, v86
	v_exp_f32_e32 v87, v87
	v_add_f32_e32 v82, v82, v82
	v_add_f32_e32 v83, v83, v83
	v_mul_f32_e32 v82, 0x3fb8aa3b, v82
	v_mul_f32_e32 v83, 0x3fb8aa3b, v83
	v_exp_f32_e32 v82, v82
	v_exp_f32_e32 v83, v83
	v_add_f32_e32 v80, 1.0, v86
	v_add_f32_e32 v81, 1.0, v87
	v_rcp_f32_e32 v80, v80
	v_rcp_f32_e32 v81, v81
	v_add_f32_e32 v82, 1.0, v82
	v_add_f32_e32 v83, 1.0, v83
	v_rcp_f32_e32 v82, v82
	v_rcp_f32_e32 v83, v83
	v_pk_fma_f32 v[80:81], v[80:81], 2.0, 1.0 op_sel_hi:[1,0,0] neg_lo:[1,0,0] neg_hi:[1,0,0]
	v_pk_mul_f32 v[76:77], v[76:77], 0.5 op_sel_hi:[1,0]
	v_pk_add_f32 v[80:81], v[80:81], 1.0 op_sel_hi:[1,0]
	v_pk_mul_f32 v[78:79], v[78:79], 0.5 op_sel_hi:[1,0]
	v_pk_mul_f32 v[76:77], v[76:77], v[80:81]
	v_pk_fma_f32 v[80:81], v[82:83], 2.0, 1.0 op_sel_hi:[1,0,0] neg_lo:[1,0,0] neg_hi:[1,0,0]
	v_lshlrev_b32_e32 v82, 16, v114
	v_and_b32_e32 v83, 0xffff0000, v114
	v_pk_fma_f32 v[72:73], v[44:45], v[82:83], v[72:73]
	v_pk_add_f32 v[80:81], v[80:81], 1.0 op_sel_hi:[1,0]
	v_mul_f32_e32 v82, 0x3d372713, v72
	v_mul_f32_e32 v83, 0x3d372713, v73
	v_mul_f32_e32 v82, v72, v82
	v_mul_f32_e32 v83, v73, v83
	v_fma_f32 v82, v72, v82, v72
	v_fma_f32 v83, v73, v83, v73
	v_mul_f32_e32 v82, 0x3f4c422a, v82
	v_mul_f32_e32 v83, 0x3f4c422a, v83
	v_add_f32_e32 v82, v82, v82
	v_add_f32_e32 v83, v83, v83
	v_mul_f32_e32 v82, 0x3fb8aa3b, v82
	v_mul_f32_e32 v83, 0x3fb8aa3b, v83
	v_exp_f32_e32 v82, v82
	v_exp_f32_e32 v83, v83
	v_pk_mul_f32 v[78:79], v[78:79], v[80:81]
	v_pk_mul_f32 v[72:73], v[72:73], 0.5 op_sel_hi:[1,0]
	v_add_f32_e32 v80, 1.0, v82
	v_add_f32_e32 v81, 1.0, v83
	v_lshlrev_b32_e32 v82, 16, v115
	v_and_b32_e32 v83, 0xffff0000, v115
	v_pk_fma_f32 v[74:75], v[46:47], v[82:83], v[74:75]
	v_rcp_f32_e32 v80, v80
	v_mul_f32_e32 v82, 0x3d372713, v74
	v_mul_f32_e32 v83, 0x3d372713, v75
	v_mul_f32_e32 v82, v74, v82
	v_mul_f32_e32 v83, v75, v83
	v_fma_f32 v82, v74, v82, v74
	v_fma_f32 v83, v75, v83, v75
	v_mul_f32_e32 v82, 0x3f4c422a, v82
	v_mul_f32_e32 v83, 0x3f4c422a, v83
	v_add_f32_e32 v82, v82, v82
	v_add_f32_e32 v83, v83, v83
	v_mul_f32_e32 v82, 0x3fb8aa3b, v82
	v_mul_f32_e32 v83, 0x3fb8aa3b, v83
	v_exp_f32_e32 v82, v82
	v_exp_f32_e32 v83, v83
	v_rcp_f32_e32 v81, v81
	v_pk_mul_f32 v[74:75], v[74:75], 0.5 op_sel_hi:[1,0]
	v_add_f32_e32 v82, 1.0, v82
	v_add_f32_e32 v83, 1.0, v83
	v_rcp_f32_e32 v82, v82
	v_rcp_f32_e32 v83, v83
	v_pk_fma_f32 v[80:81], v[80:81], 2.0, 1.0 op_sel_hi:[1,0,0] neg_lo:[1,0,0] neg_hi:[1,0,0]
	s_nop 0
	v_pk_add_f32 v[80:81], v[80:81], 1.0 op_sel_hi:[1,0]
	s_nop 0
	v_pk_mul_f32 v[80:81], v[72:73], v[80:81]
	v_pk_fma_f32 v[72:73], v[82:83], 2.0, 1.0 op_sel_hi:[1,0,0] neg_lo:[1,0,0] neg_hi:[1,0,0]
	s_nop 0
	v_pk_add_f32 v[72:73], v[72:73], 1.0 op_sel_hi:[1,0]
	s_nop 0
	v_pk_mul_f32 v[82:83], v[74:75], v[72:73]
	v_cvt_pk_bf16_f32 v72, v76, v77
	v_or_b32_e32 v76, v92, v132
	v_lshlrev_b32_e32 v76, 10, v76
	v_mov_b32_e32 v77, v173
	v_lshl_add_u64 v[76:77], s[8:9], 0, v[76:77]
	v_lshl_add_u64 v[76:77], v[76:77], 0, s[22:23]
	v_cvt_pk_bf16_f32 v73, v78, v79
	v_cvt_pk_bf16_f32 v74, v80, v81
	v_cvt_pk_bf16_f32 v75, v82, v83
	v_lshl_add_u64 v[76:77], v[76:77], 0, v[182:183]
	global_store_dwordx4 v[76:77], v[72:75], off
	s_nop 1
	v_add_u32_e32 v72, 0x80, v207
	v_mad_i64_i32 v[72:73], s[26:27], v72, s42, v[176:177]
	v_lshl_add_u64 v[72:73], v[72:73], 0, v[172:173]
	global_load_dwordx4 v[100:103], v[72:73], off
	global_load_dwordx4 v[96:99], v[72:73], off offset:256
	v_add_u32_e32 v72, 0x90, v207
	v_mad_i64_i32 v[72:73], s[26:27], v72, s42, v[176:177]
	v_lshl_add_u64 v[72:73], v[72:73], 0, v[172:173]
	global_load_dwordx4 v[92:95], v[72:73], off
	global_load_dwordx4 v[88:91], v[72:73], off offset:256
	v_add_u32_e32 v72, 0xa0, v207
	v_mad_i64_i32 v[72:73], s[26:27], v72, s42, v[176:177]
	v_lshl_add_u64 v[72:73], v[72:73], 0, v[172:173]
	global_load_dwordx4 v[84:87], v[72:73], off
	global_load_dwordx4 v[80:83], v[72:73], off offset:256
	v_add_u32_e32 v72, 0xb0, v207
	v_mad_i64_i32 v[72:73], s[26:27], v72, s42, v[176:177]
	v_lshl_add_u64 v[72:73], v[72:73], 0, v[172:173]
	global_load_dwordx4 v[76:79], v[72:73], off
	s_nop 0
	global_load_dwordx4 v[72:75], v[72:73], off offset:256
	s_waitcnt vmcnt(7)
	v_lshlrev_b32_e32 v104, 16, v100
	v_and_b32_e32 v105, 0xffff0000, v100
	v_pk_fma_f32 v[104:105], v[52:53], v[104:105], v[68:69]
	s_addk_i32 s24, 0x1000
	v_mul_f32_e32 v68, 0x3d372713, v104
	v_mul_f32_e32 v68, v104, v68
	v_fma_f32 v68, v104, v68, v104
	v_mul_f32_e32 v68, 0x3f4c422a, v68
	v_add_f32_e32 v68, v68, v68
	v_mul_f32_e32 v68, 0x3fb8aa3b, v68
	v_exp_f32_e32 v69, v68
	v_mul_f32_e32 v68, 0x3d372713, v105
	v_mul_f32_e32 v68, v105, v68
	v_fma_f32 v68, v105, v68, v105
	v_mul_f32_e32 v68, 0x3f4c422a, v68
	v_add_f32_e32 v68, v68, v68
	v_mul_f32_e32 v68, 0x3fb8aa3b, v68
	v_exp_f32_e32 v100, v68
	v_add_f32_e32 v69, 1.0, v69
	v_rcp_f32_e32 v106, v69
	v_pk_mul_f32 v[104:105], v[104:105], 0.5 op_sel_hi:[1,0]
	v_add_f32_e32 v69, 1.0, v100
	v_lshlrev_b32_e32 v100, 16, v101
	v_and_b32_e32 v101, 0xffff0000, v101
	v_pk_fma_f32 v[70:71], v[54:55], v[100:101], v[70:71]
	v_rcp_f32_e32 v107, v69
	v_mul_f32_e32 v69, 0x3d372713, v70
	v_mul_f32_e32 v69, v70, v69
	v_mul_f32_e32 v100, 0x3d372713, v71
	v_fma_f32 v69, v70, v69, v70
	v_mul_f32_e32 v100, v71, v100
	v_mul_f32_e32 v69, 0x3f4c422a, v69
	v_fma_f32 v100, v71, v100, v71
	v_add_f32_e32 v69, v69, v69
	v_mul_f32_e32 v100, 0x3f4c422a, v100
	v_mul_f32_e32 v69, 0x3fb8aa3b, v69
	v_add_f32_e32 v100, v100, v100
	v_exp_f32_e32 v69, v69
	v_mul_f32_e32 v100, 0x3fb8aa3b, v100
	v_exp_f32_e32 v108, v100
	v_pk_fma_f32 v[100:101], v[106:107], 2.0, 1.0 op_sel_hi:[1,0,0] neg_lo:[1,0,0] neg_hi:[1,0,0]
	v_add_f32_e32 v69, 1.0, v69
	v_rcp_f32_e32 v106, v69
	v_add_f32_e32 v69, 1.0, v108
	v_rcp_f32_e32 v107, v69
	v_pk_add_f32 v[100:101], v[100:101], 1.0 op_sel_hi:[1,0]
	v_pk_mul_f32 v[70:71], v[70:71], 0.5 op_sel_hi:[1,0]
	v_pk_mul_f32 v[100:101], v[104:105], v[100:101]
	v_pk_fma_f32 v[104:105], v[106:107], 2.0, 1.0 op_sel_hi:[1,0,0] neg_lo:[1,0,0] neg_hi:[1,0,0]
	v_lshlrev_b32_e32 v106, 16, v102
	v_and_b32_e32 v107, 0xffff0000, v102
	v_pk_fma_f32 v[64:65], v[44:45], v[106:107], v[64:65]
	v_pk_add_f32 v[104:105], v[104:105], 1.0 op_sel_hi:[1,0]
	v_mul_f32_e32 v69, 0x3d372713, v64
	v_mul_f32_e32 v69, v64, v69
	v_mul_f32_e32 v102, 0x3d372713, v65
	v_fma_f32 v69, v64, v69, v64
	v_mul_f32_e32 v102, v65, v102
	v_mul_f32_e32 v69, 0x3f4c422a, v69
	v_fma_f32 v102, v65, v102, v65
	v_add_f32_e32 v69, v69, v69
	v_mul_f32_e32 v102, 0x3f4c422a, v102
	v_mul_f32_e32 v69, 0x3fb8aa3b, v69
	v_add_f32_e32 v102, v102, v102
	v_exp_f32_e32 v69, v69
	v_mul_f32_e32 v102, 0x3fb8aa3b, v102
	v_exp_f32_e32 v102, v102
	v_pk_mul_f32 v[70:71], v[70:71], v[104:105]
	v_add_f32_e32 v69, 1.0, v69
	v_rcp_f32_e32 v104, v69
	v_add_f32_e32 v69, 1.0, v102
	v_lshlrev_b32_e32 v102, 16, v103
	v_and_b32_e32 v103, 0xffff0000, v103
	v_pk_fma_f32 v[66:67], v[46:47], v[102:103], v[66:67]
	v_rcp_f32_e32 v105, v69
	v_mul_f32_e32 v69, 0x3d372713, v66
	v_mul_f32_e32 v69, v66, v69
	v_mul_f32_e32 v102, 0x3d372713, v67
	v_fma_f32 v69, v66, v69, v66
	v_mul_f32_e32 v102, v67, v102
	v_mul_f32_e32 v69, 0x3f4c422a, v69
	v_fma_f32 v102, v67, v102, v67
	v_add_f32_e32 v69, v69, v69
	v_mul_f32_e32 v102, 0x3f4c422a, v102
	v_mul_f32_e32 v69, 0x3fb8aa3b, v69
	v_add_f32_e32 v102, v102, v102
	v_exp_f32_e32 v69, v69
	v_mul_f32_e32 v102, 0x3fb8aa3b, v102
	v_exp_f32_e32 v106, v102
	v_pk_fma_f32 v[102:103], v[104:105], 2.0, 1.0 op_sel_hi:[1,0,0] neg_lo:[1,0,0] neg_hi:[1,0,0]
	v_add_f32_e32 v69, 1.0, v69
	v_rcp_f32_e32 v104, v69
	v_add_f32_e32 v69, 1.0, v106
	v_rcp_f32_e32 v105, v69
	s_and_b32 s24, s24, 0x3000
	v_or_b32_e32 v68, s24, v208
	v_pk_mul_f32 v[64:65], v[64:65], 0.5 op_sel_hi:[1,0]
	v_pk_add_f32 v[102:103], v[102:103], 1.0 op_sel_hi:[1,0]
	v_or_b32_e32 v69, v68, v144
	v_pk_mul_f32 v[102:103], v[64:65], v[102:103]
	v_pk_fma_f32 v[64:65], v[104:105], 2.0, 1.0 op_sel_hi:[1,0,0] neg_lo:[1,0,0] neg_hi:[1,0,0]
	v_pk_mul_f32 v[66:67], v[66:67], 0.5 op_sel_hi:[1,0]
	v_pk_add_f32 v[64:65], v[64:65], 1.0 op_sel_hi:[1,0]
	v_lshlrev_b32_e32 v172, 10, v69
	v_pk_mul_f32 v[104:105], v[66:67], v[64:65]
	v_cvt_pk_bf16_f32 v65, v70, v71
	v_lshl_add_u64 v[70:71], s[8:9], 0, v[172:173]
	v_cvt_pk_bf16_f32 v64, v100, v101
	v_lshl_add_u64 v[70:71], v[70:71], 0, s[22:23]
	s_waitcnt vmcnt(6)
	v_lshlrev_b32_e32 v100, 16, v96
	v_and_b32_e32 v101, 0xffff0000, v96
	v_cvt_pk_bf16_f32 v66, v102, v103
	v_cvt_pk_bf16_f32 v67, v104, v105
	v_lshl_add_u64 v[70:71], v[70:71], 0, v[182:183]
	v_pk_fma_f32 v[60:61], v[52:53], v[100:101], v[60:61]
	global_store_dwordx4 v[70:71], v[64:67], off
	v_mul_f32_e32 v69, 0x3d372713, v60
	v_mul_f32_e32 v96, 0x3d372713, v61
	v_lshlrev_b32_e32 v66, 16, v97
	v_and_b32_e32 v67, 0xffff0000, v97
	v_mul_f32_e32 v69, v60, v69
	v_mul_f32_e32 v96, v61, v96
	v_pk_fma_f32 v[62:63], v[54:55], v[66:67], v[62:63]
	v_fma_f32 v69, v60, v69, v60
	v_fma_f32 v96, v61, v96, v61
	v_mul_f32_e32 v66, 0x3d372713, v62
	v_mul_f32_e32 v67, 0x3d372713, v63
	v_mul_f32_e32 v69, 0x3f4c422a, v69
	v_mul_f32_e32 v96, 0x3f4c422a, v96
	v_mul_f32_e32 v66, v62, v66
	v_mul_f32_e32 v67, v63, v67
	v_add_f32_e32 v69, v69, v69
	v_add_f32_e32 v96, v96, v96
	v_fma_f32 v66, v62, v66, v62
	v_fma_f32 v67, v63, v67, v63
	v_mul_f32_e32 v69, 0x3fb8aa3b, v69
	v_mul_f32_e32 v96, 0x3fb8aa3b, v96
	v_mul_f32_e32 v66, 0x3f4c422a, v66
	v_mul_f32_e32 v67, 0x3f4c422a, v67
	v_exp_f32_e32 v69, v69
	v_exp_f32_e32 v96, v96
	v_add_f32_e32 v66, v66, v66
	v_add_f32_e32 v67, v67, v67
	v_mul_f32_e32 v66, 0x3fb8aa3b, v66
	v_mul_f32_e32 v67, 0x3fb8aa3b, v67
	v_exp_f32_e32 v66, v66
	v_exp_f32_e32 v67, v67
	v_add_f32_e32 v64, 1.0, v69
	v_add_f32_e32 v65, 1.0, v96
	v_rcp_f32_e32 v64, v64
	v_rcp_f32_e32 v65, v65
	v_add_f32_e32 v66, 1.0, v66
	v_add_f32_e32 v67, 1.0, v67
	v_rcp_f32_e32 v66, v66
	v_rcp_f32_e32 v67, v67
	v_pk_fma_f32 v[64:65], v[64:65], 2.0, 1.0 op_sel_hi:[1,0,0] neg_lo:[1,0,0] neg_hi:[1,0,0]
	v_pk_mul_f32 v[60:61], v[60:61], 0.5 op_sel_hi:[1,0]
	v_pk_add_f32 v[64:65], v[64:65], 1.0 op_sel_hi:[1,0]
	v_pk_mul_f32 v[62:63], v[62:63], 0.5 op_sel_hi:[1,0]
	v_pk_mul_f32 v[60:61], v[60:61], v[64:65]
	v_pk_fma_f32 v[64:65], v[66:67], 2.0, 1.0 op_sel_hi:[1,0,0] neg_lo:[1,0,0] neg_hi:[1,0,0]
	v_lshlrev_b32_e32 v66, 16, v98
	v_and_b32_e32 v67, 0xffff0000, v98
	v_pk_fma_f32 v[56:57], v[44:45], v[66:67], v[56:57]
	v_pk_add_f32 v[64:65], v[64:65], 1.0 op_sel_hi:[1,0]
	v_mul_f32_e32 v66, 0x3d372713, v56
	v_mul_f32_e32 v67, 0x3d372713, v57
	v_mul_f32_e32 v66, v56, v66
	v_mul_f32_e32 v67, v57, v67
	v_fma_f32 v66, v56, v66, v56
	v_fma_f32 v67, v57, v67, v57
	v_mul_f32_e32 v66, 0x3f4c422a, v66
	v_mul_f32_e32 v67, 0x3f4c422a, v67
	v_add_f32_e32 v66, v66, v66
	v_add_f32_e32 v67, v67, v67
	v_mul_f32_e32 v66, 0x3fb8aa3b, v66
	v_mul_f32_e32 v67, 0x3fb8aa3b, v67
	v_exp_f32_e32 v66, v66
	v_exp_f32_e32 v67, v67
	v_pk_mul_f32 v[62:63], v[62:63], v[64:65]
	v_pk_mul_f32 v[56:57], v[56:57], 0.5 op_sel_hi:[1,0]
	v_add_f32_e32 v64, 1.0, v66
	v_add_f32_e32 v65, 1.0, v67
	v_lshlrev_b32_e32 v66, 16, v99
	v_and_b32_e32 v67, 0xffff0000, v99
	v_pk_fma_f32 v[58:59], v[46:47], v[66:67], v[58:59]
	v_rcp_f32_e32 v64, v64
	v_mul_f32_e32 v66, 0x3d372713, v58
	v_mul_f32_e32 v67, 0x3d372713, v59
	v_mul_f32_e32 v66, v58, v66
	v_mul_f32_e32 v67, v59, v67
	v_fma_f32 v66, v58, v66, v58
	v_fma_f32 v67, v59, v67, v59
	v_mul_f32_e32 v66, 0x3f4c422a, v66
	v_mul_f32_e32 v67, 0x3f4c422a, v67
	v_add_f32_e32 v66, v66, v66
	v_add_f32_e32 v67, v67, v67
	v_mul_f32_e32 v66, 0x3fb8aa3b, v66
	v_mul_f32_e32 v67, 0x3fb8aa3b, v67
	v_exp_f32_e32 v66, v66
	v_exp_f32_e32 v67, v67
	v_rcp_f32_e32 v65, v65
	v_pk_mul_f32 v[58:59], v[58:59], 0.5 op_sel_hi:[1,0]
	v_add_f32_e32 v66, 1.0, v66
	v_add_f32_e32 v67, 1.0, v67
	v_rcp_f32_e32 v66, v66
	v_rcp_f32_e32 v67, v67
	v_pk_fma_f32 v[64:65], v[64:65], 2.0, 1.0 op_sel_hi:[1,0,0] neg_lo:[1,0,0] neg_hi:[1,0,0]
	s_nop 0
	v_pk_add_f32 v[64:65], v[64:65], 1.0 op_sel_hi:[1,0]
	s_nop 0
	v_pk_mul_f32 v[64:65], v[56:57], v[64:65]
	v_pk_fma_f32 v[56:57], v[66:67], 2.0, 1.0 op_sel_hi:[1,0,0] neg_lo:[1,0,0] neg_hi:[1,0,0]
	s_nop 0
	v_pk_add_f32 v[56:57], v[56:57], 1.0 op_sel_hi:[1,0]
	s_nop 0
	v_pk_mul_f32 v[66:67], v[58:59], v[56:57]
	v_cvt_pk_bf16_f32 v56, v60, v61
	v_or_b32_e32 v60, v68, v132
	v_lshlrev_b32_e32 v172, 10, v60
	v_lshl_add_u64 v[60:61], s[8:9], 0, v[172:173]
	v_lshl_add_u64 v[60:61], v[60:61], 0, s[22:23]
	v_cvt_pk_bf16_f32 v57, v62, v63
	v_cvt_pk_bf16_f32 v58, v64, v65
	v_cvt_pk_bf16_f32 v59, v66, v67
	v_lshl_add_u64 v[60:61], v[60:61], 0, v[182:183]
	global_store_dwordx4 v[60:61], v[56:59], off
	v_or_b32_e32 v60, 0x200, v68
	s_waitcnt vmcnt(7)
	v_lshlrev_b32_e32 v56, 16, v92
	v_and_b32_e32 v57, 0xffff0000, v92
	v_pk_fma_f32 v[48:49], v[52:53], v[56:57], v[48:49]
	v_lshlrev_b32_e32 v58, 16, v93
	v_mul_f32_e32 v56, 0x3d372713, v48
	v_mul_f32_e32 v57, 0x3d372713, v49
	v_and_b32_e32 v59, 0xffff0000, v93
	v_mul_f32_e32 v56, v48, v56
	v_mul_f32_e32 v57, v49, v57
	v_pk_fma_f32 v[50:51], v[54:55], v[58:59], v[50:51]
	v_fma_f32 v56, v48, v56, v48
	v_fma_f32 v57, v49, v57, v49
	v_mul_f32_e32 v58, 0x3d372713, v50
	v_mul_f32_e32 v59, 0x3d372713, v51
	v_mul_f32_e32 v56, 0x3f4c422a, v56
	v_mul_f32_e32 v57, 0x3f4c422a, v57
	v_mul_f32_e32 v58, v50, v58
	v_mul_f32_e32 v59, v51, v59
	v_add_f32_e32 v56, v56, v56
	v_add_f32_e32 v57, v57, v57
	v_fma_f32 v58, v50, v58, v50
	v_fma_f32 v59, v51, v59, v51
	v_mul_f32_e32 v56, 0x3fb8aa3b, v56
	v_mul_f32_e32 v57, 0x3fb8aa3b, v57
	v_mul_f32_e32 v58, 0x3f4c422a, v58
	v_mul_f32_e32 v59, 0x3f4c422a, v59
	v_exp_f32_e32 v56, v56
	v_exp_f32_e32 v57, v57
	v_add_f32_e32 v58, v58, v58
	v_add_f32_e32 v59, v59, v59
	v_mul_f32_e32 v58, 0x3fb8aa3b, v58
	v_mul_f32_e32 v59, 0x3fb8aa3b, v59
	v_exp_f32_e32 v58, v58
	v_exp_f32_e32 v59, v59
	v_add_f32_e32 v56, 1.0, v56
	v_add_f32_e32 v57, 1.0, v57
	v_rcp_f32_e32 v56, v56
	v_rcp_f32_e32 v57, v57
	v_add_f32_e32 v58, 1.0, v58
	v_add_f32_e32 v59, 1.0, v59
	v_rcp_f32_e32 v58, v58
	v_rcp_f32_e32 v59, v59
	v_pk_fma_f32 v[56:57], v[56:57], 2.0, 1.0 op_sel_hi:[1,0,0] neg_lo:[1,0,0] neg_hi:[1,0,0]
	v_pk_mul_f32 v[48:49], v[48:49], 0.5 op_sel_hi:[1,0]
	v_pk_add_f32 v[56:57], v[56:57], 1.0 op_sel_hi:[1,0]
	v_pk_mul_f32 v[50:51], v[50:51], 0.5 op_sel_hi:[1,0]
	v_pk_mul_f32 v[48:49], v[48:49], v[56:57]
	v_pk_fma_f32 v[56:57], v[58:59], 2.0, 1.0 op_sel_hi:[1,0,0] neg_lo:[1,0,0] neg_hi:[1,0,0]
	v_lshlrev_b32_e32 v58, 16, v94
	v_and_b32_e32 v59, 0xffff0000, v94
	v_pk_fma_f32 v[40:41], v[44:45], v[58:59], v[40:41]
	v_pk_add_f32 v[56:57], v[56:57], 1.0 op_sel_hi:[1,0]
	v_mul_f32_e32 v58, 0x3d372713, v40
	v_mul_f32_e32 v59, 0x3d372713, v41
	v_mul_f32_e32 v58, v40, v58
	v_mul_f32_e32 v59, v41, v59
	v_fma_f32 v58, v40, v58, v40
	v_fma_f32 v59, v41, v59, v41
	v_mul_f32_e32 v58, 0x3f4c422a, v58
	v_mul_f32_e32 v59, 0x3f4c422a, v59
	v_add_f32_e32 v58, v58, v58
	v_add_f32_e32 v59, v59, v59
	v_mul_f32_e32 v58, 0x3fb8aa3b, v58
	v_mul_f32_e32 v59, 0x3fb8aa3b, v59
	v_exp_f32_e32 v58, v58
	v_exp_f32_e32 v59, v59
	v_pk_mul_f32 v[50:51], v[50:51], v[56:57]
	v_pk_mul_f32 v[40:41], v[40:41], 0.5 op_sel_hi:[1,0]
	v_add_f32_e32 v56, 1.0, v58
	v_add_f32_e32 v57, 1.0, v59
	v_lshlrev_b32_e32 v58, 16, v95
	v_and_b32_e32 v59, 0xffff0000, v95
	v_pk_fma_f32 v[42:43], v[46:47], v[58:59], v[42:43]
	v_rcp_f32_e32 v56, v56
	v_mul_f32_e32 v58, 0x3d372713, v42
	v_mul_f32_e32 v59, 0x3d372713, v43
	v_mul_f32_e32 v58, v42, v58
	v_mul_f32_e32 v59, v43, v59
	v_fma_f32 v58, v42, v58, v42
	v_fma_f32 v59, v43, v59, v43
	v_mul_f32_e32 v58, 0x3f4c422a, v58
	v_mul_f32_e32 v59, 0x3f4c422a, v59
	v_add_f32_e32 v58, v58, v58
	v_add_f32_e32 v59, v59, v59
	v_mul_f32_e32 v58, 0x3fb8aa3b, v58
	v_mul_f32_e32 v59, 0x3fb8aa3b, v59
	v_exp_f32_e32 v58, v58
	v_exp_f32_e32 v59, v59
	v_rcp_f32_e32 v57, v57
	v_pk_mul_f32 v[42:43], v[42:43], 0.5 op_sel_hi:[1,0]
	v_add_f32_e32 v58, 1.0, v58
	v_add_f32_e32 v59, 1.0, v59
	v_rcp_f32_e32 v58, v58
	v_rcp_f32_e32 v59, v59
	v_pk_fma_f32 v[56:57], v[56:57], 2.0, 1.0 op_sel_hi:[1,0,0] neg_lo:[1,0,0] neg_hi:[1,0,0]
	s_nop 0
	v_pk_add_f32 v[56:57], v[56:57], 1.0 op_sel_hi:[1,0]
	s_nop 0
	v_pk_mul_f32 v[56:57], v[40:41], v[56:57]
	v_pk_fma_f32 v[40:41], v[58:59], 2.0, 1.0 op_sel_hi:[1,0,0] neg_lo:[1,0,0] neg_hi:[1,0,0]
	s_nop 0
	v_pk_add_f32 v[40:41], v[40:41], 1.0 op_sel_hi:[1,0]
	s_nop 0
	v_pk_mul_f32 v[58:59], v[42:43], v[40:41]
	v_cvt_pk_bf16_f32 v40, v48, v49
	v_or_b32_e32 v48, v60, v144
	v_lshlrev_b32_e32 v172, 10, v48
	v_lshl_add_u64 v[48:49], s[8:9], 0, v[172:173]
	v_cvt_pk_bf16_f32 v41, v50, v51
	v_lshl_add_u64 v[48:49], v[48:49], 0, s[22:23]
	s_waitcnt vmcnt(6)
	v_lshlrev_b32_e32 v50, 16, v88
	v_and_b32_e32 v51, 0xffff0000, v88
	v_cvt_pk_bf16_f32 v42, v56, v57
	v_cvt_pk_bf16_f32 v43, v58, v59
	v_lshl_add_u64 v[48:49], v[48:49], 0, v[182:183]
	v_pk_fma_f32 v[36:37], v[52:53], v[50:51], v[36:37]
	global_store_dwordx4 v[48:49], v[40:43], off
	v_mul_f32_e32 v50, 0x3d372713, v36
	v_mul_f32_e32 v51, 0x3d372713, v37
	v_lshlrev_b32_e32 v42, 16, v89
	v_and_b32_e32 v43, 0xffff0000, v89
	v_mul_f32_e32 v50, v36, v50
	v_mul_f32_e32 v51, v37, v51
	v_pk_fma_f32 v[38:39], v[54:55], v[42:43], v[38:39]
	v_fma_f32 v50, v36, v50, v36
	v_fma_f32 v51, v37, v51, v37
	v_mul_f32_e32 v42, 0x3d372713, v38
	v_mul_f32_e32 v43, 0x3d372713, v39
	v_mul_f32_e32 v50, 0x3f4c422a, v50
	v_mul_f32_e32 v51, 0x3f4c422a, v51
	v_mul_f32_e32 v42, v38, v42
	v_mul_f32_e32 v43, v39, v43
	v_add_f32_e32 v50, v50, v50
	v_add_f32_e32 v51, v51, v51
	v_fma_f32 v42, v38, v42, v38
	v_fma_f32 v43, v39, v43, v39
	v_mul_f32_e32 v50, 0x3fb8aa3b, v50
	v_mul_f32_e32 v51, 0x3fb8aa3b, v51
	v_mul_f32_e32 v42, 0x3f4c422a, v42
	v_mul_f32_e32 v43, 0x3f4c422a, v43
	v_exp_f32_e32 v50, v50
	v_exp_f32_e32 v51, v51
	v_add_f32_e32 v42, v42, v42
	v_add_f32_e32 v43, v43, v43
	v_mul_f32_e32 v42, 0x3fb8aa3b, v42
	v_mul_f32_e32 v43, 0x3fb8aa3b, v43
	v_exp_f32_e32 v42, v42
	v_exp_f32_e32 v43, v43
	v_add_f32_e32 v40, 1.0, v50
	v_add_f32_e32 v41, 1.0, v51
	v_rcp_f32_e32 v40, v40
	v_rcp_f32_e32 v41, v41
	v_add_f32_e32 v42, 1.0, v42
	v_add_f32_e32 v43, 1.0, v43
	v_rcp_f32_e32 v42, v42
	v_rcp_f32_e32 v43, v43
	v_pk_fma_f32 v[40:41], v[40:41], 2.0, 1.0 op_sel_hi:[1,0,0] neg_lo:[1,0,0] neg_hi:[1,0,0]
	v_pk_mul_f32 v[36:37], v[36:37], 0.5 op_sel_hi:[1,0]
	v_pk_add_f32 v[40:41], v[40:41], 1.0 op_sel_hi:[1,0]
	v_pk_mul_f32 v[38:39], v[38:39], 0.5 op_sel_hi:[1,0]
	v_pk_mul_f32 v[36:37], v[36:37], v[40:41]
	v_pk_fma_f32 v[40:41], v[42:43], 2.0, 1.0 op_sel_hi:[1,0,0] neg_lo:[1,0,0] neg_hi:[1,0,0]
	v_lshlrev_b32_e32 v42, 16, v90
	v_and_b32_e32 v43, 0xffff0000, v90
	v_pk_fma_f32 v[32:33], v[44:45], v[42:43], v[32:33]
	v_pk_add_f32 v[40:41], v[40:41], 1.0 op_sel_hi:[1,0]
	v_mul_f32_e32 v42, 0x3d372713, v32
	v_mul_f32_e32 v43, 0x3d372713, v33
	v_mul_f32_e32 v42, v32, v42
	v_mul_f32_e32 v43, v33, v43
	v_fma_f32 v42, v32, v42, v32
	v_fma_f32 v43, v33, v43, v33
	v_mul_f32_e32 v42, 0x3f4c422a, v42
	v_mul_f32_e32 v43, 0x3f4c422a, v43
	v_add_f32_e32 v42, v42, v42
	v_add_f32_e32 v43, v43, v43
	v_mul_f32_e32 v42, 0x3fb8aa3b, v42
	v_mul_f32_e32 v43, 0x3fb8aa3b, v43
	v_exp_f32_e32 v42, v42
	v_exp_f32_e32 v43, v43
	v_pk_mul_f32 v[38:39], v[38:39], v[40:41]
	v_pk_mul_f32 v[32:33], v[32:33], 0.5 op_sel_hi:[1,0]
	v_add_f32_e32 v40, 1.0, v42
	v_add_f32_e32 v41, 1.0, v43
	v_lshlrev_b32_e32 v42, 16, v91
	v_and_b32_e32 v43, 0xffff0000, v91
	v_pk_fma_f32 v[34:35], v[46:47], v[42:43], v[34:35]
	v_rcp_f32_e32 v40, v40
	v_mul_f32_e32 v42, 0x3d372713, v34
	v_mul_f32_e32 v43, 0x3d372713, v35
	v_mul_f32_e32 v42, v34, v42
	v_mul_f32_e32 v43, v35, v43
	v_fma_f32 v42, v34, v42, v34
	v_fma_f32 v43, v35, v43, v35
	v_mul_f32_e32 v42, 0x3f4c422a, v42
	v_mul_f32_e32 v43, 0x3f4c422a, v43
	v_add_f32_e32 v42, v42, v42
	v_add_f32_e32 v43, v43, v43
	v_mul_f32_e32 v42, 0x3fb8aa3b, v42
	v_mul_f32_e32 v43, 0x3fb8aa3b, v43
	v_exp_f32_e32 v42, v42
	v_exp_f32_e32 v43, v43
	v_rcp_f32_e32 v41, v41
	v_pk_mul_f32 v[34:35], v[34:35], 0.5 op_sel_hi:[1,0]
	v_add_f32_e32 v42, 1.0, v42
	v_add_f32_e32 v43, 1.0, v43
	v_rcp_f32_e32 v42, v42
	v_rcp_f32_e32 v43, v43
	v_pk_fma_f32 v[40:41], v[40:41], 2.0, 1.0 op_sel_hi:[1,0,0] neg_lo:[1,0,0] neg_hi:[1,0,0]
	s_nop 0
	v_pk_add_f32 v[40:41], v[40:41], 1.0 op_sel_hi:[1,0]
	s_nop 0
	v_pk_mul_f32 v[40:41], v[32:33], v[40:41]
	v_pk_fma_f32 v[32:33], v[42:43], 2.0, 1.0 op_sel_hi:[1,0,0] neg_lo:[1,0,0] neg_hi:[1,0,0]
	s_nop 0
	v_pk_add_f32 v[32:33], v[32:33], 1.0 op_sel_hi:[1,0]
	s_nop 0
	v_pk_mul_f32 v[42:43], v[34:35], v[32:33]
	v_cvt_pk_bf16_f32 v32, v36, v37
	v_or_b32_e32 v36, v60, v132
	v_lshlrev_b32_e32 v172, 10, v36
	v_lshl_add_u64 v[36:37], s[8:9], 0, v[172:173]
	v_lshl_add_u64 v[36:37], v[36:37], 0, s[22:23]
	v_cvt_pk_bf16_f32 v33, v38, v39
	v_cvt_pk_bf16_f32 v34, v40, v41
	v_cvt_pk_bf16_f32 v35, v42, v43
	v_lshl_add_u64 v[36:37], v[36:37], 0, v[182:183]
	global_store_dwordx4 v[36:37], v[32:35], off
	v_or_b32_e32 v36, 0x400, v68
	s_waitcnt vmcnt(7)
	v_lshlrev_b32_e32 v32, 16, v84
	v_and_b32_e32 v33, 0xffff0000, v84
	v_pk_fma_f32 v[28:29], v[52:53], v[32:33], v[28:29]
	v_lshlrev_b32_e32 v34, 16, v85
	v_mul_f32_e32 v32, 0x3d372713, v28
	v_mul_f32_e32 v33, 0x3d372713, v29
	v_and_b32_e32 v35, 0xffff0000, v85
	v_mul_f32_e32 v32, v28, v32
	v_mul_f32_e32 v33, v29, v33
	v_pk_fma_f32 v[30:31], v[54:55], v[34:35], v[30:31]
	v_fma_f32 v32, v28, v32, v28
	v_fma_f32 v33, v29, v33, v29
	v_mul_f32_e32 v34, 0x3d372713, v30
	v_mul_f32_e32 v35, 0x3d372713, v31
	v_mul_f32_e32 v32, 0x3f4c422a, v32
	v_mul_f32_e32 v33, 0x3f4c422a, v33
	v_mul_f32_e32 v34, v30, v34
	v_mul_f32_e32 v35, v31, v35
	v_add_f32_e32 v32, v32, v32
	v_add_f32_e32 v33, v33, v33
	v_fma_f32 v34, v30, v34, v30
	v_fma_f32 v35, v31, v35, v31
	v_mul_f32_e32 v32, 0x3fb8aa3b, v32
	v_mul_f32_e32 v33, 0x3fb8aa3b, v33
	v_mul_f32_e32 v34, 0x3f4c422a, v34
	v_mul_f32_e32 v35, 0x3f4c422a, v35
	v_exp_f32_e32 v32, v32
	v_exp_f32_e32 v33, v33
	v_add_f32_e32 v34, v34, v34
	v_add_f32_e32 v35, v35, v35
	v_mul_f32_e32 v34, 0x3fb8aa3b, v34
	v_mul_f32_e32 v35, 0x3fb8aa3b, v35
	v_exp_f32_e32 v34, v34
	v_exp_f32_e32 v35, v35
	v_add_f32_e32 v32, 1.0, v32
	v_add_f32_e32 v33, 1.0, v33
	v_rcp_f32_e32 v32, v32
	v_rcp_f32_e32 v33, v33
	v_add_f32_e32 v34, 1.0, v34
	v_add_f32_e32 v35, 1.0, v35
	v_rcp_f32_e32 v34, v34
	v_rcp_f32_e32 v35, v35
	v_pk_fma_f32 v[32:33], v[32:33], 2.0, 1.0 op_sel_hi:[1,0,0] neg_lo:[1,0,0] neg_hi:[1,0,0]
	v_pk_mul_f32 v[28:29], v[28:29], 0.5 op_sel_hi:[1,0]
	v_pk_add_f32 v[32:33], v[32:33], 1.0 op_sel_hi:[1,0]
	v_pk_mul_f32 v[30:31], v[30:31], 0.5 op_sel_hi:[1,0]
	v_pk_mul_f32 v[28:29], v[28:29], v[32:33]
	v_pk_fma_f32 v[32:33], v[34:35], 2.0, 1.0 op_sel_hi:[1,0,0] neg_lo:[1,0,0] neg_hi:[1,0,0]
	v_lshlrev_b32_e32 v34, 16, v86
	v_and_b32_e32 v35, 0xffff0000, v86
	v_pk_fma_f32 v[24:25], v[44:45], v[34:35], v[24:25]
	v_pk_add_f32 v[32:33], v[32:33], 1.0 op_sel_hi:[1,0]
	v_mul_f32_e32 v34, 0x3d372713, v24
	v_mul_f32_e32 v35, 0x3d372713, v25
	v_mul_f32_e32 v34, v24, v34
	v_mul_f32_e32 v35, v25, v35
	v_fma_f32 v34, v24, v34, v24
	v_fma_f32 v35, v25, v35, v25
	v_mul_f32_e32 v34, 0x3f4c422a, v34
	v_mul_f32_e32 v35, 0x3f4c422a, v35
	v_add_f32_e32 v34, v34, v34
	v_add_f32_e32 v35, v35, v35
	v_mul_f32_e32 v34, 0x3fb8aa3b, v34
	v_mul_f32_e32 v35, 0x3fb8aa3b, v35
	v_exp_f32_e32 v34, v34
	v_exp_f32_e32 v35, v35
	v_pk_mul_f32 v[30:31], v[30:31], v[32:33]
	v_pk_mul_f32 v[24:25], v[24:25], 0.5 op_sel_hi:[1,0]
	v_add_f32_e32 v32, 1.0, v34
	v_add_f32_e32 v33, 1.0, v35
	v_lshlrev_b32_e32 v34, 16, v87
	v_and_b32_e32 v35, 0xffff0000, v87
	v_pk_fma_f32 v[26:27], v[46:47], v[34:35], v[26:27]
	v_rcp_f32_e32 v32, v32
	v_mul_f32_e32 v34, 0x3d372713, v26
	v_mul_f32_e32 v35, 0x3d372713, v27
	v_mul_f32_e32 v34, v26, v34
	v_mul_f32_e32 v35, v27, v35
	v_fma_f32 v34, v26, v34, v26
	v_fma_f32 v35, v27, v35, v27
	v_mul_f32_e32 v34, 0x3f4c422a, v34
	v_mul_f32_e32 v35, 0x3f4c422a, v35
	v_add_f32_e32 v34, v34, v34
	v_add_f32_e32 v35, v35, v35
	v_mul_f32_e32 v34, 0x3fb8aa3b, v34
	v_mul_f32_e32 v35, 0x3fb8aa3b, v35
	v_exp_f32_e32 v34, v34
	v_exp_f32_e32 v35, v35
	v_rcp_f32_e32 v33, v33
	v_pk_mul_f32 v[26:27], v[26:27], 0.5 op_sel_hi:[1,0]
	v_add_f32_e32 v34, 1.0, v34
	v_add_f32_e32 v35, 1.0, v35
	v_rcp_f32_e32 v34, v34
	v_rcp_f32_e32 v35, v35
	v_pk_fma_f32 v[32:33], v[32:33], 2.0, 1.0 op_sel_hi:[1,0,0] neg_lo:[1,0,0] neg_hi:[1,0,0]
	s_nop 0
	v_pk_add_f32 v[32:33], v[32:33], 1.0 op_sel_hi:[1,0]
	s_nop 0
	v_pk_mul_f32 v[32:33], v[24:25], v[32:33]
	v_pk_fma_f32 v[24:25], v[34:35], 2.0, 1.0 op_sel_hi:[1,0,0] neg_lo:[1,0,0] neg_hi:[1,0,0]
	s_nop 0
	v_pk_add_f32 v[24:25], v[24:25], 1.0 op_sel_hi:[1,0]
	s_nop 0
	v_pk_mul_f32 v[34:35], v[26:27], v[24:25]
	v_cvt_pk_bf16_f32 v24, v28, v29
	v_or_b32_e32 v28, v36, v144
	v_lshlrev_b32_e32 v172, 10, v28
	v_lshl_add_u64 v[28:29], s[8:9], 0, v[172:173]
	v_cvt_pk_bf16_f32 v25, v30, v31
	v_lshl_add_u64 v[28:29], v[28:29], 0, s[22:23]
	s_waitcnt vmcnt(6)
	v_lshlrev_b32_e32 v30, 16, v80
	v_and_b32_e32 v31, 0xffff0000, v80
	v_cvt_pk_bf16_f32 v26, v32, v33
	v_cvt_pk_bf16_f32 v27, v34, v35
	v_lshl_add_u64 v[28:29], v[28:29], 0, v[182:183]
	v_pk_fma_f32 v[20:21], v[52:53], v[30:31], v[20:21]
	global_store_dwordx4 v[28:29], v[24:27], off
	v_mul_f32_e32 v30, 0x3d372713, v20
	v_mul_f32_e32 v31, 0x3d372713, v21
	v_lshlrev_b32_e32 v26, 16, v81
	v_and_b32_e32 v27, 0xffff0000, v81
	v_mul_f32_e32 v30, v20, v30
	v_mul_f32_e32 v31, v21, v31
	v_pk_fma_f32 v[22:23], v[54:55], v[26:27], v[22:23]
	v_fma_f32 v30, v20, v30, v20
	v_fma_f32 v31, v21, v31, v21
	v_mul_f32_e32 v26, 0x3d372713, v22
	v_mul_f32_e32 v27, 0x3d372713, v23
	v_mul_f32_e32 v30, 0x3f4c422a, v30
	v_mul_f32_e32 v31, 0x3f4c422a, v31
	v_mul_f32_e32 v26, v22, v26
	v_mul_f32_e32 v27, v23, v27
	v_add_f32_e32 v30, v30, v30
	v_add_f32_e32 v31, v31, v31
	v_fma_f32 v26, v22, v26, v22
	v_fma_f32 v27, v23, v27, v23
	v_mul_f32_e32 v30, 0x3fb8aa3b, v30
	v_mul_f32_e32 v31, 0x3fb8aa3b, v31
	v_mul_f32_e32 v26, 0x3f4c422a, v26
	v_mul_f32_e32 v27, 0x3f4c422a, v27
	v_exp_f32_e32 v30, v30
	v_exp_f32_e32 v31, v31
	v_add_f32_e32 v26, v26, v26
	v_add_f32_e32 v27, v27, v27
	v_mul_f32_e32 v26, 0x3fb8aa3b, v26
	v_mul_f32_e32 v27, 0x3fb8aa3b, v27
	v_exp_f32_e32 v26, v26
	v_exp_f32_e32 v27, v27
	v_add_f32_e32 v24, 1.0, v30
	v_add_f32_e32 v25, 1.0, v31
	v_rcp_f32_e32 v24, v24
	v_rcp_f32_e32 v25, v25
	v_add_f32_e32 v26, 1.0, v26
	v_add_f32_e32 v27, 1.0, v27
	v_rcp_f32_e32 v26, v26
	v_rcp_f32_e32 v27, v27
	v_pk_fma_f32 v[24:25], v[24:25], 2.0, 1.0 op_sel_hi:[1,0,0] neg_lo:[1,0,0] neg_hi:[1,0,0]
	v_pk_mul_f32 v[20:21], v[20:21], 0.5 op_sel_hi:[1,0]
	v_pk_add_f32 v[24:25], v[24:25], 1.0 op_sel_hi:[1,0]
	v_pk_mul_f32 v[22:23], v[22:23], 0.5 op_sel_hi:[1,0]
	v_pk_mul_f32 v[20:21], v[20:21], v[24:25]
	v_pk_fma_f32 v[24:25], v[26:27], 2.0, 1.0 op_sel_hi:[1,0,0] neg_lo:[1,0,0] neg_hi:[1,0,0]
	v_lshlrev_b32_e32 v26, 16, v82
	v_and_b32_e32 v27, 0xffff0000, v82
	v_pk_fma_f32 v[16:17], v[44:45], v[26:27], v[16:17]
	v_pk_add_f32 v[24:25], v[24:25], 1.0 op_sel_hi:[1,0]
	v_mul_f32_e32 v26, 0x3d372713, v16
	v_mul_f32_e32 v27, 0x3d372713, v17
	v_mul_f32_e32 v26, v16, v26
	v_mul_f32_e32 v27, v17, v27
	v_fma_f32 v26, v16, v26, v16
	v_fma_f32 v27, v17, v27, v17
	v_mul_f32_e32 v26, 0x3f4c422a, v26
	v_mul_f32_e32 v27, 0x3f4c422a, v27
	v_add_f32_e32 v26, v26, v26
	v_add_f32_e32 v27, v27, v27
	v_mul_f32_e32 v26, 0x3fb8aa3b, v26
	v_mul_f32_e32 v27, 0x3fb8aa3b, v27
	v_exp_f32_e32 v26, v26
	v_exp_f32_e32 v27, v27
	v_pk_mul_f32 v[22:23], v[22:23], v[24:25]
	v_pk_mul_f32 v[16:17], v[16:17], 0.5 op_sel_hi:[1,0]
	v_add_f32_e32 v24, 1.0, v26
	v_add_f32_e32 v25, 1.0, v27
	v_lshlrev_b32_e32 v26, 16, v83
	v_and_b32_e32 v27, 0xffff0000, v83
	v_pk_fma_f32 v[18:19], v[46:47], v[26:27], v[18:19]
	v_rcp_f32_e32 v24, v24
	v_mul_f32_e32 v26, 0x3d372713, v18
	v_mul_f32_e32 v27, 0x3d372713, v19
	v_mul_f32_e32 v26, v18, v26
	v_mul_f32_e32 v27, v19, v27
	v_fma_f32 v26, v18, v26, v18
	v_fma_f32 v27, v19, v27, v19
	v_mul_f32_e32 v26, 0x3f4c422a, v26
	v_mul_f32_e32 v27, 0x3f4c422a, v27
	v_add_f32_e32 v26, v26, v26
	v_add_f32_e32 v27, v27, v27
	v_mul_f32_e32 v26, 0x3fb8aa3b, v26
	v_mul_f32_e32 v27, 0x3fb8aa3b, v27
	v_exp_f32_e32 v26, v26
	v_exp_f32_e32 v27, v27
	v_rcp_f32_e32 v25, v25
	v_pk_mul_f32 v[18:19], v[18:19], 0.5 op_sel_hi:[1,0]
	v_add_f32_e32 v26, 1.0, v26
	v_add_f32_e32 v27, 1.0, v27
	v_rcp_f32_e32 v26, v26
	v_rcp_f32_e32 v27, v27
	v_pk_fma_f32 v[24:25], v[24:25], 2.0, 1.0 op_sel_hi:[1,0,0] neg_lo:[1,0,0] neg_hi:[1,0,0]
	s_nop 0
	v_pk_add_f32 v[24:25], v[24:25], 1.0 op_sel_hi:[1,0]
	s_nop 0
	v_pk_mul_f32 v[24:25], v[16:17], v[24:25]
	v_pk_fma_f32 v[16:17], v[26:27], 2.0, 1.0 op_sel_hi:[1,0,0] neg_lo:[1,0,0] neg_hi:[1,0,0]
	s_nop 0
	v_pk_add_f32 v[16:17], v[16:17], 1.0 op_sel_hi:[1,0]
	s_nop 0
	v_pk_mul_f32 v[26:27], v[18:19], v[16:17]
	v_cvt_pk_bf16_f32 v16, v20, v21
	v_or_b32_e32 v20, v36, v132
	v_lshlrev_b32_e32 v172, 10, v20
	v_lshl_add_u64 v[20:21], s[8:9], 0, v[172:173]
	v_lshl_add_u64 v[20:21], v[20:21], 0, s[22:23]
	v_cvt_pk_bf16_f32 v17, v22, v23
	v_cvt_pk_bf16_f32 v18, v24, v25
	v_cvt_pk_bf16_f32 v19, v26, v27
	v_lshl_add_u64 v[20:21], v[20:21], 0, v[182:183]
	global_store_dwordx4 v[20:21], v[16:19], off
	v_or_b32_e32 v20, 0x600, v68
	s_waitcnt vmcnt(7)
	v_lshlrev_b32_e32 v16, 16, v76
	v_and_b32_e32 v17, 0xffff0000, v76
	v_pk_fma_f32 v[12:13], v[52:53], v[16:17], v[12:13]
	v_lshlrev_b32_e32 v18, 16, v77
	v_mul_f32_e32 v16, 0x3d372713, v12
	v_mul_f32_e32 v17, 0x3d372713, v13
	v_and_b32_e32 v19, 0xffff0000, v77
	v_mul_f32_e32 v16, v12, v16
	v_mul_f32_e32 v17, v13, v17
	v_pk_fma_f32 v[14:15], v[54:55], v[18:19], v[14:15]
	v_fma_f32 v16, v12, v16, v12
	v_fma_f32 v17, v13, v17, v13
	v_mul_f32_e32 v18, 0x3d372713, v14
	v_mul_f32_e32 v19, 0x3d372713, v15
	v_mul_f32_e32 v16, 0x3f4c422a, v16
	v_mul_f32_e32 v17, 0x3f4c422a, v17
	v_mul_f32_e32 v18, v14, v18
	v_mul_f32_e32 v19, v15, v19
	v_add_f32_e32 v16, v16, v16
	v_add_f32_e32 v17, v17, v17
	v_fma_f32 v18, v14, v18, v14
	v_fma_f32 v19, v15, v19, v15
	v_mul_f32_e32 v16, 0x3fb8aa3b, v16
	v_mul_f32_e32 v17, 0x3fb8aa3b, v17
	v_mul_f32_e32 v18, 0x3f4c422a, v18
	v_mul_f32_e32 v19, 0x3f4c422a, v19
	v_exp_f32_e32 v16, v16
	v_exp_f32_e32 v17, v17
	v_add_f32_e32 v18, v18, v18
	v_add_f32_e32 v19, v19, v19
	v_mul_f32_e32 v18, 0x3fb8aa3b, v18
	v_mul_f32_e32 v19, 0x3fb8aa3b, v19
	v_exp_f32_e32 v18, v18
	v_exp_f32_e32 v19, v19
	v_add_f32_e32 v16, 1.0, v16
	v_add_f32_e32 v17, 1.0, v17
	v_rcp_f32_e32 v16, v16
	v_rcp_f32_e32 v17, v17
	v_add_f32_e32 v18, 1.0, v18
	v_add_f32_e32 v19, 1.0, v19
	v_rcp_f32_e32 v18, v18
	v_rcp_f32_e32 v19, v19
	v_pk_fma_f32 v[16:17], v[16:17], 2.0, 1.0 op_sel_hi:[1,0,0] neg_lo:[1,0,0] neg_hi:[1,0,0]
	v_pk_mul_f32 v[12:13], v[12:13], 0.5 op_sel_hi:[1,0]
	v_pk_add_f32 v[16:17], v[16:17], 1.0 op_sel_hi:[1,0]
	v_pk_mul_f32 v[14:15], v[14:15], 0.5 op_sel_hi:[1,0]
	v_pk_mul_f32 v[12:13], v[12:13], v[16:17]
	v_pk_fma_f32 v[16:17], v[18:19], 2.0, 1.0 op_sel_hi:[1,0,0] neg_lo:[1,0,0] neg_hi:[1,0,0]
	v_lshlrev_b32_e32 v18, 16, v78
	v_and_b32_e32 v19, 0xffff0000, v78
	v_pk_fma_f32 v[8:9], v[44:45], v[18:19], v[8:9]
	v_pk_add_f32 v[16:17], v[16:17], 1.0 op_sel_hi:[1,0]
	v_mul_f32_e32 v18, 0x3d372713, v8
	v_mul_f32_e32 v19, 0x3d372713, v9
	v_mul_f32_e32 v18, v8, v18
	v_mul_f32_e32 v19, v9, v19
	v_fma_f32 v18, v8, v18, v8
	v_fma_f32 v19, v9, v19, v9
	v_mul_f32_e32 v18, 0x3f4c422a, v18
	v_mul_f32_e32 v19, 0x3f4c422a, v19
	v_add_f32_e32 v18, v18, v18
	v_add_f32_e32 v19, v19, v19
	v_mul_f32_e32 v18, 0x3fb8aa3b, v18
	v_mul_f32_e32 v19, 0x3fb8aa3b, v19
	v_exp_f32_e32 v18, v18
	v_exp_f32_e32 v19, v19
	v_pk_mul_f32 v[14:15], v[14:15], v[16:17]
	v_pk_mul_f32 v[8:9], v[8:9], 0.5 op_sel_hi:[1,0]
	v_add_f32_e32 v16, 1.0, v18
	v_add_f32_e32 v17, 1.0, v19
	v_lshlrev_b32_e32 v18, 16, v79
	v_and_b32_e32 v19, 0xffff0000, v79
	v_pk_fma_f32 v[10:11], v[46:47], v[18:19], v[10:11]
	v_rcp_f32_e32 v16, v16
	v_mul_f32_e32 v18, 0x3d372713, v10
	v_mul_f32_e32 v19, 0x3d372713, v11
	v_mul_f32_e32 v18, v10, v18
	v_mul_f32_e32 v19, v11, v19
	v_fma_f32 v18, v10, v18, v10
	v_fma_f32 v19, v11, v19, v11
	v_mul_f32_e32 v18, 0x3f4c422a, v18
	v_mul_f32_e32 v19, 0x3f4c422a, v19
	v_add_f32_e32 v18, v18, v18
	v_add_f32_e32 v19, v19, v19
	v_mul_f32_e32 v18, 0x3fb8aa3b, v18
	v_mul_f32_e32 v19, 0x3fb8aa3b, v19
	v_exp_f32_e32 v18, v18
	v_exp_f32_e32 v19, v19
	v_rcp_f32_e32 v17, v17
	v_pk_mul_f32 v[10:11], v[10:11], 0.5 op_sel_hi:[1,0]
	v_add_f32_e32 v18, 1.0, v18
	v_add_f32_e32 v19, 1.0, v19
	v_rcp_f32_e32 v18, v18
	v_rcp_f32_e32 v19, v19
	v_pk_fma_f32 v[16:17], v[16:17], 2.0, 1.0 op_sel_hi:[1,0,0] neg_lo:[1,0,0] neg_hi:[1,0,0]
	s_nop 0
	v_pk_add_f32 v[16:17], v[16:17], 1.0 op_sel_hi:[1,0]
	s_nop 0
	v_pk_mul_f32 v[16:17], v[8:9], v[16:17]
	v_pk_fma_f32 v[8:9], v[18:19], 2.0, 1.0 op_sel_hi:[1,0,0] neg_lo:[1,0,0] neg_hi:[1,0,0]
	s_nop 0
	v_pk_add_f32 v[8:9], v[8:9], 1.0 op_sel_hi:[1,0]
	s_nop 0
	v_pk_mul_f32 v[18:19], v[10:11], v[8:9]
	v_cvt_pk_bf16_f32 v8, v12, v13
	v_or_b32_e32 v12, v20, v144
	v_lshlrev_b32_e32 v172, 10, v12
	v_lshl_add_u64 v[12:13], s[8:9], 0, v[172:173]
	v_cvt_pk_bf16_f32 v9, v14, v15
	v_lshl_add_u64 v[12:13], v[12:13], 0, s[22:23]
	s_waitcnt vmcnt(6)
	v_lshlrev_b32_e32 v14, 16, v72
	v_and_b32_e32 v15, 0xffff0000, v72
	v_cvt_pk_bf16_f32 v10, v16, v17
	v_cvt_pk_bf16_f32 v11, v18, v19
	v_lshl_add_u64 v[12:13], v[12:13], 0, v[182:183]
	v_pk_fma_f32 v[4:5], v[52:53], v[14:15], v[4:5]
	global_store_dwordx4 v[12:13], v[8:11], off
	v_mul_f32_e32 v14, 0x3d372713, v4
	v_mul_f32_e32 v15, 0x3d372713, v5
	v_lshlrev_b32_e32 v10, 16, v73
	v_and_b32_e32 v11, 0xffff0000, v73
	v_mul_f32_e32 v14, v4, v14
	v_mul_f32_e32 v15, v5, v15
	v_pk_fma_f32 v[6:7], v[54:55], v[10:11], v[6:7]
	v_fma_f32 v14, v4, v14, v4
	v_fma_f32 v15, v5, v15, v5
	v_mul_f32_e32 v10, 0x3d372713, v6
	v_mul_f32_e32 v11, 0x3d372713, v7
	v_mul_f32_e32 v14, 0x3f4c422a, v14
	v_mul_f32_e32 v15, 0x3f4c422a, v15
	v_mul_f32_e32 v10, v6, v10
	v_mul_f32_e32 v11, v7, v11
	v_add_f32_e32 v14, v14, v14
	v_add_f32_e32 v15, v15, v15
	v_fma_f32 v10, v6, v10, v6
	v_fma_f32 v11, v7, v11, v7
	v_mul_f32_e32 v14, 0x3fb8aa3b, v14
	v_mul_f32_e32 v15, 0x3fb8aa3b, v15
	v_mul_f32_e32 v10, 0x3f4c422a, v10
	v_mul_f32_e32 v11, 0x3f4c422a, v11
	v_exp_f32_e32 v14, v14
	v_exp_f32_e32 v15, v15
	v_add_f32_e32 v10, v10, v10
	v_add_f32_e32 v11, v11, v11
	v_mul_f32_e32 v10, 0x3fb8aa3b, v10
	v_mul_f32_e32 v11, 0x3fb8aa3b, v11
	v_exp_f32_e32 v10, v10
	v_exp_f32_e32 v11, v11
	v_add_f32_e32 v8, 1.0, v14
	v_add_f32_e32 v9, 1.0, v15
	v_rcp_f32_e32 v8, v8
	v_rcp_f32_e32 v9, v9
	v_add_f32_e32 v10, 1.0, v10
	v_add_f32_e32 v11, 1.0, v11
	v_rcp_f32_e32 v10, v10
	v_rcp_f32_e32 v11, v11
	v_pk_fma_f32 v[8:9], v[8:9], 2.0, 1.0 op_sel_hi:[1,0,0] neg_lo:[1,0,0] neg_hi:[1,0,0]
	v_pk_mul_f32 v[4:5], v[4:5], 0.5 op_sel_hi:[1,0]
	v_pk_add_f32 v[8:9], v[8:9], 1.0 op_sel_hi:[1,0]
	v_pk_mul_f32 v[6:7], v[6:7], 0.5 op_sel_hi:[1,0]
	v_pk_mul_f32 v[4:5], v[4:5], v[8:9]
	v_pk_fma_f32 v[8:9], v[10:11], 2.0, 1.0 op_sel_hi:[1,0,0] neg_lo:[1,0,0] neg_hi:[1,0,0]
	v_lshlrev_b32_e32 v10, 16, v74
	v_and_b32_e32 v11, 0xffff0000, v74
	v_pk_fma_f32 v[0:1], v[44:45], v[10:11], v[0:1]
	v_pk_add_f32 v[8:9], v[8:9], 1.0 op_sel_hi:[1,0]
	v_mul_f32_e32 v10, 0x3d372713, v0
	v_mul_f32_e32 v11, 0x3d372713, v1
	v_mul_f32_e32 v10, v0, v10
	v_mul_f32_e32 v11, v1, v11
	v_fma_f32 v10, v0, v10, v0
	v_fma_f32 v11, v1, v11, v1
	v_mul_f32_e32 v10, 0x3f4c422a, v10
	v_mul_f32_e32 v11, 0x3f4c422a, v11
	v_add_f32_e32 v10, v10, v10
	v_add_f32_e32 v11, v11, v11
	v_mul_f32_e32 v10, 0x3fb8aa3b, v10
	v_mul_f32_e32 v11, 0x3fb8aa3b, v11
	v_exp_f32_e32 v10, v10
	v_exp_f32_e32 v11, v11
	v_pk_mul_f32 v[6:7], v[6:7], v[8:9]
	v_pk_mul_f32 v[0:1], v[0:1], 0.5 op_sel_hi:[1,0]
	v_add_f32_e32 v8, 1.0, v10
	v_add_f32_e32 v9, 1.0, v11
	v_lshlrev_b32_e32 v10, 16, v75
	v_and_b32_e32 v11, 0xffff0000, v75
	v_pk_fma_f32 v[2:3], v[46:47], v[10:11], v[2:3]
	v_rcp_f32_e32 v8, v8
	v_mul_f32_e32 v10, 0x3d372713, v2
	v_mul_f32_e32 v11, 0x3d372713, v3
	v_mul_f32_e32 v10, v2, v10
	v_mul_f32_e32 v11, v3, v11
	v_fma_f32 v10, v2, v10, v2
	v_fma_f32 v11, v3, v11, v3
	v_mul_f32_e32 v10, 0x3f4c422a, v10
	v_mul_f32_e32 v11, 0x3f4c422a, v11
	v_add_f32_e32 v10, v10, v10
	v_add_f32_e32 v11, v11, v11
	v_mul_f32_e32 v10, 0x3fb8aa3b, v10
	v_mul_f32_e32 v11, 0x3fb8aa3b, v11
	v_exp_f32_e32 v10, v10
	v_exp_f32_e32 v11, v11
	v_rcp_f32_e32 v9, v9
	v_pk_mul_f32 v[2:3], v[2:3], 0.5 op_sel_hi:[1,0]
	v_add_f32_e32 v10, 1.0, v10
	v_add_f32_e32 v11, 1.0, v11
	v_rcp_f32_e32 v10, v10
	v_rcp_f32_e32 v11, v11
	v_pk_fma_f32 v[8:9], v[8:9], 2.0, 1.0 op_sel_hi:[1,0,0] neg_lo:[1,0,0] neg_hi:[1,0,0]
	s_nop 0
	v_pk_add_f32 v[8:9], v[8:9], 1.0 op_sel_hi:[1,0]
	s_nop 0
	v_pk_mul_f32 v[8:9], v[0:1], v[8:9]
	v_pk_fma_f32 v[0:1], v[10:11], 2.0, 1.0 op_sel_hi:[1,0,0] neg_lo:[1,0,0] neg_hi:[1,0,0]
	s_nop 0
	v_pk_add_f32 v[0:1], v[0:1], 1.0 op_sel_hi:[1,0]
	s_nop 0
	v_pk_mul_f32 v[10:11], v[2:3], v[0:1]
	v_cvt_pk_bf16_f32 v0, v4, v5
	v_or_b32_e32 v4, v20, v132
	v_lshlrev_b32_e32 v172, 10, v4
	v_lshl_add_u64 v[4:5], s[8:9], 0, v[172:173]
	v_lshl_add_u64 v[4:5], v[4:5], 0, s[22:23]
	v_cvt_pk_bf16_f32 v1, v6, v7
	v_cvt_pk_bf16_f32 v2, v8, v9
	v_cvt_pk_bf16_f32 v3, v10, v11
	v_lshl_add_u64 v[4:5], v[4:5], 0, v[182:183]
	global_store_dwordx4 v[4:5], v[0:3], off
	s_and_b64 vcc, exec, s[2:3]
	s_mov_b64 s[2:3], -1
	s_cbranch_vccnz .LBB0_785
	s_andn2_b64 vcc, exec, s[10:11]
	s_cbranch_vccnz .LBB0_784
	v_writelane_b32 v255, 1, 53
	s_branch .LBB0_784

.LBB0_806:
	s_ashr_i32 s17, s16, 31
	s_lshl_b64 s[20:21], s[16:17], 18
	s_add_u32 s20, s8, s20
	s_addc_u32 s21, s9, s21
	s_and_b64 s[24:25], s[22:23], exec
	s_cselect_b32 s17, s21, s29
	s_cselect_b32 s52, s20, s28
	s_ashr_i32 s19, s18, 31
	s_lshl_b64 s[24:25], s[18:19], 18
	s_add_u32 s24, s36, s24
	s_addc_u32 s25, s37, s25
	s_and_b64 s[34:35], s[22:23], exec
	s_cselect_b32 s19, s25, s31
	s_cselect_b32 s53, s24, s30
	s_add_u32 s28, s28, 0x20080
	s_addc_u32 s29, s29, 0
	s_add_u32 s54, s30, 0x100
	v_mov_b32_e32 v0, 0
	s_addc_u32 s55, s31, 0
	s_mov_b32 s56, -2
	v_mov_b32_e32 v1, v0
	v_mov_b32_e32 v2, v0
	v_mov_b32_e32 v3, v0
	v_mov_b32_e32 v4, v0
	v_mov_b32_e32 v5, v0
	v_mov_b32_e32 v6, v0
	v_mov_b32_e32 v7, v0
	v_mov_b32_e32 v16, v0
	v_mov_b32_e32 v17, v0
	v_mov_b32_e32 v18, v0
	v_mov_b32_e32 v19, v0
	v_mov_b32_e32 v20, v0
	v_mov_b32_e32 v21, v0
	v_mov_b32_e32 v22, v0
	v_mov_b32_e32 v23, v0
	v_mov_b32_e32 v32, v0
	v_mov_b32_e32 v33, v0
	v_mov_b32_e32 v34, v0
	v_mov_b32_e32 v35, v0
	v_mov_b32_e32 v36, v0
	v_mov_b32_e32 v37, v0
	v_mov_b32_e32 v38, v0
	v_mov_b32_e32 v39, v0
	v_mov_b32_e32 v48, v0
	v_mov_b32_e32 v49, v0
	v_mov_b32_e32 v50, v0
	v_mov_b32_e32 v51, v0
	v_mov_b32_e32 v52, v0
	v_mov_b32_e32 v53, v0
	v_mov_b32_e32 v54, v0
	v_mov_b32_e32 v55, v0
	v_mov_b32_e32 v8, v0
	v_mov_b32_e32 v9, v0
	v_mov_b32_e32 v10, v0
	v_mov_b32_e32 v11, v0
	v_mov_b32_e32 v12, v0
	v_mov_b32_e32 v13, v0
	v_mov_b32_e32 v14, v0
	v_mov_b32_e32 v15, v0
	v_mov_b32_e32 v24, v0
	v_mov_b32_e32 v25, v0
	v_mov_b32_e32 v26, v0
	v_mov_b32_e32 v27, v0
	v_mov_b32_e32 v28, v0
	v_mov_b32_e32 v29, v0
	v_mov_b32_e32 v30, v0
	v_mov_b32_e32 v31, v0
	v_mov_b32_e32 v40, v0
	v_mov_b32_e32 v41, v0
	v_mov_b32_e32 v42, v0
	v_mov_b32_e32 v43, v0
	v_mov_b32_e32 v44, v0
	v_mov_b32_e32 v45, v0
	v_mov_b32_e32 v46, v0
	v_mov_b32_e32 v47, v0
	v_mov_b32_e32 v56, v0
	v_mov_b32_e32 v57, v0
	v_mov_b32_e32 v58, v0
	v_mov_b32_e32 v59, v0
	v_mov_b32_e32 v60, v0
	v_mov_b32_e32 v61, v0
	v_mov_b32_e32 v62, v0
	v_mov_b32_e32 v63, v0
	v_mov_b32_e32 v64, v0
	v_mov_b32_e32 v65, v0
	v_mov_b32_e32 v66, v0
	v_mov_b32_e32 v67, v0
	v_mov_b32_e32 v68, v0
	v_mov_b32_e32 v69, v0
	v_mov_b32_e32 v70, v0
	v_mov_b32_e32 v71, v0
	v_mov_b32_e32 v80, v0
	v_mov_b32_e32 v81, v0
	v_mov_b32_e32 v82, v0
	v_mov_b32_e32 v83, v0
	v_mov_b32_e32 v84, v0
	v_mov_b32_e32 v85, v0
	v_mov_b32_e32 v86, v0
	v_mov_b32_e32 v87, v0
	v_mov_b32_e32 v96, v0
	v_mov_b32_e32 v97, v0
	v_mov_b32_e32 v98, v0
	v_mov_b32_e32 v99, v0
	v_mov_b32_e32 v100, v0
	v_mov_b32_e32 v101, v0
	v_mov_b32_e32 v102, v0
	v_mov_b32_e32 v103, v0
	v_mov_b32_e32 v112, v0
	v_mov_b32_e32 v113, v0
	v_mov_b32_e32 v114, v0
	v_mov_b32_e32 v115, v0
	v_mov_b32_e32 v116, v0
	v_mov_b32_e32 v117, v0
	v_mov_b32_e32 v118, v0
	v_mov_b32_e32 v119, v0
	v_mov_b32_e32 v72, v0
	v_mov_b32_e32 v73, v0
	v_mov_b32_e32 v74, v0
	v_mov_b32_e32 v75, v0
	v_mov_b32_e32 v76, v0
	v_mov_b32_e32 v77, v0
	v_mov_b32_e32 v78, v0
	v_mov_b32_e32 v79, v0
	v_mov_b32_e32 v88, v0
	v_mov_b32_e32 v89, v0
	v_mov_b32_e32 v90, v0
	v_mov_b32_e32 v91, v0
	v_mov_b32_e32 v92, v0
	v_mov_b32_e32 v93, v0
	v_mov_b32_e32 v94, v0
	v_mov_b32_e32 v95, v0
	v_mov_b32_e32 v104, v0
	v_mov_b32_e32 v105, v0
	v_mov_b32_e32 v106, v0
	v_mov_b32_e32 v107, v0
	v_mov_b32_e32 v108, v0
	v_mov_b32_e32 v109, v0
	v_mov_b32_e32 v110, v0
	v_mov_b32_e32 v111, v0
	v_mov_b32_e32 v120, v0
	v_mov_b32_e32 v121, v0
	v_mov_b32_e32 v122, v0
	v_mov_b32_e32 v123, v0
	v_mov_b32_e32 v124, v0
	v_mov_b32_e32 v125, v0
	v_mov_b32_e32 v126, v0
	v_mov_b32_e32 v127, v0
	v_readlane_b32 s97, v255, 53
	s_nop 3
	s_cmp_eq_u32 s97, 1
	s_cbranch_scc0 .Llsb_skip_4
	v_writelane_b32 v255, 0, 53
	s_barrier
.Llsb_skip_4:
.LBB0_807:
	ds_read_b128 v[128:131], v175
	ds_read_b128 v[132:135], v175 offset:1024
	ds_read_b128 v[136:139], v175 offset:2048
	ds_read_b128 v[140:143], v175 offset:3072
	ds_read_b128 v[144:147], v176
	ds_read_b128 v[160:163], v176 offset:1024
	ds_read_b128 v[164:167], v176 offset:2048
	ds_read_b128 v[168:171], v176 offset:3072
	s_add_u32 s30, s28, 0xfffe0080
	s_addc_u32 s31, s29, -1
	s_cmp_eq_u32 s56, 4
	s_cselect_b32 s35, s17, s31
	s_cselect_b32 s34, s52, s30
	s_cselect_b32 s31, s19, s55
	s_cselect_b32 s30, s53, s54
	s_mov_b32 m0, s46
	v_lshl_add_u64 v[182:183], s[28:29], 0, v[156:157]
	ds_read_b128 v[178:181], v177
	ds_read_b128 v[188:191], v177 offset:1024
	ds_read_b128 v[192:195], v177 offset:2048
	ds_read_b128 v[196:199], v177 offset:3072
	ds_read_b128 v[200:203], v177 offset:4096
	ds_read_b128 v[206:209], v177 offset:5120
	ds_read_b128 v[210:213], v177 offset:6144
	ds_read_b128 v[214:217], v177 offset:7168
	global_load_lds_dwordx4 v[182:183], off
	v_lshl_add_u64 v[182:183], s[28:29], 0, v[158:159]
	s_mov_b32 m0, s47
	s_nop 0
	global_load_lds_dwordx4 v[182:183], off
	s_waitcnt vmcnt(8)
	s_waitcnt lgkmcnt(0)
	s_barrier
	s_setprio 1
	s_waitcnt lgkmcnt(0)
	v_mfma_f32_16x16x32_bf16 v[124:127], v[128:131], v[178:181], v[124:127]
	v_mfma_f32_16x16x32_bf16 v[120:123], v[136:139], v[178:181], v[120:123]
	v_mfma_f32_16x16x32_bf16 v[108:111], v[128:131], v[192:195], v[108:111]
	v_mfma_f32_16x16x32_bf16 v[104:107], v[136:139], v[192:195], v[104:107]
	v_mfma_f32_16x16x32_bf16 v[92:95], v[128:131], v[200:203], v[92:95]
	v_mfma_f32_16x16x32_bf16 v[88:91], v[136:139], v[200:203], v[88:91]
	v_mfma_f32_16x16x32_bf16 v[76:79], v[128:131], v[210:213], v[76:79]
	v_mfma_f32_16x16x32_bf16 v[72:75], v[136:139], v[210:213], v[72:75]
	v_mfma_f32_16x16x32_bf16 v[124:127], v[132:135], v[188:191], v[124:127]
	v_mfma_f32_16x16x32_bf16 v[120:123], v[140:143], v[188:191], v[120:123]
	v_mfma_f32_16x16x32_bf16 v[108:111], v[132:135], v[196:199], v[108:111]
	v_mfma_f32_16x16x32_bf16 v[104:107], v[140:143], v[196:199], v[104:107]
	v_mfma_f32_16x16x32_bf16 v[92:95], v[132:135], v[206:209], v[92:95]
	v_mfma_f32_16x16x32_bf16 v[88:91], v[140:143], v[206:209], v[88:91]
	v_mfma_f32_16x16x32_bf16 v[76:79], v[132:135], v[214:217], v[76:79]
	v_mfma_f32_16x16x32_bf16 v[72:75], v[140:143], v[214:217], v[72:75]
	s_setprio 0
	s_setprio 1
	v_mfma_f32_16x16x32_bf16 v[116:119], v[144:147], v[178:181], v[116:119]
	v_mfma_f32_16x16x32_bf16 v[112:115], v[164:167], v[178:181], v[112:115]
	v_mfma_f32_16x16x32_bf16 v[100:103], v[144:147], v[192:195], v[100:103]
	v_mfma_f32_16x16x32_bf16 v[96:99], v[164:167], v[192:195], v[96:99]
	v_mfma_f32_16x16x32_bf16 v[84:87], v[144:147], v[200:203], v[84:87]
	v_mfma_f32_16x16x32_bf16 v[80:83], v[164:167], v[200:203], v[80:83]
	v_mfma_f32_16x16x32_bf16 v[68:71], v[144:147], v[210:213], v[68:71]
	v_mfma_f32_16x16x32_bf16 v[64:67], v[164:167], v[210:213], v[64:67]
	v_mfma_f32_16x16x32_bf16 v[116:119], v[160:163], v[188:191], v[116:119]
	v_mfma_f32_16x16x32_bf16 v[112:115], v[168:171], v[188:191], v[112:115]
	v_mfma_f32_16x16x32_bf16 v[100:103], v[160:163], v[196:199], v[100:103]
	v_mfma_f32_16x16x32_bf16 v[96:99], v[168:171], v[196:199], v[96:99]
	v_mfma_f32_16x16x32_bf16 v[84:87], v[160:163], v[206:209], v[84:87]
	v_mfma_f32_16x16x32_bf16 v[80:83], v[168:171], v[206:209], v[80:83]
	v_mfma_f32_16x16x32_bf16 v[68:71], v[160:163], v[214:217], v[68:71]
	v_mfma_f32_16x16x32_bf16 v[64:67], v[168:171], v[214:217], v[64:67]
	s_setprio 0
	s_barrier
	s_mov_b32 m0, s48
	v_lshl_add_u64 v[182:183], s[30:31], 0, v[152:153]
	s_add_u32 s58, s30, 0x20000
	ds_read_b128 v[178:181], v177 offset:16384
	ds_read_b128 v[188:191], v177 offset:17408
	ds_read_b128 v[192:195], v177 offset:18432
	ds_read_b128 v[196:199], v177 offset:19456
	ds_read_b128 v[200:203], v177 offset:20480
	ds_read_b128 v[206:209], v177 offset:21504
	ds_read_b128 v[210:213], v177 offset:22528
	ds_read_b128 v[214:217], v177 offset:23552
	global_load_lds_dwordx4 v[182:183], off
	v_lshl_add_u64 v[218:219], s[30:31], 0, v[148:149]
	s_mov_b32 m0, s49
	s_addc_u32 s59, s31, 0
	global_load_lds_dwordx4 v[218:219], off
	v_lshl_add_u64 v[220:221], s[58:59], 0, v[152:153]
	s_mov_b32 m0, s50
	v_lshl_add_u64 v[222:223], s[34:35], 0, v[150:151]
	global_load_lds_dwordx4 v[220:221], off
	v_lshl_add_u64 v[220:221], s[58:59], 0, v[148:149]
	s_add_i32 m0, s50, 0x2000
	s_nop 0
	global_load_lds_dwordx4 v[220:221], off
	v_lshl_add_u64 v[220:221], s[34:35], 0, v[154:155]
	s_mov_b32 m0, s27
	s_nop 0
	global_load_lds_dwordx4 v[220:221], off
	s_mov_b32 m0, s39
	s_nop 0
	global_load_lds_dwordx4 v[222:223], off
	s_waitcnt vmcnt(8)
	s_waitcnt lgkmcnt(0)
	s_barrier
	s_setprio 1
	s_waitcnt lgkmcnt(0)
	v_mfma_f32_16x16x32_bf16 v[60:63], v[128:131], v[178:181], v[60:63]
	v_mfma_f32_16x16x32_bf16 v[56:59], v[136:139], v[178:181], v[56:59]
	v_mfma_f32_16x16x32_bf16 v[44:47], v[128:131], v[192:195], v[44:47]
	v_mfma_f32_16x16x32_bf16 v[40:43], v[136:139], v[192:195], v[40:43]
	v_mfma_f32_16x16x32_bf16 v[28:31], v[128:131], v[200:203], v[28:31]
	v_mfma_f32_16x16x32_bf16 v[24:27], v[136:139], v[200:203], v[24:27]
	v_mfma_f32_16x16x32_bf16 v[12:15], v[128:131], v[210:213], v[12:15]
	v_mfma_f32_16x16x32_bf16 v[8:11], v[136:139], v[210:213], v[8:11]
	v_mfma_f32_16x16x32_bf16 v[60:63], v[132:135], v[188:191], v[60:63]
	v_mfma_f32_16x16x32_bf16 v[56:59], v[140:143], v[188:191], v[56:59]
	v_mfma_f32_16x16x32_bf16 v[44:47], v[132:135], v[196:199], v[44:47]
	v_mfma_f32_16x16x32_bf16 v[40:43], v[140:143], v[196:199], v[40:43]
	v_mfma_f32_16x16x32_bf16 v[28:31], v[132:135], v[206:209], v[28:31]
	v_mfma_f32_16x16x32_bf16 v[24:27], v[140:143], v[206:209], v[24:27]
	v_mfma_f32_16x16x32_bf16 v[12:15], v[132:135], v[214:217], v[12:15]
	v_mfma_f32_16x16x32_bf16 v[8:11], v[140:143], v[214:217], v[8:11]
	s_setprio 0
	s_setprio 1
	v_mfma_f32_16x16x32_bf16 v[52:55], v[144:147], v[178:181], v[52:55]
	v_mfma_f32_16x16x32_bf16 v[48:51], v[164:167], v[178:181], v[48:51]
	v_mfma_f32_16x16x32_bf16 v[36:39], v[144:147], v[192:195], v[36:39]
	v_mfma_f32_16x16x32_bf16 v[32:35], v[164:167], v[192:195], v[32:35]
	v_mfma_f32_16x16x32_bf16 v[20:23], v[144:147], v[200:203], v[20:23]
	v_mfma_f32_16x16x32_bf16 v[16:19], v[164:167], v[200:203], v[16:19]
	v_mfma_f32_16x16x32_bf16 v[4:7], v[144:147], v[210:213], v[4:7]
	v_mfma_f32_16x16x32_bf16 v[0:3], v[164:167], v[210:213], v[0:3]
	v_mfma_f32_16x16x32_bf16 v[52:55], v[160:163], v[188:191], v[52:55]
	v_mfma_f32_16x16x32_bf16 v[48:51], v[168:171], v[188:191], v[48:51]
	v_mfma_f32_16x16x32_bf16 v[36:39], v[160:163], v[196:199], v[36:39]
	v_mfma_f32_16x16x32_bf16 v[32:35], v[168:171], v[196:199], v[32:35]
	v_mfma_f32_16x16x32_bf16 v[20:23], v[160:163], v[206:209], v[20:23]
	v_mfma_f32_16x16x32_bf16 v[16:19], v[168:171], v[206:209], v[16:19]
	v_mfma_f32_16x16x32_bf16 v[4:7], v[160:163], v[214:217], v[4:7]
	v_mfma_f32_16x16x32_bf16 v[0:3], v[168:171], v[214:217], v[0:3]
	s_setprio 0
	s_barrier
	s_add_i32 s57, 0, 0x18000
	s_add_i32 s58, 0, 0x1c000
	v_add_u32_e32 v140, s57, v173
	v_add_u32_e32 v168, s58, v173
	ds_read_b128 v[128:131], v140
	ds_read_b128 v[132:135], v140 offset:1024
	ds_read_b128 v[136:139], v140 offset:2048
	ds_read_b128 v[140:143], v140 offset:3072
	ds_read_b128 v[144:147], v168
	ds_read_b128 v[160:163], v168 offset:1024
	ds_read_b128 v[164:167], v168 offset:2048
	ds_read_b128 v[168:171], v168 offset:3072
	s_add_u32 s34, s34, 0x20000
	s_addc_u32 s35, s35, 0
	s_mov_b32 m0, s40
	v_lshl_add_u64 v[224:225], s[34:35], 0, v[154:155]
	ds_read_b128 v[178:181], v177 offset:32768
	ds_read_b128 v[188:191], v177 offset:33792
	ds_read_b128 v[192:195], v177 offset:34816
	ds_read_b128 v[196:199], v177 offset:35840
	ds_read_b128 v[200:203], v177 offset:36864
	ds_read_b128 v[206:209], v177 offset:37888
	ds_read_b128 v[210:213], v177 offset:38912
	ds_read_b128 v[214:217], v177 offset:39936
	global_load_lds_dwordx4 v[224:225], off
	v_lshl_add_u64 v[224:225], s[34:35], 0, v[150:151]
	s_mov_b32 m0, s41
	s_nop 0
	global_load_lds_dwordx4 v[224:225], off
	s_waitcnt vmcnt(8)
	s_waitcnt lgkmcnt(0)
	s_barrier
	s_setprio 1
	s_waitcnt lgkmcnt(0)
	v_mfma_f32_16x16x32_bf16 v[124:127], v[128:131], v[178:181], v[124:127]
	v_mfma_f32_16x16x32_bf16 v[120:123], v[136:139], v[178:181], v[120:123]
	v_mfma_f32_16x16x32_bf16 v[108:111], v[128:131], v[192:195], v[108:111]
	v_mfma_f32_16x16x32_bf16 v[104:107], v[136:139], v[192:195], v[104:107]
	v_mfma_f32_16x16x32_bf16 v[92:95], v[128:131], v[200:203], v[92:95]
	v_mfma_f32_16x16x32_bf16 v[88:91], v[136:139], v[200:203], v[88:91]
	v_mfma_f32_16x16x32_bf16 v[76:79], v[128:131], v[210:213], v[76:79]
	v_mfma_f32_16x16x32_bf16 v[72:75], v[136:139], v[210:213], v[72:75]
	v_mfma_f32_16x16x32_bf16 v[124:127], v[132:135], v[188:191], v[124:127]
	v_mfma_f32_16x16x32_bf16 v[120:123], v[140:143], v[188:191], v[120:123]
	v_mfma_f32_16x16x32_bf16 v[108:111], v[132:135], v[196:199], v[108:111]
	v_mfma_f32_16x16x32_bf16 v[104:107], v[140:143], v[196:199], v[104:107]
	v_mfma_f32_16x16x32_bf16 v[92:95], v[132:135], v[206:209], v[92:95]
	v_mfma_f32_16x16x32_bf16 v[88:91], v[140:143], v[206:209], v[88:91]
	v_mfma_f32_16x16x32_bf16 v[76:79], v[132:135], v[214:217], v[76:79]
	v_mfma_f32_16x16x32_bf16 v[72:75], v[140:143], v[214:217], v[72:75]
	s_setprio 0
	s_setprio 1
	v_mfma_f32_16x16x32_bf16 v[116:119], v[144:147], v[178:181], v[116:119]
	v_mfma_f32_16x16x32_bf16 v[112:115], v[164:167], v[178:181], v[112:115]
	v_mfma_f32_16x16x32_bf16 v[100:103], v[144:147], v[192:195], v[100:103]
	v_mfma_f32_16x16x32_bf16 v[96:99], v[164:167], v[192:195], v[96:99]
	v_mfma_f32_16x16x32_bf16 v[84:87], v[144:147], v[200:203], v[84:87]
	v_mfma_f32_16x16x32_bf16 v[80:83], v[164:167], v[200:203], v[80:83]
	v_mfma_f32_16x16x32_bf16 v[68:71], v[144:147], v[210:213], v[68:71]
	v_mfma_f32_16x16x32_bf16 v[64:67], v[164:167], v[210:213], v[64:67]
	v_mfma_f32_16x16x32_bf16 v[116:119], v[160:163], v[188:191], v[116:119]
	v_mfma_f32_16x16x32_bf16 v[112:115], v[168:171], v[188:191], v[112:115]
	v_mfma_f32_16x16x32_bf16 v[100:103], v[160:163], v[196:199], v[100:103]
	v_mfma_f32_16x16x32_bf16 v[96:99], v[168:171], v[196:199], v[96:99]
	v_mfma_f32_16x16x32_bf16 v[84:87], v[160:163], v[206:209], v[84:87]
	v_mfma_f32_16x16x32_bf16 v[80:83], v[168:171], v[206:209], v[80:83]
	v_mfma_f32_16x16x32_bf16 v[68:71], v[160:163], v[214:217], v[68:71]
	v_mfma_f32_16x16x32_bf16 v[64:67], v[168:171], v[214:217], v[64:67]
	s_setprio 0
	s_barrier
	s_add_i32 s34, s57, s38
	v_lshl_add_u64 v[182:183], v[182:183], 0, s[10:11]
	s_mov_b32 m0, s34
	ds_read_b128 v[178:181], v177 offset:49152
	ds_read_b128 v[188:191], v177 offset:50176
	ds_read_b128 v[192:195], v177 offset:51200
	ds_read_b128 v[196:199], v177 offset:52224
	ds_read_b128 v[200:203], v177 offset:53248
	ds_read_b128 v[206:209], v177 offset:54272
	ds_read_b128 v[210:213], v177 offset:55296
	ds_read_b128 v[214:217], v177 offset:56320
	global_load_lds_dwordx4 v[182:183], off
	s_add_i32 m0, s34, 0x2000
	s_add_u32 s30, s30, 0x20080
	v_lshl_add_u64 v[182:183], v[218:219], 0, s[10:11]
	s_addc_u32 s31, s31, 0
	s_add_i32 s34, s58, s38
	global_load_lds_dwordx4 v[182:183], off
	v_lshl_add_u64 v[182:183], s[30:31], 0, v[152:153]
	s_mov_b32 m0, s34
	s_nop 0
	global_load_lds_dwordx4 v[182:183], off
	v_lshl_add_u64 v[182:183], s[30:31], 0, v[148:149]
	s_add_i32 m0, s34, 0x2000
	s_nop 0
	global_load_lds_dwordx4 v[182:183], off
	v_lshl_add_u64 v[182:183], v[220:221], 0, s[10:11]
	s_mov_b32 m0, s42
	s_nop 0
	global_load_lds_dwordx4 v[182:183], off
	v_lshl_add_u64 v[182:183], v[222:223], 0, s[10:11]
	s_mov_b32 m0, s43
	s_nop 0
	global_load_lds_dwordx4 v[182:183], off
	s_waitcnt vmcnt(8)
	s_waitcnt lgkmcnt(0)
	s_barrier
	s_setprio 1
	s_waitcnt lgkmcnt(0)
	v_mfma_f32_16x16x32_bf16 v[60:63], v[128:131], v[178:181], v[60:63]
	v_mfma_f32_16x16x32_bf16 v[56:59], v[136:139], v[178:181], v[56:59]
	v_mfma_f32_16x16x32_bf16 v[44:47], v[128:131], v[192:195], v[44:47]
	v_mfma_f32_16x16x32_bf16 v[40:43], v[136:139], v[192:195], v[40:43]
	v_mfma_f32_16x16x32_bf16 v[28:31], v[128:131], v[200:203], v[28:31]
	v_mfma_f32_16x16x32_bf16 v[24:27], v[136:139], v[200:203], v[24:27]
	v_mfma_f32_16x16x32_bf16 v[12:15], v[128:131], v[210:213], v[12:15]
	v_mfma_f32_16x16x32_bf16 v[8:11], v[136:139], v[210:213], v[8:11]
	v_mfma_f32_16x16x32_bf16 v[60:63], v[132:135], v[188:191], v[60:63]
	v_mfma_f32_16x16x32_bf16 v[56:59], v[140:143], v[188:191], v[56:59]
	v_mfma_f32_16x16x32_bf16 v[44:47], v[132:135], v[196:199], v[44:47]
	v_mfma_f32_16x16x32_bf16 v[40:43], v[140:143], v[196:199], v[40:43]
	v_mfma_f32_16x16x32_bf16 v[28:31], v[132:135], v[206:209], v[28:31]
	v_mfma_f32_16x16x32_bf16 v[24:27], v[140:143], v[206:209], v[24:27]
	v_mfma_f32_16x16x32_bf16 v[12:15], v[132:135], v[214:217], v[12:15]
	v_mfma_f32_16x16x32_bf16 v[8:11], v[140:143], v[214:217], v[8:11]
	s_setprio 0
	s_setprio 1
	v_mfma_f32_16x16x32_bf16 v[52:55], v[144:147], v[178:181], v[52:55]
	v_mfma_f32_16x16x32_bf16 v[48:51], v[164:167], v[178:181], v[48:51]
	v_mfma_f32_16x16x32_bf16 v[36:39], v[144:147], v[192:195], v[36:39]
	v_mfma_f32_16x16x32_bf16 v[32:35], v[164:167], v[192:195], v[32:35]
	v_mfma_f32_16x16x32_bf16 v[20:23], v[144:147], v[200:203], v[20:23]
	v_mfma_f32_16x16x32_bf16 v[16:19], v[164:167], v[200:203], v[16:19]
	v_mfma_f32_16x16x32_bf16 v[4:7], v[144:147], v[210:213], v[4:7]
	v_mfma_f32_16x16x32_bf16 v[0:3], v[164:167], v[210:213], v[0:3]
	v_mfma_f32_16x16x32_bf16 v[52:55], v[160:163], v[188:191], v[52:55]
	v_mfma_f32_16x16x32_bf16 v[48:51], v[168:171], v[188:191], v[48:51]
	v_mfma_f32_16x16x32_bf16 v[36:39], v[160:163], v[196:199], v[36:39]
	v_mfma_f32_16x16x32_bf16 v[32:35], v[168:171], v[196:199], v[32:35]
	v_mfma_f32_16x16x32_bf16 v[20:23], v[160:163], v[206:209], v[20:23]
	v_mfma_f32_16x16x32_bf16 v[16:19], v[168:171], v[206:209], v[16:19]
	v_mfma_f32_16x16x32_bf16 v[4:7], v[160:163], v[214:217], v[4:7]
	v_mfma_f32_16x16x32_bf16 v[0:3], v[168:171], v[214:217], v[0:3]
	s_setprio 0
	s_barrier
	s_add_i32 s56, s56, 2
	s_add_u32 s28, s28, 0x100
	s_addc_u32 s29, s29, 0
	s_add_u32 s54, s54, 0x100
	s_addc_u32 s55, s55, 0
	s_cmp_gt_u32 s56, 5
	s_cbranch_scc0 .LBB0_807
	s_and_b64 vcc, exec, s[14:15]
	s_cbranch_vccz .LBB0_810
	s_barrier
.LBB0_810:
	v_lshl_or_b32 v128, s26, 8, v174
	v_lshl_add_u32 v162, s51, 8, v172
	v_ashrrev_i32_e32 v129, 31, v128
	v_lshlrev_b64 v[160:161], 1, v[128:129]
	v_ashrrev_i32_e32 v163, 31, v162
	v_lshl_add_u64 v[164:165], s[8:9], 0, v[160:161]
	v_lshlrev_b64 v[128:129], 10, v[162:163]
	v_or_b32_e32 v170, 16, v162
	v_lshl_add_u64 v[128:129], v[164:165], 0, v[128:129]
	v_ashrrev_i32_e32 v171, 31, v170
	global_load_dwordx4 v[178:181], v[128:129], off
	global_load_dwordx4 v[188:191], v[128:129], off offset:256
	v_lshlrev_b64 v[128:129], 10, v[170:171]
	v_or_b32_e32 v168, 32, v162
	v_lshl_add_u64 v[128:129], v[164:165], 0, v[128:129]
	v_ashrrev_i32_e32 v169, 31, v168
	global_load_dwordx4 v[192:195], v[128:129], off
	global_load_dwordx4 v[144:147], v[128:129], off offset:256
	v_lshlrev_b64 v[128:129], 10, v[168:169]
	v_or_b32_e32 v166, 48, v162
	v_lshl_add_u64 v[128:129], v[164:165], 0, v[128:129]
	v_ashrrev_i32_e32 v167, 31, v166
	global_load_dwordx4 v[140:143], v[128:129], off
	global_load_dwordx4 v[136:139], v[128:129], off offset:256
	v_lshlrev_b64 v[128:129], 10, v[166:167]
	v_lshl_add_u64 v[128:129], v[164:165], 0, v[128:129]
	global_load_dwordx4 v[132:135], v[128:129], off
	s_nop 0
	global_load_dwordx4 v[128:131], v[128:129], off offset:256
	v_mul_f32_e32 v126, 0xbfb8aa3b, v126
	v_mul_f32_e32 v127, 0xbfb8aa3b, v127
	v_exp_f32_e32 v126, v126
	v_exp_f32_e32 v127, v127
	v_mul_f32_e32 v120, 0xbfb8aa3b, v120
	v_exp_f32_e32 v163, v120
	v_add_f32_e32 v126, 1.0, v126
	v_add_f32_e32 v127, 1.0, v127
	v_mul_f32_e32 v120, 0xbfb8aa3b, v121
	v_mul_f32_e32 v124, 0xbfb8aa3b, v124
	v_mul_f32_e32 v125, 0xbfb8aa3b, v125
	v_rcp_f32_e32 v126, v126
	v_rcp_f32_e32 v127, v127
	v_exp_f32_e32 v167, v120
	v_mul_f32_e32 v122, 0xbfb8aa3b, v122
	v_mul_f32_e32 v123, 0xbfb8aa3b, v123
	v_exp_f32_e32 v124, v124
	v_exp_f32_e32 v125, v125
	v_exp_f32_e32 v122, v122
	v_exp_f32_e32 v123, v123
	s_waitcnt vmcnt(0)
	v_lshlrev_b32_e32 v182, 16, v178
	v_and_b32_e32 v183, 0xffff0000, v178
	v_lshlrev_b32_e32 v178, 16, v179
	v_and_b32_e32 v179, 0xffff0000, v179
	v_pk_mul_f32 v[120:121], v[126:127], v[178:179]
	v_add_f32_e32 v126, 1.0, v163
	v_add_f32_e32 v127, 1.0, v167
	v_mul_f32_e32 v116, 0xbfb8aa3b, v116
	v_mul_f32_e32 v117, 0xbfb8aa3b, v117
	v_add_f32_e32 v124, 1.0, v124
	v_add_f32_e32 v125, 1.0, v125
	v_rcp_f32_e32 v126, v126
	v_rcp_f32_e32 v127, v127
	v_add_f32_e32 v122, 1.0, v122
	v_add_f32_e32 v123, 1.0, v123
	v_exp_f32_e32 v116, v116
	v_exp_f32_e32 v117, v117
	v_mul_f32_e32 v118, 0xbfb8aa3b, v118
	v_mul_f32_e32 v119, 0xbfb8aa3b, v119
	v_rcp_f32_e32 v124, v124
	v_rcp_f32_e32 v125, v125
	v_rcp_f32_e32 v122, v122
	v_rcp_f32_e32 v123, v123
	v_exp_f32_e32 v118, v118
	v_exp_f32_e32 v119, v119
	v_mul_f32_e32 v112, 0xbfb8aa3b, v112
	v_mul_f32_e32 v113, 0xbfb8aa3b, v113
	v_exp_f32_e32 v112, v112
	v_exp_f32_e32 v113, v113
	v_mul_f32_e32 v114, 0xbfb8aa3b, v114
	v_mul_f32_e32 v115, 0xbfb8aa3b, v115
	v_lshlrev_b32_e32 v178, 16, v180
	v_and_b32_e32 v179, 0xffff0000, v180
	v_exp_f32_e32 v114, v114
	v_exp_f32_e32 v115, v115
	v_pk_mul_f32 v[126:127], v[126:127], v[178:179]
	v_lshlrev_b32_e32 v178, 16, v181
	v_and_b32_e32 v179, 0xffff0000, v181
	v_add_f32_e32 v116, 1.0, v116
	v_add_f32_e32 v117, 1.0, v117
	v_pk_mul_f32 v[124:125], v[124:125], v[182:183]
	v_pk_mul_f32 v[178:179], v[122:123], v[178:179]
	v_cvt_pk_bf16_f32 v123, v120, v121
	v_mov_b64_e32 v[120:121], s[0:1]
	v_rcp_f32_e32 v116, v116
	v_rcp_f32_e32 v117, v117
	v_add_f32_e32 v118, 1.0, v118
	v_add_f32_e32 v119, 1.0, v119
	v_mul_f32_e32 v108, 0xbfb8aa3b, v108
	v_mul_f32_e32 v109, 0xbfb8aa3b, v109
	v_cvt_pk_bf16_f32 v122, v124, v125
	v_cvt_pk_bf16_f32 v124, v126, v127
	v_mad_i64_i32 v[126:127], s[28:29], v162, s45, v[120:121]
	v_rcp_f32_e32 v118, v118
	v_rcp_f32_e32 v119, v119
	v_add_f32_e32 v112, 1.0, v112
	v_add_f32_e32 v113, 1.0, v113
	v_exp_f32_e32 v108, v108
	v_exp_f32_e32 v109, v109
	v_mul_f32_e32 v110, 0xbfb8aa3b, v110
	v_mul_f32_e32 v111, 0xbfb8aa3b, v111
	v_cvt_pk_bf16_f32 v125, v178, v179
	v_lshl_add_u64 v[126:127], v[126:127], 0, v[160:161]
	v_rcp_f32_e32 v112, v112
	v_rcp_f32_e32 v113, v113
	v_add_f32_e32 v114, 1.0, v114
	v_add_f32_e32 v115, 1.0, v115
	v_exp_f32_e32 v110, v110
	v_exp_f32_e32 v111, v111
	v_mul_f32_e32 v104, 0xbfb8aa3b, v104
	v_mul_f32_e32 v105, 0xbfb8aa3b, v105
	global_store_dwordx4 v[126:127], v[122:125], off offset:1024
	v_rcp_f32_e32 v114, v114
	v_rcp_f32_e32 v115, v115
	v_lshlrev_b32_e32 v122, 16, v188
	v_and_b32_e32 v123, 0xffff0000, v188
	v_exp_f32_e32 v104, v104
	v_exp_f32_e32 v105, v105
	v_mul_f32_e32 v106, 0xbfb8aa3b, v106
	v_mul_f32_e32 v107, 0xbfb8aa3b, v107
	v_pk_mul_f32 v[116:117], v[116:117], v[122:123]
	v_lshlrev_b32_e32 v122, 16, v189
	v_and_b32_e32 v123, 0xffff0000, v189
	v_exp_f32_e32 v106, v106
	v_exp_f32_e32 v107, v107
	v_pk_mul_f32 v[118:119], v[118:119], v[122:123]
	v_lshlrev_b32_e32 v122, 16, v190
	v_and_b32_e32 v123, 0xffff0000, v190
	v_add_f32_e32 v108, 1.0, v108
	v_add_f32_e32 v109, 1.0, v109
	v_pk_mul_f32 v[122:123], v[112:113], v[122:123]
	v_lshlrev_b32_e32 v112, 16, v191
	v_and_b32_e32 v113, 0xffff0000, v191
	v_rcp_f32_e32 v108, v108
	v_rcp_f32_e32 v109, v109
	v_add_f32_e32 v110, 1.0, v110
	v_add_f32_e32 v111, 1.0, v111
	v_mul_f32_e32 v100, 0xbfb8aa3b, v100
	v_mul_f32_e32 v101, 0xbfb8aa3b, v101
	v_pk_mul_f32 v[124:125], v[114:115], v[112:113]
	v_rcp_f32_e32 v110, v110
	v_rcp_f32_e32 v111, v111
	v_add_f32_e32 v104, 1.0, v104
	v_add_f32_e32 v105, 1.0, v105
	v_exp_f32_e32 v100, v100
	v_exp_f32_e32 v101, v101
	v_mul_f32_e32 v102, 0xbfb8aa3b, v102
	v_mul_f32_e32 v103, 0xbfb8aa3b, v103
	v_cvt_pk_bf16_f32 v112, v116, v117
	v_cvt_pk_bf16_f32 v113, v118, v119
	v_cvt_pk_bf16_f32 v114, v122, v123
	v_cvt_pk_bf16_f32 v115, v124, v125
	v_rcp_f32_e32 v104, v104
	v_rcp_f32_e32 v105, v105
	v_add_f32_e32 v106, 1.0, v106
	v_add_f32_e32 v107, 1.0, v107
	v_exp_f32_e32 v102, v102
	v_exp_f32_e32 v103, v103
	v_mul_f32_e32 v96, 0xbfb8aa3b, v96
	v_mul_f32_e32 v97, 0xbfb8aa3b, v97
	global_store_dwordx4 v[126:127], v[112:115], off offset:1280
	v_rcp_f32_e32 v106, v106
	v_rcp_f32_e32 v107, v107
	v_lshlrev_b32_e32 v112, 16, v192
	v_and_b32_e32 v113, 0xffff0000, v192
	v_exp_f32_e32 v96, v96
	v_exp_f32_e32 v97, v97
	v_mul_f32_e32 v98, 0xbfb8aa3b, v98
	v_mul_f32_e32 v99, 0xbfb8aa3b, v99
	v_pk_mul_f32 v[108:109], v[108:109], v[112:113]
	v_lshlrev_b32_e32 v112, 16, v193
	v_and_b32_e32 v113, 0xffff0000, v193
	v_exp_f32_e32 v98, v98
	v_exp_f32_e32 v99, v99
	v_pk_mul_f32 v[110:111], v[110:111], v[112:113]
	v_lshlrev_b32_e32 v112, 16, v194
	v_and_b32_e32 v113, 0xffff0000, v194
	v_add_f32_e32 v100, 1.0, v100
	v_add_f32_e32 v101, 1.0, v101
	v_pk_mul_f32 v[112:113], v[104:105], v[112:113]
	v_lshlrev_b32_e32 v104, 16, v195
	v_and_b32_e32 v105, 0xffff0000, v195
	v_rcp_f32_e32 v100, v100
	v_rcp_f32_e32 v101, v101
	v_add_f32_e32 v102, 1.0, v102
	v_add_f32_e32 v103, 1.0, v103
	v_mul_f32_e32 v92, 0xbfb8aa3b, v92
	v_mul_f32_e32 v93, 0xbfb8aa3b, v93
	v_pk_mul_f32 v[114:115], v[106:107], v[104:105]
	v_cvt_pk_bf16_f32 v104, v108, v109
	v_mad_i64_i32 v[108:109], s[28:29], v170, s45, v[120:121]
	v_rcp_f32_e32 v102, v102
	v_rcp_f32_e32 v103, v103
	v_add_f32_e32 v96, 1.0, v96
	v_add_f32_e32 v97, 1.0, v97
	v_exp_f32_e32 v92, v92
	v_exp_f32_e32 v93, v93
	v_mul_f32_e32 v94, 0xbfb8aa3b, v94
	v_mul_f32_e32 v95, 0xbfb8aa3b, v95
	v_cvt_pk_bf16_f32 v105, v110, v111
	v_cvt_pk_bf16_f32 v106, v112, v113
	v_cvt_pk_bf16_f32 v107, v114, v115
	v_lshl_add_u64 v[108:109], v[108:109], 0, v[160:161]
	v_rcp_f32_e32 v96, v96
	v_rcp_f32_e32 v97, v97
	v_add_f32_e32 v98, 1.0, v98
	v_add_f32_e32 v99, 1.0, v99
	v_exp_f32_e32 v94, v94
	v_exp_f32_e32 v95, v95
	v_mul_f32_e32 v88, 0xbfb8aa3b, v88
	v_mul_f32_e32 v89, 0xbfb8aa3b, v89
	global_store_dwordx4 v[108:109], v[104:107], off offset:1024
	v_rcp_f32_e32 v98, v98
	v_rcp_f32_e32 v99, v99
	v_lshlrev_b32_e32 v104, 16, v144
	v_and_b32_e32 v105, 0xffff0000, v144
	v_exp_f32_e32 v88, v88
	v_exp_f32_e32 v89, v89
	v_mul_f32_e32 v90, 0xbfb8aa3b, v90
	v_mul_f32_e32 v91, 0xbfb8aa3b, v91
	v_pk_mul_f32 v[100:101], v[100:101], v[104:105]
	v_lshlrev_b32_e32 v104, 16, v145
	v_and_b32_e32 v105, 0xffff0000, v145
	v_exp_f32_e32 v90, v90
	v_exp_f32_e32 v91, v91
	v_pk_mul_f32 v[102:103], v[102:103], v[104:105]
	v_lshlrev_b32_e32 v104, 16, v146
	v_and_b32_e32 v105, 0xffff0000, v146
	v_add_f32_e32 v92, 1.0, v92
	v_add_f32_e32 v93, 1.0, v93
	v_pk_mul_f32 v[104:105], v[96:97], v[104:105]
	v_lshlrev_b32_e32 v96, 16, v147
	v_and_b32_e32 v97, 0xffff0000, v147
	v_rcp_f32_e32 v92, v92
	v_rcp_f32_e32 v93, v93
	v_add_f32_e32 v94, 1.0, v94
	v_add_f32_e32 v95, 1.0, v95
	v_mul_f32_e32 v84, 0xbfb8aa3b, v84
	v_mul_f32_e32 v85, 0xbfb8aa3b, v85
	v_pk_mul_f32 v[106:107], v[98:99], v[96:97]
	v_rcp_f32_e32 v94, v94
	v_rcp_f32_e32 v95, v95
	v_add_f32_e32 v88, 1.0, v88
	v_add_f32_e32 v89, 1.0, v89
	v_exp_f32_e32 v84, v84
	v_exp_f32_e32 v85, v85
	v_mul_f32_e32 v86, 0xbfb8aa3b, v86
	v_mul_f32_e32 v87, 0xbfb8aa3b, v87
	v_cvt_pk_bf16_f32 v96, v100, v101
	v_cvt_pk_bf16_f32 v97, v102, v103
	v_cvt_pk_bf16_f32 v98, v104, v105
	v_cvt_pk_bf16_f32 v99, v106, v107
	v_rcp_f32_e32 v88, v88
	v_rcp_f32_e32 v89, v89
	v_add_f32_e32 v90, 1.0, v90
	v_add_f32_e32 v91, 1.0, v91
	v_exp_f32_e32 v86, v86
	v_exp_f32_e32 v87, v87
	v_mul_f32_e32 v80, 0xbfb8aa3b, v80
	v_mul_f32_e32 v81, 0xbfb8aa3b, v81
	global_store_dwordx4 v[108:109], v[96:99], off offset:1280
	v_rcp_f32_e32 v90, v90
	v_rcp_f32_e32 v91, v91
	v_lshlrev_b32_e32 v96, 16, v140
	v_and_b32_e32 v97, 0xffff0000, v140
	v_exp_f32_e32 v80, v80
	v_exp_f32_e32 v81, v81
	v_mul_f32_e32 v82, 0xbfb8aa3b, v82
	v_mul_f32_e32 v83, 0xbfb8aa3b, v83
	v_pk_mul_f32 v[92:93], v[92:93], v[96:97]
	v_lshlrev_b32_e32 v96, 16, v141
	v_and_b32_e32 v97, 0xffff0000, v141
	v_exp_f32_e32 v82, v82
	v_exp_f32_e32 v83, v83
	v_pk_mul_f32 v[94:95], v[94:95], v[96:97]
	v_lshlrev_b32_e32 v96, 16, v142
	v_and_b32_e32 v97, 0xffff0000, v142
	v_add_f32_e32 v84, 1.0, v84
	v_add_f32_e32 v85, 1.0, v85
	v_pk_mul_f32 v[96:97], v[88:89], v[96:97]
	v_lshlrev_b32_e32 v88, 16, v143
	v_and_b32_e32 v89, 0xffff0000, v143
	v_rcp_f32_e32 v84, v84
	v_rcp_f32_e32 v85, v85
	v_add_f32_e32 v86, 1.0, v86
	v_add_f32_e32 v87, 1.0, v87
	v_mul_f32_e32 v76, 0xbfb8aa3b, v76
	v_mul_f32_e32 v77, 0xbfb8aa3b, v77
	v_pk_mul_f32 v[98:99], v[90:91], v[88:89]
	v_cvt_pk_bf16_f32 v88, v92, v93
	v_mad_i64_i32 v[92:93], s[28:29], v168, s45, v[120:121]
	v_rcp_f32_e32 v86, v86
	v_rcp_f32_e32 v87, v87
	v_add_f32_e32 v80, 1.0, v80
	v_add_f32_e32 v81, 1.0, v81
	v_exp_f32_e32 v76, v76
	v_exp_f32_e32 v77, v77
	v_mul_f32_e32 v78, 0xbfb8aa3b, v78
	v_mul_f32_e32 v79, 0xbfb8aa3b, v79
	v_cvt_pk_bf16_f32 v89, v94, v95
	v_cvt_pk_bf16_f32 v90, v96, v97
	v_cvt_pk_bf16_f32 v91, v98, v99
	v_lshl_add_u64 v[92:93], v[92:93], 0, v[160:161]
	v_rcp_f32_e32 v80, v80
	v_rcp_f32_e32 v81, v81
	v_add_f32_e32 v82, 1.0, v82
	v_add_f32_e32 v83, 1.0, v83
	v_exp_f32_e32 v78, v78
	v_exp_f32_e32 v79, v79
	v_mul_f32_e32 v72, 0xbfb8aa3b, v72
	v_mul_f32_e32 v73, 0xbfb8aa3b, v73
	global_store_dwordx4 v[92:93], v[88:91], off offset:1024
	v_rcp_f32_e32 v82, v82
	v_rcp_f32_e32 v83, v83
	v_lshlrev_b32_e32 v88, 16, v136
	v_and_b32_e32 v89, 0xffff0000, v136
	v_exp_f32_e32 v72, v72
	v_exp_f32_e32 v73, v73
	v_mul_f32_e32 v74, 0xbfb8aa3b, v74
	v_mul_f32_e32 v75, 0xbfb8aa3b, v75
	v_pk_mul_f32 v[84:85], v[84:85], v[88:89]
	v_lshlrev_b32_e32 v88, 16, v137
	v_and_b32_e32 v89, 0xffff0000, v137
	v_exp_f32_e32 v74, v74
	v_exp_f32_e32 v75, v75
	v_pk_mul_f32 v[86:87], v[86:87], v[88:89]
	v_lshlrev_b32_e32 v88, 16, v138
	v_and_b32_e32 v89, 0xffff0000, v138
	v_add_f32_e32 v76, 1.0, v76
	v_add_f32_e32 v77, 1.0, v77
	v_pk_mul_f32 v[88:89], v[80:81], v[88:89]
	v_lshlrev_b32_e32 v80, 16, v139
	v_and_b32_e32 v81, 0xffff0000, v139
	v_rcp_f32_e32 v76, v76
	v_rcp_f32_e32 v77, v77
	v_add_f32_e32 v78, 1.0, v78
	v_add_f32_e32 v79, 1.0, v79
	v_mul_f32_e32 v68, 0xbfb8aa3b, v68
	v_mul_f32_e32 v69, 0xbfb8aa3b, v69
	v_pk_mul_f32 v[90:91], v[82:83], v[80:81]
	v_rcp_f32_e32 v78, v78
	v_rcp_f32_e32 v79, v79
	v_add_f32_e32 v72, 1.0, v72
	v_add_f32_e32 v73, 1.0, v73
	v_exp_f32_e32 v68, v68
	v_exp_f32_e32 v69, v69
	v_mul_f32_e32 v70, 0xbfb8aa3b, v70
	v_mul_f32_e32 v71, 0xbfb8aa3b, v71
	v_cvt_pk_bf16_f32 v80, v84, v85
	v_cvt_pk_bf16_f32 v81, v86, v87
	v_cvt_pk_bf16_f32 v82, v88, v89
	v_cvt_pk_bf16_f32 v83, v90, v91
	v_rcp_f32_e32 v72, v72
	v_rcp_f32_e32 v73, v73
	v_add_f32_e32 v74, 1.0, v74
	v_add_f32_e32 v75, 1.0, v75
	v_exp_f32_e32 v70, v70
	v_exp_f32_e32 v71, v71
	v_mul_f32_e32 v64, 0xbfb8aa3b, v64
	v_mul_f32_e32 v65, 0xbfb8aa3b, v65
	global_store_dwordx4 v[92:93], v[80:83], off offset:1280
	v_rcp_f32_e32 v74, v74
	v_rcp_f32_e32 v75, v75
	v_lshlrev_b32_e32 v80, 16, v132
	v_and_b32_e32 v81, 0xffff0000, v132
	v_exp_f32_e32 v64, v64
	v_exp_f32_e32 v65, v65
	v_mul_f32_e32 v66, 0xbfb8aa3b, v66
	v_mul_f32_e32 v67, 0xbfb8aa3b, v67
	v_pk_mul_f32 v[76:77], v[76:77], v[80:81]
	v_lshlrev_b32_e32 v80, 16, v133
	v_and_b32_e32 v81, 0xffff0000, v133
	v_exp_f32_e32 v66, v66
	v_exp_f32_e32 v67, v67
	v_pk_mul_f32 v[78:79], v[78:79], v[80:81]
	v_lshlrev_b32_e32 v80, 16, v134
	v_and_b32_e32 v81, 0xffff0000, v134
	v_add_f32_e32 v68, 1.0, v68
	v_add_f32_e32 v69, 1.0, v69
	v_pk_mul_f32 v[80:81], v[72:73], v[80:81]
	v_lshlrev_b32_e32 v72, 16, v135
	v_and_b32_e32 v73, 0xffff0000, v135
	v_rcp_f32_e32 v68, v68
	v_rcp_f32_e32 v69, v69
	v_add_f32_e32 v70, 1.0, v70
	v_add_f32_e32 v71, 1.0, v71
	v_pk_mul_f32 v[82:83], v[74:75], v[72:73]
	v_cvt_pk_bf16_f32 v72, v76, v77
	v_mad_i64_i32 v[76:77], s[28:29], v166, s45, v[120:121]
	v_rcp_f32_e32 v70, v70
	v_rcp_f32_e32 v71, v71
	v_add_f32_e32 v64, 1.0, v64
	v_add_f32_e32 v65, 1.0, v65
	v_cvt_pk_bf16_f32 v73, v78, v79
	v_cvt_pk_bf16_f32 v74, v80, v81
	v_cvt_pk_bf16_f32 v75, v82, v83
	v_lshl_add_u64 v[76:77], v[76:77], 0, v[160:161]
	v_rcp_f32_e32 v64, v64
	v_rcp_f32_e32 v65, v65
	v_add_f32_e32 v66, 1.0, v66
	v_add_f32_e32 v67, 1.0, v67
	global_store_dwordx4 v[76:77], v[72:75], off offset:1024
	v_rcp_f32_e32 v66, v66
	v_rcp_f32_e32 v67, v67
	v_lshlrev_b32_e32 v72, 16, v128
	v_and_b32_e32 v73, 0xffff0000, v128
	v_pk_mul_f32 v[68:69], v[68:69], v[72:73]
	v_lshlrev_b32_e32 v72, 16, v129
	v_and_b32_e32 v73, 0xffff0000, v129
	v_pk_mul_f32 v[70:71], v[70:71], v[72:73]
	v_lshlrev_b32_e32 v72, 16, v130
	v_and_b32_e32 v73, 0xffff0000, v130
	v_pk_mul_f32 v[72:73], v[64:65], v[72:73]
	v_lshlrev_b32_e32 v64, 16, v131
	v_and_b32_e32 v65, 0xffff0000, v131
	v_pk_mul_f32 v[74:75], v[66:67], v[64:65]
	v_cvt_pk_bf16_f32 v64, v68, v69
	v_cvt_pk_bf16_f32 v65, v70, v71
	v_cvt_pk_bf16_f32 v66, v72, v73
	v_cvt_pk_bf16_f32 v67, v74, v75
	global_store_dwordx4 v[76:77], v[64:67], off offset:1280
	v_add_u32_e32 v102, 0x80, v162
	v_ashrrev_i32_e32 v103, 31, v102
	v_lshlrev_b64 v[64:65], 10, v[102:103]
	v_add_u32_e32 v88, 0x90, v162
	v_lshl_add_u64 v[64:65], v[164:165], 0, v[64:65]
	v_ashrrev_i32_e32 v89, 31, v88
	global_load_dwordx4 v[90:93], v[64:65], off
	global_load_dwordx4 v[94:97], v[64:65], off offset:256
	v_lshlrev_b64 v[64:65], 10, v[88:89]
	v_add_u32_e32 v86, 0xa0, v162
	v_lshl_add_u64 v[64:65], v[164:165], 0, v[64:65]
	v_ashrrev_i32_e32 v87, 31, v86
	global_load_dwordx4 v[98:101], v[64:65], off
	global_load_dwordx4 v[80:83], v[64:65], off offset:256
	v_lshlrev_b64 v[64:65], 10, v[86:87]
	v_add_u32_e32 v84, 0xb0, v162
	v_lshl_add_u64 v[64:65], v[164:165], 0, v[64:65]
	v_ashrrev_i32_e32 v85, 31, v84
	global_load_dwordx4 v[76:79], v[64:65], off
	global_load_dwordx4 v[72:75], v[64:65], off offset:256
	v_lshlrev_b64 v[64:65], 10, v[84:85]
	v_lshl_add_u64 v[64:65], v[164:165], 0, v[64:65]
	global_load_dwordx4 v[68:71], v[64:65], off
	s_nop 0
	global_load_dwordx4 v[64:67], v[64:65], off offset:256
	v_mul_f32_e32 v62, 0xbfb8aa3b, v62
	v_mul_f32_e32 v63, 0xbfb8aa3b, v63
	v_mul_f32_e32 v60, 0xbfb8aa3b, v60
	v_mul_f32_e32 v61, 0xbfb8aa3b, v61
	v_exp_f32_e32 v62, v62
	v_exp_f32_e32 v63, v63
	v_mul_f32_e32 v56, 0xbfb8aa3b, v56
	v_mul_f32_e32 v57, 0xbfb8aa3b, v57
	v_exp_f32_e32 v60, v60
	v_exp_f32_e32 v61, v61
	v_exp_f32_e32 v56, v56
	v_exp_f32_e32 v57, v57
	v_mul_f32_e32 v58, 0xbfb8aa3b, v58
	v_mul_f32_e32 v59, 0xbfb8aa3b, v59
	v_exp_f32_e32 v58, v58
	v_exp_f32_e32 v59, v59
	v_add_f32_e32 v62, 1.0, v62
	v_add_f32_e32 v63, 1.0, v63
	v_mul_f32_e32 v52, 0xbfb8aa3b, v52
	v_mul_f32_e32 v53, 0xbfb8aa3b, v53
	v_add_f32_e32 v60, 1.0, v60
	v_add_f32_e32 v61, 1.0, v61
	v_rcp_f32_e32 v62, v62
	v_rcp_f32_e32 v63, v63
	v_add_f32_e32 v56, 1.0, v56
	v_add_f32_e32 v57, 1.0, v57
	v_exp_f32_e32 v52, v52
	v_exp_f32_e32 v53, v53
	v_mul_f32_e32 v54, 0xbfb8aa3b, v54
	v_mul_f32_e32 v55, 0xbfb8aa3b, v55
	v_rcp_f32_e32 v60, v60
	v_rcp_f32_e32 v61, v61
	v_rcp_f32_e32 v56, v56
	v_rcp_f32_e32 v57, v57
	v_add_f32_e32 v58, 1.0, v58
	v_add_f32_e32 v59, 1.0, v59
	v_exp_f32_e32 v54, v54
	v_exp_f32_e32 v55, v55
	v_mul_f32_e32 v48, 0xbfb8aa3b, v48
	v_mul_f32_e32 v49, 0xbfb8aa3b, v49
	v_rcp_f32_e32 v58, v58
	v_rcp_f32_e32 v59, v59
	v_exp_f32_e32 v48, v48
	v_exp_f32_e32 v49, v49
	v_mul_f32_e32 v50, 0xbfb8aa3b, v50
	v_mul_f32_e32 v51, 0xbfb8aa3b, v51
	s_waitcnt vmcnt(7)
	v_lshlrev_b32_e32 v104, 16, v90
	v_and_b32_e32 v105, 0xffff0000, v90
	v_lshlrev_b32_e32 v90, 16, v91
	v_and_b32_e32 v91, 0xffff0000, v91
	v_exp_f32_e32 v50, v50
	v_exp_f32_e32 v51, v51
	v_pk_mul_f32 v[62:63], v[62:63], v[90:91]
	v_lshlrev_b32_e32 v90, 16, v92
	v_and_b32_e32 v91, 0xffff0000, v92
	v_add_f32_e32 v52, 1.0, v52
	v_add_f32_e32 v53, 1.0, v53
	v_pk_mul_f32 v[60:61], v[60:61], v[104:105]
	v_pk_mul_f32 v[90:91], v[56:57], v[90:91]
	v_lshlrev_b32_e32 v56, 16, v93
	v_and_b32_e32 v57, 0xffff0000, v93
	v_rcp_f32_e32 v52, v52
	v_rcp_f32_e32 v53, v53
	v_add_f32_e32 v54, 1.0, v54
	v_add_f32_e32 v55, 1.0, v55
	v_mul_f32_e32 v44, 0xbfb8aa3b, v44
	v_mul_f32_e32 v45, 0xbfb8aa3b, v45
	v_pk_mul_f32 v[92:93], v[58:59], v[56:57]
	v_cvt_pk_bf16_f32 v56, v60, v61
	v_mad_i64_i32 v[60:61], s[28:29], v102, s45, v[120:121]
	v_rcp_f32_e32 v54, v54
	v_rcp_f32_e32 v55, v55
	v_add_f32_e32 v48, 1.0, v48
	v_add_f32_e32 v49, 1.0, v49
	v_exp_f32_e32 v44, v44
	v_exp_f32_e32 v45, v45
	v_mul_f32_e32 v46, 0xbfb8aa3b, v46
	v_mul_f32_e32 v47, 0xbfb8aa3b, v47
	v_cvt_pk_bf16_f32 v57, v62, v63
	v_cvt_pk_bf16_f32 v58, v90, v91
	v_cvt_pk_bf16_f32 v59, v92, v93
	v_lshl_add_u64 v[60:61], v[60:61], 0, v[160:161]
	v_rcp_f32_e32 v48, v48
	v_rcp_f32_e32 v49, v49
	v_add_f32_e32 v50, 1.0, v50
	v_add_f32_e32 v51, 1.0, v51
	v_exp_f32_e32 v46, v46
	v_exp_f32_e32 v47, v47
	v_mul_f32_e32 v40, 0xbfb8aa3b, v40
	v_mul_f32_e32 v41, 0xbfb8aa3b, v41
	global_store_dwordx4 v[60:61], v[56:59], off offset:1024
	v_rcp_f32_e32 v50, v50
	v_rcp_f32_e32 v51, v51
	s_waitcnt vmcnt(7)
	v_lshlrev_b32_e32 v56, 16, v94
	v_and_b32_e32 v57, 0xffff0000, v94
	v_exp_f32_e32 v40, v40
	v_exp_f32_e32 v41, v41
	v_mul_f32_e32 v42, 0xbfb8aa3b, v42
	v_mul_f32_e32 v43, 0xbfb8aa3b, v43
	v_pk_mul_f32 v[52:53], v[52:53], v[56:57]
	v_lshlrev_b32_e32 v56, 16, v95
	v_and_b32_e32 v57, 0xffff0000, v95
	v_exp_f32_e32 v42, v42
	v_exp_f32_e32 v43, v43
	v_pk_mul_f32 v[54:55], v[54:55], v[56:57]
	v_lshlrev_b32_e32 v56, 16, v96
	v_and_b32_e32 v57, 0xffff0000, v96
	v_add_f32_e32 v44, 1.0, v44
	v_add_f32_e32 v45, 1.0, v45
	v_pk_mul_f32 v[56:57], v[48:49], v[56:57]
	v_lshlrev_b32_e32 v48, 16, v97
	v_and_b32_e32 v49, 0xffff0000, v97
	v_rcp_f32_e32 v44, v44
	v_rcp_f32_e32 v45, v45
	v_add_f32_e32 v46, 1.0, v46
	v_add_f32_e32 v47, 1.0, v47
	v_mul_f32_e32 v36, 0xbfb8aa3b, v36
	v_mul_f32_e32 v37, 0xbfb8aa3b, v37
	v_pk_mul_f32 v[58:59], v[50:51], v[48:49]
	v_rcp_f32_e32 v46, v46
	v_rcp_f32_e32 v47, v47
	v_add_f32_e32 v40, 1.0, v40
	v_add_f32_e32 v41, 1.0, v41
	v_exp_f32_e32 v36, v36
	v_exp_f32_e32 v37, v37
	v_mul_f32_e32 v38, 0xbfb8aa3b, v38
	v_mul_f32_e32 v39, 0xbfb8aa3b, v39
	v_cvt_pk_bf16_f32 v48, v52, v53
	v_cvt_pk_bf16_f32 v49, v54, v55
	v_cvt_pk_bf16_f32 v50, v56, v57
	v_cvt_pk_bf16_f32 v51, v58, v59
	v_rcp_f32_e32 v40, v40
	v_rcp_f32_e32 v41, v41
	v_add_f32_e32 v42, 1.0, v42
	v_add_f32_e32 v43, 1.0, v43
	v_exp_f32_e32 v38, v38
	v_exp_f32_e32 v39, v39
	v_mul_f32_e32 v32, 0xbfb8aa3b, v32
	v_mul_f32_e32 v33, 0xbfb8aa3b, v33
	global_store_dwordx4 v[60:61], v[48:51], off offset:1280
	v_rcp_f32_e32 v42, v42
	v_rcp_f32_e32 v43, v43
	s_waitcnt vmcnt(7)
	v_lshlrev_b32_e32 v48, 16, v98
	v_and_b32_e32 v49, 0xffff0000, v98
	v_exp_f32_e32 v32, v32
	v_exp_f32_e32 v33, v33
	v_mul_f32_e32 v34, 0xbfb8aa3b, v34
	v_mul_f32_e32 v35, 0xbfb8aa3b, v35
	v_pk_mul_f32 v[44:45], v[44:45], v[48:49]
	v_lshlrev_b32_e32 v48, 16, v99
	v_and_b32_e32 v49, 0xffff0000, v99
	v_exp_f32_e32 v34, v34
	v_exp_f32_e32 v35, v35
	v_pk_mul_f32 v[46:47], v[46:47], v[48:49]
	v_lshlrev_b32_e32 v48, 16, v100
	v_and_b32_e32 v49, 0xffff0000, v100
	v_add_f32_e32 v36, 1.0, v36
	v_add_f32_e32 v37, 1.0, v37
	v_pk_mul_f32 v[48:49], v[40:41], v[48:49]
	v_lshlrev_b32_e32 v40, 16, v101
	v_and_b32_e32 v41, 0xffff0000, v101
	v_rcp_f32_e32 v36, v36
	v_rcp_f32_e32 v37, v37
	v_add_f32_e32 v38, 1.0, v38
	v_add_f32_e32 v39, 1.0, v39
	v_mul_f32_e32 v28, 0xbfb8aa3b, v28
	v_mul_f32_e32 v29, 0xbfb8aa3b, v29
	v_pk_mul_f32 v[50:51], v[42:43], v[40:41]
	v_cvt_pk_bf16_f32 v40, v44, v45
	v_mad_i64_i32 v[44:45], s[28:29], v88, s45, v[120:121]
	v_rcp_f32_e32 v38, v38
	v_rcp_f32_e32 v39, v39
	v_add_f32_e32 v32, 1.0, v32
	v_add_f32_e32 v33, 1.0, v33
	v_exp_f32_e32 v28, v28
	v_exp_f32_e32 v29, v29
	v_mul_f32_e32 v30, 0xbfb8aa3b, v30
	v_mul_f32_e32 v31, 0xbfb8aa3b, v31
	v_cvt_pk_bf16_f32 v41, v46, v47
	v_cvt_pk_bf16_f32 v42, v48, v49
	v_cvt_pk_bf16_f32 v43, v50, v51
	v_lshl_add_u64 v[44:45], v[44:45], 0, v[160:161]
	v_rcp_f32_e32 v32, v32
	v_rcp_f32_e32 v33, v33
	v_add_f32_e32 v34, 1.0, v34
	v_add_f32_e32 v35, 1.0, v35
	v_exp_f32_e32 v30, v30
	v_exp_f32_e32 v31, v31
	v_mul_f32_e32 v24, 0xbfb8aa3b, v24
	v_mul_f32_e32 v25, 0xbfb8aa3b, v25
	global_store_dwordx4 v[44:45], v[40:43], off offset:1024
	v_rcp_f32_e32 v34, v34
	v_rcp_f32_e32 v35, v35
	s_waitcnt vmcnt(7)
	v_lshlrev_b32_e32 v40, 16, v80
	v_and_b32_e32 v41, 0xffff0000, v80
	v_exp_f32_e32 v24, v24
	v_exp_f32_e32 v25, v25
	v_mul_f32_e32 v26, 0xbfb8aa3b, v26
	v_mul_f32_e32 v27, 0xbfb8aa3b, v27
	v_pk_mul_f32 v[36:37], v[36:37], v[40:41]
	v_lshlrev_b32_e32 v40, 16, v81
	v_and_b32_e32 v41, 0xffff0000, v81
	v_exp_f32_e32 v26, v26
	v_exp_f32_e32 v27, v27
	v_pk_mul_f32 v[38:39], v[38:39], v[40:41]
	v_lshlrev_b32_e32 v40, 16, v82
	v_and_b32_e32 v41, 0xffff0000, v82
	v_add_f32_e32 v28, 1.0, v28
	v_add_f32_e32 v29, 1.0, v29
	v_pk_mul_f32 v[40:41], v[32:33], v[40:41]
	v_lshlrev_b32_e32 v32, 16, v83
	v_and_b32_e32 v33, 0xffff0000, v83
	v_rcp_f32_e32 v28, v28
	v_rcp_f32_e32 v29, v29
	v_add_f32_e32 v30, 1.0, v30
	v_add_f32_e32 v31, 1.0, v31
	v_mul_f32_e32 v20, 0xbfb8aa3b, v20
	v_mul_f32_e32 v21, 0xbfb8aa3b, v21
	v_pk_mul_f32 v[42:43], v[34:35], v[32:33]
	v_rcp_f32_e32 v30, v30
	v_rcp_f32_e32 v31, v31
	v_add_f32_e32 v24, 1.0, v24
	v_add_f32_e32 v25, 1.0, v25
	v_exp_f32_e32 v20, v20
	v_exp_f32_e32 v21, v21
	v_mul_f32_e32 v22, 0xbfb8aa3b, v22
	v_mul_f32_e32 v23, 0xbfb8aa3b, v23
	v_cvt_pk_bf16_f32 v32, v36, v37
	v_cvt_pk_bf16_f32 v33, v38, v39
	v_cvt_pk_bf16_f32 v34, v40, v41
	v_cvt_pk_bf16_f32 v35, v42, v43
	v_rcp_f32_e32 v24, v24
	v_rcp_f32_e32 v25, v25
	v_add_f32_e32 v26, 1.0, v26
	v_add_f32_e32 v27, 1.0, v27
	v_exp_f32_e32 v22, v22
	v_exp_f32_e32 v23, v23
	v_mul_f32_e32 v16, 0xbfb8aa3b, v16
	v_mul_f32_e32 v17, 0xbfb8aa3b, v17
	global_store_dwordx4 v[44:45], v[32:35], off offset:1280
	v_rcp_f32_e32 v26, v26
	v_rcp_f32_e32 v27, v27
	s_waitcnt vmcnt(7)
	v_lshlrev_b32_e32 v32, 16, v76
	v_and_b32_e32 v33, 0xffff0000, v76
	v_exp_f32_e32 v16, v16
	v_exp_f32_e32 v17, v17
	v_mul_f32_e32 v18, 0xbfb8aa3b, v18
	v_mul_f32_e32 v19, 0xbfb8aa3b, v19
	v_pk_mul_f32 v[28:29], v[28:29], v[32:33]
	v_lshlrev_b32_e32 v32, 16, v77
	v_and_b32_e32 v33, 0xffff0000, v77
	v_exp_f32_e32 v18, v18
	v_exp_f32_e32 v19, v19
	v_pk_mul_f32 v[30:31], v[30:31], v[32:33]
	v_lshlrev_b32_e32 v32, 16, v78
	v_and_b32_e32 v33, 0xffff0000, v78
	v_add_f32_e32 v20, 1.0, v20
	v_add_f32_e32 v21, 1.0, v21
	v_pk_mul_f32 v[32:33], v[24:25], v[32:33]
	v_lshlrev_b32_e32 v24, 16, v79
	v_and_b32_e32 v25, 0xffff0000, v79
	v_rcp_f32_e32 v20, v20
	v_rcp_f32_e32 v21, v21
	v_add_f32_e32 v22, 1.0, v22
	v_add_f32_e32 v23, 1.0, v23
	v_mul_f32_e32 v12, 0xbfb8aa3b, v12
	v_mul_f32_e32 v13, 0xbfb8aa3b, v13
	v_pk_mul_f32 v[34:35], v[26:27], v[24:25]
	v_cvt_pk_bf16_f32 v24, v28, v29
	v_mad_i64_i32 v[28:29], s[28:29], v86, s45, v[120:121]
	v_rcp_f32_e32 v22, v22
	v_rcp_f32_e32 v23, v23
	v_add_f32_e32 v16, 1.0, v16
	v_add_f32_e32 v17, 1.0, v17
	v_exp_f32_e32 v12, v12
	v_exp_f32_e32 v13, v13
	v_mul_f32_e32 v14, 0xbfb8aa3b, v14
	v_mul_f32_e32 v15, 0xbfb8aa3b, v15
	v_cvt_pk_bf16_f32 v25, v30, v31
	v_cvt_pk_bf16_f32 v26, v32, v33
	v_cvt_pk_bf16_f32 v27, v34, v35
	v_lshl_add_u64 v[28:29], v[28:29], 0, v[160:161]
	v_rcp_f32_e32 v16, v16
	v_rcp_f32_e32 v17, v17
	v_add_f32_e32 v18, 1.0, v18
	v_add_f32_e32 v19, 1.0, v19
	v_exp_f32_e32 v14, v14
	v_exp_f32_e32 v15, v15
	v_mul_f32_e32 v8, 0xbfb8aa3b, v8
	v_mul_f32_e32 v9, 0xbfb8aa3b, v9
	global_store_dwordx4 v[28:29], v[24:27], off offset:1024
	v_rcp_f32_e32 v18, v18
	v_rcp_f32_e32 v19, v19
	s_waitcnt vmcnt(7)
	v_lshlrev_b32_e32 v24, 16, v72
	v_and_b32_e32 v25, 0xffff0000, v72
	v_exp_f32_e32 v8, v8
	v_exp_f32_e32 v9, v9
	v_mul_f32_e32 v10, 0xbfb8aa3b, v10
	v_mul_f32_e32 v11, 0xbfb8aa3b, v11
	v_pk_mul_f32 v[20:21], v[20:21], v[24:25]
	v_lshlrev_b32_e32 v24, 16, v73
	v_and_b32_e32 v25, 0xffff0000, v73
	v_exp_f32_e32 v10, v10
	v_exp_f32_e32 v11, v11
	v_pk_mul_f32 v[22:23], v[22:23], v[24:25]
	v_lshlrev_b32_e32 v24, 16, v74
	v_and_b32_e32 v25, 0xffff0000, v74
	v_add_f32_e32 v12, 1.0, v12
	v_add_f32_e32 v13, 1.0, v13
	v_pk_mul_f32 v[24:25], v[16:17], v[24:25]
	v_lshlrev_b32_e32 v16, 16, v75
	v_and_b32_e32 v17, 0xffff0000, v75
	v_rcp_f32_e32 v12, v12
	v_rcp_f32_e32 v13, v13
	v_add_f32_e32 v14, 1.0, v14
	v_add_f32_e32 v15, 1.0, v15
	v_mul_f32_e32 v4, 0xbfb8aa3b, v4
	v_mul_f32_e32 v5, 0xbfb8aa3b, v5
	v_pk_mul_f32 v[26:27], v[18:19], v[16:17]
	v_rcp_f32_e32 v14, v14
	v_rcp_f32_e32 v15, v15
	v_add_f32_e32 v8, 1.0, v8
	v_add_f32_e32 v9, 1.0, v9
	v_exp_f32_e32 v4, v4
	v_exp_f32_e32 v5, v5
	v_mul_f32_e32 v6, 0xbfb8aa3b, v6
	v_mul_f32_e32 v7, 0xbfb8aa3b, v7
	v_cvt_pk_bf16_f32 v16, v20, v21
	v_cvt_pk_bf16_f32 v17, v22, v23
	v_cvt_pk_bf16_f32 v18, v24, v25
	v_cvt_pk_bf16_f32 v19, v26, v27
	v_rcp_f32_e32 v8, v8
	v_rcp_f32_e32 v9, v9
	v_add_f32_e32 v10, 1.0, v10
	v_add_f32_e32 v11, 1.0, v11
	v_exp_f32_e32 v6, v6
	v_exp_f32_e32 v7, v7
	v_mul_f32_e32 v0, 0xbfb8aa3b, v0
	v_mul_f32_e32 v1, 0xbfb8aa3b, v1
	global_store_dwordx4 v[28:29], v[16:19], off offset:1280
	v_rcp_f32_e32 v10, v10
	v_rcp_f32_e32 v11, v11
	s_waitcnt vmcnt(7)
	v_lshlrev_b32_e32 v16, 16, v68
	v_and_b32_e32 v17, 0xffff0000, v68
	v_exp_f32_e32 v0, v0
	v_exp_f32_e32 v1, v1
	v_mul_f32_e32 v2, 0xbfb8aa3b, v2
	v_mul_f32_e32 v3, 0xbfb8aa3b, v3
	v_pk_mul_f32 v[12:13], v[12:13], v[16:17]
	v_lshlrev_b32_e32 v16, 16, v69
	v_and_b32_e32 v17, 0xffff0000, v69
	v_exp_f32_e32 v2, v2
	v_exp_f32_e32 v3, v3
	v_pk_mul_f32 v[14:15], v[14:15], v[16:17]
	v_lshlrev_b32_e32 v16, 16, v70
	v_and_b32_e32 v17, 0xffff0000, v70
	v_add_f32_e32 v4, 1.0, v4
	v_add_f32_e32 v5, 1.0, v5
	v_pk_mul_f32 v[16:17], v[8:9], v[16:17]
	v_lshlrev_b32_e32 v8, 16, v71
	v_and_b32_e32 v9, 0xffff0000, v71
	v_rcp_f32_e32 v4, v4
	v_rcp_f32_e32 v5, v5
	v_add_f32_e32 v6, 1.0, v6
	v_add_f32_e32 v7, 1.0, v7
	v_pk_mul_f32 v[18:19], v[10:11], v[8:9]
	v_cvt_pk_bf16_f32 v8, v12, v13
	v_mad_i64_i32 v[12:13], s[28:29], v84, s45, v[120:121]
	v_rcp_f32_e32 v6, v6
	v_rcp_f32_e32 v7, v7
	v_add_f32_e32 v0, 1.0, v0
	v_add_f32_e32 v1, 1.0, v1
	v_cvt_pk_bf16_f32 v9, v14, v15
	v_cvt_pk_bf16_f32 v10, v16, v17
	v_cvt_pk_bf16_f32 v11, v18, v19
	v_lshl_add_u64 v[12:13], v[12:13], 0, v[160:161]
	v_rcp_f32_e32 v0, v0
	v_rcp_f32_e32 v1, v1
	v_add_f32_e32 v2, 1.0, v2
	v_add_f32_e32 v3, 1.0, v3
	global_store_dwordx4 v[12:13], v[8:11], off offset:1024
	v_rcp_f32_e32 v2, v2
	v_rcp_f32_e32 v3, v3
	s_waitcnt vmcnt(7)
	v_lshlrev_b32_e32 v8, 16, v64
	v_and_b32_e32 v9, 0xffff0000, v64
	v_pk_mul_f32 v[4:5], v[4:5], v[8:9]
	v_lshlrev_b32_e32 v8, 16, v65
	v_and_b32_e32 v9, 0xffff0000, v65
	v_pk_mul_f32 v[6:7], v[6:7], v[8:9]
	v_lshlrev_b32_e32 v8, 16, v66
	v_and_b32_e32 v9, 0xffff0000, v66
	v_pk_mul_f32 v[8:9], v[0:1], v[8:9]
	v_lshlrev_b32_e32 v0, 16, v67
	v_and_b32_e32 v1, 0xffff0000, v67
	v_pk_mul_f32 v[10:11], v[2:3], v[0:1]
	v_cvt_pk_bf16_f32 v0, v4, v5
	v_cvt_pk_bf16_f32 v1, v6, v7
	v_cvt_pk_bf16_f32 v2, v8, v9
	v_cvt_pk_bf16_f32 v3, v10, v11
	global_store_dwordx4 v[12:13], v[0:3], off offset:1280
	s_andn2_b64 vcc, exec, s[22:23]
	s_mov_b64 s[22:23], -1
	s_cbranch_vccnz .LBB0_803
	s_andn2_b64 vcc, exec, s[2:3]
	s_cbranch_vccnz .LBB0_802
	v_writelane_b32 v255, 1, 53
	s_branch .LBB0_802

.LBB0_892:
	s_ashr_i32 s19, s18, 31
	s_lshl_b64 s[20:21], s[18:19], 18
	s_add_u32 s20, s0, s20
	s_addc_u32 s21, s1, s21
	s_and_b64 s[22:23], s[2:3], exec
	s_cselect_b32 s19, s21, s27
	s_cselect_b32 s48, s20, s26
	s_ashr_i32 s17, s16, 31
	s_lshl_b64 s[22:23], s[16:17], 18
	s_add_u32 s22, s34, s22
	s_addc_u32 s23, s35, s23
	s_and_b64 s[30:31], s[2:3], exec
	s_cselect_b32 s17, s23, s29
	s_cselect_b32 s49, s22, s28
	s_add_u32 s26, s26, 0x20080
	s_addc_u32 s27, s27, 0
	s_add_u32 s50, s28, 0x100
	v_mov_b32_e32 v0, 0
	s_addc_u32 s51, s29, 0
	s_mov_b32 s52, -2
	v_mov_b32_e32 v1, v0
	v_mov_b32_e32 v2, v0
	v_mov_b32_e32 v3, v0
	v_mov_b32_e32 v4, v0
	v_mov_b32_e32 v5, v0
	v_mov_b32_e32 v6, v0
	v_mov_b32_e32 v7, v0
	v_mov_b32_e32 v16, v0
	v_mov_b32_e32 v17, v0
	v_mov_b32_e32 v18, v0
	v_mov_b32_e32 v19, v0
	v_mov_b32_e32 v20, v0
	v_mov_b32_e32 v21, v0
	v_mov_b32_e32 v22, v0
	v_mov_b32_e32 v23, v0
	v_mov_b32_e32 v32, v0
	v_mov_b32_e32 v33, v0
	v_mov_b32_e32 v34, v0
	v_mov_b32_e32 v35, v0
	v_mov_b32_e32 v36, v0
	v_mov_b32_e32 v37, v0
	v_mov_b32_e32 v38, v0
	v_mov_b32_e32 v39, v0
	v_mov_b32_e32 v48, v0
	v_mov_b32_e32 v49, v0
	v_mov_b32_e32 v50, v0
	v_mov_b32_e32 v51, v0
	v_mov_b32_e32 v52, v0
	v_mov_b32_e32 v53, v0
	v_mov_b32_e32 v54, v0
	v_mov_b32_e32 v55, v0
	v_mov_b32_e32 v8, v0
	v_mov_b32_e32 v9, v0
	v_mov_b32_e32 v10, v0
	v_mov_b32_e32 v11, v0
	v_mov_b32_e32 v12, v0
	v_mov_b32_e32 v13, v0
	v_mov_b32_e32 v14, v0
	v_mov_b32_e32 v15, v0
	v_mov_b32_e32 v24, v0
	v_mov_b32_e32 v25, v0
	v_mov_b32_e32 v26, v0
	v_mov_b32_e32 v27, v0
	v_mov_b32_e32 v28, v0
	v_mov_b32_e32 v29, v0
	v_mov_b32_e32 v30, v0
	v_mov_b32_e32 v31, v0
	v_mov_b32_e32 v40, v0
	v_mov_b32_e32 v41, v0
	v_mov_b32_e32 v42, v0
	v_mov_b32_e32 v43, v0
	v_mov_b32_e32 v44, v0
	v_mov_b32_e32 v45, v0
	v_mov_b32_e32 v46, v0
	v_mov_b32_e32 v47, v0
	v_mov_b32_e32 v56, v0
	v_mov_b32_e32 v57, v0
	v_mov_b32_e32 v58, v0
	v_mov_b32_e32 v59, v0
	v_mov_b32_e32 v60, v0
	v_mov_b32_e32 v61, v0
	v_mov_b32_e32 v62, v0
	v_mov_b32_e32 v63, v0
	v_mov_b32_e32 v64, v0
	v_mov_b32_e32 v65, v0
	v_mov_b32_e32 v66, v0
	v_mov_b32_e32 v67, v0
	v_mov_b32_e32 v68, v0
	v_mov_b32_e32 v69, v0
	v_mov_b32_e32 v70, v0
	v_mov_b32_e32 v71, v0
	v_mov_b32_e32 v80, v0
	v_mov_b32_e32 v81, v0
	v_mov_b32_e32 v82, v0
	v_mov_b32_e32 v83, v0
	v_mov_b32_e32 v84, v0
	v_mov_b32_e32 v85, v0
	v_mov_b32_e32 v86, v0
	v_mov_b32_e32 v87, v0
	v_mov_b32_e32 v96, v0
	v_mov_b32_e32 v97, v0
	v_mov_b32_e32 v98, v0
	v_mov_b32_e32 v99, v0
	v_mov_b32_e32 v100, v0
	v_mov_b32_e32 v101, v0
	v_mov_b32_e32 v102, v0
	v_mov_b32_e32 v103, v0
	v_mov_b32_e32 v112, v0
	v_mov_b32_e32 v113, v0
	v_mov_b32_e32 v114, v0
	v_mov_b32_e32 v115, v0
	v_mov_b32_e32 v116, v0
	v_mov_b32_e32 v117, v0
	v_mov_b32_e32 v118, v0
	v_mov_b32_e32 v119, v0
	v_mov_b32_e32 v72, v0
	v_mov_b32_e32 v73, v0
	v_mov_b32_e32 v74, v0
	v_mov_b32_e32 v75, v0
	v_mov_b32_e32 v76, v0
	v_mov_b32_e32 v77, v0
	v_mov_b32_e32 v78, v0
	v_mov_b32_e32 v79, v0
	v_mov_b32_e32 v88, v0
	v_mov_b32_e32 v89, v0
	v_mov_b32_e32 v90, v0
	v_mov_b32_e32 v91, v0
	v_mov_b32_e32 v92, v0
	v_mov_b32_e32 v93, v0
	v_mov_b32_e32 v94, v0
	v_mov_b32_e32 v95, v0
	v_mov_b32_e32 v104, v0
	v_mov_b32_e32 v105, v0
	v_mov_b32_e32 v106, v0
	v_mov_b32_e32 v107, v0
	v_mov_b32_e32 v108, v0
	v_mov_b32_e32 v109, v0
	v_mov_b32_e32 v110, v0
	v_mov_b32_e32 v111, v0
	v_mov_b32_e32 v120, v0
	v_mov_b32_e32 v121, v0
	v_mov_b32_e32 v122, v0
	v_mov_b32_e32 v123, v0
	v_mov_b32_e32 v124, v0
	v_mov_b32_e32 v125, v0
	v_mov_b32_e32 v126, v0
	v_mov_b32_e32 v127, v0
	v_readlane_b32 s97, v255, 53
	s_nop 3
	s_cmp_eq_u32 s97, 1
	s_cbranch_scc0 .Llsb_skip_5
	v_writelane_b32 v255, 0, 53
	s_barrier
.Llsb_skip_5:
.LBB0_893:
	ds_read_b128 v[128:131], v189
	ds_read_b128 v[132:135], v189 offset:1024
	ds_read_b128 v[136:139], v189 offset:2048
	ds_read_b128 v[140:143], v189 offset:3072
	ds_read_b128 v[144:147], v190
	ds_read_b128 v[164:167], v190 offset:1024
	ds_read_b128 v[168:171], v190 offset:2048
	ds_read_b128 v[172:175], v190 offset:3072
	s_add_u32 s28, s26, 0xfffe0080
	s_addc_u32 s29, s27, -1
	s_cmp_eq_u32 s52, 4
	s_cselect_b32 s31, s19, s29
	s_cselect_b32 s30, s48, s28
	s_cselect_b32 s29, s17, s51
	s_cselect_b32 s28, s49, s50
	v_lshl_add_u64 v[226:227], s[26:27], 0, v[156:157]
	s_add_i32 m0, s25, 0xc000
	ds_read_b128 v[192:195], v191
	ds_read_b128 v[196:199], v191 offset:1024
	ds_read_b128 v[200:203], v191 offset:2048
	ds_read_b128 v[206:209], v191 offset:3072
	ds_read_b128 v[210:213], v191 offset:4096
	ds_read_b128 v[214:217], v191 offset:5120
	ds_read_b128 v[218:221], v191 offset:6144
	ds_read_b128 v[222:225], v191 offset:7168
	global_load_lds_dwordx4 v[226:227], off
	v_lshl_add_u64 v[226:227], s[26:27], 0, v[158:159]
	s_add_i32 m0, s25, 0xe000
	s_nop 0
	global_load_lds_dwordx4 v[226:227], off
	s_waitcnt vmcnt(8)
	s_waitcnt lgkmcnt(0)
	s_barrier
	s_setprio 1
	s_waitcnt lgkmcnt(0)
	v_mfma_f32_16x16x32_bf16 v[124:127], v[128:131], v[192:195], v[124:127]
	v_mfma_f32_16x16x32_bf16 v[120:123], v[136:139], v[192:195], v[120:123]
	v_mfma_f32_16x16x32_bf16 v[108:111], v[128:131], v[200:203], v[108:111]
	v_mfma_f32_16x16x32_bf16 v[104:107], v[136:139], v[200:203], v[104:107]
	v_mfma_f32_16x16x32_bf16 v[92:95], v[128:131], v[210:213], v[92:95]
	v_mfma_f32_16x16x32_bf16 v[88:91], v[136:139], v[210:213], v[88:91]
	v_mfma_f32_16x16x32_bf16 v[76:79], v[128:131], v[218:221], v[76:79]
	v_mfma_f32_16x16x32_bf16 v[72:75], v[136:139], v[218:221], v[72:75]
	v_mfma_f32_16x16x32_bf16 v[124:127], v[132:135], v[196:199], v[124:127]
	v_mfma_f32_16x16x32_bf16 v[120:123], v[140:143], v[196:199], v[120:123]
	v_mfma_f32_16x16x32_bf16 v[108:111], v[132:135], v[206:209], v[108:111]
	v_mfma_f32_16x16x32_bf16 v[104:107], v[140:143], v[206:209], v[104:107]
	v_mfma_f32_16x16x32_bf16 v[92:95], v[132:135], v[214:217], v[92:95]
	v_mfma_f32_16x16x32_bf16 v[88:91], v[140:143], v[214:217], v[88:91]
	v_mfma_f32_16x16x32_bf16 v[76:79], v[132:135], v[222:225], v[76:79]
	v_mfma_f32_16x16x32_bf16 v[72:75], v[140:143], v[222:225], v[72:75]
	s_setprio 0
	s_setprio 1
	v_mfma_f32_16x16x32_bf16 v[116:119], v[144:147], v[192:195], v[116:119]
	v_mfma_f32_16x16x32_bf16 v[112:115], v[168:171], v[192:195], v[112:115]
	v_mfma_f32_16x16x32_bf16 v[100:103], v[144:147], v[200:203], v[100:103]
	v_mfma_f32_16x16x32_bf16 v[96:99], v[168:171], v[200:203], v[96:99]
	v_mfma_f32_16x16x32_bf16 v[84:87], v[144:147], v[210:213], v[84:87]
	v_mfma_f32_16x16x32_bf16 v[80:83], v[168:171], v[210:213], v[80:83]
	v_mfma_f32_16x16x32_bf16 v[68:71], v[144:147], v[218:221], v[68:71]
	v_mfma_f32_16x16x32_bf16 v[64:67], v[168:171], v[218:221], v[64:67]
	v_mfma_f32_16x16x32_bf16 v[116:119], v[164:167], v[196:199], v[116:119]
	v_mfma_f32_16x16x32_bf16 v[112:115], v[172:175], v[196:199], v[112:115]
	v_mfma_f32_16x16x32_bf16 v[100:103], v[164:167], v[206:209], v[100:103]
	v_mfma_f32_16x16x32_bf16 v[96:99], v[172:175], v[206:209], v[96:99]
	v_mfma_f32_16x16x32_bf16 v[84:87], v[164:167], v[214:217], v[84:87]
	v_mfma_f32_16x16x32_bf16 v[80:83], v[172:175], v[214:217], v[80:83]
	v_mfma_f32_16x16x32_bf16 v[68:71], v[164:167], v[222:225], v[68:71]
	v_mfma_f32_16x16x32_bf16 v[64:67], v[172:175], v[222:225], v[64:67]
	s_setprio 0
	s_barrier
	s_add_i32 s53, s44, s36
	v_lshl_add_u64 v[226:227], s[28:29], 0, v[150:151]
	s_mov_b32 m0, s53
	ds_read_b128 v[192:195], v191 offset:16384
	ds_read_b128 v[196:199], v191 offset:17408
	ds_read_b128 v[200:203], v191 offset:18432
	ds_read_b128 v[206:209], v191 offset:19456
	ds_read_b128 v[210:213], v191 offset:20480
	ds_read_b128 v[214:217], v191 offset:21504
	ds_read_b128 v[218:221], v191 offset:22528
	ds_read_b128 v[222:225], v191 offset:23552
	global_load_lds_dwordx4 v[226:227], off
	s_add_i32 m0, s53, 0x2000
	s_add_u32 s54, s28, 0x20000
	v_lshl_add_u64 v[228:229], s[28:29], 0, v[154:155]
	s_addc_u32 s55, s29, 0
	s_add_i32 s53, s45, s36
	global_load_lds_dwordx4 v[228:229], off
	v_lshl_add_u64 v[230:231], s[54:55], 0, v[150:151]
	s_mov_b32 m0, s53
	v_lshl_add_u64 v[232:233], s[30:31], 0, v[152:153]
	global_load_lds_dwordx4 v[230:231], off
	v_lshl_add_u64 v[230:231], s[54:55], 0, v[154:155]
	s_add_i32 m0, s53, 0x2000
	s_nop 0
	global_load_lds_dwordx4 v[230:231], off
	v_lshl_add_u64 v[230:231], s[30:31], 0, v[148:149]
	s_mov_b32 m0, s25
	s_nop 0
	global_load_lds_dwordx4 v[230:231], off
	s_mov_b32 m0, s37
	s_nop 0
	global_load_lds_dwordx4 v[232:233], off
	s_waitcnt vmcnt(8)
	s_waitcnt lgkmcnt(0)
	s_barrier
	s_setprio 1
	s_waitcnt lgkmcnt(0)
	v_mfma_f32_16x16x32_bf16 v[60:63], v[128:131], v[192:195], v[60:63]
	v_mfma_f32_16x16x32_bf16 v[56:59], v[136:139], v[192:195], v[56:59]
	v_mfma_f32_16x16x32_bf16 v[44:47], v[128:131], v[200:203], v[44:47]
	v_mfma_f32_16x16x32_bf16 v[40:43], v[136:139], v[200:203], v[40:43]
	v_mfma_f32_16x16x32_bf16 v[28:31], v[128:131], v[210:213], v[28:31]
	v_mfma_f32_16x16x32_bf16 v[24:27], v[136:139], v[210:213], v[24:27]
	v_mfma_f32_16x16x32_bf16 v[12:15], v[128:131], v[218:221], v[12:15]
	v_mfma_f32_16x16x32_bf16 v[8:11], v[136:139], v[218:221], v[8:11]
	v_mfma_f32_16x16x32_bf16 v[60:63], v[132:135], v[196:199], v[60:63]
	v_mfma_f32_16x16x32_bf16 v[56:59], v[140:143], v[196:199], v[56:59]
	v_mfma_f32_16x16x32_bf16 v[44:47], v[132:135], v[206:209], v[44:47]
	v_mfma_f32_16x16x32_bf16 v[40:43], v[140:143], v[206:209], v[40:43]
	v_mfma_f32_16x16x32_bf16 v[28:31], v[132:135], v[214:217], v[28:31]
	v_mfma_f32_16x16x32_bf16 v[24:27], v[140:143], v[214:217], v[24:27]
	v_mfma_f32_16x16x32_bf16 v[12:15], v[132:135], v[222:225], v[12:15]
	v_mfma_f32_16x16x32_bf16 v[8:11], v[140:143], v[222:225], v[8:11]
	s_setprio 0
	s_setprio 1
	v_mfma_f32_16x16x32_bf16 v[52:55], v[144:147], v[192:195], v[52:55]
	v_mfma_f32_16x16x32_bf16 v[48:51], v[168:171], v[192:195], v[48:51]
	v_mfma_f32_16x16x32_bf16 v[36:39], v[144:147], v[200:203], v[36:39]
	v_mfma_f32_16x16x32_bf16 v[32:35], v[168:171], v[200:203], v[32:35]
	v_mfma_f32_16x16x32_bf16 v[20:23], v[144:147], v[210:213], v[20:23]
	v_mfma_f32_16x16x32_bf16 v[16:19], v[168:171], v[210:213], v[16:19]
	v_mfma_f32_16x16x32_bf16 v[4:7], v[144:147], v[218:221], v[4:7]
	v_mfma_f32_16x16x32_bf16 v[0:3], v[168:171], v[218:221], v[0:3]
	v_mfma_f32_16x16x32_bf16 v[52:55], v[164:167], v[196:199], v[52:55]
	v_mfma_f32_16x16x32_bf16 v[48:51], v[172:175], v[196:199], v[48:51]
	v_mfma_f32_16x16x32_bf16 v[36:39], v[164:167], v[206:209], v[36:39]
	v_mfma_f32_16x16x32_bf16 v[32:35], v[172:175], v[206:209], v[32:35]
	v_mfma_f32_16x16x32_bf16 v[20:23], v[164:167], v[214:217], v[20:23]
	v_mfma_f32_16x16x32_bf16 v[16:19], v[172:175], v[214:217], v[16:19]
	v_mfma_f32_16x16x32_bf16 v[4:7], v[164:167], v[222:225], v[4:7]
	v_mfma_f32_16x16x32_bf16 v[0:3], v[172:175], v[222:225], v[0:3]
	s_setprio 0
	s_barrier
	s_add_i32 s53, 0, 0x18000
	s_add_i32 s54, 0, 0x1c000
	v_add_u32_e32 v140, s53, v187
	v_add_u32_e32 v172, s54, v187
	ds_read_b128 v[128:131], v140
	ds_read_b128 v[132:135], v140 offset:1024
	ds_read_b128 v[136:139], v140 offset:2048
	ds_read_b128 v[140:143], v140 offset:3072
	ds_read_b128 v[144:147], v172
	ds_read_b128 v[164:167], v172 offset:1024
	ds_read_b128 v[168:171], v172 offset:2048
	ds_read_b128 v[172:175], v172 offset:3072
	s_add_u32 s30, s30, 0x20000
	s_addc_u32 s31, s31, 0
	s_mov_b32 m0, s38
	v_lshl_add_u64 v[234:235], s[30:31], 0, v[148:149]
	ds_read_b128 v[192:195], v191 offset:32768
	ds_read_b128 v[196:199], v191 offset:33792
	ds_read_b128 v[200:203], v191 offset:34816
	ds_read_b128 v[206:209], v191 offset:35840
	ds_read_b128 v[210:213], v191 offset:36864
	ds_read_b128 v[214:217], v191 offset:37888
	ds_read_b128 v[218:221], v191 offset:38912
	ds_read_b128 v[222:225], v191 offset:39936
	global_load_lds_dwordx4 v[234:235], off
	v_lshl_add_u64 v[234:235], s[30:31], 0, v[152:153]
	s_mov_b32 m0, s39
	s_nop 0
	global_load_lds_dwordx4 v[234:235], off
	s_waitcnt vmcnt(8)
	s_waitcnt lgkmcnt(0)
	s_barrier
	s_setprio 1
	s_waitcnt lgkmcnt(0)
	v_mfma_f32_16x16x32_bf16 v[124:127], v[128:131], v[192:195], v[124:127]
	v_mfma_f32_16x16x32_bf16 v[120:123], v[136:139], v[192:195], v[120:123]
	v_mfma_f32_16x16x32_bf16 v[108:111], v[128:131], v[200:203], v[108:111]
	v_mfma_f32_16x16x32_bf16 v[104:107], v[136:139], v[200:203], v[104:107]
	v_mfma_f32_16x16x32_bf16 v[92:95], v[128:131], v[210:213], v[92:95]
	v_mfma_f32_16x16x32_bf16 v[88:91], v[136:139], v[210:213], v[88:91]
	v_mfma_f32_16x16x32_bf16 v[76:79], v[128:131], v[218:221], v[76:79]
	v_mfma_f32_16x16x32_bf16 v[72:75], v[136:139], v[218:221], v[72:75]
	v_mfma_f32_16x16x32_bf16 v[124:127], v[132:135], v[196:199], v[124:127]
	v_mfma_f32_16x16x32_bf16 v[120:123], v[140:143], v[196:199], v[120:123]
	v_mfma_f32_16x16x32_bf16 v[108:111], v[132:135], v[206:209], v[108:111]
	v_mfma_f32_16x16x32_bf16 v[104:107], v[140:143], v[206:209], v[104:107]
	v_mfma_f32_16x16x32_bf16 v[92:95], v[132:135], v[214:217], v[92:95]
	v_mfma_f32_16x16x32_bf16 v[88:91], v[140:143], v[214:217], v[88:91]
	v_mfma_f32_16x16x32_bf16 v[76:79], v[132:135], v[222:225], v[76:79]
	v_mfma_f32_16x16x32_bf16 v[72:75], v[140:143], v[222:225], v[72:75]
	s_setprio 0
	s_setprio 1
	v_mfma_f32_16x16x32_bf16 v[116:119], v[144:147], v[192:195], v[116:119]
	v_mfma_f32_16x16x32_bf16 v[112:115], v[168:171], v[192:195], v[112:115]
	v_mfma_f32_16x16x32_bf16 v[100:103], v[144:147], v[200:203], v[100:103]
	v_mfma_f32_16x16x32_bf16 v[96:99], v[168:171], v[200:203], v[96:99]
	v_mfma_f32_16x16x32_bf16 v[84:87], v[144:147], v[210:213], v[84:87]
	v_mfma_f32_16x16x32_bf16 v[80:83], v[168:171], v[210:213], v[80:83]
	v_mfma_f32_16x16x32_bf16 v[68:71], v[144:147], v[218:221], v[68:71]
	v_mfma_f32_16x16x32_bf16 v[64:67], v[168:171], v[218:221], v[64:67]
	v_mfma_f32_16x16x32_bf16 v[116:119], v[164:167], v[196:199], v[116:119]
	v_mfma_f32_16x16x32_bf16 v[112:115], v[172:175], v[196:199], v[112:115]
	v_mfma_f32_16x16x32_bf16 v[100:103], v[164:167], v[206:209], v[100:103]
	v_mfma_f32_16x16x32_bf16 v[96:99], v[172:175], v[206:209], v[96:99]
	v_mfma_f32_16x16x32_bf16 v[84:87], v[164:167], v[214:217], v[84:87]
	v_mfma_f32_16x16x32_bf16 v[80:83], v[172:175], v[214:217], v[80:83]
	v_mfma_f32_16x16x32_bf16 v[68:71], v[164:167], v[222:225], v[68:71]
	v_mfma_f32_16x16x32_bf16 v[64:67], v[172:175], v[222:225], v[64:67]
	s_setprio 0
	s_barrier
	s_add_i32 s30, s53, s36
	v_lshl_add_u64 v[226:227], v[226:227], 0, s[12:13]
	s_mov_b32 m0, s30
	ds_read_b128 v[192:195], v191 offset:49152
	ds_read_b128 v[196:199], v191 offset:50176
	ds_read_b128 v[200:203], v191 offset:51200
	ds_read_b128 v[206:209], v191 offset:52224
	ds_read_b128 v[210:213], v191 offset:53248
	ds_read_b128 v[214:217], v191 offset:54272
	ds_read_b128 v[218:221], v191 offset:55296
	ds_read_b128 v[222:225], v191 offset:56320
	global_load_lds_dwordx4 v[226:227], off
	s_add_i32 m0, s30, 0x2000
	s_add_u32 s28, s28, 0x20080
	v_lshl_add_u64 v[226:227], v[228:229], 0, s[12:13]
	s_addc_u32 s29, s29, 0
	s_add_i32 s30, s54, s36
	global_load_lds_dwordx4 v[226:227], off
	v_lshl_add_u64 v[226:227], s[28:29], 0, v[150:151]
	s_mov_b32 m0, s30
	s_nop 0
	global_load_lds_dwordx4 v[226:227], off
	v_lshl_add_u64 v[226:227], s[28:29], 0, v[154:155]
	s_add_i32 m0, s30, 0x2000
	s_nop 0
	global_load_lds_dwordx4 v[226:227], off
	v_lshl_add_u64 v[226:227], v[230:231], 0, s[12:13]
	s_mov_b32 m0, s41
	s_nop 0
	global_load_lds_dwordx4 v[226:227], off
	v_lshl_add_u64 v[226:227], v[232:233], 0, s[12:13]
	s_mov_b32 m0, s42
	s_nop 0
	global_load_lds_dwordx4 v[226:227], off
	s_waitcnt vmcnt(8)
	s_waitcnt lgkmcnt(0)
	s_barrier
	s_setprio 1
	s_waitcnt lgkmcnt(0)
	v_mfma_f32_16x16x32_bf16 v[60:63], v[128:131], v[192:195], v[60:63]
	v_mfma_f32_16x16x32_bf16 v[56:59], v[136:139], v[192:195], v[56:59]
	v_mfma_f32_16x16x32_bf16 v[44:47], v[128:131], v[200:203], v[44:47]
	v_mfma_f32_16x16x32_bf16 v[40:43], v[136:139], v[200:203], v[40:43]
	v_mfma_f32_16x16x32_bf16 v[28:31], v[128:131], v[210:213], v[28:31]
	v_mfma_f32_16x16x32_bf16 v[24:27], v[136:139], v[210:213], v[24:27]
	v_mfma_f32_16x16x32_bf16 v[12:15], v[128:131], v[218:221], v[12:15]
	v_mfma_f32_16x16x32_bf16 v[8:11], v[136:139], v[218:221], v[8:11]
	v_mfma_f32_16x16x32_bf16 v[60:63], v[132:135], v[196:199], v[60:63]
	v_mfma_f32_16x16x32_bf16 v[56:59], v[140:143], v[196:199], v[56:59]
	v_mfma_f32_16x16x32_bf16 v[44:47], v[132:135], v[206:209], v[44:47]
	v_mfma_f32_16x16x32_bf16 v[40:43], v[140:143], v[206:209], v[40:43]
	v_mfma_f32_16x16x32_bf16 v[28:31], v[132:135], v[214:217], v[28:31]
	v_mfma_f32_16x16x32_bf16 v[24:27], v[140:143], v[214:217], v[24:27]
	v_mfma_f32_16x16x32_bf16 v[12:15], v[132:135], v[222:225], v[12:15]
	v_mfma_f32_16x16x32_bf16 v[8:11], v[140:143], v[222:225], v[8:11]
	s_setprio 0
	s_setprio 1
	v_mfma_f32_16x16x32_bf16 v[52:55], v[144:147], v[192:195], v[52:55]
	v_mfma_f32_16x16x32_bf16 v[48:51], v[168:171], v[192:195], v[48:51]
	v_mfma_f32_16x16x32_bf16 v[36:39], v[144:147], v[200:203], v[36:39]
	v_mfma_f32_16x16x32_bf16 v[32:35], v[168:171], v[200:203], v[32:35]
	v_mfma_f32_16x16x32_bf16 v[20:23], v[144:147], v[210:213], v[20:23]
	v_mfma_f32_16x16x32_bf16 v[16:19], v[168:171], v[210:213], v[16:19]
	v_mfma_f32_16x16x32_bf16 v[4:7], v[144:147], v[218:221], v[4:7]
	v_mfma_f32_16x16x32_bf16 v[0:3], v[168:171], v[218:221], v[0:3]
	v_mfma_f32_16x16x32_bf16 v[52:55], v[164:167], v[196:199], v[52:55]
	v_mfma_f32_16x16x32_bf16 v[48:51], v[172:175], v[196:199], v[48:51]
	v_mfma_f32_16x16x32_bf16 v[36:39], v[164:167], v[206:209], v[36:39]
	v_mfma_f32_16x16x32_bf16 v[32:35], v[172:175], v[206:209], v[32:35]
	v_mfma_f32_16x16x32_bf16 v[20:23], v[164:167], v[214:217], v[20:23]
	v_mfma_f32_16x16x32_bf16 v[16:19], v[172:175], v[214:217], v[16:19]
	v_mfma_f32_16x16x32_bf16 v[4:7], v[164:167], v[222:225], v[4:7]
	v_mfma_f32_16x16x32_bf16 v[0:3], v[172:175], v[222:225], v[0:3]
	s_setprio 0
	s_barrier
	s_add_i32 s52, s52, 2
	s_add_u32 s26, s26, 0x100
	s_addc_u32 s27, s27, 0
	s_add_u32 s50, s50, 0x100
	s_addc_u32 s51, s51, 0
	s_cmp_gt_u32 s52, 5
	s_cbranch_scc0 .LBB0_893
	s_and_b64 vcc, exec, s[14:15]
	s_cbranch_vccz .LBB0_896
	s_barrier
.LBB0_896:
	v_lshl_or_b32 v128, s47, 8, v188
	v_lshl_add_u32 v166, s24, 8, v186
	v_ashrrev_i32_e32 v129, 31, v128
	v_lshlrev_b64 v[164:165], 1, v[128:129]
	v_ashrrev_i32_e32 v167, 31, v166
	v_lshl_add_u64 v[168:169], s[0:1], 0, v[164:165]
	v_lshlrev_b64 v[128:129], 10, v[166:167]
	v_or_b32_e32 v174, 16, v166
	v_lshl_add_u64 v[128:129], v[168:169], 0, v[128:129]
	v_ashrrev_i32_e32 v175, 31, v174
	global_load_dwordx4 v[192:195], v[128:129], off
	global_load_dwordx4 v[196:199], v[128:129], off offset:256
	v_lshlrev_b64 v[128:129], 10, v[174:175]
	v_or_b32_e32 v172, 32, v166
	v_lshl_add_u64 v[128:129], v[168:169], 0, v[128:129]
	v_ashrrev_i32_e32 v173, 31, v172
	global_load_dwordx4 v[200:203], v[128:129], off
	global_load_dwordx4 v[144:147], v[128:129], off offset:256
	v_lshlrev_b64 v[128:129], 10, v[172:173]
	v_or_b32_e32 v170, 48, v166
	v_lshl_add_u64 v[128:129], v[168:169], 0, v[128:129]
	v_ashrrev_i32_e32 v171, 31, v170
	global_load_dwordx4 v[140:143], v[128:129], off
	global_load_dwordx4 v[136:139], v[128:129], off offset:256
	v_lshlrev_b64 v[128:129], 10, v[170:171]
	v_lshl_add_u64 v[128:129], v[168:169], 0, v[128:129]
	global_load_dwordx4 v[132:135], v[128:129], off
	s_nop 0
	global_load_dwordx4 v[128:131], v[128:129], off offset:256
	v_mul_f32_e32 v126, 0xbfb8aa3b, v126
	v_mul_f32_e32 v127, 0xbfb8aa3b, v127
	v_exp_f32_e32 v126, v126
	v_exp_f32_e32 v127, v127
	v_mul_f32_e32 v120, 0xbfb8aa3b, v120
	v_exp_f32_e32 v167, v120
	v_add_f32_e32 v126, 1.0, v126
	v_add_f32_e32 v127, 1.0, v127
	v_mul_f32_e32 v120, 0xbfb8aa3b, v121
	v_mul_f32_e32 v124, 0xbfb8aa3b, v124
	v_mul_f32_e32 v125, 0xbfb8aa3b, v125
	v_rcp_f32_e32 v126, v126
	v_rcp_f32_e32 v127, v127
	v_exp_f32_e32 v171, v120
	v_mul_f32_e32 v122, 0xbfb8aa3b, v122
	v_mul_f32_e32 v123, 0xbfb8aa3b, v123
	v_exp_f32_e32 v124, v124
	v_exp_f32_e32 v125, v125
	v_exp_f32_e32 v122, v122
	v_exp_f32_e32 v123, v123
	s_waitcnt vmcnt(0)
	v_lshlrev_b32_e32 v206, 16, v192
	v_and_b32_e32 v207, 0xffff0000, v192
	v_lshlrev_b32_e32 v192, 16, v193
	v_and_b32_e32 v193, 0xffff0000, v193
	v_pk_mul_f32 v[120:121], v[126:127], v[192:193]
	v_add_f32_e32 v126, 1.0, v167
	v_add_f32_e32 v127, 1.0, v171
	v_mul_f32_e32 v116, 0xbfb8aa3b, v116
	v_mul_f32_e32 v117, 0xbfb8aa3b, v117
	v_add_f32_e32 v124, 1.0, v124
	v_add_f32_e32 v125, 1.0, v125
	v_rcp_f32_e32 v126, v126
	v_rcp_f32_e32 v127, v127
	v_add_f32_e32 v122, 1.0, v122
	v_add_f32_e32 v123, 1.0, v123
	v_exp_f32_e32 v116, v116
	v_exp_f32_e32 v117, v117
	v_mul_f32_e32 v118, 0xbfb8aa3b, v118
	v_mul_f32_e32 v119, 0xbfb8aa3b, v119
	v_rcp_f32_e32 v124, v124
	v_rcp_f32_e32 v125, v125
	v_rcp_f32_e32 v122, v122
	v_rcp_f32_e32 v123, v123
	v_exp_f32_e32 v118, v118
	v_exp_f32_e32 v119, v119
	v_mul_f32_e32 v112, 0xbfb8aa3b, v112
	v_mul_f32_e32 v113, 0xbfb8aa3b, v113
	v_exp_f32_e32 v112, v112
	v_exp_f32_e32 v113, v113
	v_mul_f32_e32 v114, 0xbfb8aa3b, v114
	v_mul_f32_e32 v115, 0xbfb8aa3b, v115
	v_lshlrev_b32_e32 v192, 16, v194
	v_and_b32_e32 v193, 0xffff0000, v194
	v_exp_f32_e32 v114, v114
	v_exp_f32_e32 v115, v115
	v_pk_mul_f32 v[126:127], v[126:127], v[192:193]
	v_lshlrev_b32_e32 v192, 16, v195
	v_and_b32_e32 v193, 0xffff0000, v195
	v_add_f32_e32 v116, 1.0, v116
	v_add_f32_e32 v117, 1.0, v117
	v_pk_mul_f32 v[124:125], v[124:125], v[206:207]
	v_pk_mul_f32 v[192:193], v[122:123], v[192:193]
	v_cvt_pk_bf16_f32 v123, v120, v121
	v_mov_b64_e32 v[120:121], s[4:5]
	v_rcp_f32_e32 v116, v116
	v_rcp_f32_e32 v117, v117
	v_add_f32_e32 v118, 1.0, v118
	v_add_f32_e32 v119, 1.0, v119
	v_mul_f32_e32 v108, 0xbfb8aa3b, v108
	v_mul_f32_e32 v109, 0xbfb8aa3b, v109
	v_cvt_pk_bf16_f32 v122, v124, v125
	v_cvt_pk_bf16_f32 v124, v126, v127
	v_mad_i64_i32 v[126:127], s[26:27], v166, s46, v[120:121]
	v_rcp_f32_e32 v118, v118
	v_rcp_f32_e32 v119, v119
	v_add_f32_e32 v112, 1.0, v112
	v_add_f32_e32 v113, 1.0, v113
	v_exp_f32_e32 v108, v108
	v_exp_f32_e32 v109, v109
	v_mul_f32_e32 v110, 0xbfb8aa3b, v110
	v_mul_f32_e32 v111, 0xbfb8aa3b, v111
	v_cvt_pk_bf16_f32 v125, v192, v193
	v_lshl_add_u64 v[126:127], v[126:127], 0, v[164:165]
	v_rcp_f32_e32 v112, v112
	v_rcp_f32_e32 v113, v113
	v_add_f32_e32 v114, 1.0, v114
	v_add_f32_e32 v115, 1.0, v115
	v_exp_f32_e32 v110, v110
	v_exp_f32_e32 v111, v111
	v_mul_f32_e32 v104, 0xbfb8aa3b, v104
	v_mul_f32_e32 v105, 0xbfb8aa3b, v105
	global_store_dwordx4 v[126:127], v[122:125], off offset:1024
	v_rcp_f32_e32 v114, v114
	v_rcp_f32_e32 v115, v115
	v_lshlrev_b32_e32 v122, 16, v196
	v_and_b32_e32 v123, 0xffff0000, v196
	v_exp_f32_e32 v104, v104
	v_exp_f32_e32 v105, v105
	v_mul_f32_e32 v106, 0xbfb8aa3b, v106
	v_mul_f32_e32 v107, 0xbfb8aa3b, v107
	v_pk_mul_f32 v[116:117], v[116:117], v[122:123]
	v_lshlrev_b32_e32 v122, 16, v197
	v_and_b32_e32 v123, 0xffff0000, v197
	v_exp_f32_e32 v106, v106
	v_exp_f32_e32 v107, v107
	v_pk_mul_f32 v[118:119], v[118:119], v[122:123]
	v_lshlrev_b32_e32 v122, 16, v198
	v_and_b32_e32 v123, 0xffff0000, v198
	v_add_f32_e32 v108, 1.0, v108
	v_add_f32_e32 v109, 1.0, v109
	v_pk_mul_f32 v[122:123], v[112:113], v[122:123]
	v_lshlrev_b32_e32 v112, 16, v199
	v_and_b32_e32 v113, 0xffff0000, v199
	v_rcp_f32_e32 v108, v108
	v_rcp_f32_e32 v109, v109
	v_add_f32_e32 v110, 1.0, v110
	v_add_f32_e32 v111, 1.0, v111
	v_mul_f32_e32 v100, 0xbfb8aa3b, v100
	v_mul_f32_e32 v101, 0xbfb8aa3b, v101
	v_pk_mul_f32 v[124:125], v[114:115], v[112:113]
	v_rcp_f32_e32 v110, v110
	v_rcp_f32_e32 v111, v111
	v_add_f32_e32 v104, 1.0, v104
	v_add_f32_e32 v105, 1.0, v105
	v_exp_f32_e32 v100, v100
	v_exp_f32_e32 v101, v101
	v_mul_f32_e32 v102, 0xbfb8aa3b, v102
	v_mul_f32_e32 v103, 0xbfb8aa3b, v103
	v_cvt_pk_bf16_f32 v112, v116, v117
	v_cvt_pk_bf16_f32 v113, v118, v119
	v_cvt_pk_bf16_f32 v114, v122, v123
	v_cvt_pk_bf16_f32 v115, v124, v125
	v_rcp_f32_e32 v104, v104
	v_rcp_f32_e32 v105, v105
	v_add_f32_e32 v106, 1.0, v106
	v_add_f32_e32 v107, 1.0, v107
	v_exp_f32_e32 v102, v102
	v_exp_f32_e32 v103, v103
	v_mul_f32_e32 v96, 0xbfb8aa3b, v96
	v_mul_f32_e32 v97, 0xbfb8aa3b, v97
	global_store_dwordx4 v[126:127], v[112:115], off offset:1280
	v_rcp_f32_e32 v106, v106
	v_rcp_f32_e32 v107, v107
	v_lshlrev_b32_e32 v112, 16, v200
	v_and_b32_e32 v113, 0xffff0000, v200
	v_exp_f32_e32 v96, v96
	v_exp_f32_e32 v97, v97
	v_mul_f32_e32 v98, 0xbfb8aa3b, v98
	v_mul_f32_e32 v99, 0xbfb8aa3b, v99
	v_pk_mul_f32 v[108:109], v[108:109], v[112:113]
	v_lshlrev_b32_e32 v112, 16, v201
	v_and_b32_e32 v113, 0xffff0000, v201
	v_exp_f32_e32 v98, v98
	v_exp_f32_e32 v99, v99
	v_pk_mul_f32 v[110:111], v[110:111], v[112:113]
	v_lshlrev_b32_e32 v112, 16, v202
	v_and_b32_e32 v113, 0xffff0000, v202
	v_add_f32_e32 v100, 1.0, v100
	v_add_f32_e32 v101, 1.0, v101
	v_pk_mul_f32 v[112:113], v[104:105], v[112:113]
	v_lshlrev_b32_e32 v104, 16, v203
	v_and_b32_e32 v105, 0xffff0000, v203
	v_rcp_f32_e32 v100, v100
	v_rcp_f32_e32 v101, v101
	v_add_f32_e32 v102, 1.0, v102
	v_add_f32_e32 v103, 1.0, v103
	v_mul_f32_e32 v92, 0xbfb8aa3b, v92
	v_mul_f32_e32 v93, 0xbfb8aa3b, v93
	v_pk_mul_f32 v[114:115], v[106:107], v[104:105]
	v_cvt_pk_bf16_f32 v104, v108, v109
	v_mad_i64_i32 v[108:109], s[26:27], v174, s46, v[120:121]
	v_rcp_f32_e32 v102, v102
	v_rcp_f32_e32 v103, v103
	v_add_f32_e32 v96, 1.0, v96
	v_add_f32_e32 v97, 1.0, v97
	v_exp_f32_e32 v92, v92
	v_exp_f32_e32 v93, v93
	v_mul_f32_e32 v94, 0xbfb8aa3b, v94
	v_mul_f32_e32 v95, 0xbfb8aa3b, v95
	v_cvt_pk_bf16_f32 v105, v110, v111
	v_cvt_pk_bf16_f32 v106, v112, v113
	v_cvt_pk_bf16_f32 v107, v114, v115
	v_lshl_add_u64 v[108:109], v[108:109], 0, v[164:165]
	v_rcp_f32_e32 v96, v96
	v_rcp_f32_e32 v97, v97
	v_add_f32_e32 v98, 1.0, v98
	v_add_f32_e32 v99, 1.0, v99
	v_exp_f32_e32 v94, v94
	v_exp_f32_e32 v95, v95
	v_mul_f32_e32 v88, 0xbfb8aa3b, v88
	v_mul_f32_e32 v89, 0xbfb8aa3b, v89
	global_store_dwordx4 v[108:109], v[104:107], off offset:1024
	v_rcp_f32_e32 v98, v98
	v_rcp_f32_e32 v99, v99
	v_lshlrev_b32_e32 v104, 16, v144
	v_and_b32_e32 v105, 0xffff0000, v144
	v_exp_f32_e32 v88, v88
	v_exp_f32_e32 v89, v89
	v_mul_f32_e32 v90, 0xbfb8aa3b, v90
	v_mul_f32_e32 v91, 0xbfb8aa3b, v91
	v_pk_mul_f32 v[100:101], v[100:101], v[104:105]
	v_lshlrev_b32_e32 v104, 16, v145
	v_and_b32_e32 v105, 0xffff0000, v145
	v_exp_f32_e32 v90, v90
	v_exp_f32_e32 v91, v91
	v_pk_mul_f32 v[102:103], v[102:103], v[104:105]
	v_lshlrev_b32_e32 v104, 16, v146
	v_and_b32_e32 v105, 0xffff0000, v146
	v_add_f32_e32 v92, 1.0, v92
	v_add_f32_e32 v93, 1.0, v93
	v_pk_mul_f32 v[104:105], v[96:97], v[104:105]
	v_lshlrev_b32_e32 v96, 16, v147
	v_and_b32_e32 v97, 0xffff0000, v147
	v_rcp_f32_e32 v92, v92
	v_rcp_f32_e32 v93, v93
	v_add_f32_e32 v94, 1.0, v94
	v_add_f32_e32 v95, 1.0, v95
	v_mul_f32_e32 v84, 0xbfb8aa3b, v84
	v_mul_f32_e32 v85, 0xbfb8aa3b, v85
	v_pk_mul_f32 v[106:107], v[98:99], v[96:97]
	v_rcp_f32_e32 v94, v94
	v_rcp_f32_e32 v95, v95
	v_add_f32_e32 v88, 1.0, v88
	v_add_f32_e32 v89, 1.0, v89
	v_exp_f32_e32 v84, v84
	v_exp_f32_e32 v85, v85
	v_mul_f32_e32 v86, 0xbfb8aa3b, v86
	v_mul_f32_e32 v87, 0xbfb8aa3b, v87
	v_cvt_pk_bf16_f32 v96, v100, v101
	v_cvt_pk_bf16_f32 v97, v102, v103
	v_cvt_pk_bf16_f32 v98, v104, v105
	v_cvt_pk_bf16_f32 v99, v106, v107
	v_rcp_f32_e32 v88, v88
	v_rcp_f32_e32 v89, v89
	v_add_f32_e32 v90, 1.0, v90
	v_add_f32_e32 v91, 1.0, v91
	v_exp_f32_e32 v86, v86
	v_exp_f32_e32 v87, v87
	v_mul_f32_e32 v80, 0xbfb8aa3b, v80
	v_mul_f32_e32 v81, 0xbfb8aa3b, v81
	global_store_dwordx4 v[108:109], v[96:99], off offset:1280
	v_rcp_f32_e32 v90, v90
	v_rcp_f32_e32 v91, v91
	v_lshlrev_b32_e32 v96, 16, v140
	v_and_b32_e32 v97, 0xffff0000, v140
	v_exp_f32_e32 v80, v80
	v_exp_f32_e32 v81, v81
	v_mul_f32_e32 v82, 0xbfb8aa3b, v82
	v_mul_f32_e32 v83, 0xbfb8aa3b, v83
	v_pk_mul_f32 v[92:93], v[92:93], v[96:97]
	v_lshlrev_b32_e32 v96, 16, v141
	v_and_b32_e32 v97, 0xffff0000, v141
	v_exp_f32_e32 v82, v82
	v_exp_f32_e32 v83, v83
	v_pk_mul_f32 v[94:95], v[94:95], v[96:97]
	v_lshlrev_b32_e32 v96, 16, v142
	v_and_b32_e32 v97, 0xffff0000, v142
	v_add_f32_e32 v84, 1.0, v84
	v_add_f32_e32 v85, 1.0, v85
	v_pk_mul_f32 v[96:97], v[88:89], v[96:97]
	v_lshlrev_b32_e32 v88, 16, v143
	v_and_b32_e32 v89, 0xffff0000, v143
	v_rcp_f32_e32 v84, v84
	v_rcp_f32_e32 v85, v85
	v_add_f32_e32 v86, 1.0, v86
	v_add_f32_e32 v87, 1.0, v87
	v_mul_f32_e32 v76, 0xbfb8aa3b, v76
	v_mul_f32_e32 v77, 0xbfb8aa3b, v77
	v_pk_mul_f32 v[98:99], v[90:91], v[88:89]
	v_cvt_pk_bf16_f32 v88, v92, v93
	v_mad_i64_i32 v[92:93], s[26:27], v172, s46, v[120:121]
	v_rcp_f32_e32 v86, v86
	v_rcp_f32_e32 v87, v87
	v_add_f32_e32 v80, 1.0, v80
	v_add_f32_e32 v81, 1.0, v81
	v_exp_f32_e32 v76, v76
	v_exp_f32_e32 v77, v77
	v_mul_f32_e32 v78, 0xbfb8aa3b, v78
	v_mul_f32_e32 v79, 0xbfb8aa3b, v79
	v_cvt_pk_bf16_f32 v89, v94, v95
	v_cvt_pk_bf16_f32 v90, v96, v97
	v_cvt_pk_bf16_f32 v91, v98, v99
	v_lshl_add_u64 v[92:93], v[92:93], 0, v[164:165]
	v_rcp_f32_e32 v80, v80
	v_rcp_f32_e32 v81, v81
	v_add_f32_e32 v82, 1.0, v82
	v_add_f32_e32 v83, 1.0, v83
	v_exp_f32_e32 v78, v78
	v_exp_f32_e32 v79, v79
	v_mul_f32_e32 v72, 0xbfb8aa3b, v72
	v_mul_f32_e32 v73, 0xbfb8aa3b, v73
	global_store_dwordx4 v[92:93], v[88:91], off offset:1024
	v_rcp_f32_e32 v82, v82
	v_rcp_f32_e32 v83, v83
	v_lshlrev_b32_e32 v88, 16, v136
	v_and_b32_e32 v89, 0xffff0000, v136
	v_exp_f32_e32 v72, v72
	v_exp_f32_e32 v73, v73
	v_mul_f32_e32 v74, 0xbfb8aa3b, v74
	v_mul_f32_e32 v75, 0xbfb8aa3b, v75
	v_pk_mul_f32 v[84:85], v[84:85], v[88:89]
	v_lshlrev_b32_e32 v88, 16, v137
	v_and_b32_e32 v89, 0xffff0000, v137
	v_exp_f32_e32 v74, v74
	v_exp_f32_e32 v75, v75
	v_pk_mul_f32 v[86:87], v[86:87], v[88:89]
	v_lshlrev_b32_e32 v88, 16, v138
	v_and_b32_e32 v89, 0xffff0000, v138
	v_add_f32_e32 v76, 1.0, v76
	v_add_f32_e32 v77, 1.0, v77
	v_pk_mul_f32 v[88:89], v[80:81], v[88:89]
	v_lshlrev_b32_e32 v80, 16, v139
	v_and_b32_e32 v81, 0xffff0000, v139
	v_rcp_f32_e32 v76, v76
	v_rcp_f32_e32 v77, v77
	v_add_f32_e32 v78, 1.0, v78
	v_add_f32_e32 v79, 1.0, v79
	v_mul_f32_e32 v68, 0xbfb8aa3b, v68
	v_mul_f32_e32 v69, 0xbfb8aa3b, v69
	v_pk_mul_f32 v[90:91], v[82:83], v[80:81]
	v_rcp_f32_e32 v78, v78
	v_rcp_f32_e32 v79, v79
	v_add_f32_e32 v72, 1.0, v72
	v_add_f32_e32 v73, 1.0, v73
	v_exp_f32_e32 v68, v68
	v_exp_f32_e32 v69, v69
	v_mul_f32_e32 v70, 0xbfb8aa3b, v70
	v_mul_f32_e32 v71, 0xbfb8aa3b, v71
	v_cvt_pk_bf16_f32 v80, v84, v85
	v_cvt_pk_bf16_f32 v81, v86, v87
	v_cvt_pk_bf16_f32 v82, v88, v89
	v_cvt_pk_bf16_f32 v83, v90, v91
	v_rcp_f32_e32 v72, v72
	v_rcp_f32_e32 v73, v73
	v_add_f32_e32 v74, 1.0, v74
	v_add_f32_e32 v75, 1.0, v75
	v_exp_f32_e32 v70, v70
	v_exp_f32_e32 v71, v71
	v_mul_f32_e32 v64, 0xbfb8aa3b, v64
	v_mul_f32_e32 v65, 0xbfb8aa3b, v65
	global_store_dwordx4 v[92:93], v[80:83], off offset:1280
	v_rcp_f32_e32 v74, v74
	v_rcp_f32_e32 v75, v75
	v_lshlrev_b32_e32 v80, 16, v132
	v_and_b32_e32 v81, 0xffff0000, v132
	v_exp_f32_e32 v64, v64
	v_exp_f32_e32 v65, v65
	v_mul_f32_e32 v66, 0xbfb8aa3b, v66
	v_mul_f32_e32 v67, 0xbfb8aa3b, v67
	v_pk_mul_f32 v[76:77], v[76:77], v[80:81]
	v_lshlrev_b32_e32 v80, 16, v133
	v_and_b32_e32 v81, 0xffff0000, v133
	v_exp_f32_e32 v66, v66
	v_exp_f32_e32 v67, v67
	v_pk_mul_f32 v[78:79], v[78:79], v[80:81]
	v_lshlrev_b32_e32 v80, 16, v134
	v_and_b32_e32 v81, 0xffff0000, v134
	v_add_f32_e32 v68, 1.0, v68
	v_add_f32_e32 v69, 1.0, v69
	v_pk_mul_f32 v[80:81], v[72:73], v[80:81]
	v_lshlrev_b32_e32 v72, 16, v135
	v_and_b32_e32 v73, 0xffff0000, v135
	v_rcp_f32_e32 v68, v68
	v_rcp_f32_e32 v69, v69
	v_add_f32_e32 v70, 1.0, v70
	v_add_f32_e32 v71, 1.0, v71
	v_pk_mul_f32 v[82:83], v[74:75], v[72:73]
	v_cvt_pk_bf16_f32 v72, v76, v77
	v_mad_i64_i32 v[76:77], s[26:27], v170, s46, v[120:121]
	v_rcp_f32_e32 v70, v70
	v_rcp_f32_e32 v71, v71
	v_add_f32_e32 v64, 1.0, v64
	v_add_f32_e32 v65, 1.0, v65
	v_cvt_pk_bf16_f32 v73, v78, v79
	v_cvt_pk_bf16_f32 v74, v80, v81
	v_cvt_pk_bf16_f32 v75, v82, v83
	v_lshl_add_u64 v[76:77], v[76:77], 0, v[164:165]
	v_rcp_f32_e32 v64, v64
	v_rcp_f32_e32 v65, v65
	v_add_f32_e32 v66, 1.0, v66
	v_add_f32_e32 v67, 1.0, v67
	global_store_dwordx4 v[76:77], v[72:75], off offset:1024
	v_rcp_f32_e32 v66, v66
	v_rcp_f32_e32 v67, v67
	v_lshlrev_b32_e32 v72, 16, v128
	v_and_b32_e32 v73, 0xffff0000, v128
	v_pk_mul_f32 v[68:69], v[68:69], v[72:73]
	v_lshlrev_b32_e32 v72, 16, v129
	v_and_b32_e32 v73, 0xffff0000, v129
	v_pk_mul_f32 v[70:71], v[70:71], v[72:73]
	v_lshlrev_b32_e32 v72, 16, v130
	v_and_b32_e32 v73, 0xffff0000, v130
	v_pk_mul_f32 v[72:73], v[64:65], v[72:73]
	v_lshlrev_b32_e32 v64, 16, v131
	v_and_b32_e32 v65, 0xffff0000, v131
	v_pk_mul_f32 v[74:75], v[66:67], v[64:65]
	v_cvt_pk_bf16_f32 v64, v68, v69
	v_cvt_pk_bf16_f32 v65, v70, v71
	v_cvt_pk_bf16_f32 v66, v72, v73
	v_cvt_pk_bf16_f32 v67, v74, v75
	global_store_dwordx4 v[76:77], v[64:67], off offset:1280
	v_add_u32_e32 v102, 0x80, v166
	v_ashrrev_i32_e32 v103, 31, v102
	v_lshlrev_b64 v[64:65], 10, v[102:103]
	v_add_u32_e32 v88, 0x90, v166
	v_lshl_add_u64 v[64:65], v[168:169], 0, v[64:65]
	v_ashrrev_i32_e32 v89, 31, v88
	global_load_dwordx4 v[90:93], v[64:65], off
	global_load_dwordx4 v[94:97], v[64:65], off offset:256
	v_lshlrev_b64 v[64:65], 10, v[88:89]
	v_add_u32_e32 v86, 0xa0, v166
	v_lshl_add_u64 v[64:65], v[168:169], 0, v[64:65]
	v_ashrrev_i32_e32 v87, 31, v86
	global_load_dwordx4 v[98:101], v[64:65], off
	global_load_dwordx4 v[80:83], v[64:65], off offset:256
	v_lshlrev_b64 v[64:65], 10, v[86:87]
	v_add_u32_e32 v84, 0xb0, v166
	v_lshl_add_u64 v[64:65], v[168:169], 0, v[64:65]
	v_ashrrev_i32_e32 v85, 31, v84
	global_load_dwordx4 v[76:79], v[64:65], off
	global_load_dwordx4 v[72:75], v[64:65], off offset:256
	v_lshlrev_b64 v[64:65], 10, v[84:85]
	v_lshl_add_u64 v[64:65], v[168:169], 0, v[64:65]
	global_load_dwordx4 v[68:71], v[64:65], off
	s_nop 0
	global_load_dwordx4 v[64:67], v[64:65], off offset:256
	v_mul_f32_e32 v62, 0xbfb8aa3b, v62
	v_mul_f32_e32 v63, 0xbfb8aa3b, v63
	v_mul_f32_e32 v60, 0xbfb8aa3b, v60
	v_mul_f32_e32 v61, 0xbfb8aa3b, v61
	v_exp_f32_e32 v62, v62
	v_exp_f32_e32 v63, v63
	v_mul_f32_e32 v56, 0xbfb8aa3b, v56
	v_mul_f32_e32 v57, 0xbfb8aa3b, v57
	v_exp_f32_e32 v60, v60
	v_exp_f32_e32 v61, v61
	v_exp_f32_e32 v56, v56
	v_exp_f32_e32 v57, v57
	v_mul_f32_e32 v58, 0xbfb8aa3b, v58
	v_mul_f32_e32 v59, 0xbfb8aa3b, v59
	v_exp_f32_e32 v58, v58
	v_exp_f32_e32 v59, v59
	v_add_f32_e32 v62, 1.0, v62
	v_add_f32_e32 v63, 1.0, v63
	v_mul_f32_e32 v52, 0xbfb8aa3b, v52
	v_mul_f32_e32 v53, 0xbfb8aa3b, v53
	v_add_f32_e32 v60, 1.0, v60
	v_add_f32_e32 v61, 1.0, v61
	v_rcp_f32_e32 v62, v62
	v_rcp_f32_e32 v63, v63
	v_add_f32_e32 v56, 1.0, v56
	v_add_f32_e32 v57, 1.0, v57
	v_exp_f32_e32 v52, v52
	v_exp_f32_e32 v53, v53
	v_mul_f32_e32 v54, 0xbfb8aa3b, v54
	v_mul_f32_e32 v55, 0xbfb8aa3b, v55
	v_rcp_f32_e32 v60, v60
	v_rcp_f32_e32 v61, v61
	v_rcp_f32_e32 v56, v56
	v_rcp_f32_e32 v57, v57
	v_add_f32_e32 v58, 1.0, v58
	v_add_f32_e32 v59, 1.0, v59
	v_exp_f32_e32 v54, v54
	v_exp_f32_e32 v55, v55
	v_mul_f32_e32 v48, 0xbfb8aa3b, v48
	v_mul_f32_e32 v49, 0xbfb8aa3b, v49
	v_rcp_f32_e32 v58, v58
	v_rcp_f32_e32 v59, v59
	v_exp_f32_e32 v48, v48
	v_exp_f32_e32 v49, v49
	v_mul_f32_e32 v50, 0xbfb8aa3b, v50
	v_mul_f32_e32 v51, 0xbfb8aa3b, v51
	s_waitcnt vmcnt(7)
	v_lshlrev_b32_e32 v104, 16, v90
	v_and_b32_e32 v105, 0xffff0000, v90
	v_lshlrev_b32_e32 v90, 16, v91
	v_and_b32_e32 v91, 0xffff0000, v91
	v_exp_f32_e32 v50, v50
	v_exp_f32_e32 v51, v51
	v_pk_mul_f32 v[62:63], v[62:63], v[90:91]
	v_lshlrev_b32_e32 v90, 16, v92
	v_and_b32_e32 v91, 0xffff0000, v92
	v_add_f32_e32 v52, 1.0, v52
	v_add_f32_e32 v53, 1.0, v53
	v_pk_mul_f32 v[60:61], v[60:61], v[104:105]
	v_pk_mul_f32 v[90:91], v[56:57], v[90:91]
	v_lshlrev_b32_e32 v56, 16, v93
	v_and_b32_e32 v57, 0xffff0000, v93
	v_rcp_f32_e32 v52, v52
	v_rcp_f32_e32 v53, v53
	v_add_f32_e32 v54, 1.0, v54
	v_add_f32_e32 v55, 1.0, v55
	v_mul_f32_e32 v44, 0xbfb8aa3b, v44
	v_mul_f32_e32 v45, 0xbfb8aa3b, v45
	v_pk_mul_f32 v[92:93], v[58:59], v[56:57]
	v_cvt_pk_bf16_f32 v56, v60, v61
	v_mad_i64_i32 v[60:61], s[26:27], v102, s46, v[120:121]
	v_rcp_f32_e32 v54, v54
	v_rcp_f32_e32 v55, v55
	v_add_f32_e32 v48, 1.0, v48
	v_add_f32_e32 v49, 1.0, v49
	v_exp_f32_e32 v44, v44
	v_exp_f32_e32 v45, v45
	v_mul_f32_e32 v46, 0xbfb8aa3b, v46
	v_mul_f32_e32 v47, 0xbfb8aa3b, v47
	v_cvt_pk_bf16_f32 v57, v62, v63
	v_cvt_pk_bf16_f32 v58, v90, v91
	v_cvt_pk_bf16_f32 v59, v92, v93
	v_lshl_add_u64 v[60:61], v[60:61], 0, v[164:165]
	v_rcp_f32_e32 v48, v48
	v_rcp_f32_e32 v49, v49
	v_add_f32_e32 v50, 1.0, v50
	v_add_f32_e32 v51, 1.0, v51
	v_exp_f32_e32 v46, v46
	v_exp_f32_e32 v47, v47
	v_mul_f32_e32 v40, 0xbfb8aa3b, v40
	v_mul_f32_e32 v41, 0xbfb8aa3b, v41
	global_store_dwordx4 v[60:61], v[56:59], off offset:1024
	v_rcp_f32_e32 v50, v50
	v_rcp_f32_e32 v51, v51
	s_waitcnt vmcnt(7)
	v_lshlrev_b32_e32 v56, 16, v94
	v_and_b32_e32 v57, 0xffff0000, v94
	v_exp_f32_e32 v40, v40
	v_exp_f32_e32 v41, v41
	v_mul_f32_e32 v42, 0xbfb8aa3b, v42
	v_mul_f32_e32 v43, 0xbfb8aa3b, v43
	v_pk_mul_f32 v[52:53], v[52:53], v[56:57]
	v_lshlrev_b32_e32 v56, 16, v95
	v_and_b32_e32 v57, 0xffff0000, v95
	v_exp_f32_e32 v42, v42
	v_exp_f32_e32 v43, v43
	v_pk_mul_f32 v[54:55], v[54:55], v[56:57]
	v_lshlrev_b32_e32 v56, 16, v96
	v_and_b32_e32 v57, 0xffff0000, v96
	v_add_f32_e32 v44, 1.0, v44
	v_add_f32_e32 v45, 1.0, v45
	v_pk_mul_f32 v[56:57], v[48:49], v[56:57]
	v_lshlrev_b32_e32 v48, 16, v97
	v_and_b32_e32 v49, 0xffff0000, v97
	v_rcp_f32_e32 v44, v44
	v_rcp_f32_e32 v45, v45
	v_add_f32_e32 v46, 1.0, v46
	v_add_f32_e32 v47, 1.0, v47
	v_mul_f32_e32 v36, 0xbfb8aa3b, v36
	v_mul_f32_e32 v37, 0xbfb8aa3b, v37
	v_pk_mul_f32 v[58:59], v[50:51], v[48:49]
	v_rcp_f32_e32 v46, v46
	v_rcp_f32_e32 v47, v47
	v_add_f32_e32 v40, 1.0, v40
	v_add_f32_e32 v41, 1.0, v41
	v_exp_f32_e32 v36, v36
	v_exp_f32_e32 v37, v37
	v_mul_f32_e32 v38, 0xbfb8aa3b, v38
	v_mul_f32_e32 v39, 0xbfb8aa3b, v39
	v_cvt_pk_bf16_f32 v48, v52, v53
	v_cvt_pk_bf16_f32 v49, v54, v55
	v_cvt_pk_bf16_f32 v50, v56, v57
	v_cvt_pk_bf16_f32 v51, v58, v59
	v_rcp_f32_e32 v40, v40
	v_rcp_f32_e32 v41, v41
	v_add_f32_e32 v42, 1.0, v42
	v_add_f32_e32 v43, 1.0, v43
	v_exp_f32_e32 v38, v38
	v_exp_f32_e32 v39, v39
	v_mul_f32_e32 v32, 0xbfb8aa3b, v32
	v_mul_f32_e32 v33, 0xbfb8aa3b, v33
	global_store_dwordx4 v[60:61], v[48:51], off offset:1280
	v_rcp_f32_e32 v42, v42
	v_rcp_f32_e32 v43, v43
	s_waitcnt vmcnt(7)
	v_lshlrev_b32_e32 v48, 16, v98
	v_and_b32_e32 v49, 0xffff0000, v98
	v_exp_f32_e32 v32, v32
	v_exp_f32_e32 v33, v33
	v_mul_f32_e32 v34, 0xbfb8aa3b, v34
	v_mul_f32_e32 v35, 0xbfb8aa3b, v35
	v_pk_mul_f32 v[44:45], v[44:45], v[48:49]
	v_lshlrev_b32_e32 v48, 16, v99
	v_and_b32_e32 v49, 0xffff0000, v99
	v_exp_f32_e32 v34, v34
	v_exp_f32_e32 v35, v35
	v_pk_mul_f32 v[46:47], v[46:47], v[48:49]
	v_lshlrev_b32_e32 v48, 16, v100
	v_and_b32_e32 v49, 0xffff0000, v100
	v_add_f32_e32 v36, 1.0, v36
	v_add_f32_e32 v37, 1.0, v37
	v_pk_mul_f32 v[48:49], v[40:41], v[48:49]
	v_lshlrev_b32_e32 v40, 16, v101
	v_and_b32_e32 v41, 0xffff0000, v101
	v_rcp_f32_e32 v36, v36
	v_rcp_f32_e32 v37, v37
	v_add_f32_e32 v38, 1.0, v38
	v_add_f32_e32 v39, 1.0, v39
	v_mul_f32_e32 v28, 0xbfb8aa3b, v28
	v_mul_f32_e32 v29, 0xbfb8aa3b, v29
	v_pk_mul_f32 v[50:51], v[42:43], v[40:41]
	v_cvt_pk_bf16_f32 v40, v44, v45
	v_mad_i64_i32 v[44:45], s[26:27], v88, s46, v[120:121]
	v_rcp_f32_e32 v38, v38
	v_rcp_f32_e32 v39, v39
	v_add_f32_e32 v32, 1.0, v32
	v_add_f32_e32 v33, 1.0, v33
	v_exp_f32_e32 v28, v28
	v_exp_f32_e32 v29, v29
	v_mul_f32_e32 v30, 0xbfb8aa3b, v30
	v_mul_f32_e32 v31, 0xbfb8aa3b, v31
	v_cvt_pk_bf16_f32 v41, v46, v47
	v_cvt_pk_bf16_f32 v42, v48, v49
	v_cvt_pk_bf16_f32 v43, v50, v51
	v_lshl_add_u64 v[44:45], v[44:45], 0, v[164:165]
	v_rcp_f32_e32 v32, v32
	v_rcp_f32_e32 v33, v33
	v_add_f32_e32 v34, 1.0, v34
	v_add_f32_e32 v35, 1.0, v35
	v_exp_f32_e32 v30, v30
	v_exp_f32_e32 v31, v31
	v_mul_f32_e32 v24, 0xbfb8aa3b, v24
	v_mul_f32_e32 v25, 0xbfb8aa3b, v25
	global_store_dwordx4 v[44:45], v[40:43], off offset:1024
	v_rcp_f32_e32 v34, v34
	v_rcp_f32_e32 v35, v35
	s_waitcnt vmcnt(7)
	v_lshlrev_b32_e32 v40, 16, v80
	v_and_b32_e32 v41, 0xffff0000, v80
	v_exp_f32_e32 v24, v24
	v_exp_f32_e32 v25, v25
	v_mul_f32_e32 v26, 0xbfb8aa3b, v26
	v_mul_f32_e32 v27, 0xbfb8aa3b, v27
	v_pk_mul_f32 v[36:37], v[36:37], v[40:41]
	v_lshlrev_b32_e32 v40, 16, v81
	v_and_b32_e32 v41, 0xffff0000, v81
	v_exp_f32_e32 v26, v26
	v_exp_f32_e32 v27, v27
	v_pk_mul_f32 v[38:39], v[38:39], v[40:41]
	v_lshlrev_b32_e32 v40, 16, v82
	v_and_b32_e32 v41, 0xffff0000, v82
	v_add_f32_e32 v28, 1.0, v28
	v_add_f32_e32 v29, 1.0, v29
	v_pk_mul_f32 v[40:41], v[32:33], v[40:41]
	v_lshlrev_b32_e32 v32, 16, v83
	v_and_b32_e32 v33, 0xffff0000, v83
	v_rcp_f32_e32 v28, v28
	v_rcp_f32_e32 v29, v29
	v_add_f32_e32 v30, 1.0, v30
	v_add_f32_e32 v31, 1.0, v31
	v_mul_f32_e32 v20, 0xbfb8aa3b, v20
	v_mul_f32_e32 v21, 0xbfb8aa3b, v21
	v_pk_mul_f32 v[42:43], v[34:35], v[32:33]
	v_rcp_f32_e32 v30, v30
	v_rcp_f32_e32 v31, v31
	v_add_f32_e32 v24, 1.0, v24
	v_add_f32_e32 v25, 1.0, v25
	v_exp_f32_e32 v20, v20
	v_exp_f32_e32 v21, v21
	v_mul_f32_e32 v22, 0xbfb8aa3b, v22
	v_mul_f32_e32 v23, 0xbfb8aa3b, v23
	v_cvt_pk_bf16_f32 v32, v36, v37
	v_cvt_pk_bf16_f32 v33, v38, v39
	v_cvt_pk_bf16_f32 v34, v40, v41
	v_cvt_pk_bf16_f32 v35, v42, v43
	v_rcp_f32_e32 v24, v24
	v_rcp_f32_e32 v25, v25
	v_add_f32_e32 v26, 1.0, v26
	v_add_f32_e32 v27, 1.0, v27
	v_exp_f32_e32 v22, v22
	v_exp_f32_e32 v23, v23
	v_mul_f32_e32 v16, 0xbfb8aa3b, v16
	v_mul_f32_e32 v17, 0xbfb8aa3b, v17
	global_store_dwordx4 v[44:45], v[32:35], off offset:1280
	v_rcp_f32_e32 v26, v26
	v_rcp_f32_e32 v27, v27
	s_waitcnt vmcnt(7)
	v_lshlrev_b32_e32 v32, 16, v76
	v_and_b32_e32 v33, 0xffff0000, v76
	v_exp_f32_e32 v16, v16
	v_exp_f32_e32 v17, v17
	v_mul_f32_e32 v18, 0xbfb8aa3b, v18
	v_mul_f32_e32 v19, 0xbfb8aa3b, v19
	v_pk_mul_f32 v[28:29], v[28:29], v[32:33]
	v_lshlrev_b32_e32 v32, 16, v77
	v_and_b32_e32 v33, 0xffff0000, v77
	v_exp_f32_e32 v18, v18
	v_exp_f32_e32 v19, v19
	v_pk_mul_f32 v[30:31], v[30:31], v[32:33]
	v_lshlrev_b32_e32 v32, 16, v78
	v_and_b32_e32 v33, 0xffff0000, v78
	v_add_f32_e32 v20, 1.0, v20
	v_add_f32_e32 v21, 1.0, v21
	v_pk_mul_f32 v[32:33], v[24:25], v[32:33]
	v_lshlrev_b32_e32 v24, 16, v79
	v_and_b32_e32 v25, 0xffff0000, v79
	v_rcp_f32_e32 v20, v20
	v_rcp_f32_e32 v21, v21
	v_add_f32_e32 v22, 1.0, v22
	v_add_f32_e32 v23, 1.0, v23
	v_mul_f32_e32 v12, 0xbfb8aa3b, v12
	v_mul_f32_e32 v13, 0xbfb8aa3b, v13
	v_pk_mul_f32 v[34:35], v[26:27], v[24:25]
	v_cvt_pk_bf16_f32 v24, v28, v29
	v_mad_i64_i32 v[28:29], s[26:27], v86, s46, v[120:121]
	v_rcp_f32_e32 v22, v22
	v_rcp_f32_e32 v23, v23
	v_add_f32_e32 v16, 1.0, v16
	v_add_f32_e32 v17, 1.0, v17
	v_exp_f32_e32 v12, v12
	v_exp_f32_e32 v13, v13
	v_mul_f32_e32 v14, 0xbfb8aa3b, v14
	v_mul_f32_e32 v15, 0xbfb8aa3b, v15
	v_cvt_pk_bf16_f32 v25, v30, v31
	v_cvt_pk_bf16_f32 v26, v32, v33
	v_cvt_pk_bf16_f32 v27, v34, v35
	v_lshl_add_u64 v[28:29], v[28:29], 0, v[164:165]
	v_rcp_f32_e32 v16, v16
	v_rcp_f32_e32 v17, v17
	v_add_f32_e32 v18, 1.0, v18
	v_add_f32_e32 v19, 1.0, v19
	v_exp_f32_e32 v14, v14
	v_exp_f32_e32 v15, v15
	v_mul_f32_e32 v8, 0xbfb8aa3b, v8
	v_mul_f32_e32 v9, 0xbfb8aa3b, v9
	global_store_dwordx4 v[28:29], v[24:27], off offset:1024
	v_rcp_f32_e32 v18, v18
	v_rcp_f32_e32 v19, v19
	s_waitcnt vmcnt(7)
	v_lshlrev_b32_e32 v24, 16, v72
	v_and_b32_e32 v25, 0xffff0000, v72
	v_exp_f32_e32 v8, v8
	v_exp_f32_e32 v9, v9
	v_mul_f32_e32 v10, 0xbfb8aa3b, v10
	v_mul_f32_e32 v11, 0xbfb8aa3b, v11
	v_pk_mul_f32 v[20:21], v[20:21], v[24:25]
	v_lshlrev_b32_e32 v24, 16, v73
	v_and_b32_e32 v25, 0xffff0000, v73
	v_exp_f32_e32 v10, v10
	v_exp_f32_e32 v11, v11
	v_pk_mul_f32 v[22:23], v[22:23], v[24:25]
	v_lshlrev_b32_e32 v24, 16, v74
	v_and_b32_e32 v25, 0xffff0000, v74
	v_add_f32_e32 v12, 1.0, v12
	v_add_f32_e32 v13, 1.0, v13
	v_pk_mul_f32 v[24:25], v[16:17], v[24:25]
	v_lshlrev_b32_e32 v16, 16, v75
	v_and_b32_e32 v17, 0xffff0000, v75
	v_rcp_f32_e32 v12, v12
	v_rcp_f32_e32 v13, v13
	v_add_f32_e32 v14, 1.0, v14
	v_add_f32_e32 v15, 1.0, v15
	v_mul_f32_e32 v4, 0xbfb8aa3b, v4
	v_mul_f32_e32 v5, 0xbfb8aa3b, v5
	v_pk_mul_f32 v[26:27], v[18:19], v[16:17]
	v_rcp_f32_e32 v14, v14
	v_rcp_f32_e32 v15, v15
	v_add_f32_e32 v8, 1.0, v8
	v_add_f32_e32 v9, 1.0, v9
	v_exp_f32_e32 v4, v4
	v_exp_f32_e32 v5, v5
	v_mul_f32_e32 v6, 0xbfb8aa3b, v6
	v_mul_f32_e32 v7, 0xbfb8aa3b, v7
	v_cvt_pk_bf16_f32 v16, v20, v21
	v_cvt_pk_bf16_f32 v17, v22, v23
	v_cvt_pk_bf16_f32 v18, v24, v25
	v_cvt_pk_bf16_f32 v19, v26, v27
	v_rcp_f32_e32 v8, v8
	v_rcp_f32_e32 v9, v9
	v_add_f32_e32 v10, 1.0, v10
	v_add_f32_e32 v11, 1.0, v11
	v_exp_f32_e32 v6, v6
	v_exp_f32_e32 v7, v7
	v_mul_f32_e32 v0, 0xbfb8aa3b, v0
	v_mul_f32_e32 v1, 0xbfb8aa3b, v1
	global_store_dwordx4 v[28:29], v[16:19], off offset:1280
	v_rcp_f32_e32 v10, v10
	v_rcp_f32_e32 v11, v11
	s_waitcnt vmcnt(7)
	v_lshlrev_b32_e32 v16, 16, v68
	v_and_b32_e32 v17, 0xffff0000, v68
	v_exp_f32_e32 v0, v0
	v_exp_f32_e32 v1, v1
	v_mul_f32_e32 v2, 0xbfb8aa3b, v2
	v_mul_f32_e32 v3, 0xbfb8aa3b, v3
	v_pk_mul_f32 v[12:13], v[12:13], v[16:17]
	v_lshlrev_b32_e32 v16, 16, v69
	v_and_b32_e32 v17, 0xffff0000, v69
	v_exp_f32_e32 v2, v2
	v_exp_f32_e32 v3, v3
	v_pk_mul_f32 v[14:15], v[14:15], v[16:17]
	v_lshlrev_b32_e32 v16, 16, v70
	v_and_b32_e32 v17, 0xffff0000, v70
	v_add_f32_e32 v4, 1.0, v4
	v_add_f32_e32 v5, 1.0, v5
	v_pk_mul_f32 v[16:17], v[8:9], v[16:17]
	v_lshlrev_b32_e32 v8, 16, v71
	v_and_b32_e32 v9, 0xffff0000, v71
	v_rcp_f32_e32 v4, v4
	v_rcp_f32_e32 v5, v5
	v_add_f32_e32 v6, 1.0, v6
	v_add_f32_e32 v7, 1.0, v7
	v_pk_mul_f32 v[18:19], v[10:11], v[8:9]
	v_cvt_pk_bf16_f32 v8, v12, v13
	v_mad_i64_i32 v[12:13], s[26:27], v84, s46, v[120:121]
	v_rcp_f32_e32 v6, v6
	v_rcp_f32_e32 v7, v7
	v_add_f32_e32 v0, 1.0, v0
	v_add_f32_e32 v1, 1.0, v1
	v_cvt_pk_bf16_f32 v9, v14, v15
	v_cvt_pk_bf16_f32 v10, v16, v17
	v_cvt_pk_bf16_f32 v11, v18, v19
	v_lshl_add_u64 v[12:13], v[12:13], 0, v[164:165]
	v_rcp_f32_e32 v0, v0
	v_rcp_f32_e32 v1, v1
	v_add_f32_e32 v2, 1.0, v2
	v_add_f32_e32 v3, 1.0, v3
	global_store_dwordx4 v[12:13], v[8:11], off offset:1024
	v_rcp_f32_e32 v2, v2
	v_rcp_f32_e32 v3, v3
	s_waitcnt vmcnt(7)
	v_lshlrev_b32_e32 v8, 16, v64
	v_and_b32_e32 v9, 0xffff0000, v64
	v_pk_mul_f32 v[4:5], v[4:5], v[8:9]
	v_lshlrev_b32_e32 v8, 16, v65
	v_and_b32_e32 v9, 0xffff0000, v65
	v_pk_mul_f32 v[6:7], v[6:7], v[8:9]
	v_lshlrev_b32_e32 v8, 16, v66
	v_and_b32_e32 v9, 0xffff0000, v66
	v_pk_mul_f32 v[8:9], v[0:1], v[8:9]
	v_lshlrev_b32_e32 v0, 16, v67
	v_and_b32_e32 v1, 0xffff0000, v67
	v_pk_mul_f32 v[10:11], v[2:3], v[0:1]
	v_cvt_pk_bf16_f32 v0, v4, v5
	v_cvt_pk_bf16_f32 v1, v6, v7
	v_cvt_pk_bf16_f32 v2, v8, v9
	v_cvt_pk_bf16_f32 v3, v10, v11
	global_store_dwordx4 v[12:13], v[0:3], off offset:1280
	s_andn2_b64 vcc, exec, s[2:3]
	s_mov_b64 s[2:3], -1
	s_cbranch_vccnz .LBB0_885
	s_andn2_b64 vcc, exec, s[10:11]
	s_cbranch_vccnz .LBB0_884
	v_writelane_b32 v255, 1, 53
	s_branch .LBB0_884

.LBB0_912:
	s_add_u32 s26, s26, 0x60080
	s_addc_u32 s27, s27, 0
	s_add_u32 s55, s28, 0x100
	v_mov_b32_e32 v0, 0
	s_addc_u32 s56, s29, 0
	s_mov_b32 s57, -2
	v_mov_b32_e32 v1, v0
	v_mov_b32_e32 v2, v0
	v_mov_b32_e32 v3, v0
	v_mov_b32_e32 v4, v0
	v_mov_b32_e32 v5, v0
	v_mov_b32_e32 v6, v0
	v_mov_b32_e32 v7, v0
	v_mov_b32_e32 v12, v0
	v_mov_b32_e32 v13, v0
	v_mov_b32_e32 v14, v0
	v_mov_b32_e32 v15, v0
	v_mov_b32_e32 v20, v0
	v_mov_b32_e32 v21, v0
	v_mov_b32_e32 v22, v0
	v_mov_b32_e32 v23, v0
	v_mov_b32_e32 v28, v0
	v_mov_b32_e32 v29, v0
	v_mov_b32_e32 v30, v0
	v_mov_b32_e32 v31, v0
	v_mov_b32_e32 v36, v0
	v_mov_b32_e32 v37, v0
	v_mov_b32_e32 v38, v0
	v_mov_b32_e32 v39, v0
	v_mov_b32_e32 v44, v0
	v_mov_b32_e32 v45, v0
	v_mov_b32_e32 v46, v0
	v_mov_b32_e32 v47, v0
	v_mov_b32_e32 v52, v0
	v_mov_b32_e32 v53, v0
	v_mov_b32_e32 v54, v0
	v_mov_b32_e32 v55, v0
	v_mov_b32_e32 v8, v0
	v_mov_b32_e32 v9, v0
	v_mov_b32_e32 v10, v0
	v_mov_b32_e32 v11, v0
	v_mov_b32_e32 v16, v0
	v_mov_b32_e32 v17, v0
	v_mov_b32_e32 v18, v0
	v_mov_b32_e32 v19, v0
	v_mov_b32_e32 v24, v0
	v_mov_b32_e32 v25, v0
	v_mov_b32_e32 v26, v0
	v_mov_b32_e32 v27, v0
	v_mov_b32_e32 v32, v0
	v_mov_b32_e32 v33, v0
	v_mov_b32_e32 v34, v0
	v_mov_b32_e32 v35, v0
	v_mov_b32_e32 v40, v0
	v_mov_b32_e32 v41, v0
	v_mov_b32_e32 v42, v0
	v_mov_b32_e32 v43, v0
	v_mov_b32_e32 v48, v0
	v_mov_b32_e32 v49, v0
	v_mov_b32_e32 v50, v0
	v_mov_b32_e32 v51, v0
	v_mov_b32_e32 v56, v0
	v_mov_b32_e32 v57, v0
	v_mov_b32_e32 v58, v0
	v_mov_b32_e32 v59, v0
	v_mov_b32_e32 v60, v0
	v_mov_b32_e32 v61, v0
	v_mov_b32_e32 v62, v0
	v_mov_b32_e32 v63, v0
	v_mov_b32_e32 v64, v0
	v_mov_b32_e32 v65, v0
	v_mov_b32_e32 v66, v0
	v_mov_b32_e32 v67, v0
	v_mov_b32_e32 v68, v0
	v_mov_b32_e32 v69, v0
	v_mov_b32_e32 v70, v0
	v_mov_b32_e32 v71, v0
	v_mov_b32_e32 v76, v0
	v_mov_b32_e32 v77, v0
	v_mov_b32_e32 v78, v0
	v_mov_b32_e32 v79, v0
	v_mov_b32_e32 v84, v0
	v_mov_b32_e32 v85, v0
	v_mov_b32_e32 v86, v0
	v_mov_b32_e32 v87, v0
	v_mov_b32_e32 v92, v0
	v_mov_b32_e32 v93, v0
	v_mov_b32_e32 v94, v0
	v_mov_b32_e32 v95, v0
	v_mov_b32_e32 v100, v0
	v_mov_b32_e32 v101, v0
	v_mov_b32_e32 v102, v0
	v_mov_b32_e32 v103, v0
	v_mov_b32_e32 v108, v0
	v_mov_b32_e32 v109, v0
	v_mov_b32_e32 v110, v0
	v_mov_b32_e32 v111, v0
	v_mov_b32_e32 v116, v0
	v_mov_b32_e32 v117, v0
	v_mov_b32_e32 v118, v0
	v_mov_b32_e32 v119, v0
	v_mov_b32_e32 v72, v0
	v_mov_b32_e32 v73, v0
	v_mov_b32_e32 v74, v0
	v_mov_b32_e32 v75, v0
	v_mov_b32_e32 v80, v0
	v_mov_b32_e32 v81, v0
	v_mov_b32_e32 v82, v0
	v_mov_b32_e32 v83, v0
	v_mov_b32_e32 v88, v0
	v_mov_b32_e32 v89, v0
	v_mov_b32_e32 v90, v0
	v_mov_b32_e32 v91, v0
	v_mov_b32_e32 v96, v0
	v_mov_b32_e32 v97, v0
	v_mov_b32_e32 v98, v0
	v_mov_b32_e32 v99, v0
	v_mov_b32_e32 v104, v0
	v_mov_b32_e32 v105, v0
	v_mov_b32_e32 v106, v0
	v_mov_b32_e32 v107, v0
	v_mov_b32_e32 v112, v0
	v_mov_b32_e32 v113, v0
	v_mov_b32_e32 v114, v0
	v_mov_b32_e32 v115, v0
	v_mov_b32_e32 v120, v0
	v_mov_b32_e32 v121, v0
	v_mov_b32_e32 v122, v0
	v_mov_b32_e32 v123, v0
	v_mov_b32_e32 v124, v0
	v_mov_b32_e32 v125, v0
	v_mov_b32_e32 v126, v0
	v_mov_b32_e32 v127, v0
	v_readlane_b32 s97, v255, 53
	s_nop 3
	s_cmp_eq_u32 s97, 1
	s_cbranch_scc0 .Llsb_skip_6
	v_writelane_b32 v255, 0, 53
	s_barrier
.Llsb_skip_6:
.LBB0_913:
	ds_read_b128 v[136:139], v154
	ds_read_b128 v[140:143], v154 offset:1024
	ds_read_b128 v[144:147], v154 offset:2048
	ds_read_b128 v[158:161], v154 offset:3072
	ds_read_b128 v[162:165], v155
	ds_read_b128 v[166:169], v155 offset:1024
	ds_read_b128 v[170:173], v155 offset:2048
	ds_read_b128 v[180:183], v155 offset:3072
	s_add_u32 s28, s26, 0xfffa0080
	s_addc_u32 s29, s27, -1
	s_cmp_eq_u32 s57, 4
	s_cselect_b32 s31, s23, s29
	s_cselect_b32 s30, s22, s28
	s_cselect_b32 s29, s25, s56
	s_cselect_b32 s28, s24, s55
	v_lshl_add_u64 v[148:149], s[26:27], 0, v[132:133]
	s_add_i32 m0, s37, 0xc000
	ds_read_b128 v[184:187], v156
	ds_read_b128 v[188:191], v156 offset:1024
	ds_read_b128 v[192:195], v156 offset:2048
	ds_read_b128 v[196:199], v156 offset:3072
	ds_read_b128 v[200:203], v156 offset:4096
	ds_read_b128 v[206:209], v156 offset:5120
	ds_read_b128 v[210:213], v156 offset:6144
	ds_read_b128 v[214:217], v156 offset:7168
	global_load_lds_dwordx4 v[148:149], off
	v_lshl_add_u64 v[148:149], s[26:27], 0, v[134:135]
	s_add_i32 m0, s37, 0xe000
	s_nop 0
	global_load_lds_dwordx4 v[148:149], off
	s_waitcnt vmcnt(8)
	s_waitcnt lgkmcnt(0)
	s_barrier
	s_setprio 1
	s_waitcnt lgkmcnt(0)
	v_mfma_f32_16x16x32_bf16 v[124:127], v[136:139], v[184:187], v[124:127]
	v_mfma_f32_16x16x32_bf16 v[120:123], v[144:147], v[184:187], v[120:123]
	v_mfma_f32_16x16x32_bf16 v[112:115], v[136:139], v[192:195], v[112:115]
	v_mfma_f32_16x16x32_bf16 v[104:107], v[144:147], v[192:195], v[104:107]
	v_mfma_f32_16x16x32_bf16 v[96:99], v[136:139], v[200:203], v[96:99]
	v_mfma_f32_16x16x32_bf16 v[88:91], v[144:147], v[200:203], v[88:91]
	v_mfma_f32_16x16x32_bf16 v[80:83], v[136:139], v[210:213], v[80:83]
	v_mfma_f32_16x16x32_bf16 v[72:75], v[144:147], v[210:213], v[72:75]
	v_mfma_f32_16x16x32_bf16 v[124:127], v[140:143], v[188:191], v[124:127]
	v_mfma_f32_16x16x32_bf16 v[120:123], v[158:161], v[188:191], v[120:123]
	v_mfma_f32_16x16x32_bf16 v[112:115], v[140:143], v[196:199], v[112:115]
	v_mfma_f32_16x16x32_bf16 v[104:107], v[158:161], v[196:199], v[104:107]
	v_mfma_f32_16x16x32_bf16 v[96:99], v[140:143], v[206:209], v[96:99]
	v_mfma_f32_16x16x32_bf16 v[88:91], v[158:161], v[206:209], v[88:91]
	v_mfma_f32_16x16x32_bf16 v[80:83], v[140:143], v[214:217], v[80:83]
	v_mfma_f32_16x16x32_bf16 v[72:75], v[158:161], v[214:217], v[72:75]
	s_setprio 0
	s_setprio 1
	v_mfma_f32_16x16x32_bf16 v[116:119], v[162:165], v[184:187], v[116:119]
	v_mfma_f32_16x16x32_bf16 v[108:111], v[170:173], v[184:187], v[108:111]
	v_mfma_f32_16x16x32_bf16 v[100:103], v[162:165], v[192:195], v[100:103]
	v_mfma_f32_16x16x32_bf16 v[92:95], v[170:173], v[192:195], v[92:95]
	v_mfma_f32_16x16x32_bf16 v[84:87], v[162:165], v[200:203], v[84:87]
	v_mfma_f32_16x16x32_bf16 v[76:79], v[170:173], v[200:203], v[76:79]
	v_mfma_f32_16x16x32_bf16 v[68:71], v[162:165], v[210:213], v[68:71]
	v_mfma_f32_16x16x32_bf16 v[64:67], v[170:173], v[210:213], v[64:67]
	v_mfma_f32_16x16x32_bf16 v[116:119], v[166:169], v[188:191], v[116:119]
	v_mfma_f32_16x16x32_bf16 v[108:111], v[180:183], v[188:191], v[108:111]
	v_mfma_f32_16x16x32_bf16 v[100:103], v[166:169], v[196:199], v[100:103]
	v_mfma_f32_16x16x32_bf16 v[92:95], v[180:183], v[196:199], v[92:95]
	v_mfma_f32_16x16x32_bf16 v[84:87], v[166:169], v[206:209], v[84:87]
	v_mfma_f32_16x16x32_bf16 v[76:79], v[180:183], v[206:209], v[76:79]
	v_mfma_f32_16x16x32_bf16 v[68:71], v[166:169], v[214:217], v[68:71]
	v_mfma_f32_16x16x32_bf16 v[64:67], v[180:183], v[214:217], v[64:67]
	s_setprio 0
	s_barrier
	s_add_i32 s58, s44, s36
	v_lshl_add_u64 v[148:149], s[28:29], 0, v[130:131]
	s_mov_b32 m0, s58
	ds_read_b128 v[184:187], v156 offset:16384
	ds_read_b128 v[188:191], v156 offset:17408
	ds_read_b128 v[192:195], v156 offset:18432
	ds_read_b128 v[196:199], v156 offset:19456
	ds_read_b128 v[200:203], v156 offset:20480
	ds_read_b128 v[206:209], v156 offset:21504
	ds_read_b128 v[210:213], v156 offset:22528
	ds_read_b128 v[214:217], v156 offset:23552
	global_load_lds_dwordx4 v[148:149], off
	s_add_i32 m0, s58, 0x2000
	s_add_u32 s58, s28, 0x60000
	v_lshl_add_u64 v[174:175], s[28:29], 0, v[128:129]
	s_addc_u32 s59, s29, 0
	s_add_i32 s60, s45, s36
	global_load_lds_dwordx4 v[174:175], off
	v_lshl_add_u64 v[218:219], s[58:59], 0, v[130:131]
	s_mov_b32 m0, s60
	v_lshl_add_u64 v[220:221], s[30:31], 0, v[128:129]
	global_load_lds_dwordx4 v[218:219], off
	v_lshl_add_u64 v[218:219], s[58:59], 0, v[128:129]
	s_add_i32 m0, s60, 0x2000
	s_nop 0
	global_load_lds_dwordx4 v[218:219], off
	v_lshl_add_u64 v[218:219], s[30:31], 0, v[130:131]
	s_mov_b32 m0, s37
	s_nop 0
	global_load_lds_dwordx4 v[218:219], off
	s_mov_b32 m0, s38
	s_nop 0
	global_load_lds_dwordx4 v[220:221], off
	s_waitcnt vmcnt(8)
	s_waitcnt lgkmcnt(0)
	s_barrier
	s_setprio 1
	s_waitcnt lgkmcnt(0)
	v_mfma_f32_16x16x32_bf16 v[60:63], v[136:139], v[184:187], v[60:63]
	v_mfma_f32_16x16x32_bf16 v[56:59], v[144:147], v[184:187], v[56:59]
	v_mfma_f32_16x16x32_bf16 v[48:51], v[136:139], v[192:195], v[48:51]
	v_mfma_f32_16x16x32_bf16 v[40:43], v[144:147], v[192:195], v[40:43]
	v_mfma_f32_16x16x32_bf16 v[32:35], v[136:139], v[200:203], v[32:35]
	v_mfma_f32_16x16x32_bf16 v[24:27], v[144:147], v[200:203], v[24:27]
	v_mfma_f32_16x16x32_bf16 v[16:19], v[136:139], v[210:213], v[16:19]
	v_mfma_f32_16x16x32_bf16 v[8:11], v[144:147], v[210:213], v[8:11]
	v_mfma_f32_16x16x32_bf16 v[60:63], v[140:143], v[188:191], v[60:63]
	v_mfma_f32_16x16x32_bf16 v[56:59], v[158:161], v[188:191], v[56:59]
	v_mfma_f32_16x16x32_bf16 v[48:51], v[140:143], v[196:199], v[48:51]
	v_mfma_f32_16x16x32_bf16 v[40:43], v[158:161], v[196:199], v[40:43]
	v_mfma_f32_16x16x32_bf16 v[32:35], v[140:143], v[206:209], v[32:35]
	v_mfma_f32_16x16x32_bf16 v[24:27], v[158:161], v[206:209], v[24:27]
	v_mfma_f32_16x16x32_bf16 v[16:19], v[140:143], v[214:217], v[16:19]
	v_mfma_f32_16x16x32_bf16 v[8:11], v[158:161], v[214:217], v[8:11]
	s_setprio 0
	s_setprio 1
	v_mfma_f32_16x16x32_bf16 v[52:55], v[162:165], v[184:187], v[52:55]
	v_mfma_f32_16x16x32_bf16 v[44:47], v[170:173], v[184:187], v[44:47]
	v_mfma_f32_16x16x32_bf16 v[36:39], v[162:165], v[192:195], v[36:39]
	v_mfma_f32_16x16x32_bf16 v[28:31], v[170:173], v[192:195], v[28:31]
	v_mfma_f32_16x16x32_bf16 v[20:23], v[162:165], v[200:203], v[20:23]
	v_mfma_f32_16x16x32_bf16 v[12:15], v[170:173], v[200:203], v[12:15]
	v_mfma_f32_16x16x32_bf16 v[4:7], v[162:165], v[210:213], v[4:7]
	v_mfma_f32_16x16x32_bf16 v[0:3], v[170:173], v[210:213], v[0:3]
	v_mfma_f32_16x16x32_bf16 v[52:55], v[166:169], v[188:191], v[52:55]
	v_mfma_f32_16x16x32_bf16 v[44:47], v[180:183], v[188:191], v[44:47]
	v_mfma_f32_16x16x32_bf16 v[36:39], v[166:169], v[196:199], v[36:39]
	v_mfma_f32_16x16x32_bf16 v[28:31], v[180:183], v[196:199], v[28:31]
	v_mfma_f32_16x16x32_bf16 v[20:23], v[166:169], v[206:209], v[20:23]
	v_mfma_f32_16x16x32_bf16 v[12:15], v[180:183], v[206:209], v[12:15]
	v_mfma_f32_16x16x32_bf16 v[4:7], v[166:169], v[214:217], v[4:7]
	v_mfma_f32_16x16x32_bf16 v[0:3], v[180:183], v[214:217], v[0:3]
	s_setprio 0
	s_barrier
	s_add_i32 s58, 0, 0x18000
	v_add_u32_e32 v157, s58, v152
	s_add_i32 s59, 0, 0x1c000
	ds_read_b128 v[136:139], v157
	ds_read_b128 v[140:143], v157 offset:1024
	ds_read_b128 v[144:147], v157 offset:2048
	ds_read_b128 v[158:161], v157 offset:3072
	v_add_u32_e32 v157, s59, v152
	ds_read_b128 v[162:165], v157
	ds_read_b128 v[166:169], v157 offset:1024
	ds_read_b128 v[170:173], v157 offset:2048
	ds_read_b128 v[180:183], v157 offset:3072
	s_add_u32 s30, s30, 0x60000
	s_addc_u32 s31, s31, 0
	s_mov_b32 m0, s39
	v_lshl_add_u64 v[222:223], s[30:31], 0, v[130:131]
	ds_read_b128 v[184:187], v156 offset:32768
	ds_read_b128 v[188:191], v156 offset:33792
	ds_read_b128 v[192:195], v156 offset:34816
	ds_read_b128 v[196:199], v156 offset:35840
	ds_read_b128 v[200:203], v156 offset:36864
	ds_read_b128 v[206:209], v156 offset:37888
	ds_read_b128 v[210:213], v156 offset:38912
	ds_read_b128 v[214:217], v156 offset:39936
	global_load_lds_dwordx4 v[222:223], off
	v_lshl_add_u64 v[222:223], s[30:31], 0, v[128:129]
	s_mov_b32 m0, s40
	s_nop 0
	global_load_lds_dwordx4 v[222:223], off
	s_waitcnt vmcnt(8)
	s_waitcnt lgkmcnt(0)
	s_barrier
	s_setprio 1
	s_waitcnt lgkmcnt(0)
	v_mfma_f32_16x16x32_bf16 v[124:127], v[136:139], v[184:187], v[124:127]
	v_mfma_f32_16x16x32_bf16 v[120:123], v[144:147], v[184:187], v[120:123]
	v_mfma_f32_16x16x32_bf16 v[112:115], v[136:139], v[192:195], v[112:115]
	v_mfma_f32_16x16x32_bf16 v[104:107], v[144:147], v[192:195], v[104:107]
	v_mfma_f32_16x16x32_bf16 v[96:99], v[136:139], v[200:203], v[96:99]
	v_mfma_f32_16x16x32_bf16 v[88:91], v[144:147], v[200:203], v[88:91]
	v_mfma_f32_16x16x32_bf16 v[80:83], v[136:139], v[210:213], v[80:83]
	v_mfma_f32_16x16x32_bf16 v[72:75], v[144:147], v[210:213], v[72:75]
	v_mfma_f32_16x16x32_bf16 v[124:127], v[140:143], v[188:191], v[124:127]
	v_mfma_f32_16x16x32_bf16 v[120:123], v[158:161], v[188:191], v[120:123]
	v_mfma_f32_16x16x32_bf16 v[112:115], v[140:143], v[196:199], v[112:115]
	v_mfma_f32_16x16x32_bf16 v[104:107], v[158:161], v[196:199], v[104:107]
	v_mfma_f32_16x16x32_bf16 v[96:99], v[140:143], v[206:209], v[96:99]
	v_mfma_f32_16x16x32_bf16 v[88:91], v[158:161], v[206:209], v[88:91]
	v_mfma_f32_16x16x32_bf16 v[80:83], v[140:143], v[214:217], v[80:83]
	v_mfma_f32_16x16x32_bf16 v[72:75], v[158:161], v[214:217], v[72:75]
	s_setprio 0
	s_setprio 1
	v_mfma_f32_16x16x32_bf16 v[116:119], v[162:165], v[184:187], v[116:119]
	v_mfma_f32_16x16x32_bf16 v[108:111], v[170:173], v[184:187], v[108:111]
	v_mfma_f32_16x16x32_bf16 v[100:103], v[162:165], v[192:195], v[100:103]
	v_mfma_f32_16x16x32_bf16 v[92:95], v[170:173], v[192:195], v[92:95]
	v_mfma_f32_16x16x32_bf16 v[84:87], v[162:165], v[200:203], v[84:87]
	v_mfma_f32_16x16x32_bf16 v[76:79], v[170:173], v[200:203], v[76:79]
	v_mfma_f32_16x16x32_bf16 v[68:71], v[162:165], v[210:213], v[68:71]
	v_mfma_f32_16x16x32_bf16 v[64:67], v[170:173], v[210:213], v[64:67]
	v_mfma_f32_16x16x32_bf16 v[116:119], v[166:169], v[188:191], v[116:119]
	v_mfma_f32_16x16x32_bf16 v[108:111], v[180:183], v[188:191], v[108:111]
	v_mfma_f32_16x16x32_bf16 v[100:103], v[166:169], v[196:199], v[100:103]
	v_mfma_f32_16x16x32_bf16 v[92:95], v[180:183], v[196:199], v[92:95]
	v_mfma_f32_16x16x32_bf16 v[84:87], v[166:169], v[206:209], v[84:87]
	v_mfma_f32_16x16x32_bf16 v[76:79], v[180:183], v[206:209], v[76:79]
	v_mfma_f32_16x16x32_bf16 v[68:71], v[166:169], v[214:217], v[68:71]
	v_mfma_f32_16x16x32_bf16 v[64:67], v[180:183], v[214:217], v[64:67]
	s_setprio 0
	s_barrier
	s_add_i32 s30, s58, s36
	v_lshl_add_u64 v[148:149], v[148:149], 0, s[16:17]
	s_mov_b32 m0, s30
	ds_read_b128 v[184:187], v156 offset:49152
	ds_read_b128 v[188:191], v156 offset:50176
	ds_read_b128 v[192:195], v156 offset:51200
	ds_read_b128 v[196:199], v156 offset:52224
	ds_read_b128 v[200:203], v156 offset:53248
	ds_read_b128 v[206:209], v156 offset:54272
	ds_read_b128 v[210:213], v156 offset:55296
	ds_read_b128 v[214:217], v156 offset:56320
	global_load_lds_dwordx4 v[148:149], off
	s_add_i32 m0, s30, 0x2000
	s_add_u32 s28, s28, 0x60080
	v_lshl_add_u64 v[148:149], v[174:175], 0, s[16:17]
	s_addc_u32 s29, s29, 0
	s_add_i32 s30, s59, s36
	global_load_lds_dwordx4 v[148:149], off
	v_lshl_add_u64 v[148:149], s[28:29], 0, v[130:131]
	s_mov_b32 m0, s30
	s_nop 0
	global_load_lds_dwordx4 v[148:149], off
	v_lshl_add_u64 v[148:149], s[28:29], 0, v[128:129]
	s_add_i32 m0, s30, 0x2000
	s_nop 0
	global_load_lds_dwordx4 v[148:149], off
	v_lshl_add_u64 v[148:149], v[218:219], 0, s[16:17]
	s_mov_b32 m0, s41
	s_nop 0
	global_load_lds_dwordx4 v[148:149], off
	v_lshl_add_u64 v[148:149], v[220:221], 0, s[16:17]
	s_mov_b32 m0, s42
	s_nop 0
	global_load_lds_dwordx4 v[148:149], off
	s_waitcnt vmcnt(8)
	s_waitcnt lgkmcnt(0)
	s_barrier
	s_setprio 1
	s_waitcnt lgkmcnt(0)
	v_mfma_f32_16x16x32_bf16 v[60:63], v[136:139], v[184:187], v[60:63]
	v_mfma_f32_16x16x32_bf16 v[56:59], v[144:147], v[184:187], v[56:59]
	v_mfma_f32_16x16x32_bf16 v[48:51], v[136:139], v[192:195], v[48:51]
	v_mfma_f32_16x16x32_bf16 v[40:43], v[144:147], v[192:195], v[40:43]
	v_mfma_f32_16x16x32_bf16 v[32:35], v[136:139], v[200:203], v[32:35]
	v_mfma_f32_16x16x32_bf16 v[24:27], v[144:147], v[200:203], v[24:27]
	v_mfma_f32_16x16x32_bf16 v[16:19], v[136:139], v[210:213], v[16:19]
	v_mfma_f32_16x16x32_bf16 v[8:11], v[144:147], v[210:213], v[8:11]
	v_mfma_f32_16x16x32_bf16 v[60:63], v[140:143], v[188:191], v[60:63]
	v_mfma_f32_16x16x32_bf16 v[56:59], v[158:161], v[188:191], v[56:59]
	v_mfma_f32_16x16x32_bf16 v[48:51], v[140:143], v[196:199], v[48:51]
	v_mfma_f32_16x16x32_bf16 v[40:43], v[158:161], v[196:199], v[40:43]
	v_mfma_f32_16x16x32_bf16 v[32:35], v[140:143], v[206:209], v[32:35]
	v_mfma_f32_16x16x32_bf16 v[24:27], v[158:161], v[206:209], v[24:27]
	v_mfma_f32_16x16x32_bf16 v[16:19], v[140:143], v[214:217], v[16:19]
	v_mfma_f32_16x16x32_bf16 v[8:11], v[158:161], v[214:217], v[8:11]
	s_setprio 0
	s_setprio 1
	v_mfma_f32_16x16x32_bf16 v[52:55], v[162:165], v[184:187], v[52:55]
	v_mfma_f32_16x16x32_bf16 v[44:47], v[170:173], v[184:187], v[44:47]
	v_mfma_f32_16x16x32_bf16 v[36:39], v[162:165], v[192:195], v[36:39]
	v_mfma_f32_16x16x32_bf16 v[28:31], v[170:173], v[192:195], v[28:31]
	v_mfma_f32_16x16x32_bf16 v[20:23], v[162:165], v[200:203], v[20:23]
	v_mfma_f32_16x16x32_bf16 v[12:15], v[170:173], v[200:203], v[12:15]
	v_mfma_f32_16x16x32_bf16 v[4:7], v[162:165], v[210:213], v[4:7]
	v_mfma_f32_16x16x32_bf16 v[0:3], v[170:173], v[210:213], v[0:3]
	v_mfma_f32_16x16x32_bf16 v[52:55], v[166:169], v[188:191], v[52:55]
	v_mfma_f32_16x16x32_bf16 v[44:47], v[180:183], v[188:191], v[44:47]
	v_mfma_f32_16x16x32_bf16 v[36:39], v[166:169], v[196:199], v[36:39]
	v_mfma_f32_16x16x32_bf16 v[28:31], v[180:183], v[196:199], v[28:31]
	v_mfma_f32_16x16x32_bf16 v[20:23], v[166:169], v[206:209], v[20:23]
	v_mfma_f32_16x16x32_bf16 v[12:15], v[180:183], v[206:209], v[12:15]
	v_mfma_f32_16x16x32_bf16 v[4:7], v[166:169], v[214:217], v[4:7]
	v_mfma_f32_16x16x32_bf16 v[0:3], v[180:183], v[214:217], v[0:3]
	s_setprio 0
	s_barrier
	s_add_i32 s57, s57, 2
	s_add_u32 s26, s26, 0x100
	s_addc_u32 s27, s27, 0
	s_add_u32 s55, s55, 0x100
	s_addc_u32 s56, s56, 0
	s_cmp_gt_u32 s57, 5
	s_cbranch_scc0 .LBB0_913
	s_and_b64 vcc, exec, s[18:19]
	s_cbranch_vccz .LBB0_916
	s_barrier
.LBB0_916:
	s_ashr_i32 s26, s54, 31
	s_lshr_b32 s26, s26, 22
	s_add_i32 s30, s54, s26
	s_and_b32 s26, s30, 0xfffffc00
	v_lshl_add_u32 v138, s53, 8, v151
	v_lshl_or_b32 v136, s52, 8, v153
	s_ashr_i32 s27, s26, 31
	v_mov_b64_e32 v[140:141], s[0:1]
	v_ashrrev_i32_e32 v137, 31, v136
	v_mad_i64_i32 v[142:143], s[28:29], v138, s46, v[140:141]
	s_lshl_b64 s[26:27], s[26:27], 1
	v_lshl_add_u64 v[144:145], v[142:143], 0, s[26:27]
	v_lshlrev_b64 v[142:143], 1, v[136:137]
	v_lshl_add_u64 v[144:145], v[144:145], 0, v[142:143]
	v_or_b32_e32 v139, 16, v138
	global_load_dwordx2 v[158:159], v[144:145], off offset:3584
	global_load_dwordx2 v[160:161], v[144:145], off offset:3616
	global_load_dwordx2 v[162:163], v[144:145], off offset:3840
	global_load_dwordx2 v[164:165], v[144:145], off offset:3872
	v_mad_i64_i32 v[144:145], s[28:29], v139, s46, v[140:141]
	v_lshl_add_u64 v[144:145], v[144:145], 0, s[26:27]
	v_lshl_add_u64 v[144:145], v[144:145], 0, v[142:143]
	v_or_b32_e32 v139, 32, v138
	global_load_dwordx2 v[166:167], v[144:145], off offset:3584
	global_load_dwordx2 v[168:169], v[144:145], off offset:3616
	global_load_dwordx2 v[170:171], v[144:145], off offset:3840
	global_load_dwordx2 v[172:173], v[144:145], off offset:3872
	v_mad_i64_i32 v[144:145], s[28:29], v139, s46, v[140:141]
	v_lshl_add_u64 v[144:145], v[144:145], 0, s[26:27]
	v_lshl_add_u64 v[144:145], v[144:145], 0, v[142:143]
	v_or_b32_e32 v139, 48, v138
	global_load_dwordx2 v[174:175], v[144:145], off offset:3584
	global_load_dwordx2 v[180:181], v[144:145], off offset:3616
	global_load_dwordx2 v[182:183], v[144:145], off offset:3840
	global_load_dwordx2 v[184:185], v[144:145], off offset:3872
	v_mad_i64_i32 v[144:145], s[28:29], v139, s46, v[140:141]
	v_lshl_add_u64 v[144:145], v[144:145], 0, s[26:27]
	v_lshl_add_u64 v[144:145], v[144:145], 0, v[142:143]
	global_load_dwordx2 v[186:187], v[144:145], off offset:3584
	global_load_dwordx2 v[148:149], v[144:145], off offset:3616
	global_load_dwordx2 v[146:147], v[144:145], off offset:3840
	s_nop 0
	global_load_dwordx2 v[144:145], v[144:145], off offset:3872
	s_ashr_i32 s28, s30, 10
	s_ashr_i32 s29, s28, 31
	v_ashrrev_i32_e32 v139, 31, v138
	v_lshlrev_b64 v[188:189], 12, v[138:139]
	s_lshl_b64 s[28:29], s[28:29], 21
	v_lshl_add_u64 v[188:189], v[188:189], 0, s[28:29]
	s_brev_b32 s28, 63
	s_mov_b32 s29, -1
	v_lshl_add_u64 v[188:189], v[188:189], 0, s[28:29]
	v_lshl_add_u64 v[190:191], s[14:15], 0, v[188:189]
	v_lshlrev_b64 v[192:193], 2, v[136:137]
	v_lshl_add_u64 v[136:137], v[190:191], 0, v[192:193]
	s_waitcnt vmcnt(0)
	v_lshlrev_b32_e32 v190, 16, v158
	v_and_b32_e32 v191, 0xffff0000, v158
	v_lshlrev_b32_e32 v158, 16, v159
	v_and_b32_e32 v159, 0xffff0000, v159
	v_pk_mul_f32 v[124:125], v[124:125], v[190:191]
	v_pk_mul_f32 v[126:127], v[126:127], v[158:159]
	global_store_dwordx4 v[136:137], v[124:127], off
	s_nop 1
	v_lshlrev_b32_e32 v124, 16, v160
	v_and_b32_e32 v125, 0xffff0000, v160
	v_pk_mul_f32 v[120:121], v[120:121], v[124:125]
	v_lshlrev_b32_e32 v124, 16, v161
	v_and_b32_e32 v125, 0xffff0000, v161
	v_pk_mul_f32 v[122:123], v[122:123], v[124:125]
	global_store_dwordx4 v[136:137], v[120:123], off offset:64
	s_nop 1
	v_lshlrev_b32_e32 v120, 16, v162
	v_and_b32_e32 v121, 0xffff0000, v162
	v_pk_mul_f32 v[116:117], v[116:117], v[120:121]
	v_lshlrev_b32_e32 v120, 16, v163
	v_and_b32_e32 v121, 0xffff0000, v163
	v_pk_mul_f32 v[118:119], v[118:119], v[120:121]
	global_store_dwordx4 v[136:137], v[116:119], off offset:512
	s_nop 1
	v_lshlrev_b32_e32 v116, 16, v164
	v_and_b32_e32 v117, 0xffff0000, v164
	v_pk_mul_f32 v[108:109], v[108:109], v[116:117]
	v_lshlrev_b32_e32 v116, 16, v165
	v_and_b32_e32 v117, 0xffff0000, v165
	v_pk_mul_f32 v[110:111], v[110:111], v[116:117]
	global_store_dwordx4 v[136:137], v[108:111], off offset:576
	s_nop 1
	v_or_b32_e32 v108, 0x10000, v188
	v_mov_b32_e32 v109, v189
	v_lshl_add_u64 v[108:109], s[14:15], 0, v[108:109]
	v_lshl_add_u64 v[116:117], v[108:109], 0, v[192:193]
	v_lshlrev_b32_e32 v108, 16, v166
	v_and_b32_e32 v109, 0xffff0000, v166
	v_lshlrev_b32_e32 v110, 16, v167
	v_and_b32_e32 v111, 0xffff0000, v167
	v_pk_mul_f32 v[108:109], v[112:113], v[108:109]
	v_pk_mul_f32 v[110:111], v[114:115], v[110:111]
	global_store_dwordx4 v[116:117], v[108:111], off
	s_nop 1
	v_lshlrev_b32_e32 v108, 16, v168
	v_and_b32_e32 v109, 0xffff0000, v168
	v_pk_mul_f32 v[104:105], v[104:105], v[108:109]
	v_lshlrev_b32_e32 v108, 16, v169
	v_and_b32_e32 v109, 0xffff0000, v169
	v_pk_mul_f32 v[106:107], v[106:107], v[108:109]
	global_store_dwordx4 v[116:117], v[104:107], off offset:64
	s_nop 1
	v_lshlrev_b32_e32 v104, 16, v170
	v_and_b32_e32 v105, 0xffff0000, v170
	v_pk_mul_f32 v[100:101], v[100:101], v[104:105]
	v_lshlrev_b32_e32 v104, 16, v171
	v_and_b32_e32 v105, 0xffff0000, v171
	v_pk_mul_f32 v[102:103], v[102:103], v[104:105]
	global_store_dwordx4 v[116:117], v[100:103], off offset:512
	s_nop 1
	v_lshlrev_b32_e32 v100, 16, v172
	v_and_b32_e32 v101, 0xffff0000, v172
	v_pk_mul_f32 v[92:93], v[92:93], v[100:101]
	v_lshlrev_b32_e32 v100, 16, v173
	v_and_b32_e32 v101, 0xffff0000, v173
	v_pk_mul_f32 v[94:95], v[94:95], v[100:101]
	global_store_dwordx4 v[116:117], v[92:95], off offset:576
	s_nop 1
	v_or_b32_e32 v92, 0x20000, v188
	v_mov_b32_e32 v93, v189
	v_lshl_add_u64 v[92:93], s[14:15], 0, v[92:93]
	v_lshl_add_u64 v[100:101], v[92:93], 0, v[192:193]
	v_lshlrev_b32_e32 v92, 16, v174
	v_and_b32_e32 v93, 0xffff0000, v174
	v_lshlrev_b32_e32 v94, 16, v175
	v_and_b32_e32 v95, 0xffff0000, v175
	v_pk_mul_f32 v[92:93], v[96:97], v[92:93]
	v_pk_mul_f32 v[94:95], v[98:99], v[94:95]
	global_store_dwordx4 v[100:101], v[92:95], off
	v_or_b32_e32 v188, 0x30000, v188
	s_nop 0
	v_lshlrev_b32_e32 v92, 16, v180
	v_and_b32_e32 v93, 0xffff0000, v180
	v_pk_mul_f32 v[88:89], v[88:89], v[92:93]
	v_lshlrev_b32_e32 v92, 16, v181
	v_and_b32_e32 v93, 0xffff0000, v181
	v_pk_mul_f32 v[90:91], v[90:91], v[92:93]
	global_store_dwordx4 v[100:101], v[88:91], off offset:64
	s_nop 1
	v_lshlrev_b32_e32 v88, 16, v182
	v_and_b32_e32 v89, 0xffff0000, v182
	v_pk_mul_f32 v[84:85], v[84:85], v[88:89]
	v_lshlrev_b32_e32 v88, 16, v183
	v_and_b32_e32 v89, 0xffff0000, v183
	v_pk_mul_f32 v[86:87], v[86:87], v[88:89]
	global_store_dwordx4 v[100:101], v[84:87], off offset:512
	s_nop 1
	v_lshlrev_b32_e32 v84, 16, v184
	v_and_b32_e32 v85, 0xffff0000, v184
	v_pk_mul_f32 v[76:77], v[76:77], v[84:85]
	v_lshlrev_b32_e32 v84, 16, v185
	v_and_b32_e32 v85, 0xffff0000, v185
	v_pk_mul_f32 v[78:79], v[78:79], v[84:85]
	global_store_dwordx4 v[100:101], v[76:79], off offset:576
	s_nop 1
	v_lshl_add_u64 v[76:77], s[14:15], 0, v[188:189]
	v_lshl_add_u64 v[84:85], v[76:77], 0, v[192:193]
	v_lshlrev_b32_e32 v76, 16, v186
	v_and_b32_e32 v77, 0xffff0000, v186
	v_lshlrev_b32_e32 v78, 16, v187
	v_and_b32_e32 v79, 0xffff0000, v187
	v_pk_mul_f32 v[76:77], v[80:81], v[76:77]
	v_pk_mul_f32 v[78:79], v[82:83], v[78:79]
	global_store_dwordx4 v[84:85], v[76:79], off
	s_nop 1
	v_lshlrev_b32_e32 v76, 16, v148
	v_and_b32_e32 v77, 0xffff0000, v148
	v_pk_mul_f32 v[72:73], v[72:73], v[76:77]
	v_lshlrev_b32_e32 v76, 16, v149
	v_and_b32_e32 v77, 0xffff0000, v149
	v_pk_mul_f32 v[74:75], v[74:75], v[76:77]
	global_store_dwordx4 v[84:85], v[72:75], off offset:64
	s_nop 1
	v_lshlrev_b32_e32 v72, 16, v146
	v_and_b32_e32 v73, 0xffff0000, v146
	v_pk_mul_f32 v[68:69], v[68:69], v[72:73]
	v_lshlrev_b32_e32 v72, 16, v147
	v_and_b32_e32 v73, 0xffff0000, v147
	v_pk_mul_f32 v[70:71], v[70:71], v[72:73]
	global_store_dwordx4 v[84:85], v[68:71], off offset:512
	s_nop 1
	v_lshlrev_b32_e32 v68, 16, v144
	v_and_b32_e32 v69, 0xffff0000, v144
	v_pk_mul_f32 v[64:65], v[64:65], v[68:69]
	v_lshlrev_b32_e32 v68, 16, v145
	v_and_b32_e32 v69, 0xffff0000, v145
	v_pk_mul_f32 v[66:67], v[66:67], v[68:69]
	global_store_dwordx4 v[84:85], v[64:67], off offset:576
	s_nop 1
	v_add_u32_e32 v64, 0x80, v138
	v_mad_i64_i32 v[64:65], s[28:29], v64, s46, v[140:141]
	v_lshl_add_u64 v[64:65], v[64:65], 0, s[26:27]
	v_lshl_add_u64 v[64:65], v[64:65], 0, v[142:143]
	global_load_dwordx2 v[70:71], v[64:65], off offset:3584
	global_load_dwordx2 v[72:73], v[64:65], off offset:3616
	global_load_dwordx2 v[74:75], v[64:65], off offset:3840
	global_load_dwordx2 v[76:77], v[64:65], off offset:3872
	v_add_u32_e32 v64, 0x90, v138
	v_mad_i64_i32 v[64:65], s[28:29], v64, s46, v[140:141]
	v_lshl_add_u64 v[64:65], v[64:65], 0, s[26:27]
	v_lshl_add_u64 v[64:65], v[64:65], 0, v[142:143]
	global_load_dwordx2 v[78:79], v[64:65], off offset:3584
	global_load_dwordx2 v[80:81], v[64:65], off offset:3616
	global_load_dwordx2 v[82:83], v[64:65], off offset:3840
	global_load_dwordx2 v[84:85], v[64:65], off offset:3872
	v_add_u32_e32 v64, 0xa0, v138
	v_mad_i64_i32 v[64:65], s[28:29], v64, s46, v[140:141]
	v_lshl_add_u64 v[64:65], v[64:65], 0, s[26:27]
	v_lshl_add_u64 v[64:65], v[64:65], 0, v[142:143]
	global_load_dwordx2 v[86:87], v[64:65], off offset:3584
	global_load_dwordx2 v[88:89], v[64:65], off offset:3616
	global_load_dwordx2 v[90:91], v[64:65], off offset:3840
	global_load_dwordx2 v[92:93], v[64:65], off offset:3872
	v_add_u32_e32 v64, 0xb0, v138
	v_mad_i64_i32 v[64:65], s[28:29], v64, s46, v[140:141]
	v_lshl_add_u64 v[64:65], v[64:65], 0, s[26:27]
	v_lshl_add_u64 v[64:65], v[64:65], 0, v[142:143]
	global_load_dwordx2 v[94:95], v[64:65], off offset:3584
	global_load_dwordx2 v[68:69], v[64:65], off offset:3616
	global_load_dwordx2 v[66:67], v[64:65], off offset:3840
	s_nop 0
	global_load_dwordx2 v[64:65], v[64:65], off offset:3872
	s_mov_b64 s[26:27], 0x80000
	v_lshl_add_u64 v[96:97], v[136:137], 0, s[26:27]
	s_waitcnt vmcnt(15)
	v_lshlrev_b32_e32 v98, 16, v70
	v_and_b32_e32 v99, 0xffff0000, v70
	v_lshlrev_b32_e32 v70, 16, v71
	v_and_b32_e32 v71, 0xffff0000, v71
	s_mov_b32 s26, 0x80000
	v_pk_mul_f32 v[62:63], v[62:63], v[70:71]
	v_add_co_u32_e32 v70, vcc, s26, v136
	v_pk_mul_f32 v[60:61], v[60:61], v[98:99]
	s_nop 0
	v_addc_co_u32_e32 v71, vcc, 0, v137, vcc
	global_store_dwordx4 v[70:71], v[60:63], off
	s_mov_b64 s[26:27], 0x90000
	s_waitcnt vmcnt(15)
	v_lshlrev_b32_e32 v60, 16, v72
	v_and_b32_e32 v61, 0xffff0000, v72
	v_pk_mul_f32 v[56:57], v[56:57], v[60:61]
	v_lshlrev_b32_e32 v60, 16, v73
	v_and_b32_e32 v61, 0xffff0000, v73
	v_pk_mul_f32 v[58:59], v[58:59], v[60:61]
	global_store_dwordx4 v[96:97], v[56:59], off offset:64
	s_waitcnt vmcnt(15)
	s_nop 0
	v_lshlrev_b32_e32 v56, 16, v74
	v_and_b32_e32 v57, 0xffff0000, v74
	v_pk_mul_f32 v[52:53], v[52:53], v[56:57]
	v_lshlrev_b32_e32 v56, 16, v75
	v_and_b32_e32 v57, 0xffff0000, v75
	v_pk_mul_f32 v[54:55], v[54:55], v[56:57]
	global_store_dwordx4 v[96:97], v[52:55], off offset:512
	s_waitcnt vmcnt(15)
	s_nop 0
	v_lshlrev_b32_e32 v52, 16, v76
	v_and_b32_e32 v53, 0xffff0000, v76
	v_pk_mul_f32 v[44:45], v[44:45], v[52:53]
	v_lshlrev_b32_e32 v52, 16, v77
	v_and_b32_e32 v53, 0xffff0000, v77
	v_pk_mul_f32 v[46:47], v[46:47], v[52:53]
	global_store_dwordx4 v[96:97], v[44:47], off offset:576
	v_lshl_add_u64 v[52:53], v[136:137], 0, s[26:27]
	s_mov_b32 s26, 0x90000
	s_waitcnt vmcnt(15)
	v_lshlrev_b32_e32 v44, 16, v78
	v_and_b32_e32 v45, 0xffff0000, v78
	v_pk_mul_f32 v[44:45], v[48:49], v[44:45]
	v_lshlrev_b32_e32 v46, 16, v79
	v_and_b32_e32 v47, 0xffff0000, v79
	v_add_co_u32_e32 v48, vcc, s26, v136
	v_pk_mul_f32 v[46:47], v[50:51], v[46:47]
	s_nop 0
	v_addc_co_u32_e32 v49, vcc, 0, v137, vcc
	global_store_dwordx4 v[48:49], v[44:47], off
	s_mov_b64 s[26:27], 0xa0000
	s_waitcnt vmcnt(15)
	v_lshlrev_b32_e32 v44, 16, v80
	v_and_b32_e32 v45, 0xffff0000, v80
	v_pk_mul_f32 v[40:41], v[40:41], v[44:45]
	v_lshlrev_b32_e32 v44, 16, v81
	v_and_b32_e32 v45, 0xffff0000, v81
	v_pk_mul_f32 v[42:43], v[42:43], v[44:45]
	global_store_dwordx4 v[52:53], v[40:43], off offset:64
	s_waitcnt vmcnt(15)
	s_nop 0
	v_lshlrev_b32_e32 v40, 16, v82
	v_and_b32_e32 v41, 0xffff0000, v82
	v_pk_mul_f32 v[36:37], v[36:37], v[40:41]
	v_lshlrev_b32_e32 v40, 16, v83
	v_and_b32_e32 v41, 0xffff0000, v83
	v_pk_mul_f32 v[38:39], v[38:39], v[40:41]
	global_store_dwordx4 v[52:53], v[36:39], off offset:512
	s_waitcnt vmcnt(15)
	s_nop 0
	v_lshlrev_b32_e32 v36, 16, v84
	v_and_b32_e32 v37, 0xffff0000, v84
	v_pk_mul_f32 v[28:29], v[28:29], v[36:37]
	v_lshlrev_b32_e32 v36, 16, v85
	v_and_b32_e32 v37, 0xffff0000, v85
	v_pk_mul_f32 v[30:31], v[30:31], v[36:37]
	global_store_dwordx4 v[52:53], v[28:31], off offset:576
	v_lshl_add_u64 v[36:37], v[136:137], 0, s[26:27]
	s_waitcnt vmcnt(15)
	v_lshlrev_b32_e32 v28, 16, v86
	v_and_b32_e32 v29, 0xffff0000, v86
	v_pk_mul_f32 v[28:29], v[32:33], v[28:29]
	v_lshlrev_b32_e32 v30, 16, v87
	v_and_b32_e32 v31, 0xffff0000, v87
	v_add_co_u32_e32 v32, vcc, s47, v136
	v_pk_mul_f32 v[30:31], v[34:35], v[30:31]
	s_nop 0
	v_addc_co_u32_e32 v33, vcc, 0, v137, vcc
	global_store_dwordx4 v[32:33], v[28:31], off
	s_waitcnt vmcnt(15)
	s_nop 0
	v_lshlrev_b32_e32 v28, 16, v88
	v_and_b32_e32 v29, 0xffff0000, v88
	v_pk_mul_f32 v[24:25], v[24:25], v[28:29]
	v_lshlrev_b32_e32 v28, 16, v89
	v_and_b32_e32 v29, 0xffff0000, v89
	v_pk_mul_f32 v[26:27], v[26:27], v[28:29]
	global_store_dwordx4 v[36:37], v[24:27], off offset:64
	s_waitcnt vmcnt(15)
	s_nop 0
	v_lshlrev_b32_e32 v24, 16, v90
	v_and_b32_e32 v25, 0xffff0000, v90
	v_pk_mul_f32 v[20:21], v[20:21], v[24:25]
	v_lshlrev_b32_e32 v24, 16, v91
	v_and_b32_e32 v25, 0xffff0000, v91
	v_pk_mul_f32 v[22:23], v[22:23], v[24:25]
	global_store_dwordx4 v[36:37], v[20:23], off offset:512
	s_waitcnt vmcnt(15)
	s_nop 0
	v_lshlrev_b32_e32 v20, 16, v92
	v_and_b32_e32 v21, 0xffff0000, v92
	v_pk_mul_f32 v[12:13], v[12:13], v[20:21]
	v_lshlrev_b32_e32 v20, 16, v93
	v_and_b32_e32 v21, 0xffff0000, v93
	v_pk_mul_f32 v[14:15], v[14:15], v[20:21]
	global_store_dwordx4 v[36:37], v[12:15], off offset:576
	v_lshl_add_u64 v[20:21], v[136:137], 0, s[20:21]
	s_waitcnt vmcnt(15)
	v_lshlrev_b32_e32 v12, 16, v94
	v_and_b32_e32 v13, 0xffff0000, v94
	v_pk_mul_f32 v[12:13], v[16:17], v[12:13]
	v_lshlrev_b32_e32 v14, 16, v95
	v_and_b32_e32 v15, 0xffff0000, v95
	v_add_co_u32_e32 v16, vcc, s48, v136
	v_pk_mul_f32 v[14:15], v[18:19], v[14:15]
	s_nop 0
	v_addc_co_u32_e32 v17, vcc, 0, v137, vcc
	global_store_dwordx4 v[16:17], v[12:15], off
	s_waitcnt vmcnt(15)
	s_nop 0
	v_lshlrev_b32_e32 v12, 16, v68
	v_and_b32_e32 v13, 0xffff0000, v68
	v_pk_mul_f32 v[8:9], v[8:9], v[12:13]
	v_lshlrev_b32_e32 v12, 16, v69
	v_and_b32_e32 v13, 0xffff0000, v69
	v_pk_mul_f32 v[10:11], v[10:11], v[12:13]
	global_store_dwordx4 v[20:21], v[8:11], off offset:64
	s_waitcnt vmcnt(15)
	s_nop 0
	v_lshlrev_b32_e32 v8, 16, v66
	v_and_b32_e32 v9, 0xffff0000, v66
	v_pk_mul_f32 v[4:5], v[4:5], v[8:9]
	v_lshlrev_b32_e32 v8, 16, v67
	v_and_b32_e32 v9, 0xffff0000, v67
	v_pk_mul_f32 v[6:7], v[6:7], v[8:9]
	global_store_dwordx4 v[20:21], v[4:7], off offset:512
	s_waitcnt vmcnt(15)
	s_nop 0
	v_lshlrev_b32_e32 v4, 16, v64
	v_and_b32_e32 v5, 0xffff0000, v64
	v_pk_mul_f32 v[0:1], v[0:1], v[4:5]
	v_lshlrev_b32_e32 v4, 16, v65
	v_and_b32_e32 v5, 0xffff0000, v65
	v_pk_mul_f32 v[2:3], v[2:3], v[4:5]
	global_store_dwordx4 v[20:21], v[0:3], off offset:576
	s_and_b64 vcc, exec, s[2:3]
	s_mov_b64 s[2:3], -1
	s_cbranch_vccnz .LBB0_905
	s_andn2_b64 vcc, exec, s[10:11]
	s_cbranch_vccnz .LBB0_904
	v_writelane_b32 v255, 1, 53
	s_branch .LBB0_904

.LBB0_1002:
	s_lshl_b32 s56, s6, 8
	s_lshl_b32 s57, s28, 8
	s_or_b32 s58, s57, s45
	s_add_i32 s59, s56, s44
	s_add_u32 s60, s26, 0x100
	v_mov_b32_e32 v0, 0
	v_lshl_add_u64 v[184:185], s[24:25], 0, v[176:177]
	v_lshl_add_u64 v[186:187], s[24:25], 0, v[178:179]
	s_addc_u32 s61, s27, 0
	s_mov_b32 s62, 0
	s_mov_b64 s[26:27], 0
	v_mov_b32_e32 v1, v0
	v_mov_b32_e32 v2, v0
	v_mov_b32_e32 v3, v0
	v_mov_b32_e32 v4, v0
	v_mov_b32_e32 v5, v0
	v_mov_b32_e32 v6, v0
	v_mov_b32_e32 v7, v0
	v_mov_b32_e32 v16, v0
	v_mov_b32_e32 v17, v0
	v_mov_b32_e32 v18, v0
	v_mov_b32_e32 v19, v0
	v_mov_b32_e32 v20, v0
	v_mov_b32_e32 v21, v0
	v_mov_b32_e32 v22, v0
	v_mov_b32_e32 v23, v0
	v_mov_b32_e32 v32, v0
	v_mov_b32_e32 v33, v0
	v_mov_b32_e32 v34, v0
	v_mov_b32_e32 v35, v0
	v_mov_b32_e32 v36, v0
	v_mov_b32_e32 v37, v0
	v_mov_b32_e32 v38, v0
	v_mov_b32_e32 v39, v0
	v_mov_b32_e32 v48, v0
	v_mov_b32_e32 v49, v0
	v_mov_b32_e32 v50, v0
	v_mov_b32_e32 v51, v0
	v_mov_b32_e32 v52, v0
	v_mov_b32_e32 v53, v0
	v_mov_b32_e32 v54, v0
	v_mov_b32_e32 v55, v0
	v_mov_b32_e32 v8, v0
	v_mov_b32_e32 v9, v0
	v_mov_b32_e32 v10, v0
	v_mov_b32_e32 v11, v0
	v_mov_b32_e32 v12, v0
	v_mov_b32_e32 v13, v0
	v_mov_b32_e32 v14, v0
	v_mov_b32_e32 v15, v0
	v_mov_b32_e32 v24, v0
	v_mov_b32_e32 v25, v0
	v_mov_b32_e32 v26, v0
	v_mov_b32_e32 v27, v0
	v_mov_b32_e32 v28, v0
	v_mov_b32_e32 v29, v0
	v_mov_b32_e32 v30, v0
	v_mov_b32_e32 v31, v0
	v_mov_b32_e32 v40, v0
	v_mov_b32_e32 v41, v0
	v_mov_b32_e32 v42, v0
	v_mov_b32_e32 v43, v0
	v_mov_b32_e32 v44, v0
	v_mov_b32_e32 v45, v0
	v_mov_b32_e32 v46, v0
	v_mov_b32_e32 v47, v0
	v_mov_b32_e32 v56, v0
	v_mov_b32_e32 v57, v0
	v_mov_b32_e32 v58, v0
	v_mov_b32_e32 v59, v0
	v_mov_b32_e32 v60, v0
	v_mov_b32_e32 v61, v0
	v_mov_b32_e32 v62, v0
	v_mov_b32_e32 v63, v0
	v_mov_b32_e32 v64, v0
	v_mov_b32_e32 v65, v0
	v_mov_b32_e32 v66, v0
	v_mov_b32_e32 v67, v0
	v_mov_b32_e32 v68, v0
	v_mov_b32_e32 v69, v0
	v_mov_b32_e32 v70, v0
	v_mov_b32_e32 v71, v0
	v_mov_b32_e32 v80, v0
	v_mov_b32_e32 v81, v0
	v_mov_b32_e32 v82, v0
	v_mov_b32_e32 v83, v0
	v_mov_b32_e32 v84, v0
	v_mov_b32_e32 v85, v0
	v_mov_b32_e32 v86, v0
	v_mov_b32_e32 v87, v0
	v_mov_b32_e32 v96, v0
	v_mov_b32_e32 v97, v0
	v_mov_b32_e32 v98, v0
	v_mov_b32_e32 v99, v0
	v_mov_b32_e32 v100, v0
	v_mov_b32_e32 v101, v0
	v_mov_b32_e32 v102, v0
	v_mov_b32_e32 v103, v0
	v_mov_b32_e32 v112, v0
	v_mov_b32_e32 v113, v0
	v_mov_b32_e32 v114, v0
	v_mov_b32_e32 v115, v0
	v_mov_b32_e32 v116, v0
	v_mov_b32_e32 v117, v0
	v_mov_b32_e32 v118, v0
	v_mov_b32_e32 v119, v0
	v_mov_b32_e32 v72, v0
	v_mov_b32_e32 v73, v0
	v_mov_b32_e32 v74, v0
	v_mov_b32_e32 v75, v0
	v_mov_b32_e32 v76, v0
	v_mov_b32_e32 v77, v0
	v_mov_b32_e32 v78, v0
	v_mov_b32_e32 v79, v0
	v_mov_b32_e32 v88, v0
	v_mov_b32_e32 v89, v0
	v_mov_b32_e32 v90, v0
	v_mov_b32_e32 v91, v0
	v_mov_b32_e32 v92, v0
	v_mov_b32_e32 v93, v0
	v_mov_b32_e32 v94, v0
	v_mov_b32_e32 v95, v0
	v_mov_b32_e32 v104, v0
	v_mov_b32_e32 v105, v0
	v_mov_b32_e32 v106, v0
	v_mov_b32_e32 v107, v0
	v_mov_b32_e32 v108, v0
	v_mov_b32_e32 v109, v0
	v_mov_b32_e32 v110, v0
	v_mov_b32_e32 v111, v0
	v_mov_b32_e32 v120, v0
	v_mov_b32_e32 v121, v0
	v_mov_b32_e32 v122, v0
	v_mov_b32_e32 v123, v0
	v_mov_b32_e32 v124, v0
	v_mov_b32_e32 v125, v0
	v_mov_b32_e32 v126, v0
	v_mov_b32_e32 v127, v0
	v_readlane_b32 s97, v255, 53
	s_nop 3
	s_cmp_eq_u32 s97, 1
	s_cbranch_scc0 .Llsb_skip_7
	v_writelane_b32 v255, 0, 53
	s_barrier
.Llsb_skip_7:
	s_branch .LBB0_1004
.LBB0_1003:
	v_add_u32_e32 v140, s50, v195
	v_add_u32_e32 v156, s51, v195
	s_add_u32 s6, s24, s26
	ds_read_b128 v[128:131], v140
	ds_read_b128 v[132:135], v140 offset:1024
	ds_read_b128 v[136:139], v140 offset:2048
	ds_read_b128 v[140:143], v140 offset:3072
	ds_read_b128 v[144:147], v156
	ds_read_b128 v[148:151], v156 offset:1024
	ds_read_b128 v[152:155], v156 offset:2048
	ds_read_b128 v[156:159], v156 offset:3072
	s_addc_u32 s28, s25, s27
	s_add_u32 s6, s6, 0x100
	s_addc_u32 s28, s28, 0
	s_add_u32 s63, s60, s26
	s_addc_u32 s29, s61, s27
	s_cmpk_eq_i32 s26, 0xb00
	s_cselect_b32 s31, s5, s28
	s_cselect_b32 s30, s4, s6
	s_cselect_b32 s29, s23, s29
	s_cselect_b32 s28, s22, s63
	v_lshl_add_u64 v[202:203], v[184:185], 0, s[26:27]
	s_add_i32 m0, s40, 0xc000
	ds_read_b128 v[160:163], v197
	ds_read_b128 v[164:167], v197 offset:1024
	ds_read_b128 v[188:191], v197 offset:2048
	ds_read_b128 v[198:201], v197 offset:3072
	ds_read_b128 v[206:209], v197 offset:4096
	ds_read_b128 v[210:213], v197 offset:5120
	ds_read_b128 v[214:217], v197 offset:6144
	ds_read_b128 v[218:221], v197 offset:7168
	global_load_lds_dwordx4 v[202:203], off
	v_lshl_add_u64 v[202:203], v[186:187], 0, s[26:27]
	s_add_i32 m0, s40, 0xe000
	s_nop 0
	global_load_lds_dwordx4 v[202:203], off
	s_waitcnt vmcnt(8)
	s_waitcnt lgkmcnt(0)
	s_barrier
	s_setprio 1
	s_waitcnt lgkmcnt(0)
	v_mfma_f32_16x16x32_bf16 v[124:127], v[128:131], v[160:163], v[124:127]
	v_mfma_f32_16x16x32_bf16 v[120:123], v[136:139], v[160:163], v[120:123]
	v_mfma_f32_16x16x32_bf16 v[108:111], v[128:131], v[188:191], v[108:111]
	v_mfma_f32_16x16x32_bf16 v[104:107], v[136:139], v[188:191], v[104:107]
	v_mfma_f32_16x16x32_bf16 v[92:95], v[128:131], v[206:209], v[92:95]
	v_mfma_f32_16x16x32_bf16 v[88:91], v[136:139], v[206:209], v[88:91]
	v_mfma_f32_16x16x32_bf16 v[76:79], v[128:131], v[214:217], v[76:79]
	v_mfma_f32_16x16x32_bf16 v[72:75], v[136:139], v[214:217], v[72:75]
	v_mfma_f32_16x16x32_bf16 v[124:127], v[132:135], v[164:167], v[124:127]
	v_mfma_f32_16x16x32_bf16 v[120:123], v[140:143], v[164:167], v[120:123]
	v_mfma_f32_16x16x32_bf16 v[108:111], v[132:135], v[198:201], v[108:111]
	v_mfma_f32_16x16x32_bf16 v[104:107], v[140:143], v[198:201], v[104:107]
	v_mfma_f32_16x16x32_bf16 v[92:95], v[132:135], v[210:213], v[92:95]
	v_mfma_f32_16x16x32_bf16 v[88:91], v[140:143], v[210:213], v[88:91]
	v_mfma_f32_16x16x32_bf16 v[76:79], v[132:135], v[218:221], v[76:79]
	v_mfma_f32_16x16x32_bf16 v[72:75], v[140:143], v[218:221], v[72:75]
	s_setprio 0
	s_setprio 1
	v_mfma_f32_16x16x32_bf16 v[116:119], v[144:147], v[160:163], v[116:119]
	v_mfma_f32_16x16x32_bf16 v[112:115], v[152:155], v[160:163], v[112:115]
	v_mfma_f32_16x16x32_bf16 v[100:103], v[144:147], v[188:191], v[100:103]
	v_mfma_f32_16x16x32_bf16 v[96:99], v[152:155], v[188:191], v[96:99]
	v_mfma_f32_16x16x32_bf16 v[84:87], v[144:147], v[206:209], v[84:87]
	v_mfma_f32_16x16x32_bf16 v[80:83], v[152:155], v[206:209], v[80:83]
	v_mfma_f32_16x16x32_bf16 v[68:71], v[144:147], v[214:217], v[68:71]
	v_mfma_f32_16x16x32_bf16 v[64:67], v[152:155], v[214:217], v[64:67]
	v_mfma_f32_16x16x32_bf16 v[116:119], v[148:151], v[164:167], v[116:119]
	v_mfma_f32_16x16x32_bf16 v[112:115], v[156:159], v[164:167], v[112:115]
	v_mfma_f32_16x16x32_bf16 v[100:103], v[148:151], v[198:201], v[100:103]
	v_mfma_f32_16x16x32_bf16 v[96:99], v[156:159], v[198:201], v[96:99]
	v_mfma_f32_16x16x32_bf16 v[84:87], v[148:151], v[210:213], v[84:87]
	v_mfma_f32_16x16x32_bf16 v[80:83], v[156:159], v[210:213], v[80:83]
	v_mfma_f32_16x16x32_bf16 v[68:71], v[148:151], v[218:221], v[68:71]
	v_mfma_f32_16x16x32_bf16 v[64:67], v[156:159], v[218:221], v[64:67]
	s_setprio 0
	s_barrier
	s_add_i32 s6, s50, s39
	v_lshl_add_u64 v[202:203], s[28:29], 0, v[170:171]
	s_mov_b32 m0, s6
	ds_read_b128 v[160:163], v197 offset:16384
	ds_read_b128 v[164:167], v197 offset:17408
	ds_read_b128 v[188:191], v197 offset:18432
	ds_read_b128 v[198:201], v197 offset:19456
	ds_read_b128 v[206:209], v197 offset:20480
	ds_read_b128 v[210:213], v197 offset:21504
	ds_read_b128 v[214:217], v197 offset:22528
	ds_read_b128 v[218:221], v197 offset:23552
	global_load_lds_dwordx4 v[202:203], off
	s_add_i32 m0, s6, 0x2000
	s_add_u32 s64, s28, 0x60000
	v_lshl_add_u64 v[222:223], s[28:29], 0, v[174:175]
	s_addc_u32 s65, s29, 0
	s_add_i32 s6, s51, s39
	global_load_lds_dwordx4 v[222:223], off
	v_lshl_add_u64 v[224:225], s[64:65], 0, v[170:171]
	s_mov_b32 m0, s6
	v_lshl_add_u64 v[226:227], s[30:31], 0, v[172:173]
	global_load_lds_dwordx4 v[224:225], off
	v_lshl_add_u64 v[224:225], s[64:65], 0, v[174:175]
	s_add_i32 m0, s6, 0x2000
	s_nop 0
	global_load_lds_dwordx4 v[224:225], off
	v_lshl_add_u64 v[224:225], s[30:31], 0, v[168:169]
	s_mov_b32 m0, s40
	s_nop 0
	global_load_lds_dwordx4 v[224:225], off
	s_mov_b32 m0, s41
	s_nop 0
	global_load_lds_dwordx4 v[226:227], off
	s_waitcnt vmcnt(8)
	s_waitcnt lgkmcnt(0)
	s_barrier
	s_setprio 1
	s_waitcnt lgkmcnt(0)
	v_mfma_f32_16x16x32_bf16 v[60:63], v[128:131], v[160:163], v[60:63]
	v_mfma_f32_16x16x32_bf16 v[56:59], v[136:139], v[160:163], v[56:59]
	v_mfma_f32_16x16x32_bf16 v[44:47], v[128:131], v[188:191], v[44:47]
	v_mfma_f32_16x16x32_bf16 v[40:43], v[136:139], v[188:191], v[40:43]
	v_mfma_f32_16x16x32_bf16 v[28:31], v[128:131], v[206:209], v[28:31]
	v_mfma_f32_16x16x32_bf16 v[24:27], v[136:139], v[206:209], v[24:27]
	v_mfma_f32_16x16x32_bf16 v[12:15], v[128:131], v[214:217], v[12:15]
	v_mfma_f32_16x16x32_bf16 v[8:11], v[136:139], v[214:217], v[8:11]
	v_mfma_f32_16x16x32_bf16 v[60:63], v[132:135], v[164:167], v[60:63]
	v_mfma_f32_16x16x32_bf16 v[56:59], v[140:143], v[164:167], v[56:59]
	v_mfma_f32_16x16x32_bf16 v[44:47], v[132:135], v[198:201], v[44:47]
	v_mfma_f32_16x16x32_bf16 v[40:43], v[140:143], v[198:201], v[40:43]
	v_mfma_f32_16x16x32_bf16 v[28:31], v[132:135], v[210:213], v[28:31]
	v_mfma_f32_16x16x32_bf16 v[24:27], v[140:143], v[210:213], v[24:27]
	v_mfma_f32_16x16x32_bf16 v[12:15], v[132:135], v[218:221], v[12:15]
	v_mfma_f32_16x16x32_bf16 v[8:11], v[140:143], v[218:221], v[8:11]
	s_setprio 0
	s_setprio 1
	v_mfma_f32_16x16x32_bf16 v[52:55], v[144:147], v[160:163], v[52:55]
	v_mfma_f32_16x16x32_bf16 v[48:51], v[152:155], v[160:163], v[48:51]
	v_mfma_f32_16x16x32_bf16 v[36:39], v[144:147], v[188:191], v[36:39]
	v_mfma_f32_16x16x32_bf16 v[32:35], v[152:155], v[188:191], v[32:35]
	v_mfma_f32_16x16x32_bf16 v[20:23], v[144:147], v[206:209], v[20:23]
	v_mfma_f32_16x16x32_bf16 v[16:19], v[152:155], v[206:209], v[16:19]
	v_mfma_f32_16x16x32_bf16 v[4:7], v[144:147], v[214:217], v[4:7]
	v_mfma_f32_16x16x32_bf16 v[0:3], v[152:155], v[214:217], v[0:3]
	v_mfma_f32_16x16x32_bf16 v[52:55], v[148:151], v[164:167], v[52:55]
	v_mfma_f32_16x16x32_bf16 v[48:51], v[156:159], v[164:167], v[48:51]
	v_mfma_f32_16x16x32_bf16 v[36:39], v[148:151], v[198:201], v[36:39]
	v_mfma_f32_16x16x32_bf16 v[32:35], v[156:159], v[198:201], v[32:35]
	v_mfma_f32_16x16x32_bf16 v[20:23], v[148:151], v[210:213], v[20:23]
	v_mfma_f32_16x16x32_bf16 v[16:19], v[156:159], v[210:213], v[16:19]
	v_mfma_f32_16x16x32_bf16 v[4:7], v[148:151], v[218:221], v[4:7]
	v_mfma_f32_16x16x32_bf16 v[0:3], v[156:159], v[218:221], v[0:3]
	s_setprio 0
	s_barrier
	s_add_i32 s6, 0, 0x18000
	s_add_i32 s63, 0, 0x1c000
	v_add_u32_e32 v140, s6, v195
	v_add_u32_e32 v156, s63, v195
	ds_read_b128 v[128:131], v140
	ds_read_b128 v[132:135], v140 offset:1024
	ds_read_b128 v[136:139], v140 offset:2048
	ds_read_b128 v[140:143], v140 offset:3072
	ds_read_b128 v[144:147], v156
	ds_read_b128 v[148:151], v156 offset:1024
	ds_read_b128 v[152:155], v156 offset:2048
	ds_read_b128 v[156:159], v156 offset:3072
	s_add_u32 s30, s30, 0x60000
	s_addc_u32 s31, s31, 0
	s_mov_b32 m0, s42
	v_lshl_add_u64 v[228:229], s[30:31], 0, v[168:169]
	ds_read_b128 v[160:163], v197 offset:32768
	ds_read_b128 v[164:167], v197 offset:33792
	ds_read_b128 v[188:191], v197 offset:34816
	ds_read_b128 v[198:201], v197 offset:35840
	ds_read_b128 v[206:209], v197 offset:36864
	ds_read_b128 v[210:213], v197 offset:37888
	ds_read_b128 v[214:217], v197 offset:38912
	ds_read_b128 v[218:221], v197 offset:39936
	global_load_lds_dwordx4 v[228:229], off
	v_lshl_add_u64 v[228:229], s[30:31], 0, v[172:173]
	s_mov_b32 m0, s43
	s_nop 0
	global_load_lds_dwordx4 v[228:229], off
	s_waitcnt vmcnt(8)
	s_waitcnt lgkmcnt(0)
	s_barrier
	s_setprio 1
	s_waitcnt lgkmcnt(0)
	v_mfma_f32_16x16x32_bf16 v[124:127], v[128:131], v[160:163], v[124:127]
	v_mfma_f32_16x16x32_bf16 v[120:123], v[136:139], v[160:163], v[120:123]
	v_mfma_f32_16x16x32_bf16 v[108:111], v[128:131], v[188:191], v[108:111]
	v_mfma_f32_16x16x32_bf16 v[104:107], v[136:139], v[188:191], v[104:107]
	v_mfma_f32_16x16x32_bf16 v[92:95], v[128:131], v[206:209], v[92:95]
	v_mfma_f32_16x16x32_bf16 v[88:91], v[136:139], v[206:209], v[88:91]
	v_mfma_f32_16x16x32_bf16 v[76:79], v[128:131], v[214:217], v[76:79]
	v_mfma_f32_16x16x32_bf16 v[72:75], v[136:139], v[214:217], v[72:75]
	v_mfma_f32_16x16x32_bf16 v[124:127], v[132:135], v[164:167], v[124:127]
	v_mfma_f32_16x16x32_bf16 v[120:123], v[140:143], v[164:167], v[120:123]
	v_mfma_f32_16x16x32_bf16 v[108:111], v[132:135], v[198:201], v[108:111]
	v_mfma_f32_16x16x32_bf16 v[104:107], v[140:143], v[198:201], v[104:107]
	v_mfma_f32_16x16x32_bf16 v[92:95], v[132:135], v[210:213], v[92:95]
	v_mfma_f32_16x16x32_bf16 v[88:91], v[140:143], v[210:213], v[88:91]
	v_mfma_f32_16x16x32_bf16 v[76:79], v[132:135], v[218:221], v[76:79]
	v_mfma_f32_16x16x32_bf16 v[72:75], v[140:143], v[218:221], v[72:75]
	s_setprio 0
	s_setprio 1
	v_mfma_f32_16x16x32_bf16 v[116:119], v[144:147], v[160:163], v[116:119]
	v_mfma_f32_16x16x32_bf16 v[112:115], v[152:155], v[160:163], v[112:115]
	v_mfma_f32_16x16x32_bf16 v[100:103], v[144:147], v[188:191], v[100:103]
	v_mfma_f32_16x16x32_bf16 v[96:99], v[152:155], v[188:191], v[96:99]
	v_mfma_f32_16x16x32_bf16 v[84:87], v[144:147], v[206:209], v[84:87]
	v_mfma_f32_16x16x32_bf16 v[80:83], v[152:155], v[206:209], v[80:83]
	v_mfma_f32_16x16x32_bf16 v[68:71], v[144:147], v[214:217], v[68:71]
	v_mfma_f32_16x16x32_bf16 v[64:67], v[152:155], v[214:217], v[64:67]
	v_mfma_f32_16x16x32_bf16 v[116:119], v[148:151], v[164:167], v[116:119]
	v_mfma_f32_16x16x32_bf16 v[112:115], v[156:159], v[164:167], v[112:115]
	v_mfma_f32_16x16x32_bf16 v[100:103], v[148:151], v[198:201], v[100:103]
	v_mfma_f32_16x16x32_bf16 v[96:99], v[156:159], v[198:201], v[96:99]
	v_mfma_f32_16x16x32_bf16 v[84:87], v[148:151], v[210:213], v[84:87]
	v_mfma_f32_16x16x32_bf16 v[80:83], v[156:159], v[210:213], v[80:83]
	v_mfma_f32_16x16x32_bf16 v[68:71], v[148:151], v[218:221], v[68:71]
	v_mfma_f32_16x16x32_bf16 v[64:67], v[156:159], v[218:221], v[64:67]
	s_setprio 0
	s_barrier
	s_add_i32 s6, s6, s39
	v_lshl_add_u64 v[202:203], v[202:203], 0, s[14:15]
	s_mov_b32 m0, s6
	ds_read_b128 v[160:163], v197 offset:49152
	ds_read_b128 v[164:167], v197 offset:50176
	ds_read_b128 v[188:191], v197 offset:51200
	ds_read_b128 v[198:201], v197 offset:52224
	ds_read_b128 v[206:209], v197 offset:53248
	ds_read_b128 v[210:213], v197 offset:54272
	ds_read_b128 v[214:217], v197 offset:55296
	ds_read_b128 v[218:221], v197 offset:56320
	global_load_lds_dwordx4 v[202:203], off
	s_add_i32 m0, s6, 0x2000
	s_add_u32 s28, s28, 0x60080
	v_lshl_add_u64 v[202:203], v[222:223], 0, s[14:15]
	s_addc_u32 s29, s29, 0
	s_add_i32 s6, s63, s39
	global_load_lds_dwordx4 v[202:203], off
	v_lshl_add_u64 v[202:203], s[28:29], 0, v[170:171]
	s_mov_b32 m0, s6
	s_nop 0
	global_load_lds_dwordx4 v[202:203], off
	v_lshl_add_u64 v[202:203], s[28:29], 0, v[174:175]
	s_add_i32 m0, s6, 0x2000
	s_nop 0
	global_load_lds_dwordx4 v[202:203], off
	v_lshl_add_u64 v[202:203], v[224:225], 0, s[14:15]
	s_mov_b32 m0, s46
	s_nop 0
	global_load_lds_dwordx4 v[202:203], off
	v_lshl_add_u64 v[202:203], v[226:227], 0, s[14:15]
	s_mov_b32 m0, s47
	s_nop 0
	global_load_lds_dwordx4 v[202:203], off
	s_waitcnt vmcnt(8)
	s_waitcnt lgkmcnt(0)
	s_barrier
	s_setprio 1
	s_waitcnt lgkmcnt(0)
	v_mfma_f32_16x16x32_bf16 v[60:63], v[128:131], v[160:163], v[60:63]
	v_mfma_f32_16x16x32_bf16 v[56:59], v[136:139], v[160:163], v[56:59]
	v_mfma_f32_16x16x32_bf16 v[44:47], v[128:131], v[188:191], v[44:47]
	v_mfma_f32_16x16x32_bf16 v[40:43], v[136:139], v[188:191], v[40:43]
	v_mfma_f32_16x16x32_bf16 v[28:31], v[128:131], v[206:209], v[28:31]
	v_mfma_f32_16x16x32_bf16 v[24:27], v[136:139], v[206:209], v[24:27]
	v_mfma_f32_16x16x32_bf16 v[12:15], v[128:131], v[214:217], v[12:15]
	v_mfma_f32_16x16x32_bf16 v[8:11], v[136:139], v[214:217], v[8:11]
	v_mfma_f32_16x16x32_bf16 v[60:63], v[132:135], v[164:167], v[60:63]
	v_mfma_f32_16x16x32_bf16 v[56:59], v[140:143], v[164:167], v[56:59]
	v_mfma_f32_16x16x32_bf16 v[44:47], v[132:135], v[198:201], v[44:47]
	v_mfma_f32_16x16x32_bf16 v[40:43], v[140:143], v[198:201], v[40:43]
	v_mfma_f32_16x16x32_bf16 v[28:31], v[132:135], v[210:213], v[28:31]
	v_mfma_f32_16x16x32_bf16 v[24:27], v[140:143], v[210:213], v[24:27]
	v_mfma_f32_16x16x32_bf16 v[12:15], v[132:135], v[218:221], v[12:15]
	v_mfma_f32_16x16x32_bf16 v[8:11], v[140:143], v[218:221], v[8:11]
	s_setprio 0
	s_setprio 1
	v_mfma_f32_16x16x32_bf16 v[52:55], v[144:147], v[160:163], v[52:55]
	v_mfma_f32_16x16x32_bf16 v[48:51], v[152:155], v[160:163], v[48:51]
	v_mfma_f32_16x16x32_bf16 v[36:39], v[144:147], v[188:191], v[36:39]
	v_mfma_f32_16x16x32_bf16 v[32:35], v[152:155], v[188:191], v[32:35]
	v_mfma_f32_16x16x32_bf16 v[20:23], v[144:147], v[206:209], v[20:23]
	v_mfma_f32_16x16x32_bf16 v[16:19], v[152:155], v[206:209], v[16:19]
	v_mfma_f32_16x16x32_bf16 v[4:7], v[144:147], v[214:217], v[4:7]
	v_mfma_f32_16x16x32_bf16 v[0:3], v[152:155], v[214:217], v[0:3]
	v_mfma_f32_16x16x32_bf16 v[52:55], v[148:151], v[164:167], v[52:55]
	v_mfma_f32_16x16x32_bf16 v[48:51], v[156:159], v[164:167], v[48:51]
	v_mfma_f32_16x16x32_bf16 v[36:39], v[148:151], v[198:201], v[36:39]
	v_mfma_f32_16x16x32_bf16 v[32:35], v[156:159], v[198:201], v[32:35]
	v_mfma_f32_16x16x32_bf16 v[20:23], v[148:151], v[210:213], v[20:23]
	v_mfma_f32_16x16x32_bf16 v[16:19], v[156:159], v[210:213], v[16:19]
	v_mfma_f32_16x16x32_bf16 v[4:7], v[148:151], v[218:221], v[4:7]
	v_mfma_f32_16x16x32_bf16 v[0:3], v[156:159], v[218:221], v[0:3]
	s_setprio 0
	s_barrier
	s_add_i32 s6, s62, 2
	s_add_u32 s26, s26, 0x100
	s_addc_u32 s27, s27, 0
	s_cmp_gt_u32 s62, 21
	s_mov_b32 s62, s6
	s_cbranch_scc1 .LBB0_1010

.LBB0_1012:
	v_or_b32_e32 v128, s57, v196
	v_add_u32_e32 v146, s56, v194
	v_ashrrev_i32_e32 v129, 31, v128
	v_mov_b64_e32 v[148:149], s[10:11]
	v_mad_i64_i32 v[130:131], s[24:25], v146, s49, v[148:149]
	v_lshlrev_b64 v[144:145], 1, v[128:129]
	v_lshl_add_u64 v[128:129], v[130:131], 0, v[144:145]
	v_lshl_add_u64 v[130:131], v[128:129], 0, s[20:21]
	v_add_co_u32_e32 v128, vcc, 0x1000, v128
	v_or_b32_e32 v184, 16, v146
	s_nop 0
	v_addc_co_u32_e32 v129, vcc, 0, v129, vcc
	global_load_dwordx4 v[152:155], v[128:129], off offset:3584
	global_load_dwordx4 v[156:159], v[130:131], off offset:256
	v_mad_i64_i32 v[128:129], s[24:25], v184, s49, v[148:149]
	v_lshl_add_u64 v[128:129], v[128:129], 0, v[144:145]
	v_lshl_add_u64 v[130:131], v[128:129], 0, s[20:21]
	v_add_co_u32_e32 v128, vcc, 0x1000, v128
	v_or_b32_e32 v186, 32, v146
	s_nop 0
	v_addc_co_u32_e32 v129, vcc, 0, v129, vcc
	global_load_dwordx4 v[160:163], v[128:129], off offset:3584
	global_load_dwordx4 v[164:167], v[130:131], off offset:256
	v_mad_i64_i32 v[128:129], s[24:25], v186, s49, v[148:149]
	v_lshl_add_u64 v[128:129], v[128:129], 0, v[144:145]
	v_lshl_add_u64 v[130:131], v[128:129], 0, s[20:21]
	v_add_co_u32_e32 v128, vcc, 0x1000, v128
	v_or_b32_e32 v150, 48, v146
	s_nop 0
	v_addc_co_u32_e32 v129, vcc, 0, v129, vcc
	global_load_dwordx4 v[140:143], v[128:129], off offset:3584
	global_load_dwordx4 v[136:139], v[130:131], off offset:256
	v_mad_i64_i32 v[128:129], s[24:25], v150, s49, v[148:149]
	v_lshl_add_u64 v[128:129], v[128:129], 0, v[144:145]
	v_lshl_add_u64 v[130:131], v[128:129], 0, s[20:21]
	v_add_co_u32_e32 v128, vcc, 0x1000, v128
	v_ashrrev_i32_e32 v147, 31, v146
	s_nop 0
	v_addc_co_u32_e32 v129, vcc, 0, v129, vcc
	global_load_dwordx4 v[132:135], v[128:129], off offset:3584
	s_nop 0
	global_load_dwordx4 v[128:131], v[130:131], off offset:256
	v_ashrrev_i32_e32 v185, 31, v184
	v_ashrrev_i32_e32 v187, 31, v186
	v_ashrrev_i32_e32 v151, 31, v150
	v_lshlrev_b64 v[188:189], 11, v[146:147]
	s_waitcnt vmcnt(0)
	v_lshlrev_b32_e32 v147, 16, v152
	v_max_f32_e32 v147, v147, v147
	v_max_f32_e32 v190, 0x1e3ce508, v147
	v_and_b32_e32 v147, 0xffff0000, v152
	v_max_f32_e32 v147, v147, v147
	v_max_f32_e32 v191, 0x1e3ce508, v147
	v_lshlrev_b32_e32 v147, 16, v154
	v_max_f32_e32 v147, v147, v147
	v_pk_mul_f32 v[124:125], v[124:125], v[190:191]
	v_max_f32_e32 v190, 0x1e3ce508, v147
	v_and_b32_e32 v147, 0xffff0000, v154
	v_max_f32_e32 v147, v147, v147
	v_max_f32_e32 v191, 0x1e3ce508, v147
	v_pk_mul_f32 v[190:191], v[120:121], v[190:191]
	v_lshlrev_b32_e32 v120, 16, v153
	v_and_b32_e32 v121, 0xffff0000, v153
	v_max_f32_e32 v120, v120, v120
	v_max_f32_e32 v121, v121, v121
	v_max_f32_e32 v120, 0x1e3ce508, v120
	v_max_f32_e32 v121, 0x1e3ce508, v121
	v_pk_mul_f32 v[126:127], v[126:127], v[120:121]
	v_lshlrev_b32_e32 v120, 16, v155
	v_and_b32_e32 v121, 0xffff0000, v155
	v_max_f32_e32 v120, v120, v120
	v_max_f32_e32 v121, v121, v121
	v_max_f32_e32 v120, 0x1e3ce508, v120
	v_max_f32_e32 v121, 0x1e3ce508, v121
	v_pk_mul_f32 v[152:153], v[122:123], v[120:121]
	v_cvt_pk_bf16_f32 v120, v124, v125
	v_lshl_add_u64 v[124:125], s[12:13], 0, v[188:189]
	v_cvt_pk_bf16_f32 v121, v126, v127
	v_cvt_pk_bf16_f32 v122, v190, v191
	v_cvt_pk_bf16_f32 v123, v152, v153
	v_lshl_add_u64 v[124:125], v[124:125], 0, v[144:145]
	global_store_dwordx4 v[124:125], v[120:123], off
	s_nop 1
	v_lshlrev_b32_e32 v120, 16, v156
	v_and_b32_e32 v121, 0xffff0000, v156
	v_max_f32_e32 v120, v120, v120
	v_max_f32_e32 v121, v121, v121
	v_max_f32_e32 v120, 0x1e3ce508, v120
	v_max_f32_e32 v121, 0x1e3ce508, v121
	v_pk_mul_f32 v[116:117], v[116:117], v[120:121]
	v_lshlrev_b32_e32 v120, 16, v158
	v_and_b32_e32 v121, 0xffff0000, v158
	v_max_f32_e32 v120, v120, v120
	v_max_f32_e32 v121, v121, v121
	v_max_f32_e32 v120, 0x1e3ce508, v120
	v_max_f32_e32 v121, 0x1e3ce508, v121
	v_pk_mul_f32 v[120:121], v[112:113], v[120:121]
	v_lshlrev_b32_e32 v112, 16, v157
	v_and_b32_e32 v113, 0xffff0000, v157
	v_max_f32_e32 v112, v112, v112
	v_max_f32_e32 v113, v113, v113
	v_max_f32_e32 v112, 0x1e3ce508, v112
	v_max_f32_e32 v113, 0x1e3ce508, v113
	v_pk_mul_f32 v[118:119], v[118:119], v[112:113]
	v_lshlrev_b32_e32 v112, 16, v159
	v_and_b32_e32 v113, 0xffff0000, v159
	v_max_f32_e32 v112, v112, v112
	v_max_f32_e32 v113, v113, v113
	v_max_f32_e32 v112, 0x1e3ce508, v112
	v_max_f32_e32 v113, 0x1e3ce508, v113
	v_pk_mul_f32 v[122:123], v[114:115], v[112:113]
	v_cvt_pk_bf16_f32 v112, v116, v117
	v_cvt_pk_bf16_f32 v113, v118, v119
	v_cvt_pk_bf16_f32 v114, v120, v121
	v_cvt_pk_bf16_f32 v115, v122, v123
	global_store_dwordx4 v[124:125], v[112:115], off offset:256
	s_nop 1
	v_lshlrev_b32_e32 v114, 16, v160
	v_and_b32_e32 v115, 0xffff0000, v160
	v_max_f32_e32 v114, v114, v114
	v_max_f32_e32 v115, v115, v115
	v_max_f32_e32 v114, 0x1e3ce508, v114
	v_max_f32_e32 v115, 0x1e3ce508, v115
	v_pk_mul_f32 v[108:109], v[108:109], v[114:115]
	v_lshlrev_b32_e32 v114, 16, v162
	v_and_b32_e32 v115, 0xffff0000, v162
	v_max_f32_e32 v114, v114, v114
	v_max_f32_e32 v115, v115, v115
	v_max_f32_e32 v114, 0x1e3ce508, v114
	v_max_f32_e32 v115, 0x1e3ce508, v115
	v_pk_mul_f32 v[114:115], v[104:105], v[114:115]
	v_lshlrev_b32_e32 v104, 16, v161
	v_and_b32_e32 v105, 0xffff0000, v161
	v_max_f32_e32 v104, v104, v104
	v_max_f32_e32 v105, v105, v105
	v_max_f32_e32 v104, 0x1e3ce508, v104
	v_max_f32_e32 v105, 0x1e3ce508, v105
	v_pk_mul_f32 v[110:111], v[110:111], v[104:105]
	v_lshlrev_b32_e32 v104, 16, v163
	v_and_b32_e32 v105, 0xffff0000, v163
	v_max_f32_e32 v104, v104, v104
	v_max_f32_e32 v105, v105, v105
	v_lshlrev_b64 v[112:113], 11, v[184:185]
	v_max_f32_e32 v104, 0x1e3ce508, v104
	v_max_f32_e32 v105, 0x1e3ce508, v105
	v_pk_mul_f32 v[116:117], v[106:107], v[104:105]
	v_cvt_pk_bf16_f32 v104, v108, v109
	v_lshl_add_u64 v[108:109], s[12:13], 0, v[112:113]
	v_cvt_pk_bf16_f32 v105, v110, v111
	v_cvt_pk_bf16_f32 v106, v114, v115
	v_cvt_pk_bf16_f32 v107, v116, v117
	v_lshl_add_u64 v[108:109], v[108:109], 0, v[144:145]
	global_store_dwordx4 v[108:109], v[104:107], off
	s_nop 1
	v_lshlrev_b32_e32 v104, 16, v164
	v_and_b32_e32 v105, 0xffff0000, v164
	v_max_f32_e32 v104, v104, v104
	v_max_f32_e32 v105, v105, v105
	v_max_f32_e32 v104, 0x1e3ce508, v104
	v_max_f32_e32 v105, 0x1e3ce508, v105
	v_pk_mul_f32 v[100:101], v[100:101], v[104:105]
	v_lshlrev_b32_e32 v104, 16, v166
	v_and_b32_e32 v105, 0xffff0000, v166
	v_max_f32_e32 v104, v104, v104
	v_max_f32_e32 v105, v105, v105
	v_max_f32_e32 v104, 0x1e3ce508, v104
	v_max_f32_e32 v105, 0x1e3ce508, v105
	v_pk_mul_f32 v[104:105], v[96:97], v[104:105]
	v_lshlrev_b32_e32 v96, 16, v165
	v_and_b32_e32 v97, 0xffff0000, v165
	v_max_f32_e32 v96, v96, v96
	v_max_f32_e32 v97, v97, v97
	v_max_f32_e32 v96, 0x1e3ce508, v96
	v_max_f32_e32 v97, 0x1e3ce508, v97
	v_pk_mul_f32 v[102:103], v[102:103], v[96:97]
	v_lshlrev_b32_e32 v96, 16, v167
	v_and_b32_e32 v97, 0xffff0000, v167
	v_max_f32_e32 v96, v96, v96
	v_max_f32_e32 v97, v97, v97
	v_max_f32_e32 v96, 0x1e3ce508, v96
	v_max_f32_e32 v97, 0x1e3ce508, v97
	v_pk_mul_f32 v[106:107], v[98:99], v[96:97]
	v_cvt_pk_bf16_f32 v96, v100, v101
	v_cvt_pk_bf16_f32 v97, v102, v103
	v_cvt_pk_bf16_f32 v98, v104, v105
	v_cvt_pk_bf16_f32 v99, v106, v107
	global_store_dwordx4 v[108:109], v[96:99], off offset:256
	s_nop 1
	v_lshlrev_b32_e32 v98, 16, v140
	v_and_b32_e32 v99, 0xffff0000, v140
	v_max_f32_e32 v98, v98, v98
	v_max_f32_e32 v99, v99, v99
	v_max_f32_e32 v98, 0x1e3ce508, v98
	v_max_f32_e32 v99, 0x1e3ce508, v99
	v_pk_mul_f32 v[92:93], v[92:93], v[98:99]
	v_lshlrev_b32_e32 v98, 16, v142
	v_and_b32_e32 v99, 0xffff0000, v142
	v_max_f32_e32 v98, v98, v98
	v_max_f32_e32 v99, v99, v99
	v_max_f32_e32 v98, 0x1e3ce508, v98
	v_max_f32_e32 v99, 0x1e3ce508, v99
	v_pk_mul_f32 v[98:99], v[88:89], v[98:99]
	v_lshlrev_b32_e32 v88, 16, v141
	v_and_b32_e32 v89, 0xffff0000, v141
	v_max_f32_e32 v88, v88, v88
	v_max_f32_e32 v89, v89, v89
	v_max_f32_e32 v88, 0x1e3ce508, v88
	v_max_f32_e32 v89, 0x1e3ce508, v89
	v_pk_mul_f32 v[94:95], v[94:95], v[88:89]
	v_lshlrev_b32_e32 v88, 16, v143
	v_and_b32_e32 v89, 0xffff0000, v143
	v_max_f32_e32 v88, v88, v88
	v_max_f32_e32 v89, v89, v89
	v_lshlrev_b64 v[96:97], 11, v[186:187]
	v_max_f32_e32 v88, 0x1e3ce508, v88
	v_max_f32_e32 v89, 0x1e3ce508, v89
	v_pk_mul_f32 v[100:101], v[90:91], v[88:89]
	v_cvt_pk_bf16_f32 v88, v92, v93
	v_lshl_add_u64 v[92:93], s[12:13], 0, v[96:97]
	v_cvt_pk_bf16_f32 v89, v94, v95
	v_cvt_pk_bf16_f32 v90, v98, v99
	v_cvt_pk_bf16_f32 v91, v100, v101
	v_lshl_add_u64 v[92:93], v[92:93], 0, v[144:145]
	global_store_dwordx4 v[92:93], v[88:91], off
	s_nop 1
	v_lshlrev_b32_e32 v88, 16, v136
	v_and_b32_e32 v89, 0xffff0000, v136
	v_max_f32_e32 v88, v88, v88
	v_max_f32_e32 v89, v89, v89
	v_max_f32_e32 v88, 0x1e3ce508, v88
	v_max_f32_e32 v89, 0x1e3ce508, v89
	v_pk_mul_f32 v[84:85], v[84:85], v[88:89]
	v_lshlrev_b32_e32 v88, 16, v138
	v_and_b32_e32 v89, 0xffff0000, v138
	v_max_f32_e32 v88, v88, v88
	v_max_f32_e32 v89, v89, v89
	v_max_f32_e32 v88, 0x1e3ce508, v88
	v_max_f32_e32 v89, 0x1e3ce508, v89
	v_pk_mul_f32 v[88:89], v[80:81], v[88:89]
	v_lshlrev_b32_e32 v80, 16, v137
	v_and_b32_e32 v81, 0xffff0000, v137
	v_max_f32_e32 v80, v80, v80
	v_max_f32_e32 v81, v81, v81
	v_max_f32_e32 v80, 0x1e3ce508, v80
	v_max_f32_e32 v81, 0x1e3ce508, v81
	v_pk_mul_f32 v[86:87], v[86:87], v[80:81]
	v_lshlrev_b32_e32 v80, 16, v139
	v_and_b32_e32 v81, 0xffff0000, v139
	v_max_f32_e32 v80, v80, v80
	v_max_f32_e32 v81, v81, v81
	v_max_f32_e32 v80, 0x1e3ce508, v80
	v_max_f32_e32 v81, 0x1e3ce508, v81
	v_pk_mul_f32 v[90:91], v[82:83], v[80:81]
	v_cvt_pk_bf16_f32 v80, v84, v85
	v_cvt_pk_bf16_f32 v81, v86, v87
	v_cvt_pk_bf16_f32 v82, v88, v89
	v_cvt_pk_bf16_f32 v83, v90, v91
	global_store_dwordx4 v[92:93], v[80:83], off offset:256
	s_nop 1
	v_lshlrev_b32_e32 v82, 16, v132
	v_and_b32_e32 v83, 0xffff0000, v132
	v_max_f32_e32 v82, v82, v82
	v_max_f32_e32 v83, v83, v83
	v_max_f32_e32 v82, 0x1e3ce508, v82
	v_max_f32_e32 v83, 0x1e3ce508, v83
	v_pk_mul_f32 v[76:77], v[76:77], v[82:83]
	v_lshlrev_b32_e32 v82, 16, v134
	v_and_b32_e32 v83, 0xffff0000, v134
	v_max_f32_e32 v82, v82, v82
	v_max_f32_e32 v83, v83, v83
	v_max_f32_e32 v82, 0x1e3ce508, v82
	v_max_f32_e32 v83, 0x1e3ce508, v83
	v_pk_mul_f32 v[82:83], v[72:73], v[82:83]
	v_lshlrev_b32_e32 v72, 16, v133
	v_and_b32_e32 v73, 0xffff0000, v133
	v_max_f32_e32 v72, v72, v72
	v_max_f32_e32 v73, v73, v73
	v_max_f32_e32 v72, 0x1e3ce508, v72
	v_max_f32_e32 v73, 0x1e3ce508, v73
	v_pk_mul_f32 v[78:79], v[78:79], v[72:73]
	v_lshlrev_b32_e32 v72, 16, v135
	v_and_b32_e32 v73, 0xffff0000, v135
	v_max_f32_e32 v72, v72, v72
	v_max_f32_e32 v73, v73, v73
	v_lshlrev_b64 v[80:81], 11, v[150:151]
	v_max_f32_e32 v72, 0x1e3ce508, v72
	v_max_f32_e32 v73, 0x1e3ce508, v73
	v_pk_mul_f32 v[84:85], v[74:75], v[72:73]
	v_cvt_pk_bf16_f32 v72, v76, v77
	v_lshl_add_u64 v[76:77], s[12:13], 0, v[80:81]
	v_cvt_pk_bf16_f32 v73, v78, v79
	v_cvt_pk_bf16_f32 v74, v82, v83
	v_cvt_pk_bf16_f32 v75, v84, v85
	v_lshl_add_u64 v[76:77], v[76:77], 0, v[144:145]
	global_store_dwordx4 v[76:77], v[72:75], off
	s_nop 1
	v_lshlrev_b32_e32 v72, 16, v128
	v_and_b32_e32 v73, 0xffff0000, v128
	v_max_f32_e32 v72, v72, v72
	v_max_f32_e32 v73, v73, v73
	v_max_f32_e32 v72, 0x1e3ce508, v72
	v_max_f32_e32 v73, 0x1e3ce508, v73
	v_pk_mul_f32 v[68:69], v[68:69], v[72:73]
	v_lshlrev_b32_e32 v72, 16, v130
	v_and_b32_e32 v73, 0xffff0000, v130
	v_max_f32_e32 v72, v72, v72
	v_max_f32_e32 v73, v73, v73
	v_max_f32_e32 v72, 0x1e3ce508, v72
	v_max_f32_e32 v73, 0x1e3ce508, v73
	v_pk_mul_f32 v[72:73], v[64:65], v[72:73]
	v_lshlrev_b32_e32 v64, 16, v129
	v_and_b32_e32 v65, 0xffff0000, v129
	v_max_f32_e32 v64, v64, v64
	v_max_f32_e32 v65, v65, v65
	v_max_f32_e32 v64, 0x1e3ce508, v64
	v_max_f32_e32 v65, 0x1e3ce508, v65
	v_pk_mul_f32 v[70:71], v[70:71], v[64:65]
	v_lshlrev_b32_e32 v64, 16, v131
	v_and_b32_e32 v65, 0xffff0000, v131
	v_max_f32_e32 v64, v64, v64
	v_max_f32_e32 v65, v65, v65
	v_max_f32_e32 v64, 0x1e3ce508, v64
	v_max_f32_e32 v65, 0x1e3ce508, v65
	v_pk_mul_f32 v[74:75], v[66:67], v[64:65]
	v_cvt_pk_bf16_f32 v64, v68, v69
	v_cvt_pk_bf16_f32 v65, v70, v71
	v_cvt_pk_bf16_f32 v66, v72, v73
	v_cvt_pk_bf16_f32 v67, v74, v75
	global_store_dwordx4 v[76:77], v[64:67], off offset:256
	v_add_u32_e32 v98, 0x80, v146
	s_nop 0
	v_mad_i64_i32 v[64:65], s[24:25], v98, s49, v[148:149]
	v_lshl_add_u64 v[64:65], v[64:65], 0, v[144:145]
	v_lshl_add_u64 v[66:67], v[64:65], 0, s[20:21]
	v_add_co_u32_e32 v64, vcc, s52, v64
	v_add_u32_e32 v100, 0x90, v146
	s_nop 0
	v_addc_co_u32_e32 v65, vcc, 0, v65, vcc
	global_load_dwordx4 v[82:85], v[64:65], off offset:3584
	global_load_dwordx4 v[86:89], v[66:67], off offset:256
	v_mad_i64_i32 v[64:65], s[24:25], v100, s49, v[148:149]
	v_lshl_add_u64 v[64:65], v[64:65], 0, v[144:145]
	v_lshl_add_u64 v[66:67], v[64:65], 0, s[20:21]
	v_add_co_u32_e32 v64, vcc, s52, v64
	v_add_u32_e32 v102, 0xa0, v146
	s_nop 0
	v_addc_co_u32_e32 v65, vcc, 0, v65, vcc
	global_load_dwordx4 v[90:93], v[64:65], off offset:3584
	global_load_dwordx4 v[94:97], v[66:67], off offset:256
	v_mad_i64_i32 v[64:65], s[24:25], v102, s49, v[148:149]
	v_lshl_add_u64 v[64:65], v[64:65], 0, v[144:145]
	v_lshl_add_u64 v[66:67], v[64:65], 0, s[20:21]
	v_add_co_u32_e32 v64, vcc, s52, v64
	v_add_u32_e32 v80, 0xb0, v146
	s_nop 0
	v_addc_co_u32_e32 v65, vcc, 0, v65, vcc
	global_load_dwordx4 v[76:79], v[64:65], off offset:3584
	global_load_dwordx4 v[72:75], v[66:67], off offset:256
	v_mad_i64_i32 v[64:65], s[24:25], v80, s49, v[148:149]
	v_lshl_add_u64 v[64:65], v[64:65], 0, v[144:145]
	v_lshl_add_u64 v[66:67], v[64:65], 0, s[20:21]
	v_add_co_u32_e32 v64, vcc, s52, v64
	v_ashrrev_i32_e32 v99, 31, v98
	s_nop 0
	v_addc_co_u32_e32 v65, vcc, 0, v65, vcc
	global_load_dwordx4 v[68:71], v[64:65], off offset:3584
	s_nop 0
	global_load_dwordx4 v[64:67], v[66:67], off offset:256
	v_ashrrev_i32_e32 v101, 31, v100
	v_ashrrev_i32_e32 v103, 31, v102
	v_ashrrev_i32_e32 v81, 31, v80
	s_waitcnt vmcnt(7)
	v_lshlrev_b32_e32 v104, 16, v82
	v_and_b32_e32 v82, 0xffff0000, v82
	v_max_f32_e32 v82, v82, v82
	v_max_f32_e32 v104, v104, v104
	v_max_f32_e32 v105, 0x1e3ce508, v82
	v_lshlrev_b32_e32 v82, 16, v84
	v_max_f32_e32 v104, 0x1e3ce508, v104
	v_max_f32_e32 v82, v82, v82
	v_pk_mul_f32 v[60:61], v[60:61], v[104:105]
	v_max_f32_e32 v104, 0x1e3ce508, v82
	v_and_b32_e32 v82, 0xffff0000, v84
	v_max_f32_e32 v82, v82, v82
	v_max_f32_e32 v105, 0x1e3ce508, v82
	v_pk_mul_f32 v[104:105], v[56:57], v[104:105]
	v_lshlrev_b32_e32 v56, 16, v83
	v_and_b32_e32 v57, 0xffff0000, v83
	v_max_f32_e32 v56, v56, v56
	v_max_f32_e32 v57, v57, v57
	v_max_f32_e32 v56, 0x1e3ce508, v56
	v_max_f32_e32 v57, 0x1e3ce508, v57
	v_pk_mul_f32 v[62:63], v[62:63], v[56:57]
	v_lshlrev_b32_e32 v56, 16, v85
	v_and_b32_e32 v57, 0xffff0000, v85
	v_max_f32_e32 v56, v56, v56
	v_max_f32_e32 v57, v57, v57
	v_lshlrev_b64 v[98:99], 11, v[98:99]
	v_max_f32_e32 v56, 0x1e3ce508, v56
	v_max_f32_e32 v57, 0x1e3ce508, v57
	v_pk_mul_f32 v[82:83], v[58:59], v[56:57]
	v_cvt_pk_bf16_f32 v56, v60, v61
	v_lshl_add_u64 v[60:61], s[12:13], 0, v[98:99]
	v_cvt_pk_bf16_f32 v57, v62, v63
	v_cvt_pk_bf16_f32 v58, v104, v105
	v_cvt_pk_bf16_f32 v59, v82, v83
	v_lshl_add_u64 v[60:61], v[60:61], 0, v[144:145]
	global_store_dwordx4 v[60:61], v[56:59], off
	s_waitcnt vmcnt(7)
	s_nop 0
	v_lshlrev_b32_e32 v56, 16, v86
	v_and_b32_e32 v57, 0xffff0000, v86
	v_max_f32_e32 v56, v56, v56
	v_max_f32_e32 v57, v57, v57
	v_max_f32_e32 v56, 0x1e3ce508, v56
	v_max_f32_e32 v57, 0x1e3ce508, v57
	v_pk_mul_f32 v[52:53], v[52:53], v[56:57]
	v_lshlrev_b32_e32 v56, 16, v88
	v_and_b32_e32 v57, 0xffff0000, v88
	v_max_f32_e32 v56, v56, v56
	v_max_f32_e32 v57, v57, v57
	v_max_f32_e32 v56, 0x1e3ce508, v56
	v_max_f32_e32 v57, 0x1e3ce508, v57
	v_pk_mul_f32 v[56:57], v[48:49], v[56:57]
	v_lshlrev_b32_e32 v48, 16, v87
	v_and_b32_e32 v49, 0xffff0000, v87
	v_max_f32_e32 v48, v48, v48
	v_max_f32_e32 v49, v49, v49
	v_max_f32_e32 v48, 0x1e3ce508, v48
	v_max_f32_e32 v49, 0x1e3ce508, v49
	v_pk_mul_f32 v[54:55], v[54:55], v[48:49]
	v_lshlrev_b32_e32 v48, 16, v89
	v_and_b32_e32 v49, 0xffff0000, v89
	v_max_f32_e32 v48, v48, v48
	v_max_f32_e32 v49, v49, v49
	v_max_f32_e32 v48, 0x1e3ce508, v48
	v_max_f32_e32 v49, 0x1e3ce508, v49
	v_pk_mul_f32 v[58:59], v[50:51], v[48:49]
	v_cvt_pk_bf16_f32 v48, v52, v53
	v_cvt_pk_bf16_f32 v49, v54, v55
	v_cvt_pk_bf16_f32 v50, v56, v57
	v_cvt_pk_bf16_f32 v51, v58, v59
	global_store_dwordx4 v[60:61], v[48:51], off offset:256
	s_waitcnt vmcnt(7)
	s_nop 0
	v_lshlrev_b32_e32 v50, 16, v90
	v_and_b32_e32 v51, 0xffff0000, v90
	v_max_f32_e32 v50, v50, v50
	v_max_f32_e32 v51, v51, v51
	v_max_f32_e32 v50, 0x1e3ce508, v50
	v_max_f32_e32 v51, 0x1e3ce508, v51
	v_pk_mul_f32 v[44:45], v[44:45], v[50:51]
	v_lshlrev_b32_e32 v50, 16, v92
	v_and_b32_e32 v51, 0xffff0000, v92
	v_max_f32_e32 v50, v50, v50
	v_max_f32_e32 v51, v51, v51
	v_max_f32_e32 v50, 0x1e3ce508, v50
	v_max_f32_e32 v51, 0x1e3ce508, v51
	v_pk_mul_f32 v[50:51], v[40:41], v[50:51]
	v_lshlrev_b32_e32 v40, 16, v91
	v_and_b32_e32 v41, 0xffff0000, v91
	v_max_f32_e32 v40, v40, v40
	v_max_f32_e32 v41, v41, v41
	v_max_f32_e32 v40, 0x1e3ce508, v40
	v_max_f32_e32 v41, 0x1e3ce508, v41
	v_pk_mul_f32 v[46:47], v[46:47], v[40:41]
	v_lshlrev_b32_e32 v40, 16, v93
	v_and_b32_e32 v41, 0xffff0000, v93
	v_max_f32_e32 v40, v40, v40
	v_max_f32_e32 v41, v41, v41
	v_lshlrev_b64 v[48:49], 11, v[100:101]
	v_max_f32_e32 v40, 0x1e3ce508, v40
	v_max_f32_e32 v41, 0x1e3ce508, v41
	v_pk_mul_f32 v[52:53], v[42:43], v[40:41]
	v_cvt_pk_bf16_f32 v40, v44, v45
	v_lshl_add_u64 v[44:45], s[12:13], 0, v[48:49]
	v_cvt_pk_bf16_f32 v41, v46, v47
	v_cvt_pk_bf16_f32 v42, v50, v51
	v_cvt_pk_bf16_f32 v43, v52, v53
	v_lshl_add_u64 v[44:45], v[44:45], 0, v[144:145]
	global_store_dwordx4 v[44:45], v[40:43], off
	s_waitcnt vmcnt(7)
	s_nop 0
	v_lshlrev_b32_e32 v40, 16, v94
	v_and_b32_e32 v41, 0xffff0000, v94
	v_max_f32_e32 v40, v40, v40
	v_max_f32_e32 v41, v41, v41
	v_max_f32_e32 v40, 0x1e3ce508, v40
	v_max_f32_e32 v41, 0x1e3ce508, v41
	v_pk_mul_f32 v[36:37], v[36:37], v[40:41]
	v_lshlrev_b32_e32 v40, 16, v96
	v_and_b32_e32 v41, 0xffff0000, v96
	v_max_f32_e32 v40, v40, v40
	v_max_f32_e32 v41, v41, v41
	v_max_f32_e32 v40, 0x1e3ce508, v40
	v_max_f32_e32 v41, 0x1e3ce508, v41
	v_pk_mul_f32 v[40:41], v[32:33], v[40:41]
	v_lshlrev_b32_e32 v32, 16, v95
	v_and_b32_e32 v33, 0xffff0000, v95
	v_max_f32_e32 v32, v32, v32
	v_max_f32_e32 v33, v33, v33
	v_max_f32_e32 v32, 0x1e3ce508, v32
	v_max_f32_e32 v33, 0x1e3ce508, v33
	v_pk_mul_f32 v[38:39], v[38:39], v[32:33]
	v_lshlrev_b32_e32 v32, 16, v97
	v_and_b32_e32 v33, 0xffff0000, v97
	v_max_f32_e32 v32, v32, v32
	v_max_f32_e32 v33, v33, v33
	v_max_f32_e32 v32, 0x1e3ce508, v32
	v_max_f32_e32 v33, 0x1e3ce508, v33
	v_pk_mul_f32 v[42:43], v[34:35], v[32:33]
	v_cvt_pk_bf16_f32 v32, v36, v37
	v_cvt_pk_bf16_f32 v33, v38, v39
	v_cvt_pk_bf16_f32 v34, v40, v41
	v_cvt_pk_bf16_f32 v35, v42, v43
	global_store_dwordx4 v[44:45], v[32:35], off offset:256
	s_waitcnt vmcnt(7)
	s_nop 0
	v_lshlrev_b32_e32 v34, 16, v76
	v_and_b32_e32 v35, 0xffff0000, v76
	v_max_f32_e32 v34, v34, v34
	v_max_f32_e32 v35, v35, v35
	v_max_f32_e32 v34, 0x1e3ce508, v34
	v_max_f32_e32 v35, 0x1e3ce508, v35
	v_pk_mul_f32 v[28:29], v[28:29], v[34:35]
	v_lshlrev_b32_e32 v34, 16, v78
	v_and_b32_e32 v35, 0xffff0000, v78
	v_max_f32_e32 v34, v34, v34
	v_max_f32_e32 v35, v35, v35
	v_max_f32_e32 v34, 0x1e3ce508, v34
	v_max_f32_e32 v35, 0x1e3ce508, v35
	v_pk_mul_f32 v[34:35], v[24:25], v[34:35]
	v_lshlrev_b32_e32 v24, 16, v77
	v_and_b32_e32 v25, 0xffff0000, v77
	v_max_f32_e32 v24, v24, v24
	v_max_f32_e32 v25, v25, v25
	v_max_f32_e32 v24, 0x1e3ce508, v24
	v_max_f32_e32 v25, 0x1e3ce508, v25
	v_pk_mul_f32 v[30:31], v[30:31], v[24:25]
	v_lshlrev_b32_e32 v24, 16, v79
	v_and_b32_e32 v25, 0xffff0000, v79
	v_max_f32_e32 v24, v24, v24
	v_max_f32_e32 v25, v25, v25
	v_lshlrev_b64 v[32:33], 11, v[102:103]
	v_max_f32_e32 v24, 0x1e3ce508, v24
	v_max_f32_e32 v25, 0x1e3ce508, v25
	v_pk_mul_f32 v[36:37], v[26:27], v[24:25]
	v_cvt_pk_bf16_f32 v24, v28, v29
	v_lshl_add_u64 v[28:29], s[12:13], 0, v[32:33]
	v_cvt_pk_bf16_f32 v25, v30, v31
	v_cvt_pk_bf16_f32 v26, v34, v35
	v_cvt_pk_bf16_f32 v27, v36, v37
	v_lshl_add_u64 v[28:29], v[28:29], 0, v[144:145]
	global_store_dwordx4 v[28:29], v[24:27], off
	s_waitcnt vmcnt(7)
	s_nop 0
	v_lshlrev_b32_e32 v24, 16, v72
	v_and_b32_e32 v25, 0xffff0000, v72
	v_max_f32_e32 v24, v24, v24
	v_max_f32_e32 v25, v25, v25
	v_max_f32_e32 v24, 0x1e3ce508, v24
	v_max_f32_e32 v25, 0x1e3ce508, v25
	v_pk_mul_f32 v[20:21], v[20:21], v[24:25]
	v_lshlrev_b32_e32 v24, 16, v74
	v_and_b32_e32 v25, 0xffff0000, v74
	v_max_f32_e32 v24, v24, v24
	v_max_f32_e32 v25, v25, v25
	v_max_f32_e32 v24, 0x1e3ce508, v24
	v_max_f32_e32 v25, 0x1e3ce508, v25
	v_pk_mul_f32 v[24:25], v[16:17], v[24:25]
	v_lshlrev_b32_e32 v16, 16, v73
	v_and_b32_e32 v17, 0xffff0000, v73
	v_max_f32_e32 v16, v16, v16
	v_max_f32_e32 v17, v17, v17
	v_max_f32_e32 v16, 0x1e3ce508, v16
	v_max_f32_e32 v17, 0x1e3ce508, v17
	v_pk_mul_f32 v[22:23], v[22:23], v[16:17]
	v_lshlrev_b32_e32 v16, 16, v75
	v_and_b32_e32 v17, 0xffff0000, v75
	v_max_f32_e32 v16, v16, v16
	v_max_f32_e32 v17, v17, v17
	v_max_f32_e32 v16, 0x1e3ce508, v16
	v_max_f32_e32 v17, 0x1e3ce508, v17
	v_pk_mul_f32 v[26:27], v[18:19], v[16:17]
	v_cvt_pk_bf16_f32 v16, v20, v21
	v_cvt_pk_bf16_f32 v17, v22, v23
	v_cvt_pk_bf16_f32 v18, v24, v25
	v_cvt_pk_bf16_f32 v19, v26, v27
	global_store_dwordx4 v[28:29], v[16:19], off offset:256
	s_waitcnt vmcnt(7)
	s_nop 0
	v_lshlrev_b32_e32 v18, 16, v68
	v_and_b32_e32 v19, 0xffff0000, v68
	v_max_f32_e32 v18, v18, v18
	v_max_f32_e32 v19, v19, v19
	v_max_f32_e32 v18, 0x1e3ce508, v18
	v_max_f32_e32 v19, 0x1e3ce508, v19
	v_pk_mul_f32 v[12:13], v[12:13], v[18:19]
	v_lshlrev_b32_e32 v18, 16, v70
	v_and_b32_e32 v19, 0xffff0000, v70
	v_max_f32_e32 v18, v18, v18
	v_max_f32_e32 v19, v19, v19
	v_max_f32_e32 v18, 0x1e3ce508, v18
	v_max_f32_e32 v19, 0x1e3ce508, v19
	v_pk_mul_f32 v[18:19], v[8:9], v[18:19]
	v_lshlrev_b32_e32 v8, 16, v69
	v_and_b32_e32 v9, 0xffff0000, v69
	v_max_f32_e32 v8, v8, v8
	v_max_f32_e32 v9, v9, v9
	v_max_f32_e32 v8, 0x1e3ce508, v8
	v_max_f32_e32 v9, 0x1e3ce508, v9
	v_pk_mul_f32 v[14:15], v[14:15], v[8:9]
	v_lshlrev_b32_e32 v8, 16, v71
	v_and_b32_e32 v9, 0xffff0000, v71
	v_max_f32_e32 v8, v8, v8
	v_max_f32_e32 v9, v9, v9
	v_lshlrev_b64 v[16:17], 11, v[80:81]
	v_max_f32_e32 v8, 0x1e3ce508, v8
	v_max_f32_e32 v9, 0x1e3ce508, v9
	v_pk_mul_f32 v[20:21], v[10:11], v[8:9]
	v_cvt_pk_bf16_f32 v8, v12, v13
	v_lshl_add_u64 v[12:13], s[12:13], 0, v[16:17]
	v_cvt_pk_bf16_f32 v9, v14, v15
	v_cvt_pk_bf16_f32 v10, v18, v19
	v_cvt_pk_bf16_f32 v11, v20, v21
	v_lshl_add_u64 v[12:13], v[12:13], 0, v[144:145]
	global_store_dwordx4 v[12:13], v[8:11], off
	s_waitcnt vmcnt(7)
	s_nop 0
	v_lshlrev_b32_e32 v8, 16, v64
	v_and_b32_e32 v9, 0xffff0000, v64
	v_max_f32_e32 v8, v8, v8
	v_max_f32_e32 v9, v9, v9
	v_max_f32_e32 v8, 0x1e3ce508, v8
	v_max_f32_e32 v9, 0x1e3ce508, v9
	v_pk_mul_f32 v[4:5], v[4:5], v[8:9]
	v_lshlrev_b32_e32 v8, 16, v66
	v_and_b32_e32 v9, 0xffff0000, v66
	v_max_f32_e32 v8, v8, v8
	v_max_f32_e32 v9, v9, v9
	v_max_f32_e32 v8, 0x1e3ce508, v8
	v_max_f32_e32 v9, 0x1e3ce508, v9
	v_pk_mul_f32 v[8:9], v[0:1], v[8:9]
	v_lshlrev_b32_e32 v0, 16, v65
	v_and_b32_e32 v1, 0xffff0000, v65
	v_max_f32_e32 v0, v0, v0
	v_max_f32_e32 v1, v1, v1
	v_max_f32_e32 v0, 0x1e3ce508, v0
	v_max_f32_e32 v1, 0x1e3ce508, v1
	v_pk_mul_f32 v[6:7], v[6:7], v[0:1]
	v_lshlrev_b32_e32 v0, 16, v67
	v_and_b32_e32 v1, 0xffff0000, v67
	v_max_f32_e32 v0, v0, v0
	v_max_f32_e32 v1, v1, v1
	v_max_f32_e32 v0, 0x1e3ce508, v0
	v_max_f32_e32 v1, 0x1e3ce508, v1
	v_pk_mul_f32 v[10:11], v[2:3], v[0:1]
	v_cvt_pk_bf16_f32 v0, v4, v5
	v_cvt_pk_bf16_f32 v1, v6, v7
	v_cvt_pk_bf16_f32 v2, v8, v9
	v_cvt_pk_bf16_f32 v3, v10, v11
	global_store_dwordx4 v[12:13], v[0:3], off offset:256
	s_and_b64 vcc, exec, s[2:3]
	s_mov_b64 s[2:3], -1
	s_cbranch_vccnz .LBB0_991
	s_andn2_b64 vcc, exec, s[8:9]
	s_cbranch_vccnz .LBB0_990
	v_writelane_b32 v255, 1, 53
	s_branch .LBB0_990

.LBB0_1087:
	s_ashr_i32 s13, s12, 31
	s_lshl_b64 s[14:15], s[12:13], 19
	s_add_u32 s14, s34, s14
	s_addc_u32 s15, s35, s15
	s_and_b64 s[16:17], s[2:3], exec
	s_cselect_b32 s13, s15, s21
	s_cselect_b32 s50, s14, s20
	s_ashr_i32 s11, s10, 31
	s_lshl_b64 s[16:17], s[10:11], 19
	s_add_u32 s16, s36, s16
	s_addc_u32 s17, s37, s17
	s_and_b64 s[24:25], s[2:3], exec
	s_cselect_b32 s11, s17, s23
	s_cselect_b32 s51, s16, s22
	s_add_u32 s20, s20, 0x40080
	s_addc_u32 s21, s21, 0
	s_add_u32 s52, s22, 0x100
	v_mov_b32_e32 v0, 0
	s_addc_u32 s53, s23, 0
	s_mov_b32 s54, -2
	v_mov_b32_e32 v1, v0
	v_mov_b32_e32 v2, v0
	v_mov_b32_e32 v3, v0
	v_mov_b32_e32 v4, v0
	v_mov_b32_e32 v5, v0
	v_mov_b32_e32 v6, v0
	v_mov_b32_e32 v7, v0
	v_mov_b32_e32 v8, v0
	v_mov_b32_e32 v9, v0
	v_mov_b32_e32 v10, v0
	v_mov_b32_e32 v11, v0
	v_mov_b32_e32 v16, v0
	v_mov_b32_e32 v17, v0
	v_mov_b32_e32 v18, v0
	v_mov_b32_e32 v19, v0
	v_mov_b32_e32 v28, v0
	v_mov_b32_e32 v29, v0
	v_mov_b32_e32 v30, v0
	v_mov_b32_e32 v31, v0
	v_mov_b32_e32 v36, v0
	v_mov_b32_e32 v37, v0
	v_mov_b32_e32 v38, v0
	v_mov_b32_e32 v39, v0
	v_mov_b32_e32 v44, v0
	v_mov_b32_e32 v45, v0
	v_mov_b32_e32 v46, v0
	v_mov_b32_e32 v47, v0
	v_mov_b32_e32 v52, v0
	v_mov_b32_e32 v53, v0
	v_mov_b32_e32 v54, v0
	v_mov_b32_e32 v55, v0
	v_mov_b32_e32 v12, v0
	v_mov_b32_e32 v13, v0
	v_mov_b32_e32 v14, v0
	v_mov_b32_e32 v15, v0
	v_mov_b32_e32 v20, v0
	v_mov_b32_e32 v21, v0
	v_mov_b32_e32 v22, v0
	v_mov_b32_e32 v23, v0
	v_mov_b32_e32 v24, v0
	v_mov_b32_e32 v25, v0
	v_mov_b32_e32 v26, v0
	v_mov_b32_e32 v27, v0
	v_mov_b32_e32 v32, v0
	v_mov_b32_e32 v33, v0
	v_mov_b32_e32 v34, v0
	v_mov_b32_e32 v35, v0
	v_mov_b32_e32 v40, v0
	v_mov_b32_e32 v41, v0
	v_mov_b32_e32 v42, v0
	v_mov_b32_e32 v43, v0
	v_mov_b32_e32 v48, v0
	v_mov_b32_e32 v49, v0
	v_mov_b32_e32 v50, v0
	v_mov_b32_e32 v51, v0
	v_mov_b32_e32 v56, v0
	v_mov_b32_e32 v57, v0
	v_mov_b32_e32 v58, v0
	v_mov_b32_e32 v59, v0
	v_mov_b32_e32 v60, v0
	v_mov_b32_e32 v61, v0
	v_mov_b32_e32 v62, v0
	v_mov_b32_e32 v63, v0
	v_mov_b32_e32 v64, v0
	v_mov_b32_e32 v65, v0
	v_mov_b32_e32 v66, v0
	v_mov_b32_e32 v67, v0
	v_mov_b32_e32 v68, v0
	v_mov_b32_e32 v69, v0
	v_mov_b32_e32 v70, v0
	v_mov_b32_e32 v71, v0
	v_mov_b32_e32 v72, v0
	v_mov_b32_e32 v73, v0
	v_mov_b32_e32 v74, v0
	v_mov_b32_e32 v75, v0
	v_mov_b32_e32 v80, v0
	v_mov_b32_e32 v81, v0
	v_mov_b32_e32 v82, v0
	v_mov_b32_e32 v83, v0
	v_mov_b32_e32 v92, v0
	v_mov_b32_e32 v93, v0
	v_mov_b32_e32 v94, v0
	v_mov_b32_e32 v95, v0
	v_mov_b32_e32 v100, v0
	v_mov_b32_e32 v101, v0
	v_mov_b32_e32 v102, v0
	v_mov_b32_e32 v103, v0
	v_mov_b32_e32 v108, v0
	v_mov_b32_e32 v109, v0
	v_mov_b32_e32 v110, v0
	v_mov_b32_e32 v111, v0
	v_mov_b32_e32 v116, v0
	v_mov_b32_e32 v117, v0
	v_mov_b32_e32 v118, v0
	v_mov_b32_e32 v119, v0
	v_mov_b32_e32 v76, v0
	v_mov_b32_e32 v77, v0
	v_mov_b32_e32 v78, v0
	v_mov_b32_e32 v79, v0
	v_mov_b32_e32 v84, v0
	v_mov_b32_e32 v85, v0
	v_mov_b32_e32 v86, v0
	v_mov_b32_e32 v87, v0
	v_mov_b32_e32 v88, v0
	v_mov_b32_e32 v89, v0
	v_mov_b32_e32 v90, v0
	v_mov_b32_e32 v91, v0
	v_mov_b32_e32 v96, v0
	v_mov_b32_e32 v97, v0
	v_mov_b32_e32 v98, v0
	v_mov_b32_e32 v99, v0
	v_mov_b32_e32 v104, v0
	v_mov_b32_e32 v105, v0
	v_mov_b32_e32 v106, v0
	v_mov_b32_e32 v107, v0
	v_mov_b32_e32 v112, v0
	v_mov_b32_e32 v113, v0
	v_mov_b32_e32 v114, v0
	v_mov_b32_e32 v115, v0
	v_mov_b32_e32 v120, v0
	v_mov_b32_e32 v121, v0
	v_mov_b32_e32 v122, v0
	v_mov_b32_e32 v123, v0
	v_mov_b32_e32 v124, v0
	v_mov_b32_e32 v125, v0
	v_mov_b32_e32 v126, v0
	v_mov_b32_e32 v127, v0
	v_readlane_b32 s97, v255, 53
	s_nop 3
	s_cmp_eq_u32 s97, 1
	s_cbranch_scc0 .Llsb_skip_8
	v_writelane_b32 v255, 0, 53
	s_barrier
.Llsb_skip_8:
.LBB0_1088:
	ds_read_b128 v[128:131], v212
	ds_read_b128 v[132:135], v212 offset:1024
	ds_read_b128 v[136:139], v212 offset:2048
	ds_read_b128 v[140:143], v212 offset:3072
	ds_read_b128 v[144:147], v213
	ds_read_b128 v[148:151], v213 offset:1024
	ds_read_b128 v[152:155], v213 offset:2048
	ds_read_b128 v[156:159], v213 offset:3072
	s_add_u32 s22, s20, 0xfffc0080
	s_addc_u32 s23, s21, -1
	s_cmp_eq_u32 s54, 12
	s_cselect_b32 s25, s13, s23
	s_cselect_b32 s24, s50, s22
	s_cselect_b32 s23, s11, s53
	s_cselect_b32 s22, s51, s52
	v_lshl_add_u64 v[202:203], s[20:21], 0, v[182:183]
	s_add_i32 m0, s28, 0xc000
	ds_read_b128 v[160:163], v214
	ds_read_b128 v[164:167], v214 offset:1024
	ds_read_b128 v[168:171], v214 offset:2048
	ds_read_b128 v[172:175], v214 offset:3072
	ds_read_b128 v[190:193], v214 offset:4096
	ds_read_b128 v[194:197], v214 offset:5120
	ds_read_b128 v[198:201], v214 offset:6144
	ds_read_b128 v[216:219], v214 offset:7168
	global_load_lds_dwordx4 v[202:203], off
	v_lshl_add_u64 v[202:203], s[20:21], 0, v[184:185]
	s_add_i32 m0, s28, 0xe000
	s_nop 0
	global_load_lds_dwordx4 v[202:203], off
	s_waitcnt vmcnt(8)
	s_waitcnt lgkmcnt(0)
	s_barrier
	s_setprio 1
	s_waitcnt lgkmcnt(0)
	v_mfma_f32_16x16x32_bf16 v[124:127], v[128:131], v[160:163], v[124:127]
	v_mfma_f32_16x16x32_bf16 v[120:123], v[136:139], v[160:163], v[120:123]
	v_mfma_f32_16x16x32_bf16 v[112:115], v[128:131], v[168:171], v[112:115]
	v_mfma_f32_16x16x32_bf16 v[104:107], v[136:139], v[168:171], v[104:107]
	v_mfma_f32_16x16x32_bf16 v[96:99], v[128:131], v[190:193], v[96:99]
	v_mfma_f32_16x16x32_bf16 v[88:91], v[136:139], v[190:193], v[88:91]
	v_mfma_f32_16x16x32_bf16 v[84:87], v[128:131], v[198:201], v[84:87]
	v_mfma_f32_16x16x32_bf16 v[76:79], v[136:139], v[198:201], v[76:79]
	v_mfma_f32_16x16x32_bf16 v[124:127], v[132:135], v[164:167], v[124:127]
	v_mfma_f32_16x16x32_bf16 v[120:123], v[140:143], v[164:167], v[120:123]
	v_mfma_f32_16x16x32_bf16 v[112:115], v[132:135], v[172:175], v[112:115]
	v_mfma_f32_16x16x32_bf16 v[104:107], v[140:143], v[172:175], v[104:107]
	v_mfma_f32_16x16x32_bf16 v[96:99], v[132:135], v[194:197], v[96:99]
	v_mfma_f32_16x16x32_bf16 v[88:91], v[140:143], v[194:197], v[88:91]
	v_mfma_f32_16x16x32_bf16 v[84:87], v[132:135], v[216:219], v[84:87]
	v_mfma_f32_16x16x32_bf16 v[76:79], v[140:143], v[216:219], v[76:79]
	s_setprio 0
	s_setprio 1
	v_mfma_f32_16x16x32_bf16 v[116:119], v[144:147], v[160:163], v[116:119]
	v_mfma_f32_16x16x32_bf16 v[108:111], v[152:155], v[160:163], v[108:111]
	v_mfma_f32_16x16x32_bf16 v[100:103], v[144:147], v[168:171], v[100:103]
	v_mfma_f32_16x16x32_bf16 v[92:95], v[152:155], v[168:171], v[92:95]
	v_mfma_f32_16x16x32_bf16 v[80:83], v[144:147], v[190:193], v[80:83]
	v_mfma_f32_16x16x32_bf16 v[72:75], v[152:155], v[190:193], v[72:75]
	v_mfma_f32_16x16x32_bf16 v[68:71], v[144:147], v[198:201], v[68:71]
	v_mfma_f32_16x16x32_bf16 v[64:67], v[152:155], v[198:201], v[64:67]
	v_mfma_f32_16x16x32_bf16 v[116:119], v[148:151], v[164:167], v[116:119]
	v_mfma_f32_16x16x32_bf16 v[108:111], v[156:159], v[164:167], v[108:111]
	v_mfma_f32_16x16x32_bf16 v[100:103], v[148:151], v[172:175], v[100:103]
	v_mfma_f32_16x16x32_bf16 v[92:95], v[156:159], v[172:175], v[92:95]
	v_mfma_f32_16x16x32_bf16 v[80:83], v[148:151], v[194:197], v[80:83]
	v_mfma_f32_16x16x32_bf16 v[72:75], v[156:159], v[194:197], v[72:75]
	v_mfma_f32_16x16x32_bf16 v[68:71], v[148:151], v[216:219], v[68:71]
	v_mfma_f32_16x16x32_bf16 v[64:67], v[156:159], v[216:219], v[64:67]
	s_setprio 0
	s_barrier
	s_add_i32 s55, s43, s27
	v_lshl_add_u64 v[202:203], s[22:23], 0, v[176:177]
	s_mov_b32 m0, s55
	ds_read_b128 v[160:163], v214 offset:16384
	ds_read_b128 v[164:167], v214 offset:17408
	ds_read_b128 v[168:171], v214 offset:18432
	ds_read_b128 v[172:175], v214 offset:19456
	ds_read_b128 v[190:193], v214 offset:20480
	ds_read_b128 v[194:197], v214 offset:21504
	ds_read_b128 v[198:201], v214 offset:22528
	ds_read_b128 v[216:219], v214 offset:23552
	global_load_lds_dwordx4 v[202:203], off
	s_add_i32 m0, s55, 0x2000
	s_add_u32 s56, s22, 0x40000
	v_lshl_add_u64 v[220:221], s[22:23], 0, v[178:179]
	s_addc_u32 s57, s23, 0
	s_add_i32 s55, s44, s27
	global_load_lds_dwordx4 v[220:221], off
	v_lshl_add_u64 v[222:223], s[56:57], 0, v[176:177]
	s_mov_b32 m0, s55
	v_lshl_add_u64 v[224:225], s[24:25], 0, v[178:179]
	global_load_lds_dwordx4 v[222:223], off
	v_lshl_add_u64 v[222:223], s[56:57], 0, v[178:179]
	s_add_i32 m0, s55, 0x2000
	s_nop 0
	global_load_lds_dwordx4 v[222:223], off
	v_lshl_add_u64 v[222:223], s[24:25], 0, v[176:177]
	s_mov_b32 m0, s28
	s_nop 0
	global_load_lds_dwordx4 v[222:223], off
	s_mov_b32 m0, s29
	s_nop 0
	global_load_lds_dwordx4 v[224:225], off
	s_waitcnt vmcnt(8)
	s_waitcnt lgkmcnt(0)
	s_barrier
	s_setprio 1
	s_waitcnt lgkmcnt(0)
	v_mfma_f32_16x16x32_bf16 v[60:63], v[128:131], v[160:163], v[60:63]
	v_mfma_f32_16x16x32_bf16 v[56:59], v[136:139], v[160:163], v[56:59]
	v_mfma_f32_16x16x32_bf16 v[48:51], v[128:131], v[168:171], v[48:51]
	v_mfma_f32_16x16x32_bf16 v[40:43], v[136:139], v[168:171], v[40:43]
	v_mfma_f32_16x16x32_bf16 v[32:35], v[128:131], v[190:193], v[32:35]
	v_mfma_f32_16x16x32_bf16 v[24:27], v[136:139], v[190:193], v[24:27]
	v_mfma_f32_16x16x32_bf16 v[20:23], v[128:131], v[198:201], v[20:23]
	v_mfma_f32_16x16x32_bf16 v[12:15], v[136:139], v[198:201], v[12:15]
	v_mfma_f32_16x16x32_bf16 v[60:63], v[132:135], v[164:167], v[60:63]
	v_mfma_f32_16x16x32_bf16 v[56:59], v[140:143], v[164:167], v[56:59]
	v_mfma_f32_16x16x32_bf16 v[48:51], v[132:135], v[172:175], v[48:51]
	v_mfma_f32_16x16x32_bf16 v[40:43], v[140:143], v[172:175], v[40:43]
	v_mfma_f32_16x16x32_bf16 v[32:35], v[132:135], v[194:197], v[32:35]
	v_mfma_f32_16x16x32_bf16 v[24:27], v[140:143], v[194:197], v[24:27]
	v_mfma_f32_16x16x32_bf16 v[20:23], v[132:135], v[216:219], v[20:23]
	v_mfma_f32_16x16x32_bf16 v[12:15], v[140:143], v[216:219], v[12:15]
	s_setprio 0
	s_setprio 1
	v_mfma_f32_16x16x32_bf16 v[52:55], v[144:147], v[160:163], v[52:55]
	v_mfma_f32_16x16x32_bf16 v[44:47], v[152:155], v[160:163], v[44:47]
	v_mfma_f32_16x16x32_bf16 v[36:39], v[144:147], v[168:171], v[36:39]
	v_mfma_f32_16x16x32_bf16 v[28:31], v[152:155], v[168:171], v[28:31]
	v_mfma_f32_16x16x32_bf16 v[16:19], v[144:147], v[190:193], v[16:19]
	v_mfma_f32_16x16x32_bf16 v[8:11], v[152:155], v[190:193], v[8:11]
	v_mfma_f32_16x16x32_bf16 v[4:7], v[144:147], v[198:201], v[4:7]
	v_mfma_f32_16x16x32_bf16 v[0:3], v[152:155], v[198:201], v[0:3]
	v_mfma_f32_16x16x32_bf16 v[52:55], v[148:151], v[164:167], v[52:55]
	v_mfma_f32_16x16x32_bf16 v[44:47], v[156:159], v[164:167], v[44:47]
	v_mfma_f32_16x16x32_bf16 v[36:39], v[148:151], v[172:175], v[36:39]
	v_mfma_f32_16x16x32_bf16 v[28:31], v[156:159], v[172:175], v[28:31]
	v_mfma_f32_16x16x32_bf16 v[16:19], v[148:151], v[194:197], v[16:19]
	v_mfma_f32_16x16x32_bf16 v[8:11], v[156:159], v[194:197], v[8:11]
	v_mfma_f32_16x16x32_bf16 v[4:7], v[148:151], v[216:219], v[4:7]
	v_mfma_f32_16x16x32_bf16 v[0:3], v[156:159], v[216:219], v[0:3]
	s_setprio 0
	s_barrier
	s_add_i32 s55, 0, 0x18000
	s_add_i32 s56, 0, 0x1c000
	v_add_u32_e32 v140, s55, v210
	v_add_u32_e32 v156, s56, v210
	ds_read_b128 v[128:131], v140
	ds_read_b128 v[132:135], v140 offset:1024
	ds_read_b128 v[136:139], v140 offset:2048
	ds_read_b128 v[140:143], v140 offset:3072
	ds_read_b128 v[144:147], v156
	ds_read_b128 v[148:151], v156 offset:1024
	ds_read_b128 v[152:155], v156 offset:2048
	ds_read_b128 v[156:159], v156 offset:3072
	s_add_u32 s24, s24, 0x40000
	s_addc_u32 s25, s25, 0
	s_mov_b32 m0, s30
	v_lshl_add_u64 v[226:227], s[24:25], 0, v[176:177]
	ds_read_b128 v[160:163], v214 offset:32768
	ds_read_b128 v[164:167], v214 offset:33792
	ds_read_b128 v[168:171], v214 offset:34816
	ds_read_b128 v[172:175], v214 offset:35840
	ds_read_b128 v[190:193], v214 offset:36864
	ds_read_b128 v[194:197], v214 offset:37888
	ds_read_b128 v[198:201], v214 offset:38912
	ds_read_b128 v[216:219], v214 offset:39936
	global_load_lds_dwordx4 v[226:227], off
	v_lshl_add_u64 v[226:227], s[24:25], 0, v[178:179]
	s_mov_b32 m0, s31
	s_nop 0
	global_load_lds_dwordx4 v[226:227], off
	s_waitcnt vmcnt(8)
	s_waitcnt lgkmcnt(0)
	s_barrier
	s_setprio 1
	s_waitcnt lgkmcnt(0)
	v_mfma_f32_16x16x32_bf16 v[124:127], v[128:131], v[160:163], v[124:127]
	v_mfma_f32_16x16x32_bf16 v[120:123], v[136:139], v[160:163], v[120:123]
	v_mfma_f32_16x16x32_bf16 v[112:115], v[128:131], v[168:171], v[112:115]
	v_mfma_f32_16x16x32_bf16 v[104:107], v[136:139], v[168:171], v[104:107]
	v_mfma_f32_16x16x32_bf16 v[96:99], v[128:131], v[190:193], v[96:99]
	v_mfma_f32_16x16x32_bf16 v[88:91], v[136:139], v[190:193], v[88:91]
	v_mfma_f32_16x16x32_bf16 v[84:87], v[128:131], v[198:201], v[84:87]
	v_mfma_f32_16x16x32_bf16 v[76:79], v[136:139], v[198:201], v[76:79]
	v_mfma_f32_16x16x32_bf16 v[124:127], v[132:135], v[164:167], v[124:127]
	v_mfma_f32_16x16x32_bf16 v[120:123], v[140:143], v[164:167], v[120:123]
	v_mfma_f32_16x16x32_bf16 v[112:115], v[132:135], v[172:175], v[112:115]
	v_mfma_f32_16x16x32_bf16 v[104:107], v[140:143], v[172:175], v[104:107]
	v_mfma_f32_16x16x32_bf16 v[96:99], v[132:135], v[194:197], v[96:99]
	v_mfma_f32_16x16x32_bf16 v[88:91], v[140:143], v[194:197], v[88:91]
	v_mfma_f32_16x16x32_bf16 v[84:87], v[132:135], v[216:219], v[84:87]
	v_mfma_f32_16x16x32_bf16 v[76:79], v[140:143], v[216:219], v[76:79]
	s_setprio 0
	s_setprio 1
	v_mfma_f32_16x16x32_bf16 v[116:119], v[144:147], v[160:163], v[116:119]
	v_mfma_f32_16x16x32_bf16 v[108:111], v[152:155], v[160:163], v[108:111]
	v_mfma_f32_16x16x32_bf16 v[100:103], v[144:147], v[168:171], v[100:103]
	v_mfma_f32_16x16x32_bf16 v[92:95], v[152:155], v[168:171], v[92:95]
	v_mfma_f32_16x16x32_bf16 v[80:83], v[144:147], v[190:193], v[80:83]
	v_mfma_f32_16x16x32_bf16 v[72:75], v[152:155], v[190:193], v[72:75]
	v_mfma_f32_16x16x32_bf16 v[68:71], v[144:147], v[198:201], v[68:71]
	v_mfma_f32_16x16x32_bf16 v[64:67], v[152:155], v[198:201], v[64:67]
	v_mfma_f32_16x16x32_bf16 v[116:119], v[148:151], v[164:167], v[116:119]
	v_mfma_f32_16x16x32_bf16 v[108:111], v[156:159], v[164:167], v[108:111]
	v_mfma_f32_16x16x32_bf16 v[100:103], v[148:151], v[172:175], v[100:103]
	v_mfma_f32_16x16x32_bf16 v[92:95], v[156:159], v[172:175], v[92:95]
	v_mfma_f32_16x16x32_bf16 v[80:83], v[148:151], v[194:197], v[80:83]
	v_mfma_f32_16x16x32_bf16 v[72:75], v[156:159], v[194:197], v[72:75]
	v_mfma_f32_16x16x32_bf16 v[68:71], v[148:151], v[216:219], v[68:71]
	v_mfma_f32_16x16x32_bf16 v[64:67], v[156:159], v[216:219], v[64:67]
	s_setprio 0
	s_barrier
	s_add_i32 s24, s55, s27
	v_lshl_add_u64 v[202:203], v[202:203], 0, s[6:7]
	s_mov_b32 m0, s24
	ds_read_b128 v[160:163], v214 offset:49152
	ds_read_b128 v[164:167], v214 offset:50176
	ds_read_b128 v[168:171], v214 offset:51200
	ds_read_b128 v[172:175], v214 offset:52224
	ds_read_b128 v[190:193], v214 offset:53248
	ds_read_b128 v[194:197], v214 offset:54272
	ds_read_b128 v[198:201], v214 offset:55296
	ds_read_b128 v[216:219], v214 offset:56320
	global_load_lds_dwordx4 v[202:203], off
	s_add_i32 m0, s24, 0x2000
	s_add_u32 s22, s22, 0x40080
	v_lshl_add_u64 v[202:203], v[220:221], 0, s[6:7]
	s_addc_u32 s23, s23, 0
	s_add_i32 s24, s56, s27
	global_load_lds_dwordx4 v[202:203], off
	v_lshl_add_u64 v[202:203], s[22:23], 0, v[176:177]
	s_mov_b32 m0, s24
	s_nop 0
	global_load_lds_dwordx4 v[202:203], off
	v_lshl_add_u64 v[202:203], s[22:23], 0, v[178:179]
	s_add_i32 m0, s24, 0x2000
	s_nop 0
	global_load_lds_dwordx4 v[202:203], off
	v_lshl_add_u64 v[202:203], v[222:223], 0, s[6:7]
	s_mov_b32 m0, s40
	s_nop 0
	global_load_lds_dwordx4 v[202:203], off
	v_lshl_add_u64 v[202:203], v[224:225], 0, s[6:7]
	s_mov_b32 m0, s41
	s_nop 0
	global_load_lds_dwordx4 v[202:203], off
	s_waitcnt vmcnt(8)
	s_waitcnt lgkmcnt(0)
	s_barrier
	s_setprio 1
	s_waitcnt lgkmcnt(0)
	v_mfma_f32_16x16x32_bf16 v[60:63], v[128:131], v[160:163], v[60:63]
	v_mfma_f32_16x16x32_bf16 v[56:59], v[136:139], v[160:163], v[56:59]
	v_mfma_f32_16x16x32_bf16 v[48:51], v[128:131], v[168:171], v[48:51]
	v_mfma_f32_16x16x32_bf16 v[40:43], v[136:139], v[168:171], v[40:43]
	v_mfma_f32_16x16x32_bf16 v[32:35], v[128:131], v[190:193], v[32:35]
	v_mfma_f32_16x16x32_bf16 v[24:27], v[136:139], v[190:193], v[24:27]
	v_mfma_f32_16x16x32_bf16 v[20:23], v[128:131], v[198:201], v[20:23]
	v_mfma_f32_16x16x32_bf16 v[12:15], v[136:139], v[198:201], v[12:15]
	v_mfma_f32_16x16x32_bf16 v[60:63], v[132:135], v[164:167], v[60:63]
	v_mfma_f32_16x16x32_bf16 v[56:59], v[140:143], v[164:167], v[56:59]
	v_mfma_f32_16x16x32_bf16 v[48:51], v[132:135], v[172:175], v[48:51]
	v_mfma_f32_16x16x32_bf16 v[40:43], v[140:143], v[172:175], v[40:43]
	v_mfma_f32_16x16x32_bf16 v[32:35], v[132:135], v[194:197], v[32:35]
	v_mfma_f32_16x16x32_bf16 v[24:27], v[140:143], v[194:197], v[24:27]
	v_mfma_f32_16x16x32_bf16 v[20:23], v[132:135], v[216:219], v[20:23]
	v_mfma_f32_16x16x32_bf16 v[12:15], v[140:143], v[216:219], v[12:15]
	s_setprio 0
	s_setprio 1
	v_mfma_f32_16x16x32_bf16 v[52:55], v[144:147], v[160:163], v[52:55]
	v_mfma_f32_16x16x32_bf16 v[44:47], v[152:155], v[160:163], v[44:47]
	v_mfma_f32_16x16x32_bf16 v[36:39], v[144:147], v[168:171], v[36:39]
	v_mfma_f32_16x16x32_bf16 v[28:31], v[152:155], v[168:171], v[28:31]
	v_mfma_f32_16x16x32_bf16 v[16:19], v[144:147], v[190:193], v[16:19]
	v_mfma_f32_16x16x32_bf16 v[8:11], v[152:155], v[190:193], v[8:11]
	v_mfma_f32_16x16x32_bf16 v[4:7], v[144:147], v[198:201], v[4:7]
	v_mfma_f32_16x16x32_bf16 v[0:3], v[152:155], v[198:201], v[0:3]
	v_mfma_f32_16x16x32_bf16 v[52:55], v[148:151], v[164:167], v[52:55]
	v_mfma_f32_16x16x32_bf16 v[44:47], v[156:159], v[164:167], v[44:47]
	v_mfma_f32_16x16x32_bf16 v[36:39], v[148:151], v[172:175], v[36:39]
	v_mfma_f32_16x16x32_bf16 v[28:31], v[156:159], v[172:175], v[28:31]
	v_mfma_f32_16x16x32_bf16 v[16:19], v[148:151], v[194:197], v[16:19]
	v_mfma_f32_16x16x32_bf16 v[8:11], v[156:159], v[194:197], v[8:11]
	v_mfma_f32_16x16x32_bf16 v[4:7], v[148:151], v[216:219], v[4:7]
	v_mfma_f32_16x16x32_bf16 v[0:3], v[156:159], v[216:219], v[0:3]
	s_setprio 0
	s_barrier
	s_add_i32 s54, s54, 2
	s_add_u32 s20, s20, 0x100
	s_addc_u32 s21, s21, 0
	s_add_u32 s52, s52, 0x100
	s_addc_u32 s53, s53, 0
	s_cmp_gt_u32 s54, 13
	s_cbranch_scc0 .LBB0_1088
	s_and_b64 vcc, exec, s[8:9]
	s_cbranch_vccz .LBB0_1091
	s_barrier

.LBB0_1099:
	s_or_b64 exec, exec, s[18:19]
	v_lshl_add_u64 v[132:133], v[122:123], 0, v[190:191]
	global_load_dwordx4 v[120:123], v[132:133], off
	global_load_dwordx4 v[124:127], v[132:133], off offset:64
	global_load_dwordx4 v[128:131], v[132:133], off offset:512
	s_nop 0
	global_load_dwordx4 v[132:135], v[132:133], off offset:576
	v_lshlrev_b64 v[118:119], 12, v[118:119]
	v_lshl_add_u64 v[118:119], s[88:89], 0, v[118:119]
	v_lshl_add_u64 v[118:119], v[118:119], 0, v[190:191]
	s_waitcnt vmcnt(12)
	v_pk_add_f32 v[46:47], v[46:47], v[94:95]
	v_pk_add_f32 v[44:45], v[44:45], v[92:93]
	global_store_dwordx4 v[118:119], v[44:47], off offset:576
	v_pk_add_f32 v[54:55], v[54:55], v[102:103]
	v_pk_add_f32 v[52:53], v[52:53], v[100:101]
	v_lshlrev_b64 v[44:45], 12, v[116:117]
	v_lshl_add_u64 v[44:45], s[88:89], 0, v[44:45]
	global_store_dwordx4 v[118:119], v[52:55], off offset:512
	s_waitcnt vmcnt(10)
	v_pk_add_f32 v[30:31], v[30:31], v[78:79]
	v_pk_add_f32 v[28:29], v[28:29], v[76:77]
	v_lshl_add_u64 v[52:53], v[44:45], 0, v[190:191]
	global_store_dwordx4 v[52:53], v[28:31], off offset:576
	v_pk_add_f32 v[38:39], v[38:39], v[86:87]
	v_pk_add_f32 v[36:37], v[36:37], v[84:85]
	v_lshlrev_b64 v[28:29], 12, v[112:113]
	v_lshl_add_u64 v[28:29], s[88:89], 0, v[28:29]
	global_store_dwordx4 v[52:53], v[36:39], off offset:512
	s_waitcnt vmcnt(8)
	v_pk_add_f32 v[10:11], v[10:11], v[66:67]
	v_pk_add_f32 v[8:9], v[8:9], v[64:65]
	v_lshl_add_u64 v[36:37], v[28:29], 0, v[190:191]
	v_pk_add_f32 v[18:19], v[18:19], v[70:71]
	v_pk_add_f32 v[16:17], v[16:17], v[68:69]
	global_store_dwordx4 v[36:37], v[8:11], off offset:576
	v_pk_add_f32 v[62:63], v[62:63], v[110:111]
	v_pk_add_f32 v[60:61], v[60:61], v[108:109]
	v_lshl_add_u64 v[8:9], s[88:89], 0, v[114:115]
	v_pk_add_f32 v[58:59], v[58:59], v[106:107]
	v_pk_add_f32 v[56:57], v[56:57], v[104:105]
	v_pk_add_f32 v[46:47], v[50:51], v[98:99]
	v_pk_add_f32 v[44:45], v[48:49], v[96:97]
	v_pk_add_f32 v[42:43], v[42:43], v[90:91]
	v_pk_add_f32 v[40:41], v[40:41], v[88:89]
	v_pk_add_f32 v[30:31], v[34:35], v[82:83]
	v_pk_add_f32 v[28:29], v[32:33], v[80:81]
	v_pk_add_f32 v[26:27], v[26:27], v[74:75]
	v_pk_add_f32 v[24:25], v[24:25], v[72:73]
	global_store_dwordx4 v[36:37], v[16:19], off offset:512
	s_waitcnt vmcnt(9)
	v_pk_add_f32 v[10:11], v[22:23], v[122:123]
	global_store_dwordx4 v[118:119], v[60:63], off
	v_lshl_add_u64 v[16:17], v[8:9], 0, v[190:191]
	v_pk_add_f32 v[8:9], v[20:21], v[120:121]
	global_store_dwordx4 v[118:119], v[56:59], off offset:64
	global_store_dwordx4 v[52:53], v[44:47], off
	global_store_dwordx4 v[52:53], v[40:43], off offset:64
	global_store_dwordx4 v[36:37], v[28:31], off
	global_store_dwordx4 v[36:37], v[24:27], off offset:64
	global_store_dwordx4 v[16:17], v[8:11], off
	s_waitcnt vmcnt(14)
	v_pk_add_f32 v[6:7], v[6:7], v[130:131]
	v_pk_add_f32 v[4:5], v[4:5], v[128:129]
	v_pk_add_f32 v[10:11], v[14:15], v[126:127]
	v_pk_add_f32 v[8:9], v[12:13], v[124:125]
	s_waitcnt vmcnt(13)
	v_pk_add_f32 v[2:3], v[2:3], v[134:135]
	v_pk_add_f32 v[0:1], v[0:1], v[132:133]
	global_store_dwordx4 v[16:17], v[8:11], off offset:64
	global_store_dwordx4 v[16:17], v[4:7], off offset:512
	global_store_dwordx4 v[16:17], v[0:3], off offset:576
	s_andn2_b64 vcc, exec, s[2:3]
	s_mov_b64 s[2:3], -1
	s_cbranch_vccnz .LBB0_1080
	s_andn2_b64 vcc, exec, s[0:1]
	s_cbranch_vccnz .LBB0_1079
	v_writelane_b32 v255, 1, 53
	s_branch .LBB0_1079

.LBB0_1242:
	s_ashr_i32 s15, s14, 31
	s_lshl_b64 s[16:17], s[14:15], 19
	s_add_u32 s16, s29, s16
	s_addc_u32 s17, s30, s17
	s_and_b64 s[18:19], s[2:3], exec
	s_cselect_b32 s15, s17, s23
	s_cselect_b32 s47, s16, s22
	s_ashr_i32 s13, s12, 31
	s_lshl_b64 s[18:19], s[12:13], 19
	s_add_u32 s18, s31, s18
	s_addc_u32 s19, s33, s19
	s_and_b64 s[26:27], s[2:3], exec
	s_cselect_b32 s13, s19, s25
	s_cselect_b32 s48, s18, s24
	s_add_u32 s22, s22, 0x40080
	s_addc_u32 s23, s23, 0
	s_add_u32 s49, s24, 0x100
	v_mov_b32_e32 v0, 0
	s_addc_u32 s50, s25, 0
	s_mov_b32 s51, -2
	v_mov_b32_e32 v1, v0
	v_mov_b32_e32 v2, v0
	v_mov_b32_e32 v3, v0
	v_mov_b32_e32 v4, v0
	v_mov_b32_e32 v5, v0
	v_mov_b32_e32 v6, v0
	v_mov_b32_e32 v7, v0
	v_mov_b32_e32 v16, v0
	v_mov_b32_e32 v17, v0
	v_mov_b32_e32 v18, v0
	v_mov_b32_e32 v19, v0
	v_mov_b32_e32 v20, v0
	v_mov_b32_e32 v21, v0
	v_mov_b32_e32 v22, v0
	v_mov_b32_e32 v23, v0
	v_mov_b32_e32 v32, v0
	v_mov_b32_e32 v33, v0
	v_mov_b32_e32 v34, v0
	v_mov_b32_e32 v35, v0
	v_mov_b32_e32 v36, v0
	v_mov_b32_e32 v37, v0
	v_mov_b32_e32 v38, v0
	v_mov_b32_e32 v39, v0
	v_mov_b32_e32 v48, v0
	v_mov_b32_e32 v49, v0
	v_mov_b32_e32 v50, v0
	v_mov_b32_e32 v51, v0
	v_mov_b32_e32 v52, v0
	v_mov_b32_e32 v53, v0
	v_mov_b32_e32 v54, v0
	v_mov_b32_e32 v55, v0
	v_mov_b32_e32 v8, v0
	v_mov_b32_e32 v9, v0
	v_mov_b32_e32 v10, v0
	v_mov_b32_e32 v11, v0
	v_mov_b32_e32 v12, v0
	v_mov_b32_e32 v13, v0
	v_mov_b32_e32 v14, v0
	v_mov_b32_e32 v15, v0
	v_mov_b32_e32 v24, v0
	v_mov_b32_e32 v25, v0
	v_mov_b32_e32 v26, v0
	v_mov_b32_e32 v27, v0
	v_mov_b32_e32 v28, v0
	v_mov_b32_e32 v29, v0
	v_mov_b32_e32 v30, v0
	v_mov_b32_e32 v31, v0
	v_mov_b32_e32 v40, v0
	v_mov_b32_e32 v41, v0
	v_mov_b32_e32 v42, v0
	v_mov_b32_e32 v43, v0
	v_mov_b32_e32 v44, v0
	v_mov_b32_e32 v45, v0
	v_mov_b32_e32 v46, v0
	v_mov_b32_e32 v47, v0
	v_mov_b32_e32 v56, v0
	v_mov_b32_e32 v57, v0
	v_mov_b32_e32 v58, v0
	v_mov_b32_e32 v59, v0
	v_mov_b32_e32 v60, v0
	v_mov_b32_e32 v61, v0
	v_mov_b32_e32 v62, v0
	v_mov_b32_e32 v63, v0
	v_mov_b32_e32 v64, v0
	v_mov_b32_e32 v65, v0
	v_mov_b32_e32 v66, v0
	v_mov_b32_e32 v67, v0
	v_mov_b32_e32 v68, v0
	v_mov_b32_e32 v69, v0
	v_mov_b32_e32 v70, v0
	v_mov_b32_e32 v71, v0
	v_mov_b32_e32 v80, v0
	v_mov_b32_e32 v81, v0
	v_mov_b32_e32 v82, v0
	v_mov_b32_e32 v83, v0
	v_mov_b32_e32 v84, v0
	v_mov_b32_e32 v85, v0
	v_mov_b32_e32 v86, v0
	v_mov_b32_e32 v87, v0
	v_mov_b32_e32 v96, v0
	v_mov_b32_e32 v97, v0
	v_mov_b32_e32 v98, v0
	v_mov_b32_e32 v99, v0
	v_mov_b32_e32 v100, v0
	v_mov_b32_e32 v101, v0
	v_mov_b32_e32 v102, v0
	v_mov_b32_e32 v103, v0
	v_mov_b32_e32 v112, v0
	v_mov_b32_e32 v113, v0
	v_mov_b32_e32 v114, v0
	v_mov_b32_e32 v115, v0
	v_mov_b32_e32 v116, v0
	v_mov_b32_e32 v117, v0
	v_mov_b32_e32 v118, v0
	v_mov_b32_e32 v119, v0
	v_mov_b32_e32 v72, v0
	v_mov_b32_e32 v73, v0
	v_mov_b32_e32 v74, v0
	v_mov_b32_e32 v75, v0
	v_mov_b32_e32 v76, v0
	v_mov_b32_e32 v77, v0
	v_mov_b32_e32 v78, v0
	v_mov_b32_e32 v79, v0
	v_mov_b32_e32 v88, v0
	v_mov_b32_e32 v89, v0
	v_mov_b32_e32 v90, v0
	v_mov_b32_e32 v91, v0
	v_mov_b32_e32 v92, v0
	v_mov_b32_e32 v93, v0
	v_mov_b32_e32 v94, v0
	v_mov_b32_e32 v95, v0
	v_mov_b32_e32 v104, v0
	v_mov_b32_e32 v105, v0
	v_mov_b32_e32 v106, v0
	v_mov_b32_e32 v107, v0
	v_mov_b32_e32 v108, v0
	v_mov_b32_e32 v109, v0
	v_mov_b32_e32 v110, v0
	v_mov_b32_e32 v111, v0
	v_mov_b32_e32 v120, v0
	v_mov_b32_e32 v121, v0
	v_mov_b32_e32 v122, v0
	v_mov_b32_e32 v123, v0
	v_mov_b32_e32 v124, v0
	v_mov_b32_e32 v125, v0
	v_mov_b32_e32 v126, v0
	v_mov_b32_e32 v127, v0
	v_readlane_b32 s97, v255, 53
	s_nop 3
	s_cmp_eq_u32 s97, 1
	s_cbranch_scc0 .Llsb_skip_9
	v_writelane_b32 v255, 0, 53
	s_barrier
.Llsb_skip_9:
.LBB0_1243:
	ds_read_b128 v[150:153], v147
	ds_read_b128 v[154:157], v147 offset:1024
	ds_read_b128 v[158:161], v147 offset:2048
	ds_read_b128 v[162:165], v147 offset:3072
	ds_read_b128 v[166:169], v148
	ds_read_b128 v[170:173], v148 offset:1024
	ds_read_b128 v[174:177], v148 offset:2048
	ds_read_b128 v[178:181], v148 offset:3072
	s_add_u32 s24, s22, 0xfffc0080
	s_addc_u32 s25, s23, -1
	s_cmp_eq_u32 s51, 12
	s_cselect_b32 s27, s15, s25
	s_cselect_b32 s26, s47, s24
	s_cselect_b32 s25, s13, s50
	s_cselect_b32 s24, s48, s49
	v_lshl_add_u64 v[202:203], s[22:23], 0, v[136:137]
	s_add_i32 m0, s21, 0xc000
	ds_read_b128 v[182:185], v149
	ds_read_b128 v[186:189], v149 offset:1024
	ds_read_b128 v[190:193], v149 offset:2048
	ds_read_b128 v[194:197], v149 offset:3072
	ds_read_b128 v[198:201], v149 offset:4096
	ds_read_b128 v[206:209], v149 offset:5120
	ds_read_b128 v[210:213], v149 offset:6144
	ds_read_b128 v[214:217], v149 offset:7168
	global_load_lds_dwordx4 v[202:203], off
	v_lshl_add_u64 v[202:203], s[22:23], 0, v[138:139]
	s_add_i32 m0, s21, 0xe000
	s_nop 0
	global_load_lds_dwordx4 v[202:203], off
	s_waitcnt vmcnt(8)
	s_waitcnt lgkmcnt(0)
	s_barrier
	s_setprio 1
	s_waitcnt lgkmcnt(0)
	v_mfma_f32_16x16x32_bf16 v[124:127], v[150:153], v[182:185], v[124:127]
	v_mfma_f32_16x16x32_bf16 v[120:123], v[158:161], v[182:185], v[120:123]
	v_mfma_f32_16x16x32_bf16 v[108:111], v[150:153], v[190:193], v[108:111]
	v_mfma_f32_16x16x32_bf16 v[104:107], v[158:161], v[190:193], v[104:107]
	v_mfma_f32_16x16x32_bf16 v[92:95], v[150:153], v[198:201], v[92:95]
	v_mfma_f32_16x16x32_bf16 v[88:91], v[158:161], v[198:201], v[88:91]
	v_mfma_f32_16x16x32_bf16 v[76:79], v[150:153], v[210:213], v[76:79]
	v_mfma_f32_16x16x32_bf16 v[72:75], v[158:161], v[210:213], v[72:75]
	v_mfma_f32_16x16x32_bf16 v[124:127], v[154:157], v[186:189], v[124:127]
	v_mfma_f32_16x16x32_bf16 v[120:123], v[162:165], v[186:189], v[120:123]
	v_mfma_f32_16x16x32_bf16 v[108:111], v[154:157], v[194:197], v[108:111]
	v_mfma_f32_16x16x32_bf16 v[104:107], v[162:165], v[194:197], v[104:107]
	v_mfma_f32_16x16x32_bf16 v[92:95], v[154:157], v[206:209], v[92:95]
	v_mfma_f32_16x16x32_bf16 v[88:91], v[162:165], v[206:209], v[88:91]
	v_mfma_f32_16x16x32_bf16 v[76:79], v[154:157], v[214:217], v[76:79]
	v_mfma_f32_16x16x32_bf16 v[72:75], v[162:165], v[214:217], v[72:75]
	s_setprio 0
	s_setprio 1
	v_mfma_f32_16x16x32_bf16 v[116:119], v[166:169], v[182:185], v[116:119]
	v_mfma_f32_16x16x32_bf16 v[112:115], v[174:177], v[182:185], v[112:115]
	v_mfma_f32_16x16x32_bf16 v[100:103], v[166:169], v[190:193], v[100:103]
	v_mfma_f32_16x16x32_bf16 v[96:99], v[174:177], v[190:193], v[96:99]
	v_mfma_f32_16x16x32_bf16 v[84:87], v[166:169], v[198:201], v[84:87]
	v_mfma_f32_16x16x32_bf16 v[80:83], v[174:177], v[198:201], v[80:83]
	v_mfma_f32_16x16x32_bf16 v[68:71], v[166:169], v[210:213], v[68:71]
	v_mfma_f32_16x16x32_bf16 v[64:67], v[174:177], v[210:213], v[64:67]
	v_mfma_f32_16x16x32_bf16 v[116:119], v[170:173], v[186:189], v[116:119]
	v_mfma_f32_16x16x32_bf16 v[112:115], v[178:181], v[186:189], v[112:115]
	v_mfma_f32_16x16x32_bf16 v[100:103], v[170:173], v[194:197], v[100:103]
	v_mfma_f32_16x16x32_bf16 v[96:99], v[178:181], v[194:197], v[96:99]
	v_mfma_f32_16x16x32_bf16 v[84:87], v[170:173], v[206:209], v[84:87]
	v_mfma_f32_16x16x32_bf16 v[80:83], v[178:181], v[206:209], v[80:83]
	v_mfma_f32_16x16x32_bf16 v[68:71], v[170:173], v[214:217], v[68:71]
	v_mfma_f32_16x16x32_bf16 v[64:67], v[178:181], v[214:217], v[64:67]
	s_setprio 0
	s_barrier
	s_add_i32 s52, s43, s34
	v_lshl_add_u64 v[202:203], s[24:25], 0, v[130:131]
	s_mov_b32 m0, s52
	ds_read_b128 v[182:185], v149 offset:16384
	ds_read_b128 v[186:189], v149 offset:17408
	ds_read_b128 v[190:193], v149 offset:18432
	ds_read_b128 v[194:197], v149 offset:19456
	ds_read_b128 v[198:201], v149 offset:20480
	ds_read_b128 v[206:209], v149 offset:21504
	ds_read_b128 v[210:213], v149 offset:22528
	ds_read_b128 v[214:217], v149 offset:23552
	global_load_lds_dwordx4 v[202:203], off
	s_add_i32 m0, s52, 0x2000
	s_add_u32 s52, s24, 0x40000
	v_lshl_add_u64 v[218:219], s[24:25], 0, v[134:135]
	s_addc_u32 s53, s25, 0
	s_add_i32 s54, s44, s34
	global_load_lds_dwordx4 v[218:219], off
	v_lshl_add_u64 v[220:221], s[52:53], 0, v[130:131]
	s_mov_b32 m0, s54
	v_lshl_add_u64 v[222:223], s[26:27], 0, v[132:133]
	global_load_lds_dwordx4 v[220:221], off
	v_lshl_add_u64 v[220:221], s[52:53], 0, v[134:135]
	s_add_i32 m0, s54, 0x2000
	s_nop 0
	global_load_lds_dwordx4 v[220:221], off
	v_lshl_add_u64 v[220:221], s[26:27], 0, v[128:129]
	s_mov_b32 m0, s21
	s_nop 0
	global_load_lds_dwordx4 v[220:221], off
	s_mov_b32 m0, s35
	s_nop 0
	global_load_lds_dwordx4 v[222:223], off
	s_waitcnt vmcnt(8)
	s_waitcnt lgkmcnt(0)
	s_barrier
	s_setprio 1
	s_waitcnt lgkmcnt(0)
	v_mfma_f32_16x16x32_bf16 v[60:63], v[150:153], v[182:185], v[60:63]
	v_mfma_f32_16x16x32_bf16 v[56:59], v[158:161], v[182:185], v[56:59]
	v_mfma_f32_16x16x32_bf16 v[44:47], v[150:153], v[190:193], v[44:47]
	v_mfma_f32_16x16x32_bf16 v[40:43], v[158:161], v[190:193], v[40:43]
	v_mfma_f32_16x16x32_bf16 v[28:31], v[150:153], v[198:201], v[28:31]
	v_mfma_f32_16x16x32_bf16 v[24:27], v[158:161], v[198:201], v[24:27]
	v_mfma_f32_16x16x32_bf16 v[12:15], v[150:153], v[210:213], v[12:15]
	v_mfma_f32_16x16x32_bf16 v[8:11], v[158:161], v[210:213], v[8:11]
	v_mfma_f32_16x16x32_bf16 v[60:63], v[154:157], v[186:189], v[60:63]
	v_mfma_f32_16x16x32_bf16 v[56:59], v[162:165], v[186:189], v[56:59]
	v_mfma_f32_16x16x32_bf16 v[44:47], v[154:157], v[194:197], v[44:47]
	v_mfma_f32_16x16x32_bf16 v[40:43], v[162:165], v[194:197], v[40:43]
	v_mfma_f32_16x16x32_bf16 v[28:31], v[154:157], v[206:209], v[28:31]
	v_mfma_f32_16x16x32_bf16 v[24:27], v[162:165], v[206:209], v[24:27]
	v_mfma_f32_16x16x32_bf16 v[12:15], v[154:157], v[214:217], v[12:15]
	v_mfma_f32_16x16x32_bf16 v[8:11], v[162:165], v[214:217], v[8:11]
	s_setprio 0
	s_setprio 1
	v_mfma_f32_16x16x32_bf16 v[52:55], v[166:169], v[182:185], v[52:55]
	v_mfma_f32_16x16x32_bf16 v[48:51], v[174:177], v[182:185], v[48:51]
	v_mfma_f32_16x16x32_bf16 v[36:39], v[166:169], v[190:193], v[36:39]
	v_mfma_f32_16x16x32_bf16 v[32:35], v[174:177], v[190:193], v[32:35]
	v_mfma_f32_16x16x32_bf16 v[20:23], v[166:169], v[198:201], v[20:23]
	v_mfma_f32_16x16x32_bf16 v[16:19], v[174:177], v[198:201], v[16:19]
	v_mfma_f32_16x16x32_bf16 v[4:7], v[166:169], v[210:213], v[4:7]
	v_mfma_f32_16x16x32_bf16 v[0:3], v[174:177], v[210:213], v[0:3]
	v_mfma_f32_16x16x32_bf16 v[52:55], v[170:173], v[186:189], v[52:55]
	v_mfma_f32_16x16x32_bf16 v[48:51], v[178:181], v[186:189], v[48:51]
	v_mfma_f32_16x16x32_bf16 v[36:39], v[170:173], v[194:197], v[36:39]
	v_mfma_f32_16x16x32_bf16 v[32:35], v[178:181], v[194:197], v[32:35]
	v_mfma_f32_16x16x32_bf16 v[20:23], v[170:173], v[206:209], v[20:23]
	v_mfma_f32_16x16x32_bf16 v[16:19], v[178:181], v[206:209], v[16:19]
	v_mfma_f32_16x16x32_bf16 v[4:7], v[170:173], v[214:217], v[4:7]
	v_mfma_f32_16x16x32_bf16 v[0:3], v[178:181], v[214:217], v[0:3]
	s_setprio 0
	s_barrier
	s_add_i32 s52, 0, 0x18000
	s_add_i32 s53, 0, 0x1c000
	v_add_u32_e32 v162, s52, v145
	v_add_u32_e32 v178, s53, v145
	ds_read_b128 v[150:153], v162
	ds_read_b128 v[154:157], v162 offset:1024
	ds_read_b128 v[158:161], v162 offset:2048
	ds_read_b128 v[162:165], v162 offset:3072
	ds_read_b128 v[166:169], v178
	ds_read_b128 v[170:173], v178 offset:1024
	ds_read_b128 v[174:177], v178 offset:2048
	ds_read_b128 v[178:181], v178 offset:3072
	s_add_u32 s26, s26, 0x40000
	s_addc_u32 s27, s27, 0
	s_mov_b32 m0, s36
	v_lshl_add_u64 v[224:225], s[26:27], 0, v[128:129]
	ds_read_b128 v[182:185], v149 offset:32768
	ds_read_b128 v[186:189], v149 offset:33792
	ds_read_b128 v[190:193], v149 offset:34816
	ds_read_b128 v[194:197], v149 offset:35840
	ds_read_b128 v[198:201], v149 offset:36864
	ds_read_b128 v[206:209], v149 offset:37888
	ds_read_b128 v[210:213], v149 offset:38912
	ds_read_b128 v[214:217], v149 offset:39936
	global_load_lds_dwordx4 v[224:225], off
	v_lshl_add_u64 v[224:225], s[26:27], 0, v[132:133]
	s_mov_b32 m0, s37
	s_nop 0
	global_load_lds_dwordx4 v[224:225], off
	s_waitcnt vmcnt(8)
	s_waitcnt lgkmcnt(0)
	s_barrier
	s_setprio 1
	s_waitcnt lgkmcnt(0)
	v_mfma_f32_16x16x32_bf16 v[124:127], v[150:153], v[182:185], v[124:127]
	v_mfma_f32_16x16x32_bf16 v[120:123], v[158:161], v[182:185], v[120:123]
	v_mfma_f32_16x16x32_bf16 v[108:111], v[150:153], v[190:193], v[108:111]
	v_mfma_f32_16x16x32_bf16 v[104:107], v[158:161], v[190:193], v[104:107]
	v_mfma_f32_16x16x32_bf16 v[92:95], v[150:153], v[198:201], v[92:95]
	v_mfma_f32_16x16x32_bf16 v[88:91], v[158:161], v[198:201], v[88:91]
	v_mfma_f32_16x16x32_bf16 v[76:79], v[150:153], v[210:213], v[76:79]
	v_mfma_f32_16x16x32_bf16 v[72:75], v[158:161], v[210:213], v[72:75]
	v_mfma_f32_16x16x32_bf16 v[124:127], v[154:157], v[186:189], v[124:127]
	v_mfma_f32_16x16x32_bf16 v[120:123], v[162:165], v[186:189], v[120:123]
	v_mfma_f32_16x16x32_bf16 v[108:111], v[154:157], v[194:197], v[108:111]
	v_mfma_f32_16x16x32_bf16 v[104:107], v[162:165], v[194:197], v[104:107]
	v_mfma_f32_16x16x32_bf16 v[92:95], v[154:157], v[206:209], v[92:95]
	v_mfma_f32_16x16x32_bf16 v[88:91], v[162:165], v[206:209], v[88:91]
	v_mfma_f32_16x16x32_bf16 v[76:79], v[154:157], v[214:217], v[76:79]
	v_mfma_f32_16x16x32_bf16 v[72:75], v[162:165], v[214:217], v[72:75]
	s_setprio 0
	s_setprio 1
	v_mfma_f32_16x16x32_bf16 v[116:119], v[166:169], v[182:185], v[116:119]
	v_mfma_f32_16x16x32_bf16 v[112:115], v[174:177], v[182:185], v[112:115]
	v_mfma_f32_16x16x32_bf16 v[100:103], v[166:169], v[190:193], v[100:103]
	v_mfma_f32_16x16x32_bf16 v[96:99], v[174:177], v[190:193], v[96:99]
	v_mfma_f32_16x16x32_bf16 v[84:87], v[166:169], v[198:201], v[84:87]
	v_mfma_f32_16x16x32_bf16 v[80:83], v[174:177], v[198:201], v[80:83]
	v_mfma_f32_16x16x32_bf16 v[68:71], v[166:169], v[210:213], v[68:71]
	v_mfma_f32_16x16x32_bf16 v[64:67], v[174:177], v[210:213], v[64:67]
	v_mfma_f32_16x16x32_bf16 v[116:119], v[170:173], v[186:189], v[116:119]
	v_mfma_f32_16x16x32_bf16 v[112:115], v[178:181], v[186:189], v[112:115]
	v_mfma_f32_16x16x32_bf16 v[100:103], v[170:173], v[194:197], v[100:103]
	v_mfma_f32_16x16x32_bf16 v[96:99], v[178:181], v[194:197], v[96:99]
	v_mfma_f32_16x16x32_bf16 v[84:87], v[170:173], v[206:209], v[84:87]
	v_mfma_f32_16x16x32_bf16 v[80:83], v[178:181], v[206:209], v[80:83]
	v_mfma_f32_16x16x32_bf16 v[68:71], v[170:173], v[214:217], v[68:71]
	v_mfma_f32_16x16x32_bf16 v[64:67], v[178:181], v[214:217], v[64:67]
	s_setprio 0
	s_barrier
	s_add_i32 s26, s52, s34
	v_lshl_add_u64 v[202:203], v[202:203], 0, s[8:9]
	s_mov_b32 m0, s26
	ds_read_b128 v[182:185], v149 offset:49152
	ds_read_b128 v[186:189], v149 offset:50176
	ds_read_b128 v[190:193], v149 offset:51200
	ds_read_b128 v[194:197], v149 offset:52224
	ds_read_b128 v[198:201], v149 offset:53248
	ds_read_b128 v[206:209], v149 offset:54272
	ds_read_b128 v[210:213], v149 offset:55296
	ds_read_b128 v[214:217], v149 offset:56320
	global_load_lds_dwordx4 v[202:203], off
	s_add_i32 m0, s26, 0x2000
	s_add_u32 s24, s24, 0x40080
	v_lshl_add_u64 v[202:203], v[218:219], 0, s[8:9]
	s_addc_u32 s25, s25, 0
	s_add_i32 s26, s53, s34
	global_load_lds_dwordx4 v[202:203], off
	v_lshl_add_u64 v[202:203], s[24:25], 0, v[130:131]
	s_mov_b32 m0, s26
	s_nop 0
	global_load_lds_dwordx4 v[202:203], off
	v_lshl_add_u64 v[202:203], s[24:25], 0, v[134:135]
	s_add_i32 m0, s26, 0x2000
	s_nop 0
	global_load_lds_dwordx4 v[202:203], off
	v_lshl_add_u64 v[202:203], v[220:221], 0, s[8:9]
	s_mov_b32 m0, s40
	s_nop 0
	global_load_lds_dwordx4 v[202:203], off
	v_lshl_add_u64 v[202:203], v[222:223], 0, s[8:9]
	s_mov_b32 m0, s41
	s_nop 0
	global_load_lds_dwordx4 v[202:203], off
	s_waitcnt vmcnt(8)
	s_waitcnt lgkmcnt(0)
	s_barrier
	s_setprio 1
	s_waitcnt lgkmcnt(0)
	v_mfma_f32_16x16x32_bf16 v[60:63], v[150:153], v[182:185], v[60:63]
	v_mfma_f32_16x16x32_bf16 v[56:59], v[158:161], v[182:185], v[56:59]
	v_mfma_f32_16x16x32_bf16 v[44:47], v[150:153], v[190:193], v[44:47]
	v_mfma_f32_16x16x32_bf16 v[40:43], v[158:161], v[190:193], v[40:43]
	v_mfma_f32_16x16x32_bf16 v[28:31], v[150:153], v[198:201], v[28:31]
	v_mfma_f32_16x16x32_bf16 v[24:27], v[158:161], v[198:201], v[24:27]
	v_mfma_f32_16x16x32_bf16 v[12:15], v[150:153], v[210:213], v[12:15]
	v_mfma_f32_16x16x32_bf16 v[8:11], v[158:161], v[210:213], v[8:11]
	v_mfma_f32_16x16x32_bf16 v[60:63], v[154:157], v[186:189], v[60:63]
	v_mfma_f32_16x16x32_bf16 v[56:59], v[162:165], v[186:189], v[56:59]
	v_mfma_f32_16x16x32_bf16 v[44:47], v[154:157], v[194:197], v[44:47]
	v_mfma_f32_16x16x32_bf16 v[40:43], v[162:165], v[194:197], v[40:43]
	v_mfma_f32_16x16x32_bf16 v[28:31], v[154:157], v[206:209], v[28:31]
	v_mfma_f32_16x16x32_bf16 v[24:27], v[162:165], v[206:209], v[24:27]
	v_mfma_f32_16x16x32_bf16 v[12:15], v[154:157], v[214:217], v[12:15]
	v_mfma_f32_16x16x32_bf16 v[8:11], v[162:165], v[214:217], v[8:11]
	s_setprio 0
	s_setprio 1
	v_mfma_f32_16x16x32_bf16 v[52:55], v[166:169], v[182:185], v[52:55]
	v_mfma_f32_16x16x32_bf16 v[48:51], v[174:177], v[182:185], v[48:51]
	v_mfma_f32_16x16x32_bf16 v[36:39], v[166:169], v[190:193], v[36:39]
	v_mfma_f32_16x16x32_bf16 v[32:35], v[174:177], v[190:193], v[32:35]
	v_mfma_f32_16x16x32_bf16 v[20:23], v[166:169], v[198:201], v[20:23]
	v_mfma_f32_16x16x32_bf16 v[16:19], v[174:177], v[198:201], v[16:19]
	v_mfma_f32_16x16x32_bf16 v[4:7], v[166:169], v[210:213], v[4:7]
	v_mfma_f32_16x16x32_bf16 v[0:3], v[174:177], v[210:213], v[0:3]
	v_mfma_f32_16x16x32_bf16 v[52:55], v[170:173], v[186:189], v[52:55]
	v_mfma_f32_16x16x32_bf16 v[48:51], v[178:181], v[186:189], v[48:51]
	v_mfma_f32_16x16x32_bf16 v[36:39], v[170:173], v[194:197], v[36:39]
	v_mfma_f32_16x16x32_bf16 v[32:35], v[178:181], v[194:197], v[32:35]
	v_mfma_f32_16x16x32_bf16 v[20:23], v[170:173], v[206:209], v[20:23]
	v_mfma_f32_16x16x32_bf16 v[16:19], v[178:181], v[206:209], v[16:19]
	v_mfma_f32_16x16x32_bf16 v[4:7], v[170:173], v[214:217], v[4:7]
	v_mfma_f32_16x16x32_bf16 v[0:3], v[178:181], v[214:217], v[0:3]
	s_setprio 0
	s_barrier
	s_add_i32 s51, s51, 2
	s_add_u32 s22, s22, 0x100
	s_addc_u32 s23, s23, 0
	s_add_u32 s49, s49, 0x100
	s_addc_u32 s50, s50, 0
	s_cmp_gt_u32 s51, 13
	s_cbranch_scc0 .LBB0_1243
	s_and_b64 vcc, exec, s[10:11]
	s_cbranch_vccz .LBB0_1246
	s_barrier
.LBB0_1246:
	v_mul_f32_e32 v151, 0xbfb8aa3b, v124
	v_mul_f32_e32 v154, 0xbfb8aa3b, v120
	v_exp_f32_e32 v151, v151
	v_exp_f32_e32 v155, v154
	v_mul_f32_e32 v154, 0xbfb8aa3b, v125
	v_exp_f32_e32 v156, v154
	v_add_f32_e32 v151, 1.0, v151
	v_rcp_f32_e32 v154, v151
	v_add_f32_e32 v151, 1.0, v155
	v_add_f32_e32 v155, 1.0, v156
	v_rcp_f32_e32 v155, v155
	v_mul_f32_e32 v156, 0xbfb8aa3b, v121
	v_exp_f32_e32 v157, v156
	v_rcp_f32_e32 v156, v151
	v_pk_mul_f32 v[124:125], v[124:125], v[154:155]
	v_mul_f32_e32 v151, 0xbfb8aa3b, v127
	v_pk_mul_f32 v[116:117], v[124:125], v[116:117]
	v_add_f32_e32 v124, 1.0, v157
	v_mul_f32_e32 v125, 0xbfb8aa3b, v122
	v_rcp_f32_e32 v157, v124
	v_mul_f32_e32 v124, 0xbfb8aa3b, v126
	v_exp_f32_e32 v125, v125
	v_exp_f32_e32 v124, v124
	v_exp_f32_e32 v151, v151
	v_mul_f32_e32 v154, 0xbfb8aa3b, v123
	v_exp_f32_e32 v155, v154
	v_add_f32_e32 v125, 1.0, v125
	v_add_f32_e32 v124, 1.0, v124
	v_rcp_f32_e32 v154, v125
	v_add_f32_e32 v125, 1.0, v151
	v_rcp_f32_e32 v124, v124
	v_rcp_f32_e32 v125, v125
	v_add_f32_e32 v151, 1.0, v155
	v_rcp_f32_e32 v155, v151
	v_pk_mul_f32 v[120:121], v[120:121], v[156:157]
	v_lshl_or_b32 v152, s46, 7, v146
	v_pk_mul_f32 v[112:113], v[120:121], v[112:113]
	v_pk_mul_f32 v[120:121], v[126:127], v[124:125]
	v_lshl_add_u32 v150, s20, 8, v144
	v_pk_mul_f32 v[118:119], v[120:121], v[118:119]
	v_pk_mul_f32 v[120:121], v[122:123], v[154:155]
	v_ashrrev_i32_e32 v153, 31, v152
	v_pk_mul_f32 v[114:115], v[120:121], v[114:115]
	v_cvt_pk_bf16_f32 v116, v116, v117
	v_cvt_pk_bf16_f32 v117, v118, v119
	v_cvt_pk_bf16_f32 v118, v112, v113
	v_mov_b64_e32 v[112:113], s[6:7]
	v_cvt_pk_bf16_f32 v119, v114, v115
	v_mad_i64_i32 v[120:121], s[22:23], v150, s45, v[112:113]
	v_lshlrev_b64 v[114:115], 1, v[152:153]
	v_lshl_add_u64 v[120:121], v[120:121], 0, v[114:115]
	global_store_dwordx4 v[120:121], v[116:119], off
	s_andn2_b64 vcc, exec, s[2:3]
	s_mov_b64 s[2:3], -1
	v_mul_f32_e32 v116, 0xbfb8aa3b, v108
	v_mul_f32_e32 v117, 0xbfb8aa3b, v104
	v_mul_f32_e32 v118, 0xbfb8aa3b, v109
	v_exp_f32_e32 v116, v116
	v_exp_f32_e32 v117, v117
	v_exp_f32_e32 v118, v118
	v_add_f32_e32 v116, 1.0, v116
	v_add_f32_e32 v119, 1.0, v117
	v_add_f32_e32 v117, 1.0, v118
	v_rcp_f32_e32 v116, v116
	v_rcp_f32_e32 v117, v117
	v_mul_f32_e32 v118, 0xbfb8aa3b, v105
	v_exp_f32_e32 v120, v118
	v_rcp_f32_e32 v118, v119
	v_pk_mul_f32 v[108:109], v[108:109], v[116:117]
	v_mul_f32_e32 v116, 0xbfb8aa3b, v111
	v_pk_mul_f32 v[100:101], v[108:109], v[100:101]
	v_add_f32_e32 v108, 1.0, v120
	v_rcp_f32_e32 v119, v108
	v_mul_f32_e32 v109, 0xbfb8aa3b, v106
	v_mul_f32_e32 v108, 0xbfb8aa3b, v110
	v_exp_f32_e32 v109, v109
	v_exp_f32_e32 v108, v108
	v_exp_f32_e32 v117, v116
	v_mul_f32_e32 v116, 0xbfb8aa3b, v107
	v_pk_mul_f32 v[104:105], v[104:105], v[118:119]
	v_exp_f32_e32 v118, v116
	v_add_f32_e32 v109, 1.0, v109
	v_add_f32_e32 v108, 1.0, v108
	v_rcp_f32_e32 v116, v109
	v_add_f32_e32 v109, 1.0, v117
	v_rcp_f32_e32 v108, v108
	v_rcp_f32_e32 v109, v109
	v_add_f32_e32 v117, 1.0, v118
	v_rcp_f32_e32 v117, v117
	v_pk_mul_f32 v[104:105], v[104:105], v[96:97]
	v_pk_mul_f32 v[96:97], v[110:111], v[108:109]
	v_or_b32_e32 v108, 16, v150
	v_pk_mul_f32 v[102:103], v[96:97], v[102:103]
	v_pk_mul_f32 v[96:97], v[106:107], v[116:117]
	s_nop 0
	v_pk_mul_f32 v[106:107], v[96:97], v[98:99]
	v_cvt_pk_bf16_f32 v96, v100, v101
	v_mad_i64_i32 v[100:101], s[22:23], v108, s45, v[112:113]
	v_cvt_pk_bf16_f32 v97, v102, v103
	v_cvt_pk_bf16_f32 v98, v104, v105
	v_cvt_pk_bf16_f32 v99, v106, v107
	v_lshl_add_u64 v[100:101], v[100:101], 0, v[114:115]
	global_store_dwordx4 v[100:101], v[96:99], off
	s_nop 1
	v_mul_f32_e32 v96, 0xbfb8aa3b, v92
	v_mul_f32_e32 v97, 0xbfb8aa3b, v88
	v_mul_f32_e32 v98, 0xbfb8aa3b, v93
	v_exp_f32_e32 v96, v96
	v_exp_f32_e32 v97, v97
	v_exp_f32_e32 v98, v98
	v_add_f32_e32 v96, 1.0, v96
	v_add_f32_e32 v99, 1.0, v97
	v_add_f32_e32 v97, 1.0, v98
	v_rcp_f32_e32 v96, v96
	v_rcp_f32_e32 v97, v97
	v_mul_f32_e32 v98, 0xbfb8aa3b, v89
	v_exp_f32_e32 v100, v98
	v_rcp_f32_e32 v98, v99
	v_pk_mul_f32 v[92:93], v[92:93], v[96:97]
	v_mul_f32_e32 v96, 0xbfb8aa3b, v95
	v_pk_mul_f32 v[84:85], v[92:93], v[84:85]
	v_add_f32_e32 v92, 1.0, v100
	v_rcp_f32_e32 v99, v92
	v_mul_f32_e32 v93, 0xbfb8aa3b, v90
	v_mul_f32_e32 v92, 0xbfb8aa3b, v94
	v_exp_f32_e32 v93, v93
	v_exp_f32_e32 v92, v92
	v_exp_f32_e32 v97, v96
	v_mul_f32_e32 v96, 0xbfb8aa3b, v91
	v_pk_mul_f32 v[88:89], v[88:89], v[98:99]
	v_exp_f32_e32 v98, v96
	v_add_f32_e32 v93, 1.0, v93
	v_add_f32_e32 v92, 1.0, v92
	v_rcp_f32_e32 v96, v93
	v_add_f32_e32 v93, 1.0, v97
	v_rcp_f32_e32 v92, v92
	v_rcp_f32_e32 v93, v93
	v_add_f32_e32 v97, 1.0, v98
	v_rcp_f32_e32 v97, v97
	v_pk_mul_f32 v[88:89], v[88:89], v[80:81]
	v_pk_mul_f32 v[80:81], v[94:95], v[92:93]
	v_or_b32_e32 v92, 32, v150
	v_pk_mul_f32 v[86:87], v[80:81], v[86:87]
	v_pk_mul_f32 v[80:81], v[90:91], v[96:97]
	s_nop 0
	v_pk_mul_f32 v[90:91], v[80:81], v[82:83]
	v_cvt_pk_bf16_f32 v80, v84, v85
	v_mad_i64_i32 v[84:85], s[22:23], v92, s45, v[112:113]
	v_cvt_pk_bf16_f32 v81, v86, v87
	v_cvt_pk_bf16_f32 v82, v88, v89
	v_cvt_pk_bf16_f32 v83, v90, v91
	v_lshl_add_u64 v[84:85], v[84:85], 0, v[114:115]
	global_store_dwordx4 v[84:85], v[80:83], off
	s_nop 1
	v_mul_f32_e32 v80, 0xbfb8aa3b, v76
	v_mul_f32_e32 v81, 0xbfb8aa3b, v72
	v_mul_f32_e32 v82, 0xbfb8aa3b, v77
	v_exp_f32_e32 v80, v80
	v_exp_f32_e32 v81, v81
	v_exp_f32_e32 v82, v82
	v_add_f32_e32 v80, 1.0, v80
	v_add_f32_e32 v83, 1.0, v81
	v_add_f32_e32 v81, 1.0, v82
	v_rcp_f32_e32 v80, v80
	v_rcp_f32_e32 v81, v81
	v_mul_f32_e32 v82, 0xbfb8aa3b, v73
	v_exp_f32_e32 v84, v82
	v_rcp_f32_e32 v82, v83
	v_pk_mul_f32 v[76:77], v[76:77], v[80:81]
	v_mul_f32_e32 v80, 0xbfb8aa3b, v79
	v_pk_mul_f32 v[68:69], v[76:77], v[68:69]
	v_add_f32_e32 v76, 1.0, v84
	v_rcp_f32_e32 v83, v76
	v_mul_f32_e32 v77, 0xbfb8aa3b, v74
	v_mul_f32_e32 v76, 0xbfb8aa3b, v78
	v_exp_f32_e32 v77, v77
	v_exp_f32_e32 v76, v76
	v_exp_f32_e32 v81, v80
	v_mul_f32_e32 v80, 0xbfb8aa3b, v75
	v_pk_mul_f32 v[72:73], v[72:73], v[82:83]
	v_exp_f32_e32 v82, v80
	v_add_f32_e32 v77, 1.0, v77
	v_add_f32_e32 v76, 1.0, v76
	v_rcp_f32_e32 v80, v77
	v_add_f32_e32 v77, 1.0, v81
	v_rcp_f32_e32 v76, v76
	v_rcp_f32_e32 v77, v77
	v_add_f32_e32 v81, 1.0, v82
	v_rcp_f32_e32 v81, v81
	v_pk_mul_f32 v[72:73], v[72:73], v[64:65]
	v_pk_mul_f32 v[64:65], v[78:79], v[76:77]
	v_or_b32_e32 v76, 48, v150
	v_pk_mul_f32 v[70:71], v[64:65], v[70:71]
	v_pk_mul_f32 v[64:65], v[74:75], v[80:81]
	s_nop 0
	v_pk_mul_f32 v[74:75], v[64:65], v[66:67]
	v_cvt_pk_bf16_f32 v64, v68, v69
	v_mad_i64_i32 v[68:69], s[22:23], v76, s45, v[112:113]
	v_cvt_pk_bf16_f32 v65, v70, v71
	v_cvt_pk_bf16_f32 v66, v72, v73
	v_cvt_pk_bf16_f32 v67, v74, v75
	v_lshl_add_u64 v[68:69], v[68:69], 0, v[114:115]
	global_store_dwordx4 v[68:69], v[64:67], off
	v_add_u32_e32 v68, 0x80, v150
	s_nop 0
	v_mul_f32_e32 v64, 0xbfb8aa3b, v60
	v_mul_f32_e32 v65, 0xbfb8aa3b, v56
	v_mul_f32_e32 v66, 0xbfb8aa3b, v61
	v_exp_f32_e32 v64, v64
	v_exp_f32_e32 v65, v65
	v_exp_f32_e32 v66, v66
	v_add_f32_e32 v64, 1.0, v64
	v_add_f32_e32 v67, 1.0, v65
	v_add_f32_e32 v65, 1.0, v66
	v_rcp_f32_e32 v64, v64
	v_rcp_f32_e32 v65, v65
	v_mul_f32_e32 v66, 0xbfb8aa3b, v57
	v_exp_f32_e32 v69, v66
	v_rcp_f32_e32 v66, v67
	v_pk_mul_f32 v[60:61], v[60:61], v[64:65]
	v_mul_f32_e32 v64, 0xbfb8aa3b, v63
	v_pk_mul_f32 v[52:53], v[60:61], v[52:53]
	v_add_f32_e32 v60, 1.0, v69
	v_rcp_f32_e32 v67, v60
	v_mul_f32_e32 v61, 0xbfb8aa3b, v58
	v_mul_f32_e32 v60, 0xbfb8aa3b, v62
	v_exp_f32_e32 v61, v61
	v_exp_f32_e32 v60, v60
	v_exp_f32_e32 v65, v64
	v_mul_f32_e32 v64, 0xbfb8aa3b, v59
	v_pk_mul_f32 v[56:57], v[56:57], v[66:67]
	v_exp_f32_e32 v66, v64
	v_add_f32_e32 v61, 1.0, v61
	v_add_f32_e32 v60, 1.0, v60
	v_rcp_f32_e32 v64, v61
	v_add_f32_e32 v61, 1.0, v65
	v_rcp_f32_e32 v60, v60
	v_rcp_f32_e32 v61, v61
	v_add_f32_e32 v65, 1.0, v66
	v_rcp_f32_e32 v65, v65
	v_pk_mul_f32 v[56:57], v[56:57], v[48:49]
	v_pk_mul_f32 v[48:49], v[62:63], v[60:61]
	s_nop 0
	v_pk_mul_f32 v[54:55], v[48:49], v[54:55]
	v_pk_mul_f32 v[48:49], v[58:59], v[64:65]
	s_nop 0
	v_pk_mul_f32 v[58:59], v[48:49], v[50:51]
	v_cvt_pk_bf16_f32 v48, v52, v53
	v_mad_i64_i32 v[52:53], s[22:23], v68, s45, v[112:113]
	v_cvt_pk_bf16_f32 v49, v54, v55
	v_cvt_pk_bf16_f32 v50, v56, v57
	v_cvt_pk_bf16_f32 v51, v58, v59
	v_lshl_add_u64 v[52:53], v[52:53], 0, v[114:115]
	global_store_dwordx4 v[52:53], v[48:51], off
	s_nop 1
	v_mul_f32_e32 v48, 0xbfb8aa3b, v44
	v_mul_f32_e32 v49, 0xbfb8aa3b, v40
	v_mul_f32_e32 v50, 0xbfb8aa3b, v45
	v_exp_f32_e32 v48, v48
	v_exp_f32_e32 v49, v49
	v_exp_f32_e32 v50, v50
	v_add_f32_e32 v48, 1.0, v48
	v_add_f32_e32 v51, 1.0, v49
	v_add_f32_e32 v49, 1.0, v50
	v_rcp_f32_e32 v48, v48
	v_rcp_f32_e32 v49, v49
	v_mul_f32_e32 v50, 0xbfb8aa3b, v41
	v_exp_f32_e32 v52, v50
	v_rcp_f32_e32 v50, v51
	v_pk_mul_f32 v[44:45], v[44:45], v[48:49]
	v_mul_f32_e32 v48, 0xbfb8aa3b, v47
	v_pk_mul_f32 v[36:37], v[44:45], v[36:37]
	v_add_f32_e32 v44, 1.0, v52
	v_rcp_f32_e32 v51, v44
	v_mul_f32_e32 v45, 0xbfb8aa3b, v42
	v_mul_f32_e32 v44, 0xbfb8aa3b, v46
	v_exp_f32_e32 v45, v45
	v_exp_f32_e32 v44, v44
	v_exp_f32_e32 v49, v48
	v_mul_f32_e32 v48, 0xbfb8aa3b, v43
	v_pk_mul_f32 v[40:41], v[40:41], v[50:51]
	v_exp_f32_e32 v50, v48
	v_add_f32_e32 v45, 1.0, v45
	v_add_f32_e32 v44, 1.0, v44
	v_rcp_f32_e32 v48, v45
	v_add_f32_e32 v45, 1.0, v49
	v_rcp_f32_e32 v44, v44
	v_rcp_f32_e32 v45, v45
	v_add_f32_e32 v49, 1.0, v50
	v_rcp_f32_e32 v49, v49
	v_pk_mul_f32 v[40:41], v[40:41], v[32:33]
	v_pk_mul_f32 v[32:33], v[46:47], v[44:45]
	v_add_u32_e32 v44, 0x90, v150
	v_pk_mul_f32 v[38:39], v[32:33], v[38:39]
	v_pk_mul_f32 v[32:33], v[42:43], v[48:49]
	s_nop 0
	v_pk_mul_f32 v[42:43], v[32:33], v[34:35]
	v_cvt_pk_bf16_f32 v32, v36, v37
	v_mad_i64_i32 v[36:37], s[22:23], v44, s45, v[112:113]
	v_cvt_pk_bf16_f32 v33, v38, v39
	v_cvt_pk_bf16_f32 v34, v40, v41
	v_cvt_pk_bf16_f32 v35, v42, v43
	v_lshl_add_u64 v[36:37], v[36:37], 0, v[114:115]
	global_store_dwordx4 v[36:37], v[32:35], off
	s_nop 1
	v_mul_f32_e32 v32, 0xbfb8aa3b, v28
	v_mul_f32_e32 v33, 0xbfb8aa3b, v24
	v_mul_f32_e32 v34, 0xbfb8aa3b, v29
	v_exp_f32_e32 v32, v32
	v_exp_f32_e32 v33, v33
	v_exp_f32_e32 v34, v34
	v_add_f32_e32 v32, 1.0, v32
	v_add_f32_e32 v35, 1.0, v33
	v_add_f32_e32 v33, 1.0, v34
	v_rcp_f32_e32 v32, v32
	v_rcp_f32_e32 v33, v33
	v_mul_f32_e32 v34, 0xbfb8aa3b, v25
	v_exp_f32_e32 v36, v34
	v_rcp_f32_e32 v34, v35
	v_pk_mul_f32 v[28:29], v[28:29], v[32:33]
	v_mul_f32_e32 v32, 0xbfb8aa3b, v31
	v_pk_mul_f32 v[20:21], v[28:29], v[20:21]
	v_add_f32_e32 v28, 1.0, v36
	v_rcp_f32_e32 v35, v28
	v_mul_f32_e32 v29, 0xbfb8aa3b, v26
	v_mul_f32_e32 v28, 0xbfb8aa3b, v30
	v_exp_f32_e32 v29, v29
	v_exp_f32_e32 v28, v28
	v_exp_f32_e32 v33, v32
	v_mul_f32_e32 v32, 0xbfb8aa3b, v27
	v_pk_mul_f32 v[24:25], v[24:25], v[34:35]
	v_exp_f32_e32 v34, v32
	v_add_f32_e32 v29, 1.0, v29
	v_add_f32_e32 v28, 1.0, v28
	v_rcp_f32_e32 v32, v29
	v_add_f32_e32 v29, 1.0, v33
	v_rcp_f32_e32 v28, v28
	v_rcp_f32_e32 v29, v29
	v_add_f32_e32 v33, 1.0, v34
	v_rcp_f32_e32 v33, v33
	v_pk_mul_f32 v[24:25], v[24:25], v[16:17]
	v_pk_mul_f32 v[16:17], v[30:31], v[28:29]
	v_add_u32_e32 v28, 0xa0, v150
	v_pk_mul_f32 v[22:23], v[16:17], v[22:23]
	v_pk_mul_f32 v[16:17], v[26:27], v[32:33]
	s_nop 0
	v_pk_mul_f32 v[26:27], v[16:17], v[18:19]
	v_cvt_pk_bf16_f32 v16, v20, v21
	v_mad_i64_i32 v[20:21], s[22:23], v28, s45, v[112:113]
	v_cvt_pk_bf16_f32 v17, v22, v23
	v_cvt_pk_bf16_f32 v18, v24, v25
	v_cvt_pk_bf16_f32 v19, v26, v27
	v_lshl_add_u64 v[20:21], v[20:21], 0, v[114:115]
	global_store_dwordx4 v[20:21], v[16:19], off
	s_nop 1
	v_mul_f32_e32 v16, 0xbfb8aa3b, v12
	v_mul_f32_e32 v17, 0xbfb8aa3b, v8
	v_mul_f32_e32 v18, 0xbfb8aa3b, v13
	v_exp_f32_e32 v16, v16
	v_exp_f32_e32 v17, v17
	v_exp_f32_e32 v18, v18
	v_add_f32_e32 v16, 1.0, v16
	v_add_f32_e32 v19, 1.0, v17
	v_add_f32_e32 v17, 1.0, v18
	v_rcp_f32_e32 v16, v16
	v_rcp_f32_e32 v17, v17
	v_mul_f32_e32 v18, 0xbfb8aa3b, v9
	v_exp_f32_e32 v20, v18
	v_rcp_f32_e32 v18, v19
	v_pk_mul_f32 v[12:13], v[12:13], v[16:17]
	v_mul_f32_e32 v16, 0xbfb8aa3b, v15
	v_pk_mul_f32 v[4:5], v[12:13], v[4:5]
	v_add_f32_e32 v12, 1.0, v20
	v_rcp_f32_e32 v19, v12
	v_mul_f32_e32 v13, 0xbfb8aa3b, v10
	v_mul_f32_e32 v12, 0xbfb8aa3b, v14
	v_exp_f32_e32 v13, v13
	v_exp_f32_e32 v12, v12
	v_exp_f32_e32 v17, v16
	v_mul_f32_e32 v16, 0xbfb8aa3b, v11
	v_pk_mul_f32 v[8:9], v[8:9], v[18:19]
	v_exp_f32_e32 v18, v16
	v_add_f32_e32 v13, 1.0, v13
	v_add_f32_e32 v12, 1.0, v12
	v_rcp_f32_e32 v16, v13
	v_add_f32_e32 v13, 1.0, v17
	v_rcp_f32_e32 v12, v12
	v_rcp_f32_e32 v13, v13
	v_add_f32_e32 v17, 1.0, v18
	v_rcp_f32_e32 v17, v17
	v_pk_mul_f32 v[8:9], v[8:9], v[0:1]
	v_pk_mul_f32 v[0:1], v[14:15], v[12:13]
	v_add_u32_e32 v12, 0xb0, v150
	v_pk_mul_f32 v[6:7], v[0:1], v[6:7]
	v_pk_mul_f32 v[0:1], v[10:11], v[16:17]
	s_nop 0
	v_pk_mul_f32 v[10:11], v[0:1], v[2:3]
	v_cvt_pk_bf16_f32 v0, v4, v5
	v_mad_i64_i32 v[4:5], s[22:23], v12, s45, v[112:113]
	v_cvt_pk_bf16_f32 v1, v6, v7
	v_cvt_pk_bf16_f32 v2, v8, v9
	v_cvt_pk_bf16_f32 v3, v10, v11
	v_lshl_add_u64 v[4:5], v[4:5], 0, v[114:115]
	global_store_dwordx4 v[4:5], v[0:3], off
	s_cbranch_vccnz .LBB0_1235
	s_andn2_b64 vcc, exec, s[0:1]
	s_cbranch_vccnz .LBB0_1234
	v_writelane_b32 v255, 1, 53
	s_branch .LBB0_1234

.LBB0_1323:
	s_add_u32 s16, s16, 0xb0080
	s_addc_u32 s17, s17, 0
	s_add_u32 s50, s18, 0x100
	v_mov_b32_e32 v0, 0
	s_addc_u32 s51, s19, 0
	s_mov_b32 s52, -2
	v_mov_b32_e32 v1, v0
	v_mov_b32_e32 v2, v0
	v_mov_b32_e32 v3, v0
	v_mov_b32_e32 v4, v0
	v_mov_b32_e32 v5, v0
	v_mov_b32_e32 v6, v0
	v_mov_b32_e32 v7, v0
	v_mov_b32_e32 v8, v0
	v_mov_b32_e32 v9, v0
	v_mov_b32_e32 v10, v0
	v_mov_b32_e32 v11, v0
	v_mov_b32_e32 v16, v0
	v_mov_b32_e32 v17, v0
	v_mov_b32_e32 v18, v0
	v_mov_b32_e32 v19, v0
	v_mov_b32_e32 v28, v0
	v_mov_b32_e32 v29, v0
	v_mov_b32_e32 v30, v0
	v_mov_b32_e32 v31, v0
	v_mov_b32_e32 v36, v0
	v_mov_b32_e32 v37, v0
	v_mov_b32_e32 v38, v0
	v_mov_b32_e32 v39, v0
	v_mov_b32_e32 v44, v0
	v_mov_b32_e32 v45, v0
	v_mov_b32_e32 v46, v0
	v_mov_b32_e32 v47, v0
	v_mov_b32_e32 v52, v0
	v_mov_b32_e32 v53, v0
	v_mov_b32_e32 v54, v0
	v_mov_b32_e32 v55, v0
	v_mov_b32_e32 v12, v0
	v_mov_b32_e32 v13, v0
	v_mov_b32_e32 v14, v0
	v_mov_b32_e32 v15, v0
	v_mov_b32_e32 v20, v0
	v_mov_b32_e32 v21, v0
	v_mov_b32_e32 v22, v0
	v_mov_b32_e32 v23, v0
	v_mov_b32_e32 v24, v0
	v_mov_b32_e32 v25, v0
	v_mov_b32_e32 v26, v0
	v_mov_b32_e32 v27, v0
	v_mov_b32_e32 v32, v0
	v_mov_b32_e32 v33, v0
	v_mov_b32_e32 v34, v0
	v_mov_b32_e32 v35, v0
	v_mov_b32_e32 v40, v0
	v_mov_b32_e32 v41, v0
	v_mov_b32_e32 v42, v0
	v_mov_b32_e32 v43, v0
	v_mov_b32_e32 v48, v0
	v_mov_b32_e32 v49, v0
	v_mov_b32_e32 v50, v0
	v_mov_b32_e32 v51, v0
	v_mov_b32_e32 v56, v0
	v_mov_b32_e32 v57, v0
	v_mov_b32_e32 v58, v0
	v_mov_b32_e32 v59, v0
	v_mov_b32_e32 v60, v0
	v_mov_b32_e32 v61, v0
	v_mov_b32_e32 v62, v0
	v_mov_b32_e32 v63, v0
	v_mov_b32_e32 v64, v0
	v_mov_b32_e32 v65, v0
	v_mov_b32_e32 v66, v0
	v_mov_b32_e32 v67, v0
	v_mov_b32_e32 v68, v0
	v_mov_b32_e32 v69, v0
	v_mov_b32_e32 v70, v0
	v_mov_b32_e32 v71, v0
	v_mov_b32_e32 v72, v0
	v_mov_b32_e32 v73, v0
	v_mov_b32_e32 v74, v0
	v_mov_b32_e32 v75, v0
	v_mov_b32_e32 v80, v0
	v_mov_b32_e32 v81, v0
	v_mov_b32_e32 v82, v0
	v_mov_b32_e32 v83, v0
	v_mov_b32_e32 v92, v0
	v_mov_b32_e32 v93, v0
	v_mov_b32_e32 v94, v0
	v_mov_b32_e32 v95, v0
	v_mov_b32_e32 v100, v0
	v_mov_b32_e32 v101, v0
	v_mov_b32_e32 v102, v0
	v_mov_b32_e32 v103, v0
	v_mov_b32_e32 v108, v0
	v_mov_b32_e32 v109, v0
	v_mov_b32_e32 v110, v0
	v_mov_b32_e32 v111, v0
	v_mov_b32_e32 v116, v0
	v_mov_b32_e32 v117, v0
	v_mov_b32_e32 v118, v0
	v_mov_b32_e32 v119, v0
	v_mov_b32_e32 v76, v0
	v_mov_b32_e32 v77, v0
	v_mov_b32_e32 v78, v0
	v_mov_b32_e32 v79, v0
	v_mov_b32_e32 v84, v0
	v_mov_b32_e32 v85, v0
	v_mov_b32_e32 v86, v0
	v_mov_b32_e32 v87, v0
	v_mov_b32_e32 v88, v0
	v_mov_b32_e32 v89, v0
	v_mov_b32_e32 v90, v0
	v_mov_b32_e32 v91, v0
	v_mov_b32_e32 v96, v0
	v_mov_b32_e32 v97, v0
	v_mov_b32_e32 v98, v0
	v_mov_b32_e32 v99, v0
	v_mov_b32_e32 v104, v0
	v_mov_b32_e32 v105, v0
	v_mov_b32_e32 v106, v0
	v_mov_b32_e32 v107, v0
	v_mov_b32_e32 v112, v0
	v_mov_b32_e32 v113, v0
	v_mov_b32_e32 v114, v0
	v_mov_b32_e32 v115, v0
	v_mov_b32_e32 v120, v0
	v_mov_b32_e32 v121, v0
	v_mov_b32_e32 v122, v0
	v_mov_b32_e32 v123, v0
	v_mov_b32_e32 v124, v0
	v_mov_b32_e32 v125, v0
	v_mov_b32_e32 v126, v0
	v_mov_b32_e32 v127, v0
	v_readlane_b32 s97, v255, 53
	s_nop 3
	s_cmp_eq_u32 s97, 1
	s_cbranch_scc0 .Llsb_skip_10
	v_writelane_b32 v255, 0, 53
	s_barrier
.Llsb_skip_10:
.LBB0_1324:
	ds_read_b128 v[128:131], v212
	ds_read_b128 v[132:135], v212 offset:1024
	ds_read_b128 v[136:139], v212 offset:2048
	ds_read_b128 v[140:143], v212 offset:3072
	ds_read_b128 v[144:147], v213
	ds_read_b128 v[148:151], v213 offset:1024
	ds_read_b128 v[152:155], v213 offset:2048
	ds_read_b128 v[156:159], v213 offset:3072
	s_add_u32 s18, s16, 0xfff50080
	s_addc_u32 s19, s17, -1
	s_cmp_eq_u32 s52, 40
	s_cselect_b32 s21, s5, s19
	s_cselect_b32 s20, s4, s18
	s_cselect_b32 s19, s15, s51
	s_cselect_b32 s18, s14, s50
	v_lshl_add_u64 v[202:203], s[16:17], 0, v[182:183]
	s_add_i32 m0, s23, 0xc000
	ds_read_b128 v[160:163], v214
	ds_read_b128 v[164:167], v214 offset:1024
	ds_read_b128 v[168:171], v214 offset:2048
	ds_read_b128 v[172:175], v214 offset:3072
	ds_read_b128 v[190:193], v214 offset:4096
	ds_read_b128 v[194:197], v214 offset:5120
	ds_read_b128 v[198:201], v214 offset:6144
	ds_read_b128 v[216:219], v214 offset:7168
	global_load_lds_dwordx4 v[202:203], off
	v_lshl_add_u64 v[202:203], s[16:17], 0, v[184:185]
	s_add_i32 m0, s23, 0xe000
	s_nop 0
	global_load_lds_dwordx4 v[202:203], off
	s_waitcnt vmcnt(8)
	s_waitcnt lgkmcnt(0)
	s_barrier
	s_setprio 1
	s_waitcnt lgkmcnt(0)
	v_mfma_f32_16x16x32_bf16 v[124:127], v[128:131], v[160:163], v[124:127]
	v_mfma_f32_16x16x32_bf16 v[120:123], v[136:139], v[160:163], v[120:123]
	v_mfma_f32_16x16x32_bf16 v[112:115], v[128:131], v[168:171], v[112:115]
	v_mfma_f32_16x16x32_bf16 v[104:107], v[136:139], v[168:171], v[104:107]
	v_mfma_f32_16x16x32_bf16 v[96:99], v[128:131], v[190:193], v[96:99]
	v_mfma_f32_16x16x32_bf16 v[88:91], v[136:139], v[190:193], v[88:91]
	v_mfma_f32_16x16x32_bf16 v[84:87], v[128:131], v[198:201], v[84:87]
	v_mfma_f32_16x16x32_bf16 v[76:79], v[136:139], v[198:201], v[76:79]
	v_mfma_f32_16x16x32_bf16 v[124:127], v[132:135], v[164:167], v[124:127]
	v_mfma_f32_16x16x32_bf16 v[120:123], v[140:143], v[164:167], v[120:123]
	v_mfma_f32_16x16x32_bf16 v[112:115], v[132:135], v[172:175], v[112:115]
	v_mfma_f32_16x16x32_bf16 v[104:107], v[140:143], v[172:175], v[104:107]
	v_mfma_f32_16x16x32_bf16 v[96:99], v[132:135], v[194:197], v[96:99]
	v_mfma_f32_16x16x32_bf16 v[88:91], v[140:143], v[194:197], v[88:91]
	v_mfma_f32_16x16x32_bf16 v[84:87], v[132:135], v[216:219], v[84:87]
	v_mfma_f32_16x16x32_bf16 v[76:79], v[140:143], v[216:219], v[76:79]
	s_setprio 0
	s_setprio 1
	v_mfma_f32_16x16x32_bf16 v[116:119], v[144:147], v[160:163], v[116:119]
	v_mfma_f32_16x16x32_bf16 v[108:111], v[152:155], v[160:163], v[108:111]
	v_mfma_f32_16x16x32_bf16 v[100:103], v[144:147], v[168:171], v[100:103]
	v_mfma_f32_16x16x32_bf16 v[92:95], v[152:155], v[168:171], v[92:95]
	v_mfma_f32_16x16x32_bf16 v[80:83], v[144:147], v[190:193], v[80:83]
	v_mfma_f32_16x16x32_bf16 v[72:75], v[152:155], v[190:193], v[72:75]
	v_mfma_f32_16x16x32_bf16 v[68:71], v[144:147], v[198:201], v[68:71]
	v_mfma_f32_16x16x32_bf16 v[64:67], v[152:155], v[198:201], v[64:67]
	v_mfma_f32_16x16x32_bf16 v[116:119], v[148:151], v[164:167], v[116:119]
	v_mfma_f32_16x16x32_bf16 v[108:111], v[156:159], v[164:167], v[108:111]
	v_mfma_f32_16x16x32_bf16 v[100:103], v[148:151], v[172:175], v[100:103]
	v_mfma_f32_16x16x32_bf16 v[92:95], v[156:159], v[172:175], v[92:95]
	v_mfma_f32_16x16x32_bf16 v[80:83], v[148:151], v[194:197], v[80:83]
	v_mfma_f32_16x16x32_bf16 v[72:75], v[156:159], v[194:197], v[72:75]
	v_mfma_f32_16x16x32_bf16 v[68:71], v[148:151], v[216:219], v[68:71]
	v_mfma_f32_16x16x32_bf16 v[64:67], v[156:159], v[216:219], v[64:67]
	s_setprio 0
	s_barrier
	s_add_i32 s53, s35, s22
	v_lshl_add_u64 v[202:203], s[18:19], 0, v[176:177]
	s_mov_b32 m0, s53
	ds_read_b128 v[160:163], v214 offset:16384
	ds_read_b128 v[164:167], v214 offset:17408
	ds_read_b128 v[168:171], v214 offset:18432
	ds_read_b128 v[172:175], v214 offset:19456
	ds_read_b128 v[190:193], v214 offset:20480
	ds_read_b128 v[194:197], v214 offset:21504
	ds_read_b128 v[198:201], v214 offset:22528
	ds_read_b128 v[216:219], v214 offset:23552
	global_load_lds_dwordx4 v[202:203], off
	s_add_i32 m0, s53, 0x2000
	s_add_u32 s54, s18, 0xb0000
	v_lshl_add_u64 v[220:221], s[18:19], 0, v[178:179]
	s_addc_u32 s55, s19, 0
	s_add_i32 s53, s40, s22
	global_load_lds_dwordx4 v[220:221], off
	v_lshl_add_u64 v[222:223], s[54:55], 0, v[176:177]
	s_mov_b32 m0, s53
	v_lshl_add_u64 v[224:225], s[20:21], 0, v[178:179]
	global_load_lds_dwordx4 v[222:223], off
	v_lshl_add_u64 v[222:223], s[54:55], 0, v[178:179]
	s_add_i32 m0, s53, 0x2000
	s_nop 0
	global_load_lds_dwordx4 v[222:223], off
	v_lshl_add_u64 v[222:223], s[20:21], 0, v[176:177]
	s_mov_b32 m0, s23
	s_nop 0
	global_load_lds_dwordx4 v[222:223], off
	s_mov_b32 m0, s24
	s_nop 0
	global_load_lds_dwordx4 v[224:225], off
	s_waitcnt vmcnt(8)
	s_waitcnt lgkmcnt(0)
	s_barrier
	s_setprio 1
	s_waitcnt lgkmcnt(0)
	v_mfma_f32_16x16x32_bf16 v[60:63], v[128:131], v[160:163], v[60:63]
	v_mfma_f32_16x16x32_bf16 v[56:59], v[136:139], v[160:163], v[56:59]
	v_mfma_f32_16x16x32_bf16 v[48:51], v[128:131], v[168:171], v[48:51]
	v_mfma_f32_16x16x32_bf16 v[40:43], v[136:139], v[168:171], v[40:43]
	v_mfma_f32_16x16x32_bf16 v[32:35], v[128:131], v[190:193], v[32:35]
	v_mfma_f32_16x16x32_bf16 v[24:27], v[136:139], v[190:193], v[24:27]
	v_mfma_f32_16x16x32_bf16 v[20:23], v[128:131], v[198:201], v[20:23]
	v_mfma_f32_16x16x32_bf16 v[12:15], v[136:139], v[198:201], v[12:15]
	v_mfma_f32_16x16x32_bf16 v[60:63], v[132:135], v[164:167], v[60:63]
	v_mfma_f32_16x16x32_bf16 v[56:59], v[140:143], v[164:167], v[56:59]
	v_mfma_f32_16x16x32_bf16 v[48:51], v[132:135], v[172:175], v[48:51]
	v_mfma_f32_16x16x32_bf16 v[40:43], v[140:143], v[172:175], v[40:43]
	v_mfma_f32_16x16x32_bf16 v[32:35], v[132:135], v[194:197], v[32:35]
	v_mfma_f32_16x16x32_bf16 v[24:27], v[140:143], v[194:197], v[24:27]
	v_mfma_f32_16x16x32_bf16 v[20:23], v[132:135], v[216:219], v[20:23]
	v_mfma_f32_16x16x32_bf16 v[12:15], v[140:143], v[216:219], v[12:15]
	s_setprio 0
	s_setprio 1
	v_mfma_f32_16x16x32_bf16 v[52:55], v[144:147], v[160:163], v[52:55]
	v_mfma_f32_16x16x32_bf16 v[44:47], v[152:155], v[160:163], v[44:47]
	v_mfma_f32_16x16x32_bf16 v[36:39], v[144:147], v[168:171], v[36:39]
	v_mfma_f32_16x16x32_bf16 v[28:31], v[152:155], v[168:171], v[28:31]
	v_mfma_f32_16x16x32_bf16 v[16:19], v[144:147], v[190:193], v[16:19]
	v_mfma_f32_16x16x32_bf16 v[8:11], v[152:155], v[190:193], v[8:11]
	v_mfma_f32_16x16x32_bf16 v[4:7], v[144:147], v[198:201], v[4:7]
	v_mfma_f32_16x16x32_bf16 v[0:3], v[152:155], v[198:201], v[0:3]
	v_mfma_f32_16x16x32_bf16 v[52:55], v[148:151], v[164:167], v[52:55]
	v_mfma_f32_16x16x32_bf16 v[44:47], v[156:159], v[164:167], v[44:47]
	v_mfma_f32_16x16x32_bf16 v[36:39], v[148:151], v[172:175], v[36:39]
	v_mfma_f32_16x16x32_bf16 v[28:31], v[156:159], v[172:175], v[28:31]
	v_mfma_f32_16x16x32_bf16 v[16:19], v[148:151], v[194:197], v[16:19]
	v_mfma_f32_16x16x32_bf16 v[8:11], v[156:159], v[194:197], v[8:11]
	v_mfma_f32_16x16x32_bf16 v[4:7], v[148:151], v[216:219], v[4:7]
	v_mfma_f32_16x16x32_bf16 v[0:3], v[156:159], v[216:219], v[0:3]
	s_setprio 0
	s_barrier
	s_add_i32 s53, 0, 0x18000
	s_add_i32 s54, 0, 0x1c000
	v_add_u32_e32 v140, s53, v210
	v_add_u32_e32 v156, s54, v210
	ds_read_b128 v[128:131], v140
	ds_read_b128 v[132:135], v140 offset:1024
	ds_read_b128 v[136:139], v140 offset:2048
	ds_read_b128 v[140:143], v140 offset:3072
	ds_read_b128 v[144:147], v156
	ds_read_b128 v[148:151], v156 offset:1024
	ds_read_b128 v[152:155], v156 offset:2048
	ds_read_b128 v[156:159], v156 offset:3072
	s_add_u32 s20, s20, 0xb0000
	s_addc_u32 s21, s21, 0
	s_mov_b32 m0, s25
	v_lshl_add_u64 v[226:227], s[20:21], 0, v[176:177]
	ds_read_b128 v[160:163], v214 offset:32768
	ds_read_b128 v[164:167], v214 offset:33792
	ds_read_b128 v[168:171], v214 offset:34816
	ds_read_b128 v[172:175], v214 offset:35840
	ds_read_b128 v[190:193], v214 offset:36864
	ds_read_b128 v[194:197], v214 offset:37888
	ds_read_b128 v[198:201], v214 offset:38912
	ds_read_b128 v[216:219], v214 offset:39936
	global_load_lds_dwordx4 v[226:227], off
	v_lshl_add_u64 v[226:227], s[20:21], 0, v[178:179]
	s_mov_b32 m0, s26
	s_nop 0
	global_load_lds_dwordx4 v[226:227], off
	s_waitcnt vmcnt(8)
	s_waitcnt lgkmcnt(0)
	s_barrier
	s_setprio 1
	s_waitcnt lgkmcnt(0)
	v_mfma_f32_16x16x32_bf16 v[124:127], v[128:131], v[160:163], v[124:127]
	v_mfma_f32_16x16x32_bf16 v[120:123], v[136:139], v[160:163], v[120:123]
	v_mfma_f32_16x16x32_bf16 v[112:115], v[128:131], v[168:171], v[112:115]
	v_mfma_f32_16x16x32_bf16 v[104:107], v[136:139], v[168:171], v[104:107]
	v_mfma_f32_16x16x32_bf16 v[96:99], v[128:131], v[190:193], v[96:99]
	v_mfma_f32_16x16x32_bf16 v[88:91], v[136:139], v[190:193], v[88:91]
	v_mfma_f32_16x16x32_bf16 v[84:87], v[128:131], v[198:201], v[84:87]
	v_mfma_f32_16x16x32_bf16 v[76:79], v[136:139], v[198:201], v[76:79]
	v_mfma_f32_16x16x32_bf16 v[124:127], v[132:135], v[164:167], v[124:127]
	v_mfma_f32_16x16x32_bf16 v[120:123], v[140:143], v[164:167], v[120:123]
	v_mfma_f32_16x16x32_bf16 v[112:115], v[132:135], v[172:175], v[112:115]
	v_mfma_f32_16x16x32_bf16 v[104:107], v[140:143], v[172:175], v[104:107]
	v_mfma_f32_16x16x32_bf16 v[96:99], v[132:135], v[194:197], v[96:99]
	v_mfma_f32_16x16x32_bf16 v[88:91], v[140:143], v[194:197], v[88:91]
	v_mfma_f32_16x16x32_bf16 v[84:87], v[132:135], v[216:219], v[84:87]
	v_mfma_f32_16x16x32_bf16 v[76:79], v[140:143], v[216:219], v[76:79]
	s_setprio 0
	s_setprio 1
	v_mfma_f32_16x16x32_bf16 v[116:119], v[144:147], v[160:163], v[116:119]
	v_mfma_f32_16x16x32_bf16 v[108:111], v[152:155], v[160:163], v[108:111]
	v_mfma_f32_16x16x32_bf16 v[100:103], v[144:147], v[168:171], v[100:103]
	v_mfma_f32_16x16x32_bf16 v[92:95], v[152:155], v[168:171], v[92:95]
	v_mfma_f32_16x16x32_bf16 v[80:83], v[144:147], v[190:193], v[80:83]
	v_mfma_f32_16x16x32_bf16 v[72:75], v[152:155], v[190:193], v[72:75]
	v_mfma_f32_16x16x32_bf16 v[68:71], v[144:147], v[198:201], v[68:71]
	v_mfma_f32_16x16x32_bf16 v[64:67], v[152:155], v[198:201], v[64:67]
	v_mfma_f32_16x16x32_bf16 v[116:119], v[148:151], v[164:167], v[116:119]
	v_mfma_f32_16x16x32_bf16 v[108:111], v[156:159], v[164:167], v[108:111]
	v_mfma_f32_16x16x32_bf16 v[100:103], v[148:151], v[172:175], v[100:103]
	v_mfma_f32_16x16x32_bf16 v[92:95], v[156:159], v[172:175], v[92:95]
	v_mfma_f32_16x16x32_bf16 v[80:83], v[148:151], v[194:197], v[80:83]
	v_mfma_f32_16x16x32_bf16 v[72:75], v[156:159], v[194:197], v[72:75]
	v_mfma_f32_16x16x32_bf16 v[68:71], v[148:151], v[216:219], v[68:71]
	v_mfma_f32_16x16x32_bf16 v[64:67], v[156:159], v[216:219], v[64:67]
	s_setprio 0
	s_barrier
	s_add_i32 s20, s53, s22
	v_lshl_add_u64 v[202:203], v[202:203], 0, s[10:11]
	s_mov_b32 m0, s20
	ds_read_b128 v[160:163], v214 offset:49152
	ds_read_b128 v[164:167], v214 offset:50176
	ds_read_b128 v[168:171], v214 offset:51200
	ds_read_b128 v[172:175], v214 offset:52224
	ds_read_b128 v[190:193], v214 offset:53248
	ds_read_b128 v[194:197], v214 offset:54272
	ds_read_b128 v[198:201], v214 offset:55296
	ds_read_b128 v[216:219], v214 offset:56320
	global_load_lds_dwordx4 v[202:203], off
	s_add_i32 m0, s20, 0x2000
	s_add_u32 s18, s18, 0xb0080
	v_lshl_add_u64 v[202:203], v[220:221], 0, s[10:11]
	s_addc_u32 s19, s19, 0
	s_add_i32 s20, s54, s22
	global_load_lds_dwordx4 v[202:203], off
	v_lshl_add_u64 v[202:203], s[18:19], 0, v[176:177]
	s_mov_b32 m0, s20
	s_nop 0
	global_load_lds_dwordx4 v[202:203], off
	v_lshl_add_u64 v[202:203], s[18:19], 0, v[178:179]
	s_add_i32 m0, s20, 0x2000
	s_nop 0
	global_load_lds_dwordx4 v[202:203], off
	v_lshl_add_u64 v[202:203], v[222:223], 0, s[10:11]
	s_mov_b32 m0, s29
	s_nop 0
	global_load_lds_dwordx4 v[202:203], off
	v_lshl_add_u64 v[202:203], v[224:225], 0, s[10:11]
	s_mov_b32 m0, s30
	s_nop 0
	global_load_lds_dwordx4 v[202:203], off
	s_waitcnt vmcnt(8)
	s_waitcnt lgkmcnt(0)
	s_barrier
	s_setprio 1
	s_waitcnt lgkmcnt(0)
	v_mfma_f32_16x16x32_bf16 v[60:63], v[128:131], v[160:163], v[60:63]
	v_mfma_f32_16x16x32_bf16 v[56:59], v[136:139], v[160:163], v[56:59]
	v_mfma_f32_16x16x32_bf16 v[48:51], v[128:131], v[168:171], v[48:51]
	v_mfma_f32_16x16x32_bf16 v[40:43], v[136:139], v[168:171], v[40:43]
	v_mfma_f32_16x16x32_bf16 v[32:35], v[128:131], v[190:193], v[32:35]
	v_mfma_f32_16x16x32_bf16 v[24:27], v[136:139], v[190:193], v[24:27]
	v_mfma_f32_16x16x32_bf16 v[20:23], v[128:131], v[198:201], v[20:23]
	v_mfma_f32_16x16x32_bf16 v[12:15], v[136:139], v[198:201], v[12:15]
	v_mfma_f32_16x16x32_bf16 v[60:63], v[132:135], v[164:167], v[60:63]
	v_mfma_f32_16x16x32_bf16 v[56:59], v[140:143], v[164:167], v[56:59]
	v_mfma_f32_16x16x32_bf16 v[48:51], v[132:135], v[172:175], v[48:51]
	v_mfma_f32_16x16x32_bf16 v[40:43], v[140:143], v[172:175], v[40:43]
	v_mfma_f32_16x16x32_bf16 v[32:35], v[132:135], v[194:197], v[32:35]
	v_mfma_f32_16x16x32_bf16 v[24:27], v[140:143], v[194:197], v[24:27]
	v_mfma_f32_16x16x32_bf16 v[20:23], v[132:135], v[216:219], v[20:23]
	v_mfma_f32_16x16x32_bf16 v[12:15], v[140:143], v[216:219], v[12:15]
	s_setprio 0
	s_setprio 1
	v_mfma_f32_16x16x32_bf16 v[52:55], v[144:147], v[160:163], v[52:55]
	v_mfma_f32_16x16x32_bf16 v[44:47], v[152:155], v[160:163], v[44:47]
	v_mfma_f32_16x16x32_bf16 v[36:39], v[144:147], v[168:171], v[36:39]
	v_mfma_f32_16x16x32_bf16 v[28:31], v[152:155], v[168:171], v[28:31]
	v_mfma_f32_16x16x32_bf16 v[16:19], v[144:147], v[190:193], v[16:19]
	v_mfma_f32_16x16x32_bf16 v[8:11], v[152:155], v[190:193], v[8:11]
	v_mfma_f32_16x16x32_bf16 v[4:7], v[144:147], v[198:201], v[4:7]
	v_mfma_f32_16x16x32_bf16 v[0:3], v[152:155], v[198:201], v[0:3]
	v_mfma_f32_16x16x32_bf16 v[52:55], v[148:151], v[164:167], v[52:55]
	v_mfma_f32_16x16x32_bf16 v[44:47], v[156:159], v[164:167], v[44:47]
	v_mfma_f32_16x16x32_bf16 v[36:39], v[148:151], v[172:175], v[36:39]
	v_mfma_f32_16x16x32_bf16 v[28:31], v[156:159], v[172:175], v[28:31]
	v_mfma_f32_16x16x32_bf16 v[16:19], v[148:151], v[194:197], v[16:19]
	v_mfma_f32_16x16x32_bf16 v[8:11], v[156:159], v[194:197], v[8:11]
	v_mfma_f32_16x16x32_bf16 v[4:7], v[148:151], v[216:219], v[4:7]
	v_mfma_f32_16x16x32_bf16 v[0:3], v[156:159], v[216:219], v[0:3]
	s_setprio 0
	s_barrier
	s_add_i32 s52, s52, 2
	s_add_u32 s16, s16, 0x100
	s_addc_u32 s17, s17, 0
	s_add_u32 s50, s50, 0x100
	s_addc_u32 s51, s51, 0
	s_cmp_gt_u32 s52, 41
	s_cbranch_scc0 .LBB0_1324
	s_and_b64 vcc, exec, s[12:13]
	s_cbranch_vccz .LBB0_1327
	s_barrier
.LBB0_1327:
	v_lshl_add_u32 v192, s48, 8, v209
	v_add_u32_e32 v130, 0xffffc000, v192
	v_ashrrev_i32_e32 v193, 31, v192
	v_cmp_gt_i32_e32 vcc, s28, v192
	v_lshl_or_b32 v128, s49, 8, v211
	v_mov_b32_e32 v134, s9
	v_cndmask_b32_e32 v131, 0, v193, vcc
	v_cndmask_b32_e32 v130, v130, v192, vcc
	v_mov_b32_e32 v135, s89
	v_mov_b32_e32 v136, s8
	v_mov_b32_e32 v137, s88
	v_ashrrev_i32_e32 v129, 31, v128
	v_cndmask_b32_e32 v133, v134, v135, vcc
	v_cndmask_b32_e32 v132, v136, v137, vcc
	v_lshlrev_b64 v[130:131], 12, v[130:131]
	v_lshl_add_u64 v[130:131], v[132:133], 0, v[130:131]
	v_lshlrev_b64 v[190:191], 2, v[128:129]
	v_lshl_add_u64 v[128:129], v[130:131], 0, v[190:191]
	v_or_b32_e32 v198, 16, v192
	global_load_dwordx4 v[172:175], v[128:129], off
	global_load_dwordx4 v[168:171], v[128:129], off offset:64
	global_load_dwordx4 v[164:167], v[128:129], off offset:512
	global_load_dwordx4 v[156:159], v[128:129], off offset:576
	v_ashrrev_i32_e32 v199, 31, v198
	v_add_u32_e32 v128, 0xffffc010, v192
	v_cmp_gt_i32_e32 vcc, s28, v198
	v_or_b32_e32 v196, 32, v192
	v_ashrrev_i32_e32 v197, 31, v196
	v_cndmask_b32_e32 v129, 0, v199, vcc
	v_cndmask_b32_e32 v128, v128, v198, vcc
	v_cndmask_b32_e32 v131, v134, v135, vcc
	v_cndmask_b32_e32 v130, v136, v137, vcc
	v_lshlrev_b64 v[128:129], 12, v[128:129]
	v_lshl_add_u64 v[128:129], v[130:131], 0, v[128:129]
	v_lshl_add_u64 v[128:129], v[128:129], 0, v[190:191]
	global_load_dwordx4 v[160:163], v[128:129], off
	global_load_dwordx4 v[152:155], v[128:129], off offset:64
	global_load_dwordx4 v[148:151], v[128:129], off offset:512
	global_load_dwordx4 v[140:143], v[128:129], off offset:576
	v_add_u32_e32 v128, 0xffffc020, v192
	v_cmp_gt_i32_e32 vcc, s28, v196
	v_or_b32_e32 v200, 48, v192
	s_nop 0
	v_cndmask_b32_e32 v129, 0, v197, vcc
	v_cndmask_b32_e32 v128, v128, v196, vcc
	v_cndmask_b32_e32 v131, v134, v135, vcc
	v_cndmask_b32_e32 v130, v136, v137, vcc
	v_lshlrev_b64 v[128:129], 12, v[128:129]
	v_lshl_add_u64 v[128:129], v[130:131], 0, v[128:129]
	v_lshl_add_u64 v[128:129], v[128:129], 0, v[190:191]
	global_load_dwordx4 v[144:147], v[128:129], off
	global_load_dwordx4 v[136:139], v[128:129], off offset:64
	global_load_dwordx4 v[132:135], v[128:129], off offset:512
	s_nop 0
	global_load_dwordx4 v[128:131], v[128:129], off offset:576
	v_cmp_lt_i32_e32 vcc, s41, v200
	s_and_saveexec_b64 s[16:17], vcc
	s_xor_b64 s[16:17], exec, s[16:17]
	v_add_u32_e32 v180, 0xffffc030, v192
	v_lshlrev_b64 v[194:195], 12, v[180:181]
	v_mov_b32_e32 v201, v181
	v_lshl_add_u64 v[202:203], s[8:9], 0, v[194:195]
	v_lshlrev_b64 v[194:195], 12, v[200:201]
	s_andn2_saveexec_b64 s[16:17], s[16:17]
	v_ashrrev_i32_e32 v201, 31, v200
	v_lshlrev_b64 v[194:195], 12, v[200:201]
	v_lshl_add_u64 v[202:203], s[88:89], 0, v[194:195]
	s_or_b64 exec, exec, s[16:17]
	v_lshl_add_u64 v[224:225], v[202:203], 0, v[190:191]
	global_load_dwordx4 v[200:203], v[224:225], off
	global_load_dwordx4 v[216:219], v[224:225], off offset:64
	global_load_dwordx4 v[220:223], v[224:225], off offset:512
	s_nop 0
	global_load_dwordx4 v[224:227], v[224:225], off offset:576
	v_lshlrev_b64 v[228:229], 12, v[192:193]
	v_lshl_add_u64 v[228:229], s[88:89], 0, v[228:229]
	v_lshl_add_u64 v[228:229], v[228:229], 0, v[190:191]
	s_waitcnt vmcnt(0)
	v_pk_add_f32 v[110:111], v[110:111], v[158:159]
	v_pk_add_f32 v[108:109], v[108:109], v[156:157]
	global_store_dwordx4 v[228:229], v[108:111], off offset:576
	v_pk_add_f32 v[118:119], v[118:119], v[166:167]
	v_pk_add_f32 v[116:117], v[116:117], v[164:165]
	v_lshlrev_b64 v[108:109], 12, v[198:199]
	v_lshl_add_u64 v[108:109], s[88:89], 0, v[108:109]
	global_store_dwordx4 v[228:229], v[116:119], off offset:512
	v_pk_add_f32 v[94:95], v[94:95], v[142:143]
	v_pk_add_f32 v[92:93], v[92:93], v[140:141]
	v_lshl_add_u64 v[116:117], v[108:109], 0, v[190:191]
	global_store_dwordx4 v[116:117], v[92:95], off offset:576
	v_pk_add_f32 v[102:103], v[102:103], v[150:151]
	v_pk_add_f32 v[100:101], v[100:101], v[148:149]
	v_lshlrev_b64 v[92:93], 12, v[196:197]
	v_lshl_add_u64 v[92:93], s[88:89], 0, v[92:93]
	global_store_dwordx4 v[116:117], v[100:103], off offset:512
	v_pk_add_f32 v[74:75], v[74:75], v[130:131]
	v_pk_add_f32 v[72:73], v[72:73], v[128:129]
	v_lshl_add_u64 v[100:101], v[92:93], 0, v[190:191]
	v_pk_add_f32 v[82:83], v[82:83], v[134:135]
	v_pk_add_f32 v[80:81], v[80:81], v[132:133]
	global_store_dwordx4 v[100:101], v[72:75], off offset:576
	v_pk_add_f32 v[126:127], v[126:127], v[174:175]
	v_pk_add_f32 v[124:125], v[124:125], v[172:173]
	v_lshl_add_u64 v[72:73], s[88:89], 0, v[194:195]
	v_pk_add_f32 v[122:123], v[122:123], v[170:171]
	v_pk_add_f32 v[120:121], v[120:121], v[168:169]
	v_pk_add_f32 v[110:111], v[114:115], v[162:163]
	v_pk_add_f32 v[108:109], v[112:113], v[160:161]
	v_pk_add_f32 v[106:107], v[106:107], v[154:155]
	v_pk_add_f32 v[104:105], v[104:105], v[152:153]
	v_pk_add_f32 v[94:95], v[98:99], v[146:147]
	v_pk_add_f32 v[92:93], v[96:97], v[144:145]
	v_pk_add_f32 v[90:91], v[90:91], v[138:139]
	v_pk_add_f32 v[88:89], v[88:89], v[136:137]
	global_store_dwordx4 v[100:101], v[80:83], off offset:512
	v_pk_add_f32 v[74:75], v[86:87], v[202:203]
	global_store_dwordx4 v[228:229], v[124:127], off
	v_lshl_add_u64 v[80:81], v[72:73], 0, v[190:191]
	v_pk_add_f32 v[72:73], v[84:85], v[200:201]
	global_store_dwordx4 v[228:229], v[120:123], off offset:64
	global_store_dwordx4 v[116:117], v[108:111], off
	global_store_dwordx4 v[116:117], v[104:107], off offset:64
	global_store_dwordx4 v[100:101], v[92:95], off
	global_store_dwordx4 v[100:101], v[88:91], off offset:64
	global_store_dwordx4 v[80:81], v[72:75], off
	v_pk_add_f32 v[70:71], v[70:71], v[222:223]
	v_pk_add_f32 v[68:69], v[68:69], v[220:221]
	v_pk_add_f32 v[74:75], v[78:79], v[218:219]
	v_pk_add_f32 v[72:73], v[76:77], v[216:217]
	v_pk_add_f32 v[66:67], v[66:67], v[226:227]
	v_pk_add_f32 v[64:65], v[64:65], v[224:225]
	global_store_dwordx4 v[80:81], v[72:75], off offset:64
	global_store_dwordx4 v[80:81], v[68:71], off offset:512
	global_store_dwordx4 v[80:81], v[64:67], off offset:576
	v_add_u32_e32 v118, 0x80, v192
	v_ashrrev_i32_e32 v119, 31, v118
	v_add_u32_e32 v64, 0xffffc080, v192
	v_cmp_gt_i32_e32 vcc, s42, v192
	v_mov_b32_e32 v68, s9
	v_mov_b32_e32 v69, s89
	v_cndmask_b32_e32 v65, 0, v119, vcc
	v_cndmask_b32_e32 v64, v64, v118, vcc
	v_mov_b32_e32 v70, s8
	v_mov_b32_e32 v71, s88
	v_cndmask_b32_e32 v67, v68, v69, vcc
	v_cndmask_b32_e32 v66, v70, v71, vcc
	v_lshlrev_b64 v[64:65], 12, v[64:65]
	v_lshl_add_u64 v[64:65], v[66:67], 0, v[64:65]
	v_lshl_add_u64 v[64:65], v[64:65], 0, v[190:191]
	v_add_u32_e32 v116, 0x90, v192
	global_load_dwordx4 v[108:111], v[64:65], off
	global_load_dwordx4 v[104:107], v[64:65], off offset:64
	global_load_dwordx4 v[100:103], v[64:65], off offset:512
	global_load_dwordx4 v[92:95], v[64:65], off offset:576
	v_ashrrev_i32_e32 v117, 31, v116
	v_add_u32_e32 v64, 0xffffc090, v192
	v_cmp_gt_i32_e32 vcc, s43, v192
	v_add_u32_e32 v114, 0xa0, v192
	v_ashrrev_i32_e32 v115, 31, v114
	v_cndmask_b32_e32 v65, 0, v117, vcc
	v_cndmask_b32_e32 v64, v64, v116, vcc
	v_cndmask_b32_e32 v67, v68, v69, vcc
	v_cndmask_b32_e32 v66, v70, v71, vcc
	v_lshlrev_b64 v[64:65], 12, v[64:65]
	v_lshl_add_u64 v[64:65], v[66:67], 0, v[64:65]
	v_lshl_add_u64 v[64:65], v[64:65], 0, v[190:191]
	global_load_dwordx4 v[96:99], v[64:65], off
	global_load_dwordx4 v[88:91], v[64:65], off offset:64
	global_load_dwordx4 v[84:87], v[64:65], off offset:512
	global_load_dwordx4 v[76:79], v[64:65], off offset:576
	v_add_u32_e32 v64, 0xffffc0a0, v192
	v_cmp_gt_i32_e32 vcc, s44, v192
	v_add_u32_e32 v120, 0xb0, v192
	s_nop 0
	v_cndmask_b32_e32 v65, 0, v115, vcc
	v_cndmask_b32_e32 v64, v64, v114, vcc
	v_cndmask_b32_e32 v67, v68, v69, vcc
	v_cndmask_b32_e32 v66, v70, v71, vcc
	v_lshlrev_b64 v[64:65], 12, v[64:65]
	v_lshl_add_u64 v[64:65], v[66:67], 0, v[64:65]
	v_lshl_add_u64 v[64:65], v[64:65], 0, v[190:191]
	global_load_dwordx4 v[80:83], v[64:65], off
	global_load_dwordx4 v[72:75], v[64:65], off offset:64
	global_load_dwordx4 v[68:71], v[64:65], off offset:512
	s_nop 0
	global_load_dwordx4 v[64:67], v[64:65], off offset:576
	v_cmp_lt_i32_e32 vcc, s45, v192
	s_and_saveexec_b64 s[16:17], vcc
	s_xor_b64 s[16:17], exec, s[16:17]
	v_add_u32_e32 v180, 0xffffc0b0, v192
	v_lshlrev_b64 v[112:113], 12, v[180:181]
	v_mov_b32_e32 v121, v181
	v_lshl_add_u64 v[122:123], s[8:9], 0, v[112:113]
	v_lshlrev_b64 v[112:113], 12, v[120:121]
	s_andn2_saveexec_b64 s[16:17], s[16:17]
	v_ashrrev_i32_e32 v121, 31, v120
	v_lshlrev_b64 v[112:113], 12, v[120:121]
	v_lshl_add_u64 v[122:123], s[88:89], 0, v[112:113]
	s_or_b64 exec, exec, s[16:17]
	v_lshl_add_u64 v[132:133], v[122:123], 0, v[190:191]
	global_load_dwordx4 v[120:123], v[132:133], off
	global_load_dwordx4 v[124:127], v[132:133], off offset:64
	global_load_dwordx4 v[128:131], v[132:133], off offset:512
	s_nop 0
	global_load_dwordx4 v[132:135], v[132:133], off offset:576
	v_lshlrev_b64 v[118:119], 12, v[118:119]
	v_lshl_add_u64 v[118:119], s[88:89], 0, v[118:119]
	v_lshl_add_u64 v[118:119], v[118:119], 0, v[190:191]
	s_waitcnt vmcnt(12)
	v_pk_add_f32 v[46:47], v[46:47], v[94:95]
	v_pk_add_f32 v[44:45], v[44:45], v[92:93]
	global_store_dwordx4 v[118:119], v[44:47], off offset:576
	v_pk_add_f32 v[54:55], v[54:55], v[102:103]
	v_pk_add_f32 v[52:53], v[52:53], v[100:101]
	v_lshlrev_b64 v[44:45], 12, v[116:117]
	v_lshl_add_u64 v[44:45], s[88:89], 0, v[44:45]
	global_store_dwordx4 v[118:119], v[52:55], off offset:512
	s_waitcnt vmcnt(10)
	v_pk_add_f32 v[30:31], v[30:31], v[78:79]
	v_pk_add_f32 v[28:29], v[28:29], v[76:77]
	v_lshl_add_u64 v[52:53], v[44:45], 0, v[190:191]
	global_store_dwordx4 v[52:53], v[28:31], off offset:576
	v_pk_add_f32 v[38:39], v[38:39], v[86:87]
	v_pk_add_f32 v[36:37], v[36:37], v[84:85]
	v_lshlrev_b64 v[28:29], 12, v[114:115]
	v_lshl_add_u64 v[28:29], s[88:89], 0, v[28:29]
	global_store_dwordx4 v[52:53], v[36:39], off offset:512
	s_waitcnt vmcnt(8)
	v_pk_add_f32 v[10:11], v[10:11], v[66:67]
	v_pk_add_f32 v[8:9], v[8:9], v[64:65]
	v_lshl_add_u64 v[36:37], v[28:29], 0, v[190:191]
	v_pk_add_f32 v[18:19], v[18:19], v[70:71]
	v_pk_add_f32 v[16:17], v[16:17], v[68:69]
	global_store_dwordx4 v[36:37], v[8:11], off offset:576
	v_pk_add_f32 v[62:63], v[62:63], v[110:111]
	v_pk_add_f32 v[60:61], v[60:61], v[108:109]
	v_lshl_add_u64 v[8:9], s[88:89], 0, v[112:113]
	v_pk_add_f32 v[58:59], v[58:59], v[106:107]
	v_pk_add_f32 v[56:57], v[56:57], v[104:105]
	v_pk_add_f32 v[46:47], v[50:51], v[98:99]
	v_pk_add_f32 v[44:45], v[48:49], v[96:97]
	v_pk_add_f32 v[42:43], v[42:43], v[90:91]
	v_pk_add_f32 v[40:41], v[40:41], v[88:89]
	v_pk_add_f32 v[30:31], v[34:35], v[82:83]
	v_pk_add_f32 v[28:29], v[32:33], v[80:81]
	v_pk_add_f32 v[26:27], v[26:27], v[74:75]
	v_pk_add_f32 v[24:25], v[24:25], v[72:73]
	global_store_dwordx4 v[36:37], v[16:19], off offset:512
	s_waitcnt vmcnt(9)
	v_pk_add_f32 v[10:11], v[22:23], v[122:123]
	global_store_dwordx4 v[118:119], v[60:63], off
	v_lshl_add_u64 v[16:17], v[8:9], 0, v[190:191]
	v_pk_add_f32 v[8:9], v[20:21], v[120:121]
	global_store_dwordx4 v[118:119], v[56:59], off offset:64
	global_store_dwordx4 v[52:53], v[44:47], off
	global_store_dwordx4 v[52:53], v[40:43], off offset:64
	global_store_dwordx4 v[36:37], v[28:31], off
	global_store_dwordx4 v[36:37], v[24:27], off offset:64
	global_store_dwordx4 v[16:17], v[8:11], off
	s_waitcnt vmcnt(14)
	v_pk_add_f32 v[6:7], v[6:7], v[130:131]
	v_pk_add_f32 v[4:5], v[4:5], v[128:129]
	v_pk_add_f32 v[10:11], v[14:15], v[126:127]
	v_pk_add_f32 v[8:9], v[12:13], v[124:125]
	s_waitcnt vmcnt(13)
	v_pk_add_f32 v[2:3], v[2:3], v[134:135]
	v_pk_add_f32 v[0:1], v[0:1], v[132:133]
	global_store_dwordx4 v[16:17], v[8:11], off offset:64
	global_store_dwordx4 v[16:17], v[4:7], off offset:512
	global_store_dwordx4 v[16:17], v[0:3], off offset:576
	s_and_b64 vcc, exec, s[2:3]
	s_mov_b64 s[2:3], -1
	s_cbranch_vccnz .LBB0_1312
	s_andn2_b64 vcc, exec, s[6:7]
	s_cbranch_vccnz .LBB0_1311
	v_writelane_b32 v255, 1, 53
	s_branch .LBB0_1311

.LBB0_1351:
	v_mov_b32_e32 v0, 0
	s_mov_b32 s24, 0
	s_mov_b64 s[20:21], -1
	s_mov_b64 s[22:23], 0
	v_mov_b32_e32 v1, v0
	v_mov_b32_e32 v2, v0
	v_mov_b32_e32 v3, v0
	v_mov_b32_e32 v4, v0
	v_mov_b32_e32 v5, v0
	v_mov_b32_e32 v6, v0
	v_mov_b32_e32 v7, v0
	v_mov_b32_e32 v8, v0
	v_mov_b32_e32 v9, v0
	v_mov_b32_e32 v10, v0
	v_mov_b32_e32 v11, v0
	v_mov_b32_e32 v12, v0
	v_mov_b32_e32 v13, v0
	v_mov_b32_e32 v14, v0
	v_mov_b32_e32 v15, v0
	v_mov_b32_e32 v20, v0
	v_mov_b32_e32 v21, v0
	v_mov_b32_e32 v22, v0
	v_mov_b32_e32 v23, v0
	v_mov_b32_e32 v28, v0
	v_mov_b32_e32 v29, v0
	v_mov_b32_e32 v30, v0
	v_mov_b32_e32 v31, v0
	v_mov_b32_e32 v36, v0
	v_mov_b32_e32 v37, v0
	v_mov_b32_e32 v38, v0
	v_mov_b32_e32 v39, v0
	v_mov_b32_e32 v44, v0
	v_mov_b32_e32 v45, v0
	v_mov_b32_e32 v46, v0
	v_mov_b32_e32 v47, v0
	v_mov_b32_e32 v16, v0
	v_mov_b32_e32 v17, v0
	v_mov_b32_e32 v18, v0
	v_mov_b32_e32 v19, v0
	v_mov_b32_e32 v24, v0
	v_mov_b32_e32 v25, v0
	v_mov_b32_e32 v26, v0
	v_mov_b32_e32 v27, v0
	v_mov_b32_e32 v32, v0
	v_mov_b32_e32 v33, v0
	v_mov_b32_e32 v34, v0
	v_mov_b32_e32 v35, v0
	v_mov_b32_e32 v40, v0
	v_mov_b32_e32 v41, v0
	v_mov_b32_e32 v42, v0
	v_mov_b32_e32 v43, v0
	v_mov_b32_e32 v48, v0
	v_mov_b32_e32 v49, v0
	v_mov_b32_e32 v50, v0
	v_mov_b32_e32 v51, v0
	v_mov_b32_e32 v52, v0
	v_mov_b32_e32 v53, v0
	v_mov_b32_e32 v54, v0
	v_mov_b32_e32 v55, v0
	v_mov_b32_e32 v56, v0
	v_mov_b32_e32 v57, v0
	v_mov_b32_e32 v58, v0
	v_mov_b32_e32 v59, v0
	v_mov_b32_e32 v60, v0
	v_mov_b32_e32 v61, v0
	v_mov_b32_e32 v62, v0
	v_mov_b32_e32 v63, v0
	v_mov_b32_e32 v64, v0
	v_mov_b32_e32 v65, v0
	v_mov_b32_e32 v66, v0
	v_mov_b32_e32 v67, v0
	v_mov_b32_e32 v68, v0
	v_mov_b32_e32 v69, v0
	v_mov_b32_e32 v70, v0
	v_mov_b32_e32 v71, v0
	v_mov_b32_e32 v72, v0
	v_mov_b32_e32 v73, v0
	v_mov_b32_e32 v74, v0
	v_mov_b32_e32 v75, v0
	v_mov_b32_e32 v76, v0
	v_mov_b32_e32 v77, v0
	v_mov_b32_e32 v78, v0
	v_mov_b32_e32 v79, v0
	v_mov_b32_e32 v80, v0
	v_mov_b32_e32 v81, v0
	v_mov_b32_e32 v82, v0
	v_mov_b32_e32 v83, v0
	v_mov_b32_e32 v88, v0
	v_mov_b32_e32 v89, v0
	v_mov_b32_e32 v90, v0
	v_mov_b32_e32 v91, v0
	v_mov_b32_e32 v96, v0
	v_mov_b32_e32 v97, v0
	v_mov_b32_e32 v98, v0
	v_mov_b32_e32 v99, v0
	v_mov_b32_e32 v104, v0
	v_mov_b32_e32 v105, v0
	v_mov_b32_e32 v106, v0
	v_mov_b32_e32 v107, v0
	v_mov_b32_e32 v84, v0
	v_mov_b32_e32 v85, v0
	v_mov_b32_e32 v86, v0
	v_mov_b32_e32 v87, v0
	v_mov_b32_e32 v92, v0
	v_mov_b32_e32 v93, v0
	v_mov_b32_e32 v94, v0
	v_mov_b32_e32 v95, v0
	v_mov_b32_e32 v100, v0
	v_mov_b32_e32 v101, v0
	v_mov_b32_e32 v102, v0
	v_mov_b32_e32 v103, v0
	v_mov_b32_e32 v108, v0
	v_mov_b32_e32 v109, v0
	v_mov_b32_e32 v110, v0
	v_mov_b32_e32 v111, v0
	v_mov_b32_e32 v112, v0
	v_mov_b32_e32 v113, v0
	v_mov_b32_e32 v114, v0
	v_mov_b32_e32 v115, v0
	v_mov_b32_e32 v116, v0
	v_mov_b32_e32 v117, v0
	v_mov_b32_e32 v118, v0
	v_mov_b32_e32 v119, v0
	v_mov_b32_e32 v120, v0
	v_mov_b32_e32 v121, v0
	v_mov_b32_e32 v122, v0
	v_mov_b32_e32 v123, v0
	v_mov_b32_e32 v124, v0
	v_mov_b32_e32 v125, v0
	v_mov_b32_e32 v126, v0
	v_mov_b32_e32 v127, v0
	v_readlane_b32 s97, v255, 53
	s_nop 3
	s_cmp_eq_u32 s97, 1
	s_cbranch_scc0 .Llsb_skip_11
	v_writelane_b32 v255, 0, 53
	s_barrier
.Llsb_skip_11:
.LBB0_1352:
	s_add_u32 s25, s14, s24
	s_addc_u32 s30, s15, 0
	s_add_u32 s28, s25, 0x100
	s_addc_u32 s29, s30, 0
	s_and_b64 s[26:27], s[22:23], exec
	s_cselect_b32 s27, s17, s29
	s_cselect_b32 s26, s16, s28
	s_add_u32 s24, s12, s24
	s_addc_u32 s28, s13, 0
	s_add_u32 s24, s24, 0x100
	s_addc_u32 s28, s28, 0
	ds_read_b128 v[136:139], v131
	ds_read_b128 v[140:143], v131 offset:1024
	ds_read_b128 v[144:147], v131 offset:2048
	ds_read_b128 v[148:151], v131 offset:3072
	ds_read_b128 v[152:155], v132
	ds_read_b128 v[156:159], v132 offset:1024
	ds_read_b128 v[160:163], v132 offset:2048
	ds_read_b128 v[164:167], v132 offset:3072
	s_and_b64 s[22:23], s[22:23], exec
	s_cselect_b32 s29, s19, s28
	s_cselect_b32 s28, s18, s24
	s_add_u32 s34, s25, 0xb0080
	s_addc_u32 s35, s30, 0
	s_add_u32 s30, s28, 0xb0000
	s_addc_u32 s31, s29, 0
	s_add_i32 s66, 0, 0x1c000
	s_add_u32 s24, s26, 0xb0000
	s_addc_u32 s25, s27, 0
	s_add_i32 s65, s58, s41
	s_add_i32 s63, s65, 0x2000
	s_add_u32 s22, s28, 0xb0080
	s_addc_u32 s23, s29, 0
	s_add_i32 s64, s66, s41
	s_add_i32 s62, s64, 0x2000
	s_mov_b32 m0, s52
	v_lshl_add_u64 v[206:207], s[34:35], 0, v[176:177]
	ds_read_b128 v[168:171], v133
	ds_read_b128 v[172:175], v133 offset:1024
	ds_read_b128 v[180:183], v133 offset:2048
	ds_read_b128 v[184:187], v133 offset:3072
	ds_read_b128 v[188:191], v133 offset:4096
	ds_read_b128 v[192:195], v133 offset:5120
	ds_read_b128 v[196:199], v133 offset:6144
	ds_read_b128 v[200:203], v133 offset:7168
	global_load_lds_dwordx4 v[206:207], off
	v_lshl_add_u64 v[206:207], s[34:35], 0, v[178:179]
	s_mov_b32 m0, s53
	s_nop 0
	global_load_lds_dwordx4 v[206:207], off
	s_waitcnt vmcnt(8)
	s_waitcnt lgkmcnt(0)
	s_barrier
	s_setprio 1
	s_waitcnt lgkmcnt(0)
	v_mfma_f32_16x16x32_bf16 v[124:127], v[136:139], v[168:171], v[124:127]
	v_mfma_f32_16x16x32_bf16 v[120:123], v[144:147], v[168:171], v[120:123]
	v_mfma_f32_16x16x32_bf16 v[116:119], v[136:139], v[180:183], v[116:119]
	v_mfma_f32_16x16x32_bf16 v[112:115], v[144:147], v[180:183], v[112:115]
	v_mfma_f32_16x16x32_bf16 v[108:111], v[136:139], v[188:191], v[108:111]
	v_mfma_f32_16x16x32_bf16 v[100:103], v[144:147], v[188:191], v[100:103]
	v_mfma_f32_16x16x32_bf16 v[92:95], v[136:139], v[196:199], v[92:95]
	v_mfma_f32_16x16x32_bf16 v[84:87], v[144:147], v[196:199], v[84:87]
	v_mfma_f32_16x16x32_bf16 v[124:127], v[140:143], v[172:175], v[124:127]
	v_mfma_f32_16x16x32_bf16 v[120:123], v[148:151], v[172:175], v[120:123]
	v_mfma_f32_16x16x32_bf16 v[116:119], v[140:143], v[184:187], v[116:119]
	v_mfma_f32_16x16x32_bf16 v[112:115], v[148:151], v[184:187], v[112:115]
	v_mfma_f32_16x16x32_bf16 v[108:111], v[140:143], v[192:195], v[108:111]
	v_mfma_f32_16x16x32_bf16 v[100:103], v[148:151], v[192:195], v[100:103]
	v_mfma_f32_16x16x32_bf16 v[92:95], v[140:143], v[200:203], v[92:95]
	v_mfma_f32_16x16x32_bf16 v[84:87], v[148:151], v[200:203], v[84:87]
	s_setprio 0
	s_setprio 1
	v_mfma_f32_16x16x32_bf16 v[104:107], v[152:155], v[168:171], v[104:107]
	v_mfma_f32_16x16x32_bf16 v[96:99], v[160:163], v[168:171], v[96:99]
	v_mfma_f32_16x16x32_bf16 v[88:91], v[152:155], v[180:183], v[88:91]
	v_mfma_f32_16x16x32_bf16 v[80:83], v[160:163], v[180:183], v[80:83]
	v_mfma_f32_16x16x32_bf16 v[76:79], v[152:155], v[188:191], v[76:79]
	v_mfma_f32_16x16x32_bf16 v[72:75], v[160:163], v[188:191], v[72:75]
	v_mfma_f32_16x16x32_bf16 v[68:71], v[152:155], v[196:199], v[68:71]
	v_mfma_f32_16x16x32_bf16 v[64:67], v[160:163], v[196:199], v[64:67]
	v_mfma_f32_16x16x32_bf16 v[104:107], v[156:159], v[172:175], v[104:107]
	v_mfma_f32_16x16x32_bf16 v[96:99], v[164:167], v[172:175], v[96:99]
	v_mfma_f32_16x16x32_bf16 v[88:91], v[156:159], v[184:187], v[88:91]
	v_mfma_f32_16x16x32_bf16 v[80:83], v[164:167], v[184:187], v[80:83]
	v_mfma_f32_16x16x32_bf16 v[76:79], v[156:159], v[192:195], v[76:79]
	v_mfma_f32_16x16x32_bf16 v[72:75], v[164:167], v[192:195], v[72:75]
	v_mfma_f32_16x16x32_bf16 v[68:71], v[156:159], v[200:203], v[68:71]
	v_mfma_f32_16x16x32_bf16 v[64:67], v[164:167], v[200:203], v[64:67]
	s_setprio 0
	s_barrier
	s_mov_b32 m0, s54
	v_lshl_add_u64 v[206:207], s[28:29], 0, v[176:177]
	ds_read_b128 v[168:171], v133 offset:16384
	ds_read_b128 v[172:175], v133 offset:17408
	ds_read_b128 v[180:183], v133 offset:18432
	ds_read_b128 v[184:187], v133 offset:19456
	ds_read_b128 v[188:191], v133 offset:20480
	ds_read_b128 v[192:195], v133 offset:21504
	ds_read_b128 v[196:199], v133 offset:22528
	ds_read_b128 v[200:203], v133 offset:23552
	global_load_lds_dwordx4 v[206:207], off
	v_lshl_add_u64 v[208:209], s[28:29], 0, v[178:179]
	s_mov_b32 m0, s55
	v_lshl_add_u64 v[210:211], s[30:31], 0, v[176:177]
	global_load_lds_dwordx4 v[208:209], off
	s_mov_b32 m0, s56
	v_lshl_add_u64 v[212:213], s[26:27], 0, v[178:179]
	global_load_lds_dwordx4 v[210:211], off
	v_lshl_add_u64 v[210:211], s[30:31], 0, v[178:179]
	s_mov_b32 m0, s57
	s_nop 0
	global_load_lds_dwordx4 v[210:211], off
	v_lshl_add_u64 v[210:211], s[26:27], 0, v[176:177]
	s_mov_b32 m0, s42
	s_nop 0
	global_load_lds_dwordx4 v[210:211], off
	s_mov_b32 m0, s43
	s_nop 0
	global_load_lds_dwordx4 v[212:213], off
	s_waitcnt vmcnt(8)
	s_waitcnt lgkmcnt(0)
	s_barrier
	s_setprio 1
	s_waitcnt lgkmcnt(0)
	v_mfma_f32_16x16x32_bf16 v[60:63], v[136:139], v[168:171], v[60:63]
	v_mfma_f32_16x16x32_bf16 v[56:59], v[144:147], v[168:171], v[56:59]
	v_mfma_f32_16x16x32_bf16 v[52:55], v[136:139], v[180:183], v[52:55]
	v_mfma_f32_16x16x32_bf16 v[48:51], v[144:147], v[180:183], v[48:51]
	v_mfma_f32_16x16x32_bf16 v[40:43], v[136:139], v[188:191], v[40:43]
	v_mfma_f32_16x16x32_bf16 v[32:35], v[144:147], v[188:191], v[32:35]
	v_mfma_f32_16x16x32_bf16 v[24:27], v[136:139], v[196:199], v[24:27]
	v_mfma_f32_16x16x32_bf16 v[16:19], v[144:147], v[196:199], v[16:19]
	v_mfma_f32_16x16x32_bf16 v[60:63], v[140:143], v[172:175], v[60:63]
	v_mfma_f32_16x16x32_bf16 v[56:59], v[148:151], v[172:175], v[56:59]
	v_mfma_f32_16x16x32_bf16 v[52:55], v[140:143], v[184:187], v[52:55]
	v_mfma_f32_16x16x32_bf16 v[48:51], v[148:151], v[184:187], v[48:51]
	v_mfma_f32_16x16x32_bf16 v[40:43], v[140:143], v[192:195], v[40:43]
	v_mfma_f32_16x16x32_bf16 v[32:35], v[148:151], v[192:195], v[32:35]
	v_mfma_f32_16x16x32_bf16 v[24:27], v[140:143], v[200:203], v[24:27]
	v_mfma_f32_16x16x32_bf16 v[16:19], v[148:151], v[200:203], v[16:19]
	s_setprio 0
	s_setprio 1
	v_mfma_f32_16x16x32_bf16 v[44:47], v[152:155], v[168:171], v[44:47]
	v_mfma_f32_16x16x32_bf16 v[36:39], v[160:163], v[168:171], v[36:39]
	v_mfma_f32_16x16x32_bf16 v[28:31], v[152:155], v[180:183], v[28:31]
	v_mfma_f32_16x16x32_bf16 v[20:23], v[160:163], v[180:183], v[20:23]
	v_mfma_f32_16x16x32_bf16 v[12:15], v[152:155], v[188:191], v[12:15]
	v_mfma_f32_16x16x32_bf16 v[8:11], v[160:163], v[188:191], v[8:11]
	v_mfma_f32_16x16x32_bf16 v[4:7], v[152:155], v[196:199], v[4:7]
	v_mfma_f32_16x16x32_bf16 v[0:3], v[160:163], v[196:199], v[0:3]
	v_mfma_f32_16x16x32_bf16 v[44:47], v[156:159], v[172:175], v[44:47]
	v_mfma_f32_16x16x32_bf16 v[36:39], v[164:167], v[172:175], v[36:39]
	v_mfma_f32_16x16x32_bf16 v[28:31], v[156:159], v[184:187], v[28:31]
	v_mfma_f32_16x16x32_bf16 v[20:23], v[164:167], v[184:187], v[20:23]
	v_mfma_f32_16x16x32_bf16 v[12:15], v[156:159], v[192:195], v[12:15]
	v_mfma_f32_16x16x32_bf16 v[8:11], v[164:167], v[192:195], v[8:11]
	v_mfma_f32_16x16x32_bf16 v[4:7], v[156:159], v[200:203], v[4:7]
	v_mfma_f32_16x16x32_bf16 v[0:3], v[164:167], v[200:203], v[0:3]
	s_setprio 0
	s_barrier
	v_add_u32_e32 v135, s66, v128
	ds_read_b128 v[136:139], v134
	ds_read_b128 v[140:143], v134 offset:1024
	ds_read_b128 v[144:147], v134 offset:2048
	ds_read_b128 v[148:151], v134 offset:3072
	ds_read_b128 v[152:155], v135
	ds_read_b128 v[156:159], v135 offset:1024
	ds_read_b128 v[160:163], v135 offset:2048
	ds_read_b128 v[164:167], v135 offset:3072
	s_mov_b32 m0, s44
	v_lshl_add_u64 v[214:215], s[24:25], 0, v[176:177]
	ds_read_b128 v[168:171], v133 offset:32768
	ds_read_b128 v[172:175], v133 offset:33792
	ds_read_b128 v[180:183], v133 offset:34816
	ds_read_b128 v[184:187], v133 offset:35840
	ds_read_b128 v[188:191], v133 offset:36864
	ds_read_b128 v[192:195], v133 offset:37888
	ds_read_b128 v[196:199], v133 offset:38912
	ds_read_b128 v[200:203], v133 offset:39936
	global_load_lds_dwordx4 v[214:215], off
	v_lshl_add_u64 v[214:215], s[24:25], 0, v[178:179]
	s_mov_b32 m0, s45
	s_nop 0
	global_load_lds_dwordx4 v[214:215], off
	s_waitcnt vmcnt(8)
	s_waitcnt lgkmcnt(0)
	s_barrier
	s_setprio 1
	s_waitcnt lgkmcnt(0)
	v_mfma_f32_16x16x32_bf16 v[124:127], v[136:139], v[168:171], v[124:127]
	v_mfma_f32_16x16x32_bf16 v[120:123], v[144:147], v[168:171], v[120:123]
	v_mfma_f32_16x16x32_bf16 v[116:119], v[136:139], v[180:183], v[116:119]
	v_mfma_f32_16x16x32_bf16 v[112:115], v[144:147], v[180:183], v[112:115]
	v_mfma_f32_16x16x32_bf16 v[108:111], v[136:139], v[188:191], v[108:111]
	v_mfma_f32_16x16x32_bf16 v[100:103], v[144:147], v[188:191], v[100:103]
	v_mfma_f32_16x16x32_bf16 v[92:95], v[136:139], v[196:199], v[92:95]
	v_mfma_f32_16x16x32_bf16 v[84:87], v[144:147], v[196:199], v[84:87]
	v_mfma_f32_16x16x32_bf16 v[124:127], v[140:143], v[172:175], v[124:127]
	v_mfma_f32_16x16x32_bf16 v[120:123], v[148:151], v[172:175], v[120:123]
	v_mfma_f32_16x16x32_bf16 v[116:119], v[140:143], v[184:187], v[116:119]
	v_mfma_f32_16x16x32_bf16 v[112:115], v[148:151], v[184:187], v[112:115]
	v_mfma_f32_16x16x32_bf16 v[108:111], v[140:143], v[192:195], v[108:111]
	v_mfma_f32_16x16x32_bf16 v[100:103], v[148:151], v[192:195], v[100:103]
	v_mfma_f32_16x16x32_bf16 v[92:95], v[140:143], v[200:203], v[92:95]
	v_mfma_f32_16x16x32_bf16 v[84:87], v[148:151], v[200:203], v[84:87]
	s_setprio 0
	s_setprio 1
	v_mfma_f32_16x16x32_bf16 v[104:107], v[152:155], v[168:171], v[104:107]
	v_mfma_f32_16x16x32_bf16 v[96:99], v[160:163], v[168:171], v[96:99]
	v_mfma_f32_16x16x32_bf16 v[88:91], v[152:155], v[180:183], v[88:91]
	v_mfma_f32_16x16x32_bf16 v[80:83], v[160:163], v[180:183], v[80:83]
	v_mfma_f32_16x16x32_bf16 v[76:79], v[152:155], v[188:191], v[76:79]
	v_mfma_f32_16x16x32_bf16 v[72:75], v[160:163], v[188:191], v[72:75]
	v_mfma_f32_16x16x32_bf16 v[68:71], v[152:155], v[196:199], v[68:71]
	v_mfma_f32_16x16x32_bf16 v[64:67], v[160:163], v[196:199], v[64:67]
	v_mfma_f32_16x16x32_bf16 v[104:107], v[156:159], v[172:175], v[104:107]
	v_mfma_f32_16x16x32_bf16 v[96:99], v[164:167], v[172:175], v[96:99]
	v_mfma_f32_16x16x32_bf16 v[88:91], v[156:159], v[184:187], v[88:91]
	v_mfma_f32_16x16x32_bf16 v[80:83], v[164:167], v[184:187], v[80:83]
	v_mfma_f32_16x16x32_bf16 v[76:79], v[156:159], v[192:195], v[76:79]
	v_mfma_f32_16x16x32_bf16 v[72:75], v[164:167], v[192:195], v[72:75]
	v_mfma_f32_16x16x32_bf16 v[68:71], v[156:159], v[200:203], v[68:71]
	v_mfma_f32_16x16x32_bf16 v[64:67], v[164:167], v[200:203], v[64:67]
	s_setprio 0
	s_barrier
	s_mov_b32 m0, s65
	v_lshl_add_u64 v[206:207], v[206:207], 0, s[8:9]
	ds_read_b128 v[168:171], v133 offset:49152
	ds_read_b128 v[172:175], v133 offset:50176
	ds_read_b128 v[180:183], v133 offset:51200
	ds_read_b128 v[184:187], v133 offset:52224
	ds_read_b128 v[188:191], v133 offset:53248
	ds_read_b128 v[192:195], v133 offset:54272
	ds_read_b128 v[196:199], v133 offset:55296
	ds_read_b128 v[200:203], v133 offset:56320
	global_load_lds_dwordx4 v[206:207], off
	v_lshl_add_u64 v[206:207], v[208:209], 0, s[8:9]
	s_mov_b32 m0, s63
	s_nop 0
	global_load_lds_dwordx4 v[206:207], off
	v_lshl_add_u64 v[206:207], s[22:23], 0, v[176:177]
	s_mov_b32 m0, s64
	s_nop 0
	global_load_lds_dwordx4 v[206:207], off
	v_lshl_add_u64 v[206:207], s[22:23], 0, v[178:179]
	s_mov_b32 m0, s62
	s_nop 0
	global_load_lds_dwordx4 v[206:207], off
	v_lshl_add_u64 v[206:207], v[210:211], 0, s[8:9]
	s_mov_b32 m0, s47
	s_nop 0
	global_load_lds_dwordx4 v[206:207], off
	v_lshl_add_u64 v[206:207], v[212:213], 0, s[8:9]
	s_mov_b32 m0, s48
	s_nop 0
	global_load_lds_dwordx4 v[206:207], off
	s_waitcnt vmcnt(8)
	s_waitcnt lgkmcnt(0)
	s_barrier
	s_setprio 1
	s_waitcnt lgkmcnt(0)
	v_mfma_f32_16x16x32_bf16 v[60:63], v[136:139], v[168:171], v[60:63]
	v_mfma_f32_16x16x32_bf16 v[56:59], v[144:147], v[168:171], v[56:59]
	v_mfma_f32_16x16x32_bf16 v[52:55], v[136:139], v[180:183], v[52:55]
	v_mfma_f32_16x16x32_bf16 v[48:51], v[144:147], v[180:183], v[48:51]
	v_mfma_f32_16x16x32_bf16 v[40:43], v[136:139], v[188:191], v[40:43]
	v_mfma_f32_16x16x32_bf16 v[32:35], v[144:147], v[188:191], v[32:35]
	v_mfma_f32_16x16x32_bf16 v[24:27], v[136:139], v[196:199], v[24:27]
	v_mfma_f32_16x16x32_bf16 v[16:19], v[144:147], v[196:199], v[16:19]
	v_mfma_f32_16x16x32_bf16 v[60:63], v[140:143], v[172:175], v[60:63]
	v_mfma_f32_16x16x32_bf16 v[56:59], v[148:151], v[172:175], v[56:59]
	v_mfma_f32_16x16x32_bf16 v[52:55], v[140:143], v[184:187], v[52:55]
	v_mfma_f32_16x16x32_bf16 v[48:51], v[148:151], v[184:187], v[48:51]
	v_mfma_f32_16x16x32_bf16 v[40:43], v[140:143], v[192:195], v[40:43]
	v_mfma_f32_16x16x32_bf16 v[32:35], v[148:151], v[192:195], v[32:35]
	v_mfma_f32_16x16x32_bf16 v[24:27], v[140:143], v[200:203], v[24:27]
	v_mfma_f32_16x16x32_bf16 v[16:19], v[148:151], v[200:203], v[16:19]
	s_setprio 0
	s_setprio 1
	v_mfma_f32_16x16x32_bf16 v[44:47], v[152:155], v[168:171], v[44:47]
	v_mfma_f32_16x16x32_bf16 v[36:39], v[160:163], v[168:171], v[36:39]
	v_mfma_f32_16x16x32_bf16 v[28:31], v[152:155], v[180:183], v[28:31]
	v_mfma_f32_16x16x32_bf16 v[20:23], v[160:163], v[180:183], v[20:23]
	v_mfma_f32_16x16x32_bf16 v[12:15], v[152:155], v[188:191], v[12:15]
	v_mfma_f32_16x16x32_bf16 v[8:11], v[160:163], v[188:191], v[8:11]
	v_mfma_f32_16x16x32_bf16 v[4:7], v[152:155], v[196:199], v[4:7]
	v_mfma_f32_16x16x32_bf16 v[0:3], v[160:163], v[196:199], v[0:3]
	v_mfma_f32_16x16x32_bf16 v[44:47], v[156:159], v[172:175], v[44:47]
	v_mfma_f32_16x16x32_bf16 v[36:39], v[164:167], v[172:175], v[36:39]
	v_mfma_f32_16x16x32_bf16 v[28:31], v[156:159], v[184:187], v[28:31]
	v_mfma_f32_16x16x32_bf16 v[20:23], v[164:167], v[184:187], v[20:23]
	v_mfma_f32_16x16x32_bf16 v[12:15], v[156:159], v[192:195], v[12:15]
	v_mfma_f32_16x16x32_bf16 v[8:11], v[164:167], v[192:195], v[8:11]
	v_mfma_f32_16x16x32_bf16 v[4:7], v[156:159], v[200:203], v[4:7]
	v_mfma_f32_16x16x32_bf16 v[0:3], v[164:167], v[200:203], v[0:3]
	s_setprio 0
	s_barrier
	s_movk_i32 s24, 0x100
	s_andn2_b64 vcc, exec, s[20:21]
	s_mov_b64 s[22:23], -1
	s_mov_b64 s[20:21], 0
	s_cbranch_vccz .LBB0_1352
	s_and_b64 vcc, exec, s[10:11]
	s_cbranch_vccz .LBB0_1355
	s_barrier
.LBB0_1355:
	s_ashr_i32 s12, s51, 31
	s_lshr_b32 s12, s12, 23
	s_add_i32 s12, s51, s12
	s_ashr_i32 s12, s12, 9
	v_lshl_add_u32 v136, s50, 8, v129
	s_ashr_i32 s13, s12, 31
	v_ashrrev_i32_e32 v137, 31, v136
	v_lshl_or_b32 v138, s49, 8, v130
	s_lshl_b64 s[12:13], s[12:13], 21
	v_lshlrev_b64 v[136:137], 12, v[136:137]
	v_ashrrev_i32_e32 v139, 31, v138
	v_lshl_add_u64 v[136:137], v[136:137], 0, s[12:13]
	v_lshl_add_u64 v[140:141], s[6:7], 0, v[136:137]
	v_lshlrev_b64 v[138:139], 2, v[138:139]
	v_lshl_add_u64 v[140:141], v[140:141], 0, v[138:139]
	global_store_dwordx4 v[140:141], v[124:127], off
	global_store_dwordx4 v[140:141], v[120:123], off offset:64
	global_store_dwordx4 v[140:141], v[104:107], off offset:512
	global_store_dwordx4 v[140:141], v[96:99], off offset:576
	s_mov_b64 s[12:13], 0x80000
	s_nop 0
	v_or_b32_e32 v96, 0x10000, v136
	v_mov_b32_e32 v97, v137
	v_lshl_add_u64 v[96:97], s[6:7], 0, v[96:97]
	v_lshl_add_u64 v[96:97], v[96:97], 0, v[138:139]
	global_store_dwordx4 v[96:97], v[116:119], off
	global_store_dwordx4 v[96:97], v[112:115], off offset:64
	global_store_dwordx4 v[96:97], v[88:91], off offset:512
	global_store_dwordx4 v[96:97], v[80:83], off offset:576
	s_nop 1
	v_or_b32_e32 v80, 0x20000, v136
	v_mov_b32_e32 v81, v137
	v_lshl_add_u64 v[80:81], s[6:7], 0, v[80:81]
	v_lshl_add_u64 v[80:81], v[80:81], 0, v[138:139]
	v_or_b32_e32 v136, 0x30000, v136
	global_store_dwordx4 v[80:81], v[108:111], off
	global_store_dwordx4 v[80:81], v[100:103], off offset:64
	global_store_dwordx4 v[80:81], v[76:79], off offset:512
	global_store_dwordx4 v[80:81], v[72:75], off offset:576
	s_nop 1
	v_lshl_add_u64 v[72:73], s[6:7], 0, v[136:137]
	v_lshl_add_u64 v[72:73], v[72:73], 0, v[138:139]
	global_store_dwordx4 v[72:73], v[92:95], off
	global_store_dwordx4 v[72:73], v[84:87], off offset:64
	global_store_dwordx4 v[72:73], v[68:71], off offset:512
	global_store_dwordx4 v[72:73], v[64:67], off offset:576
	s_nop 1
	v_lshl_add_u64 v[64:65], v[140:141], 0, s[12:13]
	s_mov_b32 s12, 0x80000
	v_add_co_u32_e32 v66, vcc, s12, v140
	s_mov_b64 s[12:13], 0x90000
	s_nop 0
	v_addc_co_u32_e32 v67, vcc, 0, v141, vcc
	global_store_dwordx4 v[66:67], v[60:63], off
	global_store_dwordx4 v[64:65], v[56:59], off offset:64
	global_store_dwordx4 v[64:65], v[44:47], off offset:512
	global_store_dwordx4 v[64:65], v[36:39], off offset:576
	s_nop 1
	v_lshl_add_u64 v[36:37], v[140:141], 0, s[12:13]
	s_mov_b32 s12, 0x90000
	v_add_co_u32_e32 v38, vcc, s12, v140
	s_mov_b64 s[12:13], 0xa0000
	s_nop 0
	v_addc_co_u32_e32 v39, vcc, 0, v141, vcc
	global_store_dwordx4 v[38:39], v[52:55], off
	global_store_dwordx4 v[36:37], v[48:51], off offset:64
	global_store_dwordx4 v[36:37], v[28:31], off offset:512
	global_store_dwordx4 v[36:37], v[20:23], off offset:576
	s_nop 1
	v_lshl_add_u64 v[20:21], v[140:141], 0, s[12:13]
	s_mov_b32 s12, 0xa0000
	v_add_co_u32_e32 v22, vcc, s12, v140
	s_mov_b64 s[12:13], 0xb0000
	s_nop 0
	v_addc_co_u32_e32 v23, vcc, 0, v141, vcc
	global_store_dwordx4 v[22:23], v[40:43], off
	global_store_dwordx4 v[20:21], v[32:35], off offset:64
	global_store_dwordx4 v[20:21], v[12:15], off offset:512
	global_store_dwordx4 v[20:21], v[8:11], off offset:576
	s_nop 1
	v_add_co_u32_e32 v10, vcc, 0xb0000, v140
	v_lshl_add_u64 v[8:9], v[140:141], 0, s[12:13]
	s_nop 0
	v_addc_co_u32_e32 v11, vcc, 0, v141, vcc
	s_and_b64 vcc, exec, s[2:3]
	s_mov_b64 s[2:3], -1
	global_store_dwordx4 v[10:11], v[24:27], off
	global_store_dwordx4 v[8:9], v[16:19], off offset:64
	global_store_dwordx4 v[8:9], v[4:7], off offset:512
	global_store_dwordx4 v[8:9], v[0:3], off offset:576
	s_cbranch_vccnz .LBB0_1344
	s_andn2_b64 vcc, exec, s[4:5]
	s_cbranch_vccnz .LBB0_1343
	v_writelane_b32 v255, 1, 53
	s_branch .LBB0_1343

.LBB0_1638:
	s_ashr_i32 s23, s22, 31
	s_lshl_b64 s[24:25], s[22:23], 19
	s_add_u32 s24, s41, s24
	s_addc_u32 s25, s42, s25
	s_and_b64 s[26:27], s[18:19], exec
	s_cselect_b32 s23, s25, s29
	s_cselect_b32 s56, s24, s28
	s_ashr_i32 s21, s20, 31
	s_lshl_b64 s[26:27], s[20:21], 19
	s_add_u32 s26, s38, s26
	s_addc_u32 s27, s39, s27
	s_and_b64 s[34:35], s[18:19], exec
	s_cselect_b32 s21, s27, s31
	s_cselect_b32 s57, s26, s30
	s_add_u32 s28, s28, 0x40080
	s_addc_u32 s29, s29, 0
	s_add_u32 s58, s30, 0x100
	v_mov_b32_e32 v0, 0
	s_addc_u32 s59, s31, 0
	s_mov_b32 s60, -2
	v_mov_b32_e32 v1, v0
	v_mov_b32_e32 v2, v0
	v_mov_b32_e32 v3, v0
	v_mov_b32_e32 v4, v0
	v_mov_b32_e32 v5, v0
	v_mov_b32_e32 v6, v0
	v_mov_b32_e32 v7, v0
	v_mov_b32_e32 v8, v0
	v_mov_b32_e32 v9, v0
	v_mov_b32_e32 v10, v0
	v_mov_b32_e32 v11, v0
	v_mov_b32_e32 v12, v0
	v_mov_b32_e32 v13, v0
	v_mov_b32_e32 v14, v0
	v_mov_b32_e32 v15, v0
	v_mov_b32_e32 v20, v0
	v_mov_b32_e32 v21, v0
	v_mov_b32_e32 v22, v0
	v_mov_b32_e32 v23, v0
	v_mov_b32_e32 v28, v0
	v_mov_b32_e32 v29, v0
	v_mov_b32_e32 v30, v0
	v_mov_b32_e32 v31, v0
	v_mov_b32_e32 v36, v0
	v_mov_b32_e32 v37, v0
	v_mov_b32_e32 v38, v0
	v_mov_b32_e32 v39, v0
	v_mov_b32_e32 v44, v0
	v_mov_b32_e32 v45, v0
	v_mov_b32_e32 v46, v0
	v_mov_b32_e32 v47, v0
	v_mov_b32_e32 v16, v0
	v_mov_b32_e32 v17, v0
	v_mov_b32_e32 v18, v0
	v_mov_b32_e32 v19, v0
	v_mov_b32_e32 v24, v0
	v_mov_b32_e32 v25, v0
	v_mov_b32_e32 v26, v0
	v_mov_b32_e32 v27, v0
	v_mov_b32_e32 v32, v0
	v_mov_b32_e32 v33, v0
	v_mov_b32_e32 v34, v0
	v_mov_b32_e32 v35, v0
	v_mov_b32_e32 v40, v0
	v_mov_b32_e32 v41, v0
	v_mov_b32_e32 v42, v0
	v_mov_b32_e32 v43, v0
	v_mov_b32_e32 v48, v0
	v_mov_b32_e32 v49, v0
	v_mov_b32_e32 v50, v0
	v_mov_b32_e32 v51, v0
	v_mov_b32_e32 v52, v0
	v_mov_b32_e32 v53, v0
	v_mov_b32_e32 v54, v0
	v_mov_b32_e32 v55, v0
	v_mov_b32_e32 v56, v0
	v_mov_b32_e32 v57, v0
	v_mov_b32_e32 v58, v0
	v_mov_b32_e32 v59, v0
	v_mov_b32_e32 v60, v0
	v_mov_b32_e32 v61, v0
	v_mov_b32_e32 v62, v0
	v_mov_b32_e32 v63, v0
	v_mov_b32_e32 v64, v0
	v_mov_b32_e32 v65, v0
	v_mov_b32_e32 v66, v0
	v_mov_b32_e32 v67, v0
	v_mov_b32_e32 v68, v0
	v_mov_b32_e32 v69, v0
	v_mov_b32_e32 v70, v0
	v_mov_b32_e32 v71, v0
	v_mov_b32_e32 v72, v0
	v_mov_b32_e32 v73, v0
	v_mov_b32_e32 v74, v0
	v_mov_b32_e32 v75, v0
	v_mov_b32_e32 v76, v0
	v_mov_b32_e32 v77, v0
	v_mov_b32_e32 v78, v0
	v_mov_b32_e32 v79, v0
	v_mov_b32_e32 v84, v0
	v_mov_b32_e32 v85, v0
	v_mov_b32_e32 v86, v0
	v_mov_b32_e32 v87, v0
	v_mov_b32_e32 v92, v0
	v_mov_b32_e32 v93, v0
	v_mov_b32_e32 v94, v0
	v_mov_b32_e32 v95, v0
	v_mov_b32_e32 v100, v0
	v_mov_b32_e32 v101, v0
	v_mov_b32_e32 v102, v0
	v_mov_b32_e32 v103, v0
	v_mov_b32_e32 v108, v0
	v_mov_b32_e32 v109, v0
	v_mov_b32_e32 v110, v0
	v_mov_b32_e32 v111, v0
	v_mov_b32_e32 v80, v0
	v_mov_b32_e32 v81, v0
	v_mov_b32_e32 v82, v0
	v_mov_b32_e32 v83, v0
	v_mov_b32_e32 v88, v0
	v_mov_b32_e32 v89, v0
	v_mov_b32_e32 v90, v0
	v_mov_b32_e32 v91, v0
	v_mov_b32_e32 v96, v0
	v_mov_b32_e32 v97, v0
	v_mov_b32_e32 v98, v0
	v_mov_b32_e32 v99, v0
	v_mov_b32_e32 v104, v0
	v_mov_b32_e32 v105, v0
	v_mov_b32_e32 v106, v0
	v_mov_b32_e32 v107, v0
	v_mov_b32_e32 v112, v0
	v_mov_b32_e32 v113, v0
	v_mov_b32_e32 v114, v0
	v_mov_b32_e32 v115, v0
	v_mov_b32_e32 v116, v0
	v_mov_b32_e32 v117, v0
	v_mov_b32_e32 v118, v0
	v_mov_b32_e32 v119, v0
	v_mov_b32_e32 v120, v0
	v_mov_b32_e32 v121, v0
	v_mov_b32_e32 v122, v0
	v_mov_b32_e32 v123, v0
	v_mov_b32_e32 v124, v0
	v_mov_b32_e32 v125, v0
	v_mov_b32_e32 v126, v0
	v_mov_b32_e32 v127, v0
	v_readlane_b32 s97, v255, 53
	s_nop 3
	s_cmp_eq_u32 s97, 1
	s_cbranch_scc0 .Llsb_skip_13
	v_writelane_b32 v255, 0, 53
	s_barrier
.Llsb_skip_13:
.LBB0_1639:
	ds_read_b128 v[142:145], v135
	ds_read_b128 v[146:149], v135 offset:1024
	ds_read_b128 v[150:153], v135 offset:2048
	ds_read_b128 v[154:157], v135 offset:3072
	ds_read_b128 v[158:161], v140
	ds_read_b128 v[162:165], v140 offset:1024
	ds_read_b128 v[166:169], v140 offset:2048
	ds_read_b128 v[170:173], v140 offset:3072
	s_add_u32 s30, s28, 0xfffc0080
	s_addc_u32 s31, s29, -1
	s_cmp_eq_u32 s60, 12
	s_cselect_b32 s35, s23, s31
	s_cselect_b32 s34, s56, s30
	s_cselect_b32 s31, s21, s59
	s_cselect_b32 s30, s57, s58
	v_lshl_add_u64 v[202:203], s[28:29], 0, v[128:129]
	s_add_i32 m0, s43, 0xc000
	ds_read_b128 v[174:177], v141
	ds_read_b128 v[178:181], v141 offset:1024
	ds_read_b128 v[182:185], v141 offset:2048
	ds_read_b128 v[186:189], v141 offset:3072
	ds_read_b128 v[190:193], v141 offset:4096
	ds_read_b128 v[194:197], v141 offset:5120
	ds_read_b128 v[198:201], v141 offset:6144
	ds_read_b128 v[206:209], v141 offset:7168
	global_load_lds_dwordx4 v[202:203], off
	v_lshl_add_u64 v[202:203], s[28:29], 0, v[130:131]
	s_add_i32 m0, s43, 0xe000
	s_nop 0
	global_load_lds_dwordx4 v[202:203], off
	s_waitcnt vmcnt(8)
	s_waitcnt lgkmcnt(0)
	s_barrier
	s_setprio 1
	s_waitcnt lgkmcnt(0)
	v_mfma_f32_16x16x32_bf16 v[124:127], v[142:145], v[174:177], v[124:127]
	v_mfma_f32_16x16x32_bf16 v[120:123], v[150:153], v[174:177], v[120:123]
	v_mfma_f32_16x16x32_bf16 v[116:119], v[142:145], v[182:185], v[116:119]
	v_mfma_f32_16x16x32_bf16 v[112:115], v[150:153], v[182:185], v[112:115]
	v_mfma_f32_16x16x32_bf16 v[104:107], v[142:145], v[190:193], v[104:107]
	v_mfma_f32_16x16x32_bf16 v[96:99], v[150:153], v[190:193], v[96:99]
	v_mfma_f32_16x16x32_bf16 v[88:91], v[142:145], v[198:201], v[88:91]
	v_mfma_f32_16x16x32_bf16 v[80:83], v[150:153], v[198:201], v[80:83]
	v_mfma_f32_16x16x32_bf16 v[124:127], v[146:149], v[178:181], v[124:127]
	v_mfma_f32_16x16x32_bf16 v[120:123], v[154:157], v[178:181], v[120:123]
	v_mfma_f32_16x16x32_bf16 v[116:119], v[146:149], v[186:189], v[116:119]
	v_mfma_f32_16x16x32_bf16 v[112:115], v[154:157], v[186:189], v[112:115]
	v_mfma_f32_16x16x32_bf16 v[104:107], v[146:149], v[194:197], v[104:107]
	v_mfma_f32_16x16x32_bf16 v[96:99], v[154:157], v[194:197], v[96:99]
	v_mfma_f32_16x16x32_bf16 v[88:91], v[146:149], v[206:209], v[88:91]
	v_mfma_f32_16x16x32_bf16 v[80:83], v[154:157], v[206:209], v[80:83]
	s_setprio 0
	s_setprio 1
	v_mfma_f32_16x16x32_bf16 v[108:111], v[158:161], v[174:177], v[108:111]
	v_mfma_f32_16x16x32_bf16 v[100:103], v[166:169], v[174:177], v[100:103]
	v_mfma_f32_16x16x32_bf16 v[92:95], v[158:161], v[182:185], v[92:95]
	v_mfma_f32_16x16x32_bf16 v[84:87], v[166:169], v[182:185], v[84:87]
	v_mfma_f32_16x16x32_bf16 v[76:79], v[158:161], v[190:193], v[76:79]
	v_mfma_f32_16x16x32_bf16 v[72:75], v[166:169], v[190:193], v[72:75]
	v_mfma_f32_16x16x32_bf16 v[68:71], v[158:161], v[198:201], v[68:71]
	v_mfma_f32_16x16x32_bf16 v[64:67], v[166:169], v[198:201], v[64:67]
	v_mfma_f32_16x16x32_bf16 v[108:111], v[162:165], v[178:181], v[108:111]
	v_mfma_f32_16x16x32_bf16 v[100:103], v[170:173], v[178:181], v[100:103]
	v_mfma_f32_16x16x32_bf16 v[92:95], v[162:165], v[186:189], v[92:95]
	v_mfma_f32_16x16x32_bf16 v[84:87], v[170:173], v[186:189], v[84:87]
	v_mfma_f32_16x16x32_bf16 v[76:79], v[162:165], v[194:197], v[76:79]
	v_mfma_f32_16x16x32_bf16 v[72:75], v[170:173], v[194:197], v[72:75]
	v_mfma_f32_16x16x32_bf16 v[68:71], v[162:165], v[206:209], v[68:71]
	v_mfma_f32_16x16x32_bf16 v[64:67], v[170:173], v[206:209], v[64:67]
	s_setprio 0
	s_barrier
	s_add_i32 s61, s51, s40
	v_lshl_add_u64 v[202:203], s[30:31], 0, v[136:137]
	s_mov_b32 m0, s61
	ds_read_b128 v[174:177], v141 offset:16384
	ds_read_b128 v[178:181], v141 offset:17408
	ds_read_b128 v[182:185], v141 offset:18432
	ds_read_b128 v[186:189], v141 offset:19456
	ds_read_b128 v[190:193], v141 offset:20480
	ds_read_b128 v[194:197], v141 offset:21504
	ds_read_b128 v[198:201], v141 offset:22528
	ds_read_b128 v[206:209], v141 offset:23552
	global_load_lds_dwordx4 v[202:203], off
	s_add_i32 m0, s61, 0x2000
	s_add_u32 s62, s30, 0x40000
	v_lshl_add_u64 v[210:211], s[30:31], 0, v[138:139]
	s_addc_u32 s63, s31, 0
	s_add_i32 s61, s52, s40
	global_load_lds_dwordx4 v[210:211], off
	v_lshl_add_u64 v[212:213], s[62:63], 0, v[136:137]
	s_mov_b32 m0, s61
	v_lshl_add_u64 v[214:215], s[34:35], 0, v[138:139]
	global_load_lds_dwordx4 v[212:213], off
	v_lshl_add_u64 v[212:213], s[62:63], 0, v[138:139]
	s_add_i32 m0, s61, 0x2000
	s_nop 0
	global_load_lds_dwordx4 v[212:213], off
	v_lshl_add_u64 v[212:213], s[34:35], 0, v[136:137]
	s_mov_b32 m0, s43
	s_nop 0
	global_load_lds_dwordx4 v[212:213], off
	s_mov_b32 m0, s44
	s_nop 0
	global_load_lds_dwordx4 v[214:215], off
	s_waitcnt vmcnt(8)
	s_waitcnt lgkmcnt(0)
	s_barrier
	s_setprio 1
	s_waitcnt lgkmcnt(0)
	v_mfma_f32_16x16x32_bf16 v[60:63], v[142:145], v[174:177], v[60:63]
	v_mfma_f32_16x16x32_bf16 v[56:59], v[150:153], v[174:177], v[56:59]
	v_mfma_f32_16x16x32_bf16 v[52:55], v[142:145], v[182:185], v[52:55]
	v_mfma_f32_16x16x32_bf16 v[48:51], v[150:153], v[182:185], v[48:51]
	v_mfma_f32_16x16x32_bf16 v[40:43], v[142:145], v[190:193], v[40:43]
	v_mfma_f32_16x16x32_bf16 v[32:35], v[150:153], v[190:193], v[32:35]
	v_mfma_f32_16x16x32_bf16 v[24:27], v[142:145], v[198:201], v[24:27]
	v_mfma_f32_16x16x32_bf16 v[16:19], v[150:153], v[198:201], v[16:19]
	v_mfma_f32_16x16x32_bf16 v[60:63], v[146:149], v[178:181], v[60:63]
	v_mfma_f32_16x16x32_bf16 v[56:59], v[154:157], v[178:181], v[56:59]
	v_mfma_f32_16x16x32_bf16 v[52:55], v[146:149], v[186:189], v[52:55]
	v_mfma_f32_16x16x32_bf16 v[48:51], v[154:157], v[186:189], v[48:51]
	v_mfma_f32_16x16x32_bf16 v[40:43], v[146:149], v[194:197], v[40:43]
	v_mfma_f32_16x16x32_bf16 v[32:35], v[154:157], v[194:197], v[32:35]
	v_mfma_f32_16x16x32_bf16 v[24:27], v[146:149], v[206:209], v[24:27]
	v_mfma_f32_16x16x32_bf16 v[16:19], v[154:157], v[206:209], v[16:19]
	s_setprio 0
	s_setprio 1
	v_mfma_f32_16x16x32_bf16 v[44:47], v[158:161], v[174:177], v[44:47]
	v_mfma_f32_16x16x32_bf16 v[36:39], v[166:169], v[174:177], v[36:39]
	v_mfma_f32_16x16x32_bf16 v[28:31], v[158:161], v[182:185], v[28:31]
	v_mfma_f32_16x16x32_bf16 v[20:23], v[166:169], v[182:185], v[20:23]
	v_mfma_f32_16x16x32_bf16 v[12:15], v[158:161], v[190:193], v[12:15]
	v_mfma_f32_16x16x32_bf16 v[8:11], v[166:169], v[190:193], v[8:11]
	v_mfma_f32_16x16x32_bf16 v[4:7], v[158:161], v[198:201], v[4:7]
	v_mfma_f32_16x16x32_bf16 v[0:3], v[166:169], v[198:201], v[0:3]
	v_mfma_f32_16x16x32_bf16 v[44:47], v[162:165], v[178:181], v[44:47]
	v_mfma_f32_16x16x32_bf16 v[36:39], v[170:173], v[178:181], v[36:39]
	v_mfma_f32_16x16x32_bf16 v[28:31], v[162:165], v[186:189], v[28:31]
	v_mfma_f32_16x16x32_bf16 v[20:23], v[170:173], v[186:189], v[20:23]
	v_mfma_f32_16x16x32_bf16 v[12:15], v[162:165], v[194:197], v[12:15]
	v_mfma_f32_16x16x32_bf16 v[8:11], v[170:173], v[194:197], v[8:11]
	v_mfma_f32_16x16x32_bf16 v[4:7], v[162:165], v[206:209], v[4:7]
	v_mfma_f32_16x16x32_bf16 v[0:3], v[170:173], v[206:209], v[0:3]
	s_setprio 0
	s_barrier
	s_add_i32 s61, 0, 0x18000
	s_add_i32 s62, 0, 0x1c000
	v_add_u32_e32 v154, s61, v133
	v_add_u32_e32 v170, s62, v133
	ds_read_b128 v[142:145], v154
	ds_read_b128 v[146:149], v154 offset:1024
	ds_read_b128 v[150:153], v154 offset:2048
	ds_read_b128 v[154:157], v154 offset:3072
	ds_read_b128 v[158:161], v170
	ds_read_b128 v[162:165], v170 offset:1024
	ds_read_b128 v[166:169], v170 offset:2048
	ds_read_b128 v[170:173], v170 offset:3072
	s_add_u32 s34, s34, 0x40000
	s_addc_u32 s35, s35, 0
	s_mov_b32 m0, s45
	v_lshl_add_u64 v[216:217], s[34:35], 0, v[136:137]
	ds_read_b128 v[174:177], v141 offset:32768
	ds_read_b128 v[178:181], v141 offset:33792
	ds_read_b128 v[182:185], v141 offset:34816
	ds_read_b128 v[186:189], v141 offset:35840
	ds_read_b128 v[190:193], v141 offset:36864
	ds_read_b128 v[194:197], v141 offset:37888
	ds_read_b128 v[198:201], v141 offset:38912
	ds_read_b128 v[206:209], v141 offset:39936
	global_load_lds_dwordx4 v[216:217], off
	v_lshl_add_u64 v[216:217], s[34:35], 0, v[138:139]
	s_mov_b32 m0, s46
	s_nop 0
	global_load_lds_dwordx4 v[216:217], off
	s_waitcnt vmcnt(8)
	s_waitcnt lgkmcnt(0)
	s_barrier
	s_setprio 1
	s_waitcnt lgkmcnt(0)
	v_mfma_f32_16x16x32_bf16 v[124:127], v[142:145], v[174:177], v[124:127]
	v_mfma_f32_16x16x32_bf16 v[120:123], v[150:153], v[174:177], v[120:123]
	v_mfma_f32_16x16x32_bf16 v[116:119], v[142:145], v[182:185], v[116:119]
	v_mfma_f32_16x16x32_bf16 v[112:115], v[150:153], v[182:185], v[112:115]
	v_mfma_f32_16x16x32_bf16 v[104:107], v[142:145], v[190:193], v[104:107]
	v_mfma_f32_16x16x32_bf16 v[96:99], v[150:153], v[190:193], v[96:99]
	v_mfma_f32_16x16x32_bf16 v[88:91], v[142:145], v[198:201], v[88:91]
	v_mfma_f32_16x16x32_bf16 v[80:83], v[150:153], v[198:201], v[80:83]
	v_mfma_f32_16x16x32_bf16 v[124:127], v[146:149], v[178:181], v[124:127]
	v_mfma_f32_16x16x32_bf16 v[120:123], v[154:157], v[178:181], v[120:123]
	v_mfma_f32_16x16x32_bf16 v[116:119], v[146:149], v[186:189], v[116:119]
	v_mfma_f32_16x16x32_bf16 v[112:115], v[154:157], v[186:189], v[112:115]
	v_mfma_f32_16x16x32_bf16 v[104:107], v[146:149], v[194:197], v[104:107]
	v_mfma_f32_16x16x32_bf16 v[96:99], v[154:157], v[194:197], v[96:99]
	v_mfma_f32_16x16x32_bf16 v[88:91], v[146:149], v[206:209], v[88:91]
	v_mfma_f32_16x16x32_bf16 v[80:83], v[154:157], v[206:209], v[80:83]
	s_setprio 0
	s_setprio 1
	v_mfma_f32_16x16x32_bf16 v[108:111], v[158:161], v[174:177], v[108:111]
	v_mfma_f32_16x16x32_bf16 v[100:103], v[166:169], v[174:177], v[100:103]
	v_mfma_f32_16x16x32_bf16 v[92:95], v[158:161], v[182:185], v[92:95]
	v_mfma_f32_16x16x32_bf16 v[84:87], v[166:169], v[182:185], v[84:87]
	v_mfma_f32_16x16x32_bf16 v[76:79], v[158:161], v[190:193], v[76:79]
	v_mfma_f32_16x16x32_bf16 v[72:75], v[166:169], v[190:193], v[72:75]
	v_mfma_f32_16x16x32_bf16 v[68:71], v[158:161], v[198:201], v[68:71]
	v_mfma_f32_16x16x32_bf16 v[64:67], v[166:169], v[198:201], v[64:67]
	v_mfma_f32_16x16x32_bf16 v[108:111], v[162:165], v[178:181], v[108:111]
	v_mfma_f32_16x16x32_bf16 v[100:103], v[170:173], v[178:181], v[100:103]
	v_mfma_f32_16x16x32_bf16 v[92:95], v[162:165], v[186:189], v[92:95]
	v_mfma_f32_16x16x32_bf16 v[84:87], v[170:173], v[186:189], v[84:87]
	v_mfma_f32_16x16x32_bf16 v[76:79], v[162:165], v[194:197], v[76:79]
	v_mfma_f32_16x16x32_bf16 v[72:75], v[170:173], v[194:197], v[72:75]
	v_mfma_f32_16x16x32_bf16 v[68:71], v[162:165], v[206:209], v[68:71]
	v_mfma_f32_16x16x32_bf16 v[64:67], v[170:173], v[206:209], v[64:67]
	s_setprio 0
	s_barrier
	s_add_i32 s34, s61, s40
	v_lshl_add_u64 v[202:203], v[202:203], 0, s[6:7]
	s_mov_b32 m0, s34
	ds_read_b128 v[174:177], v141 offset:49152
	ds_read_b128 v[178:181], v141 offset:50176
	ds_read_b128 v[182:185], v141 offset:51200
	ds_read_b128 v[186:189], v141 offset:52224
	ds_read_b128 v[190:193], v141 offset:53248
	ds_read_b128 v[194:197], v141 offset:54272
	ds_read_b128 v[198:201], v141 offset:55296
	ds_read_b128 v[206:209], v141 offset:56320
	global_load_lds_dwordx4 v[202:203], off
	s_add_i32 m0, s34, 0x2000
	s_add_u32 s30, s30, 0x40080
	v_lshl_add_u64 v[202:203], v[210:211], 0, s[6:7]
	s_addc_u32 s31, s31, 0
	s_add_i32 s34, s62, s40
	global_load_lds_dwordx4 v[202:203], off
	v_lshl_add_u64 v[202:203], s[30:31], 0, v[136:137]
	s_mov_b32 m0, s34
	s_nop 0
	global_load_lds_dwordx4 v[202:203], off
	v_lshl_add_u64 v[202:203], s[30:31], 0, v[138:139]
	s_add_i32 m0, s34, 0x2000
	s_nop 0
	global_load_lds_dwordx4 v[202:203], off
	v_lshl_add_u64 v[202:203], v[212:213], 0, s[6:7]
	s_mov_b32 m0, s48
	s_nop 0
	global_load_lds_dwordx4 v[202:203], off
	v_lshl_add_u64 v[202:203], v[214:215], 0, s[6:7]
	s_mov_b32 m0, s49
	s_nop 0
	global_load_lds_dwordx4 v[202:203], off
	s_waitcnt vmcnt(8)
	s_waitcnt lgkmcnt(0)
	s_barrier
	s_setprio 1
	s_waitcnt lgkmcnt(0)
	v_mfma_f32_16x16x32_bf16 v[60:63], v[142:145], v[174:177], v[60:63]
	v_mfma_f32_16x16x32_bf16 v[56:59], v[150:153], v[174:177], v[56:59]
	v_mfma_f32_16x16x32_bf16 v[52:55], v[142:145], v[182:185], v[52:55]
	v_mfma_f32_16x16x32_bf16 v[48:51], v[150:153], v[182:185], v[48:51]
	v_mfma_f32_16x16x32_bf16 v[40:43], v[142:145], v[190:193], v[40:43]
	v_mfma_f32_16x16x32_bf16 v[32:35], v[150:153], v[190:193], v[32:35]
	v_mfma_f32_16x16x32_bf16 v[24:27], v[142:145], v[198:201], v[24:27]
	v_mfma_f32_16x16x32_bf16 v[16:19], v[150:153], v[198:201], v[16:19]
	v_mfma_f32_16x16x32_bf16 v[60:63], v[146:149], v[178:181], v[60:63]
	v_mfma_f32_16x16x32_bf16 v[56:59], v[154:157], v[178:181], v[56:59]
	v_mfma_f32_16x16x32_bf16 v[52:55], v[146:149], v[186:189], v[52:55]
	v_mfma_f32_16x16x32_bf16 v[48:51], v[154:157], v[186:189], v[48:51]
	v_mfma_f32_16x16x32_bf16 v[40:43], v[146:149], v[194:197], v[40:43]
	v_mfma_f32_16x16x32_bf16 v[32:35], v[154:157], v[194:197], v[32:35]
	v_mfma_f32_16x16x32_bf16 v[24:27], v[146:149], v[206:209], v[24:27]
	v_mfma_f32_16x16x32_bf16 v[16:19], v[154:157], v[206:209], v[16:19]
	s_setprio 0
	s_setprio 1
	v_mfma_f32_16x16x32_bf16 v[44:47], v[158:161], v[174:177], v[44:47]
	v_mfma_f32_16x16x32_bf16 v[36:39], v[166:169], v[174:177], v[36:39]
	v_mfma_f32_16x16x32_bf16 v[28:31], v[158:161], v[182:185], v[28:31]
	v_mfma_f32_16x16x32_bf16 v[20:23], v[166:169], v[182:185], v[20:23]
	v_mfma_f32_16x16x32_bf16 v[12:15], v[158:161], v[190:193], v[12:15]
	v_mfma_f32_16x16x32_bf16 v[8:11], v[166:169], v[190:193], v[8:11]
	v_mfma_f32_16x16x32_bf16 v[4:7], v[158:161], v[198:201], v[4:7]
	v_mfma_f32_16x16x32_bf16 v[0:3], v[166:169], v[198:201], v[0:3]
	v_mfma_f32_16x16x32_bf16 v[44:47], v[162:165], v[178:181], v[44:47]
	v_mfma_f32_16x16x32_bf16 v[36:39], v[170:173], v[178:181], v[36:39]
	v_mfma_f32_16x16x32_bf16 v[28:31], v[162:165], v[186:189], v[28:31]
	v_mfma_f32_16x16x32_bf16 v[20:23], v[170:173], v[186:189], v[20:23]
	v_mfma_f32_16x16x32_bf16 v[12:15], v[162:165], v[194:197], v[12:15]
	v_mfma_f32_16x16x32_bf16 v[8:11], v[170:173], v[194:197], v[8:11]
	v_mfma_f32_16x16x32_bf16 v[4:7], v[162:165], v[206:209], v[4:7]
	v_mfma_f32_16x16x32_bf16 v[0:3], v[170:173], v[206:209], v[0:3]
	s_setprio 0
	s_barrier
	s_add_i32 s60, s60, 2
	s_add_u32 s28, s28, 0x100
	s_addc_u32 s29, s29, 0
	s_add_u32 s58, s58, 0x100
	s_addc_u32 s59, s59, 0
	s_cmp_gt_u32 s60, 13
	s_cbranch_scc0 .LBB0_1639
	s_and_b64 vcc, exec, s[10:11]
	s_cbranch_vccz .LBB0_1642
	s_barrier
.LBB0_1642:
	v_lshl_add_u32 v142, s8, 8, v132
	v_lshl_or_b32 v144, s9, 8, v134
	v_ashrrev_i32_e32 v143, 31, v142
	v_ashrrev_i32_e32 v145, 31, v144
	v_lshlrev_b64 v[146:147], 12, v[142:143]
	v_lshl_add_u64 v[146:147], s[4:5], 0, v[146:147]
	v_lshlrev_b64 v[144:145], 2, v[144:145]
	v_lshl_add_u64 v[146:147], v[146:147], 0, v[144:145]
	global_store_dwordx4 v[146:147], v[124:127], off
	global_store_dwordx4 v[146:147], v[120:123], off offset:64
	global_store_dwordx4 v[146:147], v[108:111], off offset:512
	global_store_dwordx4 v[146:147], v[100:103], off offset:576
	s_mov_b64 s[8:9], 0x80000
	s_nop 0
	v_or_b32_e32 v100, 16, v142
	v_ashrrev_i32_e32 v101, 31, v100
	v_lshlrev_b64 v[100:101], 12, v[100:101]
	v_lshl_add_u64 v[100:101], s[4:5], 0, v[100:101]
	v_lshl_add_u64 v[100:101], v[100:101], 0, v[144:145]
	global_store_dwordx4 v[100:101], v[116:119], off
	global_store_dwordx4 v[100:101], v[112:115], off offset:64
	global_store_dwordx4 v[100:101], v[92:95], off offset:512
	global_store_dwordx4 v[100:101], v[84:87], off offset:576
	s_nop 1
	v_or_b32_e32 v84, 32, v142
	v_ashrrev_i32_e32 v85, 31, v84
	v_lshlrev_b64 v[84:85], 12, v[84:85]
	v_lshl_add_u64 v[84:85], s[4:5], 0, v[84:85]
	v_lshl_add_u64 v[84:85], v[84:85], 0, v[144:145]
	global_store_dwordx4 v[84:85], v[104:107], off
	global_store_dwordx4 v[84:85], v[96:99], off offset:64
	global_store_dwordx4 v[84:85], v[76:79], off offset:512
	global_store_dwordx4 v[84:85], v[72:75], off offset:576
	s_nop 1
	v_or_b32_e32 v72, 48, v142
	v_ashrrev_i32_e32 v73, 31, v72
	v_lshlrev_b64 v[72:73], 12, v[72:73]
	v_lshl_add_u64 v[72:73], s[4:5], 0, v[72:73]
	v_lshl_add_u64 v[72:73], v[72:73], 0, v[144:145]
	global_store_dwordx4 v[72:73], v[88:91], off
	global_store_dwordx4 v[72:73], v[80:83], off offset:64
	global_store_dwordx4 v[72:73], v[68:71], off offset:512
	global_store_dwordx4 v[72:73], v[64:67], off offset:576
	s_nop 1
	v_add_co_u32_e32 v66, vcc, s53, v146
	v_lshl_add_u64 v[64:65], v[146:147], 0, s[8:9]
	s_nop 0
	v_addc_co_u32_e32 v67, vcc, 0, v147, vcc
	global_store_dwordx4 v[66:67], v[60:63], off
	global_store_dwordx4 v[64:65], v[56:59], off offset:64
	global_store_dwordx4 v[64:65], v[44:47], off offset:512
	global_store_dwordx4 v[64:65], v[36:39], off offset:576
	s_mov_b64 s[8:9], -1
	s_nop 0
	v_add_co_u32_e32 v38, vcc, s54, v146
	v_lshl_add_u64 v[36:37], v[146:147], 0, s[12:13]
	s_nop 0
	v_addc_co_u32_e32 v39, vcc, 0, v147, vcc
	global_store_dwordx4 v[38:39], v[52:55], off
	global_store_dwordx4 v[36:37], v[48:51], off offset:64
	global_store_dwordx4 v[36:37], v[28:31], off offset:512
	global_store_dwordx4 v[36:37], v[20:23], off offset:576
	s_nop 1
	v_add_co_u32_e32 v22, vcc, s55, v146
	v_lshl_add_u64 v[20:21], v[146:147], 0, s[14:15]
	s_nop 0
	v_addc_co_u32_e32 v23, vcc, 0, v147, vcc
	global_store_dwordx4 v[22:23], v[40:43], off
	global_store_dwordx4 v[20:21], v[32:35], off offset:64
	global_store_dwordx4 v[20:21], v[12:15], off offset:512
	global_store_dwordx4 v[20:21], v[8:11], off offset:576
	s_nop 1
	v_add_co_u32_e32 v10, vcc, 0xb0000, v146
	v_lshl_add_u64 v[8:9], v[146:147], 0, s[16:17]
	s_nop 0
	v_addc_co_u32_e32 v11, vcc, 0, v147, vcc
	s_andn2_b64 vcc, exec, s[18:19]
	global_store_dwordx4 v[10:11], v[24:27], off
	global_store_dwordx4 v[8:9], v[16:19], off offset:64
	global_store_dwordx4 v[8:9], v[4:7], off offset:512
	global_store_dwordx4 v[8:9], v[0:3], off offset:576
	s_cbranch_vccnz .LBB0_1631
	s_andn2_b64 vcc, exec, s[2:3]
	s_cbranch_vccnz .LBB0_1630
	v_writelane_b32 v255, 1, 53
	s_branch .LBB0_1630

.LBB0_1946:
	s_lshl_b32 s22, s52, 8
	s_add_i32 s26, s22, s36
	s_lshl_b32 s22, s53, 8
	s_and_b32 s27, s22, 0x100
	s_lshl_b32 s22, s52, 3
	v_or_b32_e32 v207, s26, v185
	s_and_b32 s22, s22, -16
	v_bitop3_b32 v114, s27, v206, v199 bitop3:0xc8
	s_ashr_i32 s23, s22, 31
	v_mad_i64_i32 v[112:113], s[24:25], v207, s42, v[176:177]
	v_lshlrev_b32_e32 v172, 1, v114
	v_lshl_add_u64 v[52:53], s[22:23], 2, v[174:175]
	v_lshl_add_u64 v[112:113], v[112:113], 0, v[172:173]
	global_load_dwordx4 v[44:47], v[52:53], off offset:2064
	s_nop 0
	global_load_dwordx4 v[52:55], v[52:53], off offset:2048
	s_nop 0
	global_load_dwordx4 v[210:213], v[112:113], off
	global_load_dwordx4 v[160:163], v[112:113], off offset:256
	v_or_b32_e32 v112, 16, v207
	v_mad_i64_i32 v[112:113], s[24:25], v112, s42, v[176:177]
	v_lshl_add_u64 v[112:113], v[112:113], 0, v[172:173]
	global_load_dwordx4 v[156:159], v[112:113], off
	global_load_dwordx4 v[152:155], v[112:113], off offset:256
	v_or_b32_e32 v112, 32, v207
	v_mad_i64_i32 v[112:113], s[24:25], v112, s42, v[176:177]
	v_lshl_add_u64 v[112:113], v[112:113], 0, v[172:173]
	global_load_dwordx4 v[148:151], v[112:113], off
	global_load_dwordx4 v[136:139], v[112:113], off offset:256
	v_or_b32_e32 v112, 48, v207
	v_mad_i64_i32 v[112:113], s[24:25], v112, s42, v[176:177]
	v_lshl_add_u64 v[112:113], v[112:113], 0, v[172:173]
	global_load_dwordx4 v[124:127], v[112:113], off
	s_nop 0
	global_load_dwordx4 v[112:115], v[112:113], off offset:256
	v_lshlrev_b32_e32 v208, 5, v207
	v_or_b32_e32 v183, s27, v199
	v_and_b32_e32 v208, 0x9e0, v208
	s_waitcnt vmcnt(0)
	v_lshlrev_b32_e32 v214, 16, v210
	v_and_b32_e32 v215, 0xffff0000, v210
	v_pk_fma_f32 v[214:215], v[52:53], v[214:215], v[144:145]
	s_lshl_b32 s24, s26, 5
	v_mul_f32_e32 v144, 0x3d372713, v214
	v_mul_f32_e32 v144, v214, v144
	v_fma_f32 v144, v214, v144, v214
	v_mul_f32_e32 v144, 0x3f4c422a, v144
	v_add_f32_e32 v144, v144, v144
	v_mul_f32_e32 v144, 0x3fb8aa3b, v144
	v_exp_f32_e32 v145, v144
	v_mul_f32_e32 v144, 0x3d372713, v215
	v_mul_f32_e32 v144, v215, v144
	v_fma_f32 v144, v215, v144, v215
	v_mul_f32_e32 v144, 0x3f4c422a, v144
	v_add_f32_e32 v144, v144, v144
	v_mul_f32_e32 v144, 0x3fb8aa3b, v144
	v_exp_f32_e32 v210, v144
	v_add_f32_e32 v145, 1.0, v145
	v_rcp_f32_e32 v216, v145
	v_lshrrev_b32_e32 v144, 4, v183
	v_add_f32_e32 v145, 1.0, v210
	v_lshlrev_b32_e32 v210, 16, v211
	v_and_b32_e32 v211, 0xffff0000, v211
	v_pk_fma_f32 v[146:147], v[54:55], v[210:211], v[146:147]
	v_rcp_f32_e32 v217, v145
	v_mul_f32_e32 v145, 0x3d372713, v146
	v_mul_f32_e32 v145, v146, v145
	v_mul_f32_e32 v183, 0x3d372713, v147
	v_fma_f32 v145, v146, v145, v146
	v_mul_f32_e32 v183, v147, v183
	v_mul_f32_e32 v145, 0x3f4c422a, v145
	v_fma_f32 v183, v147, v183, v147
	v_add_f32_e32 v145, v145, v145
	v_mul_f32_e32 v183, 0x3f4c422a, v183
	v_mul_f32_e32 v145, 0x3fb8aa3b, v145
	v_add_f32_e32 v183, v183, v183
	v_exp_f32_e32 v145, v145
	v_mul_f32_e32 v183, 0x3fb8aa3b, v183
	v_exp_f32_e32 v183, v183
	v_pk_fma_f32 v[210:211], v[216:217], 2.0, 1.0 op_sel_hi:[1,0,0] neg_lo:[1,0,0] neg_hi:[1,0,0]
	v_add_f32_e32 v145, 1.0, v145
	v_rcp_f32_e32 v216, v145
	v_add_f32_e32 v145, 1.0, v183
	v_rcp_f32_e32 v217, v145
	v_pk_mul_f32 v[214:215], v[214:215], 0.5 op_sel_hi:[1,0]
	v_pk_add_f32 v[210:211], v[210:211], 1.0 op_sel_hi:[1,0]
	v_pk_mul_f32 v[146:147], v[146:147], 0.5 op_sel_hi:[1,0]
	v_pk_mul_f32 v[210:211], v[214:215], v[210:211]
	v_pk_fma_f32 v[214:215], v[216:217], 2.0, 1.0 op_sel_hi:[1,0,0] neg_lo:[1,0,0] neg_hi:[1,0,0]
	v_lshlrev_b32_e32 v216, 16, v212
	v_and_b32_e32 v217, 0xffff0000, v212
	v_pk_fma_f32 v[140:141], v[44:45], v[216:217], v[140:141]
	v_pk_add_f32 v[214:215], v[214:215], 1.0 op_sel_hi:[1,0]
	v_mul_f32_e32 v145, 0x3d372713, v140
	v_mul_f32_e32 v145, v140, v145
	v_mul_f32_e32 v183, 0x3d372713, v141
	v_fma_f32 v145, v140, v145, v140
	v_mul_f32_e32 v183, v141, v183
	v_mul_f32_e32 v145, 0x3f4c422a, v145
	v_fma_f32 v183, v141, v183, v141
	v_add_f32_e32 v145, v145, v145
	v_mul_f32_e32 v183, 0x3f4c422a, v183
	v_mul_f32_e32 v145, 0x3fb8aa3b, v145
	v_add_f32_e32 v183, v183, v183
	v_exp_f32_e32 v145, v145
	v_mul_f32_e32 v183, 0x3fb8aa3b, v183
	v_exp_f32_e32 v183, v183
	v_lshlrev_b32_e32 v212, 16, v213
	v_add_f32_e32 v145, 1.0, v145
	v_and_b32_e32 v213, 0xffff0000, v213
	v_pk_mul_f32 v[146:147], v[146:147], v[214:215]
	v_rcp_f32_e32 v214, v145
	v_add_f32_e32 v145, 1.0, v183
	v_pk_fma_f32 v[142:143], v[46:47], v[212:213], v[142:143]
	v_rcp_f32_e32 v215, v145
	v_mul_f32_e32 v145, 0x3d372713, v142
	v_mul_f32_e32 v145, v142, v145
	v_mul_f32_e32 v183, 0x3d372713, v143
	v_fma_f32 v145, v142, v145, v142
	v_mul_f32_e32 v183, v143, v183
	v_mul_f32_e32 v145, 0x3f4c422a, v145
	v_fma_f32 v183, v143, v183, v143
	v_add_f32_e32 v145, v145, v145
	v_mul_f32_e32 v183, 0x3f4c422a, v183
	v_mul_f32_e32 v145, 0x3fb8aa3b, v145
	v_add_f32_e32 v183, v183, v183
	v_exp_f32_e32 v145, v145
	v_mul_f32_e32 v183, 0x3fb8aa3b, v183
	v_exp_f32_e32 v183, v183
	v_pk_fma_f32 v[212:213], v[214:215], 2.0, 1.0 op_sel_hi:[1,0,0] neg_lo:[1,0,0] neg_hi:[1,0,0]
	v_add_f32_e32 v145, 1.0, v145
	v_rcp_f32_e32 v214, v145
	v_add_f32_e32 v145, 1.0, v183
	v_rcp_f32_e32 v215, v145
	s_and_b32 s25, s24, 0x3000
	v_pk_mul_f32 v[140:141], v[140:141], 0.5 op_sel_hi:[1,0]
	v_pk_add_f32 v[212:213], v[212:213], 1.0 op_sel_hi:[1,0]
	v_or_b32_e32 v209, s25, v208
	v_pk_mul_f32 v[212:213], v[140:141], v[212:213]
	v_pk_fma_f32 v[140:141], v[214:215], 2.0, 1.0 op_sel_hi:[1,0,0] neg_lo:[1,0,0] neg_hi:[1,0,0]
	v_pk_mul_f32 v[142:143], v[142:143], 0.5 op_sel_hi:[1,0]
	v_pk_add_f32 v[140:141], v[140:141], 1.0 op_sel_hi:[1,0]
	v_or_b32_e32 v145, v209, v144
	v_pk_mul_f32 v[214:215], v[142:143], v[140:141]
	v_cvt_pk_bf16_f32 v141, v146, v147
	v_lshlrev_b32_e32 v146, 10, v145
	v_mov_b32_e32 v147, v173
	v_lshl_add_u64 v[146:147], s[8:9], 0, v[146:147]
	s_lshl_b64 s[22:23], s[22:23], 1
	v_lshl_add_u64 v[146:147], v[146:147], 0, s[22:23]
	v_mov_b32_e32 v183, v173
	v_cvt_pk_bf16_f32 v140, v210, v211
	v_cvt_pk_bf16_f32 v142, v212, v213
	v_cvt_pk_bf16_f32 v143, v214, v215
	v_lshl_add_u64 v[146:147], v[146:147], 0, v[182:183]
	global_store_dwordx4 v[146:147], v[140:143], off
	v_lshlrev_b32_e32 v146, 16, v161
	v_and_b32_e32 v147, 0xffff0000, v161
	v_lshlrev_b32_e32 v140, 16, v160
	v_and_b32_e32 v141, 0xffff0000, v160
	v_pk_fma_f32 v[140:141], v[52:53], v[140:141], v[132:133]
	v_pk_fma_f32 v[134:135], v[54:55], v[146:147], v[134:135]
	v_mul_f32_e32 v132, 0x3d372713, v140
	v_mul_f32_e32 v132, v140, v132
	v_fma_f32 v132, v140, v132, v140
	v_mul_f32_e32 v132, 0x3f4c422a, v132
	v_add_f32_e32 v132, v132, v132
	v_mul_f32_e32 v132, 0x3fb8aa3b, v132
	v_exp_f32_e32 v133, v132
	v_mul_f32_e32 v132, 0x3d372713, v141
	v_mul_f32_e32 v132, v141, v132
	v_fma_f32 v132, v141, v132, v141
	v_mul_f32_e32 v132, 0x3f4c422a, v132
	v_add_f32_e32 v132, v132, v132
	v_mul_f32_e32 v132, 0x3fb8aa3b, v132
	v_exp_f32_e32 v143, v132
	v_add_f32_e32 v133, 1.0, v133
	v_rcp_f32_e32 v142, v133
	v_mul_f32_e32 v145, 0x3d372713, v135
	v_add_f32_e32 v133, 1.0, v143
	v_rcp_f32_e32 v143, v133
	v_mul_f32_e32 v133, 0x3d372713, v134
	v_mul_f32_e32 v133, v134, v133
	v_fma_f32 v133, v134, v133, v134
	v_mul_f32_e32 v145, v135, v145
	v_mul_f32_e32 v133, 0x3f4c422a, v133
	v_fma_f32 v145, v135, v145, v135
	v_add_f32_e32 v133, v133, v133
	v_mul_f32_e32 v145, 0x3f4c422a, v145
	v_mul_f32_e32 v133, 0x3fb8aa3b, v133
	v_add_f32_e32 v145, v145, v145
	v_exp_f32_e32 v133, v133
	v_mul_f32_e32 v145, 0x3fb8aa3b, v145
	v_exp_f32_e32 v145, v145
	v_pk_fma_f32 v[142:143], v[142:143], 2.0, 1.0 op_sel_hi:[1,0,0] neg_lo:[1,0,0] neg_hi:[1,0,0]
	v_add_f32_e32 v133, 1.0, v133
	v_rcp_f32_e32 v146, v133
	v_add_f32_e32 v133, 1.0, v145
	v_rcp_f32_e32 v147, v133
	v_pk_mul_f32 v[140:141], v[140:141], 0.5 op_sel_hi:[1,0]
	v_pk_add_f32 v[142:143], v[142:143], 1.0 op_sel_hi:[1,0]
	v_pk_mul_f32 v[134:135], v[134:135], 0.5 op_sel_hi:[1,0]
	v_pk_mul_f32 v[140:141], v[140:141], v[142:143]
	v_pk_fma_f32 v[142:143], v[146:147], 2.0, 1.0 op_sel_hi:[1,0,0] neg_lo:[1,0,0] neg_hi:[1,0,0]
	v_lshlrev_b32_e32 v146, 16, v162
	v_and_b32_e32 v147, 0xffff0000, v162
	v_pk_fma_f32 v[128:129], v[44:45], v[146:147], v[128:129]
	v_pk_add_f32 v[142:143], v[142:143], 1.0 op_sel_hi:[1,0]
	v_mul_f32_e32 v133, 0x3d372713, v128
	v_mul_f32_e32 v133, v128, v133
	v_mul_f32_e32 v145, 0x3d372713, v129
	v_fma_f32 v133, v128, v133, v128
	v_mul_f32_e32 v145, v129, v145
	v_mul_f32_e32 v133, 0x3f4c422a, v133
	v_fma_f32 v145, v129, v145, v129
	v_add_f32_e32 v133, v133, v133
	v_mul_f32_e32 v145, 0x3f4c422a, v145
	v_mul_f32_e32 v133, 0x3fb8aa3b, v133
	v_add_f32_e32 v145, v145, v145
	v_exp_f32_e32 v133, v133
	v_mul_f32_e32 v145, 0x3fb8aa3b, v145
	v_exp_f32_e32 v145, v145
	v_lshlrev_b32_e32 v146, 16, v163
	v_add_f32_e32 v133, 1.0, v133
	v_and_b32_e32 v147, 0xffff0000, v163
	v_pk_mul_f32 v[134:135], v[134:135], v[142:143]
	v_rcp_f32_e32 v142, v133
	v_add_f32_e32 v133, 1.0, v145
	v_pk_fma_f32 v[130:131], v[46:47], v[146:147], v[130:131]
	v_rcp_f32_e32 v143, v133
	v_mul_f32_e32 v133, 0x3d372713, v130
	v_mul_f32_e32 v133, v130, v133
	v_mul_f32_e32 v145, 0x3d372713, v131
	v_fma_f32 v133, v130, v133, v130
	v_mul_f32_e32 v145, v131, v145
	v_mul_f32_e32 v133, 0x3f4c422a, v133
	v_fma_f32 v145, v131, v145, v131
	v_add_f32_e32 v133, v133, v133
	v_mul_f32_e32 v145, 0x3f4c422a, v145
	v_mul_f32_e32 v133, 0x3fb8aa3b, v133
	v_add_f32_e32 v145, v145, v145
	v_exp_f32_e32 v133, v133
	v_mul_f32_e32 v145, 0x3fb8aa3b, v145
	v_exp_f32_e32 v145, v145
	v_pk_fma_f32 v[142:143], v[142:143], 2.0, 1.0 op_sel_hi:[1,0,0] neg_lo:[1,0,0] neg_hi:[1,0,0]
	v_add_f32_e32 v133, 1.0, v133
	v_rcp_f32_e32 v146, v133
	v_add_f32_e32 v133, 1.0, v145
	v_rcp_f32_e32 v147, v133
	v_pk_mul_f32 v[128:129], v[128:129], 0.5 op_sel_hi:[1,0]
	v_pk_add_f32 v[142:143], v[142:143], 1.0 op_sel_hi:[1,0]
	v_or_b32_e32 v132, 8, v144
	v_pk_mul_f32 v[142:143], v[128:129], v[142:143]
	v_pk_fma_f32 v[128:129], v[146:147], 2.0, 1.0 op_sel_hi:[1,0,0] neg_lo:[1,0,0] neg_hi:[1,0,0]
	v_pk_mul_f32 v[130:131], v[130:131], 0.5 op_sel_hi:[1,0]
	v_pk_add_f32 v[128:129], v[128:129], 1.0 op_sel_hi:[1,0]
	v_or_b32_e32 v133, v209, v132
	v_pk_mul_f32 v[146:147], v[130:131], v[128:129]
	v_cvt_pk_bf16_f32 v129, v134, v135
	v_lshlrev_b32_e32 v134, 10, v133
	v_mov_b32_e32 v135, v173
	v_lshl_add_u64 v[134:135], s[8:9], 0, v[134:135]
	v_lshl_add_u64 v[134:135], v[134:135], 0, s[22:23]
	v_cvt_pk_bf16_f32 v128, v140, v141
	v_cvt_pk_bf16_f32 v130, v142, v143
	v_cvt_pk_bf16_f32 v131, v146, v147
	v_lshl_add_u64 v[134:135], v[134:135], 0, v[182:183]
	global_store_dwordx4 v[134:135], v[128:131], off
	v_or_b32_e32 v133, 0x200, v209
	s_nop 0
	v_lshlrev_b32_e32 v128, 16, v156
	v_and_b32_e32 v129, 0xffff0000, v156
	v_pk_fma_f32 v[120:121], v[52:53], v[128:129], v[120:121]
	v_lshlrev_b32_e32 v130, 16, v157
	v_mul_f32_e32 v128, 0x3d372713, v120
	v_mul_f32_e32 v129, 0x3d372713, v121
	v_and_b32_e32 v131, 0xffff0000, v157
	v_mul_f32_e32 v128, v120, v128
	v_mul_f32_e32 v129, v121, v129
	v_pk_fma_f32 v[122:123], v[54:55], v[130:131], v[122:123]
	v_fma_f32 v128, v120, v128, v120
	v_fma_f32 v129, v121, v129, v121
	v_mul_f32_e32 v130, 0x3d372713, v122
	v_mul_f32_e32 v131, 0x3d372713, v123
	v_mul_f32_e32 v128, 0x3f4c422a, v128
	v_mul_f32_e32 v129, 0x3f4c422a, v129
	v_mul_f32_e32 v130, v122, v130
	v_mul_f32_e32 v131, v123, v131
	v_add_f32_e32 v128, v128, v128
	v_add_f32_e32 v129, v129, v129
	v_fma_f32 v130, v122, v130, v122
	v_fma_f32 v131, v123, v131, v123
	v_mul_f32_e32 v128, 0x3fb8aa3b, v128
	v_mul_f32_e32 v129, 0x3fb8aa3b, v129
	v_mul_f32_e32 v130, 0x3f4c422a, v130
	v_mul_f32_e32 v131, 0x3f4c422a, v131
	v_exp_f32_e32 v128, v128
	v_exp_f32_e32 v129, v129
	v_add_f32_e32 v130, v130, v130
	v_add_f32_e32 v131, v131, v131
	v_mul_f32_e32 v130, 0x3fb8aa3b, v130
	v_mul_f32_e32 v131, 0x3fb8aa3b, v131
	v_exp_f32_e32 v130, v130
	v_exp_f32_e32 v131, v131
	v_add_f32_e32 v128, 1.0, v128
	v_add_f32_e32 v129, 1.0, v129
	v_rcp_f32_e32 v128, v128
	v_rcp_f32_e32 v129, v129
	v_add_f32_e32 v130, 1.0, v130
	v_add_f32_e32 v131, 1.0, v131
	v_rcp_f32_e32 v130, v130
	v_rcp_f32_e32 v131, v131
	v_pk_fma_f32 v[128:129], v[128:129], 2.0, 1.0 op_sel_hi:[1,0,0] neg_lo:[1,0,0] neg_hi:[1,0,0]
	v_pk_mul_f32 v[120:121], v[120:121], 0.5 op_sel_hi:[1,0]
	v_pk_add_f32 v[128:129], v[128:129], 1.0 op_sel_hi:[1,0]
	v_pk_mul_f32 v[122:123], v[122:123], 0.5 op_sel_hi:[1,0]
	v_pk_mul_f32 v[120:121], v[120:121], v[128:129]
	v_pk_fma_f32 v[128:129], v[130:131], 2.0, 1.0 op_sel_hi:[1,0,0] neg_lo:[1,0,0] neg_hi:[1,0,0]
	v_lshlrev_b32_e32 v130, 16, v158
	v_and_b32_e32 v131, 0xffff0000, v158
	v_pk_fma_f32 v[116:117], v[44:45], v[130:131], v[116:117]
	v_pk_add_f32 v[128:129], v[128:129], 1.0 op_sel_hi:[1,0]
	v_mul_f32_e32 v130, 0x3d372713, v116
	v_mul_f32_e32 v131, 0x3d372713, v117
	v_mul_f32_e32 v130, v116, v130
	v_mul_f32_e32 v131, v117, v131
	v_fma_f32 v130, v116, v130, v116
	v_fma_f32 v131, v117, v131, v117
	v_mul_f32_e32 v130, 0x3f4c422a, v130
	v_mul_f32_e32 v131, 0x3f4c422a, v131
	v_add_f32_e32 v130, v130, v130
	v_add_f32_e32 v131, v131, v131
	v_mul_f32_e32 v130, 0x3fb8aa3b, v130
	v_mul_f32_e32 v131, 0x3fb8aa3b, v131
	v_exp_f32_e32 v130, v130
	v_exp_f32_e32 v131, v131
	v_pk_mul_f32 v[122:123], v[122:123], v[128:129]
	v_pk_mul_f32 v[116:117], v[116:117], 0.5 op_sel_hi:[1,0]
	v_add_f32_e32 v128, 1.0, v130
	v_add_f32_e32 v129, 1.0, v131
	v_lshlrev_b32_e32 v130, 16, v159
	v_and_b32_e32 v131, 0xffff0000, v159
	v_pk_fma_f32 v[118:119], v[46:47], v[130:131], v[118:119]
	v_rcp_f32_e32 v128, v128
	v_mul_f32_e32 v130, 0x3d372713, v118
	v_mul_f32_e32 v131, 0x3d372713, v119
	v_mul_f32_e32 v130, v118, v130
	v_mul_f32_e32 v131, v119, v131
	v_fma_f32 v130, v118, v130, v118
	v_fma_f32 v131, v119, v131, v119
	v_mul_f32_e32 v130, 0x3f4c422a, v130
	v_mul_f32_e32 v131, 0x3f4c422a, v131
	v_add_f32_e32 v130, v130, v130
	v_add_f32_e32 v131, v131, v131
	v_mul_f32_e32 v130, 0x3fb8aa3b, v130
	v_mul_f32_e32 v131, 0x3fb8aa3b, v131
	v_exp_f32_e32 v130, v130
	v_exp_f32_e32 v131, v131
	v_rcp_f32_e32 v129, v129
	v_pk_mul_f32 v[118:119], v[118:119], 0.5 op_sel_hi:[1,0]
	v_add_f32_e32 v130, 1.0, v130
	v_add_f32_e32 v131, 1.0, v131
	v_rcp_f32_e32 v130, v130
	v_rcp_f32_e32 v131, v131
	v_pk_fma_f32 v[128:129], v[128:129], 2.0, 1.0 op_sel_hi:[1,0,0] neg_lo:[1,0,0] neg_hi:[1,0,0]
	s_nop 0
	v_pk_add_f32 v[128:129], v[128:129], 1.0 op_sel_hi:[1,0]
	s_nop 0
	v_pk_mul_f32 v[128:129], v[116:117], v[128:129]
	v_pk_fma_f32 v[116:117], v[130:131], 2.0, 1.0 op_sel_hi:[1,0,0] neg_lo:[1,0,0] neg_hi:[1,0,0]
	s_nop 0
	v_pk_add_f32 v[116:117], v[116:117], 1.0 op_sel_hi:[1,0]
	s_nop 0
	v_pk_mul_f32 v[130:131], v[118:119], v[116:117]
	v_cvt_pk_bf16_f32 v116, v120, v121
	v_or_b32_e32 v120, v133, v144
	v_lshlrev_b32_e32 v120, 10, v120
	v_mov_b32_e32 v121, v173
	v_lshl_add_u64 v[120:121], s[8:9], 0, v[120:121]
	v_cvt_pk_bf16_f32 v117, v122, v123
	v_lshl_add_u64 v[120:121], v[120:121], 0, s[22:23]
	v_lshlrev_b32_e32 v122, 16, v152
	v_and_b32_e32 v123, 0xffff0000, v152
	v_cvt_pk_bf16_f32 v118, v128, v129
	v_cvt_pk_bf16_f32 v119, v130, v131
	v_lshl_add_u64 v[120:121], v[120:121], 0, v[182:183]
	v_pk_fma_f32 v[108:109], v[52:53], v[122:123], v[108:109]
	global_store_dwordx4 v[120:121], v[116:119], off
	v_mul_f32_e32 v122, 0x3d372713, v108
	v_mul_f32_e32 v123, 0x3d372713, v109
	v_lshlrev_b32_e32 v118, 16, v153
	v_and_b32_e32 v119, 0xffff0000, v153
	v_mul_f32_e32 v122, v108, v122
	v_mul_f32_e32 v123, v109, v123
	v_pk_fma_f32 v[110:111], v[54:55], v[118:119], v[110:111]
	v_fma_f32 v122, v108, v122, v108
	v_fma_f32 v123, v109, v123, v109
	v_mul_f32_e32 v118, 0x3d372713, v110
	v_mul_f32_e32 v119, 0x3d372713, v111
	v_mul_f32_e32 v122, 0x3f4c422a, v122
	v_mul_f32_e32 v123, 0x3f4c422a, v123
	v_mul_f32_e32 v118, v110, v118
	v_mul_f32_e32 v119, v111, v119
	v_add_f32_e32 v122, v122, v122
	v_add_f32_e32 v123, v123, v123
	v_fma_f32 v118, v110, v118, v110
	v_fma_f32 v119, v111, v119, v111
	v_mul_f32_e32 v122, 0x3fb8aa3b, v122
	v_mul_f32_e32 v123, 0x3fb8aa3b, v123
	v_mul_f32_e32 v118, 0x3f4c422a, v118
	v_mul_f32_e32 v119, 0x3f4c422a, v119
	v_exp_f32_e32 v122, v122
	v_exp_f32_e32 v123, v123
	v_add_f32_e32 v118, v118, v118
	v_add_f32_e32 v119, v119, v119
	v_mul_f32_e32 v118, 0x3fb8aa3b, v118
	v_mul_f32_e32 v119, 0x3fb8aa3b, v119
	v_exp_f32_e32 v118, v118
	v_exp_f32_e32 v119, v119
	v_add_f32_e32 v116, 1.0, v122
	v_add_f32_e32 v117, 1.0, v123
	v_rcp_f32_e32 v116, v116
	v_rcp_f32_e32 v117, v117
	v_add_f32_e32 v118, 1.0, v118
	v_add_f32_e32 v119, 1.0, v119
	v_rcp_f32_e32 v118, v118
	v_rcp_f32_e32 v119, v119
	v_pk_fma_f32 v[116:117], v[116:117], 2.0, 1.0 op_sel_hi:[1,0,0] neg_lo:[1,0,0] neg_hi:[1,0,0]
	v_pk_mul_f32 v[108:109], v[108:109], 0.5 op_sel_hi:[1,0]
	v_pk_add_f32 v[116:117], v[116:117], 1.0 op_sel_hi:[1,0]
	v_pk_mul_f32 v[110:111], v[110:111], 0.5 op_sel_hi:[1,0]
	v_pk_mul_f32 v[108:109], v[108:109], v[116:117]
	v_pk_fma_f32 v[116:117], v[118:119], 2.0, 1.0 op_sel_hi:[1,0,0] neg_lo:[1,0,0] neg_hi:[1,0,0]
	v_lshlrev_b32_e32 v118, 16, v154
	v_and_b32_e32 v119, 0xffff0000, v154
	v_pk_fma_f32 v[104:105], v[44:45], v[118:119], v[104:105]
	v_pk_add_f32 v[116:117], v[116:117], 1.0 op_sel_hi:[1,0]
	v_mul_f32_e32 v118, 0x3d372713, v104
	v_mul_f32_e32 v119, 0x3d372713, v105
	v_mul_f32_e32 v118, v104, v118
	v_mul_f32_e32 v119, v105, v119
	v_fma_f32 v118, v104, v118, v104
	v_fma_f32 v119, v105, v119, v105
	v_mul_f32_e32 v118, 0x3f4c422a, v118
	v_mul_f32_e32 v119, 0x3f4c422a, v119
	v_add_f32_e32 v118, v118, v118
	v_add_f32_e32 v119, v119, v119
	v_mul_f32_e32 v118, 0x3fb8aa3b, v118
	v_mul_f32_e32 v119, 0x3fb8aa3b, v119
	v_exp_f32_e32 v118, v118
	v_exp_f32_e32 v119, v119
	v_pk_mul_f32 v[110:111], v[110:111], v[116:117]
	v_pk_mul_f32 v[104:105], v[104:105], 0.5 op_sel_hi:[1,0]
	v_add_f32_e32 v116, 1.0, v118
	v_add_f32_e32 v117, 1.0, v119
	v_lshlrev_b32_e32 v118, 16, v155
	v_and_b32_e32 v119, 0xffff0000, v155
	v_pk_fma_f32 v[106:107], v[46:47], v[118:119], v[106:107]
	v_rcp_f32_e32 v116, v116
	v_mul_f32_e32 v118, 0x3d372713, v106
	v_mul_f32_e32 v119, 0x3d372713, v107
	v_mul_f32_e32 v118, v106, v118
	v_mul_f32_e32 v119, v107, v119
	v_fma_f32 v118, v106, v118, v106
	v_fma_f32 v119, v107, v119, v107
	v_mul_f32_e32 v118, 0x3f4c422a, v118
	v_mul_f32_e32 v119, 0x3f4c422a, v119
	v_add_f32_e32 v118, v118, v118
	v_add_f32_e32 v119, v119, v119
	v_mul_f32_e32 v118, 0x3fb8aa3b, v118
	v_mul_f32_e32 v119, 0x3fb8aa3b, v119
	v_exp_f32_e32 v118, v118
	v_exp_f32_e32 v119, v119
	v_rcp_f32_e32 v117, v117
	v_pk_mul_f32 v[106:107], v[106:107], 0.5 op_sel_hi:[1,0]
	v_add_f32_e32 v118, 1.0, v118
	v_add_f32_e32 v119, 1.0, v119
	v_rcp_f32_e32 v118, v118
	v_rcp_f32_e32 v119, v119
	v_pk_fma_f32 v[116:117], v[116:117], 2.0, 1.0 op_sel_hi:[1,0,0] neg_lo:[1,0,0] neg_hi:[1,0,0]
	s_nop 0
	v_pk_add_f32 v[116:117], v[116:117], 1.0 op_sel_hi:[1,0]
	s_nop 0
	v_pk_mul_f32 v[116:117], v[104:105], v[116:117]
	v_pk_fma_f32 v[104:105], v[118:119], 2.0, 1.0 op_sel_hi:[1,0,0] neg_lo:[1,0,0] neg_hi:[1,0,0]
	s_nop 0
	v_pk_add_f32 v[104:105], v[104:105], 1.0 op_sel_hi:[1,0]
	s_nop 0
	v_pk_mul_f32 v[118:119], v[106:107], v[104:105]
	v_cvt_pk_bf16_f32 v104, v108, v109
	v_or_b32_e32 v108, v133, v132
	v_lshlrev_b32_e32 v108, 10, v108
	v_mov_b32_e32 v109, v173
	v_lshl_add_u64 v[108:109], s[8:9], 0, v[108:109]
	v_lshl_add_u64 v[108:109], v[108:109], 0, s[22:23]
	v_cvt_pk_bf16_f32 v105, v110, v111
	v_cvt_pk_bf16_f32 v106, v116, v117
	v_cvt_pk_bf16_f32 v107, v118, v119
	v_lshl_add_u64 v[108:109], v[108:109], 0, v[182:183]
	global_store_dwordx4 v[108:109], v[104:107], off
	v_or_b32_e32 v108, 0x400, v209
	s_nop 0
	v_lshlrev_b32_e32 v104, 16, v148
	v_and_b32_e32 v105, 0xffff0000, v148
	v_pk_fma_f32 v[100:101], v[52:53], v[104:105], v[100:101]
	v_lshlrev_b32_e32 v106, 16, v149
	v_mul_f32_e32 v104, 0x3d372713, v100
	v_mul_f32_e32 v105, 0x3d372713, v101
	v_and_b32_e32 v107, 0xffff0000, v149
	v_mul_f32_e32 v104, v100, v104
	v_mul_f32_e32 v105, v101, v105
	v_pk_fma_f32 v[102:103], v[54:55], v[106:107], v[102:103]
	v_fma_f32 v104, v100, v104, v100
	v_fma_f32 v105, v101, v105, v101
	v_mul_f32_e32 v106, 0x3d372713, v102
	v_mul_f32_e32 v107, 0x3d372713, v103
	v_mul_f32_e32 v104, 0x3f4c422a, v104
	v_mul_f32_e32 v105, 0x3f4c422a, v105
	v_mul_f32_e32 v106, v102, v106
	v_mul_f32_e32 v107, v103, v107
	v_add_f32_e32 v104, v104, v104
	v_add_f32_e32 v105, v105, v105
	v_fma_f32 v106, v102, v106, v102
	v_fma_f32 v107, v103, v107, v103
	v_mul_f32_e32 v104, 0x3fb8aa3b, v104
	v_mul_f32_e32 v105, 0x3fb8aa3b, v105
	v_mul_f32_e32 v106, 0x3f4c422a, v106
	v_mul_f32_e32 v107, 0x3f4c422a, v107
	v_exp_f32_e32 v104, v104
	v_exp_f32_e32 v105, v105
	v_add_f32_e32 v106, v106, v106
	v_add_f32_e32 v107, v107, v107
	v_mul_f32_e32 v106, 0x3fb8aa3b, v106
	v_mul_f32_e32 v107, 0x3fb8aa3b, v107
	v_exp_f32_e32 v106, v106
	v_exp_f32_e32 v107, v107
	v_add_f32_e32 v104, 1.0, v104
	v_add_f32_e32 v105, 1.0, v105
	v_rcp_f32_e32 v104, v104
	v_rcp_f32_e32 v105, v105
	v_add_f32_e32 v106, 1.0, v106
	v_add_f32_e32 v107, 1.0, v107
	v_rcp_f32_e32 v106, v106
	v_rcp_f32_e32 v107, v107
	v_pk_fma_f32 v[104:105], v[104:105], 2.0, 1.0 op_sel_hi:[1,0,0] neg_lo:[1,0,0] neg_hi:[1,0,0]
	v_pk_mul_f32 v[100:101], v[100:101], 0.5 op_sel_hi:[1,0]
	v_pk_add_f32 v[104:105], v[104:105], 1.0 op_sel_hi:[1,0]
	v_pk_mul_f32 v[102:103], v[102:103], 0.5 op_sel_hi:[1,0]
	v_pk_mul_f32 v[100:101], v[100:101], v[104:105]
	v_pk_fma_f32 v[104:105], v[106:107], 2.0, 1.0 op_sel_hi:[1,0,0] neg_lo:[1,0,0] neg_hi:[1,0,0]
	v_lshlrev_b32_e32 v106, 16, v150
	v_and_b32_e32 v107, 0xffff0000, v150
	v_pk_fma_f32 v[96:97], v[44:45], v[106:107], v[96:97]
	v_pk_add_f32 v[104:105], v[104:105], 1.0 op_sel_hi:[1,0]
	v_mul_f32_e32 v106, 0x3d372713, v96
	v_mul_f32_e32 v107, 0x3d372713, v97
	v_mul_f32_e32 v106, v96, v106
	v_mul_f32_e32 v107, v97, v107
	v_fma_f32 v106, v96, v106, v96
	v_fma_f32 v107, v97, v107, v97
	v_mul_f32_e32 v106, 0x3f4c422a, v106
	v_mul_f32_e32 v107, 0x3f4c422a, v107
	v_add_f32_e32 v106, v106, v106
	v_add_f32_e32 v107, v107, v107
	v_mul_f32_e32 v106, 0x3fb8aa3b, v106
	v_mul_f32_e32 v107, 0x3fb8aa3b, v107
	v_exp_f32_e32 v106, v106
	v_exp_f32_e32 v107, v107
	v_pk_mul_f32 v[102:103], v[102:103], v[104:105]
	v_pk_mul_f32 v[96:97], v[96:97], 0.5 op_sel_hi:[1,0]
	v_add_f32_e32 v104, 1.0, v106
	v_add_f32_e32 v105, 1.0, v107
	v_lshlrev_b32_e32 v106, 16, v151
	v_and_b32_e32 v107, 0xffff0000, v151
	v_pk_fma_f32 v[98:99], v[46:47], v[106:107], v[98:99]
	v_rcp_f32_e32 v104, v104
	v_mul_f32_e32 v106, 0x3d372713, v98
	v_mul_f32_e32 v107, 0x3d372713, v99
	v_mul_f32_e32 v106, v98, v106
	v_mul_f32_e32 v107, v99, v107
	v_fma_f32 v106, v98, v106, v98
	v_fma_f32 v107, v99, v107, v99
	v_mul_f32_e32 v106, 0x3f4c422a, v106
	v_mul_f32_e32 v107, 0x3f4c422a, v107
	v_add_f32_e32 v106, v106, v106
	v_add_f32_e32 v107, v107, v107
	v_mul_f32_e32 v106, 0x3fb8aa3b, v106
	v_mul_f32_e32 v107, 0x3fb8aa3b, v107
	v_exp_f32_e32 v106, v106
	v_exp_f32_e32 v107, v107
	v_rcp_f32_e32 v105, v105
	v_pk_mul_f32 v[98:99], v[98:99], 0.5 op_sel_hi:[1,0]
	v_add_f32_e32 v106, 1.0, v106
	v_add_f32_e32 v107, 1.0, v107
	v_rcp_f32_e32 v106, v106
	v_rcp_f32_e32 v107, v107
	v_pk_fma_f32 v[104:105], v[104:105], 2.0, 1.0 op_sel_hi:[1,0,0] neg_lo:[1,0,0] neg_hi:[1,0,0]
	s_nop 0
	v_pk_add_f32 v[104:105], v[104:105], 1.0 op_sel_hi:[1,0]
	s_nop 0
	v_pk_mul_f32 v[104:105], v[96:97], v[104:105]
	v_pk_fma_f32 v[96:97], v[106:107], 2.0, 1.0 op_sel_hi:[1,0,0] neg_lo:[1,0,0] neg_hi:[1,0,0]
	s_nop 0
	v_pk_add_f32 v[96:97], v[96:97], 1.0 op_sel_hi:[1,0]
	s_nop 0
	v_pk_mul_f32 v[106:107], v[98:99], v[96:97]
	v_cvt_pk_bf16_f32 v96, v100, v101
	v_or_b32_e32 v100, v108, v144
	v_lshlrev_b32_e32 v100, 10, v100
	v_mov_b32_e32 v101, v173
	v_lshl_add_u64 v[100:101], s[8:9], 0, v[100:101]
	v_cvt_pk_bf16_f32 v97, v102, v103
	v_lshl_add_u64 v[100:101], v[100:101], 0, s[22:23]
	v_lshlrev_b32_e32 v102, 16, v136
	v_and_b32_e32 v103, 0xffff0000, v136
	v_cvt_pk_bf16_f32 v98, v104, v105
	v_cvt_pk_bf16_f32 v99, v106, v107
	v_lshl_add_u64 v[100:101], v[100:101], 0, v[182:183]
	v_pk_fma_f32 v[92:93], v[52:53], v[102:103], v[92:93]
	global_store_dwordx4 v[100:101], v[96:99], off
	v_mul_f32_e32 v102, 0x3d372713, v92
	v_mul_f32_e32 v103, 0x3d372713, v93
	v_lshlrev_b32_e32 v98, 16, v137
	v_and_b32_e32 v99, 0xffff0000, v137
	v_mul_f32_e32 v102, v92, v102
	v_mul_f32_e32 v103, v93, v103
	v_pk_fma_f32 v[94:95], v[54:55], v[98:99], v[94:95]
	v_fma_f32 v102, v92, v102, v92
	v_fma_f32 v103, v93, v103, v93
	v_mul_f32_e32 v98, 0x3d372713, v94
	v_mul_f32_e32 v99, 0x3d372713, v95
	v_mul_f32_e32 v102, 0x3f4c422a, v102
	v_mul_f32_e32 v103, 0x3f4c422a, v103
	v_mul_f32_e32 v98, v94, v98
	v_mul_f32_e32 v99, v95, v99
	v_add_f32_e32 v102, v102, v102
	v_add_f32_e32 v103, v103, v103
	v_fma_f32 v98, v94, v98, v94
	v_fma_f32 v99, v95, v99, v95
	v_mul_f32_e32 v102, 0x3fb8aa3b, v102
	v_mul_f32_e32 v103, 0x3fb8aa3b, v103
	v_mul_f32_e32 v98, 0x3f4c422a, v98
	v_mul_f32_e32 v99, 0x3f4c422a, v99
	v_exp_f32_e32 v102, v102
	v_exp_f32_e32 v103, v103
	v_add_f32_e32 v98, v98, v98
	v_add_f32_e32 v99, v99, v99
	v_mul_f32_e32 v98, 0x3fb8aa3b, v98
	v_mul_f32_e32 v99, 0x3fb8aa3b, v99
	v_exp_f32_e32 v98, v98
	v_exp_f32_e32 v99, v99
	v_add_f32_e32 v96, 1.0, v102
	v_add_f32_e32 v97, 1.0, v103
	v_rcp_f32_e32 v96, v96
	v_rcp_f32_e32 v97, v97
	v_add_f32_e32 v98, 1.0, v98
	v_add_f32_e32 v99, 1.0, v99
	v_rcp_f32_e32 v98, v98
	v_rcp_f32_e32 v99, v99
	v_pk_fma_f32 v[96:97], v[96:97], 2.0, 1.0 op_sel_hi:[1,0,0] neg_lo:[1,0,0] neg_hi:[1,0,0]
	v_pk_mul_f32 v[92:93], v[92:93], 0.5 op_sel_hi:[1,0]
	v_pk_add_f32 v[96:97], v[96:97], 1.0 op_sel_hi:[1,0]
	v_pk_mul_f32 v[94:95], v[94:95], 0.5 op_sel_hi:[1,0]
	v_pk_mul_f32 v[92:93], v[92:93], v[96:97]
	v_pk_fma_f32 v[96:97], v[98:99], 2.0, 1.0 op_sel_hi:[1,0,0] neg_lo:[1,0,0] neg_hi:[1,0,0]
	v_lshlrev_b32_e32 v98, 16, v138
	v_and_b32_e32 v99, 0xffff0000, v138
	v_pk_fma_f32 v[88:89], v[44:45], v[98:99], v[88:89]
	v_pk_add_f32 v[96:97], v[96:97], 1.0 op_sel_hi:[1,0]
	v_mul_f32_e32 v98, 0x3d372713, v88
	v_mul_f32_e32 v99, 0x3d372713, v89
	v_mul_f32_e32 v98, v88, v98
	v_mul_f32_e32 v99, v89, v99
	v_fma_f32 v98, v88, v98, v88
	v_fma_f32 v99, v89, v99, v89
	v_mul_f32_e32 v98, 0x3f4c422a, v98
	v_mul_f32_e32 v99, 0x3f4c422a, v99
	v_add_f32_e32 v98, v98, v98
	v_add_f32_e32 v99, v99, v99
	v_mul_f32_e32 v98, 0x3fb8aa3b, v98
	v_mul_f32_e32 v99, 0x3fb8aa3b, v99
	v_exp_f32_e32 v98, v98
	v_exp_f32_e32 v99, v99
	v_pk_mul_f32 v[94:95], v[94:95], v[96:97]
	v_pk_mul_f32 v[88:89], v[88:89], 0.5 op_sel_hi:[1,0]
	v_add_f32_e32 v96, 1.0, v98
	v_add_f32_e32 v97, 1.0, v99
	v_lshlrev_b32_e32 v98, 16, v139
	v_and_b32_e32 v99, 0xffff0000, v139
	v_pk_fma_f32 v[90:91], v[46:47], v[98:99], v[90:91]
	v_rcp_f32_e32 v96, v96
	v_mul_f32_e32 v98, 0x3d372713, v90
	v_mul_f32_e32 v99, 0x3d372713, v91
	v_mul_f32_e32 v98, v90, v98
	v_mul_f32_e32 v99, v91, v99
	v_fma_f32 v98, v90, v98, v90
	v_fma_f32 v99, v91, v99, v91
	v_mul_f32_e32 v98, 0x3f4c422a, v98
	v_mul_f32_e32 v99, 0x3f4c422a, v99
	v_add_f32_e32 v98, v98, v98
	v_add_f32_e32 v99, v99, v99
	v_mul_f32_e32 v98, 0x3fb8aa3b, v98
	v_mul_f32_e32 v99, 0x3fb8aa3b, v99
	v_exp_f32_e32 v98, v98
	v_exp_f32_e32 v99, v99
	v_rcp_f32_e32 v97, v97
	v_pk_mul_f32 v[90:91], v[90:91], 0.5 op_sel_hi:[1,0]
	v_add_f32_e32 v98, 1.0, v98
	v_add_f32_e32 v99, 1.0, v99
	v_rcp_f32_e32 v98, v98
	v_rcp_f32_e32 v99, v99
	v_pk_fma_f32 v[96:97], v[96:97], 2.0, 1.0 op_sel_hi:[1,0,0] neg_lo:[1,0,0] neg_hi:[1,0,0]
	s_nop 0
	v_pk_add_f32 v[96:97], v[96:97], 1.0 op_sel_hi:[1,0]
	s_nop 0
	v_pk_mul_f32 v[96:97], v[88:89], v[96:97]
	v_pk_fma_f32 v[88:89], v[98:99], 2.0, 1.0 op_sel_hi:[1,0,0] neg_lo:[1,0,0] neg_hi:[1,0,0]
	s_nop 0
	v_pk_add_f32 v[88:89], v[88:89], 1.0 op_sel_hi:[1,0]
	s_nop 0
	v_pk_mul_f32 v[98:99], v[90:91], v[88:89]
	v_cvt_pk_bf16_f32 v88, v92, v93
	v_or_b32_e32 v92, v108, v132
	v_lshlrev_b32_e32 v92, 10, v92
	v_mov_b32_e32 v93, v173
	v_lshl_add_u64 v[92:93], s[8:9], 0, v[92:93]
	v_lshl_add_u64 v[92:93], v[92:93], 0, s[22:23]
	v_cvt_pk_bf16_f32 v89, v94, v95
	v_cvt_pk_bf16_f32 v90, v96, v97
	v_cvt_pk_bf16_f32 v91, v98, v99
	v_lshl_add_u64 v[92:93], v[92:93], 0, v[182:183]
	global_store_dwordx4 v[92:93], v[88:91], off
	v_or_b32_e32 v92, 0x600, v209
	s_nop 0
	v_lshlrev_b32_e32 v88, 16, v124
	v_and_b32_e32 v89, 0xffff0000, v124
	v_pk_fma_f32 v[84:85], v[52:53], v[88:89], v[84:85]
	v_lshlrev_b32_e32 v90, 16, v125
	v_mul_f32_e32 v88, 0x3d372713, v84
	v_mul_f32_e32 v89, 0x3d372713, v85
	v_and_b32_e32 v91, 0xffff0000, v125
	v_mul_f32_e32 v88, v84, v88
	v_mul_f32_e32 v89, v85, v89
	v_pk_fma_f32 v[86:87], v[54:55], v[90:91], v[86:87]
	v_fma_f32 v88, v84, v88, v84
	v_fma_f32 v89, v85, v89, v85
	v_mul_f32_e32 v90, 0x3d372713, v86
	v_mul_f32_e32 v91, 0x3d372713, v87
	v_mul_f32_e32 v88, 0x3f4c422a, v88
	v_mul_f32_e32 v89, 0x3f4c422a, v89
	v_mul_f32_e32 v90, v86, v90
	v_mul_f32_e32 v91, v87, v91
	v_add_f32_e32 v88, v88, v88
	v_add_f32_e32 v89, v89, v89
	v_fma_f32 v90, v86, v90, v86
	v_fma_f32 v91, v87, v91, v87
	v_mul_f32_e32 v88, 0x3fb8aa3b, v88
	v_mul_f32_e32 v89, 0x3fb8aa3b, v89
	v_mul_f32_e32 v90, 0x3f4c422a, v90
	v_mul_f32_e32 v91, 0x3f4c422a, v91
	v_exp_f32_e32 v88, v88
	v_exp_f32_e32 v89, v89
	v_add_f32_e32 v90, v90, v90
	v_add_f32_e32 v91, v91, v91
	v_mul_f32_e32 v90, 0x3fb8aa3b, v90
	v_mul_f32_e32 v91, 0x3fb8aa3b, v91
	v_exp_f32_e32 v90, v90
	v_exp_f32_e32 v91, v91
	v_add_f32_e32 v88, 1.0, v88
	v_add_f32_e32 v89, 1.0, v89
	v_rcp_f32_e32 v88, v88
	v_rcp_f32_e32 v89, v89
	v_add_f32_e32 v90, 1.0, v90
	v_add_f32_e32 v91, 1.0, v91
	v_rcp_f32_e32 v90, v90
	v_rcp_f32_e32 v91, v91
	v_pk_fma_f32 v[88:89], v[88:89], 2.0, 1.0 op_sel_hi:[1,0,0] neg_lo:[1,0,0] neg_hi:[1,0,0]
	v_pk_mul_f32 v[84:85], v[84:85], 0.5 op_sel_hi:[1,0]
	v_pk_add_f32 v[88:89], v[88:89], 1.0 op_sel_hi:[1,0]
	v_pk_mul_f32 v[86:87], v[86:87], 0.5 op_sel_hi:[1,0]
	v_pk_mul_f32 v[84:85], v[84:85], v[88:89]
	v_pk_fma_f32 v[88:89], v[90:91], 2.0, 1.0 op_sel_hi:[1,0,0] neg_lo:[1,0,0] neg_hi:[1,0,0]
	v_lshlrev_b32_e32 v90, 16, v126
	v_and_b32_e32 v91, 0xffff0000, v126
	v_pk_fma_f32 v[80:81], v[44:45], v[90:91], v[80:81]
	v_pk_add_f32 v[88:89], v[88:89], 1.0 op_sel_hi:[1,0]
	v_mul_f32_e32 v90, 0x3d372713, v80
	v_mul_f32_e32 v91, 0x3d372713, v81
	v_mul_f32_e32 v90, v80, v90
	v_mul_f32_e32 v91, v81, v91
	v_fma_f32 v90, v80, v90, v80
	v_fma_f32 v91, v81, v91, v81
	v_mul_f32_e32 v90, 0x3f4c422a, v90
	v_mul_f32_e32 v91, 0x3f4c422a, v91
	v_add_f32_e32 v90, v90, v90
	v_add_f32_e32 v91, v91, v91
	v_mul_f32_e32 v90, 0x3fb8aa3b, v90
	v_mul_f32_e32 v91, 0x3fb8aa3b, v91
	v_exp_f32_e32 v90, v90
	v_exp_f32_e32 v91, v91
	v_pk_mul_f32 v[86:87], v[86:87], v[88:89]
	v_pk_mul_f32 v[80:81], v[80:81], 0.5 op_sel_hi:[1,0]
	v_add_f32_e32 v88, 1.0, v90
	v_add_f32_e32 v89, 1.0, v91
	v_lshlrev_b32_e32 v90, 16, v127
	v_and_b32_e32 v91, 0xffff0000, v127
	v_pk_fma_f32 v[82:83], v[46:47], v[90:91], v[82:83]
	v_rcp_f32_e32 v88, v88
	v_mul_f32_e32 v90, 0x3d372713, v82
	v_mul_f32_e32 v91, 0x3d372713, v83
	v_mul_f32_e32 v90, v82, v90
	v_mul_f32_e32 v91, v83, v91
	v_fma_f32 v90, v82, v90, v82
	v_fma_f32 v91, v83, v91, v83
	v_mul_f32_e32 v90, 0x3f4c422a, v90
	v_mul_f32_e32 v91, 0x3f4c422a, v91
	v_add_f32_e32 v90, v90, v90
	v_add_f32_e32 v91, v91, v91
	v_mul_f32_e32 v90, 0x3fb8aa3b, v90
	v_mul_f32_e32 v91, 0x3fb8aa3b, v91
	v_exp_f32_e32 v90, v90
	v_exp_f32_e32 v91, v91
	v_rcp_f32_e32 v89, v89
	v_pk_mul_f32 v[82:83], v[82:83], 0.5 op_sel_hi:[1,0]
	v_add_f32_e32 v90, 1.0, v90
	v_add_f32_e32 v91, 1.0, v91
	v_rcp_f32_e32 v90, v90
	v_rcp_f32_e32 v91, v91
	v_pk_fma_f32 v[88:89], v[88:89], 2.0, 1.0 op_sel_hi:[1,0,0] neg_lo:[1,0,0] neg_hi:[1,0,0]
	s_nop 0
	v_pk_add_f32 v[88:89], v[88:89], 1.0 op_sel_hi:[1,0]
	s_nop 0
	v_pk_mul_f32 v[88:89], v[80:81], v[88:89]
	v_pk_fma_f32 v[80:81], v[90:91], 2.0, 1.0 op_sel_hi:[1,0,0] neg_lo:[1,0,0] neg_hi:[1,0,0]
	s_nop 0
	v_pk_add_f32 v[80:81], v[80:81], 1.0 op_sel_hi:[1,0]
	s_nop 0
	v_pk_mul_f32 v[90:91], v[82:83], v[80:81]
	v_cvt_pk_bf16_f32 v80, v84, v85
	v_or_b32_e32 v84, v92, v144
	v_lshlrev_b32_e32 v84, 10, v84
	v_mov_b32_e32 v85, v173
	v_lshl_add_u64 v[84:85], s[8:9], 0, v[84:85]
	v_cvt_pk_bf16_f32 v81, v86, v87
	v_lshl_add_u64 v[84:85], v[84:85], 0, s[22:23]
	v_lshlrev_b32_e32 v86, 16, v112
	v_and_b32_e32 v87, 0xffff0000, v112
	v_cvt_pk_bf16_f32 v82, v88, v89
	v_cvt_pk_bf16_f32 v83, v90, v91
	v_lshl_add_u64 v[84:85], v[84:85], 0, v[182:183]
	v_pk_fma_f32 v[76:77], v[52:53], v[86:87], v[76:77]
	global_store_dwordx4 v[84:85], v[80:83], off
	v_mul_f32_e32 v86, 0x3d372713, v76
	v_mul_f32_e32 v87, 0x3d372713, v77
	v_lshlrev_b32_e32 v82, 16, v113
	v_and_b32_e32 v83, 0xffff0000, v113
	v_mul_f32_e32 v86, v76, v86
	v_mul_f32_e32 v87, v77, v87
	v_pk_fma_f32 v[78:79], v[54:55], v[82:83], v[78:79]
	v_fma_f32 v86, v76, v86, v76
	v_fma_f32 v87, v77, v87, v77
	v_mul_f32_e32 v82, 0x3d372713, v78
	v_mul_f32_e32 v83, 0x3d372713, v79
	v_mul_f32_e32 v86, 0x3f4c422a, v86
	v_mul_f32_e32 v87, 0x3f4c422a, v87
	v_mul_f32_e32 v82, v78, v82
	v_mul_f32_e32 v83, v79, v83
	v_add_f32_e32 v86, v86, v86
	v_add_f32_e32 v87, v87, v87
	v_fma_f32 v82, v78, v82, v78
	v_fma_f32 v83, v79, v83, v79
	v_mul_f32_e32 v86, 0x3fb8aa3b, v86
	v_mul_f32_e32 v87, 0x3fb8aa3b, v87
	v_mul_f32_e32 v82, 0x3f4c422a, v82
	v_mul_f32_e32 v83, 0x3f4c422a, v83
	v_exp_f32_e32 v86, v86
	v_exp_f32_e32 v87, v87
	v_add_f32_e32 v82, v82, v82
	v_add_f32_e32 v83, v83, v83
	v_mul_f32_e32 v82, 0x3fb8aa3b, v82
	v_mul_f32_e32 v83, 0x3fb8aa3b, v83
	v_exp_f32_e32 v82, v82
	v_exp_f32_e32 v83, v83
	v_add_f32_e32 v80, 1.0, v86
	v_add_f32_e32 v81, 1.0, v87
	v_rcp_f32_e32 v80, v80
	v_rcp_f32_e32 v81, v81
	v_add_f32_e32 v82, 1.0, v82
	v_add_f32_e32 v83, 1.0, v83
	v_rcp_f32_e32 v82, v82
	v_rcp_f32_e32 v83, v83
	v_pk_fma_f32 v[80:81], v[80:81], 2.0, 1.0 op_sel_hi:[1,0,0] neg_lo:[1,0,0] neg_hi:[1,0,0]
	v_pk_mul_f32 v[76:77], v[76:77], 0.5 op_sel_hi:[1,0]
	v_pk_add_f32 v[80:81], v[80:81], 1.0 op_sel_hi:[1,0]
	v_pk_mul_f32 v[78:79], v[78:79], 0.5 op_sel_hi:[1,0]
	v_pk_mul_f32 v[76:77], v[76:77], v[80:81]
	v_pk_fma_f32 v[80:81], v[82:83], 2.0, 1.0 op_sel_hi:[1,0,0] neg_lo:[1,0,0] neg_hi:[1,0,0]
	v_lshlrev_b32_e32 v82, 16, v114
	v_and_b32_e32 v83, 0xffff0000, v114
	v_pk_fma_f32 v[72:73], v[44:45], v[82:83], v[72:73]
	v_pk_add_f32 v[80:81], v[80:81], 1.0 op_sel_hi:[1,0]
	v_mul_f32_e32 v82, 0x3d372713, v72
	v_mul_f32_e32 v83, 0x3d372713, v73
	v_mul_f32_e32 v82, v72, v82
	v_mul_f32_e32 v83, v73, v83
	v_fma_f32 v82, v72, v82, v72
	v_fma_f32 v83, v73, v83, v73
	v_mul_f32_e32 v82, 0x3f4c422a, v82
	v_mul_f32_e32 v83, 0x3f4c422a, v83
	v_add_f32_e32 v82, v82, v82
	v_add_f32_e32 v83, v83, v83
	v_mul_f32_e32 v82, 0x3fb8aa3b, v82
	v_mul_f32_e32 v83, 0x3fb8aa3b, v83
	v_exp_f32_e32 v82, v82
	v_exp_f32_e32 v83, v83
	v_pk_mul_f32 v[78:79], v[78:79], v[80:81]
	v_pk_mul_f32 v[72:73], v[72:73], 0.5 op_sel_hi:[1,0]
	v_add_f32_e32 v80, 1.0, v82
	v_add_f32_e32 v81, 1.0, v83
	v_lshlrev_b32_e32 v82, 16, v115
	v_and_b32_e32 v83, 0xffff0000, v115
	v_pk_fma_f32 v[74:75], v[46:47], v[82:83], v[74:75]
	v_rcp_f32_e32 v80, v80
	v_mul_f32_e32 v82, 0x3d372713, v74
	v_mul_f32_e32 v83, 0x3d372713, v75
	v_mul_f32_e32 v82, v74, v82
	v_mul_f32_e32 v83, v75, v83
	v_fma_f32 v82, v74, v82, v74
	v_fma_f32 v83, v75, v83, v75
	v_mul_f32_e32 v82, 0x3f4c422a, v82
	v_mul_f32_e32 v83, 0x3f4c422a, v83
	v_add_f32_e32 v82, v82, v82
	v_add_f32_e32 v83, v83, v83
	v_mul_f32_e32 v82, 0x3fb8aa3b, v82
	v_mul_f32_e32 v83, 0x3fb8aa3b, v83
	v_exp_f32_e32 v82, v82
	v_exp_f32_e32 v83, v83
	v_rcp_f32_e32 v81, v81
	v_pk_mul_f32 v[74:75], v[74:75], 0.5 op_sel_hi:[1,0]
	v_add_f32_e32 v82, 1.0, v82
	v_add_f32_e32 v83, 1.0, v83
	v_rcp_f32_e32 v82, v82
	v_rcp_f32_e32 v83, v83
	v_pk_fma_f32 v[80:81], v[80:81], 2.0, 1.0 op_sel_hi:[1,0,0] neg_lo:[1,0,0] neg_hi:[1,0,0]
	s_nop 0
	v_pk_add_f32 v[80:81], v[80:81], 1.0 op_sel_hi:[1,0]
	s_nop 0
	v_pk_mul_f32 v[80:81], v[72:73], v[80:81]
	v_pk_fma_f32 v[72:73], v[82:83], 2.0, 1.0 op_sel_hi:[1,0,0] neg_lo:[1,0,0] neg_hi:[1,0,0]
	s_nop 0
	v_pk_add_f32 v[72:73], v[72:73], 1.0 op_sel_hi:[1,0]
	s_nop 0
	v_pk_mul_f32 v[82:83], v[74:75], v[72:73]
	v_cvt_pk_bf16_f32 v72, v76, v77
	v_or_b32_e32 v76, v92, v132
	v_lshlrev_b32_e32 v76, 10, v76
	v_mov_b32_e32 v77, v173
	v_lshl_add_u64 v[76:77], s[8:9], 0, v[76:77]
	v_lshl_add_u64 v[76:77], v[76:77], 0, s[22:23]
	v_cvt_pk_bf16_f32 v73, v78, v79
	v_cvt_pk_bf16_f32 v74, v80, v81
	v_cvt_pk_bf16_f32 v75, v82, v83
	v_lshl_add_u64 v[76:77], v[76:77], 0, v[182:183]
	global_store_dwordx4 v[76:77], v[72:75], off
	s_nop 1
	v_add_u32_e32 v72, 0x80, v207
	v_mad_i64_i32 v[72:73], s[26:27], v72, s42, v[176:177]
	v_lshl_add_u64 v[72:73], v[72:73], 0, v[172:173]
	global_load_dwordx4 v[100:103], v[72:73], off
	global_load_dwordx4 v[96:99], v[72:73], off offset:256
	v_add_u32_e32 v72, 0x90, v207
	v_mad_i64_i32 v[72:73], s[26:27], v72, s42, v[176:177]
	v_lshl_add_u64 v[72:73], v[72:73], 0, v[172:173]
	global_load_dwordx4 v[92:95], v[72:73], off
	global_load_dwordx4 v[88:91], v[72:73], off offset:256
	v_add_u32_e32 v72, 0xa0, v207
	v_mad_i64_i32 v[72:73], s[26:27], v72, s42, v[176:177]
	v_lshl_add_u64 v[72:73], v[72:73], 0, v[172:173]
	global_load_dwordx4 v[84:87], v[72:73], off
	global_load_dwordx4 v[80:83], v[72:73], off offset:256
	v_add_u32_e32 v72, 0xb0, v207
	v_mad_i64_i32 v[72:73], s[26:27], v72, s42, v[176:177]
	v_lshl_add_u64 v[72:73], v[72:73], 0, v[172:173]
	global_load_dwordx4 v[76:79], v[72:73], off
	s_nop 0
	global_load_dwordx4 v[72:75], v[72:73], off offset:256
	s_waitcnt vmcnt(7)
	v_lshlrev_b32_e32 v104, 16, v100
	v_and_b32_e32 v105, 0xffff0000, v100
	v_pk_fma_f32 v[104:105], v[52:53], v[104:105], v[68:69]
	s_addk_i32 s24, 0x1000
	v_mul_f32_e32 v68, 0x3d372713, v104
	v_mul_f32_e32 v68, v104, v68
	v_fma_f32 v68, v104, v68, v104
	v_mul_f32_e32 v68, 0x3f4c422a, v68
	v_add_f32_e32 v68, v68, v68
	v_mul_f32_e32 v68, 0x3fb8aa3b, v68
	v_exp_f32_e32 v69, v68
	v_mul_f32_e32 v68, 0x3d372713, v105
	v_mul_f32_e32 v68, v105, v68
	v_fma_f32 v68, v105, v68, v105
	v_mul_f32_e32 v68, 0x3f4c422a, v68
	v_add_f32_e32 v68, v68, v68
	v_mul_f32_e32 v68, 0x3fb8aa3b, v68
	v_exp_f32_e32 v100, v68
	v_add_f32_e32 v69, 1.0, v69
	v_rcp_f32_e32 v106, v69
	v_pk_mul_f32 v[104:105], v[104:105], 0.5 op_sel_hi:[1,0]
	v_add_f32_e32 v69, 1.0, v100
	v_lshlrev_b32_e32 v100, 16, v101
	v_and_b32_e32 v101, 0xffff0000, v101
	v_pk_fma_f32 v[70:71], v[54:55], v[100:101], v[70:71]
	v_rcp_f32_e32 v107, v69
	v_mul_f32_e32 v69, 0x3d372713, v70
	v_mul_f32_e32 v69, v70, v69
	v_mul_f32_e32 v100, 0x3d372713, v71
	v_fma_f32 v69, v70, v69, v70
	v_mul_f32_e32 v100, v71, v100
	v_mul_f32_e32 v69, 0x3f4c422a, v69
	v_fma_f32 v100, v71, v100, v71
	v_add_f32_e32 v69, v69, v69
	v_mul_f32_e32 v100, 0x3f4c422a, v100
	v_mul_f32_e32 v69, 0x3fb8aa3b, v69
	v_add_f32_e32 v100, v100, v100
	v_exp_f32_e32 v69, v69
	v_mul_f32_e32 v100, 0x3fb8aa3b, v100
	v_exp_f32_e32 v108, v100
	v_pk_fma_f32 v[100:101], v[106:107], 2.0, 1.0 op_sel_hi:[1,0,0] neg_lo:[1,0,0] neg_hi:[1,0,0]
	v_add_f32_e32 v69, 1.0, v69
	v_rcp_f32_e32 v106, v69
	v_add_f32_e32 v69, 1.0, v108
	v_rcp_f32_e32 v107, v69
	v_pk_add_f32 v[100:101], v[100:101], 1.0 op_sel_hi:[1,0]
	v_pk_mul_f32 v[70:71], v[70:71], 0.5 op_sel_hi:[1,0]
	v_pk_mul_f32 v[100:101], v[104:105], v[100:101]
	v_pk_fma_f32 v[104:105], v[106:107], 2.0, 1.0 op_sel_hi:[1,0,0] neg_lo:[1,0,0] neg_hi:[1,0,0]
	v_lshlrev_b32_e32 v106, 16, v102
	v_and_b32_e32 v107, 0xffff0000, v102
	v_pk_fma_f32 v[64:65], v[44:45], v[106:107], v[64:65]
	v_pk_add_f32 v[104:105], v[104:105], 1.0 op_sel_hi:[1,0]
	v_mul_f32_e32 v69, 0x3d372713, v64
	v_mul_f32_e32 v69, v64, v69
	v_mul_f32_e32 v102, 0x3d372713, v65
	v_fma_f32 v69, v64, v69, v64
	v_mul_f32_e32 v102, v65, v102
	v_mul_f32_e32 v69, 0x3f4c422a, v69
	v_fma_f32 v102, v65, v102, v65
	v_add_f32_e32 v69, v69, v69
	v_mul_f32_e32 v102, 0x3f4c422a, v102
	v_mul_f32_e32 v69, 0x3fb8aa3b, v69
	v_add_f32_e32 v102, v102, v102
	v_exp_f32_e32 v69, v69
	v_mul_f32_e32 v102, 0x3fb8aa3b, v102
	v_exp_f32_e32 v102, v102
	v_pk_mul_f32 v[70:71], v[70:71], v[104:105]
	v_add_f32_e32 v69, 1.0, v69
	v_rcp_f32_e32 v104, v69
	v_add_f32_e32 v69, 1.0, v102
	v_lshlrev_b32_e32 v102, 16, v103
	v_and_b32_e32 v103, 0xffff0000, v103
	v_pk_fma_f32 v[66:67], v[46:47], v[102:103], v[66:67]
	v_rcp_f32_e32 v105, v69
	v_mul_f32_e32 v69, 0x3d372713, v66
	v_mul_f32_e32 v69, v66, v69
	v_mul_f32_e32 v102, 0x3d372713, v67
	v_fma_f32 v69, v66, v69, v66
	v_mul_f32_e32 v102, v67, v102
	v_mul_f32_e32 v69, 0x3f4c422a, v69
	v_fma_f32 v102, v67, v102, v67
	v_add_f32_e32 v69, v69, v69
	v_mul_f32_e32 v102, 0x3f4c422a, v102
	v_mul_f32_e32 v69, 0x3fb8aa3b, v69
	v_add_f32_e32 v102, v102, v102
	v_exp_f32_e32 v69, v69
	v_mul_f32_e32 v102, 0x3fb8aa3b, v102
	v_exp_f32_e32 v106, v102
	v_pk_fma_f32 v[102:103], v[104:105], 2.0, 1.0 op_sel_hi:[1,0,0] neg_lo:[1,0,0] neg_hi:[1,0,0]
	v_add_f32_e32 v69, 1.0, v69
	v_rcp_f32_e32 v104, v69
	v_add_f32_e32 v69, 1.0, v106
	v_rcp_f32_e32 v105, v69
	s_and_b32 s24, s24, 0x3000
	v_or_b32_e32 v68, s24, v208
	v_pk_mul_f32 v[64:65], v[64:65], 0.5 op_sel_hi:[1,0]
	v_pk_add_f32 v[102:103], v[102:103], 1.0 op_sel_hi:[1,0]
	v_or_b32_e32 v69, v68, v144
	v_pk_mul_f32 v[102:103], v[64:65], v[102:103]
	v_pk_fma_f32 v[64:65], v[104:105], 2.0, 1.0 op_sel_hi:[1,0,0] neg_lo:[1,0,0] neg_hi:[1,0,0]
	v_pk_mul_f32 v[66:67], v[66:67], 0.5 op_sel_hi:[1,0]
	v_pk_add_f32 v[64:65], v[64:65], 1.0 op_sel_hi:[1,0]
	v_lshlrev_b32_e32 v172, 10, v69
	v_pk_mul_f32 v[104:105], v[66:67], v[64:65]
	v_cvt_pk_bf16_f32 v65, v70, v71
	v_lshl_add_u64 v[70:71], s[8:9], 0, v[172:173]
	v_cvt_pk_bf16_f32 v64, v100, v101
	v_lshl_add_u64 v[70:71], v[70:71], 0, s[22:23]
	s_waitcnt vmcnt(6)
	v_lshlrev_b32_e32 v100, 16, v96
	v_and_b32_e32 v101, 0xffff0000, v96
	v_cvt_pk_bf16_f32 v66, v102, v103
	v_cvt_pk_bf16_f32 v67, v104, v105
	v_lshl_add_u64 v[70:71], v[70:71], 0, v[182:183]
	v_pk_fma_f32 v[60:61], v[52:53], v[100:101], v[60:61]
	global_store_dwordx4 v[70:71], v[64:67], off
	v_mul_f32_e32 v69, 0x3d372713, v60
	v_mul_f32_e32 v96, 0x3d372713, v61
	v_lshlrev_b32_e32 v66, 16, v97
	v_and_b32_e32 v67, 0xffff0000, v97
	v_mul_f32_e32 v69, v60, v69
	v_mul_f32_e32 v96, v61, v96
	v_pk_fma_f32 v[62:63], v[54:55], v[66:67], v[62:63]
	v_fma_f32 v69, v60, v69, v60
	v_fma_f32 v96, v61, v96, v61
	v_mul_f32_e32 v66, 0x3d372713, v62
	v_mul_f32_e32 v67, 0x3d372713, v63
	v_mul_f32_e32 v69, 0x3f4c422a, v69
	v_mul_f32_e32 v96, 0x3f4c422a, v96
	v_mul_f32_e32 v66, v62, v66
	v_mul_f32_e32 v67, v63, v67
	v_add_f32_e32 v69, v69, v69
	v_add_f32_e32 v96, v96, v96
	v_fma_f32 v66, v62, v66, v62
	v_fma_f32 v67, v63, v67, v63
	v_mul_f32_e32 v69, 0x3fb8aa3b, v69
	v_mul_f32_e32 v96, 0x3fb8aa3b, v96
	v_mul_f32_e32 v66, 0x3f4c422a, v66
	v_mul_f32_e32 v67, 0x3f4c422a, v67
	v_exp_f32_e32 v69, v69
	v_exp_f32_e32 v96, v96
	v_add_f32_e32 v66, v66, v66
	v_add_f32_e32 v67, v67, v67
	v_mul_f32_e32 v66, 0x3fb8aa3b, v66
	v_mul_f32_e32 v67, 0x3fb8aa3b, v67
	v_exp_f32_e32 v66, v66
	v_exp_f32_e32 v67, v67
	v_add_f32_e32 v64, 1.0, v69
	v_add_f32_e32 v65, 1.0, v96
	v_rcp_f32_e32 v64, v64
	v_rcp_f32_e32 v65, v65
	v_add_f32_e32 v66, 1.0, v66
	v_add_f32_e32 v67, 1.0, v67
	v_rcp_f32_e32 v66, v66
	v_rcp_f32_e32 v67, v67
	v_pk_fma_f32 v[64:65], v[64:65], 2.0, 1.0 op_sel_hi:[1,0,0] neg_lo:[1,0,0] neg_hi:[1,0,0]
	v_pk_mul_f32 v[60:61], v[60:61], 0.5 op_sel_hi:[1,0]
	v_pk_add_f32 v[64:65], v[64:65], 1.0 op_sel_hi:[1,0]
	v_pk_mul_f32 v[62:63], v[62:63], 0.5 op_sel_hi:[1,0]
	v_pk_mul_f32 v[60:61], v[60:61], v[64:65]
	v_pk_fma_f32 v[64:65], v[66:67], 2.0, 1.0 op_sel_hi:[1,0,0] neg_lo:[1,0,0] neg_hi:[1,0,0]
	v_lshlrev_b32_e32 v66, 16, v98
	v_and_b32_e32 v67, 0xffff0000, v98
	v_pk_fma_f32 v[56:57], v[44:45], v[66:67], v[56:57]
	v_pk_add_f32 v[64:65], v[64:65], 1.0 op_sel_hi:[1,0]
	v_mul_f32_e32 v66, 0x3d372713, v56
	v_mul_f32_e32 v67, 0x3d372713, v57
	v_mul_f32_e32 v66, v56, v66
	v_mul_f32_e32 v67, v57, v67
	v_fma_f32 v66, v56, v66, v56
	v_fma_f32 v67, v57, v67, v57
	v_mul_f32_e32 v66, 0x3f4c422a, v66
	v_mul_f32_e32 v67, 0x3f4c422a, v67
	v_add_f32_e32 v66, v66, v66
	v_add_f32_e32 v67, v67, v67
	v_mul_f32_e32 v66, 0x3fb8aa3b, v66
	v_mul_f32_e32 v67, 0x3fb8aa3b, v67
	v_exp_f32_e32 v66, v66
	v_exp_f32_e32 v67, v67
	v_pk_mul_f32 v[62:63], v[62:63], v[64:65]
	v_pk_mul_f32 v[56:57], v[56:57], 0.5 op_sel_hi:[1,0]
	v_add_f32_e32 v64, 1.0, v66
	v_add_f32_e32 v65, 1.0, v67
	v_lshlrev_b32_e32 v66, 16, v99
	v_and_b32_e32 v67, 0xffff0000, v99
	v_pk_fma_f32 v[58:59], v[46:47], v[66:67], v[58:59]
	v_rcp_f32_e32 v64, v64
	v_mul_f32_e32 v66, 0x3d372713, v58
	v_mul_f32_e32 v67, 0x3d372713, v59
	v_mul_f32_e32 v66, v58, v66
	v_mul_f32_e32 v67, v59, v67
	v_fma_f32 v66, v58, v66, v58
	v_fma_f32 v67, v59, v67, v59
	v_mul_f32_e32 v66, 0x3f4c422a, v66
	v_mul_f32_e32 v67, 0x3f4c422a, v67
	v_add_f32_e32 v66, v66, v66
	v_add_f32_e32 v67, v67, v67
	v_mul_f32_e32 v66, 0x3fb8aa3b, v66
	v_mul_f32_e32 v67, 0x3fb8aa3b, v67
	v_exp_f32_e32 v66, v66
	v_exp_f32_e32 v67, v67
	v_rcp_f32_e32 v65, v65
	v_pk_mul_f32 v[58:59], v[58:59], 0.5 op_sel_hi:[1,0]
	v_add_f32_e32 v66, 1.0, v66
	v_add_f32_e32 v67, 1.0, v67
	v_rcp_f32_e32 v66, v66
	v_rcp_f32_e32 v67, v67
	v_pk_fma_f32 v[64:65], v[64:65], 2.0, 1.0 op_sel_hi:[1,0,0] neg_lo:[1,0,0] neg_hi:[1,0,0]
	s_nop 0
	v_pk_add_f32 v[64:65], v[64:65], 1.0 op_sel_hi:[1,0]
	s_nop 0
	v_pk_mul_f32 v[64:65], v[56:57], v[64:65]
	v_pk_fma_f32 v[56:57], v[66:67], 2.0, 1.0 op_sel_hi:[1,0,0] neg_lo:[1,0,0] neg_hi:[1,0,0]
	s_nop 0
	v_pk_add_f32 v[56:57], v[56:57], 1.0 op_sel_hi:[1,0]
	s_nop 0
	v_pk_mul_f32 v[66:67], v[58:59], v[56:57]
	v_cvt_pk_bf16_f32 v56, v60, v61
	v_or_b32_e32 v60, v68, v132
	v_lshlrev_b32_e32 v172, 10, v60
	v_lshl_add_u64 v[60:61], s[8:9], 0, v[172:173]
	v_lshl_add_u64 v[60:61], v[60:61], 0, s[22:23]
	v_cvt_pk_bf16_f32 v57, v62, v63
	v_cvt_pk_bf16_f32 v58, v64, v65
	v_cvt_pk_bf16_f32 v59, v66, v67
	v_lshl_add_u64 v[60:61], v[60:61], 0, v[182:183]
	global_store_dwordx4 v[60:61], v[56:59], off
	v_or_b32_e32 v60, 0x200, v68
	s_waitcnt vmcnt(7)
	v_lshlrev_b32_e32 v56, 16, v92
	v_and_b32_e32 v57, 0xffff0000, v92
	v_pk_fma_f32 v[48:49], v[52:53], v[56:57], v[48:49]
	v_lshlrev_b32_e32 v58, 16, v93
	v_mul_f32_e32 v56, 0x3d372713, v48
	v_mul_f32_e32 v57, 0x3d372713, v49
	v_and_b32_e32 v59, 0xffff0000, v93
	v_mul_f32_e32 v56, v48, v56
	v_mul_f32_e32 v57, v49, v57
	v_pk_fma_f32 v[50:51], v[54:55], v[58:59], v[50:51]
	v_fma_f32 v56, v48, v56, v48
	v_fma_f32 v57, v49, v57, v49
	v_mul_f32_e32 v58, 0x3d372713, v50
	v_mul_f32_e32 v59, 0x3d372713, v51
	v_mul_f32_e32 v56, 0x3f4c422a, v56
	v_mul_f32_e32 v57, 0x3f4c422a, v57
	v_mul_f32_e32 v58, v50, v58
	v_mul_f32_e32 v59, v51, v59
	v_add_f32_e32 v56, v56, v56
	v_add_f32_e32 v57, v57, v57
	v_fma_f32 v58, v50, v58, v50
	v_fma_f32 v59, v51, v59, v51
	v_mul_f32_e32 v56, 0x3fb8aa3b, v56
	v_mul_f32_e32 v57, 0x3fb8aa3b, v57
	v_mul_f32_e32 v58, 0x3f4c422a, v58
	v_mul_f32_e32 v59, 0x3f4c422a, v59
	v_exp_f32_e32 v56, v56
	v_exp_f32_e32 v57, v57
	v_add_f32_e32 v58, v58, v58
	v_add_f32_e32 v59, v59, v59
	v_mul_f32_e32 v58, 0x3fb8aa3b, v58
	v_mul_f32_e32 v59, 0x3fb8aa3b, v59
	v_exp_f32_e32 v58, v58
	v_exp_f32_e32 v59, v59
	v_add_f32_e32 v56, 1.0, v56
	v_add_f32_e32 v57, 1.0, v57
	v_rcp_f32_e32 v56, v56
	v_rcp_f32_e32 v57, v57
	v_add_f32_e32 v58, 1.0, v58
	v_add_f32_e32 v59, 1.0, v59
	v_rcp_f32_e32 v58, v58
	v_rcp_f32_e32 v59, v59
	v_pk_fma_f32 v[56:57], v[56:57], 2.0, 1.0 op_sel_hi:[1,0,0] neg_lo:[1,0,0] neg_hi:[1,0,0]
	v_pk_mul_f32 v[48:49], v[48:49], 0.5 op_sel_hi:[1,0]
	v_pk_add_f32 v[56:57], v[56:57], 1.0 op_sel_hi:[1,0]
	v_pk_mul_f32 v[50:51], v[50:51], 0.5 op_sel_hi:[1,0]
	v_pk_mul_f32 v[48:49], v[48:49], v[56:57]
	v_pk_fma_f32 v[56:57], v[58:59], 2.0, 1.0 op_sel_hi:[1,0,0] neg_lo:[1,0,0] neg_hi:[1,0,0]
	v_lshlrev_b32_e32 v58, 16, v94
	v_and_b32_e32 v59, 0xffff0000, v94
	v_pk_fma_f32 v[40:41], v[44:45], v[58:59], v[40:41]
	v_pk_add_f32 v[56:57], v[56:57], 1.0 op_sel_hi:[1,0]
	v_mul_f32_e32 v58, 0x3d372713, v40
	v_mul_f32_e32 v59, 0x3d372713, v41
	v_mul_f32_e32 v58, v40, v58
	v_mul_f32_e32 v59, v41, v59
	v_fma_f32 v58, v40, v58, v40
	v_fma_f32 v59, v41, v59, v41
	v_mul_f32_e32 v58, 0x3f4c422a, v58
	v_mul_f32_e32 v59, 0x3f4c422a, v59
	v_add_f32_e32 v58, v58, v58
	v_add_f32_e32 v59, v59, v59
	v_mul_f32_e32 v58, 0x3fb8aa3b, v58
	v_mul_f32_e32 v59, 0x3fb8aa3b, v59
	v_exp_f32_e32 v58, v58
	v_exp_f32_e32 v59, v59
	v_pk_mul_f32 v[50:51], v[50:51], v[56:57]
	v_pk_mul_f32 v[40:41], v[40:41], 0.5 op_sel_hi:[1,0]
	v_add_f32_e32 v56, 1.0, v58
	v_add_f32_e32 v57, 1.0, v59
	v_lshlrev_b32_e32 v58, 16, v95
	v_and_b32_e32 v59, 0xffff0000, v95
	v_pk_fma_f32 v[42:43], v[46:47], v[58:59], v[42:43]
	v_rcp_f32_e32 v56, v56
	v_mul_f32_e32 v58, 0x3d372713, v42
	v_mul_f32_e32 v59, 0x3d372713, v43
	v_mul_f32_e32 v58, v42, v58
	v_mul_f32_e32 v59, v43, v59
	v_fma_f32 v58, v42, v58, v42
	v_fma_f32 v59, v43, v59, v43
	v_mul_f32_e32 v58, 0x3f4c422a, v58
	v_mul_f32_e32 v59, 0x3f4c422a, v59
	v_add_f32_e32 v58, v58, v58
	v_add_f32_e32 v59, v59, v59
	v_mul_f32_e32 v58, 0x3fb8aa3b, v58
	v_mul_f32_e32 v59, 0x3fb8aa3b, v59
	v_exp_f32_e32 v58, v58
	v_exp_f32_e32 v59, v59
	v_rcp_f32_e32 v57, v57
	v_pk_mul_f32 v[42:43], v[42:43], 0.5 op_sel_hi:[1,0]
	v_add_f32_e32 v58, 1.0, v58
	v_add_f32_e32 v59, 1.0, v59
	v_rcp_f32_e32 v58, v58
	v_rcp_f32_e32 v59, v59
	v_pk_fma_f32 v[56:57], v[56:57], 2.0, 1.0 op_sel_hi:[1,0,0] neg_lo:[1,0,0] neg_hi:[1,0,0]
	s_nop 0
	v_pk_add_f32 v[56:57], v[56:57], 1.0 op_sel_hi:[1,0]
	s_nop 0
	v_pk_mul_f32 v[56:57], v[40:41], v[56:57]
	v_pk_fma_f32 v[40:41], v[58:59], 2.0, 1.0 op_sel_hi:[1,0,0] neg_lo:[1,0,0] neg_hi:[1,0,0]
	s_nop 0
	v_pk_add_f32 v[40:41], v[40:41], 1.0 op_sel_hi:[1,0]
	s_nop 0
	v_pk_mul_f32 v[58:59], v[42:43], v[40:41]
	v_cvt_pk_bf16_f32 v40, v48, v49
	v_or_b32_e32 v48, v60, v144
	v_lshlrev_b32_e32 v172, 10, v48
	v_lshl_add_u64 v[48:49], s[8:9], 0, v[172:173]
	v_cvt_pk_bf16_f32 v41, v50, v51
	v_lshl_add_u64 v[48:49], v[48:49], 0, s[22:23]
	s_waitcnt vmcnt(6)
	v_lshlrev_b32_e32 v50, 16, v88
	v_and_b32_e32 v51, 0xffff0000, v88
	v_cvt_pk_bf16_f32 v42, v56, v57
	v_cvt_pk_bf16_f32 v43, v58, v59
	v_lshl_add_u64 v[48:49], v[48:49], 0, v[182:183]
	v_pk_fma_f32 v[36:37], v[52:53], v[50:51], v[36:37]
	global_store_dwordx4 v[48:49], v[40:43], off
	v_mul_f32_e32 v50, 0x3d372713, v36
	v_mul_f32_e32 v51, 0x3d372713, v37
	v_lshlrev_b32_e32 v42, 16, v89
	v_and_b32_e32 v43, 0xffff0000, v89
	v_mul_f32_e32 v50, v36, v50
	v_mul_f32_e32 v51, v37, v51
	v_pk_fma_f32 v[38:39], v[54:55], v[42:43], v[38:39]
	v_fma_f32 v50, v36, v50, v36
	v_fma_f32 v51, v37, v51, v37
	v_mul_f32_e32 v42, 0x3d372713, v38
	v_mul_f32_e32 v43, 0x3d372713, v39
	v_mul_f32_e32 v50, 0x3f4c422a, v50
	v_mul_f32_e32 v51, 0x3f4c422a, v51
	v_mul_f32_e32 v42, v38, v42
	v_mul_f32_e32 v43, v39, v43
	v_add_f32_e32 v50, v50, v50
	v_add_f32_e32 v51, v51, v51
	v_fma_f32 v42, v38, v42, v38
	v_fma_f32 v43, v39, v43, v39
	v_mul_f32_e32 v50, 0x3fb8aa3b, v50
	v_mul_f32_e32 v51, 0x3fb8aa3b, v51
	v_mul_f32_e32 v42, 0x3f4c422a, v42
	v_mul_f32_e32 v43, 0x3f4c422a, v43
	v_exp_f32_e32 v50, v50
	v_exp_f32_e32 v51, v51
	v_add_f32_e32 v42, v42, v42
	v_add_f32_e32 v43, v43, v43
	v_mul_f32_e32 v42, 0x3fb8aa3b, v42
	v_mul_f32_e32 v43, 0x3fb8aa3b, v43
	v_exp_f32_e32 v42, v42
	v_exp_f32_e32 v43, v43
	v_add_f32_e32 v40, 1.0, v50
	v_add_f32_e32 v41, 1.0, v51
	v_rcp_f32_e32 v40, v40
	v_rcp_f32_e32 v41, v41
	v_add_f32_e32 v42, 1.0, v42
	v_add_f32_e32 v43, 1.0, v43
	v_rcp_f32_e32 v42, v42
	v_rcp_f32_e32 v43, v43
	v_pk_fma_f32 v[40:41], v[40:41], 2.0, 1.0 op_sel_hi:[1,0,0] neg_lo:[1,0,0] neg_hi:[1,0,0]
	v_pk_mul_f32 v[36:37], v[36:37], 0.5 op_sel_hi:[1,0]
	v_pk_add_f32 v[40:41], v[40:41], 1.0 op_sel_hi:[1,0]
	v_pk_mul_f32 v[38:39], v[38:39], 0.5 op_sel_hi:[1,0]
	v_pk_mul_f32 v[36:37], v[36:37], v[40:41]
	v_pk_fma_f32 v[40:41], v[42:43], 2.0, 1.0 op_sel_hi:[1,0,0] neg_lo:[1,0,0] neg_hi:[1,0,0]
	v_lshlrev_b32_e32 v42, 16, v90
	v_and_b32_e32 v43, 0xffff0000, v90
	v_pk_fma_f32 v[32:33], v[44:45], v[42:43], v[32:33]
	v_pk_add_f32 v[40:41], v[40:41], 1.0 op_sel_hi:[1,0]
	v_mul_f32_e32 v42, 0x3d372713, v32
	v_mul_f32_e32 v43, 0x3d372713, v33
	v_mul_f32_e32 v42, v32, v42
	v_mul_f32_e32 v43, v33, v43
	v_fma_f32 v42, v32, v42, v32
	v_fma_f32 v43, v33, v43, v33
	v_mul_f32_e32 v42, 0x3f4c422a, v42
	v_mul_f32_e32 v43, 0x3f4c422a, v43
	v_add_f32_e32 v42, v42, v42
	v_add_f32_e32 v43, v43, v43
	v_mul_f32_e32 v42, 0x3fb8aa3b, v42
	v_mul_f32_e32 v43, 0x3fb8aa3b, v43
	v_exp_f32_e32 v42, v42
	v_exp_f32_e32 v43, v43
	v_pk_mul_f32 v[38:39], v[38:39], v[40:41]
	v_pk_mul_f32 v[32:33], v[32:33], 0.5 op_sel_hi:[1,0]
	v_add_f32_e32 v40, 1.0, v42
	v_add_f32_e32 v41, 1.0, v43
	v_lshlrev_b32_e32 v42, 16, v91
	v_and_b32_e32 v43, 0xffff0000, v91
	v_pk_fma_f32 v[34:35], v[46:47], v[42:43], v[34:35]
	v_rcp_f32_e32 v40, v40
	v_mul_f32_e32 v42, 0x3d372713, v34
	v_mul_f32_e32 v43, 0x3d372713, v35
	v_mul_f32_e32 v42, v34, v42
	v_mul_f32_e32 v43, v35, v43
	v_fma_f32 v42, v34, v42, v34
	v_fma_f32 v43, v35, v43, v35
	v_mul_f32_e32 v42, 0x3f4c422a, v42
	v_mul_f32_e32 v43, 0x3f4c422a, v43
	v_add_f32_e32 v42, v42, v42
	v_add_f32_e32 v43, v43, v43
	v_mul_f32_e32 v42, 0x3fb8aa3b, v42
	v_mul_f32_e32 v43, 0x3fb8aa3b, v43
	v_exp_f32_e32 v42, v42
	v_exp_f32_e32 v43, v43
	v_rcp_f32_e32 v41, v41
	v_pk_mul_f32 v[34:35], v[34:35], 0.5 op_sel_hi:[1,0]
	v_add_f32_e32 v42, 1.0, v42
	v_add_f32_e32 v43, 1.0, v43
	v_rcp_f32_e32 v42, v42
	v_rcp_f32_e32 v43, v43
	v_pk_fma_f32 v[40:41], v[40:41], 2.0, 1.0 op_sel_hi:[1,0,0] neg_lo:[1,0,0] neg_hi:[1,0,0]
	s_nop 0
	v_pk_add_f32 v[40:41], v[40:41], 1.0 op_sel_hi:[1,0]
	s_nop 0
	v_pk_mul_f32 v[40:41], v[32:33], v[40:41]
	v_pk_fma_f32 v[32:33], v[42:43], 2.0, 1.0 op_sel_hi:[1,0,0] neg_lo:[1,0,0] neg_hi:[1,0,0]
	s_nop 0
	v_pk_add_f32 v[32:33], v[32:33], 1.0 op_sel_hi:[1,0]
	s_nop 0
	v_pk_mul_f32 v[42:43], v[34:35], v[32:33]
	v_cvt_pk_bf16_f32 v32, v36, v37
	v_or_b32_e32 v36, v60, v132
	v_lshlrev_b32_e32 v172, 10, v36
	v_lshl_add_u64 v[36:37], s[8:9], 0, v[172:173]
	v_lshl_add_u64 v[36:37], v[36:37], 0, s[22:23]
	v_cvt_pk_bf16_f32 v33, v38, v39
	v_cvt_pk_bf16_f32 v34, v40, v41
	v_cvt_pk_bf16_f32 v35, v42, v43
	v_lshl_add_u64 v[36:37], v[36:37], 0, v[182:183]
	global_store_dwordx4 v[36:37], v[32:35], off
	v_or_b32_e32 v36, 0x400, v68
	s_waitcnt vmcnt(7)
	v_lshlrev_b32_e32 v32, 16, v84
	v_and_b32_e32 v33, 0xffff0000, v84
	v_pk_fma_f32 v[28:29], v[52:53], v[32:33], v[28:29]
	v_lshlrev_b32_e32 v34, 16, v85
	v_mul_f32_e32 v32, 0x3d372713, v28
	v_mul_f32_e32 v33, 0x3d372713, v29
	v_and_b32_e32 v35, 0xffff0000, v85
	v_mul_f32_e32 v32, v28, v32
	v_mul_f32_e32 v33, v29, v33
	v_pk_fma_f32 v[30:31], v[54:55], v[34:35], v[30:31]
	v_fma_f32 v32, v28, v32, v28
	v_fma_f32 v33, v29, v33, v29
	v_mul_f32_e32 v34, 0x3d372713, v30
	v_mul_f32_e32 v35, 0x3d372713, v31
	v_mul_f32_e32 v32, 0x3f4c422a, v32
	v_mul_f32_e32 v33, 0x3f4c422a, v33
	v_mul_f32_e32 v34, v30, v34
	v_mul_f32_e32 v35, v31, v35
	v_add_f32_e32 v32, v32, v32
	v_add_f32_e32 v33, v33, v33
	v_fma_f32 v34, v30, v34, v30
	v_fma_f32 v35, v31, v35, v31
	v_mul_f32_e32 v32, 0x3fb8aa3b, v32
	v_mul_f32_e32 v33, 0x3fb8aa3b, v33
	v_mul_f32_e32 v34, 0x3f4c422a, v34
	v_mul_f32_e32 v35, 0x3f4c422a, v35
	v_exp_f32_e32 v32, v32
	v_exp_f32_e32 v33, v33
	v_add_f32_e32 v34, v34, v34
	v_add_f32_e32 v35, v35, v35
	v_mul_f32_e32 v34, 0x3fb8aa3b, v34
	v_mul_f32_e32 v35, 0x3fb8aa3b, v35
	v_exp_f32_e32 v34, v34
	v_exp_f32_e32 v35, v35
	v_add_f32_e32 v32, 1.0, v32
	v_add_f32_e32 v33, 1.0, v33
	v_rcp_f32_e32 v32, v32
	v_rcp_f32_e32 v33, v33
	v_add_f32_e32 v34, 1.0, v34
	v_add_f32_e32 v35, 1.0, v35
	v_rcp_f32_e32 v34, v34
	v_rcp_f32_e32 v35, v35
	v_pk_fma_f32 v[32:33], v[32:33], 2.0, 1.0 op_sel_hi:[1,0,0] neg_lo:[1,0,0] neg_hi:[1,0,0]
	v_pk_mul_f32 v[28:29], v[28:29], 0.5 op_sel_hi:[1,0]
	v_pk_add_f32 v[32:33], v[32:33], 1.0 op_sel_hi:[1,0]
	v_pk_mul_f32 v[30:31], v[30:31], 0.5 op_sel_hi:[1,0]
	v_pk_mul_f32 v[28:29], v[28:29], v[32:33]
	v_pk_fma_f32 v[32:33], v[34:35], 2.0, 1.0 op_sel_hi:[1,0,0] neg_lo:[1,0,0] neg_hi:[1,0,0]
	v_lshlrev_b32_e32 v34, 16, v86
	v_and_b32_e32 v35, 0xffff0000, v86
	v_pk_fma_f32 v[24:25], v[44:45], v[34:35], v[24:25]
	v_pk_add_f32 v[32:33], v[32:33], 1.0 op_sel_hi:[1,0]
	v_mul_f32_e32 v34, 0x3d372713, v24
	v_mul_f32_e32 v35, 0x3d372713, v25
	v_mul_f32_e32 v34, v24, v34
	v_mul_f32_e32 v35, v25, v35
	v_fma_f32 v34, v24, v34, v24
	v_fma_f32 v35, v25, v35, v25
	v_mul_f32_e32 v34, 0x3f4c422a, v34
	v_mul_f32_e32 v35, 0x3f4c422a, v35
	v_add_f32_e32 v34, v34, v34
	v_add_f32_e32 v35, v35, v35
	v_mul_f32_e32 v34, 0x3fb8aa3b, v34
	v_mul_f32_e32 v35, 0x3fb8aa3b, v35
	v_exp_f32_e32 v34, v34
	v_exp_f32_e32 v35, v35
	v_pk_mul_f32 v[30:31], v[30:31], v[32:33]
	v_pk_mul_f32 v[24:25], v[24:25], 0.5 op_sel_hi:[1,0]
	v_add_f32_e32 v32, 1.0, v34
	v_add_f32_e32 v33, 1.0, v35
	v_lshlrev_b32_e32 v34, 16, v87
	v_and_b32_e32 v35, 0xffff0000, v87
	v_pk_fma_f32 v[26:27], v[46:47], v[34:35], v[26:27]
	v_rcp_f32_e32 v32, v32
	v_mul_f32_e32 v34, 0x3d372713, v26
	v_mul_f32_e32 v35, 0x3d372713, v27
	v_mul_f32_e32 v34, v26, v34
	v_mul_f32_e32 v35, v27, v35
	v_fma_f32 v34, v26, v34, v26
	v_fma_f32 v35, v27, v35, v27
	v_mul_f32_e32 v34, 0x3f4c422a, v34
	v_mul_f32_e32 v35, 0x3f4c422a, v35
	v_add_f32_e32 v34, v34, v34
	v_add_f32_e32 v35, v35, v35
	v_mul_f32_e32 v34, 0x3fb8aa3b, v34
	v_mul_f32_e32 v35, 0x3fb8aa3b, v35
	v_exp_f32_e32 v34, v34
	v_exp_f32_e32 v35, v35
	v_rcp_f32_e32 v33, v33
	v_pk_mul_f32 v[26:27], v[26:27], 0.5 op_sel_hi:[1,0]
	v_add_f32_e32 v34, 1.0, v34
	v_add_f32_e32 v35, 1.0, v35
	v_rcp_f32_e32 v34, v34
	v_rcp_f32_e32 v35, v35
	v_pk_fma_f32 v[32:33], v[32:33], 2.0, 1.0 op_sel_hi:[1,0,0] neg_lo:[1,0,0] neg_hi:[1,0,0]
	s_nop 0
	v_pk_add_f32 v[32:33], v[32:33], 1.0 op_sel_hi:[1,0]
	s_nop 0
	v_pk_mul_f32 v[32:33], v[24:25], v[32:33]
	v_pk_fma_f32 v[24:25], v[34:35], 2.0, 1.0 op_sel_hi:[1,0,0] neg_lo:[1,0,0] neg_hi:[1,0,0]
	s_nop 0
	v_pk_add_f32 v[24:25], v[24:25], 1.0 op_sel_hi:[1,0]
	s_nop 0
	v_pk_mul_f32 v[34:35], v[26:27], v[24:25]
	v_cvt_pk_bf16_f32 v24, v28, v29
	v_or_b32_e32 v28, v36, v144
	v_lshlrev_b32_e32 v172, 10, v28
	v_lshl_add_u64 v[28:29], s[8:9], 0, v[172:173]
	v_cvt_pk_bf16_f32 v25, v30, v31
	v_lshl_add_u64 v[28:29], v[28:29], 0, s[22:23]
	s_waitcnt vmcnt(6)
	v_lshlrev_b32_e32 v30, 16, v80
	v_and_b32_e32 v31, 0xffff0000, v80
	v_cvt_pk_bf16_f32 v26, v32, v33
	v_cvt_pk_bf16_f32 v27, v34, v35
	v_lshl_add_u64 v[28:29], v[28:29], 0, v[182:183]
	v_pk_fma_f32 v[20:21], v[52:53], v[30:31], v[20:21]
	global_store_dwordx4 v[28:29], v[24:27], off
	v_mul_f32_e32 v30, 0x3d372713, v20
	v_mul_f32_e32 v31, 0x3d372713, v21
	v_lshlrev_b32_e32 v26, 16, v81
	v_and_b32_e32 v27, 0xffff0000, v81
	v_mul_f32_e32 v30, v20, v30
	v_mul_f32_e32 v31, v21, v31
	v_pk_fma_f32 v[22:23], v[54:55], v[26:27], v[22:23]
	v_fma_f32 v30, v20, v30, v20
	v_fma_f32 v31, v21, v31, v21
	v_mul_f32_e32 v26, 0x3d372713, v22
	v_mul_f32_e32 v27, 0x3d372713, v23
	v_mul_f32_e32 v30, 0x3f4c422a, v30
	v_mul_f32_e32 v31, 0x3f4c422a, v31
	v_mul_f32_e32 v26, v22, v26
	v_mul_f32_e32 v27, v23, v27
	v_add_f32_e32 v30, v30, v30
	v_add_f32_e32 v31, v31, v31
	v_fma_f32 v26, v22, v26, v22
	v_fma_f32 v27, v23, v27, v23
	v_mul_f32_e32 v30, 0x3fb8aa3b, v30
	v_mul_f32_e32 v31, 0x3fb8aa3b, v31
	v_mul_f32_e32 v26, 0x3f4c422a, v26
	v_mul_f32_e32 v27, 0x3f4c422a, v27
	v_exp_f32_e32 v30, v30
	v_exp_f32_e32 v31, v31
	v_add_f32_e32 v26, v26, v26
	v_add_f32_e32 v27, v27, v27
	v_mul_f32_e32 v26, 0x3fb8aa3b, v26
	v_mul_f32_e32 v27, 0x3fb8aa3b, v27
	v_exp_f32_e32 v26, v26
	v_exp_f32_e32 v27, v27
	v_add_f32_e32 v24, 1.0, v30
	v_add_f32_e32 v25, 1.0, v31
	v_rcp_f32_e32 v24, v24
	v_rcp_f32_e32 v25, v25
	v_add_f32_e32 v26, 1.0, v26
	v_add_f32_e32 v27, 1.0, v27
	v_rcp_f32_e32 v26, v26
	v_rcp_f32_e32 v27, v27
	v_pk_fma_f32 v[24:25], v[24:25], 2.0, 1.0 op_sel_hi:[1,0,0] neg_lo:[1,0,0] neg_hi:[1,0,0]
	v_pk_mul_f32 v[20:21], v[20:21], 0.5 op_sel_hi:[1,0]
	v_pk_add_f32 v[24:25], v[24:25], 1.0 op_sel_hi:[1,0]
	v_pk_mul_f32 v[22:23], v[22:23], 0.5 op_sel_hi:[1,0]
	v_pk_mul_f32 v[20:21], v[20:21], v[24:25]
	v_pk_fma_f32 v[24:25], v[26:27], 2.0, 1.0 op_sel_hi:[1,0,0] neg_lo:[1,0,0] neg_hi:[1,0,0]
	v_lshlrev_b32_e32 v26, 16, v82
	v_and_b32_e32 v27, 0xffff0000, v82
	v_pk_fma_f32 v[16:17], v[44:45], v[26:27], v[16:17]
	v_pk_add_f32 v[24:25], v[24:25], 1.0 op_sel_hi:[1,0]
	v_mul_f32_e32 v26, 0x3d372713, v16
	v_mul_f32_e32 v27, 0x3d372713, v17
	v_mul_f32_e32 v26, v16, v26
	v_mul_f32_e32 v27, v17, v27
	v_fma_f32 v26, v16, v26, v16
	v_fma_f32 v27, v17, v27, v17
	v_mul_f32_e32 v26, 0x3f4c422a, v26
	v_mul_f32_e32 v27, 0x3f4c422a, v27
	v_add_f32_e32 v26, v26, v26
	v_add_f32_e32 v27, v27, v27
	v_mul_f32_e32 v26, 0x3fb8aa3b, v26
	v_mul_f32_e32 v27, 0x3fb8aa3b, v27
	v_exp_f32_e32 v26, v26
	v_exp_f32_e32 v27, v27
	v_pk_mul_f32 v[22:23], v[22:23], v[24:25]
	v_pk_mul_f32 v[16:17], v[16:17], 0.5 op_sel_hi:[1,0]
	v_add_f32_e32 v24, 1.0, v26
	v_add_f32_e32 v25, 1.0, v27
	v_lshlrev_b32_e32 v26, 16, v83
	v_and_b32_e32 v27, 0xffff0000, v83
	v_pk_fma_f32 v[18:19], v[46:47], v[26:27], v[18:19]
	v_rcp_f32_e32 v24, v24
	v_mul_f32_e32 v26, 0x3d372713, v18
	v_mul_f32_e32 v27, 0x3d372713, v19
	v_mul_f32_e32 v26, v18, v26
	v_mul_f32_e32 v27, v19, v27
	v_fma_f32 v26, v18, v26, v18
	v_fma_f32 v27, v19, v27, v19
	v_mul_f32_e32 v26, 0x3f4c422a, v26
	v_mul_f32_e32 v27, 0x3f4c422a, v27
	v_add_f32_e32 v26, v26, v26
	v_add_f32_e32 v27, v27, v27
	v_mul_f32_e32 v26, 0x3fb8aa3b, v26
	v_mul_f32_e32 v27, 0x3fb8aa3b, v27
	v_exp_f32_e32 v26, v26
	v_exp_f32_e32 v27, v27
	v_rcp_f32_e32 v25, v25
	v_pk_mul_f32 v[18:19], v[18:19], 0.5 op_sel_hi:[1,0]
	v_add_f32_e32 v26, 1.0, v26
	v_add_f32_e32 v27, 1.0, v27
	v_rcp_f32_e32 v26, v26
	v_rcp_f32_e32 v27, v27
	v_pk_fma_f32 v[24:25], v[24:25], 2.0, 1.0 op_sel_hi:[1,0,0] neg_lo:[1,0,0] neg_hi:[1,0,0]
	s_nop 0
	v_pk_add_f32 v[24:25], v[24:25], 1.0 op_sel_hi:[1,0]
	s_nop 0
	v_pk_mul_f32 v[24:25], v[16:17], v[24:25]
	v_pk_fma_f32 v[16:17], v[26:27], 2.0, 1.0 op_sel_hi:[1,0,0] neg_lo:[1,0,0] neg_hi:[1,0,0]
	s_nop 0
	v_pk_add_f32 v[16:17], v[16:17], 1.0 op_sel_hi:[1,0]
	s_nop 0
	v_pk_mul_f32 v[26:27], v[18:19], v[16:17]
	v_cvt_pk_bf16_f32 v16, v20, v21
	v_or_b32_e32 v20, v36, v132
	v_lshlrev_b32_e32 v172, 10, v20
	v_lshl_add_u64 v[20:21], s[8:9], 0, v[172:173]
	v_lshl_add_u64 v[20:21], v[20:21], 0, s[22:23]
	v_cvt_pk_bf16_f32 v17, v22, v23
	v_cvt_pk_bf16_f32 v18, v24, v25
	v_cvt_pk_bf16_f32 v19, v26, v27
	v_lshl_add_u64 v[20:21], v[20:21], 0, v[182:183]
	global_store_dwordx4 v[20:21], v[16:19], off
	v_or_b32_e32 v20, 0x600, v68
	s_waitcnt vmcnt(7)
	v_lshlrev_b32_e32 v16, 16, v76
	v_and_b32_e32 v17, 0xffff0000, v76
	v_pk_fma_f32 v[12:13], v[52:53], v[16:17], v[12:13]
	v_lshlrev_b32_e32 v18, 16, v77
	v_mul_f32_e32 v16, 0x3d372713, v12
	v_mul_f32_e32 v17, 0x3d372713, v13
	v_and_b32_e32 v19, 0xffff0000, v77
	v_mul_f32_e32 v16, v12, v16
	v_mul_f32_e32 v17, v13, v17
	v_pk_fma_f32 v[14:15], v[54:55], v[18:19], v[14:15]
	v_fma_f32 v16, v12, v16, v12
	v_fma_f32 v17, v13, v17, v13
	v_mul_f32_e32 v18, 0x3d372713, v14
	v_mul_f32_e32 v19, 0x3d372713, v15
	v_mul_f32_e32 v16, 0x3f4c422a, v16
	v_mul_f32_e32 v17, 0x3f4c422a, v17
	v_mul_f32_e32 v18, v14, v18
	v_mul_f32_e32 v19, v15, v19
	v_add_f32_e32 v16, v16, v16
	v_add_f32_e32 v17, v17, v17
	v_fma_f32 v18, v14, v18, v14
	v_fma_f32 v19, v15, v19, v15
	v_mul_f32_e32 v16, 0x3fb8aa3b, v16
	v_mul_f32_e32 v17, 0x3fb8aa3b, v17
	v_mul_f32_e32 v18, 0x3f4c422a, v18
	v_mul_f32_e32 v19, 0x3f4c422a, v19
	v_exp_f32_e32 v16, v16
	v_exp_f32_e32 v17, v17
	v_add_f32_e32 v18, v18, v18
	v_add_f32_e32 v19, v19, v19
	v_mul_f32_e32 v18, 0x3fb8aa3b, v18
	v_mul_f32_e32 v19, 0x3fb8aa3b, v19
	v_exp_f32_e32 v18, v18
	v_exp_f32_e32 v19, v19
	v_add_f32_e32 v16, 1.0, v16
	v_add_f32_e32 v17, 1.0, v17
	v_rcp_f32_e32 v16, v16
	v_rcp_f32_e32 v17, v17
	v_add_f32_e32 v18, 1.0, v18
	v_add_f32_e32 v19, 1.0, v19
	v_rcp_f32_e32 v18, v18
	v_rcp_f32_e32 v19, v19
	v_pk_fma_f32 v[16:17], v[16:17], 2.0, 1.0 op_sel_hi:[1,0,0] neg_lo:[1,0,0] neg_hi:[1,0,0]
	v_pk_mul_f32 v[12:13], v[12:13], 0.5 op_sel_hi:[1,0]
	v_pk_add_f32 v[16:17], v[16:17], 1.0 op_sel_hi:[1,0]
	v_pk_mul_f32 v[14:15], v[14:15], 0.5 op_sel_hi:[1,0]
	v_pk_mul_f32 v[12:13], v[12:13], v[16:17]
	v_pk_fma_f32 v[16:17], v[18:19], 2.0, 1.0 op_sel_hi:[1,0,0] neg_lo:[1,0,0] neg_hi:[1,0,0]
	v_lshlrev_b32_e32 v18, 16, v78
	v_and_b32_e32 v19, 0xffff0000, v78
	v_pk_fma_f32 v[8:9], v[44:45], v[18:19], v[8:9]
	v_pk_add_f32 v[16:17], v[16:17], 1.0 op_sel_hi:[1,0]
	v_mul_f32_e32 v18, 0x3d372713, v8
	v_mul_f32_e32 v19, 0x3d372713, v9
	v_mul_f32_e32 v18, v8, v18
	v_mul_f32_e32 v19, v9, v19
	v_fma_f32 v18, v8, v18, v8
	v_fma_f32 v19, v9, v19, v9
	v_mul_f32_e32 v18, 0x3f4c422a, v18
	v_mul_f32_e32 v19, 0x3f4c422a, v19
	v_add_f32_e32 v18, v18, v18
	v_add_f32_e32 v19, v19, v19
	v_mul_f32_e32 v18, 0x3fb8aa3b, v18
	v_mul_f32_e32 v19, 0x3fb8aa3b, v19
	v_exp_f32_e32 v18, v18
	v_exp_f32_e32 v19, v19
	v_pk_mul_f32 v[14:15], v[14:15], v[16:17]
	v_pk_mul_f32 v[8:9], v[8:9], 0.5 op_sel_hi:[1,0]
	v_add_f32_e32 v16, 1.0, v18
	v_add_f32_e32 v17, 1.0, v19
	v_lshlrev_b32_e32 v18, 16, v79
	v_and_b32_e32 v19, 0xffff0000, v79
	v_pk_fma_f32 v[10:11], v[46:47], v[18:19], v[10:11]
	v_rcp_f32_e32 v16, v16
	v_mul_f32_e32 v18, 0x3d372713, v10
	v_mul_f32_e32 v19, 0x3d372713, v11
	v_mul_f32_e32 v18, v10, v18
	v_mul_f32_e32 v19, v11, v19
	v_fma_f32 v18, v10, v18, v10
	v_fma_f32 v19, v11, v19, v11
	v_mul_f32_e32 v18, 0x3f4c422a, v18
	v_mul_f32_e32 v19, 0x3f4c422a, v19
	v_add_f32_e32 v18, v18, v18
	v_add_f32_e32 v19, v19, v19
	v_mul_f32_e32 v18, 0x3fb8aa3b, v18
	v_mul_f32_e32 v19, 0x3fb8aa3b, v19
	v_exp_f32_e32 v18, v18
	v_exp_f32_e32 v19, v19
	v_rcp_f32_e32 v17, v17
	v_pk_mul_f32 v[10:11], v[10:11], 0.5 op_sel_hi:[1,0]
	v_add_f32_e32 v18, 1.0, v18
	v_add_f32_e32 v19, 1.0, v19
	v_rcp_f32_e32 v18, v18
	v_rcp_f32_e32 v19, v19
	v_pk_fma_f32 v[16:17], v[16:17], 2.0, 1.0 op_sel_hi:[1,0,0] neg_lo:[1,0,0] neg_hi:[1,0,0]
	s_nop 0
	v_pk_add_f32 v[16:17], v[16:17], 1.0 op_sel_hi:[1,0]
	s_nop 0
	v_pk_mul_f32 v[16:17], v[8:9], v[16:17]
	v_pk_fma_f32 v[8:9], v[18:19], 2.0, 1.0 op_sel_hi:[1,0,0] neg_lo:[1,0,0] neg_hi:[1,0,0]
	s_nop 0
	v_pk_add_f32 v[8:9], v[8:9], 1.0 op_sel_hi:[1,0]
	s_nop 0
	v_pk_mul_f32 v[18:19], v[10:11], v[8:9]
	v_cvt_pk_bf16_f32 v8, v12, v13
	v_or_b32_e32 v12, v20, v144
	v_lshlrev_b32_e32 v172, 10, v12
	v_lshl_add_u64 v[12:13], s[8:9], 0, v[172:173]
	v_cvt_pk_bf16_f32 v9, v14, v15
	v_lshl_add_u64 v[12:13], v[12:13], 0, s[22:23]
	s_waitcnt vmcnt(6)
	v_lshlrev_b32_e32 v14, 16, v72
	v_and_b32_e32 v15, 0xffff0000, v72
	v_cvt_pk_bf16_f32 v10, v16, v17
	v_cvt_pk_bf16_f32 v11, v18, v19
	v_lshl_add_u64 v[12:13], v[12:13], 0, v[182:183]
	v_pk_fma_f32 v[4:5], v[52:53], v[14:15], v[4:5]
	global_store_dwordx4 v[12:13], v[8:11], off
	v_mul_f32_e32 v14, 0x3d372713, v4
	v_mul_f32_e32 v15, 0x3d372713, v5
	v_lshlrev_b32_e32 v10, 16, v73
	v_and_b32_e32 v11, 0xffff0000, v73
	v_mul_f32_e32 v14, v4, v14
	v_mul_f32_e32 v15, v5, v15
	v_pk_fma_f32 v[6:7], v[54:55], v[10:11], v[6:7]
	v_fma_f32 v14, v4, v14, v4
	v_fma_f32 v15, v5, v15, v5
	v_mul_f32_e32 v10, 0x3d372713, v6
	v_mul_f32_e32 v11, 0x3d372713, v7
	v_mul_f32_e32 v14, 0x3f4c422a, v14
	v_mul_f32_e32 v15, 0x3f4c422a, v15
	v_mul_f32_e32 v10, v6, v10
	v_mul_f32_e32 v11, v7, v11
	v_add_f32_e32 v14, v14, v14
	v_add_f32_e32 v15, v15, v15
	v_fma_f32 v10, v6, v10, v6
	v_fma_f32 v11, v7, v11, v7
	v_mul_f32_e32 v14, 0x3fb8aa3b, v14
	v_mul_f32_e32 v15, 0x3fb8aa3b, v15
	v_mul_f32_e32 v10, 0x3f4c422a, v10
	v_mul_f32_e32 v11, 0x3f4c422a, v11
	v_exp_f32_e32 v14, v14
	v_exp_f32_e32 v15, v15
	v_add_f32_e32 v10, v10, v10
	v_add_f32_e32 v11, v11, v11
	v_mul_f32_e32 v10, 0x3fb8aa3b, v10
	v_mul_f32_e32 v11, 0x3fb8aa3b, v11
	v_exp_f32_e32 v10, v10
	v_exp_f32_e32 v11, v11
	v_add_f32_e32 v8, 1.0, v14
	v_add_f32_e32 v9, 1.0, v15
	v_rcp_f32_e32 v8, v8
	v_rcp_f32_e32 v9, v9
	v_add_f32_e32 v10, 1.0, v10
	v_add_f32_e32 v11, 1.0, v11
	v_rcp_f32_e32 v10, v10
	v_rcp_f32_e32 v11, v11
	v_pk_fma_f32 v[8:9], v[8:9], 2.0, 1.0 op_sel_hi:[1,0,0] neg_lo:[1,0,0] neg_hi:[1,0,0]
	v_pk_mul_f32 v[4:5], v[4:5], 0.5 op_sel_hi:[1,0]
	v_pk_add_f32 v[8:9], v[8:9], 1.0 op_sel_hi:[1,0]
	v_pk_mul_f32 v[6:7], v[6:7], 0.5 op_sel_hi:[1,0]
	v_pk_mul_f32 v[4:5], v[4:5], v[8:9]
	v_pk_fma_f32 v[8:9], v[10:11], 2.0, 1.0 op_sel_hi:[1,0,0] neg_lo:[1,0,0] neg_hi:[1,0,0]
	v_lshlrev_b32_e32 v10, 16, v74
	v_and_b32_e32 v11, 0xffff0000, v74
	v_pk_fma_f32 v[0:1], v[44:45], v[10:11], v[0:1]
	v_pk_add_f32 v[8:9], v[8:9], 1.0 op_sel_hi:[1,0]
	v_mul_f32_e32 v10, 0x3d372713, v0
	v_mul_f32_e32 v11, 0x3d372713, v1
	v_mul_f32_e32 v10, v0, v10
	v_mul_f32_e32 v11, v1, v11
	v_fma_f32 v10, v0, v10, v0
	v_fma_f32 v11, v1, v11, v1
	v_mul_f32_e32 v10, 0x3f4c422a, v10
	v_mul_f32_e32 v11, 0x3f4c422a, v11
	v_add_f32_e32 v10, v10, v10
	v_add_f32_e32 v11, v11, v11
	v_mul_f32_e32 v10, 0x3fb8aa3b, v10
	v_mul_f32_e32 v11, 0x3fb8aa3b, v11
	v_exp_f32_e32 v10, v10
	v_exp_f32_e32 v11, v11
	v_pk_mul_f32 v[6:7], v[6:7], v[8:9]
	v_pk_mul_f32 v[0:1], v[0:1], 0.5 op_sel_hi:[1,0]
	v_add_f32_e32 v8, 1.0, v10
	v_add_f32_e32 v9, 1.0, v11
	v_lshlrev_b32_e32 v10, 16, v75
	v_and_b32_e32 v11, 0xffff0000, v75
	v_pk_fma_f32 v[2:3], v[46:47], v[10:11], v[2:3]
	v_rcp_f32_e32 v8, v8
	v_mul_f32_e32 v10, 0x3d372713, v2
	v_mul_f32_e32 v11, 0x3d372713, v3
	v_mul_f32_e32 v10, v2, v10
	v_mul_f32_e32 v11, v3, v11
	v_fma_f32 v10, v2, v10, v2
	v_fma_f32 v11, v3, v11, v3
	v_mul_f32_e32 v10, 0x3f4c422a, v10
	v_mul_f32_e32 v11, 0x3f4c422a, v11
	v_add_f32_e32 v10, v10, v10
	v_add_f32_e32 v11, v11, v11
	v_mul_f32_e32 v10, 0x3fb8aa3b, v10
	v_mul_f32_e32 v11, 0x3fb8aa3b, v11
	v_exp_f32_e32 v10, v10
	v_exp_f32_e32 v11, v11
	v_rcp_f32_e32 v9, v9
	v_pk_mul_f32 v[2:3], v[2:3], 0.5 op_sel_hi:[1,0]
	v_add_f32_e32 v10, 1.0, v10
	v_add_f32_e32 v11, 1.0, v11
	v_rcp_f32_e32 v10, v10
	v_rcp_f32_e32 v11, v11
	v_pk_fma_f32 v[8:9], v[8:9], 2.0, 1.0 op_sel_hi:[1,0,0] neg_lo:[1,0,0] neg_hi:[1,0,0]
	s_nop 0
	v_pk_add_f32 v[8:9], v[8:9], 1.0 op_sel_hi:[1,0]
	s_nop 0
	v_pk_mul_f32 v[8:9], v[0:1], v[8:9]
	v_pk_fma_f32 v[0:1], v[10:11], 2.0, 1.0 op_sel_hi:[1,0,0] neg_lo:[1,0,0] neg_hi:[1,0,0]
	s_nop 0
	v_pk_add_f32 v[0:1], v[0:1], 1.0 op_sel_hi:[1,0]
	s_nop 0
	v_pk_mul_f32 v[10:11], v[2:3], v[0:1]
	v_cvt_pk_bf16_f32 v0, v4, v5
	v_or_b32_e32 v4, v20, v132
	v_lshlrev_b32_e32 v172, 10, v4
	v_lshl_add_u64 v[4:5], s[8:9], 0, v[172:173]
	v_lshl_add_u64 v[4:5], v[4:5], 0, s[22:23]
	v_cvt_pk_bf16_f32 v1, v6, v7
	v_cvt_pk_bf16_f32 v2, v8, v9
	v_cvt_pk_bf16_f32 v3, v10, v11
	v_lshl_add_u64 v[4:5], v[4:5], 0, v[182:183]
	global_store_dwordx4 v[4:5], v[0:3], off
	s_and_b64 vcc, exec, s[2:3]
	s_mov_b64 s[2:3], -1
	s_cbranch_vccnz .LBB0_1937
	s_andn2_b64 vcc, exec, s[10:11]
	s_cbranch_vccnz .LBB0_1936
	v_writelane_b32 v255, 1, 53
	s_branch .LBB0_1936

.LBB0_2064:
	s_add_u32 s36, s36, 0x60080
	s_addc_u32 s37, s37, 0
	s_add_u32 s65, s38, 0x100
	v_mov_b32_e32 v0, 0
	s_addc_u32 s66, s39, 0
	s_mov_b32 s67, -2
	v_mov_b32_e32 v1, v0
	v_mov_b32_e32 v2, v0
	v_mov_b32_e32 v3, v0
	v_mov_b32_e32 v4, v0
	v_mov_b32_e32 v5, v0
	v_mov_b32_e32 v6, v0
	v_mov_b32_e32 v7, v0
	v_mov_b32_e32 v12, v0
	v_mov_b32_e32 v13, v0
	v_mov_b32_e32 v14, v0
	v_mov_b32_e32 v15, v0
	v_mov_b32_e32 v20, v0
	v_mov_b32_e32 v21, v0
	v_mov_b32_e32 v22, v0
	v_mov_b32_e32 v23, v0
	v_mov_b32_e32 v28, v0
	v_mov_b32_e32 v29, v0
	v_mov_b32_e32 v30, v0
	v_mov_b32_e32 v31, v0
	v_mov_b32_e32 v36, v0
	v_mov_b32_e32 v37, v0
	v_mov_b32_e32 v38, v0
	v_mov_b32_e32 v39, v0
	v_mov_b32_e32 v44, v0
	v_mov_b32_e32 v45, v0
	v_mov_b32_e32 v46, v0
	v_mov_b32_e32 v47, v0
	v_mov_b32_e32 v52, v0
	v_mov_b32_e32 v53, v0
	v_mov_b32_e32 v54, v0
	v_mov_b32_e32 v55, v0
	v_mov_b32_e32 v8, v0
	v_mov_b32_e32 v9, v0
	v_mov_b32_e32 v10, v0
	v_mov_b32_e32 v11, v0
	v_mov_b32_e32 v16, v0
	v_mov_b32_e32 v17, v0
	v_mov_b32_e32 v18, v0
	v_mov_b32_e32 v19, v0
	v_mov_b32_e32 v24, v0
	v_mov_b32_e32 v25, v0
	v_mov_b32_e32 v26, v0
	v_mov_b32_e32 v27, v0
	v_mov_b32_e32 v32, v0
	v_mov_b32_e32 v33, v0
	v_mov_b32_e32 v34, v0
	v_mov_b32_e32 v35, v0
	v_mov_b32_e32 v40, v0
	v_mov_b32_e32 v41, v0
	v_mov_b32_e32 v42, v0
	v_mov_b32_e32 v43, v0
	v_mov_b32_e32 v48, v0
	v_mov_b32_e32 v49, v0
	v_mov_b32_e32 v50, v0
	v_mov_b32_e32 v51, v0
	v_mov_b32_e32 v56, v0
	v_mov_b32_e32 v57, v0
	v_mov_b32_e32 v58, v0
	v_mov_b32_e32 v59, v0
	v_mov_b32_e32 v60, v0
	v_mov_b32_e32 v61, v0
	v_mov_b32_e32 v62, v0
	v_mov_b32_e32 v63, v0
	v_mov_b32_e32 v64, v0
	v_mov_b32_e32 v65, v0
	v_mov_b32_e32 v66, v0
	v_mov_b32_e32 v67, v0
	v_mov_b32_e32 v68, v0
	v_mov_b32_e32 v69, v0
	v_mov_b32_e32 v70, v0
	v_mov_b32_e32 v71, v0
	v_mov_b32_e32 v76, v0
	v_mov_b32_e32 v77, v0
	v_mov_b32_e32 v78, v0
	v_mov_b32_e32 v79, v0
	v_mov_b32_e32 v84, v0
	v_mov_b32_e32 v85, v0
	v_mov_b32_e32 v86, v0
	v_mov_b32_e32 v87, v0
	v_mov_b32_e32 v92, v0
	v_mov_b32_e32 v93, v0
	v_mov_b32_e32 v94, v0
	v_mov_b32_e32 v95, v0
	v_mov_b32_e32 v100, v0
	v_mov_b32_e32 v101, v0
	v_mov_b32_e32 v102, v0
	v_mov_b32_e32 v103, v0
	v_mov_b32_e32 v108, v0
	v_mov_b32_e32 v109, v0
	v_mov_b32_e32 v110, v0
	v_mov_b32_e32 v111, v0
	v_mov_b32_e32 v116, v0
	v_mov_b32_e32 v117, v0
	v_mov_b32_e32 v118, v0
	v_mov_b32_e32 v119, v0
	v_mov_b32_e32 v72, v0
	v_mov_b32_e32 v73, v0
	v_mov_b32_e32 v74, v0
	v_mov_b32_e32 v75, v0
	v_mov_b32_e32 v80, v0
	v_mov_b32_e32 v81, v0
	v_mov_b32_e32 v82, v0
	v_mov_b32_e32 v83, v0
	v_mov_b32_e32 v88, v0
	v_mov_b32_e32 v89, v0
	v_mov_b32_e32 v90, v0
	v_mov_b32_e32 v91, v0
	v_mov_b32_e32 v96, v0
	v_mov_b32_e32 v97, v0
	v_mov_b32_e32 v98, v0
	v_mov_b32_e32 v99, v0
	v_mov_b32_e32 v104, v0
	v_mov_b32_e32 v105, v0
	v_mov_b32_e32 v106, v0
	v_mov_b32_e32 v107, v0
	v_mov_b32_e32 v112, v0
	v_mov_b32_e32 v113, v0
	v_mov_b32_e32 v114, v0
	v_mov_b32_e32 v115, v0
	v_mov_b32_e32 v120, v0
	v_mov_b32_e32 v121, v0
	v_mov_b32_e32 v122, v0
	v_mov_b32_e32 v123, v0
	v_mov_b32_e32 v124, v0
	v_mov_b32_e32 v125, v0
	v_mov_b32_e32 v126, v0
	v_mov_b32_e32 v127, v0
	v_readlane_b32 s97, v255, 53
	s_nop 3
	s_cmp_eq_u32 s97, 1
	s_cbranch_scc0 .Llsb_skip_17
	v_writelane_b32 v255, 0, 53
	s_barrier
.Llsb_skip_17:
.LBB0_2065:
	ds_read_b128 v[136:139], v154
	ds_read_b128 v[140:143], v154 offset:1024
	ds_read_b128 v[144:147], v154 offset:2048
	ds_read_b128 v[158:161], v154 offset:3072
	ds_read_b128 v[162:165], v155
	ds_read_b128 v[166:169], v155 offset:1024
	ds_read_b128 v[170:173], v155 offset:2048
	ds_read_b128 v[180:183], v155 offset:3072
	s_add_u32 s38, s36, 0xfffa0080
	s_addc_u32 s39, s37, -1
	s_cmp_eq_u32 s67, 4
	s_cselect_b32 s41, s31, s39
	s_cselect_b32 s40, s30, s38
	s_cselect_b32 s39, s35, s66
	s_cselect_b32 s38, s34, s65
	v_lshl_add_u64 v[148:149], s[36:37], 0, v[132:133]
	s_add_i32 m0, s45, 0xc000
	ds_read_b128 v[184:187], v156
	ds_read_b128 v[188:191], v156 offset:1024
	ds_read_b128 v[192:195], v156 offset:2048
	ds_read_b128 v[196:199], v156 offset:3072
	ds_read_b128 v[200:203], v156 offset:4096
	ds_read_b128 v[206:209], v156 offset:5120
	ds_read_b128 v[210:213], v156 offset:6144
	ds_read_b128 v[214:217], v156 offset:7168
	global_load_lds_dwordx4 v[148:149], off
	v_lshl_add_u64 v[148:149], s[36:37], 0, v[134:135]
	s_add_i32 m0, s45, 0xe000
	s_nop 0
	global_load_lds_dwordx4 v[148:149], off
	s_waitcnt vmcnt(8)
	s_waitcnt lgkmcnt(0)
	s_barrier
	s_setprio 1
	s_waitcnt lgkmcnt(0)
	v_mfma_f32_16x16x32_bf16 v[124:127], v[136:139], v[184:187], v[124:127]
	v_mfma_f32_16x16x32_bf16 v[120:123], v[144:147], v[184:187], v[120:123]
	v_mfma_f32_16x16x32_bf16 v[112:115], v[136:139], v[192:195], v[112:115]
	v_mfma_f32_16x16x32_bf16 v[104:107], v[144:147], v[192:195], v[104:107]
	v_mfma_f32_16x16x32_bf16 v[96:99], v[136:139], v[200:203], v[96:99]
	v_mfma_f32_16x16x32_bf16 v[88:91], v[144:147], v[200:203], v[88:91]
	v_mfma_f32_16x16x32_bf16 v[80:83], v[136:139], v[210:213], v[80:83]
	v_mfma_f32_16x16x32_bf16 v[72:75], v[144:147], v[210:213], v[72:75]
	v_mfma_f32_16x16x32_bf16 v[124:127], v[140:143], v[188:191], v[124:127]
	v_mfma_f32_16x16x32_bf16 v[120:123], v[158:161], v[188:191], v[120:123]
	v_mfma_f32_16x16x32_bf16 v[112:115], v[140:143], v[196:199], v[112:115]
	v_mfma_f32_16x16x32_bf16 v[104:107], v[158:161], v[196:199], v[104:107]
	v_mfma_f32_16x16x32_bf16 v[96:99], v[140:143], v[206:209], v[96:99]
	v_mfma_f32_16x16x32_bf16 v[88:91], v[158:161], v[206:209], v[88:91]
	v_mfma_f32_16x16x32_bf16 v[80:83], v[140:143], v[214:217], v[80:83]
	v_mfma_f32_16x16x32_bf16 v[72:75], v[158:161], v[214:217], v[72:75]
	s_setprio 0
	s_setprio 1
	v_mfma_f32_16x16x32_bf16 v[116:119], v[162:165], v[184:187], v[116:119]
	v_mfma_f32_16x16x32_bf16 v[108:111], v[170:173], v[184:187], v[108:111]
	v_mfma_f32_16x16x32_bf16 v[100:103], v[162:165], v[192:195], v[100:103]
	v_mfma_f32_16x16x32_bf16 v[92:95], v[170:173], v[192:195], v[92:95]
	v_mfma_f32_16x16x32_bf16 v[84:87], v[162:165], v[200:203], v[84:87]
	v_mfma_f32_16x16x32_bf16 v[76:79], v[170:173], v[200:203], v[76:79]
	v_mfma_f32_16x16x32_bf16 v[68:71], v[162:165], v[210:213], v[68:71]
	v_mfma_f32_16x16x32_bf16 v[64:67], v[170:173], v[210:213], v[64:67]
	v_mfma_f32_16x16x32_bf16 v[116:119], v[166:169], v[188:191], v[116:119]
	v_mfma_f32_16x16x32_bf16 v[108:111], v[180:183], v[188:191], v[108:111]
	v_mfma_f32_16x16x32_bf16 v[100:103], v[166:169], v[196:199], v[100:103]
	v_mfma_f32_16x16x32_bf16 v[92:95], v[180:183], v[196:199], v[92:95]
	v_mfma_f32_16x16x32_bf16 v[84:87], v[166:169], v[206:209], v[84:87]
	v_mfma_f32_16x16x32_bf16 v[76:79], v[180:183], v[206:209], v[76:79]
	v_mfma_f32_16x16x32_bf16 v[68:71], v[166:169], v[214:217], v[68:71]
	v_mfma_f32_16x16x32_bf16 v[64:67], v[180:183], v[214:217], v[64:67]
	s_setprio 0
	s_barrier
	s_add_i32 s68, s52, s44
	v_lshl_add_u64 v[148:149], s[38:39], 0, v[130:131]
	s_mov_b32 m0, s68
	ds_read_b128 v[184:187], v156 offset:16384
	ds_read_b128 v[188:191], v156 offset:17408
	ds_read_b128 v[192:195], v156 offset:18432
	ds_read_b128 v[196:199], v156 offset:19456
	ds_read_b128 v[200:203], v156 offset:20480
	ds_read_b128 v[206:209], v156 offset:21504
	ds_read_b128 v[210:213], v156 offset:22528
	ds_read_b128 v[214:217], v156 offset:23552
	global_load_lds_dwordx4 v[148:149], off
	s_add_i32 m0, s68, 0x2000
	s_add_u32 s68, s38, 0x60000
	v_lshl_add_u64 v[174:175], s[38:39], 0, v[128:129]
	s_addc_u32 s69, s39, 0
	s_add_i32 s70, s53, s44
	global_load_lds_dwordx4 v[174:175], off
	v_lshl_add_u64 v[218:219], s[68:69], 0, v[130:131]
	s_mov_b32 m0, s70
	v_lshl_add_u64 v[220:221], s[40:41], 0, v[128:129]
	global_load_lds_dwordx4 v[218:219], off
	v_lshl_add_u64 v[218:219], s[68:69], 0, v[128:129]
	s_add_i32 m0, s70, 0x2000
	s_nop 0
	global_load_lds_dwordx4 v[218:219], off
	v_lshl_add_u64 v[218:219], s[40:41], 0, v[130:131]
	s_mov_b32 m0, s45
	s_nop 0
	global_load_lds_dwordx4 v[218:219], off
	s_mov_b32 m0, s46
	s_nop 0
	global_load_lds_dwordx4 v[220:221], off
	s_waitcnt vmcnt(8)
	s_waitcnt lgkmcnt(0)
	s_barrier
	s_setprio 1
	s_waitcnt lgkmcnt(0)
	v_mfma_f32_16x16x32_bf16 v[60:63], v[136:139], v[184:187], v[60:63]
	v_mfma_f32_16x16x32_bf16 v[56:59], v[144:147], v[184:187], v[56:59]
	v_mfma_f32_16x16x32_bf16 v[48:51], v[136:139], v[192:195], v[48:51]
	v_mfma_f32_16x16x32_bf16 v[40:43], v[144:147], v[192:195], v[40:43]
	v_mfma_f32_16x16x32_bf16 v[32:35], v[136:139], v[200:203], v[32:35]
	v_mfma_f32_16x16x32_bf16 v[24:27], v[144:147], v[200:203], v[24:27]
	v_mfma_f32_16x16x32_bf16 v[16:19], v[136:139], v[210:213], v[16:19]
	v_mfma_f32_16x16x32_bf16 v[8:11], v[144:147], v[210:213], v[8:11]
	v_mfma_f32_16x16x32_bf16 v[60:63], v[140:143], v[188:191], v[60:63]
	v_mfma_f32_16x16x32_bf16 v[56:59], v[158:161], v[188:191], v[56:59]
	v_mfma_f32_16x16x32_bf16 v[48:51], v[140:143], v[196:199], v[48:51]
	v_mfma_f32_16x16x32_bf16 v[40:43], v[158:161], v[196:199], v[40:43]
	v_mfma_f32_16x16x32_bf16 v[32:35], v[140:143], v[206:209], v[32:35]
	v_mfma_f32_16x16x32_bf16 v[24:27], v[158:161], v[206:209], v[24:27]
	v_mfma_f32_16x16x32_bf16 v[16:19], v[140:143], v[214:217], v[16:19]
	v_mfma_f32_16x16x32_bf16 v[8:11], v[158:161], v[214:217], v[8:11]
	s_setprio 0
	s_setprio 1
	v_mfma_f32_16x16x32_bf16 v[52:55], v[162:165], v[184:187], v[52:55]
	v_mfma_f32_16x16x32_bf16 v[44:47], v[170:173], v[184:187], v[44:47]
	v_mfma_f32_16x16x32_bf16 v[36:39], v[162:165], v[192:195], v[36:39]
	v_mfma_f32_16x16x32_bf16 v[28:31], v[170:173], v[192:195], v[28:31]
	v_mfma_f32_16x16x32_bf16 v[20:23], v[162:165], v[200:203], v[20:23]
	v_mfma_f32_16x16x32_bf16 v[12:15], v[170:173], v[200:203], v[12:15]
	v_mfma_f32_16x16x32_bf16 v[4:7], v[162:165], v[210:213], v[4:7]
	v_mfma_f32_16x16x32_bf16 v[0:3], v[170:173], v[210:213], v[0:3]
	v_mfma_f32_16x16x32_bf16 v[52:55], v[166:169], v[188:191], v[52:55]
	v_mfma_f32_16x16x32_bf16 v[44:47], v[180:183], v[188:191], v[44:47]
	v_mfma_f32_16x16x32_bf16 v[36:39], v[166:169], v[196:199], v[36:39]
	v_mfma_f32_16x16x32_bf16 v[28:31], v[180:183], v[196:199], v[28:31]
	v_mfma_f32_16x16x32_bf16 v[20:23], v[166:169], v[206:209], v[20:23]
	v_mfma_f32_16x16x32_bf16 v[12:15], v[180:183], v[206:209], v[12:15]
	v_mfma_f32_16x16x32_bf16 v[4:7], v[166:169], v[214:217], v[4:7]
	v_mfma_f32_16x16x32_bf16 v[0:3], v[180:183], v[214:217], v[0:3]
	s_setprio 0
	s_barrier
	s_add_i32 s68, 0, 0x18000
	v_add_u32_e32 v157, s68, v152
	s_add_i32 s69, 0, 0x1c000
	ds_read_b128 v[136:139], v157
	ds_read_b128 v[140:143], v157 offset:1024
	ds_read_b128 v[144:147], v157 offset:2048
	ds_read_b128 v[158:161], v157 offset:3072
	v_add_u32_e32 v157, s69, v152
	ds_read_b128 v[162:165], v157
	ds_read_b128 v[166:169], v157 offset:1024
	ds_read_b128 v[170:173], v157 offset:2048
	ds_read_b128 v[180:183], v157 offset:3072
	s_add_u32 s40, s40, 0x60000
	s_addc_u32 s41, s41, 0
	s_mov_b32 m0, s47
	v_lshl_add_u64 v[222:223], s[40:41], 0, v[130:131]
	ds_read_b128 v[184:187], v156 offset:32768
	ds_read_b128 v[188:191], v156 offset:33792
	ds_read_b128 v[192:195], v156 offset:34816
	ds_read_b128 v[196:199], v156 offset:35840
	ds_read_b128 v[200:203], v156 offset:36864
	ds_read_b128 v[206:209], v156 offset:37888
	ds_read_b128 v[210:213], v156 offset:38912
	ds_read_b128 v[214:217], v156 offset:39936
	global_load_lds_dwordx4 v[222:223], off
	v_lshl_add_u64 v[222:223], s[40:41], 0, v[128:129]
	s_mov_b32 m0, s48
	s_nop 0
	global_load_lds_dwordx4 v[222:223], off
	s_waitcnt vmcnt(8)
	s_waitcnt lgkmcnt(0)
	s_barrier
	s_setprio 1
	s_waitcnt lgkmcnt(0)
	v_mfma_f32_16x16x32_bf16 v[124:127], v[136:139], v[184:187], v[124:127]
	v_mfma_f32_16x16x32_bf16 v[120:123], v[144:147], v[184:187], v[120:123]
	v_mfma_f32_16x16x32_bf16 v[112:115], v[136:139], v[192:195], v[112:115]
	v_mfma_f32_16x16x32_bf16 v[104:107], v[144:147], v[192:195], v[104:107]
	v_mfma_f32_16x16x32_bf16 v[96:99], v[136:139], v[200:203], v[96:99]
	v_mfma_f32_16x16x32_bf16 v[88:91], v[144:147], v[200:203], v[88:91]
	v_mfma_f32_16x16x32_bf16 v[80:83], v[136:139], v[210:213], v[80:83]
	v_mfma_f32_16x16x32_bf16 v[72:75], v[144:147], v[210:213], v[72:75]
	v_mfma_f32_16x16x32_bf16 v[124:127], v[140:143], v[188:191], v[124:127]
	v_mfma_f32_16x16x32_bf16 v[120:123], v[158:161], v[188:191], v[120:123]
	v_mfma_f32_16x16x32_bf16 v[112:115], v[140:143], v[196:199], v[112:115]
	v_mfma_f32_16x16x32_bf16 v[104:107], v[158:161], v[196:199], v[104:107]
	v_mfma_f32_16x16x32_bf16 v[96:99], v[140:143], v[206:209], v[96:99]
	v_mfma_f32_16x16x32_bf16 v[88:91], v[158:161], v[206:209], v[88:91]
	v_mfma_f32_16x16x32_bf16 v[80:83], v[140:143], v[214:217], v[80:83]
	v_mfma_f32_16x16x32_bf16 v[72:75], v[158:161], v[214:217], v[72:75]
	s_setprio 0
	s_setprio 1
	v_mfma_f32_16x16x32_bf16 v[116:119], v[162:165], v[184:187], v[116:119]
	v_mfma_f32_16x16x32_bf16 v[108:111], v[170:173], v[184:187], v[108:111]
	v_mfma_f32_16x16x32_bf16 v[100:103], v[162:165], v[192:195], v[100:103]
	v_mfma_f32_16x16x32_bf16 v[92:95], v[170:173], v[192:195], v[92:95]
	v_mfma_f32_16x16x32_bf16 v[84:87], v[162:165], v[200:203], v[84:87]
	v_mfma_f32_16x16x32_bf16 v[76:79], v[170:173], v[200:203], v[76:79]
	v_mfma_f32_16x16x32_bf16 v[68:71], v[162:165], v[210:213], v[68:71]
	v_mfma_f32_16x16x32_bf16 v[64:67], v[170:173], v[210:213], v[64:67]
	v_mfma_f32_16x16x32_bf16 v[116:119], v[166:169], v[188:191], v[116:119]
	v_mfma_f32_16x16x32_bf16 v[108:111], v[180:183], v[188:191], v[108:111]
	v_mfma_f32_16x16x32_bf16 v[100:103], v[166:169], v[196:199], v[100:103]
	v_mfma_f32_16x16x32_bf16 v[92:95], v[180:183], v[196:199], v[92:95]
	v_mfma_f32_16x16x32_bf16 v[84:87], v[166:169], v[206:209], v[84:87]
	v_mfma_f32_16x16x32_bf16 v[76:79], v[180:183], v[206:209], v[76:79]
	v_mfma_f32_16x16x32_bf16 v[68:71], v[166:169], v[214:217], v[68:71]
	v_mfma_f32_16x16x32_bf16 v[64:67], v[180:183], v[214:217], v[64:67]
	s_setprio 0
	s_barrier
	s_add_i32 s40, s68, s44
	v_lshl_add_u64 v[148:149], v[148:149], 0, s[16:17]
	s_mov_b32 m0, s40
	ds_read_b128 v[184:187], v156 offset:49152
	ds_read_b128 v[188:191], v156 offset:50176
	ds_read_b128 v[192:195], v156 offset:51200
	ds_read_b128 v[196:199], v156 offset:52224
	ds_read_b128 v[200:203], v156 offset:53248
	ds_read_b128 v[206:209], v156 offset:54272
	ds_read_b128 v[210:213], v156 offset:55296
	ds_read_b128 v[214:217], v156 offset:56320
	global_load_lds_dwordx4 v[148:149], off
	s_add_i32 m0, s40, 0x2000
	s_add_u32 s38, s38, 0x60080
	v_lshl_add_u64 v[148:149], v[174:175], 0, s[16:17]
	s_addc_u32 s39, s39, 0
	s_add_i32 s40, s69, s44
	global_load_lds_dwordx4 v[148:149], off
	v_lshl_add_u64 v[148:149], s[38:39], 0, v[130:131]
	s_mov_b32 m0, s40
	s_nop 0
	global_load_lds_dwordx4 v[148:149], off
	v_lshl_add_u64 v[148:149], s[38:39], 0, v[128:129]
	s_add_i32 m0, s40, 0x2000
	s_nop 0
	global_load_lds_dwordx4 v[148:149], off
	v_lshl_add_u64 v[148:149], v[218:219], 0, s[16:17]
	s_mov_b32 m0, s49
	s_nop 0
	global_load_lds_dwordx4 v[148:149], off
	v_lshl_add_u64 v[148:149], v[220:221], 0, s[16:17]
	s_mov_b32 m0, s50
	s_nop 0
	global_load_lds_dwordx4 v[148:149], off
	s_waitcnt vmcnt(8)
	s_waitcnt lgkmcnt(0)
	s_barrier
	s_setprio 1
	s_waitcnt lgkmcnt(0)
	v_mfma_f32_16x16x32_bf16 v[60:63], v[136:139], v[184:187], v[60:63]
	v_mfma_f32_16x16x32_bf16 v[56:59], v[144:147], v[184:187], v[56:59]
	v_mfma_f32_16x16x32_bf16 v[48:51], v[136:139], v[192:195], v[48:51]
	v_mfma_f32_16x16x32_bf16 v[40:43], v[144:147], v[192:195], v[40:43]
	v_mfma_f32_16x16x32_bf16 v[32:35], v[136:139], v[200:203], v[32:35]
	v_mfma_f32_16x16x32_bf16 v[24:27], v[144:147], v[200:203], v[24:27]
	v_mfma_f32_16x16x32_bf16 v[16:19], v[136:139], v[210:213], v[16:19]
	v_mfma_f32_16x16x32_bf16 v[8:11], v[144:147], v[210:213], v[8:11]
	v_mfma_f32_16x16x32_bf16 v[60:63], v[140:143], v[188:191], v[60:63]
	v_mfma_f32_16x16x32_bf16 v[56:59], v[158:161], v[188:191], v[56:59]
	v_mfma_f32_16x16x32_bf16 v[48:51], v[140:143], v[196:199], v[48:51]
	v_mfma_f32_16x16x32_bf16 v[40:43], v[158:161], v[196:199], v[40:43]
	v_mfma_f32_16x16x32_bf16 v[32:35], v[140:143], v[206:209], v[32:35]
	v_mfma_f32_16x16x32_bf16 v[24:27], v[158:161], v[206:209], v[24:27]
	v_mfma_f32_16x16x32_bf16 v[16:19], v[140:143], v[214:217], v[16:19]
	v_mfma_f32_16x16x32_bf16 v[8:11], v[158:161], v[214:217], v[8:11]
	s_setprio 0
	s_setprio 1
	v_mfma_f32_16x16x32_bf16 v[52:55], v[162:165], v[184:187], v[52:55]
	v_mfma_f32_16x16x32_bf16 v[44:47], v[170:173], v[184:187], v[44:47]
	v_mfma_f32_16x16x32_bf16 v[36:39], v[162:165], v[192:195], v[36:39]
	v_mfma_f32_16x16x32_bf16 v[28:31], v[170:173], v[192:195], v[28:31]
	v_mfma_f32_16x16x32_bf16 v[20:23], v[162:165], v[200:203], v[20:23]
	v_mfma_f32_16x16x32_bf16 v[12:15], v[170:173], v[200:203], v[12:15]
	v_mfma_f32_16x16x32_bf16 v[4:7], v[162:165], v[210:213], v[4:7]
	v_mfma_f32_16x16x32_bf16 v[0:3], v[170:173], v[210:213], v[0:3]
	v_mfma_f32_16x16x32_bf16 v[52:55], v[166:169], v[188:191], v[52:55]
	v_mfma_f32_16x16x32_bf16 v[44:47], v[180:183], v[188:191], v[44:47]
	v_mfma_f32_16x16x32_bf16 v[36:39], v[166:169], v[196:199], v[36:39]
	v_mfma_f32_16x16x32_bf16 v[28:31], v[180:183], v[196:199], v[28:31]
	v_mfma_f32_16x16x32_bf16 v[20:23], v[166:169], v[206:209], v[20:23]
	v_mfma_f32_16x16x32_bf16 v[12:15], v[180:183], v[206:209], v[12:15]
	v_mfma_f32_16x16x32_bf16 v[4:7], v[166:169], v[214:217], v[4:7]
	v_mfma_f32_16x16x32_bf16 v[0:3], v[180:183], v[214:217], v[0:3]
	s_setprio 0
	s_barrier
	s_add_i32 s67, s67, 2
	s_add_u32 s36, s36, 0x100
	s_addc_u32 s37, s37, 0
	s_add_u32 s65, s65, 0x100
	s_addc_u32 s66, s66, 0
	s_cmp_gt_u32 s67, 5
	s_cbranch_scc0 .LBB0_2065
	s_and_b64 vcc, exec, s[18:19]
	s_cbranch_vccz .LBB0_2068
	s_barrier
.LBB0_2068:
	s_ashr_i32 s36, s64, 31
	s_lshr_b32 s36, s36, 22
	s_add_i32 s40, s64, s36
	s_and_b32 s36, s40, 0xfffffc00
	v_lshl_add_u32 v138, s63, 8, v151
	v_lshl_or_b32 v136, s62, 8, v153
	s_ashr_i32 s37, s36, 31
	v_mov_b64_e32 v[140:141], s[0:1]
	v_ashrrev_i32_e32 v137, 31, v136
	v_mad_i64_i32 v[142:143], s[38:39], v138, s54, v[140:141]
	s_lshl_b64 s[36:37], s[36:37], 1
	v_lshl_add_u64 v[144:145], v[142:143], 0, s[36:37]
	v_lshlrev_b64 v[142:143], 1, v[136:137]
	v_lshl_add_u64 v[144:145], v[144:145], 0, v[142:143]
	v_or_b32_e32 v139, 16, v138
	global_load_dwordx2 v[158:159], v[144:145], off offset:3584
	global_load_dwordx2 v[160:161], v[144:145], off offset:3616
	global_load_dwordx2 v[162:163], v[144:145], off offset:3840
	global_load_dwordx2 v[164:165], v[144:145], off offset:3872
	v_mad_i64_i32 v[144:145], s[38:39], v139, s54, v[140:141]
	v_lshl_add_u64 v[144:145], v[144:145], 0, s[36:37]
	v_lshl_add_u64 v[144:145], v[144:145], 0, v[142:143]
	v_or_b32_e32 v139, 32, v138
	global_load_dwordx2 v[166:167], v[144:145], off offset:3584
	global_load_dwordx2 v[168:169], v[144:145], off offset:3616
	global_load_dwordx2 v[170:171], v[144:145], off offset:3840
	global_load_dwordx2 v[172:173], v[144:145], off offset:3872
	v_mad_i64_i32 v[144:145], s[38:39], v139, s54, v[140:141]
	v_lshl_add_u64 v[144:145], v[144:145], 0, s[36:37]
	v_lshl_add_u64 v[144:145], v[144:145], 0, v[142:143]
	v_or_b32_e32 v139, 48, v138
	global_load_dwordx2 v[174:175], v[144:145], off offset:3584
	global_load_dwordx2 v[180:181], v[144:145], off offset:3616
	global_load_dwordx2 v[182:183], v[144:145], off offset:3840
	global_load_dwordx2 v[184:185], v[144:145], off offset:3872
	v_mad_i64_i32 v[144:145], s[38:39], v139, s54, v[140:141]
	v_lshl_add_u64 v[144:145], v[144:145], 0, s[36:37]
	v_lshl_add_u64 v[144:145], v[144:145], 0, v[142:143]
	global_load_dwordx2 v[186:187], v[144:145], off offset:3584
	global_load_dwordx2 v[148:149], v[144:145], off offset:3616
	global_load_dwordx2 v[146:147], v[144:145], off offset:3840
	s_nop 0
	global_load_dwordx2 v[144:145], v[144:145], off offset:3872
	s_ashr_i32 s38, s40, 10
	s_ashr_i32 s39, s38, 31
	v_ashrrev_i32_e32 v139, 31, v138
	v_lshlrev_b64 v[188:189], 12, v[138:139]
	s_lshl_b64 s[38:39], s[38:39], 21
	v_lshl_add_u64 v[188:189], v[188:189], 0, s[38:39]
	v_lshl_add_u64 v[188:189], v[188:189], 0, s[20:21]
	v_lshl_add_u64 v[190:191], s[14:15], 0, v[188:189]
	v_lshlrev_b64 v[192:193], 2, v[136:137]
	v_lshl_add_u64 v[136:137], v[190:191], 0, v[192:193]
	s_waitcnt vmcnt(0)
	v_lshlrev_b32_e32 v190, 16, v158
	v_and_b32_e32 v191, 0xffff0000, v158
	v_lshlrev_b32_e32 v158, 16, v159
	v_and_b32_e32 v159, 0xffff0000, v159
	v_pk_mul_f32 v[124:125], v[124:125], v[190:191]
	v_pk_mul_f32 v[126:127], v[126:127], v[158:159]
	global_store_dwordx4 v[136:137], v[124:127], off
	s_nop 1
	v_lshlrev_b32_e32 v124, 16, v160
	v_and_b32_e32 v125, 0xffff0000, v160
	v_pk_mul_f32 v[120:121], v[120:121], v[124:125]
	v_lshlrev_b32_e32 v124, 16, v161
	v_and_b32_e32 v125, 0xffff0000, v161
	v_pk_mul_f32 v[122:123], v[122:123], v[124:125]
	global_store_dwordx4 v[136:137], v[120:123], off offset:64
	s_nop 1
	v_lshlrev_b32_e32 v120, 16, v162
	v_and_b32_e32 v121, 0xffff0000, v162
	v_pk_mul_f32 v[116:117], v[116:117], v[120:121]
	v_lshlrev_b32_e32 v120, 16, v163
	v_and_b32_e32 v121, 0xffff0000, v163
	v_pk_mul_f32 v[118:119], v[118:119], v[120:121]
	global_store_dwordx4 v[136:137], v[116:119], off offset:512
	s_nop 1
	v_lshlrev_b32_e32 v116, 16, v164
	v_and_b32_e32 v117, 0xffff0000, v164
	v_pk_mul_f32 v[108:109], v[108:109], v[116:117]
	v_lshlrev_b32_e32 v116, 16, v165
	v_and_b32_e32 v117, 0xffff0000, v165
	v_pk_mul_f32 v[110:111], v[110:111], v[116:117]
	global_store_dwordx4 v[136:137], v[108:111], off offset:576
	s_nop 1
	v_or_b32_e32 v108, 0x10000, v188
	v_mov_b32_e32 v109, v189
	v_lshl_add_u64 v[108:109], s[14:15], 0, v[108:109]
	v_lshl_add_u64 v[116:117], v[108:109], 0, v[192:193]
	v_lshlrev_b32_e32 v108, 16, v166
	v_and_b32_e32 v109, 0xffff0000, v166
	v_lshlrev_b32_e32 v110, 16, v167
	v_and_b32_e32 v111, 0xffff0000, v167
	v_pk_mul_f32 v[108:109], v[112:113], v[108:109]
	v_pk_mul_f32 v[110:111], v[114:115], v[110:111]
	global_store_dwordx4 v[116:117], v[108:111], off
	s_nop 1
	v_lshlrev_b32_e32 v108, 16, v168
	v_and_b32_e32 v109, 0xffff0000, v168
	v_pk_mul_f32 v[104:105], v[104:105], v[108:109]
	v_lshlrev_b32_e32 v108, 16, v169
	v_and_b32_e32 v109, 0xffff0000, v169
	v_pk_mul_f32 v[106:107], v[106:107], v[108:109]
	global_store_dwordx4 v[116:117], v[104:107], off offset:64
	s_nop 1
	v_lshlrev_b32_e32 v104, 16, v170
	v_and_b32_e32 v105, 0xffff0000, v170
	v_pk_mul_f32 v[100:101], v[100:101], v[104:105]
	v_lshlrev_b32_e32 v104, 16, v171
	v_and_b32_e32 v105, 0xffff0000, v171
	v_pk_mul_f32 v[102:103], v[102:103], v[104:105]
	global_store_dwordx4 v[116:117], v[100:103], off offset:512
	s_nop 1
	v_lshlrev_b32_e32 v100, 16, v172
	v_and_b32_e32 v101, 0xffff0000, v172
	v_pk_mul_f32 v[92:93], v[92:93], v[100:101]
	v_lshlrev_b32_e32 v100, 16, v173
	v_and_b32_e32 v101, 0xffff0000, v173
	v_pk_mul_f32 v[94:95], v[94:95], v[100:101]
	global_store_dwordx4 v[116:117], v[92:95], off offset:576
	s_nop 1
	v_or_b32_e32 v92, 0x20000, v188
	v_mov_b32_e32 v93, v189
	v_lshl_add_u64 v[92:93], s[14:15], 0, v[92:93]
	v_lshl_add_u64 v[100:101], v[92:93], 0, v[192:193]
	v_lshlrev_b32_e32 v92, 16, v174
	v_and_b32_e32 v93, 0xffff0000, v174
	v_lshlrev_b32_e32 v94, 16, v175
	v_and_b32_e32 v95, 0xffff0000, v175
	v_pk_mul_f32 v[92:93], v[96:97], v[92:93]
	v_pk_mul_f32 v[94:95], v[98:99], v[94:95]
	global_store_dwordx4 v[100:101], v[92:95], off
	v_or_b32_e32 v188, 0x30000, v188
	s_nop 0
	v_lshlrev_b32_e32 v92, 16, v180
	v_and_b32_e32 v93, 0xffff0000, v180
	v_pk_mul_f32 v[88:89], v[88:89], v[92:93]
	v_lshlrev_b32_e32 v92, 16, v181
	v_and_b32_e32 v93, 0xffff0000, v181
	v_pk_mul_f32 v[90:91], v[90:91], v[92:93]
	global_store_dwordx4 v[100:101], v[88:91], off offset:64
	s_nop 1
	v_lshlrev_b32_e32 v88, 16, v182
	v_and_b32_e32 v89, 0xffff0000, v182
	v_pk_mul_f32 v[84:85], v[84:85], v[88:89]
	v_lshlrev_b32_e32 v88, 16, v183
	v_and_b32_e32 v89, 0xffff0000, v183
	v_pk_mul_f32 v[86:87], v[86:87], v[88:89]
	global_store_dwordx4 v[100:101], v[84:87], off offset:512
	s_nop 1
	v_lshlrev_b32_e32 v84, 16, v184
	v_and_b32_e32 v85, 0xffff0000, v184
	v_pk_mul_f32 v[76:77], v[76:77], v[84:85]
	v_lshlrev_b32_e32 v84, 16, v185
	v_and_b32_e32 v85, 0xffff0000, v185
	v_pk_mul_f32 v[78:79], v[78:79], v[84:85]
	global_store_dwordx4 v[100:101], v[76:79], off offset:576
	s_nop 1
	v_lshl_add_u64 v[76:77], s[14:15], 0, v[188:189]
	v_lshl_add_u64 v[84:85], v[76:77], 0, v[192:193]
	v_lshlrev_b32_e32 v76, 16, v186
	v_and_b32_e32 v77, 0xffff0000, v186
	v_lshlrev_b32_e32 v78, 16, v187
	v_and_b32_e32 v79, 0xffff0000, v187
	v_pk_mul_f32 v[76:77], v[80:81], v[76:77]
	v_pk_mul_f32 v[78:79], v[82:83], v[78:79]
	global_store_dwordx4 v[84:85], v[76:79], off
	s_nop 1
	v_lshlrev_b32_e32 v76, 16, v148
	v_and_b32_e32 v77, 0xffff0000, v148
	v_pk_mul_f32 v[72:73], v[72:73], v[76:77]
	v_lshlrev_b32_e32 v76, 16, v149
	v_and_b32_e32 v77, 0xffff0000, v149
	v_pk_mul_f32 v[74:75], v[74:75], v[76:77]
	global_store_dwordx4 v[84:85], v[72:75], off offset:64
	s_nop 1
	v_lshlrev_b32_e32 v72, 16, v146
	v_and_b32_e32 v73, 0xffff0000, v146
	v_pk_mul_f32 v[68:69], v[68:69], v[72:73]
	v_lshlrev_b32_e32 v72, 16, v147
	v_and_b32_e32 v73, 0xffff0000, v147
	v_pk_mul_f32 v[70:71], v[70:71], v[72:73]
	global_store_dwordx4 v[84:85], v[68:71], off offset:512
	s_nop 1
	v_lshlrev_b32_e32 v68, 16, v144
	v_and_b32_e32 v69, 0xffff0000, v144
	v_pk_mul_f32 v[64:65], v[64:65], v[68:69]
	v_lshlrev_b32_e32 v68, 16, v145
	v_and_b32_e32 v69, 0xffff0000, v145
	v_pk_mul_f32 v[66:67], v[66:67], v[68:69]
	global_store_dwordx4 v[84:85], v[64:67], off offset:576
	s_nop 1
	v_add_u32_e32 v64, 0x80, v138
	v_mad_i64_i32 v[64:65], s[38:39], v64, s54, v[140:141]
	v_lshl_add_u64 v[64:65], v[64:65], 0, s[36:37]
	v_lshl_add_u64 v[64:65], v[64:65], 0, v[142:143]
	global_load_dwordx2 v[68:69], v[64:65], off offset:3584
	global_load_dwordx2 v[70:71], v[64:65], off offset:3616
	global_load_dwordx2 v[72:73], v[64:65], off offset:3840
	global_load_dwordx2 v[74:75], v[64:65], off offset:3872
	v_add_u32_e32 v64, 0x90, v138
	v_mad_i64_i32 v[64:65], s[38:39], v64, s54, v[140:141]
	v_lshl_add_u64 v[64:65], v[64:65], 0, s[36:37]
	v_lshl_add_u64 v[64:65], v[64:65], 0, v[142:143]
	global_load_dwordx2 v[76:77], v[64:65], off offset:3584
	global_load_dwordx2 v[78:79], v[64:65], off offset:3616
	global_load_dwordx2 v[80:81], v[64:65], off offset:3840
	global_load_dwordx2 v[82:83], v[64:65], off offset:3872
	v_add_u32_e32 v64, 0xa0, v138
	v_mad_i64_i32 v[64:65], s[38:39], v64, s54, v[140:141]
	v_lshl_add_u64 v[64:65], v[64:65], 0, s[36:37]
	v_lshl_add_u64 v[64:65], v[64:65], 0, v[142:143]
	global_load_dwordx2 v[84:85], v[64:65], off offset:3584
	global_load_dwordx2 v[86:87], v[64:65], off offset:3616
	global_load_dwordx2 v[88:89], v[64:65], off offset:3840
	global_load_dwordx2 v[90:91], v[64:65], off offset:3872
	v_add_u32_e32 v64, 0xb0, v138
	v_mad_i64_i32 v[64:65], s[38:39], v64, s54, v[140:141]
	v_lshl_add_u64 v[64:65], v[64:65], 0, s[36:37]
	v_lshl_add_u64 v[64:65], v[64:65], 0, v[142:143]
	global_load_dwordx2 v[92:93], v[64:65], off offset:3584
	global_load_dwordx2 v[94:95], v[64:65], off offset:3616
	global_load_dwordx2 v[66:67], v[64:65], off offset:3840
	s_nop 0
	global_load_dwordx2 v[64:65], v[64:65], off offset:3872
	s_waitcnt vmcnt(15)
	v_lshlrev_b32_e32 v98, 16, v68
	v_and_b32_e32 v99, 0xffff0000, v68
	v_lshlrev_b32_e32 v68, 16, v69
	v_and_b32_e32 v69, 0xffff0000, v69
	v_pk_mul_f32 v[62:63], v[62:63], v[68:69]
	v_add_co_u32_e32 v68, vcc, s55, v136
	v_pk_mul_f32 v[60:61], v[60:61], v[98:99]
	s_nop 0
	v_addc_co_u32_e32 v69, vcc, 0, v137, vcc
	global_store_dwordx4 v[68:69], v[60:63], off
	v_lshl_add_u64 v[96:97], v[136:137], 0, s[22:23]
	s_waitcnt vmcnt(15)
	v_lshlrev_b32_e32 v60, 16, v70
	v_and_b32_e32 v61, 0xffff0000, v70
	v_pk_mul_f32 v[56:57], v[56:57], v[60:61]
	v_lshlrev_b32_e32 v60, 16, v71
	v_and_b32_e32 v61, 0xffff0000, v71
	v_pk_mul_f32 v[58:59], v[58:59], v[60:61]
	global_store_dwordx4 v[96:97], v[56:59], off offset:64
	s_waitcnt vmcnt(15)
	s_nop 0
	v_lshlrev_b32_e32 v56, 16, v72
	v_and_b32_e32 v57, 0xffff0000, v72
	v_pk_mul_f32 v[52:53], v[52:53], v[56:57]
	v_lshlrev_b32_e32 v56, 16, v73
	v_and_b32_e32 v57, 0xffff0000, v73
	v_pk_mul_f32 v[54:55], v[54:55], v[56:57]
	global_store_dwordx4 v[96:97], v[52:55], off offset:512
	s_waitcnt vmcnt(15)
	s_nop 0
	v_lshlrev_b32_e32 v52, 16, v74
	v_and_b32_e32 v53, 0xffff0000, v74
	v_pk_mul_f32 v[44:45], v[44:45], v[52:53]
	v_lshlrev_b32_e32 v52, 16, v75
	v_and_b32_e32 v53, 0xffff0000, v75
	v_pk_mul_f32 v[46:47], v[46:47], v[52:53]
	global_store_dwordx4 v[96:97], v[44:47], off offset:576
	v_lshl_add_u64 v[52:53], v[136:137], 0, s[24:25]
	s_waitcnt vmcnt(15)
	v_lshlrev_b32_e32 v44, 16, v76
	v_and_b32_e32 v45, 0xffff0000, v76
	v_pk_mul_f32 v[44:45], v[48:49], v[44:45]
	v_lshlrev_b32_e32 v46, 16, v77
	v_and_b32_e32 v47, 0xffff0000, v77
	v_add_co_u32_e32 v48, vcc, s56, v136
	v_pk_mul_f32 v[46:47], v[50:51], v[46:47]
	s_nop 0
	v_addc_co_u32_e32 v49, vcc, 0, v137, vcc
	global_store_dwordx4 v[48:49], v[44:47], off
	s_waitcnt vmcnt(15)
	s_nop 0
	v_lshlrev_b32_e32 v44, 16, v78
	v_and_b32_e32 v45, 0xffff0000, v78
	v_pk_mul_f32 v[40:41], v[40:41], v[44:45]
	v_lshlrev_b32_e32 v44, 16, v79
	v_and_b32_e32 v45, 0xffff0000, v79
	v_pk_mul_f32 v[42:43], v[42:43], v[44:45]
	global_store_dwordx4 v[52:53], v[40:43], off offset:64
	s_waitcnt vmcnt(15)
	s_nop 0
	v_lshlrev_b32_e32 v40, 16, v80
	v_and_b32_e32 v41, 0xffff0000, v80
	v_pk_mul_f32 v[36:37], v[36:37], v[40:41]
	v_lshlrev_b32_e32 v40, 16, v81
	v_and_b32_e32 v41, 0xffff0000, v81
	v_pk_mul_f32 v[38:39], v[38:39], v[40:41]
	global_store_dwordx4 v[52:53], v[36:39], off offset:512
	s_waitcnt vmcnt(15)
	s_nop 0
	v_lshlrev_b32_e32 v36, 16, v82
	v_and_b32_e32 v37, 0xffff0000, v82
	v_pk_mul_f32 v[28:29], v[28:29], v[36:37]
	v_lshlrev_b32_e32 v36, 16, v83
	v_and_b32_e32 v37, 0xffff0000, v83
	v_pk_mul_f32 v[30:31], v[30:31], v[36:37]
	global_store_dwordx4 v[52:53], v[28:31], off offset:576
	v_lshl_add_u64 v[36:37], v[136:137], 0, s[26:27]
	s_waitcnt vmcnt(15)
	v_lshlrev_b32_e32 v28, 16, v84
	v_and_b32_e32 v29, 0xffff0000, v84
	v_pk_mul_f32 v[28:29], v[32:33], v[28:29]
	v_lshlrev_b32_e32 v30, 16, v85
	v_and_b32_e32 v31, 0xffff0000, v85
	v_add_co_u32_e32 v32, vcc, s57, v136
	v_pk_mul_f32 v[30:31], v[34:35], v[30:31]
	s_nop 0
	v_addc_co_u32_e32 v33, vcc, 0, v137, vcc
	global_store_dwordx4 v[32:33], v[28:31], off
	s_waitcnt vmcnt(15)
	s_nop 0
	v_lshlrev_b32_e32 v28, 16, v86
	v_and_b32_e32 v29, 0xffff0000, v86
	v_pk_mul_f32 v[24:25], v[24:25], v[28:29]
	v_lshlrev_b32_e32 v28, 16, v87
	v_and_b32_e32 v29, 0xffff0000, v87
	v_pk_mul_f32 v[26:27], v[26:27], v[28:29]
	global_store_dwordx4 v[36:37], v[24:27], off offset:64
	s_waitcnt vmcnt(15)
	s_nop 0
	v_lshlrev_b32_e32 v24, 16, v88
	v_and_b32_e32 v25, 0xffff0000, v88
	v_pk_mul_f32 v[20:21], v[20:21], v[24:25]
	v_lshlrev_b32_e32 v24, 16, v89
	v_and_b32_e32 v25, 0xffff0000, v89
	v_pk_mul_f32 v[22:23], v[22:23], v[24:25]
	global_store_dwordx4 v[36:37], v[20:23], off offset:512
	s_waitcnt vmcnt(15)
	s_nop 0
	v_lshlrev_b32_e32 v20, 16, v90
	v_and_b32_e32 v21, 0xffff0000, v90
	v_pk_mul_f32 v[12:13], v[12:13], v[20:21]
	v_lshlrev_b32_e32 v20, 16, v91
	v_and_b32_e32 v21, 0xffff0000, v91
	v_pk_mul_f32 v[14:15], v[14:15], v[20:21]
	global_store_dwordx4 v[36:37], v[12:15], off offset:576
	v_lshl_add_u64 v[20:21], v[136:137], 0, s[28:29]
	s_waitcnt vmcnt(15)
	v_lshlrev_b32_e32 v12, 16, v92
	v_and_b32_e32 v13, 0xffff0000, v92
	v_pk_mul_f32 v[12:13], v[16:17], v[12:13]
	v_lshlrev_b32_e32 v14, 16, v93
	v_and_b32_e32 v15, 0xffff0000, v93
	v_add_co_u32_e32 v16, vcc, s58, v136
	v_pk_mul_f32 v[14:15], v[18:19], v[14:15]
	s_nop 0
	v_addc_co_u32_e32 v17, vcc, 0, v137, vcc
	global_store_dwordx4 v[16:17], v[12:15], off
	s_waitcnt vmcnt(15)
	s_nop 0
	v_lshlrev_b32_e32 v12, 16, v94
	v_and_b32_e32 v13, 0xffff0000, v94
	v_pk_mul_f32 v[8:9], v[8:9], v[12:13]
	v_lshlrev_b32_e32 v12, 16, v95
	v_and_b32_e32 v13, 0xffff0000, v95
	v_pk_mul_f32 v[10:11], v[10:11], v[12:13]
	global_store_dwordx4 v[20:21], v[8:11], off offset:64
	s_waitcnt vmcnt(15)
	s_nop 0
	v_lshlrev_b32_e32 v8, 16, v66
	v_and_b32_e32 v9, 0xffff0000, v66
	v_pk_mul_f32 v[4:5], v[4:5], v[8:9]
	v_lshlrev_b32_e32 v8, 16, v67
	v_and_b32_e32 v9, 0xffff0000, v67
	v_pk_mul_f32 v[6:7], v[6:7], v[8:9]
	global_store_dwordx4 v[20:21], v[4:7], off offset:512
	s_waitcnt vmcnt(15)
	s_nop 0
	v_lshlrev_b32_e32 v4, 16, v64
	v_and_b32_e32 v5, 0xffff0000, v64
	v_pk_mul_f32 v[0:1], v[0:1], v[4:5]
	v_lshlrev_b32_e32 v4, 16, v65
	v_and_b32_e32 v5, 0xffff0000, v65
	v_pk_mul_f32 v[2:3], v[2:3], v[4:5]
	global_store_dwordx4 v[20:21], v[0:3], off offset:576
	s_and_b64 vcc, exec, s[2:3]
	s_mov_b64 s[2:3], -1
	s_cbranch_vccnz .LBB0_2057
	s_andn2_b64 vcc, exec, s[10:11]
	s_cbranch_vccnz .LBB0_2056
	v_writelane_b32 v255, 1, 53
	s_branch .LBB0_2056

.Llsb_skip_18:
	s_branch .LBB0_2156
.LBB0_2155:
	v_add_u32_e32 v140, s50, v195
	v_add_u32_e32 v156, s51, v195
	s_add_u32 s6, s24, s26
	ds_read_b128 v[128:131], v140
	ds_read_b128 v[132:135], v140 offset:1024
	ds_read_b128 v[136:139], v140 offset:2048
	ds_read_b128 v[140:143], v140 offset:3072
	ds_read_b128 v[144:147], v156
	ds_read_b128 v[148:151], v156 offset:1024
	ds_read_b128 v[152:155], v156 offset:2048
	ds_read_b128 v[156:159], v156 offset:3072
	s_addc_u32 s28, s25, s27
	s_add_u32 s6, s6, 0x100
	s_addc_u32 s28, s28, 0
	s_add_u32 s63, s60, s26
	s_addc_u32 s29, s61, s27
	s_cmpk_eq_i32 s26, 0xb00
	s_cselect_b32 s31, s5, s28
	s_cselect_b32 s30, s4, s6
	s_cselect_b32 s29, s23, s29
	s_cselect_b32 s28, s22, s63
	v_lshl_add_u64 v[202:203], v[184:185], 0, s[26:27]
	s_add_i32 m0, s40, 0xc000
	ds_read_b128 v[160:163], v197
	ds_read_b128 v[164:167], v197 offset:1024
	ds_read_b128 v[188:191], v197 offset:2048
	ds_read_b128 v[198:201], v197 offset:3072
	ds_read_b128 v[206:209], v197 offset:4096
	ds_read_b128 v[210:213], v197 offset:5120
	ds_read_b128 v[214:217], v197 offset:6144
	ds_read_b128 v[218:221], v197 offset:7168
	global_load_lds_dwordx4 v[202:203], off
	v_lshl_add_u64 v[202:203], v[186:187], 0, s[26:27]
	s_add_i32 m0, s40, 0xe000
	s_nop 0
	global_load_lds_dwordx4 v[202:203], off
	s_waitcnt vmcnt(8)
	s_waitcnt lgkmcnt(0)
	s_barrier
	s_setprio 1
	s_waitcnt lgkmcnt(0)
	v_mfma_f32_16x16x32_bf16 v[124:127], v[128:131], v[160:163], v[124:127]
	v_mfma_f32_16x16x32_bf16 v[120:123], v[136:139], v[160:163], v[120:123]
	v_mfma_f32_16x16x32_bf16 v[108:111], v[128:131], v[188:191], v[108:111]
	v_mfma_f32_16x16x32_bf16 v[104:107], v[136:139], v[188:191], v[104:107]
	v_mfma_f32_16x16x32_bf16 v[92:95], v[128:131], v[206:209], v[92:95]
	v_mfma_f32_16x16x32_bf16 v[88:91], v[136:139], v[206:209], v[88:91]
	v_mfma_f32_16x16x32_bf16 v[76:79], v[128:131], v[214:217], v[76:79]
	v_mfma_f32_16x16x32_bf16 v[72:75], v[136:139], v[214:217], v[72:75]
	v_mfma_f32_16x16x32_bf16 v[124:127], v[132:135], v[164:167], v[124:127]
	v_mfma_f32_16x16x32_bf16 v[120:123], v[140:143], v[164:167], v[120:123]
	v_mfma_f32_16x16x32_bf16 v[108:111], v[132:135], v[198:201], v[108:111]
	v_mfma_f32_16x16x32_bf16 v[104:107], v[140:143], v[198:201], v[104:107]
	v_mfma_f32_16x16x32_bf16 v[92:95], v[132:135], v[210:213], v[92:95]
	v_mfma_f32_16x16x32_bf16 v[88:91], v[140:143], v[210:213], v[88:91]
	v_mfma_f32_16x16x32_bf16 v[76:79], v[132:135], v[218:221], v[76:79]
	v_mfma_f32_16x16x32_bf16 v[72:75], v[140:143], v[218:221], v[72:75]
	s_setprio 0
	s_setprio 1
	v_mfma_f32_16x16x32_bf16 v[116:119], v[144:147], v[160:163], v[116:119]
	v_mfma_f32_16x16x32_bf16 v[112:115], v[152:155], v[160:163], v[112:115]
	v_mfma_f32_16x16x32_bf16 v[100:103], v[144:147], v[188:191], v[100:103]
	v_mfma_f32_16x16x32_bf16 v[96:99], v[152:155], v[188:191], v[96:99]
	v_mfma_f32_16x16x32_bf16 v[84:87], v[144:147], v[206:209], v[84:87]
	v_mfma_f32_16x16x32_bf16 v[80:83], v[152:155], v[206:209], v[80:83]
	v_mfma_f32_16x16x32_bf16 v[68:71], v[144:147], v[214:217], v[68:71]
	v_mfma_f32_16x16x32_bf16 v[64:67], v[152:155], v[214:217], v[64:67]
	v_mfma_f32_16x16x32_bf16 v[116:119], v[148:151], v[164:167], v[116:119]
	v_mfma_f32_16x16x32_bf16 v[112:115], v[156:159], v[164:167], v[112:115]
	v_mfma_f32_16x16x32_bf16 v[100:103], v[148:151], v[198:201], v[100:103]
	v_mfma_f32_16x16x32_bf16 v[96:99], v[156:159], v[198:201], v[96:99]
	v_mfma_f32_16x16x32_bf16 v[84:87], v[148:151], v[210:213], v[84:87]
	v_mfma_f32_16x16x32_bf16 v[80:83], v[156:159], v[210:213], v[80:83]
	v_mfma_f32_16x16x32_bf16 v[68:71], v[148:151], v[218:221], v[68:71]
	v_mfma_f32_16x16x32_bf16 v[64:67], v[156:159], v[218:221], v[64:67]
	s_setprio 0
	s_barrier
	s_add_i32 s6, s50, s39
	v_lshl_add_u64 v[202:203], s[28:29], 0, v[170:171]
	s_mov_b32 m0, s6
	ds_read_b128 v[160:163], v197 offset:16384
	ds_read_b128 v[164:167], v197 offset:17408
	ds_read_b128 v[188:191], v197 offset:18432
	ds_read_b128 v[198:201], v197 offset:19456
	ds_read_b128 v[206:209], v197 offset:20480
	ds_read_b128 v[210:213], v197 offset:21504
	ds_read_b128 v[214:217], v197 offset:22528
	ds_read_b128 v[218:221], v197 offset:23552
	global_load_lds_dwordx4 v[202:203], off
	s_add_i32 m0, s6, 0x2000
	s_add_u32 s64, s28, 0x60000
	v_lshl_add_u64 v[222:223], s[28:29], 0, v[174:175]
	s_addc_u32 s65, s29, 0
	s_add_i32 s6, s51, s39
	global_load_lds_dwordx4 v[222:223], off
	v_lshl_add_u64 v[224:225], s[64:65], 0, v[170:171]
	s_mov_b32 m0, s6
	v_lshl_add_u64 v[226:227], s[30:31], 0, v[172:173]
	global_load_lds_dwordx4 v[224:225], off
	v_lshl_add_u64 v[224:225], s[64:65], 0, v[174:175]
	s_add_i32 m0, s6, 0x2000
	s_nop 0
	global_load_lds_dwordx4 v[224:225], off
	v_lshl_add_u64 v[224:225], s[30:31], 0, v[168:169]
	s_mov_b32 m0, s40
	s_nop 0
	global_load_lds_dwordx4 v[224:225], off
	s_mov_b32 m0, s41
	s_nop 0
	global_load_lds_dwordx4 v[226:227], off
	s_waitcnt vmcnt(8)
	s_waitcnt lgkmcnt(0)
	s_barrier
	s_setprio 1
	s_waitcnt lgkmcnt(0)
	v_mfma_f32_16x16x32_bf16 v[60:63], v[128:131], v[160:163], v[60:63]
	v_mfma_f32_16x16x32_bf16 v[56:59], v[136:139], v[160:163], v[56:59]
	v_mfma_f32_16x16x32_bf16 v[44:47], v[128:131], v[188:191], v[44:47]
	v_mfma_f32_16x16x32_bf16 v[40:43], v[136:139], v[188:191], v[40:43]
	v_mfma_f32_16x16x32_bf16 v[28:31], v[128:131], v[206:209], v[28:31]
	v_mfma_f32_16x16x32_bf16 v[24:27], v[136:139], v[206:209], v[24:27]
	v_mfma_f32_16x16x32_bf16 v[12:15], v[128:131], v[214:217], v[12:15]
	v_mfma_f32_16x16x32_bf16 v[8:11], v[136:139], v[214:217], v[8:11]
	v_mfma_f32_16x16x32_bf16 v[60:63], v[132:135], v[164:167], v[60:63]
	v_mfma_f32_16x16x32_bf16 v[56:59], v[140:143], v[164:167], v[56:59]
	v_mfma_f32_16x16x32_bf16 v[44:47], v[132:135], v[198:201], v[44:47]
	v_mfma_f32_16x16x32_bf16 v[40:43], v[140:143], v[198:201], v[40:43]
	v_mfma_f32_16x16x32_bf16 v[28:31], v[132:135], v[210:213], v[28:31]
	v_mfma_f32_16x16x32_bf16 v[24:27], v[140:143], v[210:213], v[24:27]
	v_mfma_f32_16x16x32_bf16 v[12:15], v[132:135], v[218:221], v[12:15]
	v_mfma_f32_16x16x32_bf16 v[8:11], v[140:143], v[218:221], v[8:11]
	s_setprio 0
	s_setprio 1
	v_mfma_f32_16x16x32_bf16 v[52:55], v[144:147], v[160:163], v[52:55]
	v_mfma_f32_16x16x32_bf16 v[48:51], v[152:155], v[160:163], v[48:51]
	v_mfma_f32_16x16x32_bf16 v[36:39], v[144:147], v[188:191], v[36:39]
	v_mfma_f32_16x16x32_bf16 v[32:35], v[152:155], v[188:191], v[32:35]
	v_mfma_f32_16x16x32_bf16 v[20:23], v[144:147], v[206:209], v[20:23]
	v_mfma_f32_16x16x32_bf16 v[16:19], v[152:155], v[206:209], v[16:19]
	v_mfma_f32_16x16x32_bf16 v[4:7], v[144:147], v[214:217], v[4:7]
	v_mfma_f32_16x16x32_bf16 v[0:3], v[152:155], v[214:217], v[0:3]
	v_mfma_f32_16x16x32_bf16 v[52:55], v[148:151], v[164:167], v[52:55]
	v_mfma_f32_16x16x32_bf16 v[48:51], v[156:159], v[164:167], v[48:51]
	v_mfma_f32_16x16x32_bf16 v[36:39], v[148:151], v[198:201], v[36:39]
	v_mfma_f32_16x16x32_bf16 v[32:35], v[156:159], v[198:201], v[32:35]
	v_mfma_f32_16x16x32_bf16 v[20:23], v[148:151], v[210:213], v[20:23]
	v_mfma_f32_16x16x32_bf16 v[16:19], v[156:159], v[210:213], v[16:19]
	v_mfma_f32_16x16x32_bf16 v[4:7], v[148:151], v[218:221], v[4:7]
	v_mfma_f32_16x16x32_bf16 v[0:3], v[156:159], v[218:221], v[0:3]
	s_setprio 0
	s_barrier
	s_add_i32 s6, 0, 0x18000
	s_add_i32 s63, 0, 0x1c000
	v_add_u32_e32 v140, s6, v195
	v_add_u32_e32 v156, s63, v195
	ds_read_b128 v[128:131], v140
	ds_read_b128 v[132:135], v140 offset:1024
	ds_read_b128 v[136:139], v140 offset:2048
	ds_read_b128 v[140:143], v140 offset:3072
	ds_read_b128 v[144:147], v156
	ds_read_b128 v[148:151], v156 offset:1024
	ds_read_b128 v[152:155], v156 offset:2048
	ds_read_b128 v[156:159], v156 offset:3072
	s_add_u32 s30, s30, 0x60000
	s_addc_u32 s31, s31, 0
	s_mov_b32 m0, s42
	v_lshl_add_u64 v[228:229], s[30:31], 0, v[168:169]
	ds_read_b128 v[160:163], v197 offset:32768
	ds_read_b128 v[164:167], v197 offset:33792
	ds_read_b128 v[188:191], v197 offset:34816
	ds_read_b128 v[198:201], v197 offset:35840
	ds_read_b128 v[206:209], v197 offset:36864
	ds_read_b128 v[210:213], v197 offset:37888
	ds_read_b128 v[214:217], v197 offset:38912
	ds_read_b128 v[218:221], v197 offset:39936
	global_load_lds_dwordx4 v[228:229], off
	v_lshl_add_u64 v[228:229], s[30:31], 0, v[172:173]
	s_mov_b32 m0, s43
	s_nop 0
	global_load_lds_dwordx4 v[228:229], off
	s_waitcnt vmcnt(8)
	s_waitcnt lgkmcnt(0)
	s_barrier
	s_setprio 1
	s_waitcnt lgkmcnt(0)
	v_mfma_f32_16x16x32_bf16 v[124:127], v[128:131], v[160:163], v[124:127]
	v_mfma_f32_16x16x32_bf16 v[120:123], v[136:139], v[160:163], v[120:123]
	v_mfma_f32_16x16x32_bf16 v[108:111], v[128:131], v[188:191], v[108:111]
	v_mfma_f32_16x16x32_bf16 v[104:107], v[136:139], v[188:191], v[104:107]
	v_mfma_f32_16x16x32_bf16 v[92:95], v[128:131], v[206:209], v[92:95]
	v_mfma_f32_16x16x32_bf16 v[88:91], v[136:139], v[206:209], v[88:91]
	v_mfma_f32_16x16x32_bf16 v[76:79], v[128:131], v[214:217], v[76:79]
	v_mfma_f32_16x16x32_bf16 v[72:75], v[136:139], v[214:217], v[72:75]
	v_mfma_f32_16x16x32_bf16 v[124:127], v[132:135], v[164:167], v[124:127]
	v_mfma_f32_16x16x32_bf16 v[120:123], v[140:143], v[164:167], v[120:123]
	v_mfma_f32_16x16x32_bf16 v[108:111], v[132:135], v[198:201], v[108:111]
	v_mfma_f32_16x16x32_bf16 v[104:107], v[140:143], v[198:201], v[104:107]
	v_mfma_f32_16x16x32_bf16 v[92:95], v[132:135], v[210:213], v[92:95]
	v_mfma_f32_16x16x32_bf16 v[88:91], v[140:143], v[210:213], v[88:91]
	v_mfma_f32_16x16x32_bf16 v[76:79], v[132:135], v[218:221], v[76:79]
	v_mfma_f32_16x16x32_bf16 v[72:75], v[140:143], v[218:221], v[72:75]
	s_setprio 0
	s_setprio 1
	v_mfma_f32_16x16x32_bf16 v[116:119], v[144:147], v[160:163], v[116:119]
	v_mfma_f32_16x16x32_bf16 v[112:115], v[152:155], v[160:163], v[112:115]
	v_mfma_f32_16x16x32_bf16 v[100:103], v[144:147], v[188:191], v[100:103]
	v_mfma_f32_16x16x32_bf16 v[96:99], v[152:155], v[188:191], v[96:99]
	v_mfma_f32_16x16x32_bf16 v[84:87], v[144:147], v[206:209], v[84:87]
	v_mfma_f32_16x16x32_bf16 v[80:83], v[152:155], v[206:209], v[80:83]
	v_mfma_f32_16x16x32_bf16 v[68:71], v[144:147], v[214:217], v[68:71]
	v_mfma_f32_16x16x32_bf16 v[64:67], v[152:155], v[214:217], v[64:67]
	v_mfma_f32_16x16x32_bf16 v[116:119], v[148:151], v[164:167], v[116:119]
	v_mfma_f32_16x16x32_bf16 v[112:115], v[156:159], v[164:167], v[112:115]
	v_mfma_f32_16x16x32_bf16 v[100:103], v[148:151], v[198:201], v[100:103]
	v_mfma_f32_16x16x32_bf16 v[96:99], v[156:159], v[198:201], v[96:99]
	v_mfma_f32_16x16x32_bf16 v[84:87], v[148:151], v[210:213], v[84:87]
	v_mfma_f32_16x16x32_bf16 v[80:83], v[156:159], v[210:213], v[80:83]
	v_mfma_f32_16x16x32_bf16 v[68:71], v[148:151], v[218:221], v[68:71]
	v_mfma_f32_16x16x32_bf16 v[64:67], v[156:159], v[218:221], v[64:67]
	s_setprio 0
	s_barrier
	s_add_i32 s6, s6, s39
	v_lshl_add_u64 v[202:203], v[202:203], 0, s[14:15]
	s_mov_b32 m0, s6
	ds_read_b128 v[160:163], v197 offset:49152
	ds_read_b128 v[164:167], v197 offset:50176
	ds_read_b128 v[188:191], v197 offset:51200
	ds_read_b128 v[198:201], v197 offset:52224
	ds_read_b128 v[206:209], v197 offset:53248
	ds_read_b128 v[210:213], v197 offset:54272
	ds_read_b128 v[214:217], v197 offset:55296
	ds_read_b128 v[218:221], v197 offset:56320
	global_load_lds_dwordx4 v[202:203], off
	s_add_i32 m0, s6, 0x2000
	s_add_u32 s28, s28, 0x60080
	v_lshl_add_u64 v[202:203], v[222:223], 0, s[14:15]
	s_addc_u32 s29, s29, 0
	s_add_i32 s6, s63, s39
	global_load_lds_dwordx4 v[202:203], off
	v_lshl_add_u64 v[202:203], s[28:29], 0, v[170:171]
	s_mov_b32 m0, s6
	s_nop 0
	global_load_lds_dwordx4 v[202:203], off
	v_lshl_add_u64 v[202:203], s[28:29], 0, v[174:175]
	s_add_i32 m0, s6, 0x2000
	s_nop 0
	global_load_lds_dwordx4 v[202:203], off
	v_lshl_add_u64 v[202:203], v[224:225], 0, s[14:15]
	s_mov_b32 m0, s46
	s_nop 0
	global_load_lds_dwordx4 v[202:203], off
	v_lshl_add_u64 v[202:203], v[226:227], 0, s[14:15]
	s_mov_b32 m0, s47
	s_nop 0
	global_load_lds_dwordx4 v[202:203], off
	s_waitcnt vmcnt(8)
	s_waitcnt lgkmcnt(0)
	s_barrier
	s_setprio 1
	s_waitcnt lgkmcnt(0)
	v_mfma_f32_16x16x32_bf16 v[60:63], v[128:131], v[160:163], v[60:63]
	v_mfma_f32_16x16x32_bf16 v[56:59], v[136:139], v[160:163], v[56:59]
	v_mfma_f32_16x16x32_bf16 v[44:47], v[128:131], v[188:191], v[44:47]
	v_mfma_f32_16x16x32_bf16 v[40:43], v[136:139], v[188:191], v[40:43]
	v_mfma_f32_16x16x32_bf16 v[28:31], v[128:131], v[206:209], v[28:31]
	v_mfma_f32_16x16x32_bf16 v[24:27], v[136:139], v[206:209], v[24:27]
	v_mfma_f32_16x16x32_bf16 v[12:15], v[128:131], v[214:217], v[12:15]
	v_mfma_f32_16x16x32_bf16 v[8:11], v[136:139], v[214:217], v[8:11]
	v_mfma_f32_16x16x32_bf16 v[60:63], v[132:135], v[164:167], v[60:63]
	v_mfma_f32_16x16x32_bf16 v[56:59], v[140:143], v[164:167], v[56:59]
	v_mfma_f32_16x16x32_bf16 v[44:47], v[132:135], v[198:201], v[44:47]
	v_mfma_f32_16x16x32_bf16 v[40:43], v[140:143], v[198:201], v[40:43]
	v_mfma_f32_16x16x32_bf16 v[28:31], v[132:135], v[210:213], v[28:31]
	v_mfma_f32_16x16x32_bf16 v[24:27], v[140:143], v[210:213], v[24:27]
	v_mfma_f32_16x16x32_bf16 v[12:15], v[132:135], v[218:221], v[12:15]
	v_mfma_f32_16x16x32_bf16 v[8:11], v[140:143], v[218:221], v[8:11]
	s_setprio 0
	s_setprio 1
	v_mfma_f32_16x16x32_bf16 v[52:55], v[144:147], v[160:163], v[52:55]
	v_mfma_f32_16x16x32_bf16 v[48:51], v[152:155], v[160:163], v[48:51]
	v_mfma_f32_16x16x32_bf16 v[36:39], v[144:147], v[188:191], v[36:39]
	v_mfma_f32_16x16x32_bf16 v[32:35], v[152:155], v[188:191], v[32:35]
	v_mfma_f32_16x16x32_bf16 v[20:23], v[144:147], v[206:209], v[20:23]
	v_mfma_f32_16x16x32_bf16 v[16:19], v[152:155], v[206:209], v[16:19]
	v_mfma_f32_16x16x32_bf16 v[4:7], v[144:147], v[214:217], v[4:7]
	v_mfma_f32_16x16x32_bf16 v[0:3], v[152:155], v[214:217], v[0:3]
	v_mfma_f32_16x16x32_bf16 v[52:55], v[148:151], v[164:167], v[52:55]
	v_mfma_f32_16x16x32_bf16 v[48:51], v[156:159], v[164:167], v[48:51]
	v_mfma_f32_16x16x32_bf16 v[36:39], v[148:151], v[198:201], v[36:39]
	v_mfma_f32_16x16x32_bf16 v[32:35], v[156:159], v[198:201], v[32:35]
	v_mfma_f32_16x16x32_bf16 v[20:23], v[148:151], v[210:213], v[20:23]
	v_mfma_f32_16x16x32_bf16 v[16:19], v[156:159], v[210:213], v[16:19]
	v_mfma_f32_16x16x32_bf16 v[4:7], v[148:151], v[218:221], v[4:7]
	v_mfma_f32_16x16x32_bf16 v[0:3], v[156:159], v[218:221], v[0:3]
	s_setprio 0
	s_barrier
	s_add_i32 s6, s62, 2
	s_add_u32 s26, s26, 0x100
	s_addc_u32 s27, s27, 0
	s_cmp_gt_u32 s62, 21
	s_mov_b32 s62, s6
	s_cbranch_scc1 .LBB0_2162

.LBB0_2239:
	s_ashr_i32 s15, s14, 31
	s_lshl_b64 s[16:17], s[14:15], 19
	s_add_u32 s16, s36, s16
	s_addc_u32 s17, s37, s17
	s_and_b64 s[18:19], s[2:3], exec
	s_cselect_b32 s15, s17, s23
	s_cselect_b32 s52, s16, s22
	s_ashr_i32 s13, s12, 31
	s_lshl_b64 s[18:19], s[12:13], 19
	s_add_u32 s18, s38, s18
	s_addc_u32 s19, s39, s19
	s_and_b64 s[26:27], s[2:3], exec
	s_cselect_b32 s13, s19, s25
	s_cselect_b32 s53, s18, s24
	s_add_u32 s22, s22, 0x40080
	s_addc_u32 s23, s23, 0
	s_add_u32 s54, s24, 0x100
	v_mov_b32_e32 v0, 0
	s_addc_u32 s55, s25, 0
	s_mov_b32 s56, -2
	v_mov_b32_e32 v1, v0
	v_mov_b32_e32 v2, v0
	v_mov_b32_e32 v3, v0
	v_mov_b32_e32 v4, v0
	v_mov_b32_e32 v5, v0
	v_mov_b32_e32 v6, v0
	v_mov_b32_e32 v7, v0
	v_mov_b32_e32 v8, v0
	v_mov_b32_e32 v9, v0
	v_mov_b32_e32 v10, v0
	v_mov_b32_e32 v11, v0
	v_mov_b32_e32 v16, v0
	v_mov_b32_e32 v17, v0
	v_mov_b32_e32 v18, v0
	v_mov_b32_e32 v19, v0
	v_mov_b32_e32 v28, v0
	v_mov_b32_e32 v29, v0
	v_mov_b32_e32 v30, v0
	v_mov_b32_e32 v31, v0
	v_mov_b32_e32 v36, v0
	v_mov_b32_e32 v37, v0
	v_mov_b32_e32 v38, v0
	v_mov_b32_e32 v39, v0
	v_mov_b32_e32 v44, v0
	v_mov_b32_e32 v45, v0
	v_mov_b32_e32 v46, v0
	v_mov_b32_e32 v47, v0
	v_mov_b32_e32 v52, v0
	v_mov_b32_e32 v53, v0
	v_mov_b32_e32 v54, v0
	v_mov_b32_e32 v55, v0
	v_mov_b32_e32 v12, v0
	v_mov_b32_e32 v13, v0
	v_mov_b32_e32 v14, v0
	v_mov_b32_e32 v15, v0
	v_mov_b32_e32 v20, v0
	v_mov_b32_e32 v21, v0
	v_mov_b32_e32 v22, v0
	v_mov_b32_e32 v23, v0
	v_mov_b32_e32 v24, v0
	v_mov_b32_e32 v25, v0
	v_mov_b32_e32 v26, v0
	v_mov_b32_e32 v27, v0
	v_mov_b32_e32 v32, v0
	v_mov_b32_e32 v33, v0
	v_mov_b32_e32 v34, v0
	v_mov_b32_e32 v35, v0
	v_mov_b32_e32 v40, v0
	v_mov_b32_e32 v41, v0
	v_mov_b32_e32 v42, v0
	v_mov_b32_e32 v43, v0
	v_mov_b32_e32 v48, v0
	v_mov_b32_e32 v49, v0
	v_mov_b32_e32 v50, v0
	v_mov_b32_e32 v51, v0
	v_mov_b32_e32 v56, v0
	v_mov_b32_e32 v57, v0
	v_mov_b32_e32 v58, v0
	v_mov_b32_e32 v59, v0
	v_mov_b32_e32 v60, v0
	v_mov_b32_e32 v61, v0
	v_mov_b32_e32 v62, v0
	v_mov_b32_e32 v63, v0
	v_mov_b32_e32 v64, v0
	v_mov_b32_e32 v65, v0
	v_mov_b32_e32 v66, v0
	v_mov_b32_e32 v67, v0
	v_mov_b32_e32 v68, v0
	v_mov_b32_e32 v69, v0
	v_mov_b32_e32 v70, v0
	v_mov_b32_e32 v71, v0
	v_mov_b32_e32 v72, v0
	v_mov_b32_e32 v73, v0
	v_mov_b32_e32 v74, v0
	v_mov_b32_e32 v75, v0
	v_mov_b32_e32 v80, v0
	v_mov_b32_e32 v81, v0
	v_mov_b32_e32 v82, v0
	v_mov_b32_e32 v83, v0
	v_mov_b32_e32 v92, v0
	v_mov_b32_e32 v93, v0
	v_mov_b32_e32 v94, v0
	v_mov_b32_e32 v95, v0
	v_mov_b32_e32 v100, v0
	v_mov_b32_e32 v101, v0
	v_mov_b32_e32 v102, v0
	v_mov_b32_e32 v103, v0
	v_mov_b32_e32 v108, v0
	v_mov_b32_e32 v109, v0
	v_mov_b32_e32 v110, v0
	v_mov_b32_e32 v111, v0
	v_mov_b32_e32 v116, v0
	v_mov_b32_e32 v117, v0
	v_mov_b32_e32 v118, v0
	v_mov_b32_e32 v119, v0
	v_mov_b32_e32 v76, v0
	v_mov_b32_e32 v77, v0
	v_mov_b32_e32 v78, v0
	v_mov_b32_e32 v79, v0
	v_mov_b32_e32 v84, v0
	v_mov_b32_e32 v85, v0
	v_mov_b32_e32 v86, v0
	v_mov_b32_e32 v87, v0
	v_mov_b32_e32 v88, v0
	v_mov_b32_e32 v89, v0
	v_mov_b32_e32 v90, v0
	v_mov_b32_e32 v91, v0
	v_mov_b32_e32 v96, v0
	v_mov_b32_e32 v97, v0
	v_mov_b32_e32 v98, v0
	v_mov_b32_e32 v99, v0
	v_mov_b32_e32 v104, v0
	v_mov_b32_e32 v105, v0
	v_mov_b32_e32 v106, v0
	v_mov_b32_e32 v107, v0
	v_mov_b32_e32 v112, v0
	v_mov_b32_e32 v113, v0
	v_mov_b32_e32 v114, v0
	v_mov_b32_e32 v115, v0
	v_mov_b32_e32 v120, v0
	v_mov_b32_e32 v121, v0
	v_mov_b32_e32 v122, v0
	v_mov_b32_e32 v123, v0
	v_mov_b32_e32 v124, v0
	v_mov_b32_e32 v125, v0
	v_mov_b32_e32 v126, v0
	v_mov_b32_e32 v127, v0
	v_readlane_b32 s97, v255, 53
	s_nop 3
	s_cmp_eq_u32 s97, 1
	s_cbranch_scc0 .Llsb_skip_19
	v_writelane_b32 v255, 0, 53
	s_barrier
.Llsb_skip_19:
.LBB0_2240:
	ds_read_b128 v[128:131], v212
	ds_read_b128 v[132:135], v212 offset:1024
	ds_read_b128 v[136:139], v212 offset:2048
	ds_read_b128 v[140:143], v212 offset:3072
	ds_read_b128 v[144:147], v213
	ds_read_b128 v[148:151], v213 offset:1024
	ds_read_b128 v[152:155], v213 offset:2048
	ds_read_b128 v[156:159], v213 offset:3072
	s_add_u32 s24, s22, 0xfffc0080
	s_addc_u32 s25, s23, -1
	s_cmp_eq_u32 s56, 12
	s_cselect_b32 s27, s15, s25
	s_cselect_b32 s26, s52, s24
	s_cselect_b32 s25, s13, s55
	s_cselect_b32 s24, s53, s54
	v_lshl_add_u64 v[202:203], s[22:23], 0, v[182:183]
	s_add_i32 m0, s30, 0xc000
	ds_read_b128 v[160:163], v214
	ds_read_b128 v[164:167], v214 offset:1024
	ds_read_b128 v[168:171], v214 offset:2048
	ds_read_b128 v[172:175], v214 offset:3072
	ds_read_b128 v[190:193], v214 offset:4096
	ds_read_b128 v[194:197], v214 offset:5120
	ds_read_b128 v[198:201], v214 offset:6144
	ds_read_b128 v[216:219], v214 offset:7168
	global_load_lds_dwordx4 v[202:203], off
	v_lshl_add_u64 v[202:203], s[22:23], 0, v[184:185]
	s_add_i32 m0, s30, 0xe000
	s_nop 0
	global_load_lds_dwordx4 v[202:203], off
	s_waitcnt vmcnt(8)
	s_waitcnt lgkmcnt(0)
	s_barrier
	s_setprio 1
	s_waitcnt lgkmcnt(0)
	v_mfma_f32_16x16x32_bf16 v[124:127], v[128:131], v[160:163], v[124:127]
	v_mfma_f32_16x16x32_bf16 v[120:123], v[136:139], v[160:163], v[120:123]
	v_mfma_f32_16x16x32_bf16 v[112:115], v[128:131], v[168:171], v[112:115]
	v_mfma_f32_16x16x32_bf16 v[104:107], v[136:139], v[168:171], v[104:107]
	v_mfma_f32_16x16x32_bf16 v[96:99], v[128:131], v[190:193], v[96:99]
	v_mfma_f32_16x16x32_bf16 v[88:91], v[136:139], v[190:193], v[88:91]
	v_mfma_f32_16x16x32_bf16 v[84:87], v[128:131], v[198:201], v[84:87]
	v_mfma_f32_16x16x32_bf16 v[76:79], v[136:139], v[198:201], v[76:79]
	v_mfma_f32_16x16x32_bf16 v[124:127], v[132:135], v[164:167], v[124:127]
	v_mfma_f32_16x16x32_bf16 v[120:123], v[140:143], v[164:167], v[120:123]
	v_mfma_f32_16x16x32_bf16 v[112:115], v[132:135], v[172:175], v[112:115]
	v_mfma_f32_16x16x32_bf16 v[104:107], v[140:143], v[172:175], v[104:107]
	v_mfma_f32_16x16x32_bf16 v[96:99], v[132:135], v[194:197], v[96:99]
	v_mfma_f32_16x16x32_bf16 v[88:91], v[140:143], v[194:197], v[88:91]
	v_mfma_f32_16x16x32_bf16 v[84:87], v[132:135], v[216:219], v[84:87]
	v_mfma_f32_16x16x32_bf16 v[76:79], v[140:143], v[216:219], v[76:79]
	s_setprio 0
	s_setprio 1
	v_mfma_f32_16x16x32_bf16 v[116:119], v[144:147], v[160:163], v[116:119]
	v_mfma_f32_16x16x32_bf16 v[108:111], v[152:155], v[160:163], v[108:111]
	v_mfma_f32_16x16x32_bf16 v[100:103], v[144:147], v[168:171], v[100:103]
	v_mfma_f32_16x16x32_bf16 v[92:95], v[152:155], v[168:171], v[92:95]
	v_mfma_f32_16x16x32_bf16 v[80:83], v[144:147], v[190:193], v[80:83]
	v_mfma_f32_16x16x32_bf16 v[72:75], v[152:155], v[190:193], v[72:75]
	v_mfma_f32_16x16x32_bf16 v[68:71], v[144:147], v[198:201], v[68:71]
	v_mfma_f32_16x16x32_bf16 v[64:67], v[152:155], v[198:201], v[64:67]
	v_mfma_f32_16x16x32_bf16 v[116:119], v[148:151], v[164:167], v[116:119]
	v_mfma_f32_16x16x32_bf16 v[108:111], v[156:159], v[164:167], v[108:111]
	v_mfma_f32_16x16x32_bf16 v[100:103], v[148:151], v[172:175], v[100:103]
	v_mfma_f32_16x16x32_bf16 v[92:95], v[156:159], v[172:175], v[92:95]
	v_mfma_f32_16x16x32_bf16 v[80:83], v[148:151], v[194:197], v[80:83]
	v_mfma_f32_16x16x32_bf16 v[72:75], v[156:159], v[194:197], v[72:75]
	v_mfma_f32_16x16x32_bf16 v[68:71], v[148:151], v[216:219], v[68:71]
	v_mfma_f32_16x16x32_bf16 v[64:67], v[156:159], v[216:219], v[64:67]
	s_setprio 0
	s_barrier
	s_add_i32 s57, s45, s29
	v_lshl_add_u64 v[202:203], s[24:25], 0, v[176:177]
	s_mov_b32 m0, s57
	ds_read_b128 v[160:163], v214 offset:16384
	ds_read_b128 v[164:167], v214 offset:17408
	ds_read_b128 v[168:171], v214 offset:18432
	ds_read_b128 v[172:175], v214 offset:19456
	ds_read_b128 v[190:193], v214 offset:20480
	ds_read_b128 v[194:197], v214 offset:21504
	ds_read_b128 v[198:201], v214 offset:22528
	ds_read_b128 v[216:219], v214 offset:23552
	global_load_lds_dwordx4 v[202:203], off
	s_add_i32 m0, s57, 0x2000
	s_add_u32 s58, s24, 0x40000
	v_lshl_add_u64 v[220:221], s[24:25], 0, v[178:179]
	s_addc_u32 s59, s25, 0
	s_add_i32 s57, s46, s29
	global_load_lds_dwordx4 v[220:221], off
	v_lshl_add_u64 v[222:223], s[58:59], 0, v[176:177]
	s_mov_b32 m0, s57
	v_lshl_add_u64 v[224:225], s[26:27], 0, v[178:179]
	global_load_lds_dwordx4 v[222:223], off
	v_lshl_add_u64 v[222:223], s[58:59], 0, v[178:179]
	s_add_i32 m0, s57, 0x2000
	s_nop 0
	global_load_lds_dwordx4 v[222:223], off
	v_lshl_add_u64 v[222:223], s[26:27], 0, v[176:177]
	s_mov_b32 m0, s30
	s_nop 0
	global_load_lds_dwordx4 v[222:223], off
	s_mov_b32 m0, s31
	s_nop 0
	global_load_lds_dwordx4 v[224:225], off
	s_waitcnt vmcnt(8)
	s_waitcnt lgkmcnt(0)
	s_barrier
	s_setprio 1
	s_waitcnt lgkmcnt(0)
	v_mfma_f32_16x16x32_bf16 v[60:63], v[128:131], v[160:163], v[60:63]
	v_mfma_f32_16x16x32_bf16 v[56:59], v[136:139], v[160:163], v[56:59]
	v_mfma_f32_16x16x32_bf16 v[48:51], v[128:131], v[168:171], v[48:51]
	v_mfma_f32_16x16x32_bf16 v[40:43], v[136:139], v[168:171], v[40:43]
	v_mfma_f32_16x16x32_bf16 v[32:35], v[128:131], v[190:193], v[32:35]
	v_mfma_f32_16x16x32_bf16 v[24:27], v[136:139], v[190:193], v[24:27]
	v_mfma_f32_16x16x32_bf16 v[20:23], v[128:131], v[198:201], v[20:23]
	v_mfma_f32_16x16x32_bf16 v[12:15], v[136:139], v[198:201], v[12:15]
	v_mfma_f32_16x16x32_bf16 v[60:63], v[132:135], v[164:167], v[60:63]
	v_mfma_f32_16x16x32_bf16 v[56:59], v[140:143], v[164:167], v[56:59]
	v_mfma_f32_16x16x32_bf16 v[48:51], v[132:135], v[172:175], v[48:51]
	v_mfma_f32_16x16x32_bf16 v[40:43], v[140:143], v[172:175], v[40:43]
	v_mfma_f32_16x16x32_bf16 v[32:35], v[132:135], v[194:197], v[32:35]
	v_mfma_f32_16x16x32_bf16 v[24:27], v[140:143], v[194:197], v[24:27]
	v_mfma_f32_16x16x32_bf16 v[20:23], v[132:135], v[216:219], v[20:23]
	v_mfma_f32_16x16x32_bf16 v[12:15], v[140:143], v[216:219], v[12:15]
	s_setprio 0
	s_setprio 1
	v_mfma_f32_16x16x32_bf16 v[52:55], v[144:147], v[160:163], v[52:55]
	v_mfma_f32_16x16x32_bf16 v[44:47], v[152:155], v[160:163], v[44:47]
	v_mfma_f32_16x16x32_bf16 v[36:39], v[144:147], v[168:171], v[36:39]
	v_mfma_f32_16x16x32_bf16 v[28:31], v[152:155], v[168:171], v[28:31]
	v_mfma_f32_16x16x32_bf16 v[16:19], v[144:147], v[190:193], v[16:19]
	v_mfma_f32_16x16x32_bf16 v[8:11], v[152:155], v[190:193], v[8:11]
	v_mfma_f32_16x16x32_bf16 v[4:7], v[144:147], v[198:201], v[4:7]
	v_mfma_f32_16x16x32_bf16 v[0:3], v[152:155], v[198:201], v[0:3]
	v_mfma_f32_16x16x32_bf16 v[52:55], v[148:151], v[164:167], v[52:55]
	v_mfma_f32_16x16x32_bf16 v[44:47], v[156:159], v[164:167], v[44:47]
	v_mfma_f32_16x16x32_bf16 v[36:39], v[148:151], v[172:175], v[36:39]
	v_mfma_f32_16x16x32_bf16 v[28:31], v[156:159], v[172:175], v[28:31]
	v_mfma_f32_16x16x32_bf16 v[16:19], v[148:151], v[194:197], v[16:19]
	v_mfma_f32_16x16x32_bf16 v[8:11], v[156:159], v[194:197], v[8:11]
	v_mfma_f32_16x16x32_bf16 v[4:7], v[148:151], v[216:219], v[4:7]
	v_mfma_f32_16x16x32_bf16 v[0:3], v[156:159], v[216:219], v[0:3]
	s_setprio 0
	s_barrier
	s_add_i32 s57, 0, 0x18000
	s_add_i32 s58, 0, 0x1c000
	v_add_u32_e32 v140, s57, v210
	v_add_u32_e32 v156, s58, v210
	ds_read_b128 v[128:131], v140
	ds_read_b128 v[132:135], v140 offset:1024
	ds_read_b128 v[136:139], v140 offset:2048
	ds_read_b128 v[140:143], v140 offset:3072
	ds_read_b128 v[144:147], v156
	ds_read_b128 v[148:151], v156 offset:1024
	ds_read_b128 v[152:155], v156 offset:2048
	ds_read_b128 v[156:159], v156 offset:3072
	s_add_u32 s26, s26, 0x40000
	s_addc_u32 s27, s27, 0
	s_mov_b32 m0, s34
	v_lshl_add_u64 v[226:227], s[26:27], 0, v[176:177]
	ds_read_b128 v[160:163], v214 offset:32768
	ds_read_b128 v[164:167], v214 offset:33792
	ds_read_b128 v[168:171], v214 offset:34816
	ds_read_b128 v[172:175], v214 offset:35840
	ds_read_b128 v[190:193], v214 offset:36864
	ds_read_b128 v[194:197], v214 offset:37888
	ds_read_b128 v[198:201], v214 offset:38912
	ds_read_b128 v[216:219], v214 offset:39936
	global_load_lds_dwordx4 v[226:227], off
	v_lshl_add_u64 v[226:227], s[26:27], 0, v[178:179]
	s_mov_b32 m0, s35
	s_nop 0
	global_load_lds_dwordx4 v[226:227], off
	s_waitcnt vmcnt(8)
	s_waitcnt lgkmcnt(0)
	s_barrier
	s_setprio 1
	s_waitcnt lgkmcnt(0)
	v_mfma_f32_16x16x32_bf16 v[124:127], v[128:131], v[160:163], v[124:127]
	v_mfma_f32_16x16x32_bf16 v[120:123], v[136:139], v[160:163], v[120:123]
	v_mfma_f32_16x16x32_bf16 v[112:115], v[128:131], v[168:171], v[112:115]
	v_mfma_f32_16x16x32_bf16 v[104:107], v[136:139], v[168:171], v[104:107]
	v_mfma_f32_16x16x32_bf16 v[96:99], v[128:131], v[190:193], v[96:99]
	v_mfma_f32_16x16x32_bf16 v[88:91], v[136:139], v[190:193], v[88:91]
	v_mfma_f32_16x16x32_bf16 v[84:87], v[128:131], v[198:201], v[84:87]
	v_mfma_f32_16x16x32_bf16 v[76:79], v[136:139], v[198:201], v[76:79]
	v_mfma_f32_16x16x32_bf16 v[124:127], v[132:135], v[164:167], v[124:127]
	v_mfma_f32_16x16x32_bf16 v[120:123], v[140:143], v[164:167], v[120:123]
	v_mfma_f32_16x16x32_bf16 v[112:115], v[132:135], v[172:175], v[112:115]
	v_mfma_f32_16x16x32_bf16 v[104:107], v[140:143], v[172:175], v[104:107]
	v_mfma_f32_16x16x32_bf16 v[96:99], v[132:135], v[194:197], v[96:99]
	v_mfma_f32_16x16x32_bf16 v[88:91], v[140:143], v[194:197], v[88:91]
	v_mfma_f32_16x16x32_bf16 v[84:87], v[132:135], v[216:219], v[84:87]
	v_mfma_f32_16x16x32_bf16 v[76:79], v[140:143], v[216:219], v[76:79]
	s_setprio 0
	s_setprio 1
	v_mfma_f32_16x16x32_bf16 v[116:119], v[144:147], v[160:163], v[116:119]
	v_mfma_f32_16x16x32_bf16 v[108:111], v[152:155], v[160:163], v[108:111]
	v_mfma_f32_16x16x32_bf16 v[100:103], v[144:147], v[168:171], v[100:103]
	v_mfma_f32_16x16x32_bf16 v[92:95], v[152:155], v[168:171], v[92:95]
	v_mfma_f32_16x16x32_bf16 v[80:83], v[144:147], v[190:193], v[80:83]
	v_mfma_f32_16x16x32_bf16 v[72:75], v[152:155], v[190:193], v[72:75]
	v_mfma_f32_16x16x32_bf16 v[68:71], v[144:147], v[198:201], v[68:71]
	v_mfma_f32_16x16x32_bf16 v[64:67], v[152:155], v[198:201], v[64:67]
	v_mfma_f32_16x16x32_bf16 v[116:119], v[148:151], v[164:167], v[116:119]
	v_mfma_f32_16x16x32_bf16 v[108:111], v[156:159], v[164:167], v[108:111]
	v_mfma_f32_16x16x32_bf16 v[100:103], v[148:151], v[172:175], v[100:103]
	v_mfma_f32_16x16x32_bf16 v[92:95], v[156:159], v[172:175], v[92:95]
	v_mfma_f32_16x16x32_bf16 v[80:83], v[148:151], v[194:197], v[80:83]
	v_mfma_f32_16x16x32_bf16 v[72:75], v[156:159], v[194:197], v[72:75]
	v_mfma_f32_16x16x32_bf16 v[68:71], v[148:151], v[216:219], v[68:71]
	v_mfma_f32_16x16x32_bf16 v[64:67], v[156:159], v[216:219], v[64:67]
	s_setprio 0
	s_barrier
	s_add_i32 s26, s57, s29
	v_lshl_add_u64 v[202:203], v[202:203], 0, s[8:9]
	s_mov_b32 m0, s26
	ds_read_b128 v[160:163], v214 offset:49152
	ds_read_b128 v[164:167], v214 offset:50176
	ds_read_b128 v[168:171], v214 offset:51200
	ds_read_b128 v[172:175], v214 offset:52224
	ds_read_b128 v[190:193], v214 offset:53248
	ds_read_b128 v[194:197], v214 offset:54272
	ds_read_b128 v[198:201], v214 offset:55296
	ds_read_b128 v[216:219], v214 offset:56320
	global_load_lds_dwordx4 v[202:203], off
	s_add_i32 m0, s26, 0x2000
	s_add_u32 s24, s24, 0x40080
	v_lshl_add_u64 v[202:203], v[220:221], 0, s[8:9]
	s_addc_u32 s25, s25, 0
	s_add_i32 s26, s58, s29
	global_load_lds_dwordx4 v[202:203], off
	v_lshl_add_u64 v[202:203], s[24:25], 0, v[176:177]
	s_mov_b32 m0, s26
	s_nop 0
	global_load_lds_dwordx4 v[202:203], off
	v_lshl_add_u64 v[202:203], s[24:25], 0, v[178:179]
	s_add_i32 m0, s26, 0x2000
	s_nop 0
	global_load_lds_dwordx4 v[202:203], off
	v_lshl_add_u64 v[202:203], v[222:223], 0, s[8:9]
	s_mov_b32 m0, s42
	s_nop 0
	global_load_lds_dwordx4 v[202:203], off
	v_lshl_add_u64 v[202:203], v[224:225], 0, s[8:9]
	s_mov_b32 m0, s43
	s_nop 0
	global_load_lds_dwordx4 v[202:203], off
	s_waitcnt vmcnt(8)
	s_waitcnt lgkmcnt(0)
	s_barrier
	s_setprio 1
	s_waitcnt lgkmcnt(0)
	v_mfma_f32_16x16x32_bf16 v[60:63], v[128:131], v[160:163], v[60:63]
	v_mfma_f32_16x16x32_bf16 v[56:59], v[136:139], v[160:163], v[56:59]
	v_mfma_f32_16x16x32_bf16 v[48:51], v[128:131], v[168:171], v[48:51]
	v_mfma_f32_16x16x32_bf16 v[40:43], v[136:139], v[168:171], v[40:43]
	v_mfma_f32_16x16x32_bf16 v[32:35], v[128:131], v[190:193], v[32:35]
	v_mfma_f32_16x16x32_bf16 v[24:27], v[136:139], v[190:193], v[24:27]
	v_mfma_f32_16x16x32_bf16 v[20:23], v[128:131], v[198:201], v[20:23]
	v_mfma_f32_16x16x32_bf16 v[12:15], v[136:139], v[198:201], v[12:15]
	v_mfma_f32_16x16x32_bf16 v[60:63], v[132:135], v[164:167], v[60:63]
	v_mfma_f32_16x16x32_bf16 v[56:59], v[140:143], v[164:167], v[56:59]
	v_mfma_f32_16x16x32_bf16 v[48:51], v[132:135], v[172:175], v[48:51]
	v_mfma_f32_16x16x32_bf16 v[40:43], v[140:143], v[172:175], v[40:43]
	v_mfma_f32_16x16x32_bf16 v[32:35], v[132:135], v[194:197], v[32:35]
	v_mfma_f32_16x16x32_bf16 v[24:27], v[140:143], v[194:197], v[24:27]
	v_mfma_f32_16x16x32_bf16 v[20:23], v[132:135], v[216:219], v[20:23]
	v_mfma_f32_16x16x32_bf16 v[12:15], v[140:143], v[216:219], v[12:15]
	s_setprio 0
	s_setprio 1
	v_mfma_f32_16x16x32_bf16 v[52:55], v[144:147], v[160:163], v[52:55]
	v_mfma_f32_16x16x32_bf16 v[44:47], v[152:155], v[160:163], v[44:47]
	v_mfma_f32_16x16x32_bf16 v[36:39], v[144:147], v[168:171], v[36:39]
	v_mfma_f32_16x16x32_bf16 v[28:31], v[152:155], v[168:171], v[28:31]
	v_mfma_f32_16x16x32_bf16 v[16:19], v[144:147], v[190:193], v[16:19]
	v_mfma_f32_16x16x32_bf16 v[8:11], v[152:155], v[190:193], v[8:11]
	v_mfma_f32_16x16x32_bf16 v[4:7], v[144:147], v[198:201], v[4:7]
	v_mfma_f32_16x16x32_bf16 v[0:3], v[152:155], v[198:201], v[0:3]
	v_mfma_f32_16x16x32_bf16 v[52:55], v[148:151], v[164:167], v[52:55]
	v_mfma_f32_16x16x32_bf16 v[44:47], v[156:159], v[164:167], v[44:47]
	v_mfma_f32_16x16x32_bf16 v[36:39], v[148:151], v[172:175], v[36:39]
	v_mfma_f32_16x16x32_bf16 v[28:31], v[156:159], v[172:175], v[28:31]
	v_mfma_f32_16x16x32_bf16 v[16:19], v[148:151], v[194:197], v[16:19]
	v_mfma_f32_16x16x32_bf16 v[8:11], v[156:159], v[194:197], v[8:11]
	v_mfma_f32_16x16x32_bf16 v[4:7], v[148:151], v[216:219], v[4:7]
	v_mfma_f32_16x16x32_bf16 v[0:3], v[156:159], v[216:219], v[0:3]
	s_setprio 0
	s_barrier
	s_add_i32 s56, s56, 2
	s_add_u32 s22, s22, 0x100
	s_addc_u32 s23, s23, 0
	s_add_u32 s54, s54, 0x100
	s_addc_u32 s55, s55, 0
	s_cmp_gt_u32 s56, 13
	s_cbranch_scc0 .LBB0_2240
	s_and_b64 vcc, exec, s[10:11]
	s_cbranch_vccz .LBB0_2243
	s_barrier
.LBB0_2243:
	v_lshl_add_u32 v192, s20, 8, v209
	v_add_u32_e32 v130, 0xffffc000, v192
	v_ashrrev_i32_e32 v193, 31, v192
	v_cmp_gt_i32_e32 vcc, s41, v192
	v_lshl_or_b32 v128, s21, 8, v211
	v_mov_b32_e32 v134, s7
	v_cndmask_b32_e32 v131, 0, v193, vcc
	v_cndmask_b32_e32 v130, v130, v192, vcc
	v_mov_b32_e32 v135, s89
	v_mov_b32_e32 v136, s6
	v_mov_b32_e32 v137, s88
	v_ashrrev_i32_e32 v129, 31, v128
	v_cndmask_b32_e32 v133, v134, v135, vcc
	v_cndmask_b32_e32 v132, v136, v137, vcc
	v_lshlrev_b64 v[130:131], 12, v[130:131]
	v_lshl_add_u64 v[130:131], v[132:133], 0, v[130:131]
	v_lshlrev_b64 v[190:191], 2, v[128:129]
	v_lshl_add_u64 v[128:129], v[130:131], 0, v[190:191]
	v_or_b32_e32 v198, 16, v192
	global_load_dwordx4 v[172:175], v[128:129], off
	global_load_dwordx4 v[168:171], v[128:129], off offset:64
	global_load_dwordx4 v[164:167], v[128:129], off offset:512
	global_load_dwordx4 v[156:159], v[128:129], off offset:576
	v_ashrrev_i32_e32 v199, 31, v198
	v_add_u32_e32 v128, 0xffffc010, v192
	v_cmp_gt_i32_e32 vcc, s41, v198
	v_or_b32_e32 v196, 32, v192
	v_ashrrev_i32_e32 v197, 31, v196
	v_cndmask_b32_e32 v129, 0, v199, vcc
	v_cndmask_b32_e32 v128, v128, v198, vcc
	v_cndmask_b32_e32 v131, v134, v135, vcc
	v_cndmask_b32_e32 v130, v136, v137, vcc
	v_lshlrev_b64 v[128:129], 12, v[128:129]
	v_lshl_add_u64 v[128:129], v[130:131], 0, v[128:129]
	v_lshl_add_u64 v[128:129], v[128:129], 0, v[190:191]
	global_load_dwordx4 v[160:163], v[128:129], off
	global_load_dwordx4 v[152:155], v[128:129], off offset:64
	global_load_dwordx4 v[148:151], v[128:129], off offset:512
	global_load_dwordx4 v[140:143], v[128:129], off offset:576
	v_add_u32_e32 v128, 0xffffc020, v192
	v_cmp_gt_i32_e32 vcc, s41, v196
	v_or_b32_e32 v200, 48, v192
	s_nop 0
	v_cndmask_b32_e32 v129, 0, v197, vcc
	v_cndmask_b32_e32 v128, v128, v196, vcc
	v_cndmask_b32_e32 v131, v134, v135, vcc
	v_cndmask_b32_e32 v130, v136, v137, vcc
	v_lshlrev_b64 v[128:129], 12, v[128:129]
	v_lshl_add_u64 v[128:129], v[130:131], 0, v[128:129]
	v_lshl_add_u64 v[128:129], v[128:129], 0, v[190:191]
	global_load_dwordx4 v[144:147], v[128:129], off
	global_load_dwordx4 v[136:139], v[128:129], off offset:64
	global_load_dwordx4 v[132:135], v[128:129], off offset:512
	s_nop 0
	global_load_dwordx4 v[128:131], v[128:129], off offset:576
	v_cmp_lt_i32_e32 vcc, s47, v200
	s_and_saveexec_b64 s[20:21], vcc
	s_xor_b64 s[20:21], exec, s[20:21]
	v_add_u32_e32 v180, 0xffffc030, v192
	v_lshlrev_b64 v[194:195], 12, v[180:181]
	v_mov_b32_e32 v201, v181
	v_lshl_add_u64 v[202:203], s[6:7], 0, v[194:195]
	v_lshlrev_b64 v[194:195], 12, v[200:201]
	s_andn2_saveexec_b64 s[20:21], s[20:21]
	v_ashrrev_i32_e32 v201, 31, v200
	v_lshlrev_b64 v[194:195], 12, v[200:201]
	v_lshl_add_u64 v[202:203], s[88:89], 0, v[194:195]
	s_or_b64 exec, exec, s[20:21]
	v_lshl_add_u64 v[224:225], v[202:203], 0, v[190:191]
	global_load_dwordx4 v[200:203], v[224:225], off
	global_load_dwordx4 v[216:219], v[224:225], off offset:64
	global_load_dwordx4 v[220:223], v[224:225], off offset:512
	s_nop 0
	global_load_dwordx4 v[224:227], v[224:225], off offset:576
	v_lshlrev_b64 v[228:229], 12, v[192:193]
	v_lshl_add_u64 v[228:229], s[88:89], 0, v[228:229]
	v_lshl_add_u64 v[228:229], v[228:229], 0, v[190:191]
	s_waitcnt vmcnt(0)
	v_pk_add_f32 v[110:111], v[110:111], v[158:159]
	v_pk_add_f32 v[108:109], v[108:109], v[156:157]
	global_store_dwordx4 v[228:229], v[108:111], off offset:576
	v_pk_add_f32 v[118:119], v[118:119], v[166:167]
	v_pk_add_f32 v[116:117], v[116:117], v[164:165]
	v_lshlrev_b64 v[108:109], 12, v[198:199]
	v_lshl_add_u64 v[108:109], s[88:89], 0, v[108:109]
	global_store_dwordx4 v[228:229], v[116:119], off offset:512
	v_pk_add_f32 v[94:95], v[94:95], v[142:143]
	v_pk_add_f32 v[92:93], v[92:93], v[140:141]
	v_lshl_add_u64 v[116:117], v[108:109], 0, v[190:191]
	global_store_dwordx4 v[116:117], v[92:95], off offset:576
	v_pk_add_f32 v[102:103], v[102:103], v[150:151]
	v_pk_add_f32 v[100:101], v[100:101], v[148:149]
	v_lshlrev_b64 v[92:93], 12, v[196:197]
	v_lshl_add_u64 v[92:93], s[88:89], 0, v[92:93]
	global_store_dwordx4 v[116:117], v[100:103], off offset:512
	v_pk_add_f32 v[74:75], v[74:75], v[130:131]
	v_pk_add_f32 v[72:73], v[72:73], v[128:129]
	v_lshl_add_u64 v[100:101], v[92:93], 0, v[190:191]
	v_pk_add_f32 v[82:83], v[82:83], v[134:135]
	v_pk_add_f32 v[80:81], v[80:81], v[132:133]
	global_store_dwordx4 v[100:101], v[72:75], off offset:576
	v_pk_add_f32 v[126:127], v[126:127], v[174:175]
	v_pk_add_f32 v[124:125], v[124:125], v[172:173]
	v_lshl_add_u64 v[72:73], s[88:89], 0, v[194:195]
	v_pk_add_f32 v[122:123], v[122:123], v[170:171]
	v_pk_add_f32 v[120:121], v[120:121], v[168:169]
	v_pk_add_f32 v[110:111], v[114:115], v[162:163]
	v_pk_add_f32 v[108:109], v[112:113], v[160:161]
	v_pk_add_f32 v[106:107], v[106:107], v[154:155]
	v_pk_add_f32 v[104:105], v[104:105], v[152:153]
	v_pk_add_f32 v[94:95], v[98:99], v[146:147]
	v_pk_add_f32 v[92:93], v[96:97], v[144:145]
	v_pk_add_f32 v[90:91], v[90:91], v[138:139]
	v_pk_add_f32 v[88:89], v[88:89], v[136:137]
	global_store_dwordx4 v[100:101], v[80:83], off offset:512
	v_pk_add_f32 v[74:75], v[86:87], v[202:203]
	global_store_dwordx4 v[228:229], v[124:127], off
	v_lshl_add_u64 v[80:81], v[72:73], 0, v[190:191]
	v_pk_add_f32 v[72:73], v[84:85], v[200:201]
	global_store_dwordx4 v[228:229], v[120:123], off offset:64
	global_store_dwordx4 v[116:117], v[108:111], off
	global_store_dwordx4 v[116:117], v[104:107], off offset:64
	global_store_dwordx4 v[100:101], v[92:95], off
	global_store_dwordx4 v[100:101], v[88:91], off offset:64
	global_store_dwordx4 v[80:81], v[72:75], off
	v_pk_add_f32 v[70:71], v[70:71], v[222:223]
	v_pk_add_f32 v[68:69], v[68:69], v[220:221]
	v_pk_add_f32 v[74:75], v[78:79], v[218:219]
	v_pk_add_f32 v[72:73], v[76:77], v[216:217]
	v_pk_add_f32 v[66:67], v[66:67], v[226:227]
	v_pk_add_f32 v[64:65], v[64:65], v[224:225]
	global_store_dwordx4 v[80:81], v[72:75], off offset:64
	global_store_dwordx4 v[80:81], v[68:71], off offset:512
	global_store_dwordx4 v[80:81], v[64:67], off offset:576
	v_add_u32_e32 v118, 0x80, v192
	v_ashrrev_i32_e32 v119, 31, v118
	v_add_u32_e32 v64, 0xffffc080, v192
	v_cmp_gt_i32_e32 vcc, s48, v192
	v_mov_b32_e32 v68, s7
	v_mov_b32_e32 v69, s89
	v_cndmask_b32_e32 v65, 0, v119, vcc
	v_cndmask_b32_e32 v64, v64, v118, vcc
	v_mov_b32_e32 v70, s6
	v_mov_b32_e32 v71, s88
	v_cndmask_b32_e32 v67, v68, v69, vcc
	v_cndmask_b32_e32 v66, v70, v71, vcc
	v_lshlrev_b64 v[64:65], 12, v[64:65]
	v_lshl_add_u64 v[64:65], v[66:67], 0, v[64:65]
	v_lshl_add_u64 v[64:65], v[64:65], 0, v[190:191]
	v_add_u32_e32 v116, 0x90, v192
	global_load_dwordx4 v[108:111], v[64:65], off
	global_load_dwordx4 v[104:107], v[64:65], off offset:64
	global_load_dwordx4 v[100:103], v[64:65], off offset:512
	global_load_dwordx4 v[92:95], v[64:65], off offset:576
	v_ashrrev_i32_e32 v117, 31, v116
	v_add_u32_e32 v64, 0xffffc090, v192
	v_cmp_gt_i32_e32 vcc, s49, v192
	v_add_u32_e32 v114, 0xa0, v192
	v_ashrrev_i32_e32 v115, 31, v114
	v_cndmask_b32_e32 v65, 0, v117, vcc
	v_cndmask_b32_e32 v64, v64, v116, vcc
	v_cndmask_b32_e32 v67, v68, v69, vcc
	v_cndmask_b32_e32 v66, v70, v71, vcc
	v_lshlrev_b64 v[64:65], 12, v[64:65]
	v_lshl_add_u64 v[64:65], v[66:67], 0, v[64:65]
	v_lshl_add_u64 v[64:65], v[64:65], 0, v[190:191]
	global_load_dwordx4 v[96:99], v[64:65], off
	global_load_dwordx4 v[88:91], v[64:65], off offset:64
	global_load_dwordx4 v[84:87], v[64:65], off offset:512
	global_load_dwordx4 v[76:79], v[64:65], off offset:576
	v_add_u32_e32 v64, 0xffffc0a0, v192
	v_cmp_gt_i32_e32 vcc, s50, v192
	v_add_u32_e32 v120, 0xb0, v192
	s_nop 0
	v_cndmask_b32_e32 v65, 0, v115, vcc
	v_cndmask_b32_e32 v64, v64, v114, vcc
	v_cndmask_b32_e32 v67, v68, v69, vcc
	v_cndmask_b32_e32 v66, v70, v71, vcc
	v_lshlrev_b64 v[64:65], 12, v[64:65]
	v_lshl_add_u64 v[64:65], v[66:67], 0, v[64:65]
	v_lshl_add_u64 v[64:65], v[64:65], 0, v[190:191]
	global_load_dwordx4 v[80:83], v[64:65], off
	global_load_dwordx4 v[72:75], v[64:65], off offset:64
	global_load_dwordx4 v[68:71], v[64:65], off offset:512
	s_nop 0
	global_load_dwordx4 v[64:67], v[64:65], off offset:576
	v_cmp_lt_i32_e32 vcc, s51, v192
	s_and_saveexec_b64 s[20:21], vcc
	s_xor_b64 s[20:21], exec, s[20:21]
	v_add_u32_e32 v180, 0xffffc0b0, v192
	v_lshlrev_b64 v[112:113], 12, v[180:181]
	v_mov_b32_e32 v121, v181
	v_lshl_add_u64 v[122:123], s[6:7], 0, v[112:113]
	v_lshlrev_b64 v[112:113], 12, v[120:121]
	s_andn2_saveexec_b64 s[20:21], s[20:21]
	v_ashrrev_i32_e32 v121, 31, v120
	v_lshlrev_b64 v[112:113], 12, v[120:121]
	v_lshl_add_u64 v[122:123], s[88:89], 0, v[112:113]
	s_or_b64 exec, exec, s[20:21]
	v_lshl_add_u64 v[132:133], v[122:123], 0, v[190:191]
	global_load_dwordx4 v[120:123], v[132:133], off
	global_load_dwordx4 v[124:127], v[132:133], off offset:64
	global_load_dwordx4 v[128:131], v[132:133], off offset:512
	s_nop 0
	global_load_dwordx4 v[132:135], v[132:133], off offset:576
	v_lshlrev_b64 v[118:119], 12, v[118:119]
	v_lshl_add_u64 v[118:119], s[88:89], 0, v[118:119]
	v_lshl_add_u64 v[118:119], v[118:119], 0, v[190:191]
	s_waitcnt vmcnt(12)
	v_pk_add_f32 v[46:47], v[46:47], v[94:95]
	v_pk_add_f32 v[44:45], v[44:45], v[92:93]
	global_store_dwordx4 v[118:119], v[44:47], off offset:576
	v_pk_add_f32 v[54:55], v[54:55], v[102:103]
	v_pk_add_f32 v[52:53], v[52:53], v[100:101]
	v_lshlrev_b64 v[44:45], 12, v[116:117]
	v_lshl_add_u64 v[44:45], s[88:89], 0, v[44:45]
	global_store_dwordx4 v[118:119], v[52:55], off offset:512
	s_waitcnt vmcnt(10)
	v_pk_add_f32 v[30:31], v[30:31], v[78:79]
	v_pk_add_f32 v[28:29], v[28:29], v[76:77]
	v_lshl_add_u64 v[52:53], v[44:45], 0, v[190:191]
	global_store_dwordx4 v[52:53], v[28:31], off offset:576
	v_pk_add_f32 v[38:39], v[38:39], v[86:87]
	v_pk_add_f32 v[36:37], v[36:37], v[84:85]
	v_lshlrev_b64 v[28:29], 12, v[114:115]
	v_lshl_add_u64 v[28:29], s[88:89], 0, v[28:29]
	global_store_dwordx4 v[52:53], v[36:39], off offset:512
	s_waitcnt vmcnt(8)
	v_pk_add_f32 v[10:11], v[10:11], v[66:67]
	v_pk_add_f32 v[8:9], v[8:9], v[64:65]
	v_lshl_add_u64 v[36:37], v[28:29], 0, v[190:191]
	v_pk_add_f32 v[18:19], v[18:19], v[70:71]
	v_pk_add_f32 v[16:17], v[16:17], v[68:69]
	global_store_dwordx4 v[36:37], v[8:11], off offset:576
	v_pk_add_f32 v[62:63], v[62:63], v[110:111]
	v_pk_add_f32 v[60:61], v[60:61], v[108:109]
	v_lshl_add_u64 v[8:9], s[88:89], 0, v[112:113]
	v_pk_add_f32 v[58:59], v[58:59], v[106:107]
	v_pk_add_f32 v[56:57], v[56:57], v[104:105]
	v_pk_add_f32 v[46:47], v[50:51], v[98:99]
	v_pk_add_f32 v[44:45], v[48:49], v[96:97]
	v_pk_add_f32 v[42:43], v[42:43], v[90:91]
	v_pk_add_f32 v[40:41], v[40:41], v[88:89]
	v_pk_add_f32 v[30:31], v[34:35], v[82:83]
	v_pk_add_f32 v[28:29], v[32:33], v[80:81]
	v_pk_add_f32 v[26:27], v[26:27], v[74:75]
	v_pk_add_f32 v[24:25], v[24:25], v[72:73]
	global_store_dwordx4 v[36:37], v[16:19], off offset:512
	s_waitcnt vmcnt(9)
	v_pk_add_f32 v[10:11], v[22:23], v[122:123]
	global_store_dwordx4 v[118:119], v[60:63], off
	v_lshl_add_u64 v[16:17], v[8:9], 0, v[190:191]
	v_pk_add_f32 v[8:9], v[20:21], v[120:121]
	global_store_dwordx4 v[118:119], v[56:59], off offset:64
	global_store_dwordx4 v[52:53], v[44:47], off
	global_store_dwordx4 v[52:53], v[40:43], off offset:64
	global_store_dwordx4 v[36:37], v[28:31], off
	global_store_dwordx4 v[36:37], v[24:27], off offset:64
	global_store_dwordx4 v[16:17], v[8:11], off
	s_waitcnt vmcnt(14)
	v_pk_add_f32 v[6:7], v[6:7], v[130:131]
	v_pk_add_f32 v[4:5], v[4:5], v[128:129]
	v_pk_add_f32 v[10:11], v[14:15], v[126:127]
	v_pk_add_f32 v[8:9], v[12:13], v[124:125]
	s_waitcnt vmcnt(13)
	v_pk_add_f32 v[2:3], v[2:3], v[134:135]
	v_pk_add_f32 v[0:1], v[0:1], v[132:133]
	global_store_dwordx4 v[16:17], v[8:11], off offset:64
	global_store_dwordx4 v[16:17], v[4:7], off offset:512
	global_store_dwordx4 v[16:17], v[0:3], off offset:576
	s_andn2_b64 vcc, exec, s[2:3]
	s_mov_b64 s[2:3], -1
	s_cbranch_vccnz .LBB0_2232
	s_andn2_b64 vcc, exec, s[0:1]
	s_cbranch_vccnz .LBB0_2231
	v_writelane_b32 v255, 1, 53
	s_branch .LBB0_2231

.Llsb_skip_21:
.LBB0_2476:
	ds_read_b128 v[128:131], v212
	ds_read_b128 v[132:135], v212 offset:1024
	ds_read_b128 v[136:139], v212 offset:2048
	ds_read_b128 v[140:143], v212 offset:3072
	ds_read_b128 v[144:147], v213
	ds_read_b128 v[148:151], v213 offset:1024
	ds_read_b128 v[152:155], v213 offset:2048
	ds_read_b128 v[156:159], v213 offset:3072
	s_add_u32 s18, s16, 0xfff50080
	s_addc_u32 s19, s17, -1
	s_cmp_eq_u32 s52, 40
	s_cselect_b32 s21, s5, s19
	s_cselect_b32 s20, s4, s18
	s_cselect_b32 s19, s15, s51
	s_cselect_b32 s18, s14, s50
	v_lshl_add_u64 v[202:203], s[16:17], 0, v[182:183]
	s_add_i32 m0, s23, 0xc000
	ds_read_b128 v[160:163], v214
	ds_read_b128 v[164:167], v214 offset:1024
	ds_read_b128 v[168:171], v214 offset:2048
	ds_read_b128 v[172:175], v214 offset:3072
	ds_read_b128 v[190:193], v214 offset:4096
	ds_read_b128 v[194:197], v214 offset:5120
	ds_read_b128 v[198:201], v214 offset:6144
	ds_read_b128 v[216:219], v214 offset:7168
	global_load_lds_dwordx4 v[202:203], off
	v_lshl_add_u64 v[202:203], s[16:17], 0, v[184:185]
	s_add_i32 m0, s23, 0xe000
	s_nop 0
	global_load_lds_dwordx4 v[202:203], off
	s_waitcnt vmcnt(8)
	s_waitcnt lgkmcnt(0)
	s_barrier
	s_setprio 1
	s_waitcnt lgkmcnt(0)
	v_mfma_f32_16x16x32_bf16 v[124:127], v[128:131], v[160:163], v[124:127]
	v_mfma_f32_16x16x32_bf16 v[120:123], v[136:139], v[160:163], v[120:123]
	v_mfma_f32_16x16x32_bf16 v[112:115], v[128:131], v[168:171], v[112:115]
	v_mfma_f32_16x16x32_bf16 v[104:107], v[136:139], v[168:171], v[104:107]
	v_mfma_f32_16x16x32_bf16 v[96:99], v[128:131], v[190:193], v[96:99]
	v_mfma_f32_16x16x32_bf16 v[88:91], v[136:139], v[190:193], v[88:91]
	v_mfma_f32_16x16x32_bf16 v[84:87], v[128:131], v[198:201], v[84:87]
	v_mfma_f32_16x16x32_bf16 v[76:79], v[136:139], v[198:201], v[76:79]
	v_mfma_f32_16x16x32_bf16 v[124:127], v[132:135], v[164:167], v[124:127]
	v_mfma_f32_16x16x32_bf16 v[120:123], v[140:143], v[164:167], v[120:123]
	v_mfma_f32_16x16x32_bf16 v[112:115], v[132:135], v[172:175], v[112:115]
	v_mfma_f32_16x16x32_bf16 v[104:107], v[140:143], v[172:175], v[104:107]
	v_mfma_f32_16x16x32_bf16 v[96:99], v[132:135], v[194:197], v[96:99]
	v_mfma_f32_16x16x32_bf16 v[88:91], v[140:143], v[194:197], v[88:91]
	v_mfma_f32_16x16x32_bf16 v[84:87], v[132:135], v[216:219], v[84:87]
	v_mfma_f32_16x16x32_bf16 v[76:79], v[140:143], v[216:219], v[76:79]
	s_setprio 0
	s_setprio 1
	v_mfma_f32_16x16x32_bf16 v[116:119], v[144:147], v[160:163], v[116:119]
	v_mfma_f32_16x16x32_bf16 v[108:111], v[152:155], v[160:163], v[108:111]
	v_mfma_f32_16x16x32_bf16 v[100:103], v[144:147], v[168:171], v[100:103]
	v_mfma_f32_16x16x32_bf16 v[92:95], v[152:155], v[168:171], v[92:95]
	v_mfma_f32_16x16x32_bf16 v[80:83], v[144:147], v[190:193], v[80:83]
	v_mfma_f32_16x16x32_bf16 v[72:75], v[152:155], v[190:193], v[72:75]
	v_mfma_f32_16x16x32_bf16 v[68:71], v[144:147], v[198:201], v[68:71]
	v_mfma_f32_16x16x32_bf16 v[64:67], v[152:155], v[198:201], v[64:67]
	v_mfma_f32_16x16x32_bf16 v[116:119], v[148:151], v[164:167], v[116:119]
	v_mfma_f32_16x16x32_bf16 v[108:111], v[156:159], v[164:167], v[108:111]
	v_mfma_f32_16x16x32_bf16 v[100:103], v[148:151], v[172:175], v[100:103]
	v_mfma_f32_16x16x32_bf16 v[92:95], v[156:159], v[172:175], v[92:95]
	v_mfma_f32_16x16x32_bf16 v[80:83], v[148:151], v[194:197], v[80:83]
	v_mfma_f32_16x16x32_bf16 v[72:75], v[156:159], v[194:197], v[72:75]
	v_mfma_f32_16x16x32_bf16 v[68:71], v[148:151], v[216:219], v[68:71]
	v_mfma_f32_16x16x32_bf16 v[64:67], v[156:159], v[216:219], v[64:67]
	s_setprio 0
	s_barrier
	s_add_i32 s53, s35, s22
	v_lshl_add_u64 v[202:203], s[18:19], 0, v[176:177]
	s_mov_b32 m0, s53
	ds_read_b128 v[160:163], v214 offset:16384
	ds_read_b128 v[164:167], v214 offset:17408
	ds_read_b128 v[168:171], v214 offset:18432
	ds_read_b128 v[172:175], v214 offset:19456
	ds_read_b128 v[190:193], v214 offset:20480
	ds_read_b128 v[194:197], v214 offset:21504
	ds_read_b128 v[198:201], v214 offset:22528
	ds_read_b128 v[216:219], v214 offset:23552
	global_load_lds_dwordx4 v[202:203], off
	s_add_i32 m0, s53, 0x2000
	s_add_u32 s54, s18, 0xb0000
	v_lshl_add_u64 v[220:221], s[18:19], 0, v[178:179]
	s_addc_u32 s55, s19, 0
	s_add_i32 s53, s36, s22
	global_load_lds_dwordx4 v[220:221], off
	v_lshl_add_u64 v[222:223], s[54:55], 0, v[176:177]
	s_mov_b32 m0, s53
	v_lshl_add_u64 v[224:225], s[20:21], 0, v[178:179]
	global_load_lds_dwordx4 v[222:223], off
	v_lshl_add_u64 v[222:223], s[54:55], 0, v[178:179]
	s_add_i32 m0, s53, 0x2000
	s_nop 0
	global_load_lds_dwordx4 v[222:223], off
	v_lshl_add_u64 v[222:223], s[20:21], 0, v[176:177]
	s_mov_b32 m0, s23
	s_nop 0
	global_load_lds_dwordx4 v[222:223], off
	s_mov_b32 m0, s24
	s_nop 0
	global_load_lds_dwordx4 v[224:225], off
	s_waitcnt vmcnt(8)
	s_waitcnt lgkmcnt(0)
	s_barrier
	s_setprio 1
	s_waitcnt lgkmcnt(0)
	v_mfma_f32_16x16x32_bf16 v[60:63], v[128:131], v[160:163], v[60:63]
	v_mfma_f32_16x16x32_bf16 v[56:59], v[136:139], v[160:163], v[56:59]
	v_mfma_f32_16x16x32_bf16 v[48:51], v[128:131], v[168:171], v[48:51]
	v_mfma_f32_16x16x32_bf16 v[40:43], v[136:139], v[168:171], v[40:43]
	v_mfma_f32_16x16x32_bf16 v[32:35], v[128:131], v[190:193], v[32:35]
	v_mfma_f32_16x16x32_bf16 v[24:27], v[136:139], v[190:193], v[24:27]
	v_mfma_f32_16x16x32_bf16 v[20:23], v[128:131], v[198:201], v[20:23]
	v_mfma_f32_16x16x32_bf16 v[12:15], v[136:139], v[198:201], v[12:15]
	v_mfma_f32_16x16x32_bf16 v[60:63], v[132:135], v[164:167], v[60:63]
	v_mfma_f32_16x16x32_bf16 v[56:59], v[140:143], v[164:167], v[56:59]
	v_mfma_f32_16x16x32_bf16 v[48:51], v[132:135], v[172:175], v[48:51]
	v_mfma_f32_16x16x32_bf16 v[40:43], v[140:143], v[172:175], v[40:43]
	v_mfma_f32_16x16x32_bf16 v[32:35], v[132:135], v[194:197], v[32:35]
	v_mfma_f32_16x16x32_bf16 v[24:27], v[140:143], v[194:197], v[24:27]
	v_mfma_f32_16x16x32_bf16 v[20:23], v[132:135], v[216:219], v[20:23]
	v_mfma_f32_16x16x32_bf16 v[12:15], v[140:143], v[216:219], v[12:15]
	s_setprio 0
	s_setprio 1
	v_mfma_f32_16x16x32_bf16 v[52:55], v[144:147], v[160:163], v[52:55]
	v_mfma_f32_16x16x32_bf16 v[44:47], v[152:155], v[160:163], v[44:47]
	v_mfma_f32_16x16x32_bf16 v[36:39], v[144:147], v[168:171], v[36:39]
	v_mfma_f32_16x16x32_bf16 v[28:31], v[152:155], v[168:171], v[28:31]
	v_mfma_f32_16x16x32_bf16 v[16:19], v[144:147], v[190:193], v[16:19]
	v_mfma_f32_16x16x32_bf16 v[8:11], v[152:155], v[190:193], v[8:11]
	v_mfma_f32_16x16x32_bf16 v[4:7], v[144:147], v[198:201], v[4:7]
	v_mfma_f32_16x16x32_bf16 v[0:3], v[152:155], v[198:201], v[0:3]
	v_mfma_f32_16x16x32_bf16 v[52:55], v[148:151], v[164:167], v[52:55]
	v_mfma_f32_16x16x32_bf16 v[44:47], v[156:159], v[164:167], v[44:47]
	v_mfma_f32_16x16x32_bf16 v[36:39], v[148:151], v[172:175], v[36:39]
	v_mfma_f32_16x16x32_bf16 v[28:31], v[156:159], v[172:175], v[28:31]
	v_mfma_f32_16x16x32_bf16 v[16:19], v[148:151], v[194:197], v[16:19]
	v_mfma_f32_16x16x32_bf16 v[8:11], v[156:159], v[194:197], v[8:11]
	v_mfma_f32_16x16x32_bf16 v[4:7], v[148:151], v[216:219], v[4:7]
	v_mfma_f32_16x16x32_bf16 v[0:3], v[156:159], v[216:219], v[0:3]
	s_setprio 0
	s_barrier
	s_add_i32 s53, 0, 0x18000
	s_add_i32 s54, 0, 0x1c000
	v_add_u32_e32 v140, s53, v210
	v_add_u32_e32 v156, s54, v210
	ds_read_b128 v[128:131], v140
	ds_read_b128 v[132:135], v140 offset:1024
	ds_read_b128 v[136:139], v140 offset:2048
	ds_read_b128 v[140:143], v140 offset:3072
	ds_read_b128 v[144:147], v156
	ds_read_b128 v[148:151], v156 offset:1024
	ds_read_b128 v[152:155], v156 offset:2048
	ds_read_b128 v[156:159], v156 offset:3072
	s_add_u32 s20, s20, 0xb0000
	s_addc_u32 s21, s21, 0
	s_mov_b32 m0, s25
	v_lshl_add_u64 v[226:227], s[20:21], 0, v[176:177]
	ds_read_b128 v[160:163], v214 offset:32768
	ds_read_b128 v[164:167], v214 offset:33792
	ds_read_b128 v[168:171], v214 offset:34816
	ds_read_b128 v[172:175], v214 offset:35840
	ds_read_b128 v[190:193], v214 offset:36864
	ds_read_b128 v[194:197], v214 offset:37888
	ds_read_b128 v[198:201], v214 offset:38912
	ds_read_b128 v[216:219], v214 offset:39936
	global_load_lds_dwordx4 v[226:227], off
	v_lshl_add_u64 v[226:227], s[20:21], 0, v[178:179]
	s_mov_b32 m0, s26
	s_nop 0
	global_load_lds_dwordx4 v[226:227], off
	s_waitcnt vmcnt(8)
	s_waitcnt lgkmcnt(0)
	s_barrier
	s_setprio 1
	s_waitcnt lgkmcnt(0)
	v_mfma_f32_16x16x32_bf16 v[124:127], v[128:131], v[160:163], v[124:127]
	v_mfma_f32_16x16x32_bf16 v[120:123], v[136:139], v[160:163], v[120:123]
	v_mfma_f32_16x16x32_bf16 v[112:115], v[128:131], v[168:171], v[112:115]
	v_mfma_f32_16x16x32_bf16 v[104:107], v[136:139], v[168:171], v[104:107]
	v_mfma_f32_16x16x32_bf16 v[96:99], v[128:131], v[190:193], v[96:99]
	v_mfma_f32_16x16x32_bf16 v[88:91], v[136:139], v[190:193], v[88:91]
	v_mfma_f32_16x16x32_bf16 v[84:87], v[128:131], v[198:201], v[84:87]
	v_mfma_f32_16x16x32_bf16 v[76:79], v[136:139], v[198:201], v[76:79]
	v_mfma_f32_16x16x32_bf16 v[124:127], v[132:135], v[164:167], v[124:127]
	v_mfma_f32_16x16x32_bf16 v[120:123], v[140:143], v[164:167], v[120:123]
	v_mfma_f32_16x16x32_bf16 v[112:115], v[132:135], v[172:175], v[112:115]
	v_mfma_f32_16x16x32_bf16 v[104:107], v[140:143], v[172:175], v[104:107]
	v_mfma_f32_16x16x32_bf16 v[96:99], v[132:135], v[194:197], v[96:99]
	v_mfma_f32_16x16x32_bf16 v[88:91], v[140:143], v[194:197], v[88:91]
	v_mfma_f32_16x16x32_bf16 v[84:87], v[132:135], v[216:219], v[84:87]
	v_mfma_f32_16x16x32_bf16 v[76:79], v[140:143], v[216:219], v[76:79]
	s_setprio 0
	s_setprio 1
	v_mfma_f32_16x16x32_bf16 v[116:119], v[144:147], v[160:163], v[116:119]
	v_mfma_f32_16x16x32_bf16 v[108:111], v[152:155], v[160:163], v[108:111]
	v_mfma_f32_16x16x32_bf16 v[100:103], v[144:147], v[168:171], v[100:103]
	v_mfma_f32_16x16x32_bf16 v[92:95], v[152:155], v[168:171], v[92:95]
	v_mfma_f32_16x16x32_bf16 v[80:83], v[144:147], v[190:193], v[80:83]
	v_mfma_f32_16x16x32_bf16 v[72:75], v[152:155], v[190:193], v[72:75]
	v_mfma_f32_16x16x32_bf16 v[68:71], v[144:147], v[198:201], v[68:71]
	v_mfma_f32_16x16x32_bf16 v[64:67], v[152:155], v[198:201], v[64:67]
	v_mfma_f32_16x16x32_bf16 v[116:119], v[148:151], v[164:167], v[116:119]
	v_mfma_f32_16x16x32_bf16 v[108:111], v[156:159], v[164:167], v[108:111]
	v_mfma_f32_16x16x32_bf16 v[100:103], v[148:151], v[172:175], v[100:103]
	v_mfma_f32_16x16x32_bf16 v[92:95], v[156:159], v[172:175], v[92:95]
	v_mfma_f32_16x16x32_bf16 v[80:83], v[148:151], v[194:197], v[80:83]
	v_mfma_f32_16x16x32_bf16 v[72:75], v[156:159], v[194:197], v[72:75]
	v_mfma_f32_16x16x32_bf16 v[68:71], v[148:151], v[216:219], v[68:71]
	v_mfma_f32_16x16x32_bf16 v[64:67], v[156:159], v[216:219], v[64:67]
	s_setprio 0
	s_barrier
	s_add_i32 s20, s53, s22
	v_lshl_add_u64 v[202:203], v[202:203], 0, s[10:11]
	s_mov_b32 m0, s20
	ds_read_b128 v[160:163], v214 offset:49152
	ds_read_b128 v[164:167], v214 offset:50176
	ds_read_b128 v[168:171], v214 offset:51200
	ds_read_b128 v[172:175], v214 offset:52224
	ds_read_b128 v[190:193], v214 offset:53248
	ds_read_b128 v[194:197], v214 offset:54272
	ds_read_b128 v[198:201], v214 offset:55296
	ds_read_b128 v[216:219], v214 offset:56320
	global_load_lds_dwordx4 v[202:203], off
	s_add_i32 m0, s20, 0x2000
	s_add_u32 s18, s18, 0xb0080
	v_lshl_add_u64 v[202:203], v[220:221], 0, s[10:11]
	s_addc_u32 s19, s19, 0
	s_add_i32 s20, s54, s22
	global_load_lds_dwordx4 v[202:203], off
	v_lshl_add_u64 v[202:203], s[18:19], 0, v[176:177]
	s_mov_b32 m0, s20
	s_nop 0
	global_load_lds_dwordx4 v[202:203], off
	v_lshl_add_u64 v[202:203], s[18:19], 0, v[178:179]
	s_add_i32 m0, s20, 0x2000
	s_nop 0
	global_load_lds_dwordx4 v[202:203], off
	v_lshl_add_u64 v[202:203], v[222:223], 0, s[10:11]
	s_mov_b32 m0, s29
	s_nop 0
	global_load_lds_dwordx4 v[202:203], off
	v_lshl_add_u64 v[202:203], v[224:225], 0, s[10:11]
	s_mov_b32 m0, s30
	s_nop 0
	global_load_lds_dwordx4 v[202:203], off
	s_waitcnt vmcnt(8)
	s_waitcnt lgkmcnt(0)
	s_barrier
	s_setprio 1
	s_waitcnt lgkmcnt(0)
	v_mfma_f32_16x16x32_bf16 v[60:63], v[128:131], v[160:163], v[60:63]
	v_mfma_f32_16x16x32_bf16 v[56:59], v[136:139], v[160:163], v[56:59]
	v_mfma_f32_16x16x32_bf16 v[48:51], v[128:131], v[168:171], v[48:51]
	v_mfma_f32_16x16x32_bf16 v[40:43], v[136:139], v[168:171], v[40:43]
	v_mfma_f32_16x16x32_bf16 v[32:35], v[128:131], v[190:193], v[32:35]
	v_mfma_f32_16x16x32_bf16 v[24:27], v[136:139], v[190:193], v[24:27]
	v_mfma_f32_16x16x32_bf16 v[20:23], v[128:131], v[198:201], v[20:23]
	v_mfma_f32_16x16x32_bf16 v[12:15], v[136:139], v[198:201], v[12:15]
	v_mfma_f32_16x16x32_bf16 v[60:63], v[132:135], v[164:167], v[60:63]
	v_mfma_f32_16x16x32_bf16 v[56:59], v[140:143], v[164:167], v[56:59]
	v_mfma_f32_16x16x32_bf16 v[48:51], v[132:135], v[172:175], v[48:51]
	v_mfma_f32_16x16x32_bf16 v[40:43], v[140:143], v[172:175], v[40:43]
	v_mfma_f32_16x16x32_bf16 v[32:35], v[132:135], v[194:197], v[32:35]
	v_mfma_f32_16x16x32_bf16 v[24:27], v[140:143], v[194:197], v[24:27]
	v_mfma_f32_16x16x32_bf16 v[20:23], v[132:135], v[216:219], v[20:23]
	v_mfma_f32_16x16x32_bf16 v[12:15], v[140:143], v[216:219], v[12:15]
	s_setprio 0
	s_setprio 1
	v_mfma_f32_16x16x32_bf16 v[52:55], v[144:147], v[160:163], v[52:55]
	v_mfma_f32_16x16x32_bf16 v[44:47], v[152:155], v[160:163], v[44:47]
	v_mfma_f32_16x16x32_bf16 v[36:39], v[144:147], v[168:171], v[36:39]
	v_mfma_f32_16x16x32_bf16 v[28:31], v[152:155], v[168:171], v[28:31]
	v_mfma_f32_16x16x32_bf16 v[16:19], v[144:147], v[190:193], v[16:19]
	v_mfma_f32_16x16x32_bf16 v[8:11], v[152:155], v[190:193], v[8:11]
	v_mfma_f32_16x16x32_bf16 v[4:7], v[144:147], v[198:201], v[4:7]
	v_mfma_f32_16x16x32_bf16 v[0:3], v[152:155], v[198:201], v[0:3]
	v_mfma_f32_16x16x32_bf16 v[52:55], v[148:151], v[164:167], v[52:55]
	v_mfma_f32_16x16x32_bf16 v[44:47], v[156:159], v[164:167], v[44:47]
	v_mfma_f32_16x16x32_bf16 v[36:39], v[148:151], v[172:175], v[36:39]
	v_mfma_f32_16x16x32_bf16 v[28:31], v[156:159], v[172:175], v[28:31]
	v_mfma_f32_16x16x32_bf16 v[16:19], v[148:151], v[194:197], v[16:19]
	v_mfma_f32_16x16x32_bf16 v[8:11], v[156:159], v[194:197], v[8:11]
	v_mfma_f32_16x16x32_bf16 v[4:7], v[148:151], v[216:219], v[4:7]
	v_mfma_f32_16x16x32_bf16 v[0:3], v[156:159], v[216:219], v[0:3]
	s_setprio 0
	s_barrier
	s_add_i32 s52, s52, 2
	s_add_u32 s16, s16, 0x100
	s_addc_u32 s17, s17, 0
	s_add_u32 s50, s50, 0x100
	s_addc_u32 s51, s51, 0
	s_cmp_gt_u32 s52, 41
	s_cbranch_scc0 .LBB0_2476
	s_and_b64 vcc, exec, s[12:13]
	s_cbranch_vccz .LBB0_2479
	s_barrier
.LBB0_2479:
	v_lshl_add_u32 v192, s48, 8, v209
	v_add_u32_e32 v130, 0xffffc000, v192
	v_ashrrev_i32_e32 v193, 31, v192
	v_cmp_gt_i32_e32 vcc, s28, v192
	v_lshl_or_b32 v128, s49, 8, v211
	v_mov_b32_e32 v134, s9
	v_cndmask_b32_e32 v131, 0, v193, vcc
	v_cndmask_b32_e32 v130, v130, v192, vcc
	v_mov_b32_e32 v135, s89
	v_mov_b32_e32 v136, s8
	v_mov_b32_e32 v137, s88
	v_ashrrev_i32_e32 v129, 31, v128
	v_cndmask_b32_e32 v133, v134, v135, vcc
	v_cndmask_b32_e32 v132, v136, v137, vcc
	v_lshlrev_b64 v[130:131], 12, v[130:131]
	v_lshl_add_u64 v[130:131], v[132:133], 0, v[130:131]
	v_lshlrev_b64 v[190:191], 2, v[128:129]
	v_lshl_add_u64 v[128:129], v[130:131], 0, v[190:191]
	v_or_b32_e32 v198, 16, v192
	global_load_dwordx4 v[172:175], v[128:129], off
	global_load_dwordx4 v[168:171], v[128:129], off offset:64
	global_load_dwordx4 v[164:167], v[128:129], off offset:512
	global_load_dwordx4 v[156:159], v[128:129], off offset:576
	v_ashrrev_i32_e32 v199, 31, v198
	v_add_u32_e32 v128, 0xffffc010, v192
	v_cmp_gt_i32_e32 vcc, s28, v198
	v_or_b32_e32 v196, 32, v192
	v_ashrrev_i32_e32 v197, 31, v196
	v_cndmask_b32_e32 v129, 0, v199, vcc
	v_cndmask_b32_e32 v128, v128, v198, vcc
	v_cndmask_b32_e32 v131, v134, v135, vcc
	v_cndmask_b32_e32 v130, v136, v137, vcc
	v_lshlrev_b64 v[128:129], 12, v[128:129]
	v_lshl_add_u64 v[128:129], v[130:131], 0, v[128:129]
	v_lshl_add_u64 v[128:129], v[128:129], 0, v[190:191]
	global_load_dwordx4 v[160:163], v[128:129], off
	global_load_dwordx4 v[152:155], v[128:129], off offset:64
	global_load_dwordx4 v[148:151], v[128:129], off offset:512
	global_load_dwordx4 v[140:143], v[128:129], off offset:576
	v_add_u32_e32 v128, 0xffffc020, v192
	v_cmp_gt_i32_e32 vcc, s28, v196
	v_or_b32_e32 v200, 48, v192
	s_nop 0
	v_cndmask_b32_e32 v129, 0, v197, vcc
	v_cndmask_b32_e32 v128, v128, v196, vcc
	v_cndmask_b32_e32 v131, v134, v135, vcc
	v_cndmask_b32_e32 v130, v136, v137, vcc
	v_lshlrev_b64 v[128:129], 12, v[128:129]
	v_lshl_add_u64 v[128:129], v[130:131], 0, v[128:129]
	v_lshl_add_u64 v[128:129], v[128:129], 0, v[190:191]
	global_load_dwordx4 v[144:147], v[128:129], off
	global_load_dwordx4 v[136:139], v[128:129], off offset:64
	global_load_dwordx4 v[132:135], v[128:129], off offset:512
	s_nop 0
	global_load_dwordx4 v[128:131], v[128:129], off offset:576
	v_cmp_lt_i32_e32 vcc, s37, v200
	s_and_saveexec_b64 s[16:17], vcc
	s_xor_b64 s[16:17], exec, s[16:17]
	v_add_u32_e32 v180, 0xffffc030, v192
	v_lshlrev_b64 v[194:195], 12, v[180:181]
	v_mov_b32_e32 v201, v181
	v_lshl_add_u64 v[202:203], s[8:9], 0, v[194:195]
	v_lshlrev_b64 v[194:195], 12, v[200:201]
	s_andn2_saveexec_b64 s[16:17], s[16:17]
	v_ashrrev_i32_e32 v201, 31, v200
	v_lshlrev_b64 v[194:195], 12, v[200:201]
	v_lshl_add_u64 v[202:203], s[88:89], 0, v[194:195]
	s_or_b64 exec, exec, s[16:17]
	v_lshl_add_u64 v[224:225], v[202:203], 0, v[190:191]
	global_load_dwordx4 v[200:203], v[224:225], off
	global_load_dwordx4 v[216:219], v[224:225], off offset:64
	global_load_dwordx4 v[220:223], v[224:225], off offset:512
	s_nop 0
	global_load_dwordx4 v[224:227], v[224:225], off offset:576
	v_lshlrev_b64 v[228:229], 12, v[192:193]
	v_lshl_add_u64 v[228:229], s[88:89], 0, v[228:229]
	v_lshl_add_u64 v[228:229], v[228:229], 0, v[190:191]
	s_waitcnt vmcnt(0)
	v_pk_add_f32 v[110:111], v[110:111], v[158:159]
	v_pk_add_f32 v[108:109], v[108:109], v[156:157]
	global_store_dwordx4 v[228:229], v[108:111], off offset:576
	v_pk_add_f32 v[118:119], v[118:119], v[166:167]
	v_pk_add_f32 v[116:117], v[116:117], v[164:165]
	v_lshlrev_b64 v[108:109], 12, v[198:199]
	v_lshl_add_u64 v[108:109], s[88:89], 0, v[108:109]
	global_store_dwordx4 v[228:229], v[116:119], off offset:512
	v_pk_add_f32 v[94:95], v[94:95], v[142:143]
	v_pk_add_f32 v[92:93], v[92:93], v[140:141]
	v_lshl_add_u64 v[116:117], v[108:109], 0, v[190:191]
	global_store_dwordx4 v[116:117], v[92:95], off offset:576
	v_pk_add_f32 v[102:103], v[102:103], v[150:151]
	v_pk_add_f32 v[100:101], v[100:101], v[148:149]
	v_lshlrev_b64 v[92:93], 12, v[196:197]
	v_lshl_add_u64 v[92:93], s[88:89], 0, v[92:93]
	global_store_dwordx4 v[116:117], v[100:103], off offset:512
	v_pk_add_f32 v[74:75], v[74:75], v[130:131]
	v_pk_add_f32 v[72:73], v[72:73], v[128:129]
	v_lshl_add_u64 v[100:101], v[92:93], 0, v[190:191]
	v_pk_add_f32 v[82:83], v[82:83], v[134:135]
	v_pk_add_f32 v[80:81], v[80:81], v[132:133]
	global_store_dwordx4 v[100:101], v[72:75], off offset:576
	v_pk_add_f32 v[126:127], v[126:127], v[174:175]
	v_pk_add_f32 v[124:125], v[124:125], v[172:173]
	v_lshl_add_u64 v[72:73], s[88:89], 0, v[194:195]
	v_pk_add_f32 v[122:123], v[122:123], v[170:171]
	v_pk_add_f32 v[120:121], v[120:121], v[168:169]
	v_pk_add_f32 v[110:111], v[114:115], v[162:163]
	v_pk_add_f32 v[108:109], v[112:113], v[160:161]
	v_pk_add_f32 v[106:107], v[106:107], v[154:155]
	v_pk_add_f32 v[104:105], v[104:105], v[152:153]
	v_pk_add_f32 v[94:95], v[98:99], v[146:147]
	v_pk_add_f32 v[92:93], v[96:97], v[144:145]
	v_pk_add_f32 v[90:91], v[90:91], v[138:139]
	v_pk_add_f32 v[88:89], v[88:89], v[136:137]
	global_store_dwordx4 v[100:101], v[80:83], off offset:512
	v_pk_add_f32 v[74:75], v[86:87], v[202:203]
	global_store_dwordx4 v[228:229], v[124:127], off
	v_lshl_add_u64 v[80:81], v[72:73], 0, v[190:191]
	v_pk_add_f32 v[72:73], v[84:85], v[200:201]
	global_store_dwordx4 v[228:229], v[120:123], off offset:64
	global_store_dwordx4 v[116:117], v[108:111], off
	global_store_dwordx4 v[116:117], v[104:107], off offset:64
	global_store_dwordx4 v[100:101], v[92:95], off
	global_store_dwordx4 v[100:101], v[88:91], off offset:64
	global_store_dwordx4 v[80:81], v[72:75], off
	v_pk_add_f32 v[70:71], v[70:71], v[222:223]
	v_pk_add_f32 v[68:69], v[68:69], v[220:221]
	v_pk_add_f32 v[74:75], v[78:79], v[218:219]
	v_pk_add_f32 v[72:73], v[76:77], v[216:217]
	v_pk_add_f32 v[66:67], v[66:67], v[226:227]
	v_pk_add_f32 v[64:65], v[64:65], v[224:225]
	global_store_dwordx4 v[80:81], v[72:75], off offset:64
	global_store_dwordx4 v[80:81], v[68:71], off offset:512
	global_store_dwordx4 v[80:81], v[64:67], off offset:576
	v_add_u32_e32 v118, 0x80, v192
	v_ashrrev_i32_e32 v119, 31, v118
	v_add_u32_e32 v64, 0xffffc080, v192
	v_cmp_gt_i32_e32 vcc, s38, v192
	v_mov_b32_e32 v68, s9
	v_mov_b32_e32 v69, s89
	v_cndmask_b32_e32 v65, 0, v119, vcc
	v_cndmask_b32_e32 v64, v64, v118, vcc
	v_mov_b32_e32 v70, s8
	v_mov_b32_e32 v71, s88
	v_cndmask_b32_e32 v67, v68, v69, vcc
	v_cndmask_b32_e32 v66, v70, v71, vcc
	v_lshlrev_b64 v[64:65], 12, v[64:65]
	v_lshl_add_u64 v[64:65], v[66:67], 0, v[64:65]
	v_lshl_add_u64 v[64:65], v[64:65], 0, v[190:191]
	v_add_u32_e32 v116, 0x90, v192
	global_load_dwordx4 v[108:111], v[64:65], off
	global_load_dwordx4 v[104:107], v[64:65], off offset:64
	global_load_dwordx4 v[100:103], v[64:65], off offset:512
	global_load_dwordx4 v[92:95], v[64:65], off offset:576
	v_ashrrev_i32_e32 v117, 31, v116
	v_add_u32_e32 v64, 0xffffc090, v192
	v_cmp_gt_i32_e32 vcc, s39, v192
	v_add_u32_e32 v114, 0xa0, v192
	v_ashrrev_i32_e32 v115, 31, v114
	v_cndmask_b32_e32 v65, 0, v117, vcc
	v_cndmask_b32_e32 v64, v64, v116, vcc
	v_cndmask_b32_e32 v67, v68, v69, vcc
	v_cndmask_b32_e32 v66, v70, v71, vcc
	v_lshlrev_b64 v[64:65], 12, v[64:65]
	v_lshl_add_u64 v[64:65], v[66:67], 0, v[64:65]
	v_lshl_add_u64 v[64:65], v[64:65], 0, v[190:191]
	global_load_dwordx4 v[96:99], v[64:65], off
	global_load_dwordx4 v[88:91], v[64:65], off offset:64
	global_load_dwordx4 v[84:87], v[64:65], off offset:512
	global_load_dwordx4 v[76:79], v[64:65], off offset:576
	v_add_u32_e32 v64, 0xffffc0a0, v192
	v_cmp_gt_i32_e32 vcc, s40, v192
	v_add_u32_e32 v120, 0xb0, v192
	s_nop 0
	v_cndmask_b32_e32 v65, 0, v115, vcc
	v_cndmask_b32_e32 v64, v64, v114, vcc
	v_cndmask_b32_e32 v67, v68, v69, vcc
	v_cndmask_b32_e32 v66, v70, v71, vcc
	v_lshlrev_b64 v[64:65], 12, v[64:65]
	v_lshl_add_u64 v[64:65], v[66:67], 0, v[64:65]
	v_lshl_add_u64 v[64:65], v[64:65], 0, v[190:191]
	global_load_dwordx4 v[80:83], v[64:65], off
	global_load_dwordx4 v[72:75], v[64:65], off offset:64
	global_load_dwordx4 v[68:71], v[64:65], off offset:512
	s_nop 0
	global_load_dwordx4 v[64:67], v[64:65], off offset:576
	v_cmp_lt_i32_e32 vcc, s41, v192
	s_and_saveexec_b64 s[16:17], vcc
	s_xor_b64 s[16:17], exec, s[16:17]
	v_add_u32_e32 v180, 0xffffc0b0, v192
	v_lshlrev_b64 v[112:113], 12, v[180:181]
	v_mov_b32_e32 v121, v181
	v_lshl_add_u64 v[122:123], s[8:9], 0, v[112:113]
	v_lshlrev_b64 v[112:113], 12, v[120:121]
	s_andn2_saveexec_b64 s[16:17], s[16:17]
	v_ashrrev_i32_e32 v121, 31, v120
	v_lshlrev_b64 v[112:113], 12, v[120:121]
	v_lshl_add_u64 v[122:123], s[88:89], 0, v[112:113]
	s_or_b64 exec, exec, s[16:17]
	v_lshl_add_u64 v[132:133], v[122:123], 0, v[190:191]
	global_load_dwordx4 v[120:123], v[132:133], off
	global_load_dwordx4 v[124:127], v[132:133], off offset:64
	global_load_dwordx4 v[128:131], v[132:133], off offset:512
	s_nop 0
	global_load_dwordx4 v[132:135], v[132:133], off offset:576
	v_lshlrev_b64 v[118:119], 12, v[118:119]
	v_lshl_add_u64 v[118:119], s[88:89], 0, v[118:119]
	v_lshl_add_u64 v[118:119], v[118:119], 0, v[190:191]
	s_waitcnt vmcnt(12)
	v_pk_add_f32 v[46:47], v[46:47], v[94:95]
	v_pk_add_f32 v[44:45], v[44:45], v[92:93]
	global_store_dwordx4 v[118:119], v[44:47], off offset:576
	v_pk_add_f32 v[54:55], v[54:55], v[102:103]
	v_pk_add_f32 v[52:53], v[52:53], v[100:101]
	v_lshlrev_b64 v[44:45], 12, v[116:117]
	v_lshl_add_u64 v[44:45], s[88:89], 0, v[44:45]
	global_store_dwordx4 v[118:119], v[52:55], off offset:512
	s_waitcnt vmcnt(10)
	v_pk_add_f32 v[30:31], v[30:31], v[78:79]
	v_pk_add_f32 v[28:29], v[28:29], v[76:77]
	v_lshl_add_u64 v[52:53], v[44:45], 0, v[190:191]
	global_store_dwordx4 v[52:53], v[28:31], off offset:576
	v_pk_add_f32 v[38:39], v[38:39], v[86:87]
	v_pk_add_f32 v[36:37], v[36:37], v[84:85]
	v_lshlrev_b64 v[28:29], 12, v[114:115]
	v_lshl_add_u64 v[28:29], s[88:89], 0, v[28:29]
	global_store_dwordx4 v[52:53], v[36:39], off offset:512
	s_waitcnt vmcnt(8)
	v_pk_add_f32 v[10:11], v[10:11], v[66:67]
	v_pk_add_f32 v[8:9], v[8:9], v[64:65]
	v_lshl_add_u64 v[36:37], v[28:29], 0, v[190:191]
	v_pk_add_f32 v[18:19], v[18:19], v[70:71]
	v_pk_add_f32 v[16:17], v[16:17], v[68:69]
	global_store_dwordx4 v[36:37], v[8:11], off offset:576
	v_pk_add_f32 v[62:63], v[62:63], v[110:111]
	v_pk_add_f32 v[60:61], v[60:61], v[108:109]
	v_lshl_add_u64 v[8:9], s[88:89], 0, v[112:113]
	v_pk_add_f32 v[58:59], v[58:59], v[106:107]
	v_pk_add_f32 v[56:57], v[56:57], v[104:105]
	v_pk_add_f32 v[46:47], v[50:51], v[98:99]
	v_pk_add_f32 v[44:45], v[48:49], v[96:97]
	v_pk_add_f32 v[42:43], v[42:43], v[90:91]
	v_pk_add_f32 v[40:41], v[40:41], v[88:89]
	v_pk_add_f32 v[30:31], v[34:35], v[82:83]
	v_pk_add_f32 v[28:29], v[32:33], v[80:81]
	v_pk_add_f32 v[26:27], v[26:27], v[74:75]
	v_pk_add_f32 v[24:25], v[24:25], v[72:73]
	global_store_dwordx4 v[36:37], v[16:19], off offset:512
	s_waitcnt vmcnt(9)
	v_pk_add_f32 v[10:11], v[22:23], v[122:123]
	global_store_dwordx4 v[118:119], v[60:63], off
	v_lshl_add_u64 v[16:17], v[8:9], 0, v[190:191]
	v_pk_add_f32 v[8:9], v[20:21], v[120:121]
	global_store_dwordx4 v[118:119], v[56:59], off offset:64
	global_store_dwordx4 v[52:53], v[44:47], off
	global_store_dwordx4 v[52:53], v[40:43], off offset:64
	global_store_dwordx4 v[36:37], v[28:31], off
	global_store_dwordx4 v[36:37], v[24:27], off offset:64
	global_store_dwordx4 v[16:17], v[8:11], off
	s_waitcnt vmcnt(14)
	v_pk_add_f32 v[6:7], v[6:7], v[130:131]
	v_pk_add_f32 v[4:5], v[4:5], v[128:129]
	v_pk_add_f32 v[10:11], v[14:15], v[126:127]
	v_pk_add_f32 v[8:9], v[12:13], v[124:125]
	s_waitcnt vmcnt(13)
	v_pk_add_f32 v[2:3], v[2:3], v[134:135]
	v_pk_add_f32 v[0:1], v[0:1], v[132:133]
	global_store_dwordx4 v[16:17], v[8:11], off offset:64
	global_store_dwordx4 v[16:17], v[4:7], off offset:512
	global_store_dwordx4 v[16:17], v[0:3], off offset:576
	s_and_b64 vcc, exec, s[2:3]
	s_mov_b64 s[2:3], -1
	s_cbranch_vccnz .LBB0_2464
	s_andn2_b64 vcc, exec, s[6:7]
	s_cbranch_vccnz .LBB0_2463
	v_writelane_b32 v255, 1, 53
	s_branch .LBB0_2463

.LBB0_2503:
	v_mov_b32_e32 v0, 0
	s_mov_b32 s34, 0
	s_mov_b64 s[28:29], -1
	s_mov_b64 s[30:31], 0
	v_mov_b32_e32 v1, v0
	v_mov_b32_e32 v2, v0
	v_mov_b32_e32 v3, v0
	v_mov_b32_e32 v4, v0
	v_mov_b32_e32 v5, v0
	v_mov_b32_e32 v6, v0
	v_mov_b32_e32 v7, v0
	v_mov_b32_e32 v8, v0
	v_mov_b32_e32 v9, v0
	v_mov_b32_e32 v10, v0
	v_mov_b32_e32 v11, v0
	v_mov_b32_e32 v12, v0
	v_mov_b32_e32 v13, v0
	v_mov_b32_e32 v14, v0
	v_mov_b32_e32 v15, v0
	v_mov_b32_e32 v20, v0
	v_mov_b32_e32 v21, v0
	v_mov_b32_e32 v22, v0
	v_mov_b32_e32 v23, v0
	v_mov_b32_e32 v28, v0
	v_mov_b32_e32 v29, v0
	v_mov_b32_e32 v30, v0
	v_mov_b32_e32 v31, v0
	v_mov_b32_e32 v36, v0
	v_mov_b32_e32 v37, v0
	v_mov_b32_e32 v38, v0
	v_mov_b32_e32 v39, v0
	v_mov_b32_e32 v44, v0
	v_mov_b32_e32 v45, v0
	v_mov_b32_e32 v46, v0
	v_mov_b32_e32 v47, v0
	v_mov_b32_e32 v16, v0
	v_mov_b32_e32 v17, v0
	v_mov_b32_e32 v18, v0
	v_mov_b32_e32 v19, v0
	v_mov_b32_e32 v24, v0
	v_mov_b32_e32 v25, v0
	v_mov_b32_e32 v26, v0
	v_mov_b32_e32 v27, v0
	v_mov_b32_e32 v32, v0
	v_mov_b32_e32 v33, v0
	v_mov_b32_e32 v34, v0
	v_mov_b32_e32 v35, v0
	v_mov_b32_e32 v40, v0
	v_mov_b32_e32 v41, v0
	v_mov_b32_e32 v42, v0
	v_mov_b32_e32 v43, v0
	v_mov_b32_e32 v48, v0
	v_mov_b32_e32 v49, v0
	v_mov_b32_e32 v50, v0
	v_mov_b32_e32 v51, v0
	v_mov_b32_e32 v52, v0
	v_mov_b32_e32 v53, v0
	v_mov_b32_e32 v54, v0
	v_mov_b32_e32 v55, v0
	v_mov_b32_e32 v56, v0
	v_mov_b32_e32 v57, v0
	v_mov_b32_e32 v58, v0
	v_mov_b32_e32 v59, v0
	v_mov_b32_e32 v60, v0
	v_mov_b32_e32 v61, v0
	v_mov_b32_e32 v62, v0
	v_mov_b32_e32 v63, v0
	v_mov_b32_e32 v64, v0
	v_mov_b32_e32 v65, v0
	v_mov_b32_e32 v66, v0
	v_mov_b32_e32 v67, v0
	v_mov_b32_e32 v68, v0
	v_mov_b32_e32 v69, v0
	v_mov_b32_e32 v70, v0
	v_mov_b32_e32 v71, v0
	v_mov_b32_e32 v72, v0
	v_mov_b32_e32 v73, v0
	v_mov_b32_e32 v74, v0
	v_mov_b32_e32 v75, v0
	v_mov_b32_e32 v76, v0
	v_mov_b32_e32 v77, v0
	v_mov_b32_e32 v78, v0
	v_mov_b32_e32 v79, v0
	v_mov_b32_e32 v80, v0
	v_mov_b32_e32 v81, v0
	v_mov_b32_e32 v82, v0
	v_mov_b32_e32 v83, v0
	v_mov_b32_e32 v88, v0
	v_mov_b32_e32 v89, v0
	v_mov_b32_e32 v90, v0
	v_mov_b32_e32 v91, v0
	v_mov_b32_e32 v96, v0
	v_mov_b32_e32 v97, v0
	v_mov_b32_e32 v98, v0
	v_mov_b32_e32 v99, v0
	v_mov_b32_e32 v104, v0
	v_mov_b32_e32 v105, v0
	v_mov_b32_e32 v106, v0
	v_mov_b32_e32 v107, v0
	v_mov_b32_e32 v84, v0
	v_mov_b32_e32 v85, v0
	v_mov_b32_e32 v86, v0
	v_mov_b32_e32 v87, v0
	v_mov_b32_e32 v92, v0
	v_mov_b32_e32 v93, v0
	v_mov_b32_e32 v94, v0
	v_mov_b32_e32 v95, v0
	v_mov_b32_e32 v100, v0
	v_mov_b32_e32 v101, v0
	v_mov_b32_e32 v102, v0
	v_mov_b32_e32 v103, v0
	v_mov_b32_e32 v108, v0
	v_mov_b32_e32 v109, v0
	v_mov_b32_e32 v110, v0
	v_mov_b32_e32 v111, v0
	v_mov_b32_e32 v112, v0
	v_mov_b32_e32 v113, v0
	v_mov_b32_e32 v114, v0
	v_mov_b32_e32 v115, v0
	v_mov_b32_e32 v116, v0
	v_mov_b32_e32 v117, v0
	v_mov_b32_e32 v118, v0
	v_mov_b32_e32 v119, v0
	v_mov_b32_e32 v120, v0
	v_mov_b32_e32 v121, v0
	v_mov_b32_e32 v122, v0
	v_mov_b32_e32 v123, v0
	v_mov_b32_e32 v124, v0
	v_mov_b32_e32 v125, v0
	v_mov_b32_e32 v126, v0
	v_mov_b32_e32 v127, v0
	v_readlane_b32 s97, v255, 53
	s_nop 3
	s_cmp_eq_u32 s97, 1
	s_cbranch_scc0 .Llsb_skip_22
	v_writelane_b32 v255, 0, 53
	s_barrier
.Llsb_skip_22:
.LBB0_2504:
	s_add_u32 s35, s22, s34
	s_addc_u32 s40, s23, 0
	s_add_u32 s38, s35, 0x100
	s_addc_u32 s39, s40, 0
	s_and_b64 s[36:37], s[30:31], exec
	s_cselect_b32 s37, s25, s39
	s_cselect_b32 s36, s24, s38
	s_add_u32 s34, s14, s34
	s_addc_u32 s38, s15, 0
	s_add_u32 s34, s34, 0x100
	s_addc_u32 s38, s38, 0
	ds_read_b128 v[136:139], v131
	ds_read_b128 v[140:143], v131 offset:1024
	ds_read_b128 v[144:147], v131 offset:2048
	ds_read_b128 v[148:151], v131 offset:3072
	ds_read_b128 v[152:155], v132
	ds_read_b128 v[156:159], v132 offset:1024
	ds_read_b128 v[160:163], v132 offset:2048
	ds_read_b128 v[164:167], v132 offset:3072
	s_and_b64 s[30:31], s[30:31], exec
	s_cselect_b32 s39, s27, s38
	s_cselect_b32 s38, s26, s34
	s_add_u32 s42, s35, 0xb0080
	s_addc_u32 s43, s40, 0
	s_add_u32 s40, s38, 0xb0000
	s_addc_u32 s41, s39, 0
	s_add_i32 s75, 0, 0x1c000
	s_add_u32 s34, s36, 0xb0000
	s_addc_u32 s35, s37, 0
	s_add_i32 s74, s69, s49
	s_add_i32 s73, s74, 0x2000
	s_add_u32 s30, s38, 0xb0080
	s_addc_u32 s31, s39, 0
	s_add_i32 s77, s75, s49
	s_add_i32 s76, s77, 0x2000
	s_mov_b32 m0, s63
	v_lshl_add_u64 v[206:207], s[42:43], 0, v[176:177]
	ds_read_b128 v[168:171], v133
	ds_read_b128 v[172:175], v133 offset:1024
	ds_read_b128 v[180:183], v133 offset:2048
	ds_read_b128 v[184:187], v133 offset:3072
	ds_read_b128 v[188:191], v133 offset:4096
	ds_read_b128 v[192:195], v133 offset:5120
	ds_read_b128 v[196:199], v133 offset:6144
	ds_read_b128 v[200:203], v133 offset:7168
	global_load_lds_dwordx4 v[206:207], off
	v_lshl_add_u64 v[206:207], s[42:43], 0, v[178:179]
	s_mov_b32 m0, s64
	s_nop 0
	global_load_lds_dwordx4 v[206:207], off
	s_waitcnt vmcnt(8)
	s_waitcnt lgkmcnt(0)
	s_barrier
	s_setprio 1
	s_waitcnt lgkmcnt(0)
	v_mfma_f32_16x16x32_bf16 v[124:127], v[136:139], v[168:171], v[124:127]
	v_mfma_f32_16x16x32_bf16 v[120:123], v[144:147], v[168:171], v[120:123]
	v_mfma_f32_16x16x32_bf16 v[116:119], v[136:139], v[180:183], v[116:119]
	v_mfma_f32_16x16x32_bf16 v[112:115], v[144:147], v[180:183], v[112:115]
	v_mfma_f32_16x16x32_bf16 v[108:111], v[136:139], v[188:191], v[108:111]
	v_mfma_f32_16x16x32_bf16 v[100:103], v[144:147], v[188:191], v[100:103]
	v_mfma_f32_16x16x32_bf16 v[92:95], v[136:139], v[196:199], v[92:95]
	v_mfma_f32_16x16x32_bf16 v[84:87], v[144:147], v[196:199], v[84:87]
	v_mfma_f32_16x16x32_bf16 v[124:127], v[140:143], v[172:175], v[124:127]
	v_mfma_f32_16x16x32_bf16 v[120:123], v[148:151], v[172:175], v[120:123]
	v_mfma_f32_16x16x32_bf16 v[116:119], v[140:143], v[184:187], v[116:119]
	v_mfma_f32_16x16x32_bf16 v[112:115], v[148:151], v[184:187], v[112:115]
	v_mfma_f32_16x16x32_bf16 v[108:111], v[140:143], v[192:195], v[108:111]
	v_mfma_f32_16x16x32_bf16 v[100:103], v[148:151], v[192:195], v[100:103]
	v_mfma_f32_16x16x32_bf16 v[92:95], v[140:143], v[200:203], v[92:95]
	v_mfma_f32_16x16x32_bf16 v[84:87], v[148:151], v[200:203], v[84:87]
	s_setprio 0
	s_setprio 1
	v_mfma_f32_16x16x32_bf16 v[104:107], v[152:155], v[168:171], v[104:107]
	v_mfma_f32_16x16x32_bf16 v[96:99], v[160:163], v[168:171], v[96:99]
	v_mfma_f32_16x16x32_bf16 v[88:91], v[152:155], v[180:183], v[88:91]
	v_mfma_f32_16x16x32_bf16 v[80:83], v[160:163], v[180:183], v[80:83]
	v_mfma_f32_16x16x32_bf16 v[76:79], v[152:155], v[188:191], v[76:79]
	v_mfma_f32_16x16x32_bf16 v[72:75], v[160:163], v[188:191], v[72:75]
	v_mfma_f32_16x16x32_bf16 v[68:71], v[152:155], v[196:199], v[68:71]
	v_mfma_f32_16x16x32_bf16 v[64:67], v[160:163], v[196:199], v[64:67]
	v_mfma_f32_16x16x32_bf16 v[104:107], v[156:159], v[172:175], v[104:107]
	v_mfma_f32_16x16x32_bf16 v[96:99], v[164:167], v[172:175], v[96:99]
	v_mfma_f32_16x16x32_bf16 v[88:91], v[156:159], v[184:187], v[88:91]
	v_mfma_f32_16x16x32_bf16 v[80:83], v[164:167], v[184:187], v[80:83]
	v_mfma_f32_16x16x32_bf16 v[76:79], v[156:159], v[192:195], v[76:79]
	v_mfma_f32_16x16x32_bf16 v[72:75], v[164:167], v[192:195], v[72:75]
	v_mfma_f32_16x16x32_bf16 v[68:71], v[156:159], v[200:203], v[68:71]
	v_mfma_f32_16x16x32_bf16 v[64:67], v[164:167], v[200:203], v[64:67]
	s_setprio 0
	s_barrier
	s_mov_b32 m0, s65
	v_lshl_add_u64 v[206:207], s[38:39], 0, v[176:177]
	ds_read_b128 v[168:171], v133 offset:16384
	ds_read_b128 v[172:175], v133 offset:17408
	ds_read_b128 v[180:183], v133 offset:18432
	ds_read_b128 v[184:187], v133 offset:19456
	ds_read_b128 v[188:191], v133 offset:20480
	ds_read_b128 v[192:195], v133 offset:21504
	ds_read_b128 v[196:199], v133 offset:22528
	ds_read_b128 v[200:203], v133 offset:23552
	global_load_lds_dwordx4 v[206:207], off
	v_lshl_add_u64 v[208:209], s[38:39], 0, v[178:179]
	s_mov_b32 m0, s66
	v_lshl_add_u64 v[210:211], s[40:41], 0, v[176:177]
	global_load_lds_dwordx4 v[208:209], off
	s_mov_b32 m0, s67
	v_lshl_add_u64 v[212:213], s[36:37], 0, v[178:179]
	global_load_lds_dwordx4 v[210:211], off
	v_lshl_add_u64 v[210:211], s[40:41], 0, v[178:179]
	s_mov_b32 m0, s68
	s_nop 0
	global_load_lds_dwordx4 v[210:211], off
	v_lshl_add_u64 v[210:211], s[36:37], 0, v[176:177]
	s_mov_b32 m0, s50
	s_nop 0
	global_load_lds_dwordx4 v[210:211], off
	s_mov_b32 m0, s51
	s_nop 0
	global_load_lds_dwordx4 v[212:213], off
	s_waitcnt vmcnt(8)
	s_waitcnt lgkmcnt(0)
	s_barrier
	s_setprio 1
	s_waitcnt lgkmcnt(0)
	v_mfma_f32_16x16x32_bf16 v[60:63], v[136:139], v[168:171], v[60:63]
	v_mfma_f32_16x16x32_bf16 v[56:59], v[144:147], v[168:171], v[56:59]
	v_mfma_f32_16x16x32_bf16 v[52:55], v[136:139], v[180:183], v[52:55]
	v_mfma_f32_16x16x32_bf16 v[48:51], v[144:147], v[180:183], v[48:51]
	v_mfma_f32_16x16x32_bf16 v[40:43], v[136:139], v[188:191], v[40:43]
	v_mfma_f32_16x16x32_bf16 v[32:35], v[144:147], v[188:191], v[32:35]
	v_mfma_f32_16x16x32_bf16 v[24:27], v[136:139], v[196:199], v[24:27]
	v_mfma_f32_16x16x32_bf16 v[16:19], v[144:147], v[196:199], v[16:19]
	v_mfma_f32_16x16x32_bf16 v[60:63], v[140:143], v[172:175], v[60:63]
	v_mfma_f32_16x16x32_bf16 v[56:59], v[148:151], v[172:175], v[56:59]
	v_mfma_f32_16x16x32_bf16 v[52:55], v[140:143], v[184:187], v[52:55]
	v_mfma_f32_16x16x32_bf16 v[48:51], v[148:151], v[184:187], v[48:51]
	v_mfma_f32_16x16x32_bf16 v[40:43], v[140:143], v[192:195], v[40:43]
	v_mfma_f32_16x16x32_bf16 v[32:35], v[148:151], v[192:195], v[32:35]
	v_mfma_f32_16x16x32_bf16 v[24:27], v[140:143], v[200:203], v[24:27]
	v_mfma_f32_16x16x32_bf16 v[16:19], v[148:151], v[200:203], v[16:19]
	s_setprio 0
	s_setprio 1
	v_mfma_f32_16x16x32_bf16 v[44:47], v[152:155], v[168:171], v[44:47]
	v_mfma_f32_16x16x32_bf16 v[36:39], v[160:163], v[168:171], v[36:39]
	v_mfma_f32_16x16x32_bf16 v[28:31], v[152:155], v[180:183], v[28:31]
	v_mfma_f32_16x16x32_bf16 v[20:23], v[160:163], v[180:183], v[20:23]
	v_mfma_f32_16x16x32_bf16 v[12:15], v[152:155], v[188:191], v[12:15]
	v_mfma_f32_16x16x32_bf16 v[8:11], v[160:163], v[188:191], v[8:11]
	v_mfma_f32_16x16x32_bf16 v[4:7], v[152:155], v[196:199], v[4:7]
	v_mfma_f32_16x16x32_bf16 v[0:3], v[160:163], v[196:199], v[0:3]
	v_mfma_f32_16x16x32_bf16 v[44:47], v[156:159], v[172:175], v[44:47]
	v_mfma_f32_16x16x32_bf16 v[36:39], v[164:167], v[172:175], v[36:39]
	v_mfma_f32_16x16x32_bf16 v[28:31], v[156:159], v[184:187], v[28:31]
	v_mfma_f32_16x16x32_bf16 v[20:23], v[164:167], v[184:187], v[20:23]
	v_mfma_f32_16x16x32_bf16 v[12:15], v[156:159], v[192:195], v[12:15]
	v_mfma_f32_16x16x32_bf16 v[8:11], v[164:167], v[192:195], v[8:11]
	v_mfma_f32_16x16x32_bf16 v[4:7], v[156:159], v[200:203], v[4:7]
	v_mfma_f32_16x16x32_bf16 v[0:3], v[164:167], v[200:203], v[0:3]
	s_setprio 0
	s_barrier
	v_add_u32_e32 v135, s75, v128
	ds_read_b128 v[136:139], v134
	ds_read_b128 v[140:143], v134 offset:1024
	ds_read_b128 v[144:147], v134 offset:2048
	ds_read_b128 v[148:151], v134 offset:3072
	ds_read_b128 v[152:155], v135
	ds_read_b128 v[156:159], v135 offset:1024
	ds_read_b128 v[160:163], v135 offset:2048
	ds_read_b128 v[164:167], v135 offset:3072
	s_mov_b32 m0, s52
	v_lshl_add_u64 v[214:215], s[34:35], 0, v[176:177]
	ds_read_b128 v[168:171], v133 offset:32768
	ds_read_b128 v[172:175], v133 offset:33792
	ds_read_b128 v[180:183], v133 offset:34816
	ds_read_b128 v[184:187], v133 offset:35840
	ds_read_b128 v[188:191], v133 offset:36864
	ds_read_b128 v[192:195], v133 offset:37888
	ds_read_b128 v[196:199], v133 offset:38912
	ds_read_b128 v[200:203], v133 offset:39936
	global_load_lds_dwordx4 v[214:215], off
	v_lshl_add_u64 v[214:215], s[34:35], 0, v[178:179]
	s_mov_b32 m0, s53
	s_nop 0
	global_load_lds_dwordx4 v[214:215], off
	s_waitcnt vmcnt(8)
	s_waitcnt lgkmcnt(0)
	s_barrier
	s_setprio 1
	s_waitcnt lgkmcnt(0)
	v_mfma_f32_16x16x32_bf16 v[124:127], v[136:139], v[168:171], v[124:127]
	v_mfma_f32_16x16x32_bf16 v[120:123], v[144:147], v[168:171], v[120:123]
	v_mfma_f32_16x16x32_bf16 v[116:119], v[136:139], v[180:183], v[116:119]
	v_mfma_f32_16x16x32_bf16 v[112:115], v[144:147], v[180:183], v[112:115]
	v_mfma_f32_16x16x32_bf16 v[108:111], v[136:139], v[188:191], v[108:111]
	v_mfma_f32_16x16x32_bf16 v[100:103], v[144:147], v[188:191], v[100:103]
	v_mfma_f32_16x16x32_bf16 v[92:95], v[136:139], v[196:199], v[92:95]
	v_mfma_f32_16x16x32_bf16 v[84:87], v[144:147], v[196:199], v[84:87]
	v_mfma_f32_16x16x32_bf16 v[124:127], v[140:143], v[172:175], v[124:127]
	v_mfma_f32_16x16x32_bf16 v[120:123], v[148:151], v[172:175], v[120:123]
	v_mfma_f32_16x16x32_bf16 v[116:119], v[140:143], v[184:187], v[116:119]
	v_mfma_f32_16x16x32_bf16 v[112:115], v[148:151], v[184:187], v[112:115]
	v_mfma_f32_16x16x32_bf16 v[108:111], v[140:143], v[192:195], v[108:111]
	v_mfma_f32_16x16x32_bf16 v[100:103], v[148:151], v[192:195], v[100:103]
	v_mfma_f32_16x16x32_bf16 v[92:95], v[140:143], v[200:203], v[92:95]
	v_mfma_f32_16x16x32_bf16 v[84:87], v[148:151], v[200:203], v[84:87]
	s_setprio 0
	s_setprio 1
	v_mfma_f32_16x16x32_bf16 v[104:107], v[152:155], v[168:171], v[104:107]
	v_mfma_f32_16x16x32_bf16 v[96:99], v[160:163], v[168:171], v[96:99]
	v_mfma_f32_16x16x32_bf16 v[88:91], v[152:155], v[180:183], v[88:91]
	v_mfma_f32_16x16x32_bf16 v[80:83], v[160:163], v[180:183], v[80:83]
	v_mfma_f32_16x16x32_bf16 v[76:79], v[152:155], v[188:191], v[76:79]
	v_mfma_f32_16x16x32_bf16 v[72:75], v[160:163], v[188:191], v[72:75]
	v_mfma_f32_16x16x32_bf16 v[68:71], v[152:155], v[196:199], v[68:71]
	v_mfma_f32_16x16x32_bf16 v[64:67], v[160:163], v[196:199], v[64:67]
	v_mfma_f32_16x16x32_bf16 v[104:107], v[156:159], v[172:175], v[104:107]
	v_mfma_f32_16x16x32_bf16 v[96:99], v[164:167], v[172:175], v[96:99]
	v_mfma_f32_16x16x32_bf16 v[88:91], v[156:159], v[184:187], v[88:91]
	v_mfma_f32_16x16x32_bf16 v[80:83], v[164:167], v[184:187], v[80:83]
	v_mfma_f32_16x16x32_bf16 v[76:79], v[156:159], v[192:195], v[76:79]
	v_mfma_f32_16x16x32_bf16 v[72:75], v[164:167], v[192:195], v[72:75]
	v_mfma_f32_16x16x32_bf16 v[68:71], v[156:159], v[200:203], v[68:71]
	v_mfma_f32_16x16x32_bf16 v[64:67], v[164:167], v[200:203], v[64:67]
	s_setprio 0
	s_barrier
	s_mov_b32 m0, s74
	v_lshl_add_u64 v[206:207], v[206:207], 0, s[10:11]
	ds_read_b128 v[168:171], v133 offset:49152
	ds_read_b128 v[172:175], v133 offset:50176
	ds_read_b128 v[180:183], v133 offset:51200
	ds_read_b128 v[184:187], v133 offset:52224
	ds_read_b128 v[188:191], v133 offset:53248
	ds_read_b128 v[192:195], v133 offset:54272
	ds_read_b128 v[196:199], v133 offset:55296
	ds_read_b128 v[200:203], v133 offset:56320
	global_load_lds_dwordx4 v[206:207], off
	v_lshl_add_u64 v[206:207], v[208:209], 0, s[10:11]
	s_mov_b32 m0, s73
	s_nop 0
	global_load_lds_dwordx4 v[206:207], off
	v_lshl_add_u64 v[206:207], s[30:31], 0, v[176:177]
	s_mov_b32 m0, s77
	s_nop 0
	global_load_lds_dwordx4 v[206:207], off
	v_lshl_add_u64 v[206:207], s[30:31], 0, v[178:179]
	s_mov_b32 m0, s76
	s_nop 0
	global_load_lds_dwordx4 v[206:207], off
	v_lshl_add_u64 v[206:207], v[210:211], 0, s[10:11]
	s_mov_b32 m0, s55
	s_nop 0
	global_load_lds_dwordx4 v[206:207], off
	v_lshl_add_u64 v[206:207], v[212:213], 0, s[10:11]
	s_mov_b32 m0, s56
	s_nop 0
	global_load_lds_dwordx4 v[206:207], off
	s_waitcnt vmcnt(8)
	s_waitcnt lgkmcnt(0)
	s_barrier
	s_setprio 1
	s_waitcnt lgkmcnt(0)
	v_mfma_f32_16x16x32_bf16 v[60:63], v[136:139], v[168:171], v[60:63]
	v_mfma_f32_16x16x32_bf16 v[56:59], v[144:147], v[168:171], v[56:59]
	v_mfma_f32_16x16x32_bf16 v[52:55], v[136:139], v[180:183], v[52:55]
	v_mfma_f32_16x16x32_bf16 v[48:51], v[144:147], v[180:183], v[48:51]
	v_mfma_f32_16x16x32_bf16 v[40:43], v[136:139], v[188:191], v[40:43]
	v_mfma_f32_16x16x32_bf16 v[32:35], v[144:147], v[188:191], v[32:35]
	v_mfma_f32_16x16x32_bf16 v[24:27], v[136:139], v[196:199], v[24:27]
	v_mfma_f32_16x16x32_bf16 v[16:19], v[144:147], v[196:199], v[16:19]
	v_mfma_f32_16x16x32_bf16 v[60:63], v[140:143], v[172:175], v[60:63]
	v_mfma_f32_16x16x32_bf16 v[56:59], v[148:151], v[172:175], v[56:59]
	v_mfma_f32_16x16x32_bf16 v[52:55], v[140:143], v[184:187], v[52:55]
	v_mfma_f32_16x16x32_bf16 v[48:51], v[148:151], v[184:187], v[48:51]
	v_mfma_f32_16x16x32_bf16 v[40:43], v[140:143], v[192:195], v[40:43]
	v_mfma_f32_16x16x32_bf16 v[32:35], v[148:151], v[192:195], v[32:35]
	v_mfma_f32_16x16x32_bf16 v[24:27], v[140:143], v[200:203], v[24:27]
	v_mfma_f32_16x16x32_bf16 v[16:19], v[148:151], v[200:203], v[16:19]
	s_setprio 0
	s_setprio 1
	v_mfma_f32_16x16x32_bf16 v[44:47], v[152:155], v[168:171], v[44:47]
	v_mfma_f32_16x16x32_bf16 v[36:39], v[160:163], v[168:171], v[36:39]
	v_mfma_f32_16x16x32_bf16 v[28:31], v[152:155], v[180:183], v[28:31]
	v_mfma_f32_16x16x32_bf16 v[20:23], v[160:163], v[180:183], v[20:23]
	v_mfma_f32_16x16x32_bf16 v[12:15], v[152:155], v[188:191], v[12:15]
	v_mfma_f32_16x16x32_bf16 v[8:11], v[160:163], v[188:191], v[8:11]
	v_mfma_f32_16x16x32_bf16 v[4:7], v[152:155], v[196:199], v[4:7]
	v_mfma_f32_16x16x32_bf16 v[0:3], v[160:163], v[196:199], v[0:3]
	v_mfma_f32_16x16x32_bf16 v[44:47], v[156:159], v[172:175], v[44:47]
	v_mfma_f32_16x16x32_bf16 v[36:39], v[164:167], v[172:175], v[36:39]
	v_mfma_f32_16x16x32_bf16 v[28:31], v[156:159], v[184:187], v[28:31]
	v_mfma_f32_16x16x32_bf16 v[20:23], v[164:167], v[184:187], v[20:23]
	v_mfma_f32_16x16x32_bf16 v[12:15], v[156:159], v[192:195], v[12:15]
	v_mfma_f32_16x16x32_bf16 v[8:11], v[164:167], v[192:195], v[8:11]
	v_mfma_f32_16x16x32_bf16 v[4:7], v[156:159], v[200:203], v[4:7]
	v_mfma_f32_16x16x32_bf16 v[0:3], v[164:167], v[200:203], v[0:3]
	s_setprio 0
	s_barrier
	s_movk_i32 s34, 0x100
	s_andn2_b64 vcc, exec, s[28:29]
	s_mov_b64 s[30:31], -1
	s_mov_b64 s[28:29], 0
	s_cbranch_vccz .LBB0_2504
	s_and_b64 vcc, exec, s[12:13]
	s_cbranch_vccz .LBB0_2507
	s_barrier
.LBB0_2507:
	s_ashr_i32 s14, s59, 31
	s_lshr_b32 s14, s14, 23
	s_add_i32 s14, s59, s14
	s_ashr_i32 s14, s14, 9
	v_lshl_add_u32 v136, s58, 8, v129
	s_ashr_i32 s15, s14, 31
	v_ashrrev_i32_e32 v137, 31, v136
	v_lshl_or_b32 v138, s57, 8, v130
	s_lshl_b64 s[14:15], s[14:15], 21
	v_lshlrev_b64 v[136:137], 12, v[136:137]
	v_ashrrev_i32_e32 v139, 31, v138
	v_lshl_add_u64 v[136:137], v[136:137], 0, s[14:15]
	v_lshl_add_u64 v[140:141], s[8:9], 0, v[136:137]
	v_lshlrev_b64 v[138:139], 2, v[138:139]
	v_lshl_add_u64 v[140:141], v[140:141], 0, v[138:139]
	global_store_dwordx4 v[140:141], v[124:127], off
	global_store_dwordx4 v[140:141], v[120:123], off offset:64
	global_store_dwordx4 v[140:141], v[104:107], off offset:512
	global_store_dwordx4 v[140:141], v[96:99], off offset:576
	s_nop 1
	v_or_b32_e32 v96, 0x10000, v136
	v_mov_b32_e32 v97, v137
	v_lshl_add_u64 v[96:97], s[8:9], 0, v[96:97]
	v_lshl_add_u64 v[96:97], v[96:97], 0, v[138:139]
	global_store_dwordx4 v[96:97], v[116:119], off
	global_store_dwordx4 v[96:97], v[112:115], off offset:64
	global_store_dwordx4 v[96:97], v[88:91], off offset:512
	global_store_dwordx4 v[96:97], v[80:83], off offset:576
	s_nop 1
	v_or_b32_e32 v80, 0x20000, v136
	v_mov_b32_e32 v81, v137
	v_lshl_add_u64 v[80:81], s[8:9], 0, v[80:81]
	v_lshl_add_u64 v[80:81], v[80:81], 0, v[138:139]
	v_or_b32_e32 v136, 0x30000, v136
	global_store_dwordx4 v[80:81], v[108:111], off
	global_store_dwordx4 v[80:81], v[100:103], off offset:64
	global_store_dwordx4 v[80:81], v[76:79], off offset:512
	global_store_dwordx4 v[80:81], v[72:75], off offset:576
	s_nop 1
	v_lshl_add_u64 v[72:73], s[8:9], 0, v[136:137]
	v_lshl_add_u64 v[72:73], v[72:73], 0, v[138:139]
	global_store_dwordx4 v[72:73], v[92:95], off
	global_store_dwordx4 v[72:73], v[84:87], off offset:64
	global_store_dwordx4 v[72:73], v[68:71], off offset:512
	global_store_dwordx4 v[72:73], v[64:67], off offset:576
	s_nop 1
	v_add_co_u32_e32 v66, vcc, s60, v140
	v_lshl_add_u64 v[64:65], v[140:141], 0, s[16:17]
	s_nop 0
	v_addc_co_u32_e32 v67, vcc, 0, v141, vcc
	global_store_dwordx4 v[66:67], v[60:63], off
	global_store_dwordx4 v[64:65], v[56:59], off offset:64
	global_store_dwordx4 v[64:65], v[44:47], off offset:512
	global_store_dwordx4 v[64:65], v[36:39], off offset:576
	s_nop 1
	v_add_co_u32_e32 v38, vcc, s61, v140
	v_lshl_add_u64 v[36:37], v[140:141], 0, s[18:19]
	s_nop 0
	v_addc_co_u32_e32 v39, vcc, 0, v141, vcc
	global_store_dwordx4 v[38:39], v[52:55], off
	global_store_dwordx4 v[36:37], v[48:51], off offset:64
	global_store_dwordx4 v[36:37], v[28:31], off offset:512
	global_store_dwordx4 v[36:37], v[20:23], off offset:576
	s_nop 1
	v_add_co_u32_e32 v22, vcc, s62, v140
	v_lshl_add_u64 v[20:21], v[140:141], 0, s[20:21]
	s_nop 0
	v_addc_co_u32_e32 v23, vcc, 0, v141, vcc
	global_store_dwordx4 v[22:23], v[40:43], off
	global_store_dwordx4 v[20:21], v[32:35], off offset:64
	global_store_dwordx4 v[20:21], v[12:15], off offset:512
	global_store_dwordx4 v[20:21], v[8:11], off offset:576
	s_nop 1
	v_add_co_u32_e32 v10, vcc, 0xb0000, v140
	v_lshl_add_u64 v[8:9], v[140:141], 0, s[4:5]
	s_nop 0
	v_addc_co_u32_e32 v11, vcc, 0, v141, vcc
	s_and_b64 vcc, exec, s[2:3]
	s_mov_b64 s[2:3], -1
	global_store_dwordx4 v[10:11], v[24:27], off
	global_store_dwordx4 v[8:9], v[16:19], off offset:64
	global_store_dwordx4 v[8:9], v[4:7], off offset:512
	global_store_dwordx4 v[8:9], v[0:3], off offset:576
	s_cbranch_vccnz .LBB0_2496
	s_andn2_b64 vcc, exec, s[6:7]
	s_cbranch_vccnz .LBB0_2495
	v_writelane_b32 v255, 1, 53
	s_branch .LBB0_2495
